# in-projection epilogue: the 8 per-row rsqrt(sum of squares) values come from one batched load + permlane reduction prologue instead of 8 serialized round trips (30 variant copies patched), on top of v
# speedup vs baseline: 1.0198x; 1.0074x over previous
; DI float sum16(const float* p) { const f32x4* q = (const f32x4*)p; f32x4 a = q[0], b = q[1], c = q[2], d = q[3]; f32x4 s = (a + b) + (c + d); return (s[0] + s[1]) + (s[2] + s[3]); }
;     template <int PN> DI void body(AccRef acc, const Unit& u, int wr, int wc, int fr, int fq) const {
;     ...
; #pragma unroll
;         for (int ai = 0; ai < 2; ++ai) {
;             const int rb_ = u.pm * 256 + ai * 128 + wr * 64 + fr;
; #pragma unroll
;             for (int m = 0; m < 4; ++m) rinvh[ai][m] = rsqrtf(sum16(ssq + (size_t)(rb_ + 16 * m + zdep) * 16) * (1.f / 1024.f) + EPS);
;             asm volatile("v_mov_b32 %0, 0" : "=v"(zdep) : "v"(rinvh[ai][0]), "v"(rinvh[ai][1]), "v"(rinvh[ai][2]), "v"(rinvh[ai][3]));
;         }
; #pragma unroll
;         for (int ai = 0; ai < 2; ++ai) {
;             const int rb_ = u.pm * 256 + ai * 128 + wr * 64 + fr;
;             int mb_, p_, k_; row_info(rb_, mb_, p_, k_);
; #pragma unroll
;             for (int bj = 0; bj < 2; ++bj)
; #pragma unroll
;                 for (int n = 0; n < 2; ++n) cvh[ai][bj][n] = *(const f32x4*)(cv + (size_t)(mb_ + zdep) * NIN + PN * 256 + bj * 128 + cl + 4 * n);
;         }
;     ...
;                 } else {
;                     float* lo = orow(out, l, row, PN == 8 ? O_PSK : O_PSV, PN == 8 ? O_SSK : O_SSV, 256);
; #pragma unroll
;                     for (int bj = 0; bj < 2; ++bj) {
;                         *(f32x4*)(lo + bj * 128 + cl) = (f32x4){v[bj][0], v[bj][1], v[bj][2], v[bj][3]};
;                         *(f32x4*)(lo + bj * 128 + cl + 4) = (f32x4){v[bj][4], v[bj][5], v[bj][6], v[bj][7]};
;                     }
.LBB0_353:
	s_mov_b32 s2, s21
	v_mbcnt_lo_u32_b32 v128, -1, 0
	v_mbcnt_hi_u32_b32 v128, -1, v128
	s_mov_b32 s66, s36
	v_and_b32_e32 v214, 15, v128
	v_bfe_u32 v213, v128, 4, 2
	s_mov_b32 s53, s27
	s_lshl_b32 s22, s53, 6
	s_lshl_b32 s23, s34, 8
	s_add_i32 s22, s22, s23
	v_add_u32_e32 v244, s22, v214
	v_lshlrev_b32_e32 v244, 6, v244
	v_lshl_add_u32 v244, v213, 4, v244
	global_load_dwordx4 v[228:231], v244, s[56:57]
	global_load_dwordx4 v[232:235], v244, s[56:57] offset:1024
	global_load_dwordx4 v[236:239], v244, s[56:57] offset:2048
	global_load_dwordx4 v[240:243], v244, s[56:57] offset:3072
	v_add_u32_e32 v244, 0x2000, v244
	global_load_dwordx4 v[216:219], v244, s[56:57]
	global_load_dwordx4 v[220:223], v244, s[56:57] offset:1024
	global_load_dwordx4 v[142:145], v244, s[56:57] offset:2048
	global_load_dwordx4 v[146:149], v244, s[56:57] offset:3072
	v_mov_b32_e32 v245, 0x3a800000
	s_waitcnt vmcnt(4)
	v_pk_add_f32 v[228:229], v[228:229], v[230:231]
	v_pk_add_f32 v[232:233], v[232:233], v[234:235]
	v_pk_add_f32 v[236:237], v[236:237], v[238:239]
	v_pk_add_f32 v[240:241], v[240:241], v[242:243]
	v_add_f32_e32 v228, v228, v229
	v_add_f32_e32 v232, v232, v233
	v_add_f32_e32 v236, v236, v237
	v_add_f32_e32 v240, v240, v241
	v_mov_b32_e32 v229, v228
	v_mov_b32_e32 v233, v232
	v_mov_b32_e32 v237, v236
	v_mov_b32_e32 v241, v240
	s_waitcnt vmcnt(0)
	v_pk_add_f32 v[216:217], v[216:217], v[218:219]
	v_pk_add_f32 v[220:221], v[220:221], v[222:223]
	v_pk_add_f32 v[142:143], v[142:143], v[144:145]
	v_pk_add_f32 v[146:147], v[146:147], v[148:149]
	v_add_f32_e32 v216, v216, v217
	v_add_f32_e32 v220, v220, v221
	v_add_f32_e32 v142, v142, v143
	v_add_f32_e32 v146, v146, v147
	v_mov_b32_e32 v217, v216
	v_mov_b32_e32 v221, v220
	v_mov_b32_e32 v143, v142
	v_mov_b32_e32 v147, v146
	s_nop 1
	v_permlane32_swap_b32_e32 v228, v229
	v_permlane32_swap_b32_e32 v232, v233
	v_permlane32_swap_b32_e32 v236, v237
	v_permlane32_swap_b32_e32 v240, v241
	v_permlane32_swap_b32_e32 v216, v217
	v_permlane32_swap_b32_e32 v220, v221
	v_permlane32_swap_b32_e32 v142, v143
	v_permlane32_swap_b32_e32 v146, v147
	v_add_f32_e32 v228, v228, v229
	v_add_f32_e32 v232, v232, v233
	v_add_f32_e32 v236, v236, v237
	v_add_f32_e32 v240, v240, v241
	v_add_f32_e32 v216, v216, v217
	v_add_f32_e32 v220, v220, v221
	v_add_f32_e32 v142, v142, v143
	v_add_f32_e32 v146, v146, v147
	v_mov_b32_e32 v229, v228
	v_mov_b32_e32 v233, v232
	v_mov_b32_e32 v237, v236
	v_mov_b32_e32 v241, v240
	v_mov_b32_e32 v217, v216
	v_mov_b32_e32 v221, v220
	v_mov_b32_e32 v143, v142
	v_mov_b32_e32 v147, v146
	s_nop 1
	v_permlane16_swap_b32_e32 v228, v229
	v_permlane16_swap_b32_e32 v232, v233
	v_permlane16_swap_b32_e32 v236, v237
	v_permlane16_swap_b32_e32 v240, v241
	v_permlane16_swap_b32_e32 v216, v217
	v_permlane16_swap_b32_e32 v220, v221
	v_permlane16_swap_b32_e32 v142, v143
	v_permlane16_swap_b32_e32 v146, v147
	v_add_f32_e32 v228, v228, v229
	v_add_f32_e32 v232, v232, v233
	v_add_f32_e32 v236, v236, v237
	v_add_f32_e32 v240, v240, v241
	v_add_f32_e32 v216, v216, v217
	v_add_f32_e32 v220, v220, v221
	v_add_f32_e32 v142, v142, v143
	v_add_f32_e32 v146, v146, v147
	v_fmaak_f32 v228, v245, v228, 0x358637bd
	v_fmaak_f32 v232, v245, v232, 0x358637bd
	v_fmaak_f32 v236, v245, v236, 0x358637bd
	v_fmaak_f32 v240, v245, v240, 0x358637bd
	v_fmaak_f32 v216, v245, v216, 0x358637bd
	v_fmaak_f32 v220, v245, v220, 0x358637bd
	v_fmaak_f32 v142, v245, v142, 0x358637bd
	v_fmaak_f32 v146, v245, v146, 0x358637bd
	v_rsq_f32_e32 v244, v228
	v_rsq_f32_e32 v245, v232
	v_rsq_f32_e32 v246, v236
	v_rsq_f32_e32 v247, v240
	v_rsq_f32_e32 v248, v216
	v_rsq_f32_e32 v249, v220
	v_rsq_f32_e32 v250, v142
	v_rsq_f32_e32 v251, v146
	s_mov_b64 s[2:3], -1
	s_mov_b64 s[8:9], 0
	s_cmp_lt_i32 s52, 4
	s_mov_b64 s[94:95], 0
	s_cbranch_scc1 .LBB0_372
	s_cmp_gt_i32 s52, 5
	s_cbranch_scc0 .LBB0_366
	s_cmp_gt_i32 s52, 6
	s_cbranch_scc0 .LBB0_363
	s_cmp_gt_i32 s52, 7
	s_cbranch_scc0 .LBB0_360
	s_cmp_eq_u32 s52, 8
	s_mov_b64 s[94:95], -1
	s_cbranch_scc0 .LBB0_359
	s_lshl_b32 s2, s53, 6
	s_lshl_b32 s3, s34, 8
	s_add_i32 s2, s2, s3
	v_add_u32_e32 v160, s2, v214
	v_ashrrev_i32_e32 v161, 31, v160
	v_lshlrev_b64 v[128:129], 6, v[160:161]
	v_lshl_add_u64 v[140:141], s[56:57], 0, v[128:129]
	s_nop 0
	v_add_u32_e32 v168, 16, v160
	v_ashrrev_i32_e32 v169, 31, v168
	s_mov_b32 s2, 0x358637bd
	s_mov_b32 s4, 0x3a800000
	v_add_u32_e32 v164, 32, v160
	v_ashrrev_i32_e32 v165, 31, v164
	v_add_u32_e32 v166, 48, v160
	v_ashrrev_i32_e32 v167, 31, v166
	v_add_u32_e32 v163, 0x80, v160
	v_add_u32_e32 v173, 0xffffc000, v160
	s_movk_i32 s6, 0x4000
	s_mov_b64 s[12:13], 0x126000
	v_add_u32_e32 v171, 0xffffc080, v160
	v_mov_b32_e32 v175, 0x6800000
	s_mov_b64 s[94:95], 0
	s_nop 0
	v_lshlrev_b64 v[128:129], 6, v[168:169]
	v_lshl_add_u64 v[140:141], s[56:57], 0, v[128:129]
	s_nop 0
	s_nop 0
	v_mov_b64_e32 v[128:129], s[2:3]
	s_nop 0
	s_nop 0
	s_nop 0
	v_mov_b32_e32 v188, v244
	s_nop 0
	v_mov_b32_e32 v162, v245
	v_lshlrev_b64 v[130:131], 6, v[164:165]
	v_lshl_add_u64 v[142:143], s[56:57], 0, v[130:131]
	s_nop 0
	s_nop 0
	v_lshlrev_b64 v[130:131], 6, v[166:167]
	v_lshl_add_u64 v[142:143], s[56:57], 0, v[130:131]
	s_nop 0
	s_nop 0
	s_nop 0
	s_nop 0
	s_nop 0
	s_nop 0
	v_mov_b32_e32 v170, v246
	s_nop 0
	v_mov_b32_e32 v174, v247
	v_mov_b32 v130, 0
	s_nop 0
	v_add_u32_e32 v130, v130, v163
	v_ashrrev_i32_e32 v131, 31, v130
	v_lshlrev_b64 v[132:133], 6, v[130:131]
	v_lshl_add_u64 v[144:145], s[56:57], 0, v[132:133]
	s_nop 0
	s_nop 0
	v_add_u32_e32 v132, 16, v130
	v_ashrrev_i32_e32 v133, 31, v132
	v_lshlrev_b64 v[132:133], 6, v[132:133]
	v_lshl_add_u64 v[144:145], s[56:57], 0, v[132:133]
	s_nop 0
	s_nop 0
	s_nop 0
;     template <int PN> DI void body(AccRef acc, const Unit& u, int wr, int wc, int fr, int fq) const {
;     ...
;         for (int ai = 0; ai < 2; ++ai) {
;             const int rb_ = u.pm * 256 + ai * 128 + wr * 64 + fr;
;             int mb_, p_, k_; row_info(rb_, mb_, p_, k_);
; #pragma unroll
;             for (int bj = 0; bj < 2; ++bj)
; #pragma unroll
;                 for (int n = 0; n < 2; ++n) cvh[ai][bj][n] = *(const f32x4*)(cv + (size_t)(mb_ + zdep) * NIN + PN * 256 + bj * 128 + cl + 4 * n);
;         }
; #pragma unroll
;         for (int ai = 0; ai < 2; ++ai) {
;             const int rb = u.pm * 256 + ai * 128 + wr * 64 + fr;
;             int mb, pos0, kv0; row_info(rb, mb, pos0, kv0);
; #pragma unroll
;             for (int m = 0; m < 4; ++m) {
;                 const int row = rb + 16 * m, pos = pos0 + 16 * m, kvrow = kv0 + 16 * m;
;                 const float rinv = rinvh[ai][m];
;                 float v[2][8];
; #pragma unroll
;                 for (int bj = 0; bj < 2; ++bj)
; #pragma unroll
;                     for (int n = 0; n < 2; ++n)
; #pragma unroll
;                         for (int j = 0; j < 4; ++j) v[bj][4 * n + j] = acc[ai][bj][m][n][j] * rinv + cvh[ai][bj][n][j];
;     ...
;                 } else {
;                     float* lo = orow(out, l, row, PN == 8 ? O_PSK : O_PSV, PN == 8 ? O_SSK : O_SSV, 256);
; #pragma unroll
;                     for (int bj = 0; bj < 2; ++bj) {
;                         *(f32x4*)(lo + bj * 128 + cl) = (f32x4){v[bj][0], v[bj][1], v[bj][2], v[bj][3]};
;                         *(f32x4*)(lo + bj * 128 + cl + 4) = (f32x4){v[bj][4], v[bj][5], v[bj][6], v[bj][7]};
;                     }
	s_nop 0
	s_nop 0
	s_nop 0
	v_mov_b32_e32 v190, v248
	s_nop 0
	v_mov_b32_e32 v172, v249
	v_add_u32_e32 v132, 32, v130
	v_ashrrev_i32_e32 v133, 31, v132
	v_lshlrev_b64 v[132:133], 6, v[132:133]
	v_lshl_add_u64 v[144:145], s[56:57], 0, v[132:133]
	s_nop 0
	v_add_u32_e32 v130, 48, v130
	v_ashrrev_i32_e32 v131, 31, v130
	v_lshlrev_b64 v[130:131], 6, v[130:131]
	v_lshl_add_u64 v[142:143], s[56:57], 0, v[130:131]
	s_nop 0
	s_nop 0
	s_nop 0
	v_lshrrev_b32_e32 v131, 6, v173
	v_add_u32_e32 v131, 8, v131
	s_nop 0
	v_mov_b32_e32 v192, v250
	s_lshl_b32 s2, s66, 5
	v_ashrrev_i32_e32 v130, 11, v160
	v_mov_b32_e32 v194, v251
	v_lshl_add_u32 v128, v213, 3, s2
	v_cmp_gt_i32_e64 s[2:3], s6, v160
	v_mov_b32 v134, 0
	v_ashrrev_i32_e32 v129, 31, v128
	v_lshlrev_b64 v[196:197], 2, v[128:129]
	v_cndmask_b32_e64 v130, v131, v130, s[2:3]
	v_add_u32_e32 v132, v134, v130
	v_mov_b64_e32 v[130:131], s[10:11]
	v_mad_i64_i32 v[132:133], s[4:5], v132, s51, v[130:131]
	v_lshl_add_u64 v[128:129], v[132:133], 0, v[196:197]
	v_lshl_add_u64 v[132:133], v[128:129], 0, s[12:13]
	v_add_co_u32_e32 v128, vcc, s62, v128
	v_cndmask_b32_e64 v198, v173, v160, s[2:3]
	s_nop 0
	v_addc_co_u32_e32 v129, vcc, 0, v129, vcc
	global_load_dwordx4 v[152:155], v[128:129], off
	global_load_dwordx4 v[156:159], v[132:133], off offset:16
	global_load_dwordx4 v[144:147], v[132:133], off offset:528
	global_load_dwordx4 v[148:151], v[132:133], off offset:512
	v_lshrrev_b32_e32 v129, 6, v171
	v_cmp_gt_i32_e32 vcc, s6, v163
	v_ashrrev_i32_e32 v128, 11, v163
	v_add_u32_e32 v129, 8, v129
	v_cndmask_b32_e32 v128, v129, v128, vcc
	v_add_u32_e32 v128, v134, v128
	v_mad_i64_i32 v[128:129], s[4:5], v128, s51, v[130:131]
	v_lshl_add_u64 v[128:129], v[128:129], 0, v[196:197]
	v_lshl_add_u64 v[132:133], v[128:129], 0, s[12:13]
	v_add_co_u32_e64 v128, s[4:5], s62, v128
	v_mov_b32_e32 v173, 0xab98000
	s_nop 0
	v_addc_co_u32_e64 v129, s[4:5], 0, v129, s[4:5]
	global_load_dwordx4 v[140:143], v[128:129], off
	global_load_dwordx4 v[136:139], v[132:133], off offset:16
	s_nop 0
	global_load_dwordx4 v[128:131], v[132:133], off offset:528
	s_nop 0
	global_load_dwordx4 v[132:135], v[132:133], off offset:512
	v_cndmask_b32_e64 v199, 0, v161, s[2:3]
	v_cndmask_b32_e64 v224, v173, v175, s[2:3]
	v_lshl_add_u64 v[200:201], s[42:43], 0, v[224:225]
	v_lshlrev_b64 v[198:199], 10, v[198:199]
	v_lshl_add_u64 v[198:199], v[200:201], 0, v[198:199]
	v_lshl_add_u64 v[202:203], v[198:199], 0, v[196:197]
	v_cmp_gt_i32_e64 s[2:3], s82, v160
	v_add_u32_e32 v161, 0xffffc010, v160
	s_waitcnt vmcnt(7)
	v_pk_fma_f32 v[200:201], v[126:127], v[188:189], v[154:155] op_sel_hi:[1,0,1]
	v_pk_fma_f32 v[198:199], v[124:125], v[188:189], v[152:153] op_sel_hi:[1,0,1]
	global_store_dwordx4 v[202:203], v[198:201], off
	v_cndmask_b32_e64 v169, 0, v169, s[2:3]
	v_cndmask_b32_e64 v168, v161, v168, s[2:3]
	s_waitcnt vmcnt(7)
	v_pk_fma_f32 v[200:201], v[122:123], v[188:189], v[158:159] op_sel_hi:[1,0,1]
	v_pk_fma_f32 v[198:199], v[120:121], v[188:189], v[156:157] op_sel_hi:[1,0,1]
	global_store_dwordx4 v[202:203], v[198:201], off offset:16
	v_cndmask_b32_e64 v224, v173, v175, s[2:3]
	v_lshlrev_b64 v[168:169], 10, v[168:169]
	s_waitcnt vmcnt(6)
	v_pk_fma_f32 v[200:201], v[118:119], v[188:189], v[150:151] op_sel_hi:[1,0,1]
	v_pk_fma_f32 v[198:199], v[116:117], v[188:189], v[148:149] op_sel_hi:[1,0,1]
	global_store_dwordx4 v[202:203], v[198:201], off offset:512
	v_cmp_gt_i32_e64 s[2:3], s83, v160
	v_add_u32_e32 v161, 0xffffc020, v160
	v_pk_fma_f32 v[200:201], v[114:115], v[188:189], v[146:147] op_sel_hi:[1,0,1]
	v_pk_fma_f32 v[198:199], v[112:113], v[188:189], v[144:145] op_sel_hi:[1,0,1]
	v_lshl_add_u64 v[188:189], s[42:43], 0, v[224:225]
	v_lshl_add_u64 v[168:169], v[188:189], 0, v[168:169]
	global_store_dwordx4 v[202:203], v[198:201], off offset:528
	v_lshl_add_u64 v[168:169], v[168:169], 0, v[196:197]
	v_cndmask_b32_e64 v165, 0, v165, s[2:3]
	v_pk_fma_f32 v[200:201], v[110:111], v[162:163], v[154:155] op_sel_hi:[1,0,1]
	v_pk_fma_f32 v[198:199], v[108:109], v[162:163], v[152:153] op_sel_hi:[1,0,1]
	global_store_dwordx4 v[168:169], v[198:201], off
	v_cndmask_b32_e64 v164, v161, v164, s[2:3]
	v_cndmask_b32_e64 v224, v173, v175, s[2:3]
	v_pk_fma_f32 v[200:201], v[106:107], v[162:163], v[158:159] op_sel_hi:[1,0,1]
	v_pk_fma_f32 v[198:199], v[104:105], v[162:163], v[156:157] op_sel_hi:[1,0,1]
	global_store_dwordx4 v[168:169], v[198:201], off offset:16
	v_lshlrev_b64 v[164:165], 10, v[164:165]
	v_cmp_gt_i32_e64 s[2:3], s92, v160
	v_pk_fma_f32 v[200:201], v[102:103], v[162:163], v[150:151] op_sel_hi:[1,0,1]
	v_pk_fma_f32 v[198:199], v[100:101], v[162:163], v[148:149] op_sel_hi:[1,0,1]
	global_store_dwordx4 v[168:169], v[198:201], off offset:512
	v_add_u32_e32 v161, 0xffffc030, v160
	s_nop 0
	v_pk_fma_f32 v[200:201], v[98:99], v[162:163], v[146:147] op_sel_hi:[1,0,1]
	v_pk_fma_f32 v[198:199], v[96:97], v[162:163], v[144:145] op_sel_hi:[1,0,1]
	global_store_dwordx4 v[168:169], v[198:201], off offset:528
	v_lshl_add_u64 v[168:169], s[42:43], 0, v[224:225]
	v_lshl_add_u64 v[164:165], v[168:169], 0, v[164:165]
	v_lshl_add_u64 v[164:165], v[164:165], 0, v[196:197]
	v_pk_fma_f32 v[200:201], v[94:95], v[170:171], v[154:155] op_sel_hi:[1,0,1]
	v_pk_fma_f32 v[198:199], v[92:93], v[170:171], v[152:153] op_sel_hi:[1,0,1]
	global_store_dwordx4 v[164:165], v[198:201], off
	v_cndmask_b32_e64 v224, v173, v175, s[2:3]
	v_pk_fma_f32 v[154:155], v[78:79], v[174:175], v[154:155] op_sel_hi:[1,0,1]
	v_pk_fma_f32 v[200:201], v[90:91], v[170:171], v[158:159] op_sel_hi:[1,0,1]
	v_pk_fma_f32 v[198:199], v[88:89], v[170:171], v[156:157] op_sel_hi:[1,0,1]
	global_store_dwordx4 v[164:165], v[198:201], off offset:16
;     template <int PN> DI void body(AccRef acc, const Unit& u, int wr, int wc, int fr, int fq) const {
;     ...
; #pragma unroll
;         for (int ai = 0; ai < 2; ++ai) {
;             const int rb = u.pm * 256 + ai * 128 + wr * 64 + fr;
;             int mb, pos0, kv0; row_info(rb, mb, pos0, kv0);
; #pragma unroll
;             for (int m = 0; m < 4; ++m) {
;                 const int row = rb + 16 * m, pos = pos0 + 16 * m, kvrow = kv0 + 16 * m;
;                 const float rinv = rinvh[ai][m];
;                 float v[2][8];
; #pragma unroll
;                 for (int bj = 0; bj < 2; ++bj)
; #pragma unroll
;                     for (int n = 0; n < 2; ++n)
; #pragma unroll
;                         for (int j = 0; j < 4; ++j) v[bj][4 * n + j] = acc[ai][bj][m][n][j] * rinv + cvh[ai][bj][n][j];
;     ...
;                 } else {
;                     float* lo = orow(out, l, row, PN == 8 ? O_PSK : O_PSV, PN == 8 ? O_SSK : O_SSV, 256);
; #pragma unroll
;                     for (int bj = 0; bj < 2; ++bj) {
;                         *(f32x4*)(lo + bj * 128 + cl) = (f32x4){v[bj][0], v[bj][1], v[bj][2], v[bj][3]};
;                         *(f32x4*)(lo + bj * 128 + cl + 4) = (f32x4){v[bj][4], v[bj][5], v[bj][6], v[bj][7]};
;                     }
	v_pk_fma_f32 v[152:153], v[76:77], v[174:175], v[152:153] op_sel_hi:[1,0,1]
	s_nop 0
	v_pk_fma_f32 v[200:201], v[86:87], v[170:171], v[150:151] op_sel_hi:[1,0,1]
	v_pk_fma_f32 v[198:199], v[84:85], v[170:171], v[148:149] op_sel_hi:[1,0,1]
	global_store_dwordx4 v[164:165], v[198:201], off offset:512
	v_pk_fma_f32 v[150:151], v[70:71], v[174:175], v[150:151] op_sel_hi:[1,0,1]
	v_pk_fma_f32 v[148:149], v[68:69], v[174:175], v[148:149] op_sel_hi:[1,0,1]
	v_pk_fma_f32 v[200:201], v[82:83], v[170:171], v[146:147] op_sel_hi:[1,0,1]
	v_pk_fma_f32 v[198:199], v[80:81], v[170:171], v[144:145] op_sel_hi:[1,0,1]
	global_store_dwordx4 v[164:165], v[198:201], off offset:528
	v_cndmask_b32_e64 v165, 0, v167, s[2:3]
	v_cndmask_b32_e64 v164, v161, v166, s[2:3]
	v_lshl_add_u64 v[166:167], s[42:43], 0, v[224:225]
	v_lshlrev_b64 v[164:165], 10, v[164:165]
	v_lshl_add_u64 v[164:165], v[166:167], 0, v[164:165]
	v_lshl_add_u64 v[164:165], v[164:165], 0, v[196:197]
	v_pk_fma_f32 v[146:147], v[66:67], v[174:175], v[146:147] op_sel_hi:[1,0,1]
	v_pk_fma_f32 v[144:145], v[64:65], v[174:175], v[144:145] op_sel_hi:[1,0,1]
	global_store_dwordx4 v[164:165], v[144:147], off offset:528
	v_cndmask_b32_e32 v224, v173, v175, vcc
	global_store_dwordx4 v[164:165], v[152:155], off
	v_ashrrev_i32_e32 v144, 31, v163
	v_cndmask_b32_e32 v145, 0, v144, vcc
	v_cndmask_b32_e32 v144, v171, v163, vcc
	v_lshl_add_u64 v[146:147], s[42:43], 0, v[224:225]
	v_lshlrev_b64 v[144:145], 10, v[144:145]
	v_lshl_add_u64 v[144:145], v[146:147], 0, v[144:145]
	v_pk_fma_f32 v[154:155], v[74:75], v[174:175], v[158:159] op_sel_hi:[1,0,1]
	v_pk_fma_f32 v[152:153], v[72:73], v[174:175], v[156:157] op_sel_hi:[1,0,1]
	global_store_dwordx4 v[164:165], v[148:151], off offset:512
	s_waitcnt vmcnt(18)
	v_pk_fma_f32 v[146:147], v[62:63], v[190:191], v[142:143] op_sel_hi:[1,0,1]
	global_store_dwordx4 v[164:165], v[152:155], off offset:16
	v_lshl_add_u64 v[148:149], v[144:145], 0, v[196:197]
	v_pk_fma_f32 v[144:145], v[60:61], v[190:191], v[140:141] op_sel_hi:[1,0,1]
	global_store_dwordx4 v[148:149], v[144:147], off
	v_cmp_gt_i32_e32 vcc, s82, v163
	s_waitcnt vmcnt(19)
	v_pk_fma_f32 v[146:147], v[58:59], v[190:191], v[138:139] op_sel_hi:[1,0,1]
	v_pk_fma_f32 v[144:145], v[56:57], v[190:191], v[136:137] op_sel_hi:[1,0,1]
	global_store_dwordx4 v[148:149], v[144:147], off offset:16
	v_cndmask_b32_e32 v224, v173, v175, vcc
	s_waitcnt vmcnt(18)
	v_pk_fma_f32 v[146:147], v[54:55], v[190:191], v[134:135] op_sel_hi:[1,0,1]
	v_pk_fma_f32 v[144:145], v[52:53], v[190:191], v[132:133] op_sel_hi:[1,0,1]
	global_store_dwordx4 v[148:149], v[144:147], off offset:512
	s_nop 1
	v_pk_fma_f32 v[146:147], v[50:51], v[190:191], v[130:131] op_sel_hi:[1,0,1]
	v_pk_fma_f32 v[144:145], v[48:49], v[190:191], v[128:129] op_sel_hi:[1,0,1]
	global_store_dwordx4 v[148:149], v[144:147], off offset:528
	s_nop 1
	v_add_u32_e32 v146, 0x90, v160
	v_add_u32_e32 v144, 0xffffc090, v160
	v_ashrrev_i32_e32 v145, 31, v146
	v_cndmask_b32_e32 v145, 0, v145, vcc
	v_cndmask_b32_e32 v144, v144, v146, vcc
	v_lshl_add_u64 v[146:147], s[42:43], 0, v[224:225]
	v_lshlrev_b64 v[144:145], 10, v[144:145]
	v_lshl_add_u64 v[144:145], v[146:147], 0, v[144:145]
	v_lshl_add_u64 v[148:149], v[144:145], 0, v[196:197]
	v_pk_fma_f32 v[146:147], v[46:47], v[172:173], v[142:143] op_sel_hi:[1,0,1]
	v_pk_fma_f32 v[144:145], v[44:45], v[172:173], v[140:141] op_sel_hi:[1,0,1]
	global_store_dwordx4 v[148:149], v[144:147], off
	v_cmp_gt_i32_e32 vcc, s83, v163
	s_nop 0
	v_pk_fma_f32 v[146:147], v[42:43], v[172:173], v[138:139] op_sel_hi:[1,0,1]
	v_pk_fma_f32 v[144:145], v[40:41], v[172:173], v[136:137] op_sel_hi:[1,0,1]
	global_store_dwordx4 v[148:149], v[144:147], off offset:16
	v_cndmask_b32_e32 v224, v173, v175, vcc
	s_nop 0
	v_pk_fma_f32 v[146:147], v[38:39], v[172:173], v[134:135] op_sel_hi:[1,0,1]
	v_pk_fma_f32 v[144:145], v[36:37], v[172:173], v[132:133] op_sel_hi:[1,0,1]
	global_store_dwordx4 v[148:149], v[144:147], off offset:512
	s_nop 1
	v_pk_fma_f32 v[146:147], v[30:31], v[172:173], v[130:131] op_sel_hi:[1,0,1]
	v_pk_fma_f32 v[144:145], v[28:29], v[172:173], v[128:129] op_sel_hi:[1,0,1]
	global_store_dwordx4 v[148:149], v[144:147], off offset:528
	s_nop 1
	v_add_u32_e32 v146, 0xa0, v160
	v_add_u32_e32 v144, 0xffffc0a0, v160
	v_ashrrev_i32_e32 v145, 31, v146
	v_cndmask_b32_e32 v145, 0, v145, vcc
	v_cndmask_b32_e32 v144, v144, v146, vcc
	v_lshl_add_u64 v[146:147], s[42:43], 0, v[224:225]
	v_lshlrev_b64 v[144:145], 10, v[144:145]
	v_lshl_add_u64 v[144:145], v[146:147], 0, v[144:145]
	v_lshl_add_u64 v[148:149], v[144:145], 0, v[196:197]
	v_pk_fma_f32 v[146:147], v[34:35], v[192:193], v[142:143] op_sel_hi:[1,0,1]
	v_pk_fma_f32 v[144:145], v[32:33], v[192:193], v[140:141] op_sel_hi:[1,0,1]
	global_store_dwordx4 v[148:149], v[144:147], off
	v_cmp_gt_i32_e32 vcc, s92, v163
	v_pk_fma_f32 v[142:143], v[14:15], v[194:195], v[142:143] op_sel_hi:[1,0,1]
	v_pk_fma_f32 v[146:147], v[26:27], v[192:193], v[138:139] op_sel_hi:[1,0,1]
	v_pk_fma_f32 v[144:145], v[24:25], v[192:193], v[136:137] op_sel_hi:[1,0,1]
	global_store_dwordx4 v[148:149], v[144:147], off offset:16
	v_cndmask_b32_e32 v224, v173, v175, vcc
	v_pk_fma_f32 v[140:141], v[12:13], v[194:195], v[140:141] op_sel_hi:[1,0,1]
	v_pk_fma_f32 v[146:147], v[22:23], v[192:193], v[134:135] op_sel_hi:[1,0,1]
	v_pk_fma_f32 v[144:145], v[20:21], v[192:193], v[132:133] op_sel_hi:[1,0,1]
	global_store_dwordx4 v[148:149], v[144:147], off offset:512
	v_pk_fma_f32 v[138:139], v[10:11], v[194:195], v[138:139] op_sel_hi:[1,0,1]
	v_pk_fma_f32 v[136:137], v[8:9], v[194:195], v[136:137] op_sel_hi:[1,0,1]
	v_pk_fma_f32 v[146:147], v[18:19], v[192:193], v[130:131] op_sel_hi:[1,0,1]
	v_pk_fma_f32 v[144:145], v[16:17], v[192:193], v[128:129] op_sel_hi:[1,0,1]
	global_store_dwordx4 v[148:149], v[144:147], off offset:528
	v_pk_fma_f32 v[134:135], v[6:7], v[194:195], v[134:135] op_sel_hi:[1,0,1]
	v_pk_fma_f32 v[132:133], v[4:5], v[194:195], v[132:133] op_sel_hi:[1,0,1]
	v_add_u32_e32 v146, 0xb0, v160
	v_add_u32_e32 v144, 0xffffc0b0, v160
	v_ashrrev_i32_e32 v145, 31, v146
	v_cndmask_b32_e32 v145, 0, v145, vcc
	v_cndmask_b32_e32 v144, v144, v146, vcc
	v_lshl_add_u64 v[146:147], s[42:43], 0, v[224:225]
	v_lshlrev_b64 v[144:145], 10, v[144:145]
	v_lshl_add_u64 v[144:145], v[146:147], 0, v[144:145]
	v_lshl_add_u64 v[144:145], v[144:145], 0, v[196:197]
	v_pk_fma_f32 v[130:131], v[2:3], v[194:195], v[130:131] op_sel_hi:[1,0,1]
	v_pk_fma_f32 v[128:129], v[0:1], v[194:195], v[128:129] op_sel_hi:[1,0,1]
	global_store_dwordx4 v[144:145], v[140:143], off
	global_store_dwordx4 v[144:145], v[136:139], off offset:16
	global_store_dwordx4 v[144:145], v[132:135], off offset:512
	global_store_dwordx4 v[144:145], v[128:131], off offset:528

; DI u32x4 pack8(const float* v) { u32x4 w; w.x = pk2(v[0], v[1]); w.y = pk2(v[2], v[3]); w.z = pk2(v[4], v[5]); w.w = pk2(v[6], v[7]); return w; }
; DI float silu(float x) { return x * __builtin_amdgcn_rcpf(1.f + ex2(-x * LOG2E)); }
; DI float sum16(const float* p) { const f32x4* q = (const f32x4*)p; f32x4 a = q[0], b = q[1], c = q[2], d = q[3]; f32x4 s = (a + b) + (c + d); return (s[0] + s[1]) + (s[2] + s[3]); }
;     template <int PN> DI void body(AccRef acc, const Unit& u, int wr, int wc, int fr, int fq) const {
;     ...
; #pragma unroll
;         for (int ai = 0; ai < 2; ++ai) {
;             const int rb_ = u.pm * 256 + ai * 128 + wr * 64 + fr;
; #pragma unroll
;             for (int m = 0; m < 4; ++m) rinvh[ai][m] = rsqrtf(sum16(ssq + (size_t)(rb_ + 16 * m + zdep) * 16) * (1.f / 1024.f) + EPS);
;             asm volatile("v_mov_b32 %0, 0" : "=v"(zdep) : "v"(rinvh[ai][0]), "v"(rinvh[ai][1]), "v"(rinvh[ai][2]), "v"(rinvh[ai][3]));
;         }
; #pragma unroll
;         for (int ai = 0; ai < 2; ++ai) {
;             const int rb_ = u.pm * 256 + ai * 128 + wr * 64 + fr;
;             int mb_, p_, k_; row_info(rb_, mb_, p_, k_);
; #pragma unroll
;             for (int bj = 0; bj < 2; ++bj)
; #pragma unroll
;                 for (int n = 0; n < 2; ++n) cvh[ai][bj][n] = *(const f32x4*)(cv + (size_t)(mb_ + zdep) * NIN + PN * 256 + bj * 128 + cl + 4 * n);
;         }
;     ...
;                 } else if constexpr (PN == 5 || PN == 6 || PN == 7) {
;                     bf16_t* dst = PN == 5 ? rv : (PN == 6 ? rg : sq);
; #pragma unroll
;                     for (int bj = 0; bj < 2; ++bj) {
;                         if constexpr (PN == 6) {
; #pragma unroll
;                             for (int j = 0; j < 8; ++j) v[bj][j] = silu(v[bj][j]);
;                         }
;                         if constexpr (PN == 7) {
; #pragma unroll
;                             for (int j = 0; j < 8; ++j) v[bj][j] *= 0.125f;
;                         }
;                         *(u32x4*)(dst + (size_t)row * 256 + bj * 128 + cl) = pack8(v[bj]);
;                     }
.LBB0_360:
	s_and_b64 vcc, exec, s[2:3]
	s_cbranch_vccz .LBB0_362
	s_lshl_b32 s2, s53, 6
	s_lshl_b32 s3, s34, 8
	s_add_i32 s2, s2, s3
	v_add_u32_e32 v160, s2, v214
	v_ashrrev_i32_e32 v161, 31, v160
	v_lshlrev_b64 v[128:129], 6, v[160:161]
	v_lshl_add_u64 v[140:141], s[56:57], 0, v[128:129]
	s_nop 0
	v_add_u32_e32 v168, 16, v160
	v_ashrrev_i32_e32 v169, 31, v168
	s_mov_b32 s2, 0x358637bd
	s_mov_b32 s4, 0x3a800000
	v_add_u32_e32 v164, 32, v160
	v_ashrrev_i32_e32 v165, 31, v164
	v_add_u32_e32 v166, 48, v160
	v_ashrrev_i32_e32 v167, 31, v166
	v_add_u32_e32 v174, 0x80, v160
	s_mov_b64 s[6:7], 0x125c00
	v_lshlrev_b64 v[200:201], 9, v[160:161]
	v_ashrrev_i32_e32 v175, 31, v174
	s_nop 0
	v_lshlrev_b64 v[128:129], 6, v[168:169]
	v_lshl_add_u64 v[140:141], s[56:57], 0, v[128:129]
	s_nop 0
	v_lshlrev_b64 v[168:169], 9, v[168:169]
	s_nop 0
	v_mov_b64_e32 v[128:129], s[2:3]
	s_nop 0
	s_nop 0
	s_nop 0
	v_mov_b32_e32 v172, v244
	s_nop 0
	v_mov_b32_e32 v162, v245
	v_lshlrev_b64 v[130:131], 6, v[164:165]
	v_lshl_add_u64 v[142:143], s[56:57], 0, v[130:131]
	s_nop 0
	s_nop 0
	v_lshlrev_b64 v[130:131], 6, v[166:167]
	v_lshl_add_u64 v[142:143], s[56:57], 0, v[130:131]
	s_nop 0
	s_nop 0
	s_nop 0
	s_nop 0
	s_nop 0
	s_nop 0
	v_mov_b32_e32 v170, v246
	s_nop 0
	v_mov_b32_e32 v190, v247
	v_mov_b32 v130, 0
	s_nop 0
	v_add_u32_e32 v130, v130, v174
	v_ashrrev_i32_e32 v131, 31, v130
	v_lshlrev_b64 v[132:133], 6, v[130:131]
	v_lshl_add_u64 v[144:145], s[56:57], 0, v[132:133]
	s_nop 0
	s_nop 0
	v_add_u32_e32 v132, 16, v130
	v_ashrrev_i32_e32 v133, 31, v132
	v_lshlrev_b64 v[132:133], 6, v[132:133]
	v_lshl_add_u64 v[144:145], s[56:57], 0, v[132:133]
	s_nop 0
	s_nop 0
	s_nop 0
	s_nop 0
	s_nop 0
	s_nop 0
	v_mov_b32_e32 v192, v248
	s_nop 0
	v_mov_b32_e32 v188, v249
	v_add_u32_e32 v132, 32, v130
	v_ashrrev_i32_e32 v133, 31, v132
	v_lshlrev_b64 v[132:133], 6, v[132:133]
	v_lshl_add_u64 v[144:145], s[56:57], 0, v[132:133]
	s_nop 0
	v_add_u32_e32 v130, 48, v130
	v_ashrrev_i32_e32 v131, 31, v130
	v_lshlrev_b64 v[130:131], 6, v[130:131]
	v_lshl_add_u64 v[142:143], s[56:57], 0, v[130:131]
	s_nop 0
	s_nop 0
	s_nop 0
	s_movk_i32 s4, 0x4000
	s_nop 0
	s_nop 0
	v_mov_b32_e32 v194, v250
	s_lshl_b32 s2, s66, 5
	v_lshl_add_u32 v198, v213, 3, s2
	v_ashrrev_i32_e32 v199, 31, v198
	v_mov_b32_e32 v196, v251
	v_add_u32_e32 v129, 0xffffc000, v160
	v_lshrrev_b32_e32 v129, 6, v129
	v_cmp_gt_i32_e32 vcc, s4, v160
	v_ashrrev_i32_e32 v128, 11, v160
	v_add_u32_e32 v129, 8, v129
	v_cndmask_b32_e32 v128, v129, v128, vcc
	v_mov_b32 v136, 0
	v_lshlrev_b64 v[132:133], 2, v[198:199]
	v_add_u32_e32 v130, v136, v128
	v_mov_b64_e32 v[128:129], s[10:11]
	v_mad_i64_i32 v[130:131], s[2:3], v130, s51, v[128:129]
	v_lshl_add_u64 v[130:131], v[130:131], 0, v[132:133]
	v_lshl_add_u64 v[134:135], v[130:131], 0, s[6:7]
	v_add_co_u32_e32 v130, vcc, s79, v130
	s_nop 1
	v_addc_co_u32_e32 v131, vcc, 0, v131, vcc
	global_load_dwordx4 v[152:155], v[130:131], off offset:3072
	global_load_dwordx4 v[156:159], v[134:135], off offset:16
	global_load_dwordx4 v[144:147], v[134:135], off offset:528
	global_load_dwordx4 v[148:151], v[134:135], off offset:512
	v_add_u32_e32 v131, 0xffffc080, v160
	v_lshrrev_b32_e32 v131, 6, v131
	v_cmp_gt_i32_e32 vcc, s4, v174
	v_ashrrev_i32_e32 v130, 11, v174
	v_add_u32_e32 v131, 8, v131
	v_cndmask_b32_e32 v130, v131, v130, vcc
	v_add_u32_e32 v130, v136, v130
	v_mad_i64_i32 v[128:129], s[2:3], v130, s51, v[128:129]
	v_lshl_add_u64 v[128:129], v[128:129], 0, v[132:133]
	v_lshl_add_u64 v[132:133], v[128:129], 0, s[6:7]
	v_add_co_u32_e32 v128, vcc, s79, v128
	v_readlane_b32 s2, v254, 40
	s_nop 0
	v_addc_co_u32_e32 v129, vcc, 0, v129, vcc
	global_load_dwordx4 v[140:143], v[128:129], off offset:3072
	global_load_dwordx4 v[136:139], v[132:133], off offset:16
	s_nop 0
	global_load_dwordx4 v[128:131], v[132:133], off offset:528
	s_nop 0
	global_load_dwordx4 v[132:135], v[132:133], off offset:512
	v_readlane_b32 s3, v254, 41
	s_waitcnt vmcnt(7)
	v_pk_fma_f32 v[202:203], v[126:127], v[172:173], v[154:155] op_sel_hi:[1,0,1]
	v_lshl_add_u64 v[198:199], v[198:199], 1, s[2:3]
	v_lshl_add_u64 v[204:205], v[198:199], 0, v[200:201]
	v_pk_fma_f32 v[200:201], v[124:125], v[172:173], v[152:153] op_sel_hi:[1,0,1]
	s_mov_b32 s2, 0x3e000000
	s_waitcnt vmcnt(6)
	v_pk_fma_f32 v[206:207], v[120:121], v[172:173], v[156:157] op_sel_hi:[1,0,1]
	v_pk_fma_f32 v[216:217], v[122:123], v[172:173], v[158:159] op_sel_hi:[1,0,1]
	v_pk_mul_f32 v[200:201], v[200:201], s[2:3] op_sel_hi:[1,0]
	v_pk_mul_f32 v[202:203], v[202:203], s[2:3] op_sel_hi:[1,0]
	v_pk_mul_f32 v[206:207], v[206:207], s[2:3] op_sel_hi:[1,0]
	v_pk_mul_f32 v[216:217], v[216:217], s[2:3] op_sel_hi:[1,0]
	v_cvt_pk_bf16_f32 v200, v200, v201
	v_cvt_pk_bf16_f32 v201, v202, v203
	v_cvt_pk_bf16_f32 v202, v206, v207
	v_cvt_pk_bf16_f32 v203, v216, v217
	global_store_dwordx4 v[204:205], v[200:203], off
	s_waitcnt vmcnt(6)
	v_pk_fma_f32 v[206:207], v[112:113], v[172:173], v[144:145] op_sel_hi:[1,0,1]
	v_lshl_add_u64 v[168:169], v[198:199], 0, v[168:169]
	s_waitcnt vmcnt(5)
; DI u32x4 pack8(const float* v) { u32x4 w; w.x = pk2(v[0], v[1]); w.y = pk2(v[2], v[3]); w.z = pk2(v[4], v[5]); w.w = pk2(v[6], v[7]); return w; }
; DI float silu(float x) { return x * __builtin_amdgcn_rcpf(1.f + ex2(-x * LOG2E)); }
;     template <int PN> DI void body(AccRef acc, const Unit& u, int wr, int wc, int fr, int fq) const {
;     ...
; #pragma unroll
;         for (int ai = 0; ai < 2; ++ai) {
;             const int rb = u.pm * 256 + ai * 128 + wr * 64 + fr;
;             int mb, pos0, kv0; row_info(rb, mb, pos0, kv0);
; #pragma unroll
;             for (int m = 0; m < 4; ++m) {
;                 const int row = rb + 16 * m, pos = pos0 + 16 * m, kvrow = kv0 + 16 * m;
;                 const float rinv = rinvh[ai][m];
;                 float v[2][8];
; #pragma unroll
;                 for (int bj = 0; bj < 2; ++bj)
; #pragma unroll
;                     for (int n = 0; n < 2; ++n)
; #pragma unroll
;                         for (int j = 0; j < 4; ++j) v[bj][4 * n + j] = acc[ai][bj][m][n][j] * rinv + cvh[ai][bj][n][j];
;     ...
;                 } else if constexpr (PN == 5 || PN == 6 || PN == 7) {
;                     bf16_t* dst = PN == 5 ? rv : (PN == 6 ? rg : sq);
; #pragma unroll
;                     for (int bj = 0; bj < 2; ++bj) {
;                         if constexpr (PN == 6) {
; #pragma unroll
;                             for (int j = 0; j < 8; ++j) v[bj][j] = silu(v[bj][j]);
;                         }
;                         if constexpr (PN == 7) {
; #pragma unroll
;                             for (int j = 0; j < 8; ++j) v[bj][j] *= 0.125f;
;                         }
;                         *(u32x4*)(dst + (size_t)row * 256 + bj * 128 + cl) = pack8(v[bj]);
;                     }
	v_pk_fma_f32 v[200:201], v[116:117], v[172:173], v[148:149] op_sel_hi:[1,0,1]
	v_pk_fma_f32 v[202:203], v[118:119], v[172:173], v[150:151] op_sel_hi:[1,0,1]
	v_pk_fma_f32 v[172:173], v[114:115], v[172:173], v[146:147] op_sel_hi:[1,0,1]
	v_pk_mul_f32 v[200:201], v[200:201], s[2:3] op_sel_hi:[1,0]
	v_pk_mul_f32 v[202:203], v[202:203], s[2:3] op_sel_hi:[1,0]
	v_pk_mul_f32 v[206:207], v[206:207], s[2:3] op_sel_hi:[1,0]
	v_pk_mul_f32 v[172:173], v[172:173], s[2:3] op_sel_hi:[1,0]
	v_cvt_pk_bf16_f32 v200, v200, v201
	v_cvt_pk_bf16_f32 v201, v202, v203
	v_cvt_pk_bf16_f32 v202, v206, v207
	v_cvt_pk_bf16_f32 v203, v172, v173
	global_store_dwordx4 v[204:205], v[200:203], off offset:256
	v_pk_fma_f32 v[172:173], v[108:109], v[162:163], v[152:153] op_sel_hi:[1,0,1]
	s_nop 0
	v_pk_fma_f32 v[200:201], v[110:111], v[162:163], v[154:155] op_sel_hi:[1,0,1]
	v_pk_mul_f32 v[172:173], v[172:173], s[2:3] op_sel_hi:[1,0]
	v_pk_mul_f32 v[202:203], v[200:201], s[2:3] op_sel_hi:[1,0]
	v_pk_fma_f32 v[200:201], v[104:105], v[162:163], v[156:157] op_sel_hi:[1,0,1]
	s_nop 0
	v_pk_mul_f32 v[204:205], v[200:201], s[2:3] op_sel_hi:[1,0]
	v_pk_fma_f32 v[200:201], v[106:107], v[162:163], v[158:159] op_sel_hi:[1,0,1]
	s_nop 0
	v_pk_mul_f32 v[206:207], v[200:201], s[2:3] op_sel_hi:[1,0]
	v_cvt_pk_bf16_f32 v200, v172, v173
	v_cvt_pk_bf16_f32 v201, v202, v203
	v_cvt_pk_bf16_f32 v202, v204, v205
	v_cvt_pk_bf16_f32 v203, v206, v207
	global_store_dwordx4 v[168:169], v[200:203], off
	v_pk_fma_f32 v[172:173], v[100:101], v[162:163], v[148:149] op_sel_hi:[1,0,1]
	s_nop 0
	v_pk_fma_f32 v[200:201], v[102:103], v[162:163], v[150:151] op_sel_hi:[1,0,1]
	v_pk_mul_f32 v[172:173], v[172:173], s[2:3] op_sel_hi:[1,0]
	v_pk_mul_f32 v[202:203], v[200:201], s[2:3] op_sel_hi:[1,0]
	v_pk_fma_f32 v[200:201], v[96:97], v[162:163], v[144:145] op_sel_hi:[1,0,1]
	v_pk_fma_f32 v[162:163], v[98:99], v[162:163], v[146:147] op_sel_hi:[1,0,1]
	v_pk_mul_f32 v[204:205], v[200:201], s[2:3] op_sel_hi:[1,0]
	v_pk_mul_f32 v[162:163], v[162:163], s[2:3] op_sel_hi:[1,0]
	v_cvt_pk_bf16_f32 v200, v172, v173
	v_cvt_pk_bf16_f32 v201, v202, v203
	v_cvt_pk_bf16_f32 v202, v204, v205
	v_cvt_pk_bf16_f32 v203, v162, v163
	v_lshlrev_b64 v[162:163], 9, v[164:165]
	global_store_dwordx4 v[168:169], v[200:203], off offset:256
	v_lshl_add_u64 v[168:169], v[198:199], 0, v[162:163]
	v_pk_fma_f32 v[162:163], v[92:93], v[170:171], v[152:153] op_sel_hi:[1,0,1]
	v_pk_fma_f32 v[164:165], v[94:95], v[170:171], v[154:155] op_sel_hi:[1,0,1]
	v_pk_fma_f32 v[172:173], v[88:89], v[170:171], v[156:157] op_sel_hi:[1,0,1]
	v_pk_fma_f32 v[200:201], v[90:91], v[170:171], v[158:159] op_sel_hi:[1,0,1]
	v_pk_mul_f32 v[162:163], v[162:163], s[2:3] op_sel_hi:[1,0]
	v_pk_mul_f32 v[164:165], v[164:165], s[2:3] op_sel_hi:[1,0]
	v_pk_mul_f32 v[172:173], v[172:173], s[2:3] op_sel_hi:[1,0]
	v_pk_mul_f32 v[200:201], v[200:201], s[2:3] op_sel_hi:[1,0]
	v_cvt_pk_bf16_f32 v162, v162, v163
	v_cvt_pk_bf16_f32 v163, v164, v165
	v_cvt_pk_bf16_f32 v164, v172, v173
	v_cvt_pk_bf16_f32 v165, v200, v201
	global_store_dwordx4 v[168:169], v[162:165], off
	v_pk_fma_f32 v[172:173], v[80:81], v[170:171], v[144:145] op_sel_hi:[1,0,1]
	v_pk_fma_f32 v[152:153], v[76:77], v[190:191], v[152:153] op_sel_hi:[1,0,1]
	v_pk_fma_f32 v[162:163], v[84:85], v[170:171], v[148:149] op_sel_hi:[1,0,1]
	v_pk_fma_f32 v[164:165], v[86:87], v[170:171], v[150:151] op_sel_hi:[1,0,1]
	v_pk_fma_f32 v[170:171], v[82:83], v[170:171], v[146:147] op_sel_hi:[1,0,1]
	v_pk_mul_f32 v[162:163], v[162:163], s[2:3] op_sel_hi:[1,0]
	v_pk_mul_f32 v[164:165], v[164:165], s[2:3] op_sel_hi:[1,0]
	v_pk_mul_f32 v[172:173], v[172:173], s[2:3] op_sel_hi:[1,0]
	v_pk_mul_f32 v[170:171], v[170:171], s[2:3] op_sel_hi:[1,0]
	v_cvt_pk_bf16_f32 v162, v162, v163
	v_cvt_pk_bf16_f32 v163, v164, v165
	v_cvt_pk_bf16_f32 v164, v172, v173
	v_cvt_pk_bf16_f32 v165, v170, v171
	v_pk_fma_f32 v[154:155], v[78:79], v[190:191], v[154:155] op_sel_hi:[1,0,1]
	v_pk_fma_f32 v[156:157], v[72:73], v[190:191], v[156:157] op_sel_hi:[1,0,1]
	v_pk_fma_f32 v[158:159], v[74:75], v[190:191], v[158:159] op_sel_hi:[1,0,1]
	global_store_dwordx4 v[168:169], v[162:165], off offset:256
	v_pk_mul_f32 v[152:153], v[152:153], s[2:3] op_sel_hi:[1,0]
	v_pk_mul_f32 v[154:155], v[154:155], s[2:3] op_sel_hi:[1,0]
	v_lshlrev_b64 v[162:163], 9, v[166:167]
	v_pk_mul_f32 v[156:157], v[156:157], s[2:3] op_sel_hi:[1,0]
	v_pk_mul_f32 v[158:159], v[158:159], s[2:3] op_sel_hi:[1,0]
	v_lshl_add_u64 v[162:163], v[198:199], 0, v[162:163]
	v_cvt_pk_bf16_f32 v152, v152, v153
	v_cvt_pk_bf16_f32 v153, v154, v155
	v_cvt_pk_bf16_f32 v154, v156, v157
	v_cvt_pk_bf16_f32 v155, v158, v159
	v_pk_fma_f32 v[144:145], v[64:65], v[190:191], v[144:145] op_sel_hi:[1,0,1]
	global_store_dwordx4 v[162:163], v[152:155], off
	v_pk_fma_f32 v[148:149], v[68:69], v[190:191], v[148:149] op_sel_hi:[1,0,1]
	v_pk_fma_f32 v[150:151], v[70:71], v[190:191], v[150:151] op_sel_hi:[1,0,1]
	v_pk_mul_f32 v[152:153], v[144:145], s[2:3] op_sel_hi:[1,0]
	v_pk_fma_f32 v[144:145], v[66:67], v[190:191], v[146:147] op_sel_hi:[1,0,1]
	v_pk_mul_f32 v[148:149], v[148:149], s[2:3] op_sel_hi:[1,0]
	v_pk_mul_f32 v[150:151], v[150:151], s[2:3] op_sel_hi:[1,0]
	v_pk_mul_f32 v[154:155], v[144:145], s[2:3] op_sel_hi:[1,0]
	v_cvt_pk_bf16_f32 v144, v148, v149
	v_cvt_pk_bf16_f32 v145, v150, v151
	v_cvt_pk_bf16_f32 v146, v152, v153
	v_cvt_pk_bf16_f32 v147, v154, v155
	global_store_dwordx4 v[162:163], v[144:147], off offset:256
	s_waitcnt vmcnt(10)
; DI u32x4 pack8(const float* v) { u32x4 w; w.x = pk2(v[0], v[1]); w.y = pk2(v[2], v[3]); w.z = pk2(v[4], v[5]); w.w = pk2(v[6], v[7]); return w; }
; DI float silu(float x) { return x * __builtin_amdgcn_rcpf(1.f + ex2(-x * LOG2E)); }
;     template <int PN> DI void body(AccRef acc, const Unit& u, int wr, int wc, int fr, int fq) const {
;     ...
; #pragma unroll
;         for (int ai = 0; ai < 2; ++ai) {
;             const int rb = u.pm * 256 + ai * 128 + wr * 64 + fr;
;             int mb, pos0, kv0; row_info(rb, mb, pos0, kv0);
; #pragma unroll
;             for (int m = 0; m < 4; ++m) {
;                 const int row = rb + 16 * m, pos = pos0 + 16 * m, kvrow = kv0 + 16 * m;
;                 const float rinv = rinvh[ai][m];
;                 float v[2][8];
; #pragma unroll
;                 for (int bj = 0; bj < 2; ++bj)
; #pragma unroll
;                     for (int n = 0; n < 2; ++n)
; #pragma unroll
;                         for (int j = 0; j < 4; ++j) v[bj][4 * n + j] = acc[ai][bj][m][n][j] * rinv + cvh[ai][bj][n][j];
;     ...
;                 } else if constexpr (PN == 5 || PN == 6 || PN == 7) {
;                     bf16_t* dst = PN == 5 ? rv : (PN == 6 ? rg : sq);
; #pragma unroll
;                     for (int bj = 0; bj < 2; ++bj) {
;                         if constexpr (PN == 6) {
; #pragma unroll
;                             for (int j = 0; j < 8; ++j) v[bj][j] = silu(v[bj][j]);
;                         }
;                         if constexpr (PN == 7) {
; #pragma unroll
;                             for (int j = 0; j < 8; ++j) v[bj][j] *= 0.125f;
;                         }
;                         *(u32x4*)(dst + (size_t)row * 256 + bj * 128 + cl) = pack8(v[bj]);
;                     }
	v_pk_fma_f32 v[150:151], v[56:57], v[192:193], v[136:137] op_sel_hi:[1,0,1]
	v_pk_fma_f32 v[152:153], v[58:59], v[192:193], v[138:139] op_sel_hi:[1,0,1]
	v_lshlrev_b64 v[144:145], 9, v[174:175]
	v_lshl_add_u64 v[148:149], v[198:199], 0, v[144:145]
	v_pk_fma_f32 v[144:145], v[60:61], v[192:193], v[140:141] op_sel_hi:[1,0,1]
	v_pk_fma_f32 v[146:147], v[62:63], v[192:193], v[142:143] op_sel_hi:[1,0,1]
	v_pk_mul_f32 v[144:145], v[144:145], s[2:3] op_sel_hi:[1,0]
	v_pk_mul_f32 v[146:147], v[146:147], s[2:3] op_sel_hi:[1,0]
	v_pk_mul_f32 v[150:151], v[150:151], s[2:3] op_sel_hi:[1,0]
	v_pk_mul_f32 v[152:153], v[152:153], s[2:3] op_sel_hi:[1,0]
	v_cvt_pk_bf16_f32 v144, v144, v145
	v_cvt_pk_bf16_f32 v145, v146, v147
	v_cvt_pk_bf16_f32 v146, v150, v151
	v_cvt_pk_bf16_f32 v147, v152, v153
	global_store_dwordx4 v[148:149], v[144:147], off
	s_waitcnt vmcnt(10)
	v_pk_fma_f32 v[150:151], v[48:49], v[192:193], v[128:129] op_sel_hi:[1,0,1]
	v_pk_fma_f32 v[152:153], v[50:51], v[192:193], v[130:131] op_sel_hi:[1,0,1]
	s_waitcnt vmcnt(9)
	v_pk_fma_f32 v[144:145], v[52:53], v[192:193], v[132:133] op_sel_hi:[1,0,1]
	v_pk_fma_f32 v[146:147], v[54:55], v[192:193], v[134:135] op_sel_hi:[1,0,1]
	v_pk_mul_f32 v[144:145], v[144:145], s[2:3] op_sel_hi:[1,0]
	v_pk_mul_f32 v[146:147], v[146:147], s[2:3] op_sel_hi:[1,0]
	v_pk_mul_f32 v[150:151], v[150:151], s[2:3] op_sel_hi:[1,0]
	v_pk_mul_f32 v[152:153], v[152:153], s[2:3] op_sel_hi:[1,0]
	v_cvt_pk_bf16_f32 v144, v144, v145
	v_cvt_pk_bf16_f32 v145, v146, v147
	v_cvt_pk_bf16_f32 v146, v150, v151
	v_cvt_pk_bf16_f32 v147, v152, v153
	global_store_dwordx4 v[148:149], v[144:147], off offset:256
	v_pk_fma_f32 v[150:151], v[40:41], v[188:189], v[136:137] op_sel_hi:[1,0,1]
	v_pk_fma_f32 v[152:153], v[42:43], v[188:189], v[138:139] op_sel_hi:[1,0,1]
	v_add_u32_e32 v144, 0x90, v160
	v_ashrrev_i32_e32 v145, 31, v144
	v_lshlrev_b64 v[144:145], 9, v[144:145]
	v_lshl_add_u64 v[148:149], v[198:199], 0, v[144:145]
	v_pk_fma_f32 v[144:145], v[44:45], v[188:189], v[140:141] op_sel_hi:[1,0,1]
	v_pk_fma_f32 v[146:147], v[46:47], v[188:189], v[142:143] op_sel_hi:[1,0,1]
	v_pk_mul_f32 v[144:145], v[144:145], s[2:3] op_sel_hi:[1,0]
	v_pk_mul_f32 v[146:147], v[146:147], s[2:3] op_sel_hi:[1,0]
	v_pk_mul_f32 v[150:151], v[150:151], s[2:3] op_sel_hi:[1,0]
	v_pk_mul_f32 v[152:153], v[152:153], s[2:3] op_sel_hi:[1,0]
	v_cvt_pk_bf16_f32 v144, v144, v145
	v_cvt_pk_bf16_f32 v145, v146, v147
	v_cvt_pk_bf16_f32 v146, v150, v151
	v_cvt_pk_bf16_f32 v147, v152, v153
	global_store_dwordx4 v[148:149], v[144:147], off
	v_pk_fma_f32 v[150:151], v[28:29], v[188:189], v[128:129] op_sel_hi:[1,0,1]
	v_pk_fma_f32 v[152:153], v[30:31], v[188:189], v[130:131] op_sel_hi:[1,0,1]
	v_pk_fma_f32 v[144:145], v[36:37], v[188:189], v[132:133] op_sel_hi:[1,0,1]
	v_pk_fma_f32 v[146:147], v[38:39], v[188:189], v[134:135] op_sel_hi:[1,0,1]
	v_pk_mul_f32 v[144:145], v[144:145], s[2:3] op_sel_hi:[1,0]
	v_pk_mul_f32 v[146:147], v[146:147], s[2:3] op_sel_hi:[1,0]
	v_pk_mul_f32 v[150:151], v[150:151], s[2:3] op_sel_hi:[1,0]
	v_pk_mul_f32 v[152:153], v[152:153], s[2:3] op_sel_hi:[1,0]
	v_cvt_pk_bf16_f32 v144, v144, v145
	v_cvt_pk_bf16_f32 v145, v146, v147
	v_cvt_pk_bf16_f32 v146, v150, v151
	v_cvt_pk_bf16_f32 v147, v152, v153
	global_store_dwordx4 v[148:149], v[144:147], off offset:256
	v_pk_fma_f32 v[150:151], v[24:25], v[194:195], v[136:137] op_sel_hi:[1,0,1]
	v_pk_fma_f32 v[152:153], v[26:27], v[194:195], v[138:139] op_sel_hi:[1,0,1]
	v_add_u32_e32 v144, 0xa0, v160
	v_ashrrev_i32_e32 v145, 31, v144
	v_lshlrev_b64 v[144:145], 9, v[144:145]
	v_lshl_add_u64 v[148:149], v[198:199], 0, v[144:145]
	v_pk_fma_f32 v[144:145], v[32:33], v[194:195], v[140:141] op_sel_hi:[1,0,1]
	v_pk_fma_f32 v[146:147], v[34:35], v[194:195], v[142:143] op_sel_hi:[1,0,1]
	v_pk_mul_f32 v[144:145], v[144:145], s[2:3] op_sel_hi:[1,0]
	v_pk_mul_f32 v[146:147], v[146:147], s[2:3] op_sel_hi:[1,0]
	v_pk_mul_f32 v[150:151], v[150:151], s[2:3] op_sel_hi:[1,0]
	v_pk_mul_f32 v[152:153], v[152:153], s[2:3] op_sel_hi:[1,0]
	v_cvt_pk_bf16_f32 v144, v144, v145
	v_cvt_pk_bf16_f32 v145, v146, v147
	v_cvt_pk_bf16_f32 v146, v150, v151
	v_cvt_pk_bf16_f32 v147, v152, v153
	global_store_dwordx4 v[148:149], v[144:147], off
	v_pk_fma_f32 v[150:151], v[16:17], v[194:195], v[128:129] op_sel_hi:[1,0,1]
	v_pk_fma_f32 v[152:153], v[18:19], v[194:195], v[130:131] op_sel_hi:[1,0,1]
	v_pk_fma_f32 v[144:145], v[20:21], v[194:195], v[132:133] op_sel_hi:[1,0,1]
	v_pk_fma_f32 v[146:147], v[22:23], v[194:195], v[134:135] op_sel_hi:[1,0,1]
	v_pk_mul_f32 v[144:145], v[144:145], s[2:3] op_sel_hi:[1,0]
	v_pk_mul_f32 v[146:147], v[146:147], s[2:3] op_sel_hi:[1,0]
	v_pk_mul_f32 v[150:151], v[150:151], s[2:3] op_sel_hi:[1,0]
	v_pk_mul_f32 v[152:153], v[152:153], s[2:3] op_sel_hi:[1,0]
	v_cvt_pk_bf16_f32 v144, v144, v145
	v_cvt_pk_bf16_f32 v145, v146, v147
	v_cvt_pk_bf16_f32 v146, v150, v151
	v_cvt_pk_bf16_f32 v147, v152, v153
	global_store_dwordx4 v[148:149], v[144:147], off offset:256
	v_pk_fma_f32 v[136:137], v[8:9], v[196:197], v[136:137] op_sel_hi:[1,0,1]
	v_pk_fma_f32 v[140:141], v[12:13], v[196:197], v[140:141] op_sel_hi:[1,0,1]
	v_add_u32_e32 v144, 0xb0, v160
	v_ashrrev_i32_e32 v145, 31, v144
	v_pk_fma_f32 v[142:143], v[14:15], v[196:197], v[142:143] op_sel_hi:[1,0,1]
	v_pk_mul_f32 v[146:147], v[136:137], s[2:3] op_sel_hi:[1,0]
	v_pk_fma_f32 v[136:137], v[10:11], v[196:197], v[138:139] op_sel_hi:[1,0,1]
	v_lshlrev_b64 v[144:145], 9, v[144:145]
	v_pk_mul_f32 v[140:141], v[140:141], s[2:3] op_sel_hi:[1,0]
	v_pk_mul_f32 v[142:143], v[142:143], s[2:3] op_sel_hi:[1,0]
	v_pk_mul_f32 v[148:149], v[136:137], s[2:3] op_sel_hi:[1,0]
	v_lshl_add_u64 v[144:145], v[198:199], 0, v[144:145]
	v_cvt_pk_bf16_f32 v136, v140, v141
	v_cvt_pk_bf16_f32 v137, v142, v143
	v_cvt_pk_bf16_f32 v138, v146, v147
	v_cvt_pk_bf16_f32 v139, v148, v149
	v_pk_fma_f32 v[128:129], v[0:1], v[196:197], v[128:129] op_sel_hi:[1,0,1]
	global_store_dwordx4 v[144:145], v[136:139], off
	v_pk_fma_f32 v[132:133], v[4:5], v[196:197], v[132:133] op_sel_hi:[1,0,1]
	v_pk_fma_f32 v[134:135], v[6:7], v[196:197], v[134:135] op_sel_hi:[1,0,1]
	v_pk_mul_f32 v[136:137], v[128:129], s[2:3] op_sel_hi:[1,0]
	v_pk_fma_f32 v[128:129], v[2:3], v[196:197], v[130:131] op_sel_hi:[1,0,1]
	v_pk_mul_f32 v[132:133], v[132:133], s[2:3] op_sel_hi:[1,0]
	v_pk_mul_f32 v[134:135], v[134:135], s[2:3] op_sel_hi:[1,0]
	v_pk_mul_f32 v[138:139], v[128:129], s[2:3] op_sel_hi:[1,0]
	v_cvt_pk_bf16_f32 v128, v132, v133
	v_cvt_pk_bf16_f32 v129, v134, v135
	v_cvt_pk_bf16_f32 v130, v136, v137
	v_cvt_pk_bf16_f32 v131, v138, v139
	global_store_dwordx4 v[144:145], v[128:131], off offset:256

; DI u32x4 pack8(const float* v) { u32x4 w; w.x = pk2(v[0], v[1]); w.y = pk2(v[2], v[3]); w.z = pk2(v[4], v[5]); w.w = pk2(v[6], v[7]); return w; }
; DI float ex2(float x) { return __builtin_amdgcn_exp2f(x); }
; DI float sum16(const float* p) { const f32x4* q = (const f32x4*)p; f32x4 a = q[0], b = q[1], c = q[2], d = q[3]; f32x4 s = (a + b) + (c + d); return (s[0] + s[1]) + (s[2] + s[3]); }
; DI float silu(float x) { return x * __builtin_amdgcn_rcpf(1.f + ex2(-x * LOG2E)); }
;     template <int PN> DI void body(AccRef acc, const Unit& u, int wr, int wc, int fr, int fq) const {
;     ...
; #pragma unroll
;         for (int ai = 0; ai < 2; ++ai) {
;             const int rb_ = u.pm * 256 + ai * 128 + wr * 64 + fr;
; #pragma unroll
;             for (int m = 0; m < 4; ++m) rinvh[ai][m] = rsqrtf(sum16(ssq + (size_t)(rb_ + 16 * m + zdep) * 16) * (1.f / 1024.f) + EPS);
;             asm volatile("v_mov_b32 %0, 0" : "=v"(zdep) : "v"(rinvh[ai][0]), "v"(rinvh[ai][1]), "v"(rinvh[ai][2]), "v"(rinvh[ai][3]));
;         }
; #pragma unroll
;         for (int ai = 0; ai < 2; ++ai) {
;             const int rb_ = u.pm * 256 + ai * 128 + wr * 64 + fr;
;             int mb_, p_, k_; row_info(rb_, mb_, p_, k_);
; #pragma unroll
;             for (int bj = 0; bj < 2; ++bj)
; #pragma unroll
;                 for (int n = 0; n < 2; ++n) cvh[ai][bj][n] = *(const f32x4*)(cv + (size_t)(mb_ + zdep) * NIN + PN * 256 + bj * 128 + cl + 4 * n);
;         }
;     ...
;                 } else if constexpr (PN == 5 || PN == 6 || PN == 7) {
;                     bf16_t* dst = PN == 5 ? rv : (PN == 6 ? rg : sq);
; #pragma unroll
;                     for (int bj = 0; bj < 2; ++bj) {
;                         if constexpr (PN == 6) {
; #pragma unroll
;                             for (int j = 0; j < 8; ++j) v[bj][j] = silu(v[bj][j]);
;                         }
;                         if constexpr (PN == 7) {
; #pragma unroll
;                             for (int j = 0; j < 8; ++j) v[bj][j] *= 0.125f;
;                         }
;                         *(u32x4*)(dst + (size_t)row * 256 + bj * 128 + cl) = pack8(v[bj]);
;                     }
.LBB0_363:
	s_and_b64 vcc, exec, s[2:3]
	s_cbranch_vccz .LBB0_365
	s_lshl_b32 s2, s53, 6
	s_lshl_b32 s3, s34, 8
	s_add_i32 s2, s2, s3
	v_add_u32_e32 v160, s2, v214
	v_ashrrev_i32_e32 v161, 31, v160
	v_lshlrev_b64 v[128:129], 6, v[160:161]
	v_lshl_add_u64 v[140:141], s[56:57], 0, v[128:129]
	s_nop 0
	v_add_u32_e32 v196, 16, v160
	v_ashrrev_i32_e32 v197, 31, v196
	s_mov_b32 s2, 0x358637bd
	s_mov_b32 s4, 0x3a800000
	v_add_u32_e32 v194, 32, v160
	v_ashrrev_i32_e32 v195, 31, v194
	v_add_u32_e32 v188, 48, v160
	v_ashrrev_i32_e32 v189, 31, v188
	v_add_u32_e32 v172, 0x80, v160
	s_mov_b64 s[6:7], 0x125800
	v_lshlrev_b64 v[200:201], 9, v[160:161]
	v_ashrrev_i32_e32 v173, 31, v172
	s_nop 0
	v_lshlrev_b64 v[128:129], 6, v[196:197]
	v_lshl_add_u64 v[140:141], s[56:57], 0, v[128:129]
	s_nop 0
	v_lshlrev_b64 v[196:197], 9, v[196:197]
	s_nop 0
	v_mov_b64_e32 v[128:129], s[2:3]
	s_nop 0
	s_nop 0
	s_nop 0
	v_mov_b32_e32 v198, v244
	s_nop 0
	v_mov_b32_e32 v190, v245
	v_lshlrev_b64 v[130:131], 6, v[194:195]
	v_lshl_add_u64 v[142:143], s[56:57], 0, v[130:131]
	s_nop 0
	s_nop 0
	v_lshlrev_b64 v[130:131], 6, v[188:189]
	v_lshl_add_u64 v[142:143], s[56:57], 0, v[130:131]
	s_nop 0
	v_lshlrev_b64 v[188:189], 9, v[188:189]
	s_nop 0
	s_nop 0
	s_nop 0
	s_nop 0
	s_nop 0
	v_mov_b32_e32 v192, v246
	s_nop 0
	v_mov_b32_e32 v174, v247
	v_mov_b32 v130, 0
	s_nop 0
	v_add_u32_e32 v130, v130, v172
	v_ashrrev_i32_e32 v131, 31, v130
	v_lshlrev_b64 v[132:133], 6, v[130:131]
	v_lshl_add_u64 v[144:145], s[56:57], 0, v[132:133]
	s_nop 0
	s_nop 0
	v_add_u32_e32 v132, 16, v130
	v_ashrrev_i32_e32 v133, 31, v132
	v_lshlrev_b64 v[132:133], 6, v[132:133]
	v_lshl_add_u64 v[144:145], s[56:57], 0, v[132:133]
	s_nop 0
	s_nop 0
	s_nop 0
	s_nop 0
	s_nop 0
	s_nop 0
	v_mov_b32_e32 v170, v248
	s_nop 0
	v_mov_b32_e32 v164, v249
	v_add_u32_e32 v132, 32, v130
	v_ashrrev_i32_e32 v133, 31, v132
	v_lshlrev_b64 v[132:133], 6, v[132:133]
	v_lshl_add_u64 v[144:145], s[56:57], 0, v[132:133]
	s_nop 0
	v_add_u32_e32 v130, 48, v130
	v_ashrrev_i32_e32 v131, 31, v130
	v_lshlrev_b64 v[130:131], 6, v[130:131]
	v_lshl_add_u64 v[142:143], s[56:57], 0, v[130:131]
	s_nop 0
	s_nop 0
	s_nop 0
	s_movk_i32 s4, 0x4000
	s_nop 0
	s_nop 0
	v_mov_b32_e32 v166, v250
	s_lshl_b32 s2, s66, 5
	v_lshl_add_u32 v168, v213, 3, s2
	v_ashrrev_i32_e32 v169, 31, v168
	v_mov_b32_e32 v162, v251
	v_add_u32_e32 v129, 0xffffc000, v160
	v_lshrrev_b32_e32 v129, 6, v129
	v_cmp_gt_i32_e32 vcc, s4, v160
	v_ashrrev_i32_e32 v128, 11, v160
	v_add_u32_e32 v129, 8, v129
	v_cndmask_b32_e32 v128, v129, v128, vcc
	v_mov_b32 v136, 0
	v_lshlrev_b64 v[132:133], 2, v[168:169]
	v_add_u32_e32 v130, v136, v128
	v_mov_b64_e32 v[128:129], s[10:11]
	v_mad_i64_i32 v[130:131], s[2:3], v130, s51, v[128:129]
	v_lshl_add_u64 v[130:131], v[130:131], 0, v[132:133]
	v_lshl_add_u64 v[134:135], v[130:131], 0, s[6:7]
	v_add_co_u32_e32 v130, vcc, s79, v130
	s_nop 1
	v_addc_co_u32_e32 v131, vcc, 0, v131, vcc
	global_load_dwordx4 v[156:159], v[130:131], off offset:2048
	global_load_dwordx4 v[152:155], v[134:135], off offset:16
	global_load_dwordx4 v[144:147], v[134:135], off offset:528
	global_load_dwordx4 v[148:151], v[134:135], off offset:512
	v_add_u32_e32 v131, 0xffffc080, v160
	v_lshrrev_b32_e32 v131, 6, v131
	v_cmp_gt_i32_e32 vcc, s4, v172
	v_ashrrev_i32_e32 v130, 11, v172
	v_add_u32_e32 v131, 8, v131
	v_cndmask_b32_e32 v130, v131, v130, vcc
	v_add_u32_e32 v130, v136, v130
	v_mad_i64_i32 v[128:129], s[2:3], v130, s51, v[128:129]
	v_readlane_b32 s2, v254, 42
	v_lshl_add_u64 v[128:129], v[128:129], 0, v[132:133]
	v_readlane_b32 s3, v254, 43
	v_lshl_add_u64 v[132:133], v[128:129], 0, s[6:7]
	v_add_co_u32_e32 v128, vcc, s79, v128
	v_lshl_add_u64 v[168:169], v[168:169], 1, s[2:3]
	s_nop 0
	v_addc_co_u32_e32 v129, vcc, 0, v129, vcc
	v_lshl_add_u64 v[200:201], v[168:169], 0, v[200:201]
	global_load_dwordx4 v[140:143], v[128:129], off offset:2048
	global_load_dwordx4 v[136:139], v[132:133], off offset:16
	s_nop 0
	global_load_dwordx4 v[128:131], v[132:133], off offset:528
	s_nop 0
	global_load_dwordx4 v[132:135], v[132:133], off offset:512
	v_lshl_add_u64 v[196:197], v[168:169], 0, v[196:197]
	v_lshl_add_u64 v[188:189], v[168:169], 0, v[188:189]
	s_waitcnt vmcnt(7)
	v_pk_fma_f32 v[202:203], v[124:125], v[198:199], v[156:157] op_sel_hi:[1,0,1]
	s_nop 0
	v_mul_f32_e32 v161, 0xbfb8aa3b, v202
	v_exp_f32_e32 v161, v161
	s_nop 0
	v_add_f32_e32 v161, 1.0, v161
	v_rcp_f32_e32 v204, v161
	v_mul_f32_e32 v161, 0xbfb8aa3b, v203
	v_exp_f32_e32 v161, v161
	s_nop 0
	v_add_f32_e32 v161, 1.0, v161
	v_rcp_f32_e32 v205, v161
	s_nop 0
	v_pk_mul_f32 v[202:203], v[202:203], v[204:205]
	v_pk_fma_f32 v[204:205], v[126:127], v[198:199], v[158:159] op_sel_hi:[1,0,1]
	v_cvt_pk_bf16_f32 v202, v202, v203
	v_mul_f32_e32 v161, 0xbfb8aa3b, v204
	v_exp_f32_e32 v161, v161
	s_nop 0
	v_add_f32_e32 v161, 1.0, v161
	v_rcp_f32_e32 v206, v161
	v_mul_f32_e32 v161, 0xbfb8aa3b, v205
	v_exp_f32_e32 v161, v161
	s_nop 0
	v_add_f32_e32 v161, 1.0, v161
	v_rcp_f32_e32 v207, v161
	s_nop 0
	v_pk_mul_f32 v[204:205], v[204:205], v[206:207]
	s_waitcnt vmcnt(6)
	v_pk_fma_f32 v[206:207], v[120:121], v[198:199], v[152:153] op_sel_hi:[1,0,1]
	v_cvt_pk_bf16_f32 v203, v204, v205
	v_mul_f32_e32 v161, 0xbfb8aa3b, v206
	v_exp_f32_e32 v161, v161
	s_nop 0
	v_add_f32_e32 v161, 1.0, v161
	v_rcp_f32_e32 v216, v161
	v_mul_f32_e32 v161, 0xbfb8aa3b, v207
	v_exp_f32_e32 v161, v161
	s_nop 0
	v_add_f32_e32 v161, 1.0, v161
	v_rcp_f32_e32 v217, v161
	s_nop 0
	v_pk_mul_f32 v[206:207], v[206:207], v[216:217]
	v_pk_fma_f32 v[216:217], v[122:123], v[198:199], v[154:155] op_sel_hi:[1,0,1]
	v_cvt_pk_bf16_f32 v204, v206, v207
	v_mul_f32_e32 v161, 0xbfb8aa3b, v216
	v_exp_f32_e32 v161, v161
	s_nop 0
	v_add_f32_e32 v161, 1.0, v161
	v_rcp_f32_e32 v218, v161
	v_mul_f32_e32 v161, 0xbfb8aa3b, v217
	v_exp_f32_e32 v161, v161
	s_nop 0
	v_add_f32_e32 v161, 1.0, v161
	v_rcp_f32_e32 v219, v161
	s_nop 0
	v_pk_mul_f32 v[216:217], v[216:217], v[218:219]
	s_nop 0
	v_cvt_pk_bf16_f32 v205, v216, v217
	global_store_dwordx4 v[200:201], v[202:205], off
	s_waitcnt vmcnt(5)
; DI float ex2(float x) { return __builtin_amdgcn_exp2f(x); }
; DI float silu(float x) { return x * __builtin_amdgcn_rcpf(1.f + ex2(-x * LOG2E)); }
;     template <int PN> DI void body(AccRef acc, const Unit& u, int wr, int wc, int fr, int fq) const {
;     ...
; #pragma unroll
;         for (int ai = 0; ai < 2; ++ai) {
;             const int rb = u.pm * 256 + ai * 128 + wr * 64 + fr;
;             int mb, pos0, kv0; row_info(rb, mb, pos0, kv0);
; #pragma unroll
;             for (int m = 0; m < 4; ++m) {
;                 const int row = rb + 16 * m, pos = pos0 + 16 * m, kvrow = kv0 + 16 * m;
;                 const float rinv = rinvh[ai][m];
;                 float v[2][8];
; #pragma unroll
;                 for (int bj = 0; bj < 2; ++bj)
; #pragma unroll
;                     for (int n = 0; n < 2; ++n)
; #pragma unroll
;                         for (int j = 0; j < 4; ++j) v[bj][4 * n + j] = acc[ai][bj][m][n][j] * rinv + cvh[ai][bj][n][j];
;     ...
;                             for (int j = 0; j < 8; ++j) v[bj][j] = silu(v[bj][j]);
	s_nop 0
	v_pk_fma_f32 v[202:203], v[116:117], v[198:199], v[148:149] op_sel_hi:[1,0,1]
	s_nop 0
	v_mul_f32_e32 v161, 0xbfb8aa3b, v202
	v_exp_f32_e32 v161, v161
	s_nop 0
	v_add_f32_e32 v161, 1.0, v161
	v_rcp_f32_e32 v204, v161
	v_mul_f32_e32 v161, 0xbfb8aa3b, v203
	v_exp_f32_e32 v161, v161
	s_nop 0
	v_add_f32_e32 v161, 1.0, v161
	v_rcp_f32_e32 v205, v161
	s_nop 0
	v_pk_mul_f32 v[202:203], v[202:203], v[204:205]
	v_pk_fma_f32 v[204:205], v[118:119], v[198:199], v[150:151] op_sel_hi:[1,0,1]
	v_cvt_pk_bf16_f32 v202, v202, v203
	v_mul_f32_e32 v161, 0xbfb8aa3b, v204
	v_exp_f32_e32 v161, v161
	s_nop 0
	v_add_f32_e32 v161, 1.0, v161
	v_rcp_f32_e32 v206, v161
	v_mul_f32_e32 v161, 0xbfb8aa3b, v205
	v_exp_f32_e32 v161, v161
	s_nop 0
	v_add_f32_e32 v161, 1.0, v161
	v_rcp_f32_e32 v207, v161
	s_nop 0
	v_pk_mul_f32 v[204:205], v[204:205], v[206:207]
	v_pk_fma_f32 v[206:207], v[112:113], v[198:199], v[144:145] op_sel_hi:[1,0,1]
	v_pk_fma_f32 v[198:199], v[114:115], v[198:199], v[146:147] op_sel_hi:[1,0,1]
	v_mul_f32_e32 v161, 0xbfb8aa3b, v206
	v_exp_f32_e32 v161, v161
	v_cvt_pk_bf16_f32 v203, v204, v205
	v_add_f32_e32 v161, 1.0, v161
	v_rcp_f32_e32 v216, v161
	v_mul_f32_e32 v161, 0xbfb8aa3b, v207
	v_exp_f32_e32 v161, v161
	s_nop 0
	v_add_f32_e32 v161, 1.0, v161
	v_rcp_f32_e32 v217, v161
	v_mul_f32_e32 v161, 0xbfb8aa3b, v198
	v_exp_f32_e32 v161, v161
	v_pk_mul_f32 v[206:207], v[206:207], v[216:217]
	s_nop 0
	v_cvt_pk_bf16_f32 v204, v206, v207
	v_add_f32_e32 v161, 1.0, v161
	v_rcp_f32_e32 v216, v161
	v_mul_f32_e32 v161, 0xbfb8aa3b, v199
	v_exp_f32_e32 v161, v161
	s_nop 0
	v_add_f32_e32 v161, 1.0, v161
	v_rcp_f32_e32 v217, v161
	s_nop 0
	v_pk_mul_f32 v[198:199], v[198:199], v[216:217]
	s_nop 0
	v_cvt_pk_bf16_f32 v205, v198, v199
	v_pk_fma_f32 v[198:199], v[108:109], v[190:191], v[156:157] op_sel_hi:[1,0,1]
	global_store_dwordx4 v[200:201], v[202:205], off offset:256
	v_mul_f32_e32 v161, 0xbfb8aa3b, v198
	v_exp_f32_e32 v161, v161
	s_nop 0
	v_add_f32_e32 v161, 1.0, v161
	v_rcp_f32_e32 v200, v161
	v_mul_f32_e32 v161, 0xbfb8aa3b, v199
	v_exp_f32_e32 v161, v161
	s_nop 0
	v_add_f32_e32 v161, 1.0, v161
	v_rcp_f32_e32 v201, v161
	s_nop 0
	v_pk_mul_f32 v[198:199], v[198:199], v[200:201]
	v_pk_fma_f32 v[200:201], v[110:111], v[190:191], v[158:159] op_sel_hi:[1,0,1]
	v_cvt_pk_bf16_f32 v198, v198, v199
	v_mul_f32_e32 v161, 0xbfb8aa3b, v200
	v_exp_f32_e32 v161, v161
	s_nop 0
	v_add_f32_e32 v161, 1.0, v161
	v_rcp_f32_e32 v202, v161
	v_mul_f32_e32 v161, 0xbfb8aa3b, v201
	v_exp_f32_e32 v161, v161
	s_nop 0
	v_add_f32_e32 v161, 1.0, v161
	v_rcp_f32_e32 v203, v161
	s_nop 0
	v_pk_mul_f32 v[200:201], v[200:201], v[202:203]
	v_pk_fma_f32 v[202:203], v[104:105], v[190:191], v[152:153] op_sel_hi:[1,0,1]
	v_cvt_pk_bf16_f32 v199, v200, v201
	v_mul_f32_e32 v161, 0xbfb8aa3b, v202
	v_exp_f32_e32 v161, v161
	s_nop 0
	v_add_f32_e32 v161, 1.0, v161
	v_rcp_f32_e32 v204, v161
	v_mul_f32_e32 v161, 0xbfb8aa3b, v203
	v_exp_f32_e32 v161, v161
	s_nop 0
	v_add_f32_e32 v161, 1.0, v161
	v_rcp_f32_e32 v205, v161
	s_nop 0
	v_pk_mul_f32 v[202:203], v[202:203], v[204:205]
	v_pk_fma_f32 v[204:205], v[106:107], v[190:191], v[154:155] op_sel_hi:[1,0,1]
	v_cvt_pk_bf16_f32 v200, v202, v203
	v_mul_f32_e32 v161, 0xbfb8aa3b, v204
	v_exp_f32_e32 v161, v161
	s_nop 0
	v_add_f32_e32 v161, 1.0, v161
	v_rcp_f32_e32 v206, v161
	v_mul_f32_e32 v161, 0xbfb8aa3b, v205
	v_exp_f32_e32 v161, v161
	s_nop 0
	v_add_f32_e32 v161, 1.0, v161
	v_rcp_f32_e32 v207, v161
	s_nop 0
	v_pk_mul_f32 v[204:205], v[204:205], v[206:207]
	s_nop 0
	v_cvt_pk_bf16_f32 v201, v204, v205
	global_store_dwordx4 v[196:197], v[198:201], off
	s_nop 1
	v_pk_fma_f32 v[198:199], v[100:101], v[190:191], v[148:149] op_sel_hi:[1,0,1]
	s_nop 0
	v_mul_f32_e32 v161, 0xbfb8aa3b, v198
	v_exp_f32_e32 v161, v161
	s_nop 0
	v_add_f32_e32 v161, 1.0, v161
	v_rcp_f32_e32 v200, v161
	v_mul_f32_e32 v161, 0xbfb8aa3b, v199
	v_exp_f32_e32 v161, v161
	s_nop 0
	v_add_f32_e32 v161, 1.0, v161
	v_rcp_f32_e32 v201, v161
	s_nop 0
	v_pk_mul_f32 v[198:199], v[198:199], v[200:201]
	v_pk_fma_f32 v[200:201], v[102:103], v[190:191], v[150:151] op_sel_hi:[1,0,1]
	v_cvt_pk_bf16_f32 v198, v198, v199
	v_mul_f32_e32 v161, 0xbfb8aa3b, v200
	v_exp_f32_e32 v161, v161
	s_nop 0
	v_add_f32_e32 v161, 1.0, v161
	v_rcp_f32_e32 v202, v161
	v_mul_f32_e32 v161, 0xbfb8aa3b, v201
	v_exp_f32_e32 v161, v161
	s_nop 0
	v_add_f32_e32 v161, 1.0, v161
	v_rcp_f32_e32 v203, v161
	s_nop 0
	v_pk_mul_f32 v[200:201], v[200:201], v[202:203]
	v_pk_fma_f32 v[202:203], v[96:97], v[190:191], v[144:145] op_sel_hi:[1,0,1]
	v_pk_fma_f32 v[190:191], v[98:99], v[190:191], v[146:147] op_sel_hi:[1,0,1]
	v_mul_f32_e32 v161, 0xbfb8aa3b, v202
	v_exp_f32_e32 v161, v161
	v_cvt_pk_bf16_f32 v199, v200, v201
	v_add_f32_e32 v161, 1.0, v161
	v_rcp_f32_e32 v204, v161
	v_mul_f32_e32 v161, 0xbfb8aa3b, v203
	v_exp_f32_e32 v161, v161
	s_nop 0
	v_add_f32_e32 v161, 1.0, v161
	v_rcp_f32_e32 v205, v161
	v_mul_f32_e32 v161, 0xbfb8aa3b, v190
	v_exp_f32_e32 v161, v161
	v_pk_mul_f32 v[202:203], v[202:203], v[204:205]
	s_nop 0
	v_cvt_pk_bf16_f32 v200, v202, v203
	v_add_f32_e32 v161, 1.0, v161
	v_rcp_f32_e32 v204, v161
	v_mul_f32_e32 v161, 0xbfb8aa3b, v191
	v_exp_f32_e32 v161, v161
	s_nop 0
	v_add_f32_e32 v161, 1.0, v161
	v_rcp_f32_e32 v205, v161
	s_nop 0
	v_pk_mul_f32 v[190:191], v[190:191], v[204:205]
	s_nop 0
	v_cvt_pk_bf16_f32 v201, v190, v191
	v_lshlrev_b64 v[190:191], 9, v[194:195]
	v_pk_fma_f32 v[194:195], v[92:93], v[192:193], v[156:157] op_sel_hi:[1,0,1]
	global_store_dwordx4 v[196:197], v[198:201], off offset:256
	v_mul_f32_e32 v161, 0xbfb8aa3b, v194
	v_exp_f32_e32 v161, v161
	v_lshl_add_u64 v[190:191], v[168:169], 0, v[190:191]
; DI float ex2(float x) { return __builtin_amdgcn_exp2f(x); }
; DI float silu(float x) { return x * __builtin_amdgcn_rcpf(1.f + ex2(-x * LOG2E)); }
;     template <int PN> DI void body(AccRef acc, const Unit& u, int wr, int wc, int fr, int fq) const {
;     ...
; #pragma unroll
;         for (int ai = 0; ai < 2; ++ai) {
;             const int rb = u.pm * 256 + ai * 128 + wr * 64 + fr;
;             int mb, pos0, kv0; row_info(rb, mb, pos0, kv0);
; #pragma unroll
;             for (int m = 0; m < 4; ++m) {
;                 const int row = rb + 16 * m, pos = pos0 + 16 * m, kvrow = kv0 + 16 * m;
;                 const float rinv = rinvh[ai][m];
;                 float v[2][8];
; #pragma unroll
;                 for (int bj = 0; bj < 2; ++bj)
; #pragma unroll
;                     for (int n = 0; n < 2; ++n)
; #pragma unroll
;                         for (int j = 0; j < 4; ++j) v[bj][4 * n + j] = acc[ai][bj][m][n][j] * rinv + cvh[ai][bj][n][j];
;     ...
;                             for (int j = 0; j < 8; ++j) v[bj][j] = silu(v[bj][j]);
	v_pk_fma_f32 v[156:157], v[76:77], v[174:175], v[156:157] op_sel_hi:[1,0,1]
	v_add_f32_e32 v161, 1.0, v161
	v_rcp_f32_e32 v196, v161
	v_mul_f32_e32 v161, 0xbfb8aa3b, v195
	v_exp_f32_e32 v161, v161
	s_nop 0
	v_add_f32_e32 v161, 1.0, v161
	v_rcp_f32_e32 v197, v161
	s_nop 0
	v_pk_mul_f32 v[194:195], v[194:195], v[196:197]
	v_pk_fma_f32 v[196:197], v[94:95], v[192:193], v[158:159] op_sel_hi:[1,0,1]
	v_cvt_pk_bf16_f32 v194, v194, v195
	v_mul_f32_e32 v161, 0xbfb8aa3b, v196
	v_exp_f32_e32 v161, v161
	v_pk_fma_f32 v[158:159], v[78:79], v[174:175], v[158:159] op_sel_hi:[1,0,1]
	v_add_f32_e32 v161, 1.0, v161
	v_rcp_f32_e32 v198, v161
	v_mul_f32_e32 v161, 0xbfb8aa3b, v197
	v_exp_f32_e32 v161, v161
	s_nop 0
	v_add_f32_e32 v161, 1.0, v161
	v_rcp_f32_e32 v199, v161
	s_nop 0
	v_pk_mul_f32 v[196:197], v[196:197], v[198:199]
	v_pk_fma_f32 v[198:199], v[88:89], v[192:193], v[152:153] op_sel_hi:[1,0,1]
	v_cvt_pk_bf16_f32 v195, v196, v197
	v_mul_f32_e32 v161, 0xbfb8aa3b, v198
	v_exp_f32_e32 v161, v161
	v_pk_fma_f32 v[152:153], v[72:73], v[174:175], v[152:153] op_sel_hi:[1,0,1]
	v_add_f32_e32 v161, 1.0, v161
	v_rcp_f32_e32 v200, v161
	v_mul_f32_e32 v161, 0xbfb8aa3b, v199
	v_exp_f32_e32 v161, v161
	s_nop 0
	v_add_f32_e32 v161, 1.0, v161
	v_rcp_f32_e32 v201, v161
	s_nop 0
	v_pk_mul_f32 v[198:199], v[198:199], v[200:201]
	v_pk_fma_f32 v[200:201], v[90:91], v[192:193], v[154:155] op_sel_hi:[1,0,1]
	v_cvt_pk_bf16_f32 v196, v198, v199
	v_mul_f32_e32 v161, 0xbfb8aa3b, v200
	v_exp_f32_e32 v161, v161
	s_nop 0
	v_add_f32_e32 v161, 1.0, v161
	v_rcp_f32_e32 v202, v161
	v_mul_f32_e32 v161, 0xbfb8aa3b, v201
	v_exp_f32_e32 v161, v161
	s_nop 0
	v_add_f32_e32 v161, 1.0, v161
	v_rcp_f32_e32 v203, v161
	s_nop 0
	v_pk_mul_f32 v[200:201], v[200:201], v[202:203]
	s_nop 0
	v_cvt_pk_bf16_f32 v197, v200, v201
	global_store_dwordx4 v[190:191], v[194:197], off
	s_nop 1
	v_pk_fma_f32 v[194:195], v[84:85], v[192:193], v[148:149] op_sel_hi:[1,0,1]
	v_pk_fma_f32 v[148:149], v[68:69], v[174:175], v[148:149] op_sel_hi:[1,0,1]
	v_mul_f32_e32 v161, 0xbfb8aa3b, v194
	v_exp_f32_e32 v161, v161
	s_nop 0
	v_add_f32_e32 v161, 1.0, v161
	v_rcp_f32_e32 v196, v161
	v_mul_f32_e32 v161, 0xbfb8aa3b, v195
	v_exp_f32_e32 v161, v161
	s_nop 0
	v_add_f32_e32 v161, 1.0, v161
	v_rcp_f32_e32 v197, v161
	s_nop 0
	v_pk_mul_f32 v[194:195], v[194:195], v[196:197]
	v_pk_fma_f32 v[196:197], v[86:87], v[192:193], v[150:151] op_sel_hi:[1,0,1]
	v_pk_fma_f32 v[150:151], v[70:71], v[174:175], v[150:151] op_sel_hi:[1,0,1]
	v_mul_f32_e32 v161, 0xbfb8aa3b, v196
	v_exp_f32_e32 v161, v161
	s_nop 0
	v_add_f32_e32 v161, 1.0, v161
	v_rcp_f32_e32 v198, v161
	v_mul_f32_e32 v161, 0xbfb8aa3b, v197
	v_exp_f32_e32 v161, v161
	s_nop 0
	v_add_f32_e32 v161, 1.0, v161
	v_rcp_f32_e32 v199, v161
	s_nop 0
	v_pk_mul_f32 v[196:197], v[196:197], v[198:199]
	v_pk_fma_f32 v[198:199], v[80:81], v[192:193], v[144:145] op_sel_hi:[1,0,1]
	v_pk_fma_f32 v[192:193], v[82:83], v[192:193], v[146:147] op_sel_hi:[1,0,1]
	v_mul_f32_e32 v161, 0xbfb8aa3b, v198
	v_exp_f32_e32 v161, v161
	v_pk_fma_f32 v[144:145], v[64:65], v[174:175], v[144:145] op_sel_hi:[1,0,1]
	v_add_f32_e32 v161, 1.0, v161
	v_rcp_f32_e32 v200, v161
	v_mul_f32_e32 v161, 0xbfb8aa3b, v199
	v_exp_f32_e32 v161, v161
	s_nop 0
	v_add_f32_e32 v161, 1.0, v161
	v_rcp_f32_e32 v201, v161
	v_mul_f32_e32 v161, 0xbfb8aa3b, v192
	v_exp_f32_e32 v161, v161
	v_pk_mul_f32 v[198:199], v[198:199], v[200:201]
	v_add_f32_e32 v161, 1.0, v161
	v_rcp_f32_e32 v200, v161
	v_mul_f32_e32 v161, 0xbfb8aa3b, v193
	v_exp_f32_e32 v161, v161
	s_nop 0
	v_add_f32_e32 v161, 1.0, v161
	v_rcp_f32_e32 v201, v161
	v_mul_f32_e32 v161, 0xbfb8aa3b, v156
	v_exp_f32_e32 v161, v161
	v_pk_mul_f32 v[200:201], v[192:193], v[200:201]
	v_cvt_pk_bf16_f32 v192, v194, v195
	v_cvt_pk_bf16_f32 v193, v196, v197
	v_cvt_pk_bf16_f32 v194, v198, v199
	v_cvt_pk_bf16_f32 v195, v200, v201
	v_add_f32_e32 v161, 1.0, v161
	global_store_dwordx4 v[190:191], v[192:195], off offset:256
	v_rcp_f32_e32 v190, v161
	v_mul_f32_e32 v161, 0xbfb8aa3b, v157
	v_exp_f32_e32 v161, v161
	s_nop 0
	v_add_f32_e32 v161, 1.0, v161
	v_rcp_f32_e32 v191, v161
	v_mul_f32_e32 v161, 0xbfb8aa3b, v158
	v_exp_f32_e32 v161, v161
	v_pk_mul_f32 v[156:157], v[156:157], v[190:191]
	v_add_f32_e32 v161, 1.0, v161
	v_rcp_f32_e32 v190, v161
	v_mul_f32_e32 v161, 0xbfb8aa3b, v159
	v_exp_f32_e32 v161, v161
	s_nop 0
	v_add_f32_e32 v161, 1.0, v161
	v_rcp_f32_e32 v191, v161
	v_mul_f32_e32 v161, 0xbfb8aa3b, v152
	v_exp_f32_e32 v161, v161
	v_pk_mul_f32 v[158:159], v[158:159], v[190:191]
	v_add_f32_e32 v161, 1.0, v161
	v_rcp_f32_e32 v190, v161
	v_mul_f32_e32 v161, 0xbfb8aa3b, v153
	v_exp_f32_e32 v161, v161
	s_nop 0
	v_add_f32_e32 v161, 1.0, v161
	v_rcp_f32_e32 v191, v161
	s_nop 0
	v_pk_mul_f32 v[190:191], v[152:153], v[190:191]
	v_pk_fma_f32 v[152:153], v[74:75], v[174:175], v[154:155] op_sel_hi:[1,0,1]
	s_nop 0
	v_mul_f32_e32 v154, 0xbfb8aa3b, v152
	v_mul_f32_e32 v155, 0xbfb8aa3b, v153
	v_exp_f32_e32 v154, v154
	v_exp_f32_e32 v155, v155
	v_add_f32_e32 v154, 1.0, v154
	v_add_f32_e32 v155, 1.0, v155
	v_rcp_f32_e32 v154, v154
	v_rcp_f32_e32 v155, v155
	s_nop 0
	v_pk_mul_f32 v[192:193], v[152:153], v[154:155]
	v_cvt_pk_bf16_f32 v152, v156, v157
	v_cvt_pk_bf16_f32 v153, v158, v159
	v_cvt_pk_bf16_f32 v154, v190, v191
	v_cvt_pk_bf16_f32 v155, v192, v193
	global_store_dwordx4 v[188:189], v[152:155], off
	s_nop 1
	v_mul_f32_e32 v152, 0xbfb8aa3b, v148
	v_mul_f32_e32 v153, 0xbfb8aa3b, v149
	v_exp_f32_e32 v152, v152
	v_exp_f32_e32 v153, v153
	v_add_f32_e32 v152, 1.0, v152
	v_add_f32_e32 v153, 1.0, v153
	v_rcp_f32_e32 v152, v152
	v_rcp_f32_e32 v153, v153
	s_nop 0
	v_pk_mul_f32 v[148:149], v[148:149], v[152:153]
	v_mul_f32_e32 v152, 0xbfb8aa3b, v150
	v_mul_f32_e32 v153, 0xbfb8aa3b, v151
	v_exp_f32_e32 v152, v152
	v_exp_f32_e32 v153, v153
	v_add_f32_e32 v152, 1.0, v152
	v_add_f32_e32 v153, 1.0, v153
	v_rcp_f32_e32 v152, v152
	v_rcp_f32_e32 v153, v153
	s_nop 0
	v_pk_mul_f32 v[150:151], v[150:151], v[152:153]
	v_mul_f32_e32 v152, 0xbfb8aa3b, v144
	v_mul_f32_e32 v153, 0xbfb8aa3b, v145
	v_exp_f32_e32 v152, v152
	v_exp_f32_e32 v153, v153
	v_add_f32_e32 v152, 1.0, v152
	v_add_f32_e32 v153, 1.0, v153
	v_rcp_f32_e32 v152, v152
	v_rcp_f32_e32 v153, v153
	s_nop 0
	v_pk_mul_f32 v[152:153], v[144:145], v[152:153]
	v_pk_fma_f32 v[144:145], v[66:67], v[174:175], v[146:147] op_sel_hi:[1,0,1]
	s_nop 0
	v_mul_f32_e32 v146, 0xbfb8aa3b, v144
	v_mul_f32_e32 v147, 0xbfb8aa3b, v145
	v_exp_f32_e32 v146, v146
	v_exp_f32_e32 v147, v147
	v_add_f32_e32 v146, 1.0, v146
	v_add_f32_e32 v147, 1.0, v147
	v_rcp_f32_e32 v146, v146
	v_rcp_f32_e32 v147, v147
	s_nop 0
	v_pk_mul_f32 v[154:155], v[144:145], v[146:147]
	v_cvt_pk_bf16_f32 v144, v148, v149
	v_cvt_pk_bf16_f32 v145, v150, v151
	v_cvt_pk_bf16_f32 v146, v152, v153
	v_cvt_pk_bf16_f32 v147, v154, v155
	global_store_dwordx4 v[188:189], v[144:147], off offset:256
	s_waitcnt vmcnt(11)
; DI float ex2(float x) { return __builtin_amdgcn_exp2f(x); }
; DI float silu(float x) { return x * __builtin_amdgcn_rcpf(1.f + ex2(-x * LOG2E)); }
;     template <int PN> DI void body(AccRef acc, const Unit& u, int wr, int wc, int fr, int fq) const {
;     ...
; #pragma unroll
;         for (int ai = 0; ai < 2; ++ai) {
;             const int rb = u.pm * 256 + ai * 128 + wr * 64 + fr;
;             int mb, pos0, kv0; row_info(rb, mb, pos0, kv0);
; #pragma unroll
;             for (int m = 0; m < 4; ++m) {
;                 const int row = rb + 16 * m, pos = pos0 + 16 * m, kvrow = kv0 + 16 * m;
;                 const float rinv = rinvh[ai][m];
;                 float v[2][8];
; #pragma unroll
;                 for (int bj = 0; bj < 2; ++bj)
; #pragma unroll
;                     for (int n = 0; n < 2; ++n)
; #pragma unroll
;                         for (int j = 0; j < 4; ++j) v[bj][4 * n + j] = acc[ai][bj][m][n][j] * rinv + cvh[ai][bj][n][j];
;     ...
;                             for (int j = 0; j < 8; ++j) v[bj][j] = silu(v[bj][j]);
	s_nop 0
	v_pk_fma_f32 v[146:147], v[60:61], v[170:171], v[140:141] op_sel_hi:[1,0,1]
	v_lshlrev_b64 v[144:145], 9, v[172:173]
	v_mul_f32_e32 v148, 0xbfb8aa3b, v146
	v_mul_f32_e32 v149, 0xbfb8aa3b, v147
	v_exp_f32_e32 v148, v148
	v_exp_f32_e32 v149, v149
	v_lshl_add_u64 v[144:145], v[168:169], 0, v[144:145]
	v_add_f32_e32 v148, 1.0, v148
	v_add_f32_e32 v149, 1.0, v149
	v_rcp_f32_e32 v148, v148
	v_rcp_f32_e32 v149, v149
	s_nop 0
	v_pk_mul_f32 v[146:147], v[146:147], v[148:149]
	v_pk_fma_f32 v[148:149], v[62:63], v[170:171], v[142:143] op_sel_hi:[1,0,1]
	v_cvt_pk_bf16_f32 v146, v146, v147
	v_mul_f32_e32 v150, 0xbfb8aa3b, v148
	v_mul_f32_e32 v151, 0xbfb8aa3b, v149
	v_exp_f32_e32 v150, v150
	v_exp_f32_e32 v151, v151
	v_add_f32_e32 v150, 1.0, v150
	v_add_f32_e32 v151, 1.0, v151
	v_rcp_f32_e32 v150, v150
	v_rcp_f32_e32 v151, v151
	s_nop 0
	v_pk_mul_f32 v[148:149], v[148:149], v[150:151]
	s_waitcnt vmcnt(10)
	v_pk_fma_f32 v[150:151], v[56:57], v[170:171], v[136:137] op_sel_hi:[1,0,1]
	v_cvt_pk_bf16_f32 v147, v148, v149
	v_mul_f32_e32 v152, 0xbfb8aa3b, v150
	v_mul_f32_e32 v153, 0xbfb8aa3b, v151
	v_exp_f32_e32 v152, v152
	v_exp_f32_e32 v153, v153
	v_add_f32_e32 v152, 1.0, v152
	v_add_f32_e32 v153, 1.0, v153
	v_rcp_f32_e32 v152, v152
	v_rcp_f32_e32 v153, v153
	s_nop 0
	v_pk_mul_f32 v[150:151], v[150:151], v[152:153]
	v_pk_fma_f32 v[152:153], v[58:59], v[170:171], v[138:139] op_sel_hi:[1,0,1]
	v_cvt_pk_bf16_f32 v148, v150, v151
	v_mul_f32_e32 v154, 0xbfb8aa3b, v152
	v_mul_f32_e32 v155, 0xbfb8aa3b, v153
	v_exp_f32_e32 v154, v154
	v_exp_f32_e32 v155, v155
	v_add_f32_e32 v154, 1.0, v154
	v_add_f32_e32 v155, 1.0, v155
	v_rcp_f32_e32 v154, v154
	v_rcp_f32_e32 v155, v155
	s_nop 0
	v_pk_mul_f32 v[152:153], v[152:153], v[154:155]
	s_nop 0
	v_cvt_pk_bf16_f32 v149, v152, v153
	global_store_dwordx4 v[144:145], v[146:149], off
	s_waitcnt vmcnt(9)
	s_nop 0
	v_pk_fma_f32 v[146:147], v[52:53], v[170:171], v[132:133] op_sel_hi:[1,0,1]
	s_nop 0
	v_mul_f32_e32 v148, 0xbfb8aa3b, v146
	v_mul_f32_e32 v149, 0xbfb8aa3b, v147
	v_exp_f32_e32 v148, v148
	v_exp_f32_e32 v149, v149
	v_add_f32_e32 v148, 1.0, v148
	v_add_f32_e32 v149, 1.0, v149
	v_rcp_f32_e32 v148, v148
	v_rcp_f32_e32 v149, v149
	s_nop 0
	v_pk_mul_f32 v[146:147], v[146:147], v[148:149]
	v_pk_fma_f32 v[148:149], v[54:55], v[170:171], v[134:135] op_sel_hi:[1,0,1]
	v_cvt_pk_bf16_f32 v146, v146, v147
	v_mul_f32_e32 v150, 0xbfb8aa3b, v148
	v_mul_f32_e32 v151, 0xbfb8aa3b, v149
	v_exp_f32_e32 v150, v150
	v_exp_f32_e32 v151, v151
	v_add_f32_e32 v150, 1.0, v150
	v_add_f32_e32 v151, 1.0, v151
	v_rcp_f32_e32 v150, v150
	v_rcp_f32_e32 v151, v151
	s_nop 0
	v_pk_mul_f32 v[148:149], v[148:149], v[150:151]
	v_pk_fma_f32 v[150:151], v[48:49], v[170:171], v[128:129] op_sel_hi:[1,0,1]
	v_cvt_pk_bf16_f32 v147, v148, v149
	v_mul_f32_e32 v152, 0xbfb8aa3b, v150
	v_mul_f32_e32 v153, 0xbfb8aa3b, v151
	v_exp_f32_e32 v152, v152
	v_exp_f32_e32 v153, v153
	v_add_f32_e32 v152, 1.0, v152
	v_add_f32_e32 v153, 1.0, v153
	v_rcp_f32_e32 v152, v152
	v_rcp_f32_e32 v153, v153
	s_nop 0
	v_pk_mul_f32 v[150:151], v[150:151], v[152:153]
	v_pk_fma_f32 v[152:153], v[50:51], v[170:171], v[130:131] op_sel_hi:[1,0,1]
	v_cvt_pk_bf16_f32 v148, v150, v151
	v_mul_f32_e32 v154, 0xbfb8aa3b, v152
	v_mul_f32_e32 v155, 0xbfb8aa3b, v153
	v_exp_f32_e32 v154, v154
	v_exp_f32_e32 v155, v155
	v_add_f32_e32 v154, 1.0, v154
	v_add_f32_e32 v155, 1.0, v155
	v_rcp_f32_e32 v154, v154
	v_rcp_f32_e32 v155, v155
	s_nop 0
	v_pk_mul_f32 v[152:153], v[152:153], v[154:155]
	s_nop 0
	v_cvt_pk_bf16_f32 v149, v152, v153
	global_store_dwordx4 v[144:145], v[146:149], off offset:256
	v_add_u32_e32 v144, 0x90, v160
	v_ashrrev_i32_e32 v145, 31, v144
	v_pk_fma_f32 v[146:147], v[44:45], v[164:165], v[140:141] op_sel_hi:[1,0,1]
	v_lshlrev_b64 v[144:145], 9, v[144:145]
	v_mul_f32_e32 v148, 0xbfb8aa3b, v146
	v_mul_f32_e32 v149, 0xbfb8aa3b, v147
	v_exp_f32_e32 v148, v148
	v_exp_f32_e32 v149, v149
	v_lshl_add_u64 v[144:145], v[168:169], 0, v[144:145]
	v_add_f32_e32 v148, 1.0, v148
	v_add_f32_e32 v149, 1.0, v149
	v_rcp_f32_e32 v148, v148
	v_rcp_f32_e32 v149, v149
	s_nop 0
	v_pk_mul_f32 v[146:147], v[146:147], v[148:149]
	v_pk_fma_f32 v[148:149], v[46:47], v[164:165], v[142:143] op_sel_hi:[1,0,1]
	v_cvt_pk_bf16_f32 v146, v146, v147
	v_mul_f32_e32 v150, 0xbfb8aa3b, v148
	v_mul_f32_e32 v151, 0xbfb8aa3b, v149
	v_exp_f32_e32 v150, v150
	v_exp_f32_e32 v151, v151
	v_add_f32_e32 v150, 1.0, v150
	v_add_f32_e32 v151, 1.0, v151
	v_rcp_f32_e32 v150, v150
	v_rcp_f32_e32 v151, v151
	s_nop 0
	v_pk_mul_f32 v[148:149], v[148:149], v[150:151]
	v_pk_fma_f32 v[150:151], v[40:41], v[164:165], v[136:137] op_sel_hi:[1,0,1]
	v_cvt_pk_bf16_f32 v147, v148, v149
	v_mul_f32_e32 v152, 0xbfb8aa3b, v150
	v_mul_f32_e32 v153, 0xbfb8aa3b, v151
	v_exp_f32_e32 v152, v152
	v_exp_f32_e32 v153, v153
	v_add_f32_e32 v152, 1.0, v152
	v_add_f32_e32 v153, 1.0, v153
	v_rcp_f32_e32 v152, v152
	v_rcp_f32_e32 v153, v153
	s_nop 0
	v_pk_mul_f32 v[150:151], v[150:151], v[152:153]
	v_pk_fma_f32 v[152:153], v[42:43], v[164:165], v[138:139] op_sel_hi:[1,0,1]
	v_cvt_pk_bf16_f32 v148, v150, v151
	v_mul_f32_e32 v154, 0xbfb8aa3b, v152
	v_mul_f32_e32 v155, 0xbfb8aa3b, v153
	v_exp_f32_e32 v154, v154
	v_exp_f32_e32 v155, v155
	v_add_f32_e32 v154, 1.0, v154
	v_add_f32_e32 v155, 1.0, v155
	v_rcp_f32_e32 v154, v154
	v_rcp_f32_e32 v155, v155
	s_nop 0
	v_pk_mul_f32 v[152:153], v[152:153], v[154:155]
	s_nop 0
	v_cvt_pk_bf16_f32 v149, v152, v153
	global_store_dwordx4 v[144:145], v[146:149], off
	s_nop 1
	v_pk_fma_f32 v[146:147], v[36:37], v[164:165], v[132:133] op_sel_hi:[1,0,1]
	s_nop 0
	v_mul_f32_e32 v148, 0xbfb8aa3b, v146
	v_mul_f32_e32 v149, 0xbfb8aa3b, v147
; DI float ex2(float x) { return __builtin_amdgcn_exp2f(x); }
; DI float silu(float x) { return x * __builtin_amdgcn_rcpf(1.f + ex2(-x * LOG2E)); }
;     template <int PN> DI void body(AccRef acc, const Unit& u, int wr, int wc, int fr, int fq) const {
;     ...
; #pragma unroll
;         for (int ai = 0; ai < 2; ++ai) {
;             const int rb = u.pm * 256 + ai * 128 + wr * 64 + fr;
;             int mb, pos0, kv0; row_info(rb, mb, pos0, kv0);
; #pragma unroll
;             for (int m = 0; m < 4; ++m) {
;                 const int row = rb + 16 * m, pos = pos0 + 16 * m, kvrow = kv0 + 16 * m;
;                 const float rinv = rinvh[ai][m];
;                 float v[2][8];
; #pragma unroll
;                 for (int bj = 0; bj < 2; ++bj)
; #pragma unroll
;                     for (int n = 0; n < 2; ++n)
; #pragma unroll
;                         for (int j = 0; j < 4; ++j) v[bj][4 * n + j] = acc[ai][bj][m][n][j] * rinv + cvh[ai][bj][n][j];
;     ...
;                             for (int j = 0; j < 8; ++j) v[bj][j] = silu(v[bj][j]);
	v_exp_f32_e32 v148, v148
	v_exp_f32_e32 v149, v149
	v_add_f32_e32 v148, 1.0, v148
	v_add_f32_e32 v149, 1.0, v149
	v_rcp_f32_e32 v148, v148
	v_rcp_f32_e32 v149, v149
	s_nop 0
	v_pk_mul_f32 v[146:147], v[146:147], v[148:149]
	v_pk_fma_f32 v[148:149], v[38:39], v[164:165], v[134:135] op_sel_hi:[1,0,1]
	v_cvt_pk_bf16_f32 v146, v146, v147
	v_mul_f32_e32 v150, 0xbfb8aa3b, v148
	v_mul_f32_e32 v151, 0xbfb8aa3b, v149
	v_exp_f32_e32 v150, v150
	v_exp_f32_e32 v151, v151
	v_add_f32_e32 v150, 1.0, v150
	v_add_f32_e32 v151, 1.0, v151
	v_rcp_f32_e32 v150, v150
	v_rcp_f32_e32 v151, v151
	s_nop 0
	v_pk_mul_f32 v[148:149], v[148:149], v[150:151]
	v_pk_fma_f32 v[150:151], v[28:29], v[164:165], v[128:129] op_sel_hi:[1,0,1]
	v_cvt_pk_bf16_f32 v147, v148, v149
	v_mul_f32_e32 v152, 0xbfb8aa3b, v150
	v_mul_f32_e32 v153, 0xbfb8aa3b, v151
	v_exp_f32_e32 v152, v152
	v_exp_f32_e32 v153, v153
	v_add_f32_e32 v152, 1.0, v152
	v_add_f32_e32 v153, 1.0, v153
	v_rcp_f32_e32 v152, v152
	v_rcp_f32_e32 v153, v153
	s_nop 0
	v_pk_mul_f32 v[150:151], v[150:151], v[152:153]
	v_pk_fma_f32 v[152:153], v[30:31], v[164:165], v[130:131] op_sel_hi:[1,0,1]
	v_cvt_pk_bf16_f32 v148, v150, v151
	v_mul_f32_e32 v154, 0xbfb8aa3b, v152
	v_mul_f32_e32 v155, 0xbfb8aa3b, v153
	v_exp_f32_e32 v154, v154
	v_exp_f32_e32 v155, v155
	v_add_f32_e32 v154, 1.0, v154
	v_add_f32_e32 v155, 1.0, v155
	v_rcp_f32_e32 v154, v154
	v_rcp_f32_e32 v155, v155
	s_nop 0
	v_pk_mul_f32 v[152:153], v[152:153], v[154:155]
	s_nop 0
	v_cvt_pk_bf16_f32 v149, v152, v153
	global_store_dwordx4 v[144:145], v[146:149], off offset:256
	v_add_u32_e32 v144, 0xa0, v160
	v_ashrrev_i32_e32 v145, 31, v144
	v_pk_fma_f32 v[146:147], v[32:33], v[166:167], v[140:141] op_sel_hi:[1,0,1]
	v_lshlrev_b64 v[144:145], 9, v[144:145]
	v_mul_f32_e32 v148, 0xbfb8aa3b, v146
	v_mul_f32_e32 v149, 0xbfb8aa3b, v147
	v_exp_f32_e32 v148, v148
	v_exp_f32_e32 v149, v149
	v_lshl_add_u64 v[144:145], v[168:169], 0, v[144:145]
	v_pk_fma_f32 v[140:141], v[12:13], v[162:163], v[140:141] op_sel_hi:[1,0,1]
	v_add_f32_e32 v148, 1.0, v148
	v_add_f32_e32 v149, 1.0, v149
	v_rcp_f32_e32 v148, v148
	v_rcp_f32_e32 v149, v149
	s_nop 0
	v_pk_mul_f32 v[146:147], v[146:147], v[148:149]
	v_pk_fma_f32 v[148:149], v[34:35], v[166:167], v[142:143] op_sel_hi:[1,0,1]
	v_cvt_pk_bf16_f32 v146, v146, v147
	v_mul_f32_e32 v150, 0xbfb8aa3b, v148
	v_mul_f32_e32 v151, 0xbfb8aa3b, v149
	v_exp_f32_e32 v150, v150
	v_exp_f32_e32 v151, v151
	v_pk_fma_f32 v[142:143], v[14:15], v[162:163], v[142:143] op_sel_hi:[1,0,1]
	v_add_f32_e32 v150, 1.0, v150
	v_add_f32_e32 v151, 1.0, v151
	v_rcp_f32_e32 v150, v150
	v_rcp_f32_e32 v151, v151
	s_nop 0
	v_pk_mul_f32 v[148:149], v[148:149], v[150:151]
	v_pk_fma_f32 v[150:151], v[24:25], v[166:167], v[136:137] op_sel_hi:[1,0,1]
	v_cvt_pk_bf16_f32 v147, v148, v149
	v_mul_f32_e32 v152, 0xbfb8aa3b, v150
	v_mul_f32_e32 v153, 0xbfb8aa3b, v151
	v_exp_f32_e32 v152, v152
	v_exp_f32_e32 v153, v153
	v_pk_fma_f32 v[136:137], v[8:9], v[162:163], v[136:137] op_sel_hi:[1,0,1]
	v_add_f32_e32 v152, 1.0, v152
	v_add_f32_e32 v153, 1.0, v153
	v_rcp_f32_e32 v152, v152
	v_rcp_f32_e32 v153, v153
	s_nop 0
	v_pk_mul_f32 v[150:151], v[150:151], v[152:153]
	v_pk_fma_f32 v[152:153], v[26:27], v[166:167], v[138:139] op_sel_hi:[1,0,1]
	v_cvt_pk_bf16_f32 v148, v150, v151
	v_mul_f32_e32 v154, 0xbfb8aa3b, v152
	v_mul_f32_e32 v155, 0xbfb8aa3b, v153
	v_exp_f32_e32 v154, v154
	v_exp_f32_e32 v155, v155
	v_add_f32_e32 v154, 1.0, v154
	v_add_f32_e32 v155, 1.0, v155
	v_rcp_f32_e32 v154, v154
	v_rcp_f32_e32 v155, v155
	s_nop 0
	v_pk_mul_f32 v[152:153], v[152:153], v[154:155]
	s_nop 0
	v_cvt_pk_bf16_f32 v149, v152, v153
	global_store_dwordx4 v[144:145], v[146:149], off
	s_nop 1
	v_pk_fma_f32 v[146:147], v[20:21], v[166:167], v[132:133] op_sel_hi:[1,0,1]
	v_pk_fma_f32 v[132:133], v[4:5], v[162:163], v[132:133] op_sel_hi:[1,0,1]
	v_mul_f32_e32 v148, 0xbfb8aa3b, v146
	v_mul_f32_e32 v149, 0xbfb8aa3b, v147
	v_exp_f32_e32 v148, v148
	v_exp_f32_e32 v149, v149
	v_add_f32_e32 v148, 1.0, v148
	v_add_f32_e32 v149, 1.0, v149
	v_rcp_f32_e32 v148, v148
	v_rcp_f32_e32 v149, v149
	s_nop 0
	v_pk_mul_f32 v[146:147], v[146:147], v[148:149]
	v_pk_fma_f32 v[148:149], v[22:23], v[166:167], v[134:135] op_sel_hi:[1,0,1]
	v_cvt_pk_bf16_f32 v146, v146, v147
	v_mul_f32_e32 v150, 0xbfb8aa3b, v148
	v_mul_f32_e32 v151, 0xbfb8aa3b, v149
	v_exp_f32_e32 v150, v150
	v_exp_f32_e32 v151, v151
; DI float ex2(float x) { return __builtin_amdgcn_exp2f(x); }
; DI float silu(float x) { return x * __builtin_amdgcn_rcpf(1.f + ex2(-x * LOG2E)); }
;     template <int PN> DI void body(AccRef acc, const Unit& u, int wr, int wc, int fr, int fq) const {
;     ...
; #pragma unroll
;         for (int ai = 0; ai < 2; ++ai) {
;             const int rb = u.pm * 256 + ai * 128 + wr * 64 + fr;
;             int mb, pos0, kv0; row_info(rb, mb, pos0, kv0);
; #pragma unroll
;             for (int m = 0; m < 4; ++m) {
;                 const int row = rb + 16 * m, pos = pos0 + 16 * m, kvrow = kv0 + 16 * m;
;                 const float rinv = rinvh[ai][m];
;                 float v[2][8];
; #pragma unroll
;                 for (int bj = 0; bj < 2; ++bj)
; #pragma unroll
;                     for (int n = 0; n < 2; ++n)
; #pragma unroll
;                         for (int j = 0; j < 4; ++j) v[bj][4 * n + j] = acc[ai][bj][m][n][j] * rinv + cvh[ai][bj][n][j];
;     ...
;                             for (int j = 0; j < 8; ++j) v[bj][j] = silu(v[bj][j]);
	v_pk_fma_f32 v[134:135], v[6:7], v[162:163], v[134:135] op_sel_hi:[1,0,1]
	v_add_f32_e32 v150, 1.0, v150
	v_add_f32_e32 v151, 1.0, v151
	v_rcp_f32_e32 v150, v150
	v_rcp_f32_e32 v151, v151
	s_nop 0
	v_pk_mul_f32 v[148:149], v[148:149], v[150:151]
	v_pk_fma_f32 v[150:151], v[16:17], v[166:167], v[128:129] op_sel_hi:[1,0,1]
	v_cvt_pk_bf16_f32 v147, v148, v149
	v_mul_f32_e32 v152, 0xbfb8aa3b, v150
	v_mul_f32_e32 v153, 0xbfb8aa3b, v151
	v_exp_f32_e32 v152, v152
	v_exp_f32_e32 v153, v153
	v_pk_fma_f32 v[128:129], v[0:1], v[162:163], v[128:129] op_sel_hi:[1,0,1]
	v_add_f32_e32 v152, 1.0, v152
	v_add_f32_e32 v153, 1.0, v153
	v_rcp_f32_e32 v152, v152
	v_rcp_f32_e32 v153, v153
	s_nop 0
	v_pk_mul_f32 v[150:151], v[150:151], v[152:153]
	v_pk_fma_f32 v[152:153], v[18:19], v[166:167], v[130:131] op_sel_hi:[1,0,1]
	v_cvt_pk_bf16_f32 v148, v150, v151
	v_mul_f32_e32 v154, 0xbfb8aa3b, v152
	v_mul_f32_e32 v155, 0xbfb8aa3b, v153
	v_exp_f32_e32 v154, v154
	v_exp_f32_e32 v155, v155
	v_add_f32_e32 v154, 1.0, v154
	v_add_f32_e32 v155, 1.0, v155
	v_rcp_f32_e32 v154, v154
	v_rcp_f32_e32 v155, v155
	s_nop 0
	v_pk_mul_f32 v[152:153], v[152:153], v[154:155]
	s_nop 0
	v_cvt_pk_bf16_f32 v149, v152, v153
	global_store_dwordx4 v[144:145], v[146:149], off offset:256
	v_add_u32_e32 v144, 0xb0, v160
	v_ashrrev_i32_e32 v145, 31, v144
	v_mul_f32_e32 v146, 0xbfb8aa3b, v140
	v_mul_f32_e32 v147, 0xbfb8aa3b, v141
	v_exp_f32_e32 v146, v146
	v_exp_f32_e32 v147, v147
	v_lshlrev_b64 v[144:145], 9, v[144:145]
	v_lshl_add_u64 v[144:145], v[168:169], 0, v[144:145]
	v_add_f32_e32 v146, 1.0, v146
	v_add_f32_e32 v147, 1.0, v147
	v_rcp_f32_e32 v146, v146
	v_rcp_f32_e32 v147, v147
	s_nop 0
	v_pk_mul_f32 v[140:141], v[140:141], v[146:147]
	v_mul_f32_e32 v146, 0xbfb8aa3b, v142
	v_mul_f32_e32 v147, 0xbfb8aa3b, v143
	v_exp_f32_e32 v146, v146
	v_exp_f32_e32 v147, v147
	v_add_f32_e32 v146, 1.0, v146
	v_add_f32_e32 v147, 1.0, v147
	v_rcp_f32_e32 v146, v146
	v_rcp_f32_e32 v147, v147
	s_nop 0
	v_pk_mul_f32 v[142:143], v[142:143], v[146:147]
	v_mul_f32_e32 v146, 0xbfb8aa3b, v136
	v_mul_f32_e32 v147, 0xbfb8aa3b, v137
	v_exp_f32_e32 v146, v146
	v_exp_f32_e32 v147, v147
	v_add_f32_e32 v146, 1.0, v146
	v_add_f32_e32 v147, 1.0, v147
	v_rcp_f32_e32 v146, v146
	v_rcp_f32_e32 v147, v147
	s_nop 0
	v_pk_mul_f32 v[146:147], v[136:137], v[146:147]
	v_pk_fma_f32 v[136:137], v[10:11], v[162:163], v[138:139] op_sel_hi:[1,0,1]
	s_nop 0
	v_mul_f32_e32 v138, 0xbfb8aa3b, v136
	v_mul_f32_e32 v139, 0xbfb8aa3b, v137
	v_exp_f32_e32 v138, v138
	v_exp_f32_e32 v139, v139
	v_add_f32_e32 v138, 1.0, v138
	v_add_f32_e32 v139, 1.0, v139
	v_rcp_f32_e32 v138, v138
	v_rcp_f32_e32 v139, v139
	s_nop 0
	v_pk_mul_f32 v[148:149], v[136:137], v[138:139]
	v_cvt_pk_bf16_f32 v136, v140, v141
	v_cvt_pk_bf16_f32 v137, v142, v143
	v_cvt_pk_bf16_f32 v138, v146, v147
	v_cvt_pk_bf16_f32 v139, v148, v149
	global_store_dwordx4 v[144:145], v[136:139], off
	s_nop 1
	v_mul_f32_e32 v136, 0xbfb8aa3b, v132
	v_mul_f32_e32 v137, 0xbfb8aa3b, v133
	v_exp_f32_e32 v136, v136
	v_exp_f32_e32 v137, v137
	v_add_f32_e32 v136, 1.0, v136
	v_add_f32_e32 v137, 1.0, v137
	v_rcp_f32_e32 v136, v136
	v_rcp_f32_e32 v137, v137
	s_nop 0
	v_pk_mul_f32 v[132:133], v[132:133], v[136:137]
	v_mul_f32_e32 v136, 0xbfb8aa3b, v134
	v_mul_f32_e32 v137, 0xbfb8aa3b, v135
	v_exp_f32_e32 v136, v136
	v_exp_f32_e32 v137, v137
	v_add_f32_e32 v136, 1.0, v136
	v_add_f32_e32 v137, 1.0, v137
	v_rcp_f32_e32 v136, v136
	v_rcp_f32_e32 v137, v137
	s_nop 0
	v_pk_mul_f32 v[134:135], v[134:135], v[136:137]
	v_mul_f32_e32 v136, 0xbfb8aa3b, v128
	v_mul_f32_e32 v137, 0xbfb8aa3b, v129
	v_exp_f32_e32 v136, v136
	v_exp_f32_e32 v137, v137
	v_add_f32_e32 v136, 1.0, v136
	v_add_f32_e32 v137, 1.0, v137
	v_rcp_f32_e32 v136, v136
	v_rcp_f32_e32 v137, v137
	s_nop 0
	v_pk_mul_f32 v[136:137], v[128:129], v[136:137]
	v_pk_fma_f32 v[128:129], v[2:3], v[162:163], v[130:131] op_sel_hi:[1,0,1]
	s_nop 0
	v_mul_f32_e32 v130, 0xbfb8aa3b, v128
	v_mul_f32_e32 v131, 0xbfb8aa3b, v129
	v_exp_f32_e32 v130, v130
	v_exp_f32_e32 v131, v131
	v_add_f32_e32 v130, 1.0, v130
	v_add_f32_e32 v131, 1.0, v131
	v_rcp_f32_e32 v130, v130
	v_rcp_f32_e32 v131, v131
	s_nop 0
	v_pk_mul_f32 v[138:139], v[128:129], v[130:131]
	v_cvt_pk_bf16_f32 v128, v132, v133
	v_cvt_pk_bf16_f32 v129, v134, v135
	v_cvt_pk_bf16_f32 v130, v136, v137
	v_cvt_pk_bf16_f32 v131, v138, v139
	global_store_dwordx4 v[144:145], v[128:131], off offset:256

; DI u32x4 pack8(const float* v) { u32x4 w; w.x = pk2(v[0], v[1]); w.y = pk2(v[2], v[3]); w.z = pk2(v[4], v[5]); w.w = pk2(v[6], v[7]); return w; }
; DI float silu(float x) { return x * __builtin_amdgcn_rcpf(1.f + ex2(-x * LOG2E)); }
; DI float sum16(const float* p) { const f32x4* q = (const f32x4*)p; f32x4 a = q[0], b = q[1], c = q[2], d = q[3]; f32x4 s = (a + b) + (c + d); return (s[0] + s[1]) + (s[2] + s[3]); }
;     template <int PN> DI void body(AccRef acc, const Unit& u, int wr, int wc, int fr, int fq) const {
;     ...
; #pragma unroll
;         for (int ai = 0; ai < 2; ++ai) {
;             const int rb_ = u.pm * 256 + ai * 128 + wr * 64 + fr;
; #pragma unroll
;             for (int m = 0; m < 4; ++m) rinvh[ai][m] = rsqrtf(sum16(ssq + (size_t)(rb_ + 16 * m + zdep) * 16) * (1.f / 1024.f) + EPS);
;             asm volatile("v_mov_b32 %0, 0" : "=v"(zdep) : "v"(rinvh[ai][0]), "v"(rinvh[ai][1]), "v"(rinvh[ai][2]), "v"(rinvh[ai][3]));
;         }
; #pragma unroll
;         for (int ai = 0; ai < 2; ++ai) {
;             const int rb_ = u.pm * 256 + ai * 128 + wr * 64 + fr;
;             int mb_, p_, k_; row_info(rb_, mb_, p_, k_);
; #pragma unroll
;             for (int bj = 0; bj < 2; ++bj)
; #pragma unroll
;                 for (int n = 0; n < 2; ++n) cvh[ai][bj][n] = *(const f32x4*)(cv + (size_t)(mb_ + zdep) * NIN + PN * 256 + bj * 128 + cl + 4 * n);
;         }
;     ...
;                 } else if constexpr (PN == 5 || PN == 6 || PN == 7) {
;                     bf16_t* dst = PN == 5 ? rv : (PN == 6 ? rg : sq);
; #pragma unroll
;                     for (int bj = 0; bj < 2; ++bj) {
;                         if constexpr (PN == 6) {
; #pragma unroll
;                             for (int j = 0; j < 8; ++j) v[bj][j] = silu(v[bj][j]);
;                         }
;                         if constexpr (PN == 7) {
; #pragma unroll
;                             for (int j = 0; j < 8; ++j) v[bj][j] *= 0.125f;
;                         }
;                         *(u32x4*)(dst + (size_t)row * 256 + bj * 128 + cl) = pack8(v[bj]);
;                     }
.LBB0_366:
	s_and_b64 vcc, exec, s[2:3]
	s_cbranch_vccz .LBB0_371
	s_cmp_gt_i32 s52, 4
	s_mov_b64 s[2:3], -1
	s_cbranch_scc0 .LBB0_369
	s_lshl_b32 s2, s53, 6
	s_lshl_b32 s3, s34, 8
	s_add_i32 s2, s2, s3
	v_add_u32_e32 v160, s2, v214
	v_ashrrev_i32_e32 v161, 31, v160
	v_lshlrev_b64 v[128:129], 6, v[160:161]
	v_lshl_add_u64 v[140:141], s[56:57], 0, v[128:129]
	s_nop 0
	v_add_u32_e32 v166, 16, v160
	v_ashrrev_i32_e32 v167, 31, v166
	s_mov_b32 s2, 0x358637bd
	s_mov_b32 s4, 0x3a800000
	v_add_u32_e32 v162, 32, v160
	v_ashrrev_i32_e32 v163, 31, v162
	v_add_u32_e32 v164, 48, v160
	v_ashrrev_i32_e32 v165, 31, v164
	v_add_u32_e32 v174, 0x80, v160
	s_mov_b64 s[6:7], 0x125400
	v_lshlrev_b64 v[222:223], 9, v[160:161]
	v_ashrrev_i32_e32 v175, 31, v174
	s_nop 0
	v_lshlrev_b64 v[128:129], 6, v[166:167]
	v_lshl_add_u64 v[140:141], s[56:57], 0, v[128:129]
	s_nop 0
	v_lshlrev_b64 v[166:167], 9, v[166:167]
	s_nop 0
	v_mov_b64_e32 v[128:129], s[2:3]
	s_nop 0
	s_nop 0
	s_nop 0
	v_mov_b32_e32 v170, v244
	s_nop 0
	v_mov_b32_e32 v168, v245
	v_lshlrev_b64 v[130:131], 6, v[162:163]
	v_lshl_add_u64 v[142:143], s[56:57], 0, v[130:131]
	s_nop 0
	v_lshlrev_b64 v[162:163], 9, v[162:163]
	s_nop 0
	v_lshlrev_b64 v[130:131], 6, v[164:165]
	v_lshl_add_u64 v[142:143], s[56:57], 0, v[130:131]
	s_nop 0
	s_nop 0
	s_nop 0
	s_nop 0
	s_nop 0
	s_nop 0
	v_mov_b32_e32 v172, v246
	s_nop 0
	v_mov_b32_e32 v188, v247
	v_mov_b32 v130, 0
	s_nop 0
	v_add_u32_e32 v130, v130, v174
	v_ashrrev_i32_e32 v131, 31, v130
	v_lshlrev_b64 v[132:133], 6, v[130:131]
	v_lshl_add_u64 v[144:145], s[56:57], 0, v[132:133]
	s_nop 0
	s_nop 0
	v_add_u32_e32 v132, 16, v130
	v_ashrrev_i32_e32 v133, 31, v132
	v_lshlrev_b64 v[132:133], 6, v[132:133]
	v_lshl_add_u64 v[144:145], s[56:57], 0, v[132:133]
	s_nop 0
	s_nop 0
	s_nop 0
	s_nop 0
	s_nop 0
	s_nop 0
	v_mov_b32_e32 v192, v248
	s_nop 0
	v_mov_b32_e32 v190, v249
	v_add_u32_e32 v132, 32, v130
	v_ashrrev_i32_e32 v133, 31, v132
	v_lshlrev_b64 v[132:133], 6, v[132:133]
	v_lshl_add_u64 v[144:145], s[56:57], 0, v[132:133]
	s_nop 0
	v_add_u32_e32 v130, 48, v130
	v_ashrrev_i32_e32 v131, 31, v130
	v_lshlrev_b64 v[130:131], 6, v[130:131]
	v_lshl_add_u64 v[142:143], s[56:57], 0, v[130:131]
	s_nop 0
	s_nop 0
	s_nop 0
	s_movk_i32 s4, 0x4000
	s_nop 0
	s_nop 0
	v_mov_b32_e32 v194, v250
	s_lshl_b32 s2, s66, 5
	v_lshl_add_u32 v198, v213, 3, s2
	v_ashrrev_i32_e32 v199, 31, v198
	v_mov_b32_e32 v196, v251
	v_add_u32_e32 v129, 0xffffc000, v160
	v_lshrrev_b32_e32 v129, 6, v129
	v_cmp_gt_i32_e32 vcc, s4, v160
	v_ashrrev_i32_e32 v128, 11, v160
	v_add_u32_e32 v129, 8, v129
	v_cndmask_b32_e32 v128, v129, v128, vcc
	v_mov_b32 v136, 0
	v_lshlrev_b64 v[132:133], 2, v[198:199]
	v_add_u32_e32 v130, v136, v128
	v_mov_b64_e32 v[128:129], s[10:11]
	v_mad_i64_i32 v[130:131], s[2:3], v130, s51, v[128:129]
	v_lshl_add_u64 v[130:131], v[130:131], 0, v[132:133]
	v_lshl_add_u64 v[134:135], v[130:131], 0, s[6:7]
	v_add_co_u32_e32 v130, vcc, s79, v130
	s_nop 1
	v_addc_co_u32_e32 v131, vcc, 0, v131, vcc
	global_load_dwordx4 v[148:151], v[130:131], off offset:1024
	global_load_dwordx4 v[152:155], v[134:135], off offset:16
	global_load_dwordx4 v[144:147], v[134:135], off offset:528
	global_load_dwordx4 v[156:159], v[134:135], off offset:512
	v_add_u32_e32 v131, 0xffffc080, v160
	v_lshrrev_b32_e32 v131, 6, v131
	v_cmp_gt_i32_e32 vcc, s4, v174
	v_ashrrev_i32_e32 v130, 11, v174
	v_add_u32_e32 v131, 8, v131
	v_cndmask_b32_e32 v130, v131, v130, vcc
	v_add_u32_e32 v130, v136, v130
	v_mad_i64_i32 v[128:129], s[2:3], v130, s51, v[128:129]
	v_lshl_add_u64 v[128:129], v[128:129], 0, v[132:133]
	v_lshl_add_u64 v[132:133], v[128:129], 0, s[6:7]
	v_add_co_u32_e32 v128, vcc, s79, v128
	v_readlane_b32 s2, v254, 44
	s_nop 0
	v_addc_co_u32_e32 v129, vcc, 0, v129, vcc
	global_load_dwordx4 v[140:143], v[128:129], off offset:1024
	global_load_dwordx4 v[136:139], v[132:133], off offset:16
	s_nop 0
	global_load_dwordx4 v[128:131], v[132:133], off offset:528
	s_nop 0
	global_load_dwordx4 v[132:135], v[132:133], off offset:512
	v_readlane_b32 s3, v254, 45
	s_waitcnt vmcnt(7)
	v_pk_fma_f32 v[200:201], v[124:125], v[170:171], v[148:149] op_sel_hi:[1,0,1]
	v_lshl_add_u64 v[198:199], v[198:199], 1, s[2:3]
	v_pk_fma_f32 v[202:203], v[126:127], v[170:171], v[150:151] op_sel_hi:[1,0,1]
	s_waitcnt vmcnt(6)
	v_pk_fma_f32 v[204:205], v[120:121], v[170:171], v[152:153] op_sel_hi:[1,0,1]
	v_pk_fma_f32 v[206:207], v[122:123], v[170:171], v[154:155] op_sel_hi:[1,0,1]
	s_waitcnt vmcnt(4)
; DI u32x4 pack8(const float* v) { u32x4 w; w.x = pk2(v[0], v[1]); w.y = pk2(v[2], v[3]); w.z = pk2(v[4], v[5]); w.w = pk2(v[6], v[7]); return w; }
; DI float silu(float x) { return x * __builtin_amdgcn_rcpf(1.f + ex2(-x * LOG2E)); }
;     template <int PN> DI void body(AccRef acc, const Unit& u, int wr, int wc, int fr, int fq) const {
;     ...
; #pragma unroll
;         for (int ai = 0; ai < 2; ++ai) {
;             const int rb = u.pm * 256 + ai * 128 + wr * 64 + fr;
;             int mb, pos0, kv0; row_info(rb, mb, pos0, kv0);
; #pragma unroll
;             for (int m = 0; m < 4; ++m) {
;                 const int row = rb + 16 * m, pos = pos0 + 16 * m, kvrow = kv0 + 16 * m;
;                 const float rinv = rinvh[ai][m];
;                 float v[2][8];
; #pragma unroll
;                 for (int bj = 0; bj < 2; ++bj)
; #pragma unroll
;                     for (int n = 0; n < 2; ++n)
; #pragma unroll
;                         for (int j = 0; j < 4; ++j) v[bj][4 * n + j] = acc[ai][bj][m][n][j] * rinv + cvh[ai][bj][n][j];
;     ...
;                 } else if constexpr (PN == 5 || PN == 6 || PN == 7) {
;                     bf16_t* dst = PN == 5 ? rv : (PN == 6 ? rg : sq);
; #pragma unroll
;                     for (int bj = 0; bj < 2; ++bj) {
;                         if constexpr (PN == 6) {
; #pragma unroll
;                             for (int j = 0; j < 8; ++j) v[bj][j] = silu(v[bj][j]);
;                         }
;                         if constexpr (PN == 7) {
; #pragma unroll
;                             for (int j = 0; j < 8; ++j) v[bj][j] *= 0.125f;
;                         }
;                         *(u32x4*)(dst + (size_t)row * 256 + bj * 128 + cl) = pack8(v[bj]);
;                     }
	v_pk_fma_f32 v[216:217], v[116:117], v[170:171], v[156:157] op_sel_hi:[1,0,1]
	v_pk_fma_f32 v[218:219], v[118:119], v[170:171], v[158:159] op_sel_hi:[1,0,1]
	v_pk_fma_f32 v[220:221], v[112:113], v[170:171], v[144:145] op_sel_hi:[1,0,1]
	v_pk_fma_f32 v[170:171], v[114:115], v[170:171], v[146:147] op_sel_hi:[1,0,1]
	v_lshl_add_u64 v[222:223], v[198:199], 0, v[222:223]
	v_cvt_pk_bf16_f32 v200, v200, v201
	v_cvt_pk_bf16_f32 v201, v202, v203
	v_cvt_pk_bf16_f32 v202, v204, v205
	v_cvt_pk_bf16_f32 v203, v206, v207
	global_store_dwordx4 v[222:223], v[200:203], off
	v_pk_fma_f32 v[204:205], v[110:111], v[168:169], v[150:151] op_sel_hi:[1,0,1]
	v_pk_fma_f32 v[206:207], v[104:105], v[168:169], v[152:153] op_sel_hi:[1,0,1]
	v_cvt_pk_bf16_f32 v200, v216, v217
	v_cvt_pk_bf16_f32 v201, v218, v219
	v_cvt_pk_bf16_f32 v202, v220, v221
	v_cvt_pk_bf16_f32 v203, v170, v171
	global_store_dwordx4 v[222:223], v[200:203], off offset:256
	v_pk_fma_f32 v[216:217], v[106:107], v[168:169], v[154:155] op_sel_hi:[1,0,1]
	v_pk_fma_f32 v[218:219], v[100:101], v[168:169], v[156:157] op_sel_hi:[1,0,1]
	v_pk_fma_f32 v[202:203], v[108:109], v[168:169], v[148:149] op_sel_hi:[1,0,1]
	v_pk_fma_f32 v[200:201], v[102:103], v[168:169], v[158:159] op_sel_hi:[1,0,1]
	v_pk_fma_f32 v[170:171], v[96:97], v[168:169], v[144:145] op_sel_hi:[1,0,1]
	v_pk_fma_f32 v[168:169], v[98:99], v[168:169], v[146:147] op_sel_hi:[1,0,1]
	v_lshl_add_u64 v[166:167], v[198:199], 0, v[166:167]
	v_cvt_pk_bf16_f32 v202, v202, v203
	v_cvt_pk_bf16_f32 v203, v204, v205
	v_cvt_pk_bf16_f32 v204, v206, v207
	v_cvt_pk_bf16_f32 v205, v216, v217
	global_store_dwordx4 v[166:167], v[202:205], off
	v_pk_fma_f32 v[206:207], v[80:81], v[172:173], v[144:145] op_sel_hi:[1,0,1]
	v_lshl_add_u64 v[162:163], v[198:199], 0, v[162:163]
	v_cvt_pk_bf16_f32 v202, v218, v219
	v_cvt_pk_bf16_f32 v203, v200, v201
	v_cvt_pk_bf16_f32 v204, v170, v171
	v_cvt_pk_bf16_f32 v205, v168, v169
	global_store_dwordx4 v[166:167], v[202:205], off offset:256
	v_pk_fma_f32 v[166:167], v[92:93], v[172:173], v[148:149] op_sel_hi:[1,0,1]
	v_pk_fma_f32 v[168:169], v[94:95], v[172:173], v[150:151] op_sel_hi:[1,0,1]
	v_pk_fma_f32 v[170:171], v[88:89], v[172:173], v[152:153] op_sel_hi:[1,0,1]
	v_pk_fma_f32 v[200:201], v[90:91], v[172:173], v[154:155] op_sel_hi:[1,0,1]
	v_pk_fma_f32 v[202:203], v[84:85], v[172:173], v[156:157] op_sel_hi:[1,0,1]
	v_pk_fma_f32 v[204:205], v[86:87], v[172:173], v[158:159] op_sel_hi:[1,0,1]
	v_pk_fma_f32 v[172:173], v[82:83], v[172:173], v[146:147] op_sel_hi:[1,0,1]
	v_cvt_pk_bf16_f32 v166, v166, v167
	v_cvt_pk_bf16_f32 v167, v168, v169
	v_cvt_pk_bf16_f32 v168, v170, v171
	v_cvt_pk_bf16_f32 v169, v200, v201
	global_store_dwordx4 v[162:163], v[166:169], off
	v_pk_fma_f32 v[148:149], v[76:77], v[188:189], v[148:149] op_sel_hi:[1,0,1]
	v_pk_fma_f32 v[150:151], v[78:79], v[188:189], v[150:151] op_sel_hi:[1,0,1]
	v_cvt_pk_bf16_f32 v166, v202, v203
	v_cvt_pk_bf16_f32 v167, v204, v205
	v_cvt_pk_bf16_f32 v168, v206, v207
	v_cvt_pk_bf16_f32 v169, v172, v173
	global_store_dwordx4 v[162:163], v[166:169], off offset:256
	v_pk_fma_f32 v[152:153], v[72:73], v[188:189], v[152:153] op_sel_hi:[1,0,1]
	v_pk_fma_f32 v[154:155], v[74:75], v[188:189], v[154:155] op_sel_hi:[1,0,1]
	v_pk_fma_f32 v[162:163], v[64:65], v[188:189], v[144:145] op_sel_hi:[1,0,1]
	v_lshlrev_b64 v[144:145], 9, v[164:165]
	v_pk_fma_f32 v[156:157], v[68:69], v[188:189], v[156:157] op_sel_hi:[1,0,1]
	v_pk_fma_f32 v[158:159], v[70:71], v[188:189], v[158:159] op_sel_hi:[1,0,1]
	v_pk_fma_f32 v[166:167], v[66:67], v[188:189], v[146:147] op_sel_hi:[1,0,1]
	v_lshl_add_u64 v[164:165], v[198:199], 0, v[144:145]
	v_cvt_pk_bf16_f32 v144, v148, v149
	v_cvt_pk_bf16_f32 v145, v150, v151
	v_cvt_pk_bf16_f32 v146, v152, v153
	v_cvt_pk_bf16_f32 v147, v154, v155
	global_store_dwordx4 v[164:165], v[144:147], off
	s_waitcnt vmcnt(9)
	v_pk_fma_f32 v[148:149], v[56:57], v[192:193], v[136:137] op_sel_hi:[1,0,1]
	v_pk_fma_f32 v[150:151], v[58:59], v[192:193], v[138:139] op_sel_hi:[1,0,1]
	v_cvt_pk_bf16_f32 v144, v156, v157
	v_cvt_pk_bf16_f32 v145, v158, v159
	v_cvt_pk_bf16_f32 v146, v162, v163
	v_cvt_pk_bf16_f32 v147, v166, v167
	global_store_dwordx4 v[164:165], v[144:147], off offset:256
	v_lshlrev_b64 v[162:163], 9, v[174:175]
	s_waitcnt vmcnt(8)
; DI u32x4 pack8(const float* v) { u32x4 w; w.x = pk2(v[0], v[1]); w.y = pk2(v[2], v[3]); w.z = pk2(v[4], v[5]); w.w = pk2(v[6], v[7]); return w; }
; DI float silu(float x) { return x * __builtin_amdgcn_rcpf(1.f + ex2(-x * LOG2E)); }
;     template <int PN> DI void body(AccRef acc, const Unit& u, int wr, int wc, int fr, int fq) const {
;     ...
; #pragma unroll
;         for (int ai = 0; ai < 2; ++ai) {
;             const int rb = u.pm * 256 + ai * 128 + wr * 64 + fr;
;             int mb, pos0, kv0; row_info(rb, mb, pos0, kv0);
; #pragma unroll
;             for (int m = 0; m < 4; ++m) {
;                 const int row = rb + 16 * m, pos = pos0 + 16 * m, kvrow = kv0 + 16 * m;
;                 const float rinv = rinvh[ai][m];
;                 float v[2][8];
; #pragma unroll
;                 for (int bj = 0; bj < 2; ++bj)
; #pragma unroll
;                     for (int n = 0; n < 2; ++n)
; #pragma unroll
;                         for (int j = 0; j < 4; ++j) v[bj][4 * n + j] = acc[ai][bj][m][n][j] * rinv + cvh[ai][bj][n][j];
;     ...
;                 } else if constexpr (PN == 5 || PN == 6 || PN == 7) {
;                     bf16_t* dst = PN == 5 ? rv : (PN == 6 ? rg : sq);
; #pragma unroll
;                     for (int bj = 0; bj < 2; ++bj) {
;                         if constexpr (PN == 6) {
; #pragma unroll
;                             for (int j = 0; j < 8; ++j) v[bj][j] = silu(v[bj][j]);
;                         }
;                         if constexpr (PN == 7) {
; #pragma unroll
;                             for (int j = 0; j < 8; ++j) v[bj][j] *= 0.125f;
;                         }
;                         *(u32x4*)(dst + (size_t)row * 256 + bj * 128 + cl) = pack8(v[bj]);
;                     }
	v_pk_fma_f32 v[152:153], v[52:53], v[192:193], v[132:133] op_sel_hi:[1,0,1]
	v_pk_fma_f32 v[144:145], v[60:61], v[192:193], v[140:141] op_sel_hi:[1,0,1]
	v_pk_fma_f32 v[146:147], v[62:63], v[192:193], v[142:143] op_sel_hi:[1,0,1]
	v_pk_fma_f32 v[154:155], v[54:55], v[192:193], v[134:135] op_sel_hi:[1,0,1]
	v_pk_fma_f32 v[156:157], v[48:49], v[192:193], v[128:129] op_sel_hi:[1,0,1]
	v_pk_fma_f32 v[158:159], v[50:51], v[192:193], v[130:131] op_sel_hi:[1,0,1]
	v_lshl_add_u64 v[162:163], v[198:199], 0, v[162:163]
	v_cvt_pk_bf16_f32 v144, v144, v145
	v_cvt_pk_bf16_f32 v145, v146, v147
	v_cvt_pk_bf16_f32 v146, v148, v149
	v_cvt_pk_bf16_f32 v147, v150, v151
	global_store_dwordx4 v[162:163], v[144:147], off
	v_pk_fma_f32 v[148:149], v[40:41], v[190:191], v[136:137] op_sel_hi:[1,0,1]
	v_pk_fma_f32 v[150:151], v[42:43], v[190:191], v[138:139] op_sel_hi:[1,0,1]
	v_cvt_pk_bf16_f32 v144, v152, v153
	v_cvt_pk_bf16_f32 v145, v154, v155
	v_cvt_pk_bf16_f32 v146, v156, v157
	v_cvt_pk_bf16_f32 v147, v158, v159
	global_store_dwordx4 v[162:163], v[144:147], off offset:256
	v_add_u32_e32 v162, 0x90, v160
	v_ashrrev_i32_e32 v163, 31, v162
	v_pk_fma_f32 v[144:145], v[44:45], v[190:191], v[140:141] op_sel_hi:[1,0,1]
	v_pk_fma_f32 v[146:147], v[46:47], v[190:191], v[142:143] op_sel_hi:[1,0,1]
	v_lshlrev_b64 v[162:163], 9, v[162:163]
	v_pk_fma_f32 v[152:153], v[36:37], v[190:191], v[132:133] op_sel_hi:[1,0,1]
	v_pk_fma_f32 v[154:155], v[38:39], v[190:191], v[134:135] op_sel_hi:[1,0,1]
	v_pk_fma_f32 v[156:157], v[28:29], v[190:191], v[128:129] op_sel_hi:[1,0,1]
	v_pk_fma_f32 v[158:159], v[30:31], v[190:191], v[130:131] op_sel_hi:[1,0,1]
	v_lshl_add_u64 v[162:163], v[198:199], 0, v[162:163]
	v_cvt_pk_bf16_f32 v144, v144, v145
	v_cvt_pk_bf16_f32 v145, v146, v147
	v_cvt_pk_bf16_f32 v146, v148, v149
	v_cvt_pk_bf16_f32 v147, v150, v151
	global_store_dwordx4 v[162:163], v[144:147], off
	v_pk_fma_f32 v[148:149], v[24:25], v[194:195], v[136:137] op_sel_hi:[1,0,1]
	v_pk_fma_f32 v[150:151], v[26:27], v[194:195], v[138:139] op_sel_hi:[1,0,1]
	v_cvt_pk_bf16_f32 v144, v152, v153
	v_cvt_pk_bf16_f32 v145, v154, v155
	v_cvt_pk_bf16_f32 v146, v156, v157
	v_cvt_pk_bf16_f32 v147, v158, v159
	global_store_dwordx4 v[162:163], v[144:147], off offset:256
	v_add_u32_e32 v162, 0xa0, v160
	v_ashrrev_i32_e32 v163, 31, v162
	v_pk_fma_f32 v[144:145], v[32:33], v[194:195], v[140:141] op_sel_hi:[1,0,1]
	v_pk_fma_f32 v[146:147], v[34:35], v[194:195], v[142:143] op_sel_hi:[1,0,1]
	v_lshlrev_b64 v[162:163], 9, v[162:163]
	v_pk_fma_f32 v[152:153], v[20:21], v[194:195], v[132:133] op_sel_hi:[1,0,1]
	v_pk_fma_f32 v[154:155], v[22:23], v[194:195], v[134:135] op_sel_hi:[1,0,1]
	v_pk_fma_f32 v[156:157], v[16:17], v[194:195], v[128:129] op_sel_hi:[1,0,1]
	v_pk_fma_f32 v[158:159], v[18:19], v[194:195], v[130:131] op_sel_hi:[1,0,1]
	v_lshl_add_u64 v[162:163], v[198:199], 0, v[162:163]
	v_cvt_pk_bf16_f32 v144, v144, v145
	v_cvt_pk_bf16_f32 v145, v146, v147
	v_cvt_pk_bf16_f32 v146, v148, v149
	v_cvt_pk_bf16_f32 v147, v150, v151
	global_store_dwordx4 v[162:163], v[144:147], off
	v_pk_fma_f32 v[140:141], v[12:13], v[196:197], v[140:141] op_sel_hi:[1,0,1]
	v_pk_fma_f32 v[142:143], v[14:15], v[196:197], v[142:143] op_sel_hi:[1,0,1]
	v_cvt_pk_bf16_f32 v144, v152, v153
	v_cvt_pk_bf16_f32 v145, v154, v155
	v_cvt_pk_bf16_f32 v146, v156, v157
	v_cvt_pk_bf16_f32 v147, v158, v159
	global_store_dwordx4 v[162:163], v[144:147], off offset:256
	v_pk_fma_f32 v[136:137], v[8:9], v[196:197], v[136:137] op_sel_hi:[1,0,1]
	v_pk_fma_f32 v[138:139], v[10:11], v[196:197], v[138:139] op_sel_hi:[1,0,1]
	v_pk_fma_f32 v[144:145], v[0:1], v[196:197], v[128:129] op_sel_hi:[1,0,1]
	v_add_u32_e32 v128, 0xb0, v160
	v_ashrrev_i32_e32 v129, 31, v128
	v_lshlrev_b64 v[128:129], 9, v[128:129]
	v_pk_fma_f32 v[132:133], v[4:5], v[196:197], v[132:133] op_sel_hi:[1,0,1]
	v_pk_fma_f32 v[134:135], v[6:7], v[196:197], v[134:135] op_sel_hi:[1,0,1]
	v_pk_fma_f32 v[146:147], v[2:3], v[196:197], v[130:131] op_sel_hi:[1,0,1]
	v_lshl_add_u64 v[148:149], v[198:199], 0, v[128:129]
	v_cvt_pk_bf16_f32 v128, v140, v141
	v_cvt_pk_bf16_f32 v129, v142, v143
	v_cvt_pk_bf16_f32 v130, v136, v137
	v_cvt_pk_bf16_f32 v131, v138, v139
	global_store_dwordx4 v[148:149], v[128:131], off
	s_mov_b64 s[2:3], 0
	s_nop 0
	v_cvt_pk_bf16_f32 v128, v132, v133
	v_cvt_pk_bf16_f32 v129, v134, v135
	v_cvt_pk_bf16_f32 v130, v144, v145
	v_cvt_pk_bf16_f32 v131, v146, v147
	global_store_dwordx4 v[148:149], v[128:131], off offset:256
; DI u32x2 pack4(const float* v) { u32x2 w; w.x = pk2(v[0], v[1]); w.y = pk2(v[2], v[3]); return w; }
; DI float ex2(float x) { return __builtin_amdgcn_exp2f(x); }
; DI void sincos_rev(float ang, float& s, float& c) { float rev = ang * 0.15915494309189535f; rev = __builtin_amdgcn_fractf(rev); s = __builtin_amdgcn_sinf(rev); c = __builtin_amdgcn_cosf(rev); }
; DI float sum16(const float* p) { const f32x4* q = (const f32x4*)p; f32x4 a = q[0], b = q[1], c = q[2], d = q[3]; f32x4 s = (a + b) + (c + d); return (s[0] + s[1]) + (s[2] + s[3]); }
;     template <int PN> DI void body(AccRef acc, const Unit& u, int wr, int wc, int fr, int fq) const {
;     ...
;         for (int ai = 0; ai < 2; ++ai) {
;             const int rb_ = u.pm * 256 + ai * 128 + wr * 64 + fr;
; #pragma unroll
;             for (int m = 0; m < 4; ++m) rinvh[ai][m] = rsqrtf(sum16(ssq + (size_t)(rb_ + 16 * m + zdep) * 16) * (1.f / 1024.f) + EPS);
;             asm volatile("v_mov_b32 %0, 0" : "=v"(zdep) : "v"(rinvh[ai][0]), "v"(rinvh[ai][1]), "v"(rinvh[ai][2]), "v"(rinvh[ai][3]));
;         }
; #pragma unroll
;         for (int ai = 0; ai < 2; ++ai) {
;             const int rb_ = u.pm * 256 + ai * 128 + wr * 64 + fr;
;             int mb_, p_, k_; row_info(rb_, mb_, p_, k_);
; #pragma unroll
;             for (int bj = 0; bj < 2; ++bj)
; #pragma unroll
;                 for (int n = 0; n < 2; ++n) cvh[ai][bj][n] = *(const f32x4*)(cv + (size_t)(mb_ + zdep) * NIN + PN * 256 + bj * 128 + cl + 4 * n);
;         }
;     ...
;                 } else if constexpr (PN == 3 || PN == 4) {
;                     bf16_t* dst = PN == 3 ? rq : rk;
;                     const float sc = PN == 3 ? 0.125f : 1.f;
; #pragma unroll
;                     for (int bj = 0; bj < 2; ++bj) {
;                         const int head = 2 * bj + (wc >> 1), i0 = 16 * (wc & 1) + 4 * fq;
;                         float o1[4], o2[4];
; #pragma unroll
;                         for (int j = 0; j < 4; ++j) { float sn, cs; sincos_rev((float)pos * ex2(-(float)(i0 + j) * KEXP64), sn, cs);
;                             o1[j] = (v[bj][j] * cs - v[bj][4 + j] * sn) * sc; o2[j] = (v[bj][j] * sn + v[bj][4 + j] * cs) * sc; }
;                         *(u32x2*)(dst + (size_t)row * 256 + head * 64 + i0) = pack4(o1);
;                         *(u32x2*)(dst + (size_t)row * 256 + head * 64 + 32 + i0) = pack4(o2);
;                     }
.LBB0_369:
	s_andn2_b64 vcc, exec, s[2:3]
	s_cbranch_vccnz .LBB0_371
	s_lshl_b32 s2, s53, 6
	s_lshl_b32 s3, s34, 8
	s_add_i32 s2, s2, s3
	v_add_u32_e32 v160, s2, v214
	v_add_u32_e32 v164, 16, v160
	v_ashrrev_i32_e32 v161, 31, v160
	v_ashrrev_i32_e32 v165, 31, v164
	v_lshlrev_b64 v[128:129], 6, v[160:161]
	v_lshlrev_b64 v[144:145], 6, v[164:165]
	v_add_u32_e32 v166, 32, v160
	v_lshl_add_u64 v[140:141], s[56:57], 0, v[128:129]
	v_lshl_add_u64 v[144:145], s[56:57], 0, v[144:145]
	v_ashrrev_i32_e32 v167, 31, v166
	s_nop 0
	s_nop 0
	v_lshlrev_b64 v[144:145], 6, v[166:167]
	v_add_u32_e32 v162, 48, v160
	v_lshl_add_u64 v[144:145], s[56:57], 0, v[144:145]
	v_ashrrev_i32_e32 v163, 31, v162
	v_lshlrev_b64 v[144:145], 6, v[162:163]
	v_lshl_add_u64 v[144:145], s[56:57], 0, v[144:145]
	s_mov_b32 s2, 0x358637bd
	v_mov_b64_e32 v[144:145], s[2:3]
	s_mov_b32 s12, 0x3a800000
	v_lshlrev_b64 v[164:165], 9, v[164:165]
	v_lshl_add_u64 v[164:165], s[14:15], 0, v[164:165]
	v_lshlrev_b64 v[162:163], 9, v[162:163]
	v_lshl_add_u64 v[162:163], s[14:15], 0, v[162:163]
	v_mov_b32_e32 v190, v245
	v_mov_b32_e32 v174, v246
	v_add_u32_e32 v168, 0x80, v160
	v_mov_b32_e32 v194, v244
	v_mov_b32_e32 v170, v247
	v_mov_b32 v128, 0
	s_movk_i32 s7, 0x4000
	v_add_u32_e32 v158, v128, v168
	v_add_u32_e32 v146, 16, v158
	v_ashrrev_i32_e32 v159, 31, v158
	v_ashrrev_i32_e32 v147, 31, v146
	v_lshlrev_b64 v[128:129], 6, v[158:159]
	v_lshlrev_b64 v[146:147], 6, v[146:147]
	v_lshl_add_u64 v[140:141], s[56:57], 0, v[128:129]
	v_lshl_add_u64 v[172:173], s[56:57], 0, v[146:147]
	s_nop 0
	s_nop 0
	v_add_u32_e32 v172, 32, v158
	v_ashrrev_i32_e32 v173, 31, v172
	v_add_u32_e32 v158, 48, v158
	v_lshlrev_b64 v[172:173], 6, v[172:173]
	v_ashrrev_i32_e32 v159, 31, v158
	v_lshl_add_u64 v[172:173], s[56:57], 0, v[172:173]
	v_lshlrev_b64 v[158:159], 6, v[158:159]
	v_lshl_add_u64 v[158:159], s[56:57], 0, v[158:159]
	s_lshl_b32 s6, s66, 5
	v_mov_b32_e32 v196, v248
	v_mov_b32_e32 v192, v249
	v_mov_b32_e32 v188, v250
	v_mov_b32_e32 v172, v251
	v_add_u32_e32 v129, 0xffffc000, v160
	v_lshrrev_b32_e32 v129, 6, v129
	v_ashrrev_i32_e32 v128, 11, v160
	v_add_u32_e32 v129, 8, v129
	v_cmp_gt_i32_e64 s[2:3], s7, v160
	v_lshl_add_u32 v130, v213, 3, s6
	v_mov_b32 v136, 0
	v_ashrrev_i32_e32 v131, 31, v130
	v_cndmask_b32_e64 v128, v129, v128, s[2:3]
	v_add_u32_e32 v132, v136, v128
	v_mov_b64_e32 v[128:129], s[10:11]
	v_mad_i64_i32 v[132:133], s[4:5], v132, s51, v[128:129]
	v_lshlrev_b64 v[130:131], 2, v[130:131]
	v_lshl_add_u64 v[132:133], v[132:133], 0, v[130:131]
	s_mov_b64 s[12:13], 0x125000
	v_lshl_add_u64 v[134:135], v[132:133], 0, s[12:13]
	v_add_co_u32_e32 v132, vcc, s79, v132
	s_lshl_b32 s4, s66, 4
	s_nop 0
	v_addc_co_u32_e32 v133, vcc, 0, v133, vcc
	global_load_dwordx4 v[144:147], v[132:133], off
	global_load_dwordx4 v[148:151], v[134:135], off offset:16
	global_load_dwordx4 v[156:159], v[134:135], off offset:512
	global_load_dwordx4 v[152:155], v[134:135], off offset:528
	s_and_b32 s5, s4, 16
	v_lshl_add_u32 v198, v213, 2, s5
	v_cvt_f32_i32_e32 v138, v198
	v_or_b32_e32 v139, 1, v198
	v_mov_b32_e32 v132, 0x400
	v_cvt_f32_i32_e32 v139, v139
	v_and_or_b32 v169, v214, 63, v132
	v_add_u32_e32 v132, 0xffffc080, v160
	v_and_b32_e32 v137, 0x7ff, v160
	v_lshrrev_b32_e32 v140, 6, v132
	v_lshlrev_b64 v[132:133], 9, v[160:161]
	v_or_b32_e32 v134, 2, v198
	v_lshl_add_u64 v[200:201], s[14:15], 0, v[132:133]
	v_cndmask_b32_e64 v189, v169, v137, s[2:3]
	v_mul_f32_e32 v133, 0xbed49a78, v138
	v_cvt_f32_i32_e32 v134, v134
	v_cvt_f32_u32_e32 v191, v189
	v_exp_f32_e32 v161, v133
	v_mul_f32_e32 v133, 0xbed49a78, v139
	v_or_b32_e32 v175, 3, v198
	v_exp_f32_e32 v173, v133
	v_cvt_f32_i32_e32 v175, v175
	v_mul_f32_e32 v134, 0xbed49a78, v134
	v_mul_f32_e32 v133, v161, v191
	v_exp_f32_e32 v171, v134
	v_mul_f32_e32 v133, 0.15915494, v133
	v_mul_f32_e32 v134, v173, v191
	v_mul_f32_e32 v175, 0xbed49a78, v175
	v_fract_f32_e32 v133, v133
	v_mul_f32_e32 v134, 0.15915494, v134
	v_exp_f32_e32 v175, v175
	v_sin_f32_e32 v202, v133
	v_cos_f32_e32 v204, v133
	v_fract_f32_e32 v133, v134
	v_sin_f32_e32 v203, v133
	v_cos_f32_e32 v205, v133
	v_ashrrev_i32_e32 v135, 11, v168
	v_add_u32_e32 v140, 8, v140
	v_cmp_gt_i32_e32 vcc, s7, v168
	v_mul_f32_e32 v193, v171, v191
	v_mul_f32_e32 v191, v175, v191
	v_cndmask_b32_e32 v132, v140, v135, vcc
	v_mul_f32_e32 v193, 0.15915494, v193
	v_mul_f32_e32 v191, 0.15915494, v191
	v_add_u32_e32 v132, v136, v132
	v_fract_f32_e32 v193, v193
	v_fract_f32_e32 v191, v191
	v_mad_i64_i32 v[128:129], s[2:3], v132, s51, v[128:129]
	v_cos_f32_e32 v220, v193
	v_cos_f32_e32 v221, v191
	v_lshl_add_u64 v[128:129], v[128:129], 0, v[130:131]
	s_and_b32 s4, s6, 0xffffffc0
	v_lshl_add_u64 v[132:133], v[128:129], 0, s[12:13]
	v_add_co_u32_e64 v128, s[2:3], s79, v128
	s_ashr_i32 s5, s4, 31
	s_nop 0
	v_addc_co_u32_e64 v129, s[2:3], 0, v129, s[2:3]
	v_ashrrev_i32_e32 v199, 31, v198
	s_lshl_b64 s[2:3], s[4:5], 1
	v_lshl_add_u64 v[200:201], v[200:201], 0, s[2:3]
	v_lshlrev_b64 v[198:199], 1, v[198:199]
	v_lshl_add_u64 v[200:201], v[200:201], 0, v[198:199]
	global_load_dwordx4 v[140:143], v[128:129], off
	s_nop 0
	global_load_dwordx4 v[128:131], v[132:133], off offset:528
	global_load_dwordx4 v[136:139], v[132:133], off offset:16
	s_nop 0
	global_load_dwordx4 v[132:135], v[132:133], off offset:512
	v_lshl_add_u64 v[164:165], v[164:165], 0, s[2:3]
	v_lshl_add_u64 v[164:165], v[164:165], 0, v[198:199]
	s_waitcnt vmcnt(7)
	v_pk_fma_f32 v[206:207], v[124:125], v[194:195], v[144:145] op_sel_hi:[1,0,1]
	s_waitcnt vmcnt(6)
; DI u32x2 pack4(const float* v) { u32x2 w; w.x = pk2(v[0], v[1]); w.y = pk2(v[2], v[3]); return w; }
; DI float ex2(float x) { return __builtin_amdgcn_exp2f(x); }
; DI void sincos_rev(float ang, float& s, float& c) { float rev = ang * 0.15915494309189535f; rev = __builtin_amdgcn_fractf(rev); s = __builtin_amdgcn_sinf(rev); c = __builtin_amdgcn_cosf(rev); }
;     template <int PN> DI void body(AccRef acc, const Unit& u, int wr, int wc, int fr, int fq) const {
;     ...
;         for (int ai = 0; ai < 2; ++ai) {
;             const int rb = u.pm * 256 + ai * 128 + wr * 64 + fr;
;             int mb, pos0, kv0; row_info(rb, mb, pos0, kv0);
; #pragma unroll
;             for (int m = 0; m < 4; ++m) {
;                 const int row = rb + 16 * m, pos = pos0 + 16 * m, kvrow = kv0 + 16 * m;
;                 const float rinv = rinvh[ai][m];
;                 float v[2][8];
; #pragma unroll
;                 for (int bj = 0; bj < 2; ++bj)
; #pragma unroll
;                     for (int n = 0; n < 2; ++n)
; #pragma unroll
;                         for (int j = 0; j < 4; ++j) v[bj][4 * n + j] = acc[ai][bj][m][n][j] * rinv + cvh[ai][bj][n][j];
;     ...
;                 } else if constexpr (PN == 3 || PN == 4) {
;                     bf16_t* dst = PN == 3 ? rq : rk;
;                     const float sc = PN == 3 ? 0.125f : 1.f;
; #pragma unroll
;                     for (int bj = 0; bj < 2; ++bj) {
;                         const int head = 2 * bj + (wc >> 1), i0 = 16 * (wc & 1) + 4 * fq;
;                         float o1[4], o2[4];
; #pragma unroll
;                         for (int j = 0; j < 4; ++j) { float sn, cs; sincos_rev((float)pos * ex2(-(float)(i0 + j) * KEXP64), sn, cs);
;                             o1[j] = (v[bj][j] * cs - v[bj][4 + j] * sn) * sc; o2[j] = (v[bj][j] * sn + v[bj][4 + j] * cs) * sc; }
;                         *(u32x2*)(dst + (size_t)row * 256 + head * 64 + i0) = pack4(o1);
;                         *(u32x2*)(dst + (size_t)row * 256 + head * 64 + 32 + i0) = pack4(o2);
;                     }
	v_pk_fma_f32 v[216:217], v[120:121], v[194:195], v[148:149] op_sel_hi:[1,0,1]
	v_pk_fma_f32 v[228:229], v[122:123], v[194:195], v[150:151] op_sel_hi:[1,0,1]
	v_pk_mul_f32 v[218:219], v[204:205], v[216:217]
	v_pk_mul_f32 v[216:217], v[202:203], v[216:217]
	v_pk_fma_f32 v[218:219], v[202:203], v[206:207], v[218:219]
	v_pk_fma_f32 v[206:207], v[204:205], v[206:207], v[216:217] neg_lo:[0,0,1] neg_hi:[0,0,1]
	v_sin_f32_e32 v216, v193
	v_sin_f32_e32 v217, v191
	v_pk_fma_f32 v[222:223], v[126:127], v[194:195], v[146:147] op_sel_hi:[1,0,1]
	v_pk_mul_f32 v[230:231], v[220:221], v[228:229]
	v_cvt_pk_bf16_f32 v206, v206, v207
	v_pk_mul_f32 v[228:229], v[216:217], v[228:229]
	v_pk_fma_f32 v[230:231], v[216:217], v[222:223], v[230:231]
	v_pk_fma_f32 v[222:223], v[220:221], v[222:223], v[228:229] neg_lo:[0,0,1] neg_hi:[0,0,1]
	v_add_u32_e32 v191, 16, v189
	v_cvt_pk_bf16_f32 v207, v222, v223
	global_store_dwordx2 v[200:201], v[206:207], off
	v_cvt_pk_bf16_f32 v206, v218, v219
	v_cvt_pk_bf16_f32 v207, v230, v231
	s_waitcnt vmcnt(5)
	v_pk_fma_f32 v[218:219], v[112:113], v[194:195], v[152:153] op_sel_hi:[1,0,1]
	v_cvt_f32_u32_e32 v191, v191
	global_store_dwordx2 v[200:201], v[206:207], off offset:64
	v_pk_fma_f32 v[206:207], v[116:117], v[194:195], v[156:157] op_sel_hi:[1,0,1]
	v_pk_mul_f32 v[222:223], v[204:205], v[218:219]
	v_mul_f32_e32 v193, v161, v191
	v_pk_fma_f32 v[222:223], v[202:203], v[206:207], v[222:223]
	v_pk_mul_f32 v[202:203], v[202:203], v[218:219]
	v_mul_f32_e32 v193, 0.15915494, v193
	v_pk_fma_f32 v[202:203], v[204:205], v[206:207], v[202:203] neg_lo:[0,0,1] neg_hi:[0,0,1]
	v_pk_fma_f32 v[204:205], v[118:119], v[194:195], v[158:159] op_sel_hi:[1,0,1]
	v_pk_fma_f32 v[194:195], v[114:115], v[194:195], v[154:155] op_sel_hi:[1,0,1]
	v_cvt_pk_bf16_f32 v202, v202, v203
	v_pk_mul_f32 v[206:207], v[220:221], v[194:195]
	v_pk_mul_f32 v[194:195], v[216:217], v[194:195]
	v_pk_fma_f32 v[206:207], v[216:217], v[204:205], v[206:207]
	v_pk_fma_f32 v[194:195], v[220:221], v[204:205], v[194:195] neg_lo:[0,0,1] neg_hi:[0,0,1]
	v_fract_f32_e32 v193, v193
	v_cvt_pk_bf16_f32 v203, v194, v195
	v_cvt_pk_bf16_f32 v194, v222, v223
	v_cvt_pk_bf16_f32 v195, v206, v207
	global_store_dwordx2 v[200:201], v[202:203], off offset:256
	global_store_dwordx2 v[200:201], v[194:195], off offset:320
	v_sin_f32_e32 v194, v193
	v_cos_f32_e32 v200, v193
	v_mul_f32_e32 v193, v173, v191
	v_mul_f32_e32 v193, 0.15915494, v193
	v_fract_f32_e32 v193, v193
	v_cos_f32_e32 v201, v193
	v_sin_f32_e32 v195, v193
	v_pk_fma_f32 v[202:203], v[108:109], v[190:191], v[144:145] op_sel_hi:[1,0,1]
	v_pk_fma_f32 v[204:205], v[104:105], v[190:191], v[148:149] op_sel_hi:[1,0,1]
	v_mul_f32_e32 v193, v171, v191
	v_mul_f32_e32 v191, v175, v191
	v_mul_f32_e32 v193, 0.15915494, v193
	v_mul_f32_e32 v191, 0.15915494, v191
	v_pk_mul_f32 v[206:207], v[200:201], v[204:205]
	v_pk_mul_f32 v[204:205], v[194:195], v[204:205]
	v_fract_f32_e32 v193, v193
	v_fract_f32_e32 v191, v191
	v_pk_fma_f32 v[206:207], v[194:195], v[202:203], v[206:207]
	v_pk_fma_f32 v[202:203], v[200:201], v[202:203], v[204:205] neg_lo:[0,0,1] neg_hi:[0,0,1]
	v_sin_f32_e32 v204, v193
	v_cos_f32_e32 v216, v193
	v_cos_f32_e32 v217, v191
	v_sin_f32_e32 v205, v191
	v_pk_fma_f32 v[220:221], v[106:107], v[190:191], v[150:151] op_sel_hi:[1,0,1]
	v_pk_fma_f32 v[218:219], v[110:111], v[190:191], v[146:147] op_sel_hi:[1,0,1]
	v_pk_mul_f32 v[222:223], v[216:217], v[220:221]
	v_pk_mul_f32 v[220:221], v[204:205], v[220:221]
	v_pk_fma_f32 v[222:223], v[204:205], v[218:219], v[222:223]
	v_pk_fma_f32 v[218:219], v[216:217], v[218:219], v[220:221] neg_lo:[0,0,1] neg_hi:[0,0,1]
	v_cvt_pk_bf16_f32 v202, v202, v203
	v_cvt_pk_bf16_f32 v203, v218, v219
	global_store_dwordx2 v[164:165], v[202:203], off
	v_cvt_pk_bf16_f32 v202, v206, v207
	v_cvt_pk_bf16_f32 v203, v222, v223
	v_pk_fma_f32 v[206:207], v[96:97], v[190:191], v[152:153] op_sel_hi:[1,0,1]
	global_store_dwordx2 v[164:165], v[202:203], off offset:64
	v_pk_fma_f32 v[202:203], v[100:101], v[190:191], v[156:157] op_sel_hi:[1,0,1]
	v_pk_mul_f32 v[218:219], v[200:201], v[206:207]
	v_add_u32_e32 v193, 32, v189
	v_pk_fma_f32 v[218:219], v[194:195], v[202:203], v[218:219]
	v_pk_mul_f32 v[194:195], v[194:195], v[206:207]
	v_cvt_f32_u32_e32 v193, v193
	v_pk_fma_f32 v[194:195], v[200:201], v[202:203], v[194:195] neg_lo:[0,0,1] neg_hi:[0,0,1]
	v_pk_fma_f32 v[200:201], v[102:103], v[190:191], v[158:159] op_sel_hi:[1,0,1]
	v_pk_fma_f32 v[190:191], v[98:99], v[190:191], v[154:155] op_sel_hi:[1,0,1]
	v_cvt_pk_bf16_f32 v194, v194, v195
	v_pk_mul_f32 v[202:203], v[216:217], v[190:191]
	v_pk_mul_f32 v[190:191], v[204:205], v[190:191]
	v_pk_fma_f32 v[202:203], v[204:205], v[200:201], v[202:203]
	v_pk_fma_f32 v[190:191], v[216:217], v[200:201], v[190:191] neg_lo:[0,0,1] neg_hi:[0,0,1]
	v_mul_f32_e32 v197, v171, v193
	v_cvt_pk_bf16_f32 v195, v190, v191
	v_cvt_pk_bf16_f32 v190, v218, v219
	v_cvt_pk_bf16_f32 v191, v202, v203
	global_store_dwordx2 v[164:165], v[194:195], off offset:256
	global_store_dwordx2 v[164:165], v[190:191], off offset:320
	v_lshlrev_b64 v[164:165], 9, v[166:167]
	v_mul_f32_e32 v166, v161, v193
	v_mul_f32_e32 v166, 0.15915494, v166
	v_fract_f32_e32 v167, v166
	v_sin_f32_e32 v166, v167
	v_cos_f32_e32 v190, v167
	v_mul_f32_e32 v167, v173, v193
	v_mul_f32_e32 v167, 0.15915494, v167
	v_fract_f32_e32 v167, v167
	v_cos_f32_e32 v191, v167
	v_sin_f32_e32 v167, v167
	v_mul_f32_e32 v193, v175, v193
	v_pk_fma_f32 v[200:201], v[88:89], v[174:175], v[148:149] op_sel_hi:[1,0,1]
	v_mul_f32_e32 v197, 0.15915494, v197
	v_mul_f32_e32 v193, 0.15915494, v193
	v_pk_fma_f32 v[194:195], v[92:93], v[174:175], v[144:145] op_sel_hi:[1,0,1]
; DI u32x2 pack4(const float* v) { u32x2 w; w.x = pk2(v[0], v[1]); w.y = pk2(v[2], v[3]); return w; }
; DI float ex2(float x) { return __builtin_amdgcn_exp2f(x); }
; DI void sincos_rev(float ang, float& s, float& c) { float rev = ang * 0.15915494309189535f; rev = __builtin_amdgcn_fractf(rev); s = __builtin_amdgcn_sinf(rev); c = __builtin_amdgcn_cosf(rev); }
;     template <int PN> DI void body(AccRef acc, const Unit& u, int wr, int wc, int fr, int fq) const {
;     ...
;         for (int ai = 0; ai < 2; ++ai) {
;             const int rb = u.pm * 256 + ai * 128 + wr * 64 + fr;
;             int mb, pos0, kv0; row_info(rb, mb, pos0, kv0);
; #pragma unroll
;             for (int m = 0; m < 4; ++m) {
;                 const int row = rb + 16 * m, pos = pos0 + 16 * m, kvrow = kv0 + 16 * m;
;                 const float rinv = rinvh[ai][m];
;                 float v[2][8];
; #pragma unroll
;                 for (int bj = 0; bj < 2; ++bj)
; #pragma unroll
;                     for (int n = 0; n < 2; ++n)
; #pragma unroll
;                         for (int j = 0; j < 4; ++j) v[bj][4 * n + j] = acc[ai][bj][m][n][j] * rinv + cvh[ai][bj][n][j];
;     ...
;                 } else if constexpr (PN == 3 || PN == 4) {
;                     bf16_t* dst = PN == 3 ? rq : rk;
;                     const float sc = PN == 3 ? 0.125f : 1.f;
; #pragma unroll
;                     for (int bj = 0; bj < 2; ++bj) {
;                         const int head = 2 * bj + (wc >> 1), i0 = 16 * (wc & 1) + 4 * fq;
;                         float o1[4], o2[4];
; #pragma unroll
;                         for (int j = 0; j < 4; ++j) { float sn, cs; sincos_rev((float)pos * ex2(-(float)(i0 + j) * KEXP64), sn, cs);
;                             o1[j] = (v[bj][j] * cs - v[bj][4 + j] * sn) * sc; o2[j] = (v[bj][j] * sn + v[bj][4 + j] * cs) * sc; }
;                         *(u32x2*)(dst + (size_t)row * 256 + head * 64 + i0) = pack4(o1);
;                         *(u32x2*)(dst + (size_t)row * 256 + head * 64 + 32 + i0) = pack4(o2);
;                     }
	v_pk_mul_f32 v[202:203], v[190:191], v[200:201]
	v_pk_mul_f32 v[200:201], v[166:167], v[200:201]
	v_fract_f32_e32 v197, v197
	v_fract_f32_e32 v193, v193
	v_pk_fma_f32 v[202:203], v[166:167], v[194:195], v[202:203]
	v_pk_fma_f32 v[194:195], v[190:191], v[194:195], v[200:201] neg_lo:[0,0,1] neg_hi:[0,0,1]
	v_sin_f32_e32 v200, v197
	v_cos_f32_e32 v204, v197
	v_cos_f32_e32 v205, v193
	v_sin_f32_e32 v201, v193
	v_pk_fma_f32 v[216:217], v[90:91], v[174:175], v[150:151] op_sel_hi:[1,0,1]
	v_lshl_add_u64 v[164:165], s[14:15], 0, v[164:165]
	v_pk_fma_f32 v[206:207], v[94:95], v[174:175], v[146:147] op_sel_hi:[1,0,1]
	v_pk_mul_f32 v[218:219], v[204:205], v[216:217]
	v_pk_mul_f32 v[216:217], v[200:201], v[216:217]
	v_pk_fma_f32 v[218:219], v[200:201], v[206:207], v[218:219]
	v_pk_fma_f32 v[206:207], v[204:205], v[206:207], v[216:217] neg_lo:[0,0,1] neg_hi:[0,0,1]
	v_lshl_add_u64 v[164:165], v[164:165], 0, s[2:3]
	v_cvt_pk_bf16_f32 v194, v194, v195
	v_cvt_pk_bf16_f32 v195, v206, v207
	v_lshl_add_u64 v[164:165], v[164:165], 0, v[198:199]
	global_store_dwordx2 v[164:165], v[194:195], off
	v_cvt_pk_bf16_f32 v194, v202, v203
	v_cvt_pk_bf16_f32 v195, v218, v219
	v_pk_fma_f32 v[202:203], v[80:81], v[174:175], v[152:153] op_sel_hi:[1,0,1]
	global_store_dwordx2 v[164:165], v[194:195], off offset:64
	v_pk_fma_f32 v[194:195], v[84:85], v[174:175], v[156:157] op_sel_hi:[1,0,1]
	v_pk_mul_f32 v[206:207], v[190:191], v[202:203]
	v_pk_fma_f32 v[148:149], v[72:73], v[170:171], v[148:149] op_sel_hi:[1,0,1]
	v_pk_fma_f32 v[206:207], v[166:167], v[194:195], v[206:207]
	v_pk_mul_f32 v[166:167], v[166:167], v[202:203]
	v_pk_fma_f32 v[144:145], v[76:77], v[170:171], v[144:145] op_sel_hi:[1,0,1]
	v_pk_fma_f32 v[166:167], v[190:191], v[194:195], v[166:167] neg_lo:[0,0,1] neg_hi:[0,0,1]
	v_pk_fma_f32 v[190:191], v[86:87], v[174:175], v[158:159] op_sel_hi:[1,0,1]
	v_pk_fma_f32 v[194:195], v[82:83], v[174:175], v[154:155] op_sel_hi:[1,0,1]
	v_add_u32_e32 v174, 48, v189
	v_pk_mul_f32 v[202:203], v[204:205], v[194:195]
	v_pk_mul_f32 v[194:195], v[200:201], v[194:195]
	v_cvt_f32_u32_e32 v174, v174
	v_pk_fma_f32 v[202:203], v[200:201], v[190:191], v[202:203]
	v_pk_fma_f32 v[190:191], v[204:205], v[190:191], v[194:195] neg_lo:[0,0,1] neg_hi:[0,0,1]
	v_cvt_pk_bf16_f32 v166, v166, v167
	v_cvt_pk_bf16_f32 v167, v190, v191
	global_store_dwordx2 v[164:165], v[166:167], off offset:256
	v_cvt_pk_bf16_f32 v166, v206, v207
	v_cvt_pk_bf16_f32 v167, v202, v203
	global_store_dwordx2 v[164:165], v[166:167], off offset:320
	v_mul_f32_e32 v164, v161, v174
	v_mul_f32_e32 v164, 0.15915494, v164
	v_fract_f32_e32 v165, v164
	v_sin_f32_e32 v164, v165
	v_cos_f32_e32 v166, v165
	v_mul_f32_e32 v165, v173, v174
	v_mul_f32_e32 v165, 0.15915494, v165
	v_fract_f32_e32 v165, v165
	v_cos_f32_e32 v167, v165
	v_sin_f32_e32 v165, v165
	v_pk_fma_f32 v[150:151], v[74:75], v[170:171], v[150:151] op_sel_hi:[1,0,1]
	v_pk_fma_f32 v[146:147], v[78:79], v[170:171], v[146:147] op_sel_hi:[1,0,1]
	v_pk_mul_f32 v[190:191], v[166:167], v[148:149]
	v_pk_mul_f32 v[148:149], v[164:165], v[148:149]
	v_pk_fma_f32 v[190:191], v[164:165], v[144:145], v[190:191]
	v_pk_fma_f32 v[144:145], v[166:167], v[144:145], v[148:149] neg_lo:[0,0,1] neg_hi:[0,0,1]
	v_mul_f32_e32 v148, v171, v174
	v_mul_f32_e32 v148, 0.15915494, v148
	v_fract_f32_e32 v149, v148
	v_sin_f32_e32 v148, v149
	v_cos_f32_e32 v194, v149
	v_mul_f32_e32 v149, v175, v174
	v_mul_f32_e32 v149, 0.15915494, v149
	v_fract_f32_e32 v149, v149
	v_cos_f32_e32 v195, v149
	v_sin_f32_e32 v149, v149
	v_cvt_pk_bf16_f32 v144, v144, v145
	v_pk_fma_f32 v[154:155], v[66:67], v[170:171], v[154:155] op_sel_hi:[1,0,1]
	v_pk_mul_f32 v[200:201], v[194:195], v[150:151]
	v_pk_mul_f32 v[150:151], v[148:149], v[150:151]
	v_pk_fma_f32 v[200:201], v[148:149], v[146:147], v[200:201]
	v_pk_fma_f32 v[146:147], v[194:195], v[146:147], v[150:151] neg_lo:[0,0,1] neg_hi:[0,0,1]
	v_pk_fma_f32 v[150:151], v[64:65], v[170:171], v[152:153] op_sel_hi:[1,0,1]
	v_cvt_pk_bf16_f32 v145, v146, v147
	v_lshl_add_u64 v[146:147], v[162:163], 0, s[2:3]
	v_lshl_add_u64 v[146:147], v[146:147], 0, v[198:199]
	global_store_dwordx2 v[146:147], v[144:145], off
	v_cvt_pk_bf16_f32 v144, v190, v191
	v_cvt_pk_bf16_f32 v145, v200, v201
	global_store_dwordx2 v[146:147], v[144:145], off offset:64
	v_pk_fma_f32 v[144:145], v[68:69], v[170:171], v[156:157] op_sel_hi:[1,0,1]
	v_pk_mul_f32 v[152:153], v[166:167], v[150:151]
	v_pk_mul_f32 v[150:151], v[164:165], v[150:151]
	v_pk_fma_f32 v[152:153], v[164:165], v[144:145], v[152:153]
	v_pk_fma_f32 v[144:145], v[166:167], v[144:145], v[150:151] neg_lo:[0,0,1] neg_hi:[0,0,1]
	v_pk_fma_f32 v[150:151], v[70:71], v[170:171], v[158:159] op_sel_hi:[1,0,1]
	v_pk_mul_f32 v[156:157], v[194:195], v[154:155]
	v_cvt_pk_bf16_f32 v144, v144, v145
	v_pk_fma_f32 v[156:157], v[148:149], v[150:151], v[156:157]
	v_pk_mul_f32 v[148:149], v[148:149], v[154:155]
	s_waitcnt vmcnt(15)
; DI u32x2 pack4(const float* v) { u32x2 w; w.x = pk2(v[0], v[1]); w.y = pk2(v[2], v[3]); return w; }
; DI float ex2(float x) { return __builtin_amdgcn_exp2f(x); }
; DI void sincos_rev(float ang, float& s, float& c) { float rev = ang * 0.15915494309189535f; rev = __builtin_amdgcn_fractf(rev); s = __builtin_amdgcn_sinf(rev); c = __builtin_amdgcn_cosf(rev); }
;     template <int PN> DI void body(AccRef acc, const Unit& u, int wr, int wc, int fr, int fq) const {
;     ...
;         for (int ai = 0; ai < 2; ++ai) {
;             const int rb = u.pm * 256 + ai * 128 + wr * 64 + fr;
;             int mb, pos0, kv0; row_info(rb, mb, pos0, kv0);
; #pragma unroll
;             for (int m = 0; m < 4; ++m) {
;                 const int row = rb + 16 * m, pos = pos0 + 16 * m, kvrow = kv0 + 16 * m;
;                 const float rinv = rinvh[ai][m];
;                 float v[2][8];
; #pragma unroll
;                 for (int bj = 0; bj < 2; ++bj)
; #pragma unroll
;                     for (int n = 0; n < 2; ++n)
; #pragma unroll
;                         for (int j = 0; j < 4; ++j) v[bj][4 * n + j] = acc[ai][bj][m][n][j] * rinv + cvh[ai][bj][n][j];
;     ...
;                 } else if constexpr (PN == 3 || PN == 4) {
;                     bf16_t* dst = PN == 3 ? rq : rk;
;                     const float sc = PN == 3 ? 0.125f : 1.f;
; #pragma unroll
;                     for (int bj = 0; bj < 2; ++bj) {
;                         const int head = 2 * bj + (wc >> 1), i0 = 16 * (wc & 1) + 4 * fq;
;                         float o1[4], o2[4];
; #pragma unroll
;                         for (int j = 0; j < 4; ++j) { float sn, cs; sincos_rev((float)pos * ex2(-(float)(i0 + j) * KEXP64), sn, cs);
;                             o1[j] = (v[bj][j] * cs - v[bj][4 + j] * sn) * sc; o2[j] = (v[bj][j] * sn + v[bj][4 + j] * cs) * sc; }
;                         *(u32x2*)(dst + (size_t)row * 256 + head * 64 + i0) = pack4(o1);
;                         *(u32x2*)(dst + (size_t)row * 256 + head * 64 + 32 + i0) = pack4(o2);
;                     }
	v_pk_fma_f32 v[162:163], v[58:59], v[196:197], v[138:139] op_sel_hi:[1,0,1]
	v_pk_fma_f32 v[148:149], v[194:195], v[150:151], v[148:149] neg_lo:[0,0,1] neg_hi:[0,0,1]
	v_pk_fma_f32 v[150:151], v[60:61], v[196:197], v[140:141] op_sel_hi:[1,0,1]
	v_cvt_pk_bf16_f32 v145, v148, v149
	global_store_dwordx2 v[146:147], v[144:145], off offset:256
	v_cvt_pk_bf16_f32 v144, v152, v153
	v_cvt_pk_bf16_f32 v145, v156, v157
	global_store_dwordx2 v[146:147], v[144:145], off offset:320
	v_and_b32_e32 v144, 0x7ff, v168
	v_cndmask_b32_e32 v166, v169, v144, vcc
	v_cvt_f32_u32_e32 v157, v166
	v_pk_fma_f32 v[152:153], v[56:57], v[196:197], v[136:137] op_sel_hi:[1,0,1]
	v_ashrrev_i32_e32 v169, 31, v168
	v_lshlrev_b64 v[144:145], 9, v[168:169]
	v_mul_f32_e32 v146, v161, v157
	v_mul_f32_e32 v146, 0.15915494, v146
	v_fract_f32_e32 v147, v146
	v_sin_f32_e32 v146, v147
	v_cos_f32_e32 v148, v147
	v_mul_f32_e32 v147, v173, v157
	v_mul_f32_e32 v147, 0.15915494, v147
	v_fract_f32_e32 v147, v147
	v_cos_f32_e32 v149, v147
	v_sin_f32_e32 v147, v147
	v_lshl_add_u64 v[144:145], s[14:15], 0, v[144:145]
	v_pk_fma_f32 v[158:159], v[62:63], v[196:197], v[142:143] op_sel_hi:[1,0,1]
	v_pk_mul_f32 v[154:155], v[148:149], v[152:153]
	v_pk_mul_f32 v[152:153], v[146:147], v[152:153]
	v_pk_fma_f32 v[154:155], v[146:147], v[150:151], v[154:155]
	v_pk_fma_f32 v[150:151], v[148:149], v[150:151], v[152:153] neg_lo:[0,0,1] neg_hi:[0,0,1]
	v_mul_f32_e32 v152, v171, v157
	v_mul_f32_e32 v152, 0.15915494, v152
	v_fract_f32_e32 v153, v152
	v_sin_f32_e32 v152, v153
	v_cos_f32_e32 v156, v153
	v_mul_f32_e32 v153, v175, v157
	v_mul_f32_e32 v153, 0.15915494, v153
	v_fract_f32_e32 v153, v153
	v_cos_f32_e32 v157, v153
	v_sin_f32_e32 v153, v153
	v_lshl_add_u64 v[144:145], v[144:145], 0, s[2:3]
	v_cvt_pk_bf16_f32 v150, v150, v151
	v_pk_mul_f32 v[164:165], v[156:157], v[162:163]
	v_pk_mul_f32 v[162:163], v[152:153], v[162:163]
	v_pk_fma_f32 v[164:165], v[152:153], v[158:159], v[164:165]
	v_pk_fma_f32 v[158:159], v[156:157], v[158:159], v[162:163] neg_lo:[0,0,1] neg_hi:[0,0,1]
	v_lshl_add_u64 v[144:145], v[144:145], 0, v[198:199]
	v_cvt_pk_bf16_f32 v151, v158, v159
	global_store_dwordx2 v[144:145], v[150:151], off
	v_cvt_pk_bf16_f32 v150, v154, v155
	v_cvt_pk_bf16_f32 v151, v164, v165
	v_pk_fma_f32 v[154:155], v[48:49], v[196:197], v[128:129] op_sel_hi:[1,0,1]
	global_store_dwordx2 v[144:145], v[150:151], off offset:64
	s_waitcnt vmcnt(18)
	v_pk_fma_f32 v[150:151], v[52:53], v[196:197], v[132:133] op_sel_hi:[1,0,1]
	v_pk_mul_f32 v[158:159], v[148:149], v[154:155]
	v_pk_fma_f32 v[162:163], v[42:43], v[192:193], v[138:139] op_sel_hi:[1,0,1]
	v_pk_fma_f32 v[158:159], v[146:147], v[150:151], v[158:159]
	v_pk_mul_f32 v[146:147], v[146:147], v[154:155]
	s_nop 0
	v_pk_fma_f32 v[146:147], v[148:149], v[150:151], v[146:147] neg_lo:[0,0,1] neg_hi:[0,0,1]
	v_pk_fma_f32 v[150:151], v[50:51], v[196:197], v[130:131] op_sel_hi:[1,0,1]
	v_pk_fma_f32 v[148:149], v[54:55], v[196:197], v[134:135] op_sel_hi:[1,0,1]
	v_pk_mul_f32 v[154:155], v[156:157], v[150:151]
	v_pk_mul_f32 v[150:151], v[152:153], v[150:151]
	v_pk_fma_f32 v[154:155], v[152:153], v[148:149], v[154:155]
	v_pk_fma_f32 v[148:149], v[156:157], v[148:149], v[150:151] neg_lo:[0,0,1] neg_hi:[0,0,1]
	v_cvt_pk_bf16_f32 v146, v146, v147
	v_cvt_pk_bf16_f32 v147, v148, v149
	global_store_dwordx2 v[144:145], v[146:147], off offset:256
	v_cvt_pk_bf16_f32 v146, v158, v159
	v_cvt_pk_bf16_f32 v147, v154, v155
	global_store_dwordx2 v[144:145], v[146:147], off offset:320
	v_add_u32_e32 v145, 16, v166
	v_cvt_f32_u32_e32 v157, v145
	v_pk_fma_f32 v[152:153], v[40:41], v[192:193], v[136:137] op_sel_hi:[1,0,1]
	v_pk_fma_f32 v[150:151], v[44:45], v[192:193], v[140:141] op_sel_hi:[1,0,1]
	v_add_u32_e32 v144, 0x90, v160
	v_mul_f32_e32 v146, v161, v157
	v_mul_f32_e32 v146, 0.15915494, v146
	v_fract_f32_e32 v147, v146
	v_sin_f32_e32 v146, v147
	v_cos_f32_e32 v148, v147
	v_mul_f32_e32 v147, v173, v157
	v_mul_f32_e32 v147, 0.15915494, v147
	v_fract_f32_e32 v147, v147
	v_cos_f32_e32 v149, v147
	v_sin_f32_e32 v147, v147
	v_ashrrev_i32_e32 v145, 31, v144
	v_lshlrev_b64 v[144:145], 9, v[144:145]
	v_pk_mul_f32 v[154:155], v[148:149], v[152:153]
	v_pk_mul_f32 v[152:153], v[146:147], v[152:153]
	v_pk_fma_f32 v[154:155], v[146:147], v[150:151], v[154:155]
	v_pk_fma_f32 v[150:151], v[148:149], v[150:151], v[152:153] neg_lo:[0,0,1] neg_hi:[0,0,1]
	v_mul_f32_e32 v152, v171, v157
	v_mul_f32_e32 v152, 0.15915494, v152
	v_fract_f32_e32 v153, v152
	v_sin_f32_e32 v152, v153
	v_cos_f32_e32 v156, v153
	v_mul_f32_e32 v153, v175, v157
	v_mul_f32_e32 v153, 0.15915494, v153
	v_fract_f32_e32 v153, v153
	v_cos_f32_e32 v157, v153
	v_sin_f32_e32 v153, v153
	v_lshl_add_u64 v[144:145], s[14:15], 0, v[144:145]
	v_pk_fma_f32 v[158:159], v[46:47], v[192:193], v[142:143] op_sel_hi:[1,0,1]
	v_pk_mul_f32 v[164:165], v[156:157], v[162:163]
	v_pk_mul_f32 v[162:163], v[152:153], v[162:163]
	v_pk_fma_f32 v[164:165], v[152:153], v[158:159], v[164:165]
	v_pk_fma_f32 v[158:159], v[156:157], v[158:159], v[162:163] neg_lo:[0,0,1] neg_hi:[0,0,1]
	v_lshl_add_u64 v[144:145], v[144:145], 0, s[2:3]
	v_cvt_pk_bf16_f32 v150, v150, v151
	v_cvt_pk_bf16_f32 v151, v158, v159
	v_lshl_add_u64 v[144:145], v[144:145], 0, v[198:199]
	global_store_dwordx2 v[144:145], v[150:151], off
	v_cvt_pk_bf16_f32 v150, v154, v155
	v_cvt_pk_bf16_f32 v151, v164, v165
	v_pk_fma_f32 v[154:155], v[28:29], v[192:193], v[128:129] op_sel_hi:[1,0,1]
	global_store_dwordx2 v[144:145], v[150:151], off offset:64
	v_pk_fma_f32 v[150:151], v[36:37], v[192:193], v[132:133] op_sel_hi:[1,0,1]
	v_pk_mul_f32 v[158:159], v[148:149], v[154:155]
; DI u32x2 pack4(const float* v) { u32x2 w; w.x = pk2(v[0], v[1]); w.y = pk2(v[2], v[3]); return w; }
; DI float ex2(float x) { return __builtin_amdgcn_exp2f(x); }
; DI void sincos_rev(float ang, float& s, float& c) { float rev = ang * 0.15915494309189535f; rev = __builtin_amdgcn_fractf(rev); s = __builtin_amdgcn_sinf(rev); c = __builtin_amdgcn_cosf(rev); }
;     template <int PN> DI void body(AccRef acc, const Unit& u, int wr, int wc, int fr, int fq) const {
;     ...
;         for (int ai = 0; ai < 2; ++ai) {
;             const int rb = u.pm * 256 + ai * 128 + wr * 64 + fr;
;             int mb, pos0, kv0; row_info(rb, mb, pos0, kv0);
; #pragma unroll
;             for (int m = 0; m < 4; ++m) {
;                 const int row = rb + 16 * m, pos = pos0 + 16 * m, kvrow = kv0 + 16 * m;
;                 const float rinv = rinvh[ai][m];
;                 float v[2][8];
; #pragma unroll
;                 for (int bj = 0; bj < 2; ++bj)
; #pragma unroll
;                     for (int n = 0; n < 2; ++n)
; #pragma unroll
;                         for (int j = 0; j < 4; ++j) v[bj][4 * n + j] = acc[ai][bj][m][n][j] * rinv + cvh[ai][bj][n][j];
;     ...
;                 } else if constexpr (PN == 3 || PN == 4) {
;                     bf16_t* dst = PN == 3 ? rq : rk;
;                     const float sc = PN == 3 ? 0.125f : 1.f;
; #pragma unroll
;                     for (int bj = 0; bj < 2; ++bj) {
;                         const int head = 2 * bj + (wc >> 1), i0 = 16 * (wc & 1) + 4 * fq;
;                         float o1[4], o2[4];
; #pragma unroll
;                         for (int j = 0; j < 4; ++j) { float sn, cs; sincos_rev((float)pos * ex2(-(float)(i0 + j) * KEXP64), sn, cs);
;                             o1[j] = (v[bj][j] * cs - v[bj][4 + j] * sn) * sc; o2[j] = (v[bj][j] * sn + v[bj][4 + j] * cs) * sc; }
;                         *(u32x2*)(dst + (size_t)row * 256 + head * 64 + i0) = pack4(o1);
;                         *(u32x2*)(dst + (size_t)row * 256 + head * 64 + 32 + i0) = pack4(o2);
;                     }
	v_pk_fma_f32 v[162:163], v[26:27], v[188:189], v[138:139] op_sel_hi:[1,0,1]
	v_pk_fma_f32 v[158:159], v[146:147], v[150:151], v[158:159]
	v_pk_mul_f32 v[146:147], v[146:147], v[154:155]
	v_pk_fma_f32 v[138:139], v[10:11], v[172:173], v[138:139] op_sel_hi:[1,0,1]
	v_pk_fma_f32 v[146:147], v[148:149], v[150:151], v[146:147] neg_lo:[0,0,1] neg_hi:[0,0,1]
	v_pk_fma_f32 v[150:151], v[30:31], v[192:193], v[130:131] op_sel_hi:[1,0,1]
	v_pk_fma_f32 v[148:149], v[38:39], v[192:193], v[134:135] op_sel_hi:[1,0,1]
	v_pk_mul_f32 v[154:155], v[156:157], v[150:151]
	v_pk_mul_f32 v[150:151], v[152:153], v[150:151]
	v_pk_fma_f32 v[154:155], v[152:153], v[148:149], v[154:155]
	v_pk_fma_f32 v[148:149], v[156:157], v[148:149], v[150:151] neg_lo:[0,0,1] neg_hi:[0,0,1]
	v_cvt_pk_bf16_f32 v146, v146, v147
	v_cvt_pk_bf16_f32 v147, v148, v149
	global_store_dwordx2 v[144:145], v[146:147], off offset:256
	v_cvt_pk_bf16_f32 v146, v158, v159
	v_cvt_pk_bf16_f32 v147, v154, v155
	global_store_dwordx2 v[144:145], v[146:147], off offset:320
	v_add_u32_e32 v145, 32, v166
	v_cvt_f32_u32_e32 v157, v145
	v_pk_fma_f32 v[152:153], v[24:25], v[188:189], v[136:137] op_sel_hi:[1,0,1]
	v_pk_fma_f32 v[150:151], v[32:33], v[188:189], v[140:141] op_sel_hi:[1,0,1]
	v_add_u32_e32 v144, 0xa0, v160
	v_mul_f32_e32 v146, v161, v157
	v_mul_f32_e32 v146, 0.15915494, v146
	v_fract_f32_e32 v147, v146
	v_sin_f32_e32 v146, v147
	v_cos_f32_e32 v148, v147
	v_mul_f32_e32 v147, v173, v157
	v_mul_f32_e32 v147, 0.15915494, v147
	v_fract_f32_e32 v147, v147
	v_cos_f32_e32 v149, v147
	v_sin_f32_e32 v147, v147
	v_ashrrev_i32_e32 v145, 31, v144
	v_lshlrev_b64 v[144:145], 9, v[144:145]
	v_pk_mul_f32 v[154:155], v[148:149], v[152:153]
	v_pk_mul_f32 v[152:153], v[146:147], v[152:153]
	v_pk_fma_f32 v[154:155], v[146:147], v[150:151], v[154:155]
	v_pk_fma_f32 v[150:151], v[148:149], v[150:151], v[152:153] neg_lo:[0,0,1] neg_hi:[0,0,1]
	v_mul_f32_e32 v152, v171, v157
	v_mul_f32_e32 v152, 0.15915494, v152
	v_fract_f32_e32 v153, v152
	v_sin_f32_e32 v152, v153
	v_cos_f32_e32 v156, v153
	v_mul_f32_e32 v153, v175, v157
	v_mul_f32_e32 v153, 0.15915494, v153
	v_fract_f32_e32 v153, v153
	v_cos_f32_e32 v157, v153
	v_sin_f32_e32 v153, v153
	v_lshl_add_u64 v[144:145], s[14:15], 0, v[144:145]
	v_pk_fma_f32 v[158:159], v[34:35], v[188:189], v[142:143] op_sel_hi:[1,0,1]
	v_pk_mul_f32 v[164:165], v[156:157], v[162:163]
	v_pk_mul_f32 v[162:163], v[152:153], v[162:163]
	v_pk_fma_f32 v[164:165], v[152:153], v[158:159], v[164:165]
	v_pk_fma_f32 v[158:159], v[156:157], v[158:159], v[162:163] neg_lo:[0,0,1] neg_hi:[0,0,1]
	v_lshl_add_u64 v[144:145], v[144:145], 0, s[2:3]
	v_cvt_pk_bf16_f32 v150, v150, v151
	v_cvt_pk_bf16_f32 v151, v158, v159
	v_lshl_add_u64 v[144:145], v[144:145], 0, v[198:199]
	global_store_dwordx2 v[144:145], v[150:151], off
	v_cvt_pk_bf16_f32 v150, v154, v155
	v_cvt_pk_bf16_f32 v151, v164, v165
	v_pk_fma_f32 v[154:155], v[16:17], v[188:189], v[128:129] op_sel_hi:[1,0,1]
	global_store_dwordx2 v[144:145], v[150:151], off offset:64
	v_pk_fma_f32 v[150:151], v[20:21], v[188:189], v[132:133] op_sel_hi:[1,0,1]
	v_pk_mul_f32 v[158:159], v[148:149], v[154:155]
	v_pk_fma_f32 v[136:137], v[8:9], v[172:173], v[136:137] op_sel_hi:[1,0,1]
	v_pk_fma_f32 v[158:159], v[146:147], v[150:151], v[158:159]
	v_pk_mul_f32 v[146:147], v[146:147], v[154:155]
	v_pk_fma_f32 v[140:141], v[12:13], v[172:173], v[140:141] op_sel_hi:[1,0,1]
	v_pk_fma_f32 v[146:147], v[148:149], v[150:151], v[146:147] neg_lo:[0,0,1] neg_hi:[0,0,1]
	v_pk_fma_f32 v[150:151], v[18:19], v[188:189], v[130:131] op_sel_hi:[1,0,1]
	v_pk_fma_f32 v[148:149], v[22:23], v[188:189], v[134:135] op_sel_hi:[1,0,1]
	v_pk_mul_f32 v[154:155], v[156:157], v[150:151]
	v_pk_mul_f32 v[150:151], v[152:153], v[150:151]
	v_pk_fma_f32 v[154:155], v[152:153], v[148:149], v[154:155]
	v_pk_fma_f32 v[148:149], v[156:157], v[148:149], v[150:151] neg_lo:[0,0,1] neg_hi:[0,0,1]
	v_cvt_pk_bf16_f32 v146, v146, v147
	v_cvt_pk_bf16_f32 v147, v148, v149
	global_store_dwordx2 v[144:145], v[146:147], off offset:256
	v_cvt_pk_bf16_f32 v146, v158, v159
	v_cvt_pk_bf16_f32 v147, v154, v155
	global_store_dwordx2 v[144:145], v[146:147], off offset:320
	v_add_u32_e32 v145, 48, v166
	v_cvt_f32_u32_e32 v153, v145
	v_add_u32_e32 v144, 0xb0, v160
	v_ashrrev_i32_e32 v145, 31, v144
	v_lshlrev_b64 v[144:145], 9, v[144:145]
	v_mul_f32_e32 v146, v161, v153
	v_mul_f32_e32 v146, 0.15915494, v146
	v_fract_f32_e32 v147, v146
	v_sin_f32_e32 v146, v147
	v_cos_f32_e32 v148, v147
	v_mul_f32_e32 v147, v173, v153
	v_mul_f32_e32 v147, 0.15915494, v147
	v_fract_f32_e32 v147, v147
	v_cos_f32_e32 v149, v147
	v_sin_f32_e32 v147, v147
	v_pk_fma_f32 v[142:143], v[14:15], v[172:173], v[142:143] op_sel_hi:[1,0,1]
	v_lshl_add_u64 v[144:145], s[14:15], 0, v[144:145]
	v_pk_mul_f32 v[150:151], v[148:149], v[136:137]
	v_pk_mul_f32 v[136:137], v[146:147], v[136:137]
	v_pk_fma_f32 v[150:151], v[146:147], v[140:141], v[150:151]
	v_pk_fma_f32 v[136:137], v[148:149], v[140:141], v[136:137] neg_lo:[0,0,1] neg_hi:[0,0,1]
	v_mul_f32_e32 v140, v171, v153
	v_mul_f32_e32 v140, 0.15915494, v140
	v_fract_f32_e32 v141, v140
	v_sin_f32_e32 v140, v141
	v_cos_f32_e32 v152, v141
	v_mul_f32_e32 v141, v175, v153
	v_mul_f32_e32 v141, 0.15915494, v141
	v_fract_f32_e32 v141, v141
	v_cos_f32_e32 v153, v141
	v_sin_f32_e32 v141, v141
	v_cvt_pk_bf16_f32 v136, v136, v137
	v_pk_fma_f32 v[128:129], v[0:1], v[172:173], v[128:129] op_sel_hi:[1,0,1]
	v_pk_mul_f32 v[154:155], v[152:153], v[138:139]
	v_pk_mul_f32 v[138:139], v[140:141], v[138:139]
	v_pk_fma_f32 v[154:155], v[140:141], v[142:143], v[154:155]
	v_pk_fma_f32 v[138:139], v[152:153], v[142:143], v[138:139] neg_lo:[0,0,1] neg_hi:[0,0,1]
	v_pk_fma_f32 v[132:133], v[4:5], v[172:173], v[132:133] op_sel_hi:[1,0,1]
	v_cvt_pk_bf16_f32 v137, v138, v139
	v_lshl_add_u64 v[138:139], v[144:145], 0, s[2:3]
	v_lshl_add_u64 v[138:139], v[138:139], 0, v[198:199]
	global_store_dwordx2 v[138:139], v[136:137], off
	v_cvt_pk_bf16_f32 v136, v150, v151
	v_cvt_pk_bf16_f32 v137, v154, v155
	global_store_dwordx2 v[138:139], v[136:137], off offset:64
	v_pk_mul_f32 v[136:137], v[148:149], v[128:129]
	v_pk_mul_f32 v[128:129], v[146:147], v[128:129]
	v_pk_fma_f32 v[130:131], v[2:3], v[172:173], v[130:131] op_sel_hi:[1,0,1]
	v_pk_fma_f32 v[136:137], v[146:147], v[132:133], v[136:137]
	v_pk_fma_f32 v[128:129], v[148:149], v[132:133], v[128:129] neg_lo:[0,0,1] neg_hi:[0,0,1]
	v_pk_fma_f32 v[132:133], v[6:7], v[172:173], v[134:135] op_sel_hi:[1,0,1]
	v_pk_mul_f32 v[134:135], v[152:153], v[130:131]
	v_pk_mul_f32 v[130:131], v[140:141], v[130:131]
	v_pk_fma_f32 v[134:135], v[140:141], v[132:133], v[134:135]
	v_pk_fma_f32 v[130:131], v[152:153], v[132:133], v[130:131] neg_lo:[0,0,1] neg_hi:[0,0,1]
	v_cvt_pk_bf16_f32 v128, v128, v129
	v_cvt_pk_bf16_f32 v129, v130, v131
	global_store_dwordx2 v[138:139], v[128:129], off offset:256
	v_cvt_pk_bf16_f32 v128, v136, v137
	v_cvt_pk_bf16_f32 v129, v134, v135
	global_store_dwordx2 v[138:139], v[128:129], off offset:320

; DI u32x2 pack4(const float* v) { u32x2 w; w.x = pk2(v[0], v[1]); w.y = pk2(v[2], v[3]); return w; }
; DI float ex2(float x) { return __builtin_amdgcn_exp2f(x); }
; DI void sincos_rev(float ang, float& s, float& c) { float rev = ang * 0.15915494309189535f; rev = __builtin_amdgcn_fractf(rev); s = __builtin_amdgcn_sinf(rev); c = __builtin_amdgcn_cosf(rev); }
; DI float sum16(const float* p) { const f32x4* q = (const f32x4*)p; f32x4 a = q[0], b = q[1], c = q[2], d = q[3]; f32x4 s = (a + b) + (c + d); return (s[0] + s[1]) + (s[2] + s[3]); }
;     template <int PN> DI void body(AccRef acc, const Unit& u, int wr, int wc, int fr, int fq) const {
;     ...
;         for (int ai = 0; ai < 2; ++ai) {
;             const int rb_ = u.pm * 256 + ai * 128 + wr * 64 + fr;
; #pragma unroll
;             for (int m = 0; m < 4; ++m) rinvh[ai][m] = rsqrtf(sum16(ssq + (size_t)(rb_ + 16 * m + zdep) * 16) * (1.f / 1024.f) + EPS);
;             asm volatile("v_mov_b32 %0, 0" : "=v"(zdep) : "v"(rinvh[ai][0]), "v"(rinvh[ai][1]), "v"(rinvh[ai][2]), "v"(rinvh[ai][3]));
;         }
; #pragma unroll
;         for (int ai = 0; ai < 2; ++ai) {
;             const int rb_ = u.pm * 256 + ai * 128 + wr * 64 + fr;
;             int mb_, p_, k_; row_info(rb_, mb_, p_, k_);
; #pragma unroll
;             for (int bj = 0; bj < 2; ++bj)
; #pragma unroll
;                 for (int n = 0; n < 2; ++n) cvh[ai][bj][n] = *(const f32x4*)(cv + (size_t)(mb_ + zdep) * NIN + PN * 256 + bj * 128 + cl + 4 * n);
;         }
;     ...
;                 } else if constexpr (PN == 3 || PN == 4) {
;                     bf16_t* dst = PN == 3 ? rq : rk;
;                     const float sc = PN == 3 ? 0.125f : 1.f;
; #pragma unroll
;                     for (int bj = 0; bj < 2; ++bj) {
;                         const int head = 2 * bj + (wc >> 1), i0 = 16 * (wc & 1) + 4 * fq;
;                         float o1[4], o2[4];
; #pragma unroll
;                         for (int j = 0; j < 4; ++j) { float sn, cs; sincos_rev((float)pos * ex2(-(float)(i0 + j) * KEXP64), sn, cs);
;                             o1[j] = (v[bj][j] * cs - v[bj][4 + j] * sn) * sc; o2[j] = (v[bj][j] * sn + v[bj][4 + j] * cs) * sc; }
;                         *(u32x2*)(dst + (size_t)row * 256 + head * 64 + i0) = pack4(o1);
;                         *(u32x2*)(dst + (size_t)row * 256 + head * 64 + 32 + i0) = pack4(o2);
;                     }
.LBB0_372:
	s_and_b64 vcc, exec, s[2:3]
	s_cbranch_vccz .LBB0_436
	s_cmp_gt_i32 s52, 1
	s_mov_b64 s[2:3], -1
	s_cbranch_scc0 .LBB0_415
	s_cmp_gt_i32 s52, 2
	s_cbranch_scc0 .LBB0_376
	s_lshl_b32 s2, s53, 6
	s_lshl_b32 s3, s34, 8
	s_add_i32 s2, s2, s3
	v_add_u32_e32 v160, s2, v214
	v_add_u32_e32 v164, 16, v160
	v_ashrrev_i32_e32 v161, 31, v160
	v_ashrrev_i32_e32 v165, 31, v164
	v_lshlrev_b64 v[128:129], 6, v[160:161]
	v_lshlrev_b64 v[144:145], 6, v[164:165]
	v_add_u32_e32 v166, 32, v160
	v_lshl_add_u64 v[140:141], s[56:57], 0, v[128:129]
	v_lshl_add_u64 v[144:145], s[56:57], 0, v[144:145]
	v_ashrrev_i32_e32 v167, 31, v166
	s_nop 0
	s_nop 0
	v_lshlrev_b64 v[144:145], 6, v[166:167]
	v_add_u32_e32 v162, 48, v160
	v_lshl_add_u64 v[144:145], s[56:57], 0, v[144:145]
	v_ashrrev_i32_e32 v163, 31, v162
	v_lshlrev_b64 v[144:145], 6, v[162:163]
	v_lshl_add_u64 v[144:145], s[56:57], 0, v[144:145]
	s_mov_b32 s2, 0x358637bd
	v_mov_b64_e32 v[144:145], s[2:3]
	s_mov_b32 s8, 0x3a800000
	v_lshlrev_b64 v[164:165], 9, v[164:165]
	v_lshl_add_u64 v[164:165], s[58:59], 0, v[164:165]
	v_lshlrev_b64 v[162:163], 9, v[162:163]
	v_lshl_add_u64 v[162:163], s[58:59], 0, v[162:163]
	v_mov_b32_e32 v190, v245
	v_mov_b32_e32 v174, v246
	v_add_u32_e32 v168, 0x80, v160
	v_mov_b32_e32 v194, v244
	v_mov_b32_e32 v170, v247
	v_mov_b32 v128, 0
	s_movk_i32 s7, 0x4000
	v_add_u32_e32 v158, v128, v168
	v_add_u32_e32 v146, 16, v158
	v_ashrrev_i32_e32 v159, 31, v158
	v_ashrrev_i32_e32 v147, 31, v146
	v_lshlrev_b64 v[128:129], 6, v[158:159]
	v_lshlrev_b64 v[146:147], 6, v[146:147]
	v_lshl_add_u64 v[140:141], s[56:57], 0, v[128:129]
	v_lshl_add_u64 v[172:173], s[56:57], 0, v[146:147]
	s_nop 0
	s_nop 0
	v_add_u32_e32 v172, 32, v158
	v_ashrrev_i32_e32 v173, 31, v172
	v_add_u32_e32 v158, 48, v158
	v_lshlrev_b64 v[172:173], 6, v[172:173]
	v_ashrrev_i32_e32 v159, 31, v158
	v_lshl_add_u64 v[172:173], s[56:57], 0, v[172:173]
	v_lshlrev_b64 v[158:159], 6, v[158:159]
	v_lshl_add_u64 v[158:159], s[56:57], 0, v[158:159]
	s_lshl_b32 s6, s66, 5
	v_mov_b32_e32 v196, v248
	v_mov_b32_e32 v192, v249
	v_mov_b32_e32 v188, v250
	v_mov_b32_e32 v172, v251
	v_add_u32_e32 v129, 0xffffc000, v160
	v_lshrrev_b32_e32 v129, 6, v129
	v_ashrrev_i32_e32 v128, 11, v160
	v_add_u32_e32 v129, 8, v129
	v_cmp_gt_i32_e64 s[2:3], s7, v160
	v_lshl_add_u32 v130, v213, 3, s6
	v_mov_b32 v136, 0
	v_ashrrev_i32_e32 v131, 31, v130
	v_cndmask_b32_e64 v128, v129, v128, s[2:3]
	v_add_u32_e32 v132, v136, v128
	v_mov_b64_e32 v[128:129], s[10:11]
	v_mad_i64_i32 v[132:133], s[4:5], v132, s51, v[128:129]
	v_lshlrev_b64 v[130:131], 2, v[130:131]
	v_lshl_add_u64 v[132:133], v[132:133], 0, v[130:131]
	s_mov_b64 s[8:9], 0x124c00
	v_lshl_add_u64 v[134:135], v[132:133], 0, s[8:9]
	v_add_co_u32_e32 v132, vcc, s39, v132
	s_lshl_b32 s4, s66, 4
	s_nop 0
	v_addc_co_u32_e32 v133, vcc, 0, v133, vcc
	global_load_dwordx4 v[144:147], v[132:133], off offset:3072
	global_load_dwordx4 v[148:151], v[134:135], off offset:16
	global_load_dwordx4 v[156:159], v[134:135], off offset:512
	global_load_dwordx4 v[152:155], v[134:135], off offset:528
	s_and_b32 s5, s4, 16
	v_lshl_add_u32 v198, v213, 2, s5
	v_cvt_f32_i32_e32 v138, v198
	v_or_b32_e32 v139, 1, v198
	v_mov_b32_e32 v132, 0x400
	v_cvt_f32_i32_e32 v134, v139
	v_and_or_b32 v169, v214, 63, v132
	v_add_u32_e32 v132, 0xffffc080, v160
	v_and_b32_e32 v137, 0x7ff, v160
	v_lshrrev_b32_e32 v142, 6, v132
	v_lshlrev_b64 v[132:133], 9, v[160:161]
	v_lshl_add_u64 v[200:201], s[58:59], 0, v[132:133]
	v_cndmask_b32_e64 v189, v169, v137, s[2:3]
	v_mul_f32_e32 v133, 0xbed49a78, v138
	v_cvt_f32_u32_e32 v191, v189
	v_exp_f32_e32 v171, v133
	v_mul_f32_e32 v133, 0xbed49a78, v134
	v_or_b32_e32 v140, 2, v198
	v_exp_f32_e32 v161, v133
	v_or_b32_e32 v175, 3, v198
	v_cvt_f32_i32_e32 v135, v140
	v_cvt_f32_i32_e32 v175, v175
	v_mul_f32_e32 v133, v171, v191
	v_mul_f32_e32 v133, 0.15915494, v133
	v_mul_f32_e32 v134, v161, v191
	v_mul_f32_e32 v173, 0xbed49a78, v135
	v_fract_f32_e32 v133, v133
	v_mul_f32_e32 v134, 0.15915494, v134
	v_mul_f32_e32 v175, 0xbed49a78, v175
	v_sin_f32_e32 v202, v133
	v_cos_f32_e32 v204, v133
	v_fract_f32_e32 v133, v134
	v_exp_f32_e32 v173, v173
	v_exp_f32_e32 v175, v175
	v_cos_f32_e32 v205, v133
	v_sin_f32_e32 v203, v133
	v_mul_f32_e32 v193, v173, v191
	v_mul_f32_e32 v191, v175, v191
	v_ashrrev_i32_e32 v141, 11, v168
	v_add_u32_e32 v139, 8, v142
	v_cmp_gt_i32_e32 vcc, s7, v168
	v_mul_f32_e32 v193, 0.15915494, v193
	v_mul_f32_e32 v191, 0.15915494, v191
	s_and_b32 s4, s6, 0xffffffc0
	v_cndmask_b32_e32 v132, v139, v141, vcc
	s_mov_b32 s6, 0x3e000000
	v_fract_f32_e32 v193, v193
	v_fract_f32_e32 v191, v191
	v_add_u32_e32 v132, v136, v132
	v_cos_f32_e32 v220, v193
	v_cos_f32_e32 v221, v191
	v_mad_i64_i32 v[128:129], s[2:3], v132, s51, v[128:129]
	v_lshl_add_u64 v[128:129], v[128:129], 0, v[130:131]
	v_lshl_add_u64 v[132:133], v[128:129], 0, s[8:9]
	v_add_co_u32_e64 v128, s[2:3], s39, v128
	s_ashr_i32 s5, s4, 31
	s_nop 0
	v_addc_co_u32_e64 v129, s[2:3], 0, v129, s[2:3]
	v_ashrrev_i32_e32 v199, 31, v198
	s_lshl_b64 s[2:3], s[4:5], 1
	v_lshl_add_u64 v[200:201], v[200:201], 0, s[2:3]
	v_lshlrev_b64 v[198:199], 1, v[198:199]
	v_lshl_add_u64 v[200:201], v[200:201], 0, v[198:199]
	global_load_dwordx4 v[140:143], v[128:129], off offset:3072
	s_nop 0
	global_load_dwordx4 v[128:131], v[132:133], off offset:528
	global_load_dwordx4 v[136:139], v[132:133], off offset:16
	s_nop 0
	global_load_dwordx4 v[132:135], v[132:133], off offset:512
	v_lshl_add_u64 v[164:165], v[164:165], 0, s[2:3]
	v_lshl_add_u64 v[164:165], v[164:165], 0, v[198:199]
	s_waitcnt vmcnt(7)
	v_pk_fma_f32 v[206:207], v[124:125], v[194:195], v[144:145] op_sel_hi:[1,0,1]
	s_waitcnt vmcnt(6)
; DI u32x2 pack4(const float* v) { u32x2 w; w.x = pk2(v[0], v[1]); w.y = pk2(v[2], v[3]); return w; }
; DI float ex2(float x) { return __builtin_amdgcn_exp2f(x); }
; DI void sincos_rev(float ang, float& s, float& c) { float rev = ang * 0.15915494309189535f; rev = __builtin_amdgcn_fractf(rev); s = __builtin_amdgcn_sinf(rev); c = __builtin_amdgcn_cosf(rev); }
;     template <int PN> DI void body(AccRef acc, const Unit& u, int wr, int wc, int fr, int fq) const {
;     ...
;         for (int ai = 0; ai < 2; ++ai) {
;             const int rb = u.pm * 256 + ai * 128 + wr * 64 + fr;
;             int mb, pos0, kv0; row_info(rb, mb, pos0, kv0);
; #pragma unroll
;             for (int m = 0; m < 4; ++m) {
;                 const int row = rb + 16 * m, pos = pos0 + 16 * m, kvrow = kv0 + 16 * m;
;                 const float rinv = rinvh[ai][m];
;                 float v[2][8];
; #pragma unroll
;                 for (int bj = 0; bj < 2; ++bj)
; #pragma unroll
;                     for (int n = 0; n < 2; ++n)
; #pragma unroll
;                         for (int j = 0; j < 4; ++j) v[bj][4 * n + j] = acc[ai][bj][m][n][j] * rinv + cvh[ai][bj][n][j];
;     ...
;                 } else if constexpr (PN == 3 || PN == 4) {
;                     bf16_t* dst = PN == 3 ? rq : rk;
;                     const float sc = PN == 3 ? 0.125f : 1.f;
; #pragma unroll
;                     for (int bj = 0; bj < 2; ++bj) {
;                         const int head = 2 * bj + (wc >> 1), i0 = 16 * (wc & 1) + 4 * fq;
;                         float o1[4], o2[4];
; #pragma unroll
;                         for (int j = 0; j < 4; ++j) { float sn, cs; sincos_rev((float)pos * ex2(-(float)(i0 + j) * KEXP64), sn, cs);
;                             o1[j] = (v[bj][j] * cs - v[bj][4 + j] * sn) * sc; o2[j] = (v[bj][j] * sn + v[bj][4 + j] * cs) * sc; }
;                         *(u32x2*)(dst + (size_t)row * 256 + head * 64 + i0) = pack4(o1);
;                         *(u32x2*)(dst + (size_t)row * 256 + head * 64 + 32 + i0) = pack4(o2);
;                     }
	v_pk_fma_f32 v[216:217], v[120:121], v[194:195], v[148:149] op_sel_hi:[1,0,1]
	v_pk_fma_f32 v[228:229], v[122:123], v[194:195], v[150:151] op_sel_hi:[1,0,1]
	v_pk_mul_f32 v[218:219], v[204:205], v[216:217]
	v_pk_mul_f32 v[216:217], v[202:203], v[216:217]
	v_pk_fma_f32 v[218:219], v[202:203], v[206:207], v[218:219]
	v_pk_fma_f32 v[206:207], v[204:205], v[206:207], v[216:217] neg_lo:[0,0,1] neg_hi:[0,0,1]
	v_pk_mul_f32 v[216:217], v[218:219], s[6:7] op_sel_hi:[1,0]
	v_sin_f32_e32 v218, v193
	v_sin_f32_e32 v219, v191
	v_pk_fma_f32 v[222:223], v[126:127], v[194:195], v[146:147] op_sel_hi:[1,0,1]
	v_pk_mul_f32 v[230:231], v[220:221], v[228:229]
	v_pk_mul_f32 v[206:207], v[206:207], s[6:7] op_sel_hi:[1,0]
	v_pk_mul_f32 v[228:229], v[218:219], v[228:229]
	v_pk_fma_f32 v[230:231], v[218:219], v[222:223], v[230:231]
	v_pk_fma_f32 v[222:223], v[220:221], v[222:223], v[228:229] neg_lo:[0,0,1] neg_hi:[0,0,1]
	v_pk_mul_f32 v[230:231], v[230:231], s[6:7] op_sel_hi:[1,0]
	v_pk_mul_f32 v[222:223], v[222:223], s[6:7] op_sel_hi:[1,0]
	v_cvt_pk_bf16_f32 v206, v206, v207
	v_cvt_pk_bf16_f32 v207, v222, v223
	global_store_dwordx2 v[200:201], v[206:207], off
	v_cvt_pk_bf16_f32 v206, v216, v217
	v_cvt_pk_bf16_f32 v207, v230, v231
	s_waitcnt vmcnt(5)
	v_pk_fma_f32 v[216:217], v[112:113], v[194:195], v[152:153] op_sel_hi:[1,0,1]
	v_add_u32_e32 v191, 16, v189
	global_store_dwordx2 v[200:201], v[206:207], off offset:64
	v_pk_fma_f32 v[206:207], v[116:117], v[194:195], v[156:157] op_sel_hi:[1,0,1]
	v_pk_mul_f32 v[222:223], v[204:205], v[216:217]
	v_cvt_f32_u32_e32 v191, v191
	v_pk_fma_f32 v[222:223], v[202:203], v[206:207], v[222:223]
	v_pk_mul_f32 v[202:203], v[202:203], v[216:217]
	v_pk_mul_f32 v[222:223], v[222:223], s[6:7] op_sel_hi:[1,0]
	v_pk_fma_f32 v[202:203], v[204:205], v[206:207], v[202:203] neg_lo:[0,0,1] neg_hi:[0,0,1]
	v_pk_fma_f32 v[204:205], v[118:119], v[194:195], v[158:159] op_sel_hi:[1,0,1]
	v_pk_fma_f32 v[194:195], v[114:115], v[194:195], v[154:155] op_sel_hi:[1,0,1]
	v_mul_f32_e32 v193, v171, v191
	v_pk_mul_f32 v[206:207], v[220:221], v[194:195]
	v_pk_mul_f32 v[194:195], v[218:219], v[194:195]
	v_pk_fma_f32 v[206:207], v[218:219], v[204:205], v[206:207]
	v_pk_fma_f32 v[194:195], v[220:221], v[204:205], v[194:195] neg_lo:[0,0,1] neg_hi:[0,0,1]
	v_pk_mul_f32 v[202:203], v[202:203], s[6:7] op_sel_hi:[1,0]
	v_pk_mul_f32 v[206:207], v[206:207], s[6:7] op_sel_hi:[1,0]
	v_pk_mul_f32 v[194:195], v[194:195], s[6:7] op_sel_hi:[1,0]
	v_mul_f32_e32 v193, 0.15915494, v193
	v_cvt_pk_bf16_f32 v202, v202, v203
	v_cvt_pk_bf16_f32 v203, v194, v195
	v_cvt_pk_bf16_f32 v194, v222, v223
	v_cvt_pk_bf16_f32 v195, v206, v207
	v_fract_f32_e32 v193, v193
	global_store_dwordx2 v[200:201], v[202:203], off offset:256
	global_store_dwordx2 v[200:201], v[194:195], off offset:320
	v_sin_f32_e32 v194, v193
	v_cos_f32_e32 v200, v193
	v_mul_f32_e32 v193, v161, v191
	v_mul_f32_e32 v193, 0.15915494, v193
	v_fract_f32_e32 v193, v193
	v_cos_f32_e32 v201, v193
	v_sin_f32_e32 v195, v193
	v_pk_fma_f32 v[202:203], v[108:109], v[190:191], v[144:145] op_sel_hi:[1,0,1]
	v_pk_fma_f32 v[204:205], v[104:105], v[190:191], v[148:149] op_sel_hi:[1,0,1]
	v_mul_f32_e32 v193, v173, v191
	v_mul_f32_e32 v191, v175, v191
	v_mul_f32_e32 v193, 0.15915494, v193
	v_mul_f32_e32 v191, 0.15915494, v191
	v_pk_mul_f32 v[206:207], v[200:201], v[204:205]
	v_pk_mul_f32 v[204:205], v[194:195], v[204:205]
	v_fract_f32_e32 v193, v193
	v_fract_f32_e32 v191, v191
	v_pk_fma_f32 v[206:207], v[194:195], v[202:203], v[206:207]
	v_pk_fma_f32 v[202:203], v[200:201], v[202:203], v[204:205] neg_lo:[0,0,1] neg_hi:[0,0,1]
	v_sin_f32_e32 v204, v193
	v_cos_f32_e32 v216, v193
	v_cos_f32_e32 v217, v191
	v_sin_f32_e32 v205, v191
	v_pk_fma_f32 v[220:221], v[106:107], v[190:191], v[150:151] op_sel_hi:[1,0,1]
	v_pk_fma_f32 v[218:219], v[110:111], v[190:191], v[146:147] op_sel_hi:[1,0,1]
	v_pk_mul_f32 v[222:223], v[216:217], v[220:221]
	v_pk_mul_f32 v[220:221], v[204:205], v[220:221]
	v_pk_fma_f32 v[222:223], v[204:205], v[218:219], v[222:223]
	v_pk_fma_f32 v[218:219], v[216:217], v[218:219], v[220:221] neg_lo:[0,0,1] neg_hi:[0,0,1]
	v_pk_mul_f32 v[202:203], v[202:203], s[6:7] op_sel_hi:[1,0]
	v_pk_mul_f32 v[218:219], v[218:219], s[6:7] op_sel_hi:[1,0]
	v_pk_mul_f32 v[206:207], v[206:207], s[6:7] op_sel_hi:[1,0]
	v_pk_mul_f32 v[222:223], v[222:223], s[6:7] op_sel_hi:[1,0]
	v_cvt_pk_bf16_f32 v202, v202, v203
	v_cvt_pk_bf16_f32 v203, v218, v219
	global_store_dwordx2 v[164:165], v[202:203], off
	v_cvt_pk_bf16_f32 v202, v206, v207
	v_cvt_pk_bf16_f32 v203, v222, v223
	v_pk_fma_f32 v[206:207], v[96:97], v[190:191], v[152:153] op_sel_hi:[1,0,1]
	global_store_dwordx2 v[164:165], v[202:203], off offset:64
	v_pk_fma_f32 v[202:203], v[100:101], v[190:191], v[156:157] op_sel_hi:[1,0,1]
	v_pk_mul_f32 v[218:219], v[200:201], v[206:207]
	v_add_u32_e32 v193, 32, v189
	v_pk_fma_f32 v[218:219], v[194:195], v[202:203], v[218:219]
	v_pk_mul_f32 v[194:195], v[194:195], v[206:207]
	v_cvt_f32_u32_e32 v193, v193
	v_pk_fma_f32 v[194:195], v[200:201], v[202:203], v[194:195] neg_lo:[0,0,1] neg_hi:[0,0,1]
	v_pk_fma_f32 v[200:201], v[102:103], v[190:191], v[158:159] op_sel_hi:[1,0,1]
	v_pk_fma_f32 v[190:191], v[98:99], v[190:191], v[154:155] op_sel_hi:[1,0,1]
	v_pk_mul_f32 v[218:219], v[218:219], s[6:7] op_sel_hi:[1,0]
	v_pk_mul_f32 v[202:203], v[216:217], v[190:191]
	v_pk_mul_f32 v[190:191], v[204:205], v[190:191]
	v_pk_fma_f32 v[202:203], v[204:205], v[200:201], v[202:203]
	v_pk_fma_f32 v[190:191], v[216:217], v[200:201], v[190:191] neg_lo:[0,0,1] neg_hi:[0,0,1]
	v_pk_mul_f32 v[194:195], v[194:195], s[6:7] op_sel_hi:[1,0]
	v_pk_mul_f32 v[202:203], v[202:203], s[6:7] op_sel_hi:[1,0]
; DI u32x2 pack4(const float* v) { u32x2 w; w.x = pk2(v[0], v[1]); w.y = pk2(v[2], v[3]); return w; }
; DI float ex2(float x) { return __builtin_amdgcn_exp2f(x); }
; DI void sincos_rev(float ang, float& s, float& c) { float rev = ang * 0.15915494309189535f; rev = __builtin_amdgcn_fractf(rev); s = __builtin_amdgcn_sinf(rev); c = __builtin_amdgcn_cosf(rev); }
;     template <int PN> DI void body(AccRef acc, const Unit& u, int wr, int wc, int fr, int fq) const {
;     ...
;         for (int ai = 0; ai < 2; ++ai) {
;             const int rb = u.pm * 256 + ai * 128 + wr * 64 + fr;
;             int mb, pos0, kv0; row_info(rb, mb, pos0, kv0);
; #pragma unroll
;             for (int m = 0; m < 4; ++m) {
;                 const int row = rb + 16 * m, pos = pos0 + 16 * m, kvrow = kv0 + 16 * m;
;                 const float rinv = rinvh[ai][m];
;                 float v[2][8];
; #pragma unroll
;                 for (int bj = 0; bj < 2; ++bj)
; #pragma unroll
;                     for (int n = 0; n < 2; ++n)
; #pragma unroll
;                         for (int j = 0; j < 4; ++j) v[bj][4 * n + j] = acc[ai][bj][m][n][j] * rinv + cvh[ai][bj][n][j];
;     ...
;                 } else if constexpr (PN == 3 || PN == 4) {
;                     bf16_t* dst = PN == 3 ? rq : rk;
;                     const float sc = PN == 3 ? 0.125f : 1.f;
; #pragma unroll
;                     for (int bj = 0; bj < 2; ++bj) {
;                         const int head = 2 * bj + (wc >> 1), i0 = 16 * (wc & 1) + 4 * fq;
;                         float o1[4], o2[4];
; #pragma unroll
;                         for (int j = 0; j < 4; ++j) { float sn, cs; sincos_rev((float)pos * ex2(-(float)(i0 + j) * KEXP64), sn, cs);
;                             o1[j] = (v[bj][j] * cs - v[bj][4 + j] * sn) * sc; o2[j] = (v[bj][j] * sn + v[bj][4 + j] * cs) * sc; }
;                         *(u32x2*)(dst + (size_t)row * 256 + head * 64 + i0) = pack4(o1);
;                         *(u32x2*)(dst + (size_t)row * 256 + head * 64 + 32 + i0) = pack4(o2);
;                     }
	v_pk_mul_f32 v[190:191], v[190:191], s[6:7] op_sel_hi:[1,0]
	v_cvt_pk_bf16_f32 v194, v194, v195
	v_cvt_pk_bf16_f32 v195, v190, v191
	v_cvt_pk_bf16_f32 v190, v218, v219
	v_cvt_pk_bf16_f32 v191, v202, v203
	global_store_dwordx2 v[164:165], v[194:195], off offset:256
	global_store_dwordx2 v[164:165], v[190:191], off offset:320
	v_lshlrev_b64 v[164:165], 9, v[166:167]
	v_mul_f32_e32 v166, v171, v193
	v_mul_f32_e32 v166, 0.15915494, v166
	v_fract_f32_e32 v167, v166
	v_sin_f32_e32 v166, v167
	v_cos_f32_e32 v190, v167
	v_mul_f32_e32 v167, v161, v193
	v_mul_f32_e32 v167, 0.15915494, v167
	v_fract_f32_e32 v167, v167
	v_cos_f32_e32 v191, v167
	v_sin_f32_e32 v167, v167
	v_mul_f32_e32 v197, v173, v193
	v_mul_f32_e32 v193, v175, v193
	v_pk_fma_f32 v[200:201], v[88:89], v[174:175], v[148:149] op_sel_hi:[1,0,1]
	v_mul_f32_e32 v197, 0.15915494, v197
	v_mul_f32_e32 v193, 0.15915494, v193
	v_pk_fma_f32 v[194:195], v[92:93], v[174:175], v[144:145] op_sel_hi:[1,0,1]
	v_pk_mul_f32 v[202:203], v[190:191], v[200:201]
	v_pk_mul_f32 v[200:201], v[166:167], v[200:201]
	v_fract_f32_e32 v197, v197
	v_fract_f32_e32 v193, v193
	v_pk_fma_f32 v[202:203], v[166:167], v[194:195], v[202:203]
	v_pk_fma_f32 v[194:195], v[190:191], v[194:195], v[200:201] neg_lo:[0,0,1] neg_hi:[0,0,1]
	v_sin_f32_e32 v200, v197
	v_cos_f32_e32 v204, v197
	v_cos_f32_e32 v205, v193
	v_sin_f32_e32 v201, v193
	v_pk_fma_f32 v[216:217], v[90:91], v[174:175], v[150:151] op_sel_hi:[1,0,1]
	v_pk_fma_f32 v[206:207], v[94:95], v[174:175], v[146:147] op_sel_hi:[1,0,1]
	v_pk_mul_f32 v[218:219], v[204:205], v[216:217]
	v_pk_mul_f32 v[216:217], v[200:201], v[216:217]
	v_lshl_add_u64 v[164:165], s[58:59], 0, v[164:165]
	v_pk_fma_f32 v[218:219], v[200:201], v[206:207], v[218:219]
	v_pk_fma_f32 v[206:207], v[204:205], v[206:207], v[216:217] neg_lo:[0,0,1] neg_hi:[0,0,1]
	v_pk_mul_f32 v[194:195], v[194:195], s[6:7] op_sel_hi:[1,0]
	v_pk_mul_f32 v[206:207], v[206:207], s[6:7] op_sel_hi:[1,0]
	v_lshl_add_u64 v[164:165], v[164:165], 0, s[2:3]
	v_pk_mul_f32 v[202:203], v[202:203], s[6:7] op_sel_hi:[1,0]
	v_pk_mul_f32 v[218:219], v[218:219], s[6:7] op_sel_hi:[1,0]
	v_cvt_pk_bf16_f32 v194, v194, v195
	v_cvt_pk_bf16_f32 v195, v206, v207
	v_lshl_add_u64 v[164:165], v[164:165], 0, v[198:199]
	global_store_dwordx2 v[164:165], v[194:195], off
	v_cvt_pk_bf16_f32 v194, v202, v203
	v_cvt_pk_bf16_f32 v195, v218, v219
	v_pk_fma_f32 v[202:203], v[80:81], v[174:175], v[152:153] op_sel_hi:[1,0,1]
	global_store_dwordx2 v[164:165], v[194:195], off offset:64
	v_pk_fma_f32 v[194:195], v[84:85], v[174:175], v[156:157] op_sel_hi:[1,0,1]
	v_pk_mul_f32 v[206:207], v[190:191], v[202:203]
	v_pk_fma_f32 v[148:149], v[72:73], v[170:171], v[148:149] op_sel_hi:[1,0,1]
	v_pk_fma_f32 v[206:207], v[166:167], v[194:195], v[206:207]
	v_pk_mul_f32 v[166:167], v[166:167], v[202:203]
	v_pk_mul_f32 v[206:207], v[206:207], s[6:7] op_sel_hi:[1,0]
	v_pk_fma_f32 v[166:167], v[190:191], v[194:195], v[166:167] neg_lo:[0,0,1] neg_hi:[0,0,1]
	v_pk_fma_f32 v[194:195], v[82:83], v[174:175], v[154:155] op_sel_hi:[1,0,1]
	v_pk_fma_f32 v[190:191], v[86:87], v[174:175], v[158:159] op_sel_hi:[1,0,1]
	v_pk_mul_f32 v[202:203], v[204:205], v[194:195]
	v_pk_mul_f32 v[194:195], v[200:201], v[194:195]
	v_add_u32_e32 v174, 48, v189
	v_pk_fma_f32 v[202:203], v[200:201], v[190:191], v[202:203]
	v_pk_fma_f32 v[190:191], v[204:205], v[190:191], v[194:195] neg_lo:[0,0,1] neg_hi:[0,0,1]
	v_cvt_f32_u32_e32 v174, v174
	v_pk_mul_f32 v[166:167], v[166:167], s[6:7] op_sel_hi:[1,0]
	v_pk_mul_f32 v[190:191], v[190:191], s[6:7] op_sel_hi:[1,0]
	v_pk_mul_f32 v[202:203], v[202:203], s[6:7] op_sel_hi:[1,0]
	v_cvt_pk_bf16_f32 v166, v166, v167
	v_cvt_pk_bf16_f32 v167, v190, v191
	global_store_dwordx2 v[164:165], v[166:167], off offset:256
	v_cvt_pk_bf16_f32 v166, v206, v207
	v_cvt_pk_bf16_f32 v167, v202, v203
	global_store_dwordx2 v[164:165], v[166:167], off offset:320
	v_mul_f32_e32 v164, v171, v174
	v_mul_f32_e32 v164, 0.15915494, v164
	v_fract_f32_e32 v165, v164
	v_sin_f32_e32 v164, v165
	v_cos_f32_e32 v166, v165
	v_mul_f32_e32 v165, v161, v174
	v_mul_f32_e32 v165, 0.15915494, v165
	v_fract_f32_e32 v165, v165
	v_cos_f32_e32 v167, v165
	v_sin_f32_e32 v165, v165
	v_pk_fma_f32 v[144:145], v[76:77], v[170:171], v[144:145] op_sel_hi:[1,0,1]
	v_pk_fma_f32 v[150:151], v[74:75], v[170:171], v[150:151] op_sel_hi:[1,0,1]
	v_pk_mul_f32 v[190:191], v[166:167], v[148:149]
	v_pk_mul_f32 v[148:149], v[164:165], v[148:149]
	v_pk_fma_f32 v[190:191], v[164:165], v[144:145], v[190:191]
	v_pk_fma_f32 v[144:145], v[166:167], v[144:145], v[148:149] neg_lo:[0,0,1] neg_hi:[0,0,1]
	v_mul_f32_e32 v148, v173, v174
	v_mul_f32_e32 v148, 0.15915494, v148
	v_fract_f32_e32 v149, v148
	v_sin_f32_e32 v148, v149
	v_cos_f32_e32 v194, v149
	v_mul_f32_e32 v149, v175, v174
	v_mul_f32_e32 v149, 0.15915494, v149
	v_fract_f32_e32 v149, v149
	v_cos_f32_e32 v195, v149
	v_sin_f32_e32 v149, v149
	v_pk_fma_f32 v[146:147], v[78:79], v[170:171], v[146:147] op_sel_hi:[1,0,1]
	v_pk_mul_f32 v[144:145], v[144:145], s[6:7] op_sel_hi:[1,0]
	v_pk_mul_f32 v[200:201], v[194:195], v[150:151]
	v_pk_mul_f32 v[150:151], v[148:149], v[150:151]
	v_pk_fma_f32 v[200:201], v[148:149], v[146:147], v[200:201]
	v_pk_fma_f32 v[146:147], v[194:195], v[146:147], v[150:151] neg_lo:[0,0,1] neg_hi:[0,0,1]
	v_cvt_pk_bf16_f32 v144, v144, v145
	v_pk_mul_f32 v[146:147], v[146:147], s[6:7] op_sel_hi:[1,0]
	v_pk_mul_f32 v[190:191], v[190:191], s[6:7] op_sel_hi:[1,0]
	v_cvt_pk_bf16_f32 v145, v146, v147
	v_lshl_add_u64 v[146:147], v[162:163], 0, s[2:3]
	v_pk_mul_f32 v[200:201], v[200:201], s[6:7] op_sel_hi:[1,0]
	v_lshl_add_u64 v[146:147], v[146:147], 0, v[198:199]
; DI u32x2 pack4(const float* v) { u32x2 w; w.x = pk2(v[0], v[1]); w.y = pk2(v[2], v[3]); return w; }
; DI float ex2(float x) { return __builtin_amdgcn_exp2f(x); }
; DI void sincos_rev(float ang, float& s, float& c) { float rev = ang * 0.15915494309189535f; rev = __builtin_amdgcn_fractf(rev); s = __builtin_amdgcn_sinf(rev); c = __builtin_amdgcn_cosf(rev); }
;     template <int PN> DI void body(AccRef acc, const Unit& u, int wr, int wc, int fr, int fq) const {
;     ...
;         for (int ai = 0; ai < 2; ++ai) {
;             const int rb = u.pm * 256 + ai * 128 + wr * 64 + fr;
;             int mb, pos0, kv0; row_info(rb, mb, pos0, kv0);
; #pragma unroll
;             for (int m = 0; m < 4; ++m) {
;                 const int row = rb + 16 * m, pos = pos0 + 16 * m, kvrow = kv0 + 16 * m;
;                 const float rinv = rinvh[ai][m];
;                 float v[2][8];
; #pragma unroll
;                 for (int bj = 0; bj < 2; ++bj)
; #pragma unroll
;                     for (int n = 0; n < 2; ++n)
; #pragma unroll
;                         for (int j = 0; j < 4; ++j) v[bj][4 * n + j] = acc[ai][bj][m][n][j] * rinv + cvh[ai][bj][n][j];
;     ...
;                 } else if constexpr (PN == 3 || PN == 4) {
;                     bf16_t* dst = PN == 3 ? rq : rk;
;                     const float sc = PN == 3 ? 0.125f : 1.f;
; #pragma unroll
;                     for (int bj = 0; bj < 2; ++bj) {
;                         const int head = 2 * bj + (wc >> 1), i0 = 16 * (wc & 1) + 4 * fq;
;                         float o1[4], o2[4];
; #pragma unroll
;                         for (int j = 0; j < 4; ++j) { float sn, cs; sincos_rev((float)pos * ex2(-(float)(i0 + j) * KEXP64), sn, cs);
;                             o1[j] = (v[bj][j] * cs - v[bj][4 + j] * sn) * sc; o2[j] = (v[bj][j] * sn + v[bj][4 + j] * cs) * sc; }
;                         *(u32x2*)(dst + (size_t)row * 256 + head * 64 + i0) = pack4(o1);
;                         *(u32x2*)(dst + (size_t)row * 256 + head * 64 + 32 + i0) = pack4(o2);
;                     }
	global_store_dwordx2 v[146:147], v[144:145], off
	v_cvt_pk_bf16_f32 v144, v190, v191
	v_cvt_pk_bf16_f32 v145, v200, v201
	v_pk_fma_f32 v[150:151], v[64:65], v[170:171], v[152:153] op_sel_hi:[1,0,1]
	global_store_dwordx2 v[146:147], v[144:145], off offset:64
	v_pk_fma_f32 v[144:145], v[68:69], v[170:171], v[156:157] op_sel_hi:[1,0,1]
	v_pk_mul_f32 v[152:153], v[166:167], v[150:151]
	v_pk_mul_f32 v[150:151], v[164:165], v[150:151]
	v_pk_fma_f32 v[154:155], v[66:67], v[170:171], v[154:155] op_sel_hi:[1,0,1]
	v_pk_fma_f32 v[152:153], v[164:165], v[144:145], v[152:153]
	v_pk_fma_f32 v[144:145], v[166:167], v[144:145], v[150:151] neg_lo:[0,0,1] neg_hi:[0,0,1]
	v_pk_fma_f32 v[150:151], v[70:71], v[170:171], v[158:159] op_sel_hi:[1,0,1]
	v_pk_mul_f32 v[156:157], v[194:195], v[154:155]
	v_pk_mul_f32 v[144:145], v[144:145], s[6:7] op_sel_hi:[1,0]
	v_pk_fma_f32 v[156:157], v[148:149], v[150:151], v[156:157]
	v_pk_mul_f32 v[148:149], v[148:149], v[154:155]
	v_pk_mul_f32 v[152:153], v[152:153], s[6:7] op_sel_hi:[1,0]
	v_pk_fma_f32 v[148:149], v[194:195], v[150:151], v[148:149] neg_lo:[0,0,1] neg_hi:[0,0,1]
	v_pk_mul_f32 v[156:157], v[156:157], s[6:7] op_sel_hi:[1,0]
	v_pk_mul_f32 v[148:149], v[148:149], s[6:7] op_sel_hi:[1,0]
	v_cvt_pk_bf16_f32 v144, v144, v145
	v_cvt_pk_bf16_f32 v145, v148, v149
	global_store_dwordx2 v[146:147], v[144:145], off offset:256
	v_cvt_pk_bf16_f32 v144, v152, v153
	v_cvt_pk_bf16_f32 v145, v156, v157
	global_store_dwordx2 v[146:147], v[144:145], off offset:320
	v_and_b32_e32 v144, 0x7ff, v168
	v_cndmask_b32_e32 v166, v169, v144, vcc
	v_cvt_f32_u32_e32 v157, v166
	s_waitcnt vmcnt(17)
	v_pk_fma_f32 v[152:153], v[56:57], v[196:197], v[136:137] op_sel_hi:[1,0,1]
	v_pk_fma_f32 v[150:151], v[60:61], v[196:197], v[140:141] op_sel_hi:[1,0,1]
	v_ashrrev_i32_e32 v169, 31, v168
	v_mul_f32_e32 v146, v171, v157
	v_mul_f32_e32 v146, 0.15915494, v146
	v_fract_f32_e32 v147, v146
	v_sin_f32_e32 v146, v147
	v_cos_f32_e32 v148, v147
	v_mul_f32_e32 v147, v161, v157
	v_mul_f32_e32 v147, 0.15915494, v147
	v_fract_f32_e32 v147, v147
	v_cos_f32_e32 v149, v147
	v_sin_f32_e32 v147, v147
	v_pk_fma_f32 v[162:163], v[58:59], v[196:197], v[138:139] op_sel_hi:[1,0,1]
	v_lshlrev_b64 v[144:145], 9, v[168:169]
	v_pk_mul_f32 v[154:155], v[148:149], v[152:153]
	v_pk_mul_f32 v[152:153], v[146:147], v[152:153]
	v_pk_fma_f32 v[154:155], v[146:147], v[150:151], v[154:155]
	v_pk_fma_f32 v[150:151], v[148:149], v[150:151], v[152:153] neg_lo:[0,0,1] neg_hi:[0,0,1]
	v_mul_f32_e32 v152, v173, v157
	v_mul_f32_e32 v152, 0.15915494, v152
	v_fract_f32_e32 v153, v152
	v_sin_f32_e32 v152, v153
	v_cos_f32_e32 v156, v153
	v_mul_f32_e32 v153, v175, v157
	v_mul_f32_e32 v153, 0.15915494, v153
	v_fract_f32_e32 v153, v153
	v_cos_f32_e32 v157, v153
	v_sin_f32_e32 v153, v153
	v_pk_fma_f32 v[158:159], v[62:63], v[196:197], v[142:143] op_sel_hi:[1,0,1]
	v_lshl_add_u64 v[144:145], s[58:59], 0, v[144:145]
	v_pk_mul_f32 v[164:165], v[156:157], v[162:163]
	v_pk_mul_f32 v[162:163], v[152:153], v[162:163]
	v_pk_fma_f32 v[164:165], v[152:153], v[158:159], v[164:165]
	v_pk_fma_f32 v[158:159], v[156:157], v[158:159], v[162:163] neg_lo:[0,0,1] neg_hi:[0,0,1]
	v_pk_mul_f32 v[150:151], v[150:151], s[6:7] op_sel_hi:[1,0]
	v_pk_mul_f32 v[158:159], v[158:159], s[6:7] op_sel_hi:[1,0]
	v_lshl_add_u64 v[144:145], v[144:145], 0, s[2:3]
	v_pk_mul_f32 v[154:155], v[154:155], s[6:7] op_sel_hi:[1,0]
	v_pk_mul_f32 v[164:165], v[164:165], s[6:7] op_sel_hi:[1,0]
	v_cvt_pk_bf16_f32 v150, v150, v151
	v_cvt_pk_bf16_f32 v151, v158, v159
	v_lshl_add_u64 v[144:145], v[144:145], 0, v[198:199]
	global_store_dwordx2 v[144:145], v[150:151], off
	v_cvt_pk_bf16_f32 v150, v154, v155
	v_cvt_pk_bf16_f32 v151, v164, v165
	v_pk_fma_f32 v[154:155], v[48:49], v[196:197], v[128:129] op_sel_hi:[1,0,1]
	global_store_dwordx2 v[144:145], v[150:151], off offset:64
	s_waitcnt vmcnt(18)
	v_pk_fma_f32 v[150:151], v[52:53], v[196:197], v[132:133] op_sel_hi:[1,0,1]
	v_pk_mul_f32 v[158:159], v[148:149], v[154:155]
	v_pk_fma_f32 v[162:163], v[42:43], v[192:193], v[138:139] op_sel_hi:[1,0,1]
	v_pk_fma_f32 v[158:159], v[146:147], v[150:151], v[158:159]
	v_pk_mul_f32 v[146:147], v[146:147], v[154:155]
	v_pk_mul_f32 v[158:159], v[158:159], s[6:7] op_sel_hi:[1,0]
	v_pk_fma_f32 v[146:147], v[148:149], v[150:151], v[146:147] neg_lo:[0,0,1] neg_hi:[0,0,1]
	v_pk_fma_f32 v[150:151], v[50:51], v[196:197], v[130:131] op_sel_hi:[1,0,1]
	v_pk_fma_f32 v[148:149], v[54:55], v[196:197], v[134:135] op_sel_hi:[1,0,1]
	v_pk_mul_f32 v[154:155], v[156:157], v[150:151]
	v_pk_mul_f32 v[150:151], v[152:153], v[150:151]
	v_pk_fma_f32 v[154:155], v[152:153], v[148:149], v[154:155]
	v_pk_fma_f32 v[148:149], v[156:157], v[148:149], v[150:151] neg_lo:[0,0,1] neg_hi:[0,0,1]
	v_pk_mul_f32 v[146:147], v[146:147], s[6:7] op_sel_hi:[1,0]
	v_pk_mul_f32 v[148:149], v[148:149], s[6:7] op_sel_hi:[1,0]
	v_pk_mul_f32 v[154:155], v[154:155], s[6:7] op_sel_hi:[1,0]
	v_cvt_pk_bf16_f32 v146, v146, v147
	v_cvt_pk_bf16_f32 v147, v148, v149
	global_store_dwordx2 v[144:145], v[146:147], off offset:256
	v_cvt_pk_bf16_f32 v146, v158, v159
	v_cvt_pk_bf16_f32 v147, v154, v155
	global_store_dwordx2 v[144:145], v[146:147], off offset:320
	v_add_u32_e32 v145, 16, v166
	v_cvt_f32_u32_e32 v157, v145
	v_pk_fma_f32 v[152:153], v[40:41], v[192:193], v[136:137] op_sel_hi:[1,0,1]
	v_pk_fma_f32 v[150:151], v[44:45], v[192:193], v[140:141] op_sel_hi:[1,0,1]
	v_add_u32_e32 v144, 0x90, v160
	v_mul_f32_e32 v146, v171, v157
	v_mul_f32_e32 v146, 0.15915494, v146
	v_fract_f32_e32 v147, v146
	v_sin_f32_e32 v146, v147
	v_cos_f32_e32 v148, v147
	v_mul_f32_e32 v147, v161, v157
	v_mul_f32_e32 v147, 0.15915494, v147
; DI u32x2 pack4(const float* v) { u32x2 w; w.x = pk2(v[0], v[1]); w.y = pk2(v[2], v[3]); return w; }
; DI float ex2(float x) { return __builtin_amdgcn_exp2f(x); }
; DI void sincos_rev(float ang, float& s, float& c) { float rev = ang * 0.15915494309189535f; rev = __builtin_amdgcn_fractf(rev); s = __builtin_amdgcn_sinf(rev); c = __builtin_amdgcn_cosf(rev); }
;     template <int PN> DI void body(AccRef acc, const Unit& u, int wr, int wc, int fr, int fq) const {
;     ...
;         for (int ai = 0; ai < 2; ++ai) {
;             const int rb = u.pm * 256 + ai * 128 + wr * 64 + fr;
;             int mb, pos0, kv0; row_info(rb, mb, pos0, kv0);
; #pragma unroll
;             for (int m = 0; m < 4; ++m) {
;                 const int row = rb + 16 * m, pos = pos0 + 16 * m, kvrow = kv0 + 16 * m;
;                 const float rinv = rinvh[ai][m];
;                 float v[2][8];
; #pragma unroll
;                 for (int bj = 0; bj < 2; ++bj)
; #pragma unroll
;                     for (int n = 0; n < 2; ++n)
; #pragma unroll
;                         for (int j = 0; j < 4; ++j) v[bj][4 * n + j] = acc[ai][bj][m][n][j] * rinv + cvh[ai][bj][n][j];
;     ...
;                 } else if constexpr (PN == 3 || PN == 4) {
;                     bf16_t* dst = PN == 3 ? rq : rk;
;                     const float sc = PN == 3 ? 0.125f : 1.f;
; #pragma unroll
;                     for (int bj = 0; bj < 2; ++bj) {
;                         const int head = 2 * bj + (wc >> 1), i0 = 16 * (wc & 1) + 4 * fq;
;                         float o1[4], o2[4];
; #pragma unroll
;                         for (int j = 0; j < 4; ++j) { float sn, cs; sincos_rev((float)pos * ex2(-(float)(i0 + j) * KEXP64), sn, cs);
;                             o1[j] = (v[bj][j] * cs - v[bj][4 + j] * sn) * sc; o2[j] = (v[bj][j] * sn + v[bj][4 + j] * cs) * sc; }
;                         *(u32x2*)(dst + (size_t)row * 256 + head * 64 + i0) = pack4(o1);
;                         *(u32x2*)(dst + (size_t)row * 256 + head * 64 + 32 + i0) = pack4(o2);
;                     }
	v_fract_f32_e32 v147, v147
	v_cos_f32_e32 v149, v147
	v_sin_f32_e32 v147, v147
	v_ashrrev_i32_e32 v145, 31, v144
	v_lshlrev_b64 v[144:145], 9, v[144:145]
	v_pk_mul_f32 v[154:155], v[148:149], v[152:153]
	v_pk_mul_f32 v[152:153], v[146:147], v[152:153]
	v_pk_fma_f32 v[154:155], v[146:147], v[150:151], v[154:155]
	v_pk_fma_f32 v[150:151], v[148:149], v[150:151], v[152:153] neg_lo:[0,0,1] neg_hi:[0,0,1]
	v_mul_f32_e32 v152, v173, v157
	v_mul_f32_e32 v152, 0.15915494, v152
	v_fract_f32_e32 v153, v152
	v_sin_f32_e32 v152, v153
	v_cos_f32_e32 v156, v153
	v_mul_f32_e32 v153, v175, v157
	v_mul_f32_e32 v153, 0.15915494, v153
	v_fract_f32_e32 v153, v153
	v_cos_f32_e32 v157, v153
	v_sin_f32_e32 v153, v153
	v_pk_fma_f32 v[158:159], v[46:47], v[192:193], v[142:143] op_sel_hi:[1,0,1]
	v_lshl_add_u64 v[144:145], s[58:59], 0, v[144:145]
	v_pk_mul_f32 v[164:165], v[156:157], v[162:163]
	v_pk_mul_f32 v[162:163], v[152:153], v[162:163]
	v_pk_fma_f32 v[164:165], v[152:153], v[158:159], v[164:165]
	v_pk_fma_f32 v[158:159], v[156:157], v[158:159], v[162:163] neg_lo:[0,0,1] neg_hi:[0,0,1]
	v_pk_mul_f32 v[150:151], v[150:151], s[6:7] op_sel_hi:[1,0]
	v_pk_mul_f32 v[158:159], v[158:159], s[6:7] op_sel_hi:[1,0]
	v_lshl_add_u64 v[144:145], v[144:145], 0, s[2:3]
	v_pk_mul_f32 v[154:155], v[154:155], s[6:7] op_sel_hi:[1,0]
	v_pk_mul_f32 v[164:165], v[164:165], s[6:7] op_sel_hi:[1,0]
	v_cvt_pk_bf16_f32 v150, v150, v151
	v_cvt_pk_bf16_f32 v151, v158, v159
	v_lshl_add_u64 v[144:145], v[144:145], 0, v[198:199]
	global_store_dwordx2 v[144:145], v[150:151], off
	v_cvt_pk_bf16_f32 v150, v154, v155
	v_cvt_pk_bf16_f32 v151, v164, v165
	v_pk_fma_f32 v[154:155], v[28:29], v[192:193], v[128:129] op_sel_hi:[1,0,1]
	global_store_dwordx2 v[144:145], v[150:151], off offset:64
	v_pk_fma_f32 v[150:151], v[36:37], v[192:193], v[132:133] op_sel_hi:[1,0,1]
	v_pk_mul_f32 v[158:159], v[148:149], v[154:155]
	v_pk_fma_f32 v[162:163], v[26:27], v[188:189], v[138:139] op_sel_hi:[1,0,1]
	v_pk_fma_f32 v[158:159], v[146:147], v[150:151], v[158:159]
	v_pk_mul_f32 v[146:147], v[146:147], v[154:155]
	v_pk_mul_f32 v[158:159], v[158:159], s[6:7] op_sel_hi:[1,0]
	v_pk_fma_f32 v[146:147], v[148:149], v[150:151], v[146:147] neg_lo:[0,0,1] neg_hi:[0,0,1]
	v_pk_fma_f32 v[150:151], v[30:31], v[192:193], v[130:131] op_sel_hi:[1,0,1]
	v_pk_fma_f32 v[148:149], v[38:39], v[192:193], v[134:135] op_sel_hi:[1,0,1]
	v_pk_mul_f32 v[154:155], v[156:157], v[150:151]
	v_pk_mul_f32 v[150:151], v[152:153], v[150:151]
	v_pk_fma_f32 v[154:155], v[152:153], v[148:149], v[154:155]
	v_pk_fma_f32 v[148:149], v[156:157], v[148:149], v[150:151] neg_lo:[0,0,1] neg_hi:[0,0,1]
	v_pk_mul_f32 v[146:147], v[146:147], s[6:7] op_sel_hi:[1,0]
	v_pk_mul_f32 v[148:149], v[148:149], s[6:7] op_sel_hi:[1,0]
	v_pk_mul_f32 v[154:155], v[154:155], s[6:7] op_sel_hi:[1,0]
	v_cvt_pk_bf16_f32 v146, v146, v147
	v_cvt_pk_bf16_f32 v147, v148, v149
	global_store_dwordx2 v[144:145], v[146:147], off offset:256
	v_cvt_pk_bf16_f32 v146, v158, v159
	v_cvt_pk_bf16_f32 v147, v154, v155
	global_store_dwordx2 v[144:145], v[146:147], off offset:320
	v_add_u32_e32 v145, 32, v166
	v_cvt_f32_u32_e32 v157, v145
	v_pk_fma_f32 v[152:153], v[24:25], v[188:189], v[136:137] op_sel_hi:[1,0,1]
	v_pk_fma_f32 v[150:151], v[32:33], v[188:189], v[140:141] op_sel_hi:[1,0,1]
	v_add_u32_e32 v144, 0xa0, v160
	v_mul_f32_e32 v146, v171, v157
	v_mul_f32_e32 v146, 0.15915494, v146
	v_fract_f32_e32 v147, v146
	v_sin_f32_e32 v146, v147
	v_cos_f32_e32 v148, v147
	v_mul_f32_e32 v147, v161, v157
	v_mul_f32_e32 v147, 0.15915494, v147
	v_fract_f32_e32 v147, v147
	v_cos_f32_e32 v149, v147
	v_sin_f32_e32 v147, v147
	v_ashrrev_i32_e32 v145, 31, v144
	v_lshlrev_b64 v[144:145], 9, v[144:145]
	v_pk_mul_f32 v[154:155], v[148:149], v[152:153]
	v_pk_mul_f32 v[152:153], v[146:147], v[152:153]
	v_pk_fma_f32 v[154:155], v[146:147], v[150:151], v[154:155]
	v_pk_fma_f32 v[150:151], v[148:149], v[150:151], v[152:153] neg_lo:[0,0,1] neg_hi:[0,0,1]
	v_mul_f32_e32 v152, v173, v157
	v_mul_f32_e32 v152, 0.15915494, v152
	v_fract_f32_e32 v153, v152
	v_sin_f32_e32 v152, v153
	v_cos_f32_e32 v156, v153
	v_mul_f32_e32 v153, v175, v157
	v_mul_f32_e32 v153, 0.15915494, v153
	v_fract_f32_e32 v153, v153
	v_cos_f32_e32 v157, v153
	v_sin_f32_e32 v153, v153
	v_pk_fma_f32 v[158:159], v[34:35], v[188:189], v[142:143] op_sel_hi:[1,0,1]
	v_lshl_add_u64 v[144:145], s[58:59], 0, v[144:145]
	v_pk_mul_f32 v[164:165], v[156:157], v[162:163]
	v_pk_mul_f32 v[162:163], v[152:153], v[162:163]
	v_pk_fma_f32 v[164:165], v[152:153], v[158:159], v[164:165]
	v_pk_fma_f32 v[158:159], v[156:157], v[158:159], v[162:163] neg_lo:[0,0,1] neg_hi:[0,0,1]
	v_pk_mul_f32 v[150:151], v[150:151], s[6:7] op_sel_hi:[1,0]
	v_pk_mul_f32 v[158:159], v[158:159], s[6:7] op_sel_hi:[1,0]
	v_lshl_add_u64 v[144:145], v[144:145], 0, s[2:3]
	v_pk_mul_f32 v[154:155], v[154:155], s[6:7] op_sel_hi:[1,0]
	v_pk_mul_f32 v[164:165], v[164:165], s[6:7] op_sel_hi:[1,0]
	v_cvt_pk_bf16_f32 v150, v150, v151
	v_cvt_pk_bf16_f32 v151, v158, v159
	v_lshl_add_u64 v[144:145], v[144:145], 0, v[198:199]
	global_store_dwordx2 v[144:145], v[150:151], off
	v_cvt_pk_bf16_f32 v150, v154, v155
	v_cvt_pk_bf16_f32 v151, v164, v165
	v_pk_fma_f32 v[154:155], v[16:17], v[188:189], v[128:129] op_sel_hi:[1,0,1]
	global_store_dwordx2 v[144:145], v[150:151], off offset:64
	v_pk_fma_f32 v[150:151], v[20:21], v[188:189], v[132:133] op_sel_hi:[1,0,1]
	v_pk_mul_f32 v[158:159], v[148:149], v[154:155]
	v_pk_fma_f32 v[136:137], v[8:9], v[172:173], v[136:137] op_sel_hi:[1,0,1]
	v_pk_fma_f32 v[158:159], v[146:147], v[150:151], v[158:159]
	v_pk_mul_f32 v[146:147], v[146:147], v[154:155]
; DI u32x2 pack4(const float* v) { u32x2 w; w.x = pk2(v[0], v[1]); w.y = pk2(v[2], v[3]); return w; }
; DI float ex2(float x) { return __builtin_amdgcn_exp2f(x); }
; DI void sincos_rev(float ang, float& s, float& c) { float rev = ang * 0.15915494309189535f; rev = __builtin_amdgcn_fractf(rev); s = __builtin_amdgcn_sinf(rev); c = __builtin_amdgcn_cosf(rev); }
;     template <int PN> DI void body(AccRef acc, const Unit& u, int wr, int wc, int fr, int fq) const {
;     ...
;         for (int ai = 0; ai < 2; ++ai) {
;             const int rb = u.pm * 256 + ai * 128 + wr * 64 + fr;
;             int mb, pos0, kv0; row_info(rb, mb, pos0, kv0);
; #pragma unroll
;             for (int m = 0; m < 4; ++m) {
;                 const int row = rb + 16 * m, pos = pos0 + 16 * m, kvrow = kv0 + 16 * m;
;                 const float rinv = rinvh[ai][m];
;                 float v[2][8];
; #pragma unroll
;                 for (int bj = 0; bj < 2; ++bj)
; #pragma unroll
;                     for (int n = 0; n < 2; ++n)
; #pragma unroll
;                         for (int j = 0; j < 4; ++j) v[bj][4 * n + j] = acc[ai][bj][m][n][j] * rinv + cvh[ai][bj][n][j];
;     ...
;                 } else if constexpr (PN == 3 || PN == 4) {
;                     bf16_t* dst = PN == 3 ? rq : rk;
;                     const float sc = PN == 3 ? 0.125f : 1.f;
; #pragma unroll
;                     for (int bj = 0; bj < 2; ++bj) {
;                         const int head = 2 * bj + (wc >> 1), i0 = 16 * (wc & 1) + 4 * fq;
;                         float o1[4], o2[4];
; #pragma unroll
;                         for (int j = 0; j < 4; ++j) { float sn, cs; sincos_rev((float)pos * ex2(-(float)(i0 + j) * KEXP64), sn, cs);
;                             o1[j] = (v[bj][j] * cs - v[bj][4 + j] * sn) * sc; o2[j] = (v[bj][j] * sn + v[bj][4 + j] * cs) * sc; }
;                         *(u32x2*)(dst + (size_t)row * 256 + head * 64 + i0) = pack4(o1);
;                         *(u32x2*)(dst + (size_t)row * 256 + head * 64 + 32 + i0) = pack4(o2);
;                     }
	v_pk_mul_f32 v[158:159], v[158:159], s[6:7] op_sel_hi:[1,0]
	v_pk_fma_f32 v[146:147], v[148:149], v[150:151], v[146:147] neg_lo:[0,0,1] neg_hi:[0,0,1]
	v_pk_fma_f32 v[150:151], v[18:19], v[188:189], v[130:131] op_sel_hi:[1,0,1]
	v_pk_fma_f32 v[148:149], v[22:23], v[188:189], v[134:135] op_sel_hi:[1,0,1]
	v_pk_mul_f32 v[154:155], v[156:157], v[150:151]
	v_pk_mul_f32 v[150:151], v[152:153], v[150:151]
	v_pk_fma_f32 v[154:155], v[152:153], v[148:149], v[154:155]
	v_pk_fma_f32 v[148:149], v[156:157], v[148:149], v[150:151] neg_lo:[0,0,1] neg_hi:[0,0,1]
	v_pk_mul_f32 v[146:147], v[146:147], s[6:7] op_sel_hi:[1,0]
	v_pk_mul_f32 v[148:149], v[148:149], s[6:7] op_sel_hi:[1,0]
	v_pk_mul_f32 v[154:155], v[154:155], s[6:7] op_sel_hi:[1,0]
	v_cvt_pk_bf16_f32 v146, v146, v147
	v_cvt_pk_bf16_f32 v147, v148, v149
	global_store_dwordx2 v[144:145], v[146:147], off offset:256
	v_cvt_pk_bf16_f32 v146, v158, v159
	v_cvt_pk_bf16_f32 v147, v154, v155
	global_store_dwordx2 v[144:145], v[146:147], off offset:320
	v_add_u32_e32 v145, 48, v166
	v_cvt_f32_u32_e32 v153, v145
	v_pk_fma_f32 v[140:141], v[12:13], v[172:173], v[140:141] op_sel_hi:[1,0,1]
	v_add_u32_e32 v144, 0xb0, v160
	v_pk_fma_f32 v[138:139], v[10:11], v[172:173], v[138:139] op_sel_hi:[1,0,1]
	v_mul_f32_e32 v146, v171, v153
	v_mul_f32_e32 v146, 0.15915494, v146
	v_fract_f32_e32 v147, v146
	v_sin_f32_e32 v146, v147
	v_cos_f32_e32 v148, v147
	v_mul_f32_e32 v147, v161, v153
	v_mul_f32_e32 v147, 0.15915494, v147
	v_fract_f32_e32 v147, v147
	v_cos_f32_e32 v149, v147
	v_sin_f32_e32 v147, v147
	v_ashrrev_i32_e32 v145, 31, v144
	v_pk_fma_f32 v[142:143], v[14:15], v[172:173], v[142:143] op_sel_hi:[1,0,1]
	v_pk_mul_f32 v[150:151], v[148:149], v[136:137]
	v_pk_mul_f32 v[136:137], v[146:147], v[136:137]
	v_pk_fma_f32 v[150:151], v[146:147], v[140:141], v[150:151]
	v_pk_fma_f32 v[136:137], v[148:149], v[140:141], v[136:137] neg_lo:[0,0,1] neg_hi:[0,0,1]
	v_mul_f32_e32 v140, v173, v153
	v_mul_f32_e32 v140, 0.15915494, v140
	v_fract_f32_e32 v141, v140
	v_sin_f32_e32 v140, v141
	v_cos_f32_e32 v152, v141
	v_mul_f32_e32 v141, v175, v153
	v_mul_f32_e32 v141, 0.15915494, v141
	v_fract_f32_e32 v141, v141
	v_cos_f32_e32 v153, v141
	v_sin_f32_e32 v141, v141
	v_lshlrev_b64 v[144:145], 9, v[144:145]
	v_lshl_add_u64 v[144:145], s[58:59], 0, v[144:145]
	v_pk_mul_f32 v[154:155], v[152:153], v[138:139]
	v_pk_mul_f32 v[138:139], v[140:141], v[138:139]
	v_pk_mul_f32 v[136:137], v[136:137], s[6:7] op_sel_hi:[1,0]
	v_pk_fma_f32 v[138:139], v[152:153], v[142:143], v[138:139] neg_lo:[0,0,1] neg_hi:[0,0,1]
	v_pk_fma_f32 v[154:155], v[140:141], v[142:143], v[154:155]
	v_pk_mul_f32 v[138:139], v[138:139], s[6:7] op_sel_hi:[1,0]
	v_cvt_pk_bf16_f32 v136, v136, v137
	v_cvt_pk_bf16_f32 v137, v138, v139
	v_lshl_add_u64 v[138:139], v[144:145], 0, s[2:3]
	v_pk_mul_f32 v[150:151], v[150:151], s[6:7] op_sel_hi:[1,0]
	v_pk_mul_f32 v[154:155], v[154:155], s[6:7] op_sel_hi:[1,0]
	v_lshl_add_u64 v[138:139], v[138:139], 0, v[198:199]
	global_store_dwordx2 v[138:139], v[136:137], off
	v_cvt_pk_bf16_f32 v136, v150, v151
	v_cvt_pk_bf16_f32 v137, v154, v155
	v_pk_fma_f32 v[128:129], v[0:1], v[172:173], v[128:129] op_sel_hi:[1,0,1]
	global_store_dwordx2 v[138:139], v[136:137], off offset:64
	v_pk_fma_f32 v[132:133], v[4:5], v[172:173], v[132:133] op_sel_hi:[1,0,1]
	v_pk_mul_f32 v[136:137], v[148:149], v[128:129]
	v_pk_mul_f32 v[128:129], v[146:147], v[128:129]
	v_pk_fma_f32 v[130:131], v[2:3], v[172:173], v[130:131] op_sel_hi:[1,0,1]
	v_pk_fma_f32 v[136:137], v[146:147], v[132:133], v[136:137]
	v_pk_fma_f32 v[128:129], v[148:149], v[132:133], v[128:129] neg_lo:[0,0,1] neg_hi:[0,0,1]
	v_pk_fma_f32 v[132:133], v[6:7], v[172:173], v[134:135] op_sel_hi:[1,0,1]
	v_pk_mul_f32 v[134:135], v[152:153], v[130:131]
	v_pk_mul_f32 v[130:131], v[140:141], v[130:131]
	v_pk_mul_f32 v[128:129], v[128:129], s[6:7] op_sel_hi:[1,0]
	v_pk_fma_f32 v[130:131], v[152:153], v[132:133], v[130:131] neg_lo:[0,0,1] neg_hi:[0,0,1]
	v_pk_fma_f32 v[134:135], v[140:141], v[132:133], v[134:135]
	v_pk_mul_f32 v[130:131], v[130:131], s[6:7] op_sel_hi:[1,0]
	v_pk_mul_f32 v[136:137], v[136:137], s[6:7] op_sel_hi:[1,0]
	v_pk_mul_f32 v[134:135], v[134:135], s[6:7] op_sel_hi:[1,0]
	v_cvt_pk_bf16_f32 v128, v128, v129
	v_cvt_pk_bf16_f32 v129, v130, v131
	global_store_dwordx2 v[138:139], v[128:129], off offset:256
	v_cvt_pk_bf16_f32 v128, v136, v137
	v_cvt_pk_bf16_f32 v129, v134, v135
	global_store_dwordx2 v[138:139], v[128:129], off offset:320
	s_mov_b64 s[2:3], 0
; DI u32x4 pack8(const float* v) { u32x4 w; w.x = pk2(v[0], v[1]); w.y = pk2(v[2], v[3]); w.z = pk2(v[4], v[5]); w.w = pk2(v[6], v[7]); return w; }
; DI float sum16(const float* p) { const f32x4* q = (const f32x4*)p; f32x4 a = q[0], b = q[1], c = q[2], d = q[3]; f32x4 s = (a + b) + (c + d); return (s[0] + s[1]) + (s[2] + s[3]); }
; #define xor16_32(s) xor16_32_l((s), fr + 16 * fq)
;     template <int PN> DI void body(AccRef acc, const Unit& u, int wr, int wc, int fr, int fq) const {
;     ...
;         for (int ai = 0; ai < 2; ++ai) {
;             const int rb_ = u.pm * 256 + ai * 128 + wr * 64 + fr;
; #pragma unroll
;             for (int m = 0; m < 4; ++m) rinvh[ai][m] = rsqrtf(sum16(ssq + (size_t)(rb_ + 16 * m + zdep) * 16) * (1.f / 1024.f) + EPS);
;             asm volatile("v_mov_b32 %0, 0" : "=v"(zdep) : "v"(rinvh[ai][0]), "v"(rinvh[ai][1]), "v"(rinvh[ai][2]), "v"(rinvh[ai][3]));
;         }
; #pragma unroll
;         for (int ai = 0; ai < 2; ++ai) {
;             const int rb_ = u.pm * 256 + ai * 128 + wr * 64 + fr;
;             int mb_, p_, k_; row_info(rb_, mb_, p_, k_);
; #pragma unroll
;             for (int bj = 0; bj < 2; ++bj)
; #pragma unroll
;                 for (int n = 0; n < 2; ++n) cvh[ai][bj][n] = *(const f32x4*)(cv + (size_t)(mb_ + zdep) * NIN + PN * 256 + bj * 128 + cl + 4 * n);
;         }
;     ...
;                 } else if constexpr (PN == 2) {
;                     float s = 0.f;
;                     *(u32x4*)(zq + (size_t)row * 384 + 256 + cl) = pack8(v[0]);
; #pragma unroll
;                     for (int j = 0; j < 8; ++j) s += v[0][j] * v[0][j];
;                     s = xor16_32(s);
;                     if (fq == 0) ssqq[(size_t)row * 8 + 4 + wc] = s;
.LBB0_376:
	s_andn2_b64 vcc, exec, s[2:3]
	s_cbranch_vccnz .LBB0_414
	s_lshl_b32 s2, s53, 6
	s_lshl_b32 s3, s34, 8
	s_add_i32 s2, s2, s3
	v_add_u32_e32 v160, s2, v214
	v_add_u32_e32 v190, 16, v160
	v_ashrrev_i32_e32 v161, 31, v160
	v_ashrrev_i32_e32 v191, 31, v190
	v_lshlrev_b64 v[128:129], 6, v[160:161]
	v_lshlrev_b64 v[144:145], 6, v[190:191]
	v_add_u32_e32 v174, 32, v160
	v_lshl_add_u64 v[140:141], s[56:57], 0, v[128:129]
	v_lshl_add_u64 v[144:145], s[56:57], 0, v[144:145]
	v_ashrrev_i32_e32 v175, 31, v174
	s_nop 0
	s_nop 0
	v_lshlrev_b64 v[144:145], 6, v[174:175]
	v_add_u32_e32 v172, 48, v160
	v_lshl_add_u64 v[144:145], s[56:57], 0, v[144:145]
	v_ashrrev_i32_e32 v173, 31, v172
	v_lshlrev_b64 v[144:145], 6, v[172:173]
	v_lshl_add_u64 v[144:145], s[56:57], 0, v[144:145]
	s_mov_b32 s2, 0x358637bd
	v_mov_b64_e32 v[144:145], s[2:3]
	s_mov_b32 s8, 0x3a800000
	v_mov_b32_e32 v202, v245
	v_mov_b32_e32 v196, v246
	v_add_u32_e32 v162, 0x80, v160
	v_mov_b32_e32 v204, v244
	v_mov_b32_e32 v192, v247
	v_mov_b32 v128, 0
	v_add_u32_e32 v193, 0xffffc000, v160
	v_add_u32_e32 v158, v128, v162
	v_ashrrev_i32_e32 v159, 31, v158
	v_add_u32_e32 v146, 16, v158
	v_lshlrev_b64 v[128:129], 6, v[158:159]
	v_ashrrev_i32_e32 v147, 31, v146
	v_add_u32_e32 v168, 32, v158
	v_lshl_add_u64 v[140:141], s[56:57], 0, v[128:129]
	v_lshlrev_b64 v[146:147], 6, v[146:147]
	v_ashrrev_i32_e32 v169, 31, v168
	v_add_u32_e32 v158, 48, v158
	s_nop 0
	v_lshl_add_u64 v[164:165], s[56:57], 0, v[146:147]
	v_lshlrev_b64 v[168:169], 6, v[168:169]
	v_ashrrev_i32_e32 v159, 31, v158
	s_nop 0
	v_lshl_add_u64 v[188:189], s[56:57], 0, v[168:169]
	v_lshlrev_b64 v[158:159], 6, v[158:159]
	v_lshl_add_u64 v[158:159], s[56:57], 0, v[158:159]
	s_movk_i32 s6, 0x4000
	v_mov_b32_e32 v194, v248
	v_mov_b32_e32 v188, v249
	v_mov_b32_e32 v170, v250
	v_lshrrev_b32_e32 v164, 6, v193
	v_mov_b32_e32 v166, v251
	s_lshl_b32 s2, s66, 5
	v_ashrrev_i32_e32 v128, 11, v160
	v_add_u32_e32 v129, 8, v164
	v_cmp_gt_i32_e64 s[4:5], s6, v160
	v_lshl_add_u32 v168, v213, 3, s2
	v_mov_b32 v136, 0
	v_ashrrev_i32_e32 v169, 31, v168
	v_cndmask_b32_e64 v128, v129, v128, s[4:5]
	v_add_u32_e32 v130, v136, v128
	v_mov_b64_e32 v[128:129], s[10:11]
	v_mad_i64_i32 v[130:131], s[2:3], v130, s51, v[128:129]
	v_lshlrev_b64 v[132:133], 2, v[168:169]
	v_lshl_add_u64 v[130:131], v[130:131], 0, v[132:133]
	s_mov_b64 s[8:9], 0x124800
	v_lshl_add_u64 v[134:135], v[130:131], 0, s[8:9]
	v_add_co_u32_e32 v130, vcc, s39, v130
	v_add_u32_e32 v171, 0xffffc080, v160
	s_nop 0
	v_addc_co_u32_e32 v131, vcc, 0, v131, vcc
	v_lshrrev_b32_e32 v163, 6, v171
	global_load_dwordx4 v[152:155], v[130:131], off offset:2048
	global_load_dwordx4 v[144:147], v[134:135], off offset:528
	global_load_dwordx4 v[156:159], v[134:135], off offset:16
	global_load_dwordx4 v[148:151], v[134:135], off offset:512
	v_ashrrev_i32_e32 v130, 11, v162
	v_add_u32_e32 v131, 8, v163
	v_cmp_gt_i32_e64 s[6:7], s6, v162
	v_and_b32_e32 v165, 63, v214
	v_or_b32_e32 v198, 0x4400, v165
	v_cndmask_b32_e64 v130, v131, v130, s[6:7]
	v_add_u32_e32 v130, v136, v130
	v_mad_i64_i32 v[128:129], s[2:3], v130, s51, v[128:129]
	v_lshl_add_u64 v[128:129], v[128:129], 0, v[132:133]
	v_lshl_add_u64 v[132:133], v[128:129], 0, s[8:9]
	v_add_co_u32_e32 v128, vcc, 0x124000, v128
	s_movk_i32 s2, 0x3fff
	s_nop 0
	v_addc_co_u32_e32 v129, vcc, 0, v129, vcc
	global_load_dwordx4 v[136:139], v[128:129], off offset:2048
	s_nop 0
	global_load_dwordx4 v[128:131], v[132:133], off offset:528
	global_load_dwordx4 v[140:143], v[132:133], off offset:16
	s_nop 0
	global_load_dwordx4 v[132:135], v[132:133], off offset:512
	v_cmp_lt_i32_e32 vcc, s2, v160
	v_cmp_lt_i32_e64 s[8:9], s2, v162
	s_and_saveexec_b64 s[2:3], vcc
	s_xor_b64 s[2:3], exec, s[2:3]
	s_movk_i32 s12, 0x440
	v_mad_u64_u32 v[200:201], s[12:13], v164, s12, v[198:199]
	s_or_saveexec_b64 s[2:3], s[2:3]
	v_or_b32_e32 v199, 0x400, v165
	v_mov_b32_e32 v189, v199
	s_xor_b64 exec, exec, s[2:3]
	v_and_b32_e32 v189, 0x7ff, v160
	v_mov_b32_e32 v200, v160
	s_or_b64 exec, exec, s[2:3]
	v_lshlrev_b32_e32 v164, 2, v214
	v_lshl_add_u32 v164, v213, 6, v164
	v_xor_b32_e32 v206, 64, v164
	v_xor_b32_e32 v167, 0x80, v164
	s_waitcnt vmcnt(7)
	v_pk_fma_f32 v[164:165], v[124:125], v[204:205], v[152:153] op_sel_hi:[1,0,1]
	v_pk_fma_f32 v[220:221], v[126:127], v[204:205], v[154:155] op_sel_hi:[1,0,1]
	v_cvt_pk_bf16_f32 v216, v164, v165
	v_pk_mul_f32 v[164:165], v[164:165], v[164:165]
	v_cvt_pk_bf16_f32 v217, v220, v221
	v_pk_mul_f32 v[220:221], v[220:221], v[220:221]
	v_add_f32_e32 v164, v164, v165
	s_waitcnt vmcnt(5)
	v_pk_fma_f32 v[222:223], v[120:121], v[204:205], v[156:157] op_sel_hi:[1,0,1]
	v_add_f32_e32 v164, v220, v164
	v_cvt_pk_bf16_f32 v218, v222, v223
	v_pk_mul_f32 v[222:223], v[222:223], v[222:223]
	v_add_f32_e32 v164, v221, v164
	v_pk_fma_f32 v[228:229], v[122:123], v[204:205], v[158:159] op_sel_hi:[1,0,1]
	v_add_f32_e32 v164, v222, v164
	v_cvt_pk_bf16_f32 v219, v228, v229
	v_pk_mul_f32 v[228:229], v[228:229], v[228:229]
	v_add_f32_e32 v164, v223, v164
	v_add_f32_e32 v164, v228, v164
	v_add_f32_e32 v195, v229, v164
	ds_bpermute_b32 v197, v206, v195
	s_ashr_i32 s67, s66, 31
	s_lshl_b64 s[12:13], s[66:67], 2
	v_readlane_b32 s16, v254, 48
	s_add_u32 s16, s16, s12
	v_readlane_b32 s12, v254, 50
	v_mov_b64_e32 v[164:165], s[10:11]
	s_addc_u32 s17, s12, s13
	v_mad_i64_i32 v[164:165], s[12:13], v160, s72, v[164:165]
	v_lshl_add_u64 v[220:221], v[168:169], 1, v[164:165]
	s_waitcnt lgkmcnt(0)
	v_add_f32_e32 v164, v195, v197
	ds_bpermute_b32 v165, v167, v164
	v_add_co_u32_e32 v220, vcc, s73, v220
	v_cmp_eq_u32_e64 s[2:3], 0, v213
	s_nop 0
	v_addc_co_u32_e32 v221, vcc, 0, v221, vcc
	global_store_dwordx4 v[220:221], v[216:219], off offset:512
	s_and_saveexec_b64 s[12:13], s[2:3]
	s_cbranch_execz .LBB0_383
	v_lshlrev_b64 v[216:217], 5, v[160:161]
	v_lshl_add_u64 v[216:217], s[16:17], 0, v[216:217]
	s_waitcnt lgkmcnt(0)
	v_add_f32_e32 v164, v164, v165
	global_store_dword v[216:217], v164, off

; DI u32x4 pack8(const float* v) { u32x4 w; w.x = pk2(v[0], v[1]); w.y = pk2(v[2], v[3]); w.z = pk2(v[4], v[5]); w.w = pk2(v[6], v[7]); return w; }
; DI float sum16(const float* p) { const f32x4* q = (const f32x4*)p; f32x4 a = q[0], b = q[1], c = q[2], d = q[3]; f32x4 s = (a + b) + (c + d); return (s[0] + s[1]) + (s[2] + s[3]); }
; #define xor16_32(s) xor16_32_l((s), fr + 16 * fq)
;     template <int PN> DI void body(AccRef acc, const Unit& u, int wr, int wc, int fr, int fq) const {
;     ...
;         for (int ai = 0; ai < 2; ++ai) {
;             const int rb_ = u.pm * 256 + ai * 128 + wr * 64 + fr;
; #pragma unroll
;             for (int m = 0; m < 4; ++m) rinvh[ai][m] = rsqrtf(sum16(ssq + (size_t)(rb_ + 16 * m + zdep) * 16) * (1.f / 1024.f) + EPS);
;             asm volatile("v_mov_b32 %0, 0" : "=v"(zdep) : "v"(rinvh[ai][0]), "v"(rinvh[ai][1]), "v"(rinvh[ai][2]), "v"(rinvh[ai][3]));
;         }
; #pragma unroll
;         for (int ai = 0; ai < 2; ++ai) {
;             const int rb_ = u.pm * 256 + ai * 128 + wr * 64 + fr;
;             int mb_, p_, k_; row_info(rb_, mb_, p_, k_);
; #pragma unroll
;             for (int bj = 0; bj < 2; ++bj)
; #pragma unroll
;                 for (int n = 0; n < 2; ++n) cvh[ai][bj][n] = *(const f32x4*)(cv + (size_t)(mb_ + zdep) * NIN + PN * 256 + bj * 128 + cl + 4 * n);
;         }
;     ...
;                 } else if constexpr (PN == 1) {
;                     float s = 0.f;
; #pragma unroll
;                     for (int bj = 0; bj < 2; ++bj) {
;                         *(u32x4*)(zq + (size_t)row * 384 + bj * 128 + cl) = pack8(v[bj]);
; #pragma unroll
;                         for (int j = 0; j < 8; ++j) s += v[bj][j] * v[bj][j];
;                     }
;                     s = xor16_32(s);
;                     if (fq == 0) ssqq[(size_t)row * 8 + wc] = s;
.LBB0_415:
	s_andn2_b64 vcc, exec, s[2:3]
	s_mov_b64 s[8:9], 0
	s_cbranch_vccnz .LBB0_436
	s_cmp_gt_i32 s52, 0
	s_mov_b64 s[2:3], -1
	s_cbranch_scc0 .LBB0_434
	s_lshl_b32 s2, s66, 5
	v_lshl_add_u32 v190, v213, 3, s2
	s_lshl_b32 s2, s53, 6
	s_lshl_b32 s3, s34, 8
	s_add_i32 s2, s2, s3
	v_add_u32_e32 v160, s2, v214
	v_ashrrev_i32_e32 v161, 31, v160
	v_lshlrev_b64 v[128:129], 6, v[160:161]
	v_lshl_add_u64 v[140:141], s[56:57], 0, v[128:129]
	s_waitcnt lgkmcnt(0)
	s_nop 0
	v_add_u32_e32 v164, 16, v160
	v_ashrrev_i32_e32 v165, 31, v164
	s_mov_b32 s2, 0x358637bd
	s_mov_b32 s4, 0x3a800000
	v_add_u32_e32 v166, 32, v160
	v_ashrrev_i32_e32 v167, 31, v166
	v_add_u32_e32 v162, 48, v160
	v_ashrrev_i32_e32 v163, 31, v162
	v_add_u32_e32 v168, 0x80, v160
	v_ashrrev_i32_e32 v191, 31, v190
	s_mov_b64 s[6:7], 0x124400
	v_lshlrev_b32_e32 v169, 2, v214
	v_lshl_add_u32 v169, v213, 6, v169
	v_xor_b32_e32 v173, 64, v169
	v_xor_b32_e32 v171, 0x80, v169
	s_ashr_i32 s67, s66, 31
	s_nop 0
	v_lshlrev_b64 v[128:129], 6, v[164:165]
	v_lshl_add_u64 v[140:141], s[56:57], 0, v[128:129]
	s_nop 0
	s_nop 0
	v_mov_b64_e32 v[128:129], s[2:3]
	s_nop 0
	s_nop 0
	s_nop 0
	v_mov_b32_e32 v194, v244
	s_nop 0
	v_mov_b32_e32 v170, v245
	v_lshlrev_b64 v[130:131], 6, v[166:167]
	v_lshl_add_u64 v[142:143], s[56:57], 0, v[130:131]
	s_nop 0
	s_nop 0
	v_lshlrev_b64 v[130:131], 6, v[162:163]
	v_lshl_add_u64 v[142:143], s[56:57], 0, v[130:131]
	s_nop 0
	s_nop 0
	s_nop 0
	s_nop 0
	s_nop 0
	s_nop 0
	v_mov_b32_e32 v196, v246
	s_nop 0
	v_mov_b32_e32 v192, v247
	v_mov_b32 v130, 0
	s_nop 0
	v_add_u32_e32 v130, v130, v168
	v_ashrrev_i32_e32 v131, 31, v130
	v_lshlrev_b64 v[132:133], 6, v[130:131]
	v_lshl_add_u64 v[144:145], s[56:57], 0, v[132:133]
	s_nop 0
	s_nop 0
	v_add_u32_e32 v132, 16, v130
	v_ashrrev_i32_e32 v133, 31, v132
	v_lshlrev_b64 v[132:133], 6, v[132:133]
	v_lshl_add_u64 v[144:145], s[56:57], 0, v[132:133]
	s_nop 0
	s_nop 0
	s_nop 0
	s_nop 0
	s_nop 0
	s_nop 0
	v_mov_b32_e32 v174, v248
	s_nop 0
	v_mov_b32_e32 v172, v249
	v_add_u32_e32 v132, 32, v130
	v_ashrrev_i32_e32 v133, 31, v132
	v_lshlrev_b64 v[132:133], 6, v[132:133]
	v_lshl_add_u64 v[144:145], s[56:57], 0, v[132:133]
	s_nop 0
	v_add_u32_e32 v130, 48, v130
	v_ashrrev_i32_e32 v131, 31, v130
	v_lshlrev_b64 v[130:131], 6, v[130:131]
	v_lshl_add_u64 v[142:143], s[56:57], 0, v[130:131]
	s_nop 0
	s_nop 0
	v_lshlrev_b64 v[132:133], 2, v[190:191]
	s_movk_i32 s4, 0x4000
	s_nop 0
	s_nop 0
	v_mov_b32_e32 v198, v250
	s_nop 0
	v_mov_b32_e32 v188, v251
	v_add_u32_e32 v129, 0xffffc000, v160
	v_lshrrev_b32_e32 v129, 6, v129
	v_cmp_gt_i32_e32 vcc, s4, v160
	v_ashrrev_i32_e32 v128, 11, v160
	v_add_u32_e32 v129, 8, v129
	v_cndmask_b32_e32 v128, v129, v128, vcc
	v_mov_b32 v136, 0
	s_nop 0
	v_add_u32_e32 v130, v136, v128
	v_mov_b64_e32 v[128:129], s[10:11]
	v_mad_i64_i32 v[130:131], s[2:3], v130, s51, v[128:129]
	v_lshl_add_u64 v[130:131], v[130:131], 0, v[132:133]
	v_lshl_add_u64 v[134:135], v[130:131], 0, s[6:7]
	v_add_co_u32_e32 v130, vcc, s39, v130
	s_nop 1
	v_addc_co_u32_e32 v131, vcc, 0, v131, vcc
	global_load_dwordx4 v[148:151], v[130:131], off offset:1024
	global_load_dwordx4 v[152:155], v[134:135], off offset:16
	global_load_dwordx4 v[144:147], v[134:135], off offset:528
	global_load_dwordx4 v[156:159], v[134:135], off offset:512
	v_add_u32_e32 v131, 0xffffc080, v160
	v_lshrrev_b32_e32 v131, 6, v131
	v_cmp_gt_i32_e32 vcc, s4, v168
	v_ashrrev_i32_e32 v130, 11, v168
	v_add_u32_e32 v131, 8, v131
	v_cndmask_b32_e32 v130, v131, v130, vcc
	v_add_u32_e32 v130, v136, v130
	v_mad_i64_i32 v[128:129], s[2:3], v130, s51, v[128:129]
	v_lshl_add_u64 v[128:129], v[128:129], 0, v[132:133]
	v_lshl_add_u64 v[140:141], v[128:129], 0, s[6:7]
	v_add_co_u32_e32 v128, vcc, s39, v128
	v_readlane_b32 s2, v254, 51
	s_nop 0
	v_addc_co_u32_e32 v129, vcc, 0, v129, vcc
	global_load_dwordx4 v[136:139], v[128:129], off offset:1024
	global_load_dwordx4 v[132:135], v[140:141], off offset:16
	s_nop 0
	global_load_dwordx4 v[128:131], v[140:141], off offset:528
	s_nop 0
	global_load_dwordx4 v[140:143], v[140:141], off offset:512
	v_readlane_b32 s3, v254, 52
	v_readlane_b32 s4, v254, 53
	v_cmp_eq_u32_e32 vcc, 0, v213
	v_lshl_add_u64 v[190:191], v[190:191], 1, s[2:3]
	s_lshl_b64 s[2:3], s[66:67], 2
	s_add_u32 s2, s4, s2
	v_mad_i64_i32 v[230:231], s[4:5], v160, s72, v[190:191]
	s_addc_u32 s3, s44, s3
	s_waitcnt vmcnt(7)
	v_pk_fma_f32 v[204:205], v[124:125], v[194:195], v[148:149] op_sel_hi:[1,0,1]
	v_pk_fma_f32 v[206:207], v[126:127], v[194:195], v[150:151] op_sel_hi:[1,0,1]
	v_cvt_pk_bf16_f32 v200, v204, v205
	v_pk_mul_f32 v[204:205], v[204:205], v[204:205]
	v_cvt_pk_bf16_f32 v201, v206, v207
	v_pk_mul_f32 v[206:207], v[206:207], v[206:207]
	v_add_f32_e32 v169, v204, v205
	s_waitcnt vmcnt(6)
	v_pk_fma_f32 v[216:217], v[120:121], v[194:195], v[152:153] op_sel_hi:[1,0,1]
	v_add_f32_e32 v169, v206, v169
	v_cvt_pk_bf16_f32 v202, v216, v217
	v_pk_mul_f32 v[216:217], v[216:217], v[216:217]
	v_add_f32_e32 v169, v207, v169
	v_pk_fma_f32 v[218:219], v[122:123], v[194:195], v[154:155] op_sel_hi:[1,0,1]
	v_add_f32_e32 v169, v216, v169
	s_waitcnt vmcnt(4)
	v_pk_fma_f32 v[220:221], v[116:117], v[194:195], v[156:157] op_sel_hi:[1,0,1]
	v_pk_fma_f32 v[222:223], v[118:119], v[194:195], v[158:159] op_sel_hi:[1,0,1]
	v_pk_fma_f32 v[228:229], v[112:113], v[194:195], v[144:145] op_sel_hi:[1,0,1]
	v_pk_fma_f32 v[194:195], v[114:115], v[194:195], v[146:147] op_sel_hi:[1,0,1]
	v_cvt_pk_bf16_f32 v203, v218, v219
	v_pk_mul_f32 v[218:219], v[218:219], v[218:219]
	v_add_f32_e32 v169, v217, v169
	global_store_dwordx4 v[230:231], v[200:203], off
	v_add_f32_e32 v169, v218, v169
	v_add_f32_e32 v169, v219, v169
	v_cvt_pk_bf16_f32 v200, v220, v221
	v_cvt_pk_bf16_f32 v201, v222, v223
	v_cvt_pk_bf16_f32 v202, v228, v229
	v_cvt_pk_bf16_f32 v203, v194, v195
	global_store_dwordx4 v[230:231], v[200:203], off offset:256
	v_pk_mul_f32 v[194:195], v[194:195], v[194:195]
	s_nop 0
	v_pk_mul_f32 v[200:201], v[220:221], v[220:221]
	v_pk_mul_f32 v[202:203], v[222:223], v[222:223]
	v_add_f32_e32 v169, v200, v169
	v_add_f32_e32 v169, v201, v169
	v_add_f32_e32 v169, v202, v169
	v_pk_mul_f32 v[220:221], v[228:229], v[228:229]
	v_add_f32_e32 v169, v203, v169
	v_add_f32_e32 v169, v220, v169
	v_add_f32_e32 v169, v221, v169
	v_add_f32_e32 v169, v194, v169
	v_add_f32_e32 v169, v195, v169
	ds_bpermute_b32 v175, v173, v169
	s_waitcnt lgkmcnt(0)
	v_add_f32_e32 v169, v169, v175
	ds_bpermute_b32 v175, v171, v169
	s_and_saveexec_b64 s[4:5], vcc
	s_cbranch_execz .LBB0_419
	v_lshlrev_b64 v[194:195], 5, v[160:161]
	v_lshl_add_u64 v[194:195], s[2:3], 0, v[194:195]
	s_waitcnt lgkmcnt(0)
	v_add_f32_e32 v161, v169, v175
	global_store_dword v[194:195], v161, off

; DI float sum16(const float* p) { const f32x4* q = (const f32x4*)p; f32x4 a = q[0], b = q[1], c = q[2], d = q[3]; f32x4 s = (a + b) + (c + d); return (s[0] + s[1]) + (s[2] + s[3]); }
;     template <int PN> DI void body(AccRef acc, const Unit& u, int wr, int wc, int fr, int fq) const {
;     ...
;         for (int ai = 0; ai < 2; ++ai) {
;             const int rb_ = u.pm * 256 + ai * 128 + wr * 64 + fr;
; #pragma unroll
;             for (int m = 0; m < 4; ++m) rinvh[ai][m] = rsqrtf(sum16(ssq + (size_t)(rb_ + 16 * m + zdep) * 16) * (1.f / 1024.f) + EPS);
;             asm volatile("v_mov_b32 %0, 0" : "=v"(zdep) : "v"(rinvh[ai][0]), "v"(rinvh[ai][1]), "v"(rinvh[ai][2]), "v"(rinvh[ai][3]));
;         }
; #pragma unroll
;         for (int ai = 0; ai < 2; ++ai) {
;             const int rb_ = u.pm * 256 + ai * 128 + wr * 64 + fr;
;             int mb_, p_, k_; row_info(rb_, mb_, p_, k_);
; #pragma unroll
;             for (int bj = 0; bj < 2; ++bj)
; #pragma unroll
;                 for (int n = 0; n < 2; ++n) cvh[ai][bj][n] = *(const f32x4*)(cv + (size_t)(mb_ + zdep) * NIN + PN * 256 + bj * 128 + cl + 4 * n);
;         }
;     ...
;                 } else {
;                     float* lo = orow(out, l, row, PN == 8 ? O_PSK : O_PSV, PN == 8 ? O_SSK : O_SSV, 256);
; #pragma unroll
;                     for (int bj = 0; bj < 2; ++bj) {
;                         *(f32x4*)(lo + bj * 128 + cl) = (f32x4){v[bj][0], v[bj][1], v[bj][2], v[bj][3]};
;                         *(f32x4*)(lo + bj * 128 + cl + 4) = (f32x4){v[bj][4], v[bj][5], v[bj][6], v[bj][7]};
;                     }
.LBB0_436:
	s_and_b64 vcc, exec, s[94:95]
	s_movk_i32 s94, 0x4000
	s_cbranch_vccz .LBB0_439
	s_lshl_b32 s2, s53, 6
	s_lshl_b32 s3, s34, 8
	s_add_i32 s2, s2, s3
	v_add_u32_e32 v160, s2, v214
	v_ashrrev_i32_e32 v161, 31, v160
	v_lshlrev_b64 v[128:129], 6, v[160:161]
	v_lshl_add_u64 v[140:141], s[56:57], 0, v[128:129]
	s_waitcnt lgkmcnt(0)
	s_nop 0
	v_add_u32_e32 v168, 16, v160
	v_ashrrev_i32_e32 v169, 31, v168
	s_mov_b32 s2, 0x358637bd
	s_mov_b32 s4, 0x3a800000
	v_add_u32_e32 v164, 32, v160
	v_ashrrev_i32_e32 v165, 31, v164
	v_add_u32_e32 v166, 48, v160
	v_ashrrev_i32_e32 v167, 31, v166
	v_add_u32_e32 v163, 0x80, v160
	v_add_u32_e32 v173, 0xffffc000, v160
	v_add_u32_e32 v171, 0xffffc080, v160
	v_mov_b32_e32 v175, 0x8800000
	s_nop 0
	v_lshlrev_b64 v[128:129], 6, v[168:169]
	v_lshl_add_u64 v[140:141], s[56:57], 0, v[128:129]
	s_nop 0
	s_nop 0
	v_mov_b64_e32 v[128:129], s[2:3]
	s_nop 0
	s_nop 0
	s_nop 0
	v_mov_b32_e32 v188, v244
	s_nop 0
	v_mov_b32_e32 v162, v245
	v_lshlrev_b64 v[130:131], 6, v[164:165]
	v_lshl_add_u64 v[142:143], s[56:57], 0, v[130:131]
	s_nop 0
	s_nop 0
	v_lshlrev_b64 v[130:131], 6, v[166:167]
	v_lshl_add_u64 v[142:143], s[56:57], 0, v[130:131]
	s_nop 0
	s_nop 0
	s_nop 0
	s_nop 0
	s_nop 0
	s_nop 0
	v_mov_b32_e32 v170, v246
	s_nop 0
	v_mov_b32_e32 v174, v247
	v_mov_b32 v130, 0
	s_nop 0
	v_add_u32_e32 v130, v130, v163
	v_ashrrev_i32_e32 v131, 31, v130
	v_lshlrev_b64 v[132:133], 6, v[130:131]
	v_lshl_add_u64 v[144:145], s[56:57], 0, v[132:133]
	s_nop 0
	s_nop 0
	v_add_u32_e32 v132, 16, v130
	v_ashrrev_i32_e32 v133, 31, v132
	v_lshlrev_b64 v[132:133], 6, v[132:133]
	v_lshl_add_u64 v[144:145], s[56:57], 0, v[132:133]
	s_nop 0
	s_nop 0
	s_nop 0
	s_nop 0
	s_nop 0
	s_nop 0
	v_mov_b32_e32 v190, v248
	s_nop 0
	v_mov_b32_e32 v172, v249
	v_add_u32_e32 v132, 32, v130
	v_ashrrev_i32_e32 v133, 31, v132
	v_lshlrev_b64 v[132:133], 6, v[132:133]
	v_lshl_add_u64 v[144:145], s[56:57], 0, v[132:133]
	s_nop 0
	v_add_u32_e32 v130, 48, v130
	v_ashrrev_i32_e32 v131, 31, v130
	v_lshlrev_b64 v[130:131], 6, v[130:131]
	v_lshl_add_u64 v[142:143], s[56:57], 0, v[130:131]
	s_nop 0
	s_nop 0
	s_nop 0
	v_lshrrev_b32_e32 v131, 6, v173
	v_add_u32_e32 v131, 8, v131
	s_nop 0
	v_mov_b32_e32 v192, v250
	s_lshl_b32 s2, s66, 5
	v_ashrrev_i32_e32 v130, 11, v160
	v_mov_b32_e32 v194, v251
	v_lshl_add_u32 v128, v213, 3, s2
	v_cmp_gt_i32_e64 s[2:3], s94, v160
	v_mov_b32 v134, 0
	v_ashrrev_i32_e32 v129, 31, v128
	v_lshlrev_b64 v[196:197], 2, v[128:129]
	v_cndmask_b32_e64 v130, v131, v130, s[2:3]
	v_add_u32_e32 v132, v134, v130
	v_mov_b64_e32 v[130:131], s[10:11]
	v_mad_i64_i32 v[132:133], s[4:5], v132, s51, v[130:131]
	v_lshl_add_u64 v[128:129], v[132:133], 0, v[196:197]
	v_lshl_add_u64 v[132:133], v[128:129], 0, s[40:41]
	v_add_co_u32_e32 v128, vcc, s62, v128
	v_cndmask_b32_e64 v198, v173, v160, s[2:3]
	s_nop 0
	v_addc_co_u32_e32 v129, vcc, 0, v129, vcc
	global_load_dwordx4 v[152:155], v[128:129], off offset:1024
	global_load_dwordx4 v[156:159], v[132:133], off offset:16
	global_load_dwordx4 v[144:147], v[132:133], off offset:528
	global_load_dwordx4 v[148:151], v[132:133], off offset:512
	v_lshrrev_b32_e32 v129, 6, v171
	v_cmp_gt_i32_e32 vcc, s94, v163
	v_ashrrev_i32_e32 v128, 11, v163
	v_add_u32_e32 v129, 8, v129
	v_cndmask_b32_e32 v128, v129, v128, vcc
	v_add_u32_e32 v128, v134, v128
	v_mad_i64_i32 v[128:129], s[4:5], v128, s51, v[130:131]
	v_lshl_add_u64 v[128:129], v[128:129], 0, v[196:197]
	v_lshl_add_u64 v[132:133], v[128:129], 0, s[40:41]
	v_add_co_u32_e64 v128, s[4:5], s62, v128
	v_mov_b32_e32 v173, 0xad98000
	s_nop 0
	v_addc_co_u32_e64 v129, s[4:5], 0, v129, s[4:5]
	global_load_dwordx4 v[140:143], v[128:129], off offset:1024
	global_load_dwordx4 v[136:139], v[132:133], off offset:16
	s_nop 0
	global_load_dwordx4 v[128:131], v[132:133], off offset:528
	s_nop 0
	global_load_dwordx4 v[132:135], v[132:133], off offset:512
	v_cndmask_b32_e64 v199, 0, v161, s[2:3]
	v_cndmask_b32_e64 v224, v173, v175, s[2:3]
	v_lshl_add_u64 v[200:201], s[42:43], 0, v[224:225]
	v_lshlrev_b64 v[198:199], 10, v[198:199]
	v_lshl_add_u64 v[198:199], v[200:201], 0, v[198:199]
	v_lshl_add_u64 v[202:203], v[198:199], 0, v[196:197]
	v_cmp_gt_i32_e64 s[2:3], s82, v160
	v_add_u32_e32 v161, 0xffffc010, v160
	s_waitcnt vmcnt(7)
	v_pk_fma_f32 v[200:201], v[126:127], v[188:189], v[154:155] op_sel_hi:[1,0,1]
	v_pk_fma_f32 v[198:199], v[124:125], v[188:189], v[152:153] op_sel_hi:[1,0,1]
	global_store_dwordx4 v[202:203], v[198:201], off
	v_cndmask_b32_e64 v169, 0, v169, s[2:3]
	v_cndmask_b32_e64 v168, v161, v168, s[2:3]
	s_waitcnt vmcnt(7)
	v_pk_fma_f32 v[200:201], v[122:123], v[188:189], v[158:159] op_sel_hi:[1,0,1]
	v_pk_fma_f32 v[198:199], v[120:121], v[188:189], v[156:157] op_sel_hi:[1,0,1]
	global_store_dwordx4 v[202:203], v[198:201], off offset:16
	v_cndmask_b32_e64 v224, v173, v175, s[2:3]
	v_lshlrev_b64 v[168:169], 10, v[168:169]
	s_waitcnt vmcnt(6)
;     template <int PN> DI void body(AccRef acc, const Unit& u, int wr, int wc, int fr, int fq) const {
;     ...
;         for (int ai = 0; ai < 2; ++ai) {
;             const int rb = u.pm * 256 + ai * 128 + wr * 64 + fr;
;             int mb, pos0, kv0; row_info(rb, mb, pos0, kv0);
; #pragma unroll
;             for (int m = 0; m < 4; ++m) {
;                 const int row = rb + 16 * m, pos = pos0 + 16 * m, kvrow = kv0 + 16 * m;
;                 const float rinv = rinvh[ai][m];
;                 float v[2][8];
; #pragma unroll
;                 for (int bj = 0; bj < 2; ++bj)
; #pragma unroll
;                     for (int n = 0; n < 2; ++n)
; #pragma unroll
;                         for (int j = 0; j < 4; ++j) v[bj][4 * n + j] = acc[ai][bj][m][n][j] * rinv + cvh[ai][bj][n][j];
;     ...
;                 } else {
;                     float* lo = orow(out, l, row, PN == 8 ? O_PSK : O_PSV, PN == 8 ? O_SSK : O_SSV, 256);
; #pragma unroll
;                     for (int bj = 0; bj < 2; ++bj) {
;                         *(f32x4*)(lo + bj * 128 + cl) = (f32x4){v[bj][0], v[bj][1], v[bj][2], v[bj][3]};
;                         *(f32x4*)(lo + bj * 128 + cl + 4) = (f32x4){v[bj][4], v[bj][5], v[bj][6], v[bj][7]};
;                     }
	v_pk_fma_f32 v[200:201], v[118:119], v[188:189], v[150:151] op_sel_hi:[1,0,1]
	v_pk_fma_f32 v[198:199], v[116:117], v[188:189], v[148:149] op_sel_hi:[1,0,1]
	global_store_dwordx4 v[202:203], v[198:201], off offset:512
	v_cmp_gt_i32_e64 s[2:3], s83, v160
	v_add_u32_e32 v161, 0xffffc020, v160
	v_pk_fma_f32 v[200:201], v[114:115], v[188:189], v[146:147] op_sel_hi:[1,0,1]
	v_pk_fma_f32 v[198:199], v[112:113], v[188:189], v[144:145] op_sel_hi:[1,0,1]
	v_lshl_add_u64 v[188:189], s[42:43], 0, v[224:225]
	v_lshl_add_u64 v[168:169], v[188:189], 0, v[168:169]
	global_store_dwordx4 v[202:203], v[198:201], off offset:528
	v_lshl_add_u64 v[168:169], v[168:169], 0, v[196:197]
	v_cndmask_b32_e64 v165, 0, v165, s[2:3]
	v_pk_fma_f32 v[200:201], v[110:111], v[162:163], v[154:155] op_sel_hi:[1,0,1]
	v_pk_fma_f32 v[198:199], v[108:109], v[162:163], v[152:153] op_sel_hi:[1,0,1]
	global_store_dwordx4 v[168:169], v[198:201], off
	v_cndmask_b32_e64 v164, v161, v164, s[2:3]
	v_cndmask_b32_e64 v224, v173, v175, s[2:3]
	v_pk_fma_f32 v[200:201], v[106:107], v[162:163], v[158:159] op_sel_hi:[1,0,1]
	v_pk_fma_f32 v[198:199], v[104:105], v[162:163], v[156:157] op_sel_hi:[1,0,1]
	global_store_dwordx4 v[168:169], v[198:201], off offset:16
	v_lshlrev_b64 v[164:165], 10, v[164:165]
	v_cmp_gt_i32_e64 s[2:3], s92, v160
	v_pk_fma_f32 v[200:201], v[102:103], v[162:163], v[150:151] op_sel_hi:[1,0,1]
	v_pk_fma_f32 v[198:199], v[100:101], v[162:163], v[148:149] op_sel_hi:[1,0,1]
	global_store_dwordx4 v[168:169], v[198:201], off offset:512
	v_add_u32_e32 v161, 0xffffc030, v160
	s_nop 0
	v_pk_fma_f32 v[200:201], v[98:99], v[162:163], v[146:147] op_sel_hi:[1,0,1]
	v_pk_fma_f32 v[198:199], v[96:97], v[162:163], v[144:145] op_sel_hi:[1,0,1]
	global_store_dwordx4 v[168:169], v[198:201], off offset:528
	v_lshl_add_u64 v[168:169], s[42:43], 0, v[224:225]
	v_lshl_add_u64 v[164:165], v[168:169], 0, v[164:165]
	v_lshl_add_u64 v[164:165], v[164:165], 0, v[196:197]
	v_pk_fma_f32 v[200:201], v[94:95], v[170:171], v[154:155] op_sel_hi:[1,0,1]
	v_pk_fma_f32 v[198:199], v[92:93], v[170:171], v[152:153] op_sel_hi:[1,0,1]
	global_store_dwordx4 v[164:165], v[198:201], off
	v_cndmask_b32_e64 v224, v173, v175, s[2:3]
	v_pk_fma_f32 v[154:155], v[78:79], v[174:175], v[154:155] op_sel_hi:[1,0,1]
	v_pk_fma_f32 v[200:201], v[90:91], v[170:171], v[158:159] op_sel_hi:[1,0,1]
	v_pk_fma_f32 v[198:199], v[88:89], v[170:171], v[156:157] op_sel_hi:[1,0,1]
	global_store_dwordx4 v[164:165], v[198:201], off offset:16
	v_pk_fma_f32 v[152:153], v[76:77], v[174:175], v[152:153] op_sel_hi:[1,0,1]
	s_nop 0
	v_pk_fma_f32 v[200:201], v[86:87], v[170:171], v[150:151] op_sel_hi:[1,0,1]
	v_pk_fma_f32 v[198:199], v[84:85], v[170:171], v[148:149] op_sel_hi:[1,0,1]
	global_store_dwordx4 v[164:165], v[198:201], off offset:512
	v_pk_fma_f32 v[150:151], v[70:71], v[174:175], v[150:151] op_sel_hi:[1,0,1]
	v_pk_fma_f32 v[148:149], v[68:69], v[174:175], v[148:149] op_sel_hi:[1,0,1]
	v_pk_fma_f32 v[200:201], v[82:83], v[170:171], v[146:147] op_sel_hi:[1,0,1]
	v_pk_fma_f32 v[198:199], v[80:81], v[170:171], v[144:145] op_sel_hi:[1,0,1]
	global_store_dwordx4 v[164:165], v[198:201], off offset:528
	v_cndmask_b32_e64 v165, 0, v167, s[2:3]
	v_cndmask_b32_e64 v164, v161, v166, s[2:3]
	v_lshl_add_u64 v[166:167], s[42:43], 0, v[224:225]
	v_lshlrev_b64 v[164:165], 10, v[164:165]
	v_lshl_add_u64 v[164:165], v[166:167], 0, v[164:165]
	v_lshl_add_u64 v[164:165], v[164:165], 0, v[196:197]
	v_pk_fma_f32 v[146:147], v[66:67], v[174:175], v[146:147] op_sel_hi:[1,0,1]
	v_pk_fma_f32 v[144:145], v[64:65], v[174:175], v[144:145] op_sel_hi:[1,0,1]
	global_store_dwordx4 v[164:165], v[144:147], off offset:528
	v_cndmask_b32_e32 v224, v173, v175, vcc
	global_store_dwordx4 v[164:165], v[152:155], off
	v_ashrrev_i32_e32 v144, 31, v163
	v_cndmask_b32_e32 v145, 0, v144, vcc
	v_cndmask_b32_e32 v144, v171, v163, vcc
	v_lshl_add_u64 v[146:147], s[42:43], 0, v[224:225]
	v_lshlrev_b64 v[144:145], 10, v[144:145]
	v_lshl_add_u64 v[144:145], v[146:147], 0, v[144:145]
	v_pk_fma_f32 v[154:155], v[74:75], v[174:175], v[158:159] op_sel_hi:[1,0,1]
	v_pk_fma_f32 v[152:153], v[72:73], v[174:175], v[156:157] op_sel_hi:[1,0,1]
	global_store_dwordx4 v[164:165], v[148:151], off offset:512
	s_waitcnt vmcnt(18)
	v_pk_fma_f32 v[146:147], v[62:63], v[190:191], v[142:143] op_sel_hi:[1,0,1]
	global_store_dwordx4 v[164:165], v[152:155], off offset:16
	v_lshl_add_u64 v[148:149], v[144:145], 0, v[196:197]
	v_pk_fma_f32 v[144:145], v[60:61], v[190:191], v[140:141] op_sel_hi:[1,0,1]
	global_store_dwordx4 v[148:149], v[144:147], off
	v_cmp_gt_i32_e32 vcc, s82, v163
	s_waitcnt vmcnt(19)
;     template <int PN> DI void body(AccRef acc, const Unit& u, int wr, int wc, int fr, int fq) const {
;     ...
;         for (int ai = 0; ai < 2; ++ai) {
;             const int rb = u.pm * 256 + ai * 128 + wr * 64 + fr;
;             int mb, pos0, kv0; row_info(rb, mb, pos0, kv0);
; #pragma unroll
;             for (int m = 0; m < 4; ++m) {
;                 const int row = rb + 16 * m, pos = pos0 + 16 * m, kvrow = kv0 + 16 * m;
;                 const float rinv = rinvh[ai][m];
;                 float v[2][8];
; #pragma unroll
;                 for (int bj = 0; bj < 2; ++bj)
; #pragma unroll
;                     for (int n = 0; n < 2; ++n)
; #pragma unroll
;                         for (int j = 0; j < 4; ++j) v[bj][4 * n + j] = acc[ai][bj][m][n][j] * rinv + cvh[ai][bj][n][j];
;     ...
;                 } else {
;                     float* lo = orow(out, l, row, PN == 8 ? O_PSK : O_PSV, PN == 8 ? O_SSK : O_SSV, 256);
; #pragma unroll
;                     for (int bj = 0; bj < 2; ++bj) {
;                         *(f32x4*)(lo + bj * 128 + cl) = (f32x4){v[bj][0], v[bj][1], v[bj][2], v[bj][3]};
;                         *(f32x4*)(lo + bj * 128 + cl + 4) = (f32x4){v[bj][4], v[bj][5], v[bj][6], v[bj][7]};
;                     }
	v_pk_fma_f32 v[146:147], v[58:59], v[190:191], v[138:139] op_sel_hi:[1,0,1]
	v_pk_fma_f32 v[144:145], v[56:57], v[190:191], v[136:137] op_sel_hi:[1,0,1]
	global_store_dwordx4 v[148:149], v[144:147], off offset:16
	v_cndmask_b32_e32 v224, v173, v175, vcc
	s_waitcnt vmcnt(18)
	v_pk_fma_f32 v[146:147], v[54:55], v[190:191], v[134:135] op_sel_hi:[1,0,1]
	v_pk_fma_f32 v[144:145], v[52:53], v[190:191], v[132:133] op_sel_hi:[1,0,1]
	global_store_dwordx4 v[148:149], v[144:147], off offset:512
	s_nop 1
	v_pk_fma_f32 v[146:147], v[50:51], v[190:191], v[130:131] op_sel_hi:[1,0,1]
	v_pk_fma_f32 v[144:145], v[48:49], v[190:191], v[128:129] op_sel_hi:[1,0,1]
	global_store_dwordx4 v[148:149], v[144:147], off offset:528
	s_nop 1
	v_add_u32_e32 v146, 0x90, v160
	v_add_u32_e32 v144, 0xffffc090, v160
	v_ashrrev_i32_e32 v145, 31, v146
	v_cndmask_b32_e32 v145, 0, v145, vcc
	v_cndmask_b32_e32 v144, v144, v146, vcc
	v_lshl_add_u64 v[146:147], s[42:43], 0, v[224:225]
	v_lshlrev_b64 v[144:145], 10, v[144:145]
	v_lshl_add_u64 v[144:145], v[146:147], 0, v[144:145]
	v_lshl_add_u64 v[148:149], v[144:145], 0, v[196:197]
	v_pk_fma_f32 v[146:147], v[46:47], v[172:173], v[142:143] op_sel_hi:[1,0,1]
	v_pk_fma_f32 v[144:145], v[44:45], v[172:173], v[140:141] op_sel_hi:[1,0,1]
	global_store_dwordx4 v[148:149], v[144:147], off
	v_cmp_gt_i32_e32 vcc, s83, v163
	s_nop 0
	v_pk_fma_f32 v[146:147], v[42:43], v[172:173], v[138:139] op_sel_hi:[1,0,1]
	v_pk_fma_f32 v[144:145], v[40:41], v[172:173], v[136:137] op_sel_hi:[1,0,1]
	global_store_dwordx4 v[148:149], v[144:147], off offset:16
	v_cndmask_b32_e32 v224, v173, v175, vcc
	s_nop 0
	v_pk_fma_f32 v[146:147], v[38:39], v[172:173], v[134:135] op_sel_hi:[1,0,1]
	v_pk_fma_f32 v[144:145], v[36:37], v[172:173], v[132:133] op_sel_hi:[1,0,1]
	global_store_dwordx4 v[148:149], v[144:147], off offset:512
	s_nop 1
	v_pk_fma_f32 v[146:147], v[30:31], v[172:173], v[130:131] op_sel_hi:[1,0,1]
	v_pk_fma_f32 v[144:145], v[28:29], v[172:173], v[128:129] op_sel_hi:[1,0,1]
	global_store_dwordx4 v[148:149], v[144:147], off offset:528
	s_nop 1
	v_add_u32_e32 v146, 0xa0, v160
	v_add_u32_e32 v144, 0xffffc0a0, v160
	v_ashrrev_i32_e32 v145, 31, v146
	v_cndmask_b32_e32 v145, 0, v145, vcc
	v_cndmask_b32_e32 v144, v144, v146, vcc
	v_lshl_add_u64 v[146:147], s[42:43], 0, v[224:225]
	v_lshlrev_b64 v[144:145], 10, v[144:145]
	v_lshl_add_u64 v[144:145], v[146:147], 0, v[144:145]
	v_lshl_add_u64 v[148:149], v[144:145], 0, v[196:197]
	v_pk_fma_f32 v[146:147], v[34:35], v[192:193], v[142:143] op_sel_hi:[1,0,1]
	v_pk_fma_f32 v[144:145], v[32:33], v[192:193], v[140:141] op_sel_hi:[1,0,1]
	global_store_dwordx4 v[148:149], v[144:147], off
	v_cmp_gt_i32_e32 vcc, s92, v163
	v_pk_fma_f32 v[142:143], v[14:15], v[194:195], v[142:143] op_sel_hi:[1,0,1]
	v_pk_fma_f32 v[146:147], v[26:27], v[192:193], v[138:139] op_sel_hi:[1,0,1]
	v_pk_fma_f32 v[144:145], v[24:25], v[192:193], v[136:137] op_sel_hi:[1,0,1]
	global_store_dwordx4 v[148:149], v[144:147], off offset:16
	v_cndmask_b32_e32 v224, v173, v175, vcc
	v_pk_fma_f32 v[140:141], v[12:13], v[194:195], v[140:141] op_sel_hi:[1,0,1]
	v_pk_fma_f32 v[146:147], v[22:23], v[192:193], v[134:135] op_sel_hi:[1,0,1]
	v_pk_fma_f32 v[144:145], v[20:21], v[192:193], v[132:133] op_sel_hi:[1,0,1]
	global_store_dwordx4 v[148:149], v[144:147], off offset:512
	v_pk_fma_f32 v[138:139], v[10:11], v[194:195], v[138:139] op_sel_hi:[1,0,1]
	v_pk_fma_f32 v[136:137], v[8:9], v[194:195], v[136:137] op_sel_hi:[1,0,1]
	v_pk_fma_f32 v[146:147], v[18:19], v[192:193], v[130:131] op_sel_hi:[1,0,1]
	v_pk_fma_f32 v[144:145], v[16:17], v[192:193], v[128:129] op_sel_hi:[1,0,1]
	global_store_dwordx4 v[148:149], v[144:147], off offset:528
	v_pk_fma_f32 v[134:135], v[6:7], v[194:195], v[134:135] op_sel_hi:[1,0,1]
	v_pk_fma_f32 v[132:133], v[4:5], v[194:195], v[132:133] op_sel_hi:[1,0,1]
	v_add_u32_e32 v146, 0xb0, v160
	v_add_u32_e32 v144, 0xffffc0b0, v160
	v_ashrrev_i32_e32 v145, 31, v146
	v_cndmask_b32_e32 v145, 0, v145, vcc
	v_cndmask_b32_e32 v144, v144, v146, vcc
	v_lshl_add_u64 v[146:147], s[42:43], 0, v[224:225]
	v_lshlrev_b64 v[144:145], 10, v[144:145]
	v_lshl_add_u64 v[144:145], v[146:147], 0, v[144:145]
	v_lshl_add_u64 v[144:145], v[144:145], 0, v[196:197]
	v_pk_fma_f32 v[130:131], v[2:3], v[194:195], v[130:131] op_sel_hi:[1,0,1]
	v_pk_fma_f32 v[128:129], v[0:1], v[194:195], v[128:129] op_sel_hi:[1,0,1]
	global_store_dwordx4 v[144:145], v[140:143], off
	global_store_dwordx4 v[144:145], v[136:139], off offset:16
	global_store_dwordx4 v[144:145], v[132:135], off offset:512
	global_store_dwordx4 v[144:145], v[128:131], off offset:528
	s_cbranch_execz .LBB0_440

; #define LAS __attribute__((address_space(3)))
; #define xor16_32(s) xor16_32_l((s), fr + 16 * fq)
;     template <int PN> DI void body(AccRef acc, const Unit& u, int wr, int wc, int fr, int fq) const {
;     ...
;         float rinvh[2][4];
;         f32x4 cvh[2][2][2];
;         int zdep = 0;
; #pragma unroll
;         for (int ai = 0; ai < 2; ++ai) {
;             const int rb_ = u.pm * 256 + ai * 128 + wr * 64 + fr;
; #pragma unroll
;             for (int m = 0; m < 4; ++m) rinvh[ai][m] = rsqrtf(sum16(ssq + (size_t)(rb_ + 16 * m + zdep) * 16) * (1.f / 1024.f) + EPS);
;             asm volatile("v_mov_b32 %0, 0" : "=v"(zdep) : "v"(rinvh[ai][0]), "v"(rinvh[ai][1]), "v"(rinvh[ai][2]), "v"(rinvh[ai][3]));
;         }
; #pragma unroll
;         for (int ai = 0; ai < 2; ++ai) {
;             const int rb_ = u.pm * 256 + ai * 128 + wr * 64 + fr;
;             int mb_, p_, k_; row_info(rb_, mb_, p_, k_);
; #pragma unroll
;             for (int bj = 0; bj < 2; ++bj)
; #pragma unroll
;                 for (int n = 0; n < 2; ++n) cvh[ai][bj][n] = *(const f32x4*)(cv + (size_t)(mb_ + zdep) * NIN + PN * 256 + bj * 128 + cl + 4 * n);
;         }
; #pragma unroll
;         for (int ai = 0; ai < 2; ++ai) {
;             const int rb = u.pm * 256 + ai * 128 + wr * 64 + fr;
;             int mb, pos0, kv0; row_info(rb, mb, pos0, kv0);
; #pragma unroll
;             for (int m = 0; m < 4; ++m) {
;                 const int row = rb + 16 * m, pos = pos0 + 16 * m, kvrow = kv0 + 16 * m;
;                 const float rinv = rinvh[ai][m];
;                 float v[2][8];
; #pragma unroll
;                 for (int bj = 0; bj < 2; ++bj)
; #pragma unroll
;                     for (int n = 0; n < 2; ++n)
; #pragma unroll
;                         for (int j = 0; j < 4; ++j) v[bj][4 * n + j] = acc[ai][bj][m][n][j] * rinv + cvh[ai][bj][n][j];
;                 if constexpr (PN == 0) {
;                     float s = 0.f;
; #pragma unroll
;                     for (int bj = 0; bj < 2; ++bj) {
;                         *(u32x4*)(zkv + (size_t)row * 256 + bj * 128 + cl) = pack8(v[bj]);
; #pragma unroll
;                         for (int j = 0; j < 8; ++j) s += v[bj][j] * v[bj][j];
;                     }
;                     s = xor16_32(s);
;                     if (fq == 0) { ssqkv[(size_t)row * 4 + wc] = s; *(LAS float*)(xl + ((ai * 128 + wr * 64 + 16 * m + fr) * 4 + wc) * 4) = s; }
.LBB0_440:
	v_lshl_add_u32 v164, s53, 6, v214
	s_lshl_b32 s4, s34, 8
	v_add_u32_e32 v192, s4, v164
	v_ashrrev_i32_e32 v193, 31, v192
	v_lshlrev_b64 v[128:129], 6, v[192:193]
	v_lshl_add_u64 v[140:141], s[56:57], 0, v[128:129]
	s_waitcnt lgkmcnt(0)
	s_nop 0
	v_add_u32_e32 v206, 16, v192
	v_ashrrev_i32_e32 v207, 31, v206
	s_mov_b32 s2, 0x358637bd
	s_mov_b32 s6, 0x3a800000
	v_add_u32_e32 v202, 32, v192
	v_ashrrev_i32_e32 v203, 31, v202
	v_add_u32_e32 v194, 48, v192
	v_ashrrev_i32_e32 v195, 31, v194
	v_add_u32_e32 v191, 0x80, v164
	v_add_u32_e32 v188, s4, v191
	v_add_u32_e32 v199, 0xffffc000, v192
	v_lshlrev_b64 v[168:169], 9, v[192:193]
	v_lshlrev_b32_e32 v165, 2, v214
	v_lshl_add_u32 v165, v213, 6, v165
	v_xor_b32_e32 v166, 64, v165
	v_xor_b32_e32 v165, 0x80, v165
	s_ashr_i32 s67, s66, 31
	v_cmp_eq_u32_e64 s[4:5], 0, v213
	s_nop 0
	v_lshlrev_b64 v[128:129], 6, v[206:207]
	v_lshl_add_u64 v[140:141], s[56:57], 0, v[128:129]
	s_nop 0
	s_nop 0
	v_mov_b64_e32 v[128:129], s[2:3]
	s_nop 0
	s_nop 0
	s_nop 0
	v_mov_b32_e32 v212, v244
	s_nop 0
	v_mov_b32_e32 v196, v245
	v_lshlrev_b64 v[130:131], 6, v[202:203]
	v_lshl_add_u64 v[142:143], s[56:57], 0, v[130:131]
	s_nop 0
	s_nop 0
	v_lshlrev_b64 v[130:131], 6, v[194:195]
	v_lshl_add_u64 v[142:143], s[56:57], 0, v[130:131]
	s_nop 0
	s_nop 0
	s_nop 0
	s_nop 0
	s_nop 0
	s_nop 0
	v_mov_b32_e32 v208, v246
	s_nop 0
	v_mov_b32_e32 v200, v247
	v_mov_b32 v130, 0
	s_nop 0
	v_add_u32_e32 v130, v130, v188
	v_ashrrev_i32_e32 v131, 31, v130
	v_lshlrev_b64 v[132:133], 6, v[130:131]
	v_lshl_add_u64 v[144:145], s[56:57], 0, v[132:133]
	s_nop 0
	s_nop 0
	v_add_u32_e32 v132, 16, v130
	v_ashrrev_i32_e32 v133, 31, v132
	v_lshlrev_b64 v[132:133], 6, v[132:133]
	v_lshl_add_u64 v[144:145], s[56:57], 0, v[132:133]
	s_nop 0
	s_nop 0
	s_nop 0
	s_nop 0
	s_nop 0
	s_nop 0
	v_mov_b32_e32 v204, v248
	s_nop 0
	v_mov_b32_e32 v198, v249
	v_add_u32_e32 v132, 32, v130
	v_ashrrev_i32_e32 v133, 31, v132
	v_lshlrev_b64 v[132:133], 6, v[132:133]
	v_lshl_add_u64 v[144:145], s[56:57], 0, v[132:133]
	s_nop 0
	v_add_u32_e32 v130, 48, v130
	v_ashrrev_i32_e32 v131, 31, v130
	v_lshlrev_b64 v[130:131], 6, v[130:131]
	v_lshl_add_u64 v[142:143], s[56:57], 0, v[130:131]
	s_nop 0
	s_nop 0
	s_nop 0
	v_lshrrev_b32_e32 v131, 6, v199
	v_add_u32_e32 v131, 8, v131
	s_lshl_b64 s[6:7], s[66:67], 2
	v_mov_b32_e32 v210, v250
	s_lshl_b32 s2, s66, 5
	v_lshl_add_u32 v160, v213, 3, s2
	v_ashrrev_i32_e32 v130, 11, v192
	v_mov_b32_e32 v190, v251
	v_cmp_gt_i32_e32 vcc, s94, v192
	v_ashrrev_i32_e32 v161, 31, v160
	v_mov_b32 v132, 0
	v_lshl_add_u64 v[128:129], v[160:161], 2, s[74:75]
	v_cndmask_b32_e32 v130, v131, v130, vcc
	v_add_u32_e32 v130, v132, v130
	v_mad_i64_i32 v[130:131], s[2:3], v130, s51, v[128:129]
	global_load_dwordx4 v[148:151], v[130:131], off offset:16
	global_load_dwordx4 v[156:159], v[130:131], off
	global_load_dwordx4 v[144:147], v[130:131], off offset:528
	global_load_dwordx4 v[152:155], v[130:131], off offset:512
	v_add_u32_e32 v131, 0xffffc080, v192
	v_add_u32_e32 v130, 0x80, v192
	v_lshrrev_b32_e32 v131, 6, v131
	v_cmp_gt_i32_e64 s[2:3], s94, v130
	v_ashrrev_i32_e32 v130, 11, v130
	v_add_u32_e32 v131, 8, v131
	v_cndmask_b32_e64 v130, v131, v130, s[2:3]
	v_add_u32_e32 v130, v132, v130
	v_mad_i64_i32 v[132:133], s[2:3], v130, s51, v[128:129]
	global_load_dwordx4 v[136:139], v[132:133], off offset:16
	global_load_dwordx4 v[140:143], v[132:133], off
	global_load_dwordx4 v[128:131], v[132:133], off offset:528
	s_nop 0
	global_load_dwordx4 v[132:135], v[132:133], off offset:512
	v_lshl_add_u64 v[162:163], v[160:161], 1, s[70:71]
	v_lshl_add_u64 v[230:231], v[162:163], 0, v[168:169]
	s_add_u32 s6, s45, s6
	v_cmp_ne_u32_e64 s[2:3], 0, v213
	s_addc_u32 s7, s46, s7
	s_lshl_b32 s12, s66, 2
	s_waitcnt vmcnt(7)
	v_pk_fma_f32 v[214:215], v[120:121], v[212:213], v[148:149] op_sel_hi:[1,0,1]
	s_waitcnt vmcnt(6)
	v_pk_fma_f32 v[172:173], v[124:125], v[212:213], v[156:157] op_sel_hi:[1,0,1]
	v_pk_fma_f32 v[174:175], v[126:127], v[212:213], v[158:159] op_sel_hi:[1,0,1]
	v_cvt_pk_bf16_f32 v168, v172, v173
	v_pk_mul_f32 v[172:173], v[172:173], v[172:173]
	v_cvt_pk_bf16_f32 v169, v174, v175
	v_pk_mul_f32 v[174:175], v[174:175], v[174:175]
	v_add_f32_e32 v167, v172, v173
	v_add_f32_e32 v167, v174, v167
	v_cvt_pk_bf16_f32 v170, v214, v215
	v_pk_mul_f32 v[214:215], v[214:215], v[214:215]
	v_add_f32_e32 v167, v175, v167
	v_pk_fma_f32 v[216:217], v[122:123], v[212:213], v[150:151] op_sel_hi:[1,0,1]
	v_add_f32_e32 v167, v214, v167
	s_waitcnt vmcnt(4)
	v_pk_fma_f32 v[218:219], v[116:117], v[212:213], v[152:153] op_sel_hi:[1,0,1]
	v_pk_fma_f32 v[220:221], v[118:119], v[212:213], v[154:155] op_sel_hi:[1,0,1]
	v_pk_fma_f32 v[222:223], v[112:113], v[212:213], v[144:145] op_sel_hi:[1,0,1]
	v_pk_fma_f32 v[228:229], v[114:115], v[212:213], v[146:147] op_sel_hi:[1,0,1]
	v_cvt_pk_bf16_f32 v171, v216, v217
	v_pk_mul_f32 v[216:217], v[216:217], v[216:217]
	v_add_f32_e32 v167, v215, v167
	global_store_dwordx4 v[230:231], v[168:171], off
	v_add_f32_e32 v167, v216, v167
	v_add_f32_e32 v167, v217, v167
	v_cvt_pk_bf16_f32 v168, v218, v219
	v_cvt_pk_bf16_f32 v169, v220, v221
	v_cvt_pk_bf16_f32 v170, v222, v223
	v_cvt_pk_bf16_f32 v171, v228, v229
	global_store_dwordx4 v[230:231], v[168:171], off offset:256
	s_nop 1
	v_pk_mul_f32 v[168:169], v[218:219], v[218:219]
	v_pk_mul_f32 v[170:171], v[220:221], v[220:221]
	v_add_f32_e32 v167, v168, v167
	v_add_f32_e32 v167, v169, v167
	v_add_f32_e32 v167, v170, v167
	v_pk_mul_f32 v[218:219], v[222:223], v[222:223]
	v_add_f32_e32 v167, v171, v167
	v_add_f32_e32 v167, v218, v167
	v_pk_mul_f32 v[220:221], v[228:229], v[228:229]
	v_add_f32_e32 v167, v219, v167
	v_add_f32_e32 v167, v220, v167
	v_add_f32_e32 v167, v221, v167
	ds_bpermute_b32 v168, v166, v167
	s_waitcnt lgkmcnt(0)
	v_add_f32_e32 v167, v167, v168
	ds_bpermute_b32 v168, v165, v167
	s_and_saveexec_b64 s[8:9], s[4:5]
	s_cbranch_execz .LBB0_442
	s_add_i32 s13, s12, 0
	v_lshl_add_u32 v169, v164, 4, s13
	v_add_u32_e32 v169, 0x20000, v169
	v_lshl_add_u64 v[170:171], v[192:193], 4, s[6:7]
	s_waitcnt lgkmcnt(0)
	v_add_f32_e32 v167, v167, v168
	global_store_dword v[170:171], v167, off
	ds_write_b32 v169, v167

; DI float sum16(const float* p) { const f32x4* q = (const f32x4*)p; f32x4 a = q[0], b = q[1], c = q[2], d = q[3]; f32x4 s = (a + b) + (c + d); return (s[0] + s[1]) + (s[2] + s[3]); }
;     template <int PN> DI void body(AccRef acc, const Unit& u, int wr, int wc, int fr, int fq) const {
;     ...
;         float rinvh[2][4];
;         f32x4 cvh[2][2][2];
;         int zdep = 0;
; #pragma unroll
;         for (int ai = 0; ai < 2; ++ai) {
;             const int rb_ = u.pm * 256 + ai * 128 + wr * 64 + fr;
; #pragma unroll
;             for (int m = 0; m < 4; ++m) rinvh[ai][m] = rsqrtf(sum16(ssq + (size_t)(rb_ + 16 * m + zdep) * 16) * (1.f / 1024.f) + EPS);
;             asm volatile("v_mov_b32 %0, 0" : "=v"(zdep) : "v"(rinvh[ai][0]), "v"(rinvh[ai][1]), "v"(rinvh[ai][2]), "v"(rinvh[ai][3]));
;         }
;     DI void operator()(AccRef acc, const Unit& u, int wr, int wc, int fr, int fq) const {
;         switch (u.pn) {
;             case 0: body<0>(acc, u, wr, wc, fr, fq); break;
;             case 1: body<1>(acc, u, wr, wc, fr, fq); break;
;             case 2: body<2>(acc, u, wr, wc, fr, fq); break;
;             case 3: body<3>(acc, u, wr, wc, fr, fq); break;
;             case 4: body<4>(acc, u, wr, wc, fr, fq); break;
;             case 5: body<5>(acc, u, wr, wc, fr, fq); break;
;             case 6: body<6>(acc, u, wr, wc, fr, fq); break;
;             case 7: body<7>(acc, u, wr, wc, fr, fq); break;
;             case 8: body<8>(acc, u, wr, wc, fr, fq); break;
;             default: body<9>(acc, u, wr, wc, fr, fq); break;
;         }
.LBB0_1709:
	v_readlane_b32 s4, v253, 32
	v_mbcnt_lo_u32_b32 v128, -1, 0
	v_mbcnt_hi_u32_b32 v128, -1, v128
	s_mov_b32 s54, s39
	v_and_b32_e32 v214, 15, v128
	v_bfe_u32 v213, v128, 4, 2
	s_mov_b32 s43, s29
	s_lshl_b32 s22, s43, 6
	s_lshl_b32 s23, s34, 8
	s_add_i32 s22, s22, s23
	v_add_u32_e32 v244, s22, v214
	v_lshlrev_b32_e32 v244, 6, v244
	v_lshl_add_u32 v244, v213, 4, v244
	global_load_dwordx4 v[228:231], v244, s[70:71]
	global_load_dwordx4 v[232:235], v244, s[70:71] offset:1024
	global_load_dwordx4 v[236:239], v244, s[70:71] offset:2048
	global_load_dwordx4 v[240:243], v244, s[70:71] offset:3072
	v_add_u32_e32 v244, 0x2000, v244
	global_load_dwordx4 v[216:219], v244, s[70:71]
	global_load_dwordx4 v[220:223], v244, s[70:71] offset:1024
	global_load_dwordx4 v[142:145], v244, s[70:71] offset:2048
	global_load_dwordx4 v[146:149], v244, s[70:71] offset:3072
	v_mov_b32_e32 v245, 0x3a800000
	s_waitcnt vmcnt(4)
	v_pk_add_f32 v[228:229], v[228:229], v[230:231]
	v_pk_add_f32 v[232:233], v[232:233], v[234:235]
	v_pk_add_f32 v[236:237], v[236:237], v[238:239]
	v_pk_add_f32 v[240:241], v[240:241], v[242:243]
	v_add_f32_e32 v228, v228, v229
	v_add_f32_e32 v232, v232, v233
	v_add_f32_e32 v236, v236, v237
	v_add_f32_e32 v240, v240, v241
	v_mov_b32_e32 v229, v228
	v_mov_b32_e32 v233, v232
	v_mov_b32_e32 v237, v236
	v_mov_b32_e32 v241, v240
	s_waitcnt vmcnt(0)
	v_pk_add_f32 v[216:217], v[216:217], v[218:219]
	v_pk_add_f32 v[220:221], v[220:221], v[222:223]
	v_pk_add_f32 v[142:143], v[142:143], v[144:145]
	v_pk_add_f32 v[146:147], v[146:147], v[148:149]
	v_add_f32_e32 v216, v216, v217
	v_add_f32_e32 v220, v220, v221
	v_add_f32_e32 v142, v142, v143
	v_add_f32_e32 v146, v146, v147
	v_mov_b32_e32 v217, v216
	v_mov_b32_e32 v221, v220
	v_mov_b32_e32 v143, v142
	v_mov_b32_e32 v147, v146
	s_nop 1
	v_permlane32_swap_b32_e32 v228, v229
	v_permlane32_swap_b32_e32 v232, v233
	v_permlane32_swap_b32_e32 v236, v237
	v_permlane32_swap_b32_e32 v240, v241
	v_permlane32_swap_b32_e32 v216, v217
	v_permlane32_swap_b32_e32 v220, v221
	v_permlane32_swap_b32_e32 v142, v143
	v_permlane32_swap_b32_e32 v146, v147
	v_add_f32_e32 v228, v228, v229
	v_add_f32_e32 v232, v232, v233
	v_add_f32_e32 v236, v236, v237
	v_add_f32_e32 v240, v240, v241
	v_add_f32_e32 v216, v216, v217
	v_add_f32_e32 v220, v220, v221
	v_add_f32_e32 v142, v142, v143
	v_add_f32_e32 v146, v146, v147
	v_mov_b32_e32 v229, v228
	v_mov_b32_e32 v233, v232
	v_mov_b32_e32 v237, v236
	v_mov_b32_e32 v241, v240
	v_mov_b32_e32 v217, v216
	v_mov_b32_e32 v221, v220
	v_mov_b32_e32 v143, v142
	v_mov_b32_e32 v147, v146
	s_nop 1
	v_permlane16_swap_b32_e32 v228, v229
	v_permlane16_swap_b32_e32 v232, v233
	v_permlane16_swap_b32_e32 v236, v237
	v_permlane16_swap_b32_e32 v240, v241
	v_permlane16_swap_b32_e32 v216, v217
	v_permlane16_swap_b32_e32 v220, v221
	v_permlane16_swap_b32_e32 v142, v143
	v_permlane16_swap_b32_e32 v146, v147
	v_add_f32_e32 v228, v228, v229
	v_add_f32_e32 v232, v232, v233
	v_add_f32_e32 v236, v236, v237
	v_add_f32_e32 v240, v240, v241
	v_add_f32_e32 v216, v216, v217
	v_add_f32_e32 v220, v220, v221
	v_add_f32_e32 v142, v142, v143
	v_add_f32_e32 v146, v146, v147
	v_fmaak_f32 v228, v245, v228, 0x358637bd
	v_fmaak_f32 v232, v245, v232, 0x358637bd
	v_fmaak_f32 v236, v245, v236, 0x358637bd
	v_fmaak_f32 v240, v245, v240, 0x358637bd
	v_fmaak_f32 v216, v245, v216, 0x358637bd
	v_fmaak_f32 v220, v245, v220, 0x358637bd
	v_fmaak_f32 v142, v245, v142, 0x358637bd
	v_fmaak_f32 v146, v245, v146, 0x358637bd
	v_rsq_f32_e32 v244, v228
	v_rsq_f32_e32 v245, v232
	v_rsq_f32_e32 v246, v236
	v_rsq_f32_e32 v247, v240
	v_rsq_f32_e32 v248, v216
	v_rsq_f32_e32 v249, v220
	v_rsq_f32_e32 v250, v142
	v_rsq_f32_e32 v251, v146
	s_mov_b64 s[4:5], -1
	s_mov_b64 s[10:11], 0
	s_cmp_lt_i32 s66, 4
	s_mov_b64 s[80:81], 0
	s_cbranch_scc1 .LBB0_1744
	s_cmp_gt_i32 s66, 5
	s_cbranch_scc0 .LBB0_1738
	s_cmp_gt_i32 s66, 6
	s_cbranch_scc0 .LBB0_1735
	s_cmp_gt_i32 s66, 7
	s_cbranch_scc0 .LBB0_1732
	s_cmp_eq_u32 s66, 8
	s_mov_b64 s[80:81], -1
	s_cbranch_scc0 .LBB0_1731
	s_lshl_b32 s4, s43, 6
	s_lshl_b32 s5, s34, 8
	s_add_i32 s4, s4, s5
	v_add_u32_e32 v160, s4, v214
	v_ashrrev_i32_e32 v161, 31, v160
	v_lshlrev_b64 v[128:129], 6, v[160:161]
	v_lshl_add_u64 v[140:141], s[70:71], 0, v[128:129]
	s_nop 0
	v_add_u32_e32 v190, 16, v160
	v_ashrrev_i32_e32 v191, 31, v190
	s_mov_b32 s4, 0x358637bd
	s_mov_b32 s6, 0x3a800000
	v_add_u32_e32 v166, 32, v160
	v_ashrrev_i32_e32 v167, 31, v166
	v_add_u32_e32 v168, 48, v160
	v_ashrrev_i32_e32 v169, 31, v168
	v_add_u32_e32 v164, 0x80, v160
	s_movk_i32 s8, 0x2800
	s_mov_b64 s[12:13], 0x126000
	s_mov_b32 s9, 0x126000
	v_add_u32_e32 v163, 0xffffc080, v160
	v_mov_b32_e32 v165, 0xffffc400
	v_mov_b32_e32 v171, 0x4000
	s_nop 0
	v_lshlrev_b64 v[128:129], 6, v[190:191]
	v_lshl_add_u64 v[140:141], s[70:71], 0, v[128:129]
	s_nop 0
	s_nop 0
	v_mov_b64_e32 v[128:129], s[4:5]
	s_nop 0
	s_nop 0
	s_nop 0
	v_mov_b32_e32 v192, v244
	s_nop 0
	v_mov_b32_e32 v162, v245
	v_lshlrev_b64 v[130:131], 6, v[166:167]
	v_lshl_add_u64 v[142:143], s[70:71], 0, v[130:131]
	s_nop 0
	s_nop 0
	v_lshlrev_b64 v[130:131], 6, v[168:169]
	v_lshl_add_u64 v[142:143], s[70:71], 0, v[130:131]
	s_nop 0
	s_nop 0
	s_nop 0
	s_nop 0
	s_nop 0
	s_nop 0
	v_mov_b32_e32 v172, v246
	s_nop 0
	v_mov_b32_e32 v188, v247
	v_mov_b32 v130, 0
	s_nop 0
	v_add_u32_e32 v130, v130, v164
	v_ashrrev_i32_e32 v131, 31, v130
	v_lshlrev_b64 v[132:133], 6, v[130:131]
	v_lshl_add_u64 v[144:145], s[70:71], 0, v[132:133]
	s_nop 0
	s_nop 0
	v_add_u32_e32 v132, 16, v130
	v_ashrrev_i32_e32 v133, 31, v132
	v_lshlrev_b64 v[132:133], 6, v[132:133]
	v_lshl_add_u64 v[144:145], s[70:71], 0, v[132:133]
	s_nop 0
;     template <int PN> DI void body(AccRef acc, const Unit& u, int wr, int wc, int fr, int fq) const {
;     ...
;         for (int ai = 0; ai < 2; ++ai) {
;             const int rb_ = u.pm * 256 + ai * 128 + wr * 64 + fr;
;             int mb_, p_, k_; row_info(rb_, mb_, p_, k_);
; #pragma unroll
;             for (int bj = 0; bj < 2; ++bj)
; #pragma unroll
;                 for (int n = 0; n < 2; ++n) cvh[ai][bj][n] = *(const f32x4*)(cv + (size_t)(mb_ + zdep) * NIN + PN * 256 + bj * 128 + cl + 4 * n);
;         }
; #pragma unroll
;         for (int ai = 0; ai < 2; ++ai) {
;             const int rb = u.pm * 256 + ai * 128 + wr * 64 + fr;
;             int mb, pos0, kv0; row_info(rb, mb, pos0, kv0);
; #pragma unroll
;             for (int m = 0; m < 4; ++m) {
;                 const int row = rb + 16 * m, pos = pos0 + 16 * m, kvrow = kv0 + 16 * m;
;                 const float rinv = rinvh[ai][m];
;                 float v[2][8];
; #pragma unroll
;                 for (int bj = 0; bj < 2; ++bj)
; #pragma unroll
;                     for (int n = 0; n < 2; ++n)
; #pragma unroll
;                         for (int j = 0; j < 4; ++j) v[bj][4 * n + j] = acc[ai][bj][m][n][j] * rinv + cvh[ai][bj][n][j];
;     ...
;                 } else {
;                     float* lo = orow(out, l, row, PN == 8 ? O_PSK : O_PSV, PN == 8 ? O_SSK : O_SSV, 256);
; #pragma unroll
;                     for (int bj = 0; bj < 2; ++bj) {
;                         *(f32x4*)(lo + bj * 128 + cl) = (f32x4){v[bj][0], v[bj][1], v[bj][2], v[bj][3]};
;                         *(f32x4*)(lo + bj * 128 + cl + 4) = (f32x4){v[bj][4], v[bj][5], v[bj][6], v[bj][7]};
;                     }
	s_nop 0
	s_nop 0
	s_nop 0
	s_nop 0
	s_nop 0
	v_mov_b32_e32 v174, v248
	s_nop 0
	v_mov_b32_e32 v170, v249
	v_add_u32_e32 v132, 32, v130
	v_ashrrev_i32_e32 v133, 31, v132
	v_lshlrev_b64 v[132:133], 6, v[132:133]
	v_lshl_add_u64 v[144:145], s[70:71], 0, v[132:133]
	s_nop 0
	v_add_u32_e32 v130, 48, v130
	v_ashrrev_i32_e32 v131, 31, v130
	v_lshlrev_b64 v[130:131], 6, v[130:131]
	v_lshl_add_u64 v[142:143], s[70:71], 0, v[130:131]
	s_nop 0
	s_nop 0
	s_nop 0
	s_nop 0
	s_nop 0
	s_nop 0
	v_mov_b32_e32 v196, v250
	s_lshl_b32 s4, s54, 5
	v_lshl_add_u32 v198, v213, 3, s4
	v_cmp_gt_i32_e64 s[4:5], s94, v160
	v_mov_b32_e32 v194, v251
	v_add_u32_e32 v129, 0xffffc000, v160
	v_lshrrev_b32_e32 v129, 6, v129
	v_ashrrev_i32_e32 v128, 11, v160
	v_add_u32_e32 v129, 8, v129
	v_cndmask_b32_e64 v128, v129, v128, s[4:5]
	v_mov_b32 v134, 0
	v_ashrrev_i32_e32 v199, 31, v198
	v_add_u32_e32 v130, v134, v128
	v_mov_b64_e32 v[128:129], s[60:61]
	v_mad_i64_i32 v[130:131], s[6:7], v130, s8, v[128:129]
	v_lshlrev_b64 v[200:201], 2, v[198:199]
	v_lshl_add_u64 v[130:131], v[130:131], 0, v[200:201]
	v_lshl_add_u64 v[132:133], v[130:131], 0, s[12:13]
	v_add_co_u32_e32 v130, vcc, s9, v130
	s_movk_i32 s6, 0x3fff
	s_nop 0
	v_addc_co_u32_e32 v131, vcc, 0, v131, vcc
	global_load_dwordx4 v[152:155], v[130:131], off
	global_load_dwordx4 v[156:159], v[132:133], off offset:16
	global_load_dwordx4 v[144:147], v[132:133], off offset:528
	global_load_dwordx4 v[148:151], v[132:133], off offset:512
	v_lshrrev_b32_e32 v131, 6, v163
	v_cmp_lt_i32_e32 vcc, s6, v164
	v_cmp_gt_i32_e64 s[6:7], s94, v164
	v_ashrrev_i32_e32 v130, 11, v164
	v_add_u32_e32 v131, 8, v131
	v_cndmask_b32_e64 v130, v131, v130, s[6:7]
	v_add_u32_e32 v130, v134, v130
	v_mad_i64_i32 v[128:129], s[6:7], v130, s8, v[128:129]
	v_lshl_add_u64 v[128:129], v[128:129], 0, v[200:201]
	v_lshl_add_u64 v[132:133], v[128:129], 0, s[12:13]
	v_add_co_u32_e64 v128, s[6:7], s9, v128
	v_cndmask_b32_e64 v203, -1, 0, s[4:5]
	s_nop 0
	v_addc_co_u32_e64 v129, s[6:7], 0, v129, s[6:7]
	global_load_dwordx4 v[140:143], v[128:129], off
	global_load_dwordx4 v[136:139], v[132:133], off offset:16
	s_nop 0
	global_load_dwordx4 v[128:131], v[132:133], off offset:528
	s_nop 0
	global_load_dwordx4 v[132:135], v[132:133], off offset:512
	v_cndmask_b32_e64 v202, v165, v171, s[4:5]
	v_mov_b32_e32 v165, 0xab98000
	v_mov_b32_e32 v171, 0x6800000
	v_lshl_add_u64 v[202:203], v[202:203], 0, v[160:161]
	v_cndmask_b32_e64 v224, v165, v171, s[4:5]
	v_lshl_add_u64 v[204:205], s[84:85], 0, v[224:225]
	v_lshlrev_b64 v[202:203], 10, v[202:203]
	v_lshl_add_u64 v[202:203], v[204:205], 0, v[202:203]
	v_lshl_add_u64 v[206:207], v[202:203], 0, v[200:201]
	s_movk_i32 s6, 0xc410
	v_mov_b32_e32 v224, v160
	s_mov_b32 s7, -1
	v_cmp_gt_i32_e64 s[4:5], s82, v160
	s_movk_i32 s8, 0xc420
	s_mov_b32 s9, -1
	s_waitcnt vmcnt(7)
	v_pk_fma_f32 v[204:205], v[126:127], v[192:193], v[154:155] op_sel_hi:[1,0,1]
	v_pk_fma_f32 v[202:203], v[124:125], v[192:193], v[152:153] op_sel_hi:[1,0,1]
	global_store_dwordx4 v[206:207], v[202:205], off
	s_waitcnt vmcnt(7)
	s_nop 0
	v_pk_fma_f32 v[204:205], v[122:123], v[192:193], v[158:159] op_sel_hi:[1,0,1]
	v_pk_fma_f32 v[202:203], v[120:121], v[192:193], v[156:157] op_sel_hi:[1,0,1]
	global_store_dwordx4 v[206:207], v[202:205], off offset:16
	s_waitcnt vmcnt(6)
	s_nop 0
	v_pk_fma_f32 v[204:205], v[118:119], v[192:193], v[150:151] op_sel_hi:[1,0,1]
	v_pk_fma_f32 v[202:203], v[116:117], v[192:193], v[148:149] op_sel_hi:[1,0,1]
	global_store_dwordx4 v[206:207], v[202:205], off offset:512
	s_nop 1
	v_pk_fma_f32 v[204:205], v[114:115], v[192:193], v[146:147] op_sel_hi:[1,0,1]
	v_pk_fma_f32 v[202:203], v[112:113], v[192:193], v[144:145] op_sel_hi:[1,0,1]
	v_lshl_add_u64 v[192:193], v[224:225], 0, s[6:7]
	s_mov_b64 s[6:7], 0x4000
	v_lshl_add_u64 v[190:191], v[190:191], 0, s[6:7]
	v_cndmask_b32_e64 v191, v193, v191, s[4:5]
	v_cndmask_b32_e64 v190, v192, v190, s[4:5]
	v_cndmask_b32_e64 v192, v165, v171, s[4:5]
	v_mov_b32_e32 v193, v225
	v_lshl_add_u64 v[192:193], s[84:85], 0, v[192:193]
	v_lshlrev_b64 v[190:191], 10, v[190:191]
	v_lshl_add_u64 v[190:191], v[192:193], 0, v[190:191]
	global_store_dwordx4 v[206:207], v[202:205], off offset:528
	v_pk_fma_f32 v[192:193], v[110:111], v[162:163], v[154:155] op_sel_hi:[1,0,1]
	v_cmp_gt_i32_e64 s[4:5], s83, v160
	v_lshl_add_u64 v[202:203], v[190:191], 0, v[200:201]
	v_pk_fma_f32 v[190:191], v[108:109], v[162:163], v[152:153] op_sel_hi:[1,0,1]
	global_store_dwordx4 v[202:203], v[190:193], off
	v_lshl_add_u64 v[166:167], v[166:167], 0, s[6:7]
	s_nop 0
	v_pk_fma_f32 v[192:193], v[106:107], v[162:163], v[158:159] op_sel_hi:[1,0,1]
	v_pk_fma_f32 v[190:191], v[104:105], v[162:163], v[156:157] op_sel_hi:[1,0,1]
	global_store_dwordx4 v[202:203], v[190:193], off offset:16
	s_nop 1
	v_pk_fma_f32 v[192:193], v[102:103], v[162:163], v[150:151] op_sel_hi:[1,0,1]
	v_pk_fma_f32 v[190:191], v[100:101], v[162:163], v[148:149] op_sel_hi:[1,0,1]
	global_store_dwordx4 v[202:203], v[190:193], off offset:512
	s_nop 1
	v_pk_fma_f32 v[192:193], v[98:99], v[162:163], v[146:147] op_sel_hi:[1,0,1]
	v_pk_fma_f32 v[190:191], v[96:97], v[162:163], v[144:145] op_sel_hi:[1,0,1]
	global_store_dwordx4 v[202:203], v[190:193], off offset:528
	s_nop 1
	v_lshl_add_u64 v[190:191], v[224:225], 0, s[8:9]
	v_cndmask_b32_e64 v167, v191, v167, s[4:5]
	v_cndmask_b32_e64 v166, v190, v166, s[4:5]
	v_cndmask_b32_e64 v190, v165, v171, s[4:5]
	v_mov_b32_e32 v191, v225
	v_lshl_add_u64 v[190:191], s[84:85], 0, v[190:191]
	v_lshlrev_b64 v[166:167], 10, v[166:167]
	v_lshl_add_u64 v[166:167], v[190:191], 0, v[166:167]
	v_lshl_add_u64 v[166:167], v[166:167], 0, v[200:201]
;     template <int PN> DI void body(AccRef acc, const Unit& u, int wr, int wc, int fr, int fq) const {
;     ...
;                 } else {
;                     float* lo = orow(out, l, row, PN == 8 ? O_PSK : O_PSV, PN == 8 ? O_SSK : O_SSV, 256);
; #pragma unroll
;                     for (int bj = 0; bj < 2; ++bj) {
;                         *(f32x4*)(lo + bj * 128 + cl) = (f32x4){v[bj][0], v[bj][1], v[bj][2], v[bj][3]};
;                         *(f32x4*)(lo + bj * 128 + cl + 4) = (f32x4){v[bj][4], v[bj][5], v[bj][6], v[bj][7]};
;                     }
	v_pk_fma_f32 v[192:193], v[94:95], v[172:173], v[154:155] op_sel_hi:[1,0,1]
	v_pk_fma_f32 v[190:191], v[92:93], v[172:173], v[152:153] op_sel_hi:[1,0,1]
	global_store_dwordx4 v[166:167], v[190:193], off
	s_movk_i32 s8, 0xc430
	s_mov_b32 s9, -1
	v_pk_fma_f32 v[192:193], v[90:91], v[172:173], v[158:159] op_sel_hi:[1,0,1]
	v_pk_fma_f32 v[190:191], v[88:89], v[172:173], v[156:157] op_sel_hi:[1,0,1]
	global_store_dwordx4 v[166:167], v[190:193], off offset:16
	v_cmp_gt_i32_e64 s[4:5], s92, v160
	v_lshl_add_u64 v[160:161], v[224:225], 0, s[8:9]
	v_pk_fma_f32 v[192:193], v[86:87], v[172:173], v[150:151] op_sel_hi:[1,0,1]
	v_pk_fma_f32 v[190:191], v[84:85], v[172:173], v[148:149] op_sel_hi:[1,0,1]
	global_store_dwordx4 v[166:167], v[190:193], off offset:512
	v_pk_fma_f32 v[154:155], v[78:79], v[188:189], v[154:155] op_sel_hi:[1,0,1]
	v_pk_fma_f32 v[152:153], v[76:77], v[188:189], v[152:153] op_sel_hi:[1,0,1]
	v_pk_fma_f32 v[192:193], v[82:83], v[172:173], v[146:147] op_sel_hi:[1,0,1]
	v_pk_fma_f32 v[190:191], v[80:81], v[172:173], v[144:145] op_sel_hi:[1,0,1]
	global_store_dwordx4 v[166:167], v[190:193], off offset:528
	v_lshl_add_u64 v[166:167], v[168:169], 0, s[6:7]
	v_cndmask_b32_e64 v161, v161, v167, s[4:5]
	v_cndmask_b32_e64 v160, v160, v166, s[4:5]
	v_cndmask_b32_e64 v166, v165, v171, s[4:5]
	v_mov_b32_e32 v167, v225
	v_lshl_add_u64 v[166:167], s[84:85], 0, v[166:167]
	v_lshlrev_b64 v[160:161], 10, v[160:161]
	v_lshl_add_u64 v[160:161], v[166:167], 0, v[160:161]
	v_lshl_add_u64 v[160:161], v[160:161], 0, v[200:201]
	global_store_dwordx4 v[160:161], v[152:155], off
	v_pk_fma_f32 v[150:151], v[70:71], v[188:189], v[150:151] op_sel_hi:[1,0,1]
	v_pk_fma_f32 v[148:149], v[68:69], v[188:189], v[148:149] op_sel_hi:[1,0,1]
	v_pk_fma_f32 v[154:155], v[74:75], v[188:189], v[158:159] op_sel_hi:[1,0,1]
	v_pk_fma_f32 v[152:153], v[72:73], v[188:189], v[156:157] op_sel_hi:[1,0,1]
	v_pk_fma_f32 v[146:147], v[66:67], v[188:189], v[146:147] op_sel_hi:[1,0,1]
	v_pk_fma_f32 v[144:145], v[64:65], v[188:189], v[144:145] op_sel_hi:[1,0,1]
	global_store_dwordx4 v[160:161], v[152:155], off offset:16
	global_store_dwordx4 v[160:161], v[148:151], off offset:512
	global_store_dwordx4 v[160:161], v[144:147], off offset:528
	s_and_saveexec_b64 s[4:5], vcc
	s_xor_b64 s[4:5], exec, s[4:5]
	v_add_u32_e32 v144, 0x400, v163
	v_mov_b32_e32 v145, v225
	s_or_saveexec_b64 s[4:5], s[4:5]
	v_mov_b64_e32 v[146:147], 0x2ae6000
	s_xor_b64 exec, exec, s[4:5]
	v_ashrrev_i32_e32 v165, 31, v164
	v_lshl_add_u64 v[144:145], v[164:165], 0, s[6:7]
	v_mov_b64_e32 v[146:147], 0x1a00000
	s_or_b64 exec, exec, s[4:5]
	v_lshlrev_b32_e32 v146, 2, v146
	v_mov_b32_e32 v147, v225
	v_lshl_add_u64 v[146:147], s[84:85], 0, v[146:147]
	v_lshlrev_b64 v[144:145], 10, v[144:145]
	v_lshl_add_u64 v[144:145], v[146:147], 0, v[144:145]
	v_lshl_add_u64 v[148:149], v[198:199], 2, v[144:145]
	s_waitcnt vmcnt(19)
	v_pk_fma_f32 v[146:147], v[62:63], v[174:175], v[142:143] op_sel_hi:[1,0,1]
	v_pk_fma_f32 v[144:145], v[60:61], v[174:175], v[140:141] op_sel_hi:[1,0,1]
	global_store_dwordx4 v[148:149], v[144:147], off
	s_movk_i32 s4, 0x3fef
	v_cmp_lt_i32_e32 vcc, s4, v164
	s_waitcnt vmcnt(19)
	v_pk_fma_f32 v[146:147], v[58:59], v[174:175], v[138:139] op_sel_hi:[1,0,1]
	v_pk_fma_f32 v[144:145], v[56:57], v[174:175], v[136:137] op_sel_hi:[1,0,1]
	global_store_dwordx4 v[148:149], v[144:147], off offset:16
	s_waitcnt vmcnt(18)
;     template <int PN> DI void body(AccRef acc, const Unit& u, int wr, int wc, int fr, int fq) const {
;     ...
;                 } else {
;                     float* lo = orow(out, l, row, PN == 8 ? O_PSK : O_PSV, PN == 8 ? O_SSK : O_SSV, 256);
; #pragma unroll
;                     for (int bj = 0; bj < 2; ++bj) {
;                         *(f32x4*)(lo + bj * 128 + cl) = (f32x4){v[bj][0], v[bj][1], v[bj][2], v[bj][3]};
;                         *(f32x4*)(lo + bj * 128 + cl + 4) = (f32x4){v[bj][4], v[bj][5], v[bj][6], v[bj][7]};
;                     }
	s_nop 0
	v_pk_fma_f32 v[146:147], v[54:55], v[174:175], v[134:135] op_sel_hi:[1,0,1]
	v_pk_fma_f32 v[144:145], v[52:53], v[174:175], v[132:133] op_sel_hi:[1,0,1]
	global_store_dwordx4 v[148:149], v[144:147], off offset:512
	s_nop 1
	v_pk_fma_f32 v[146:147], v[50:51], v[174:175], v[130:131] op_sel_hi:[1,0,1]
	v_pk_fma_f32 v[144:145], v[48:49], v[174:175], v[128:129] op_sel_hi:[1,0,1]
	global_store_dwordx4 v[148:149], v[144:147], off offset:528
	s_and_saveexec_b64 s[4:5], vcc
	s_xor_b64 s[4:5], exec, s[4:5]
	s_movk_i32 s6, 0xc490
	s_mov_b32 s7, -1
	v_lshl_add_u64 v[144:145], v[224:225], 0, s[6:7]
	s_or_saveexec_b64 s[4:5], s[4:5]
	v_mov_b64_e32 v[146:147], 0x2ae6000
	s_xor_b64 exec, exec, s[4:5]
	v_add_u32_e32 v144, 0x90, v224
	v_ashrrev_i32_e32 v145, 31, v144
	s_mov_b64 s[6:7], 0x4000
	v_lshl_add_u64 v[144:145], v[144:145], 0, s[6:7]
	v_mov_b64_e32 v[146:147], 0x1a00000
	s_or_b64 exec, exec, s[4:5]
	v_lshlrev_b32_e32 v146, 2, v146
	v_mov_b32_e32 v147, v225
	v_lshl_add_u64 v[146:147], s[84:85], 0, v[146:147]
	v_lshlrev_b64 v[144:145], 10, v[144:145]
	v_lshl_add_u64 v[144:145], v[146:147], 0, v[144:145]
	v_lshl_add_u64 v[148:149], v[198:199], 2, v[144:145]
	v_pk_fma_f32 v[146:147], v[46:47], v[170:171], v[142:143] op_sel_hi:[1,0,1]
	v_pk_fma_f32 v[144:145], v[44:45], v[170:171], v[140:141] op_sel_hi:[1,0,1]
	global_store_dwordx4 v[148:149], v[144:147], off
	s_movk_i32 s4, 0x3fdf
	v_cmp_lt_i32_e32 vcc, s4, v164
	v_pk_fma_f32 v[146:147], v[42:43], v[170:171], v[138:139] op_sel_hi:[1,0,1]
	v_pk_fma_f32 v[144:145], v[40:41], v[170:171], v[136:137] op_sel_hi:[1,0,1]
	global_store_dwordx4 v[148:149], v[144:147], off offset:16
	s_nop 1
	v_pk_fma_f32 v[146:147], v[38:39], v[170:171], v[134:135] op_sel_hi:[1,0,1]
	v_pk_fma_f32 v[144:145], v[36:37], v[170:171], v[132:133] op_sel_hi:[1,0,1]
	global_store_dwordx4 v[148:149], v[144:147], off offset:512
	s_nop 1
	v_pk_fma_f32 v[146:147], v[30:31], v[170:171], v[130:131] op_sel_hi:[1,0,1]
	v_pk_fma_f32 v[144:145], v[28:29], v[170:171], v[128:129] op_sel_hi:[1,0,1]
	global_store_dwordx4 v[148:149], v[144:147], off offset:528
	s_and_saveexec_b64 s[4:5], vcc
	s_xor_b64 s[4:5], exec, s[4:5]
	s_movk_i32 s6, 0xc4a0
	s_mov_b32 s7, -1
	v_lshl_add_u64 v[144:145], v[224:225], 0, s[6:7]
	s_or_saveexec_b64 s[4:5], s[4:5]
	v_mov_b64_e32 v[146:147], 0x2ae6000
	s_xor_b64 exec, exec, s[4:5]
	v_add_u32_e32 v144, 0xa0, v224
	v_ashrrev_i32_e32 v145, 31, v144
	s_mov_b64 s[6:7], 0x4000
	v_lshl_add_u64 v[144:145], v[144:145], 0, s[6:7]
	v_mov_b64_e32 v[146:147], 0x1a00000
	s_or_b64 exec, exec, s[4:5]
	v_lshlrev_b32_e32 v146, 2, v146
	v_mov_b32_e32 v147, v225
	v_lshl_add_u64 v[146:147], s[84:85], 0, v[146:147]
	v_lshlrev_b64 v[144:145], 10, v[144:145]
	v_lshl_add_u64 v[144:145], v[146:147], 0, v[144:145]
	v_lshl_add_u64 v[148:149], v[198:199], 2, v[144:145]
	v_pk_fma_f32 v[146:147], v[34:35], v[196:197], v[142:143] op_sel_hi:[1,0,1]
	v_pk_fma_f32 v[144:145], v[32:33], v[196:197], v[140:141] op_sel_hi:[1,0,1]
	global_store_dwordx4 v[148:149], v[144:147], off
	s_movk_i32 s4, 0x3fcf
	v_cmp_lt_i32_e32 vcc, s4, v164
	v_pk_fma_f32 v[146:147], v[26:27], v[196:197], v[138:139] op_sel_hi:[1,0,1]
	v_pk_fma_f32 v[144:145], v[24:25], v[196:197], v[136:137] op_sel_hi:[1,0,1]
	global_store_dwordx4 v[148:149], v[144:147], off offset:16
	s_nop 1
	v_pk_fma_f32 v[146:147], v[22:23], v[196:197], v[134:135] op_sel_hi:[1,0,1]
	v_pk_fma_f32 v[144:145], v[20:21], v[196:197], v[132:133] op_sel_hi:[1,0,1]
	global_store_dwordx4 v[148:149], v[144:147], off offset:512
	s_nop 1
	v_pk_fma_f32 v[146:147], v[18:19], v[196:197], v[130:131] op_sel_hi:[1,0,1]
	v_pk_fma_f32 v[144:145], v[16:17], v[196:197], v[128:129] op_sel_hi:[1,0,1]
	global_store_dwordx4 v[148:149], v[144:147], off offset:528
	s_and_saveexec_b64 s[4:5], vcc
	s_xor_b64 s[4:5], exec, s[4:5]
	s_movk_i32 s6, 0xc4b0
	s_mov_b32 s7, -1
	v_lshl_add_u64 v[144:145], v[224:225], 0, s[6:7]
	s_or_saveexec_b64 s[4:5], s[4:5]
	v_mov_b64_e32 v[146:147], 0x2ae6000
	s_xor_b64 exec, exec, s[4:5]
	v_add_u32_e32 v144, 0xb0, v224
	v_ashrrev_i32_e32 v145, 31, v144
	s_mov_b64 s[6:7], 0x4000
	v_lshl_add_u64 v[144:145], v[144:145], 0, s[6:7]
	v_mov_b64_e32 v[146:147], 0x1a00000
	s_or_b64 exec, exec, s[4:5]
	v_lshlrev_b32_e32 v224, 2, v146
	v_lshl_add_u64 v[146:147], s[84:85], 0, v[224:225]
	v_lshlrev_b64 v[144:145], 10, v[144:145]
	v_lshl_add_u64 v[144:145], v[146:147], 0, v[144:145]
	v_lshl_add_u64 v[144:145], v[198:199], 2, v[144:145]
	v_pk_fma_f32 v[142:143], v[14:15], v[194:195], v[142:143] op_sel_hi:[1,0,1]
	v_pk_fma_f32 v[140:141], v[12:13], v[194:195], v[140:141] op_sel_hi:[1,0,1]
	v_pk_fma_f32 v[138:139], v[10:11], v[194:195], v[138:139] op_sel_hi:[1,0,1]
	v_pk_fma_f32 v[136:137], v[8:9], v[194:195], v[136:137] op_sel_hi:[1,0,1]
	v_pk_fma_f32 v[134:135], v[6:7], v[194:195], v[134:135] op_sel_hi:[1,0,1]
	v_pk_fma_f32 v[132:133], v[4:5], v[194:195], v[132:133] op_sel_hi:[1,0,1]
	v_pk_fma_f32 v[130:131], v[2:3], v[194:195], v[130:131] op_sel_hi:[1,0,1]
	v_pk_fma_f32 v[128:129], v[0:1], v[194:195], v[128:129] op_sel_hi:[1,0,1]
	s_mov_b64 s[80:81], 0
	global_store_dwordx4 v[144:145], v[140:143], off
	global_store_dwordx4 v[144:145], v[136:139], off offset:16
	global_store_dwordx4 v[144:145], v[132:135], off offset:512
	global_store_dwordx4 v[144:145], v[128:131], off offset:528

; DI float silu(float x) { return x * __builtin_amdgcn_rcpf(1.f + ex2(-x * LOG2E)); }
;     template <int PN> DI void body(AccRef acc, const Unit& u, int wr, int wc, int fr, int fq) const {
;     ...
;         float rinvh[2][4];
;         f32x4 cvh[2][2][2];
;         int zdep = 0;
; #pragma unroll
;         for (int ai = 0; ai < 2; ++ai) {
;             const int rb_ = u.pm * 256 + ai * 128 + wr * 64 + fr;
; #pragma unroll
;             for (int m = 0; m < 4; ++m) rinvh[ai][m] = rsqrtf(sum16(ssq + (size_t)(rb_ + 16 * m + zdep) * 16) * (1.f / 1024.f) + EPS);
;             asm volatile("v_mov_b32 %0, 0" : "=v"(zdep) : "v"(rinvh[ai][0]), "v"(rinvh[ai][1]), "v"(rinvh[ai][2]), "v"(rinvh[ai][3]));
;         }
; #pragma unroll
;         for (int ai = 0; ai < 2; ++ai) {
;             const int rb_ = u.pm * 256 + ai * 128 + wr * 64 + fr;
;             int mb_, p_, k_; row_info(rb_, mb_, p_, k_);
; #pragma unroll
;             for (int bj = 0; bj < 2; ++bj)
; #pragma unroll
;                 for (int n = 0; n < 2; ++n) cvh[ai][bj][n] = *(const f32x4*)(cv + (size_t)(mb_ + zdep) * NIN + PN * 256 + bj * 128 + cl + 4 * n);
;         }
; #pragma unroll
;         for (int ai = 0; ai < 2; ++ai) {
;             const int rb = u.pm * 256 + ai * 128 + wr * 64 + fr;
;             int mb, pos0, kv0; row_info(rb, mb, pos0, kv0);
; #pragma unroll
;             for (int m = 0; m < 4; ++m) {
;                 const int row = rb + 16 * m, pos = pos0 + 16 * m, kvrow = kv0 + 16 * m;
;                 const float rinv = rinvh[ai][m];
;                 float v[2][8];
; #pragma unroll
;                 for (int bj = 0; bj < 2; ++bj)
; #pragma unroll
;                     for (int n = 0; n < 2; ++n)
; #pragma unroll
;                         for (int j = 0; j < 4; ++j) v[bj][4 * n + j] = acc[ai][bj][m][n][j] * rinv + cvh[ai][bj][n][j];
;     ...
;                 } else if constexpr (PN == 5 || PN == 6 || PN == 7) {
;                     bf16_t* dst = PN == 5 ? rv : (PN == 6 ? rg : sq);
; #pragma unroll
;                     for (int bj = 0; bj < 2; ++bj) {
;                         if constexpr (PN == 6) {
; #pragma unroll
;                             for (int j = 0; j < 8; ++j) v[bj][j] = silu(v[bj][j]);
;                         }
;                         if constexpr (PN == 7) {
; #pragma unroll
;                             for (int j = 0; j < 8; ++j) v[bj][j] *= 0.125f;
;                         }
.LBB0_1732:
	s_and_b64 vcc, exec, s[4:5]
	s_cbranch_vccz .LBB0_1734
	s_lshl_b32 s4, s43, 6
	s_lshl_b32 s5, s34, 8
	s_add_i32 s4, s4, s5
	v_add_u32_e32 v160, s4, v214
	v_ashrrev_i32_e32 v161, 31, v160
	v_lshlrev_b64 v[128:129], 6, v[160:161]
	v_lshl_add_u64 v[140:141], s[70:71], 0, v[128:129]
	s_nop 0
	v_add_u32_e32 v168, 16, v160
	v_ashrrev_i32_e32 v169, 31, v168
	s_mov_b32 s4, 0x358637bd
	s_mov_b32 s6, 0x3a800000
	v_add_u32_e32 v164, 32, v160
	v_ashrrev_i32_e32 v165, 31, v164
	v_add_u32_e32 v166, 48, v160
	v_ashrrev_i32_e32 v167, 31, v166
	v_add_u32_e32 v174, 0x80, v160
	s_mov_b64 s[8:9], 0x125c00
	v_lshlrev_b64 v[200:201], 9, v[160:161]
	v_ashrrev_i32_e32 v175, 31, v174
	s_nop 0
	v_lshlrev_b64 v[128:129], 6, v[168:169]
	v_lshl_add_u64 v[140:141], s[70:71], 0, v[128:129]
	s_nop 0
	v_lshlrev_b64 v[168:169], 9, v[168:169]
	s_nop 0
	v_mov_b64_e32 v[128:129], s[4:5]
	s_nop 0
	s_nop 0
	s_nop 0
	v_mov_b32_e32 v172, v244
	s_nop 0
	v_mov_b32_e32 v162, v245
	v_lshlrev_b64 v[130:131], 6, v[164:165]
	v_lshl_add_u64 v[142:143], s[70:71], 0, v[130:131]
	s_nop 0
	s_nop 0
	v_lshlrev_b64 v[130:131], 6, v[166:167]
	v_lshl_add_u64 v[142:143], s[70:71], 0, v[130:131]
	s_nop 0
	s_nop 0
	s_nop 0
	s_nop 0
	s_nop 0
	s_nop 0
	v_mov_b32_e32 v170, v246
	s_nop 0
	v_mov_b32_e32 v190, v247
	v_mov_b32 v130, 0
	s_nop 0
	v_add_u32_e32 v130, v130, v174
	v_ashrrev_i32_e32 v131, 31, v130
	v_lshlrev_b64 v[132:133], 6, v[130:131]
	v_lshl_add_u64 v[144:145], s[70:71], 0, v[132:133]
	s_nop 0
	s_nop 0
	v_add_u32_e32 v132, 16, v130
	v_ashrrev_i32_e32 v133, 31, v132
	v_lshlrev_b64 v[132:133], 6, v[132:133]
	v_lshl_add_u64 v[144:145], s[70:71], 0, v[132:133]
	s_nop 0
	s_nop 0
	s_nop 0
	s_nop 0
	s_nop 0
	s_nop 0
	v_mov_b32_e32 v192, v248
	s_nop 0
	v_mov_b32_e32 v188, v249
	v_add_u32_e32 v132, 32, v130
	v_ashrrev_i32_e32 v133, 31, v132
	v_lshlrev_b64 v[132:133], 6, v[132:133]
	v_lshl_add_u64 v[144:145], s[70:71], 0, v[132:133]
	s_nop 0
	v_add_u32_e32 v130, 48, v130
	v_ashrrev_i32_e32 v131, 31, v130
	v_lshlrev_b64 v[130:131], 6, v[130:131]
	v_lshl_add_u64 v[142:143], s[70:71], 0, v[130:131]
	s_nop 0
	s_nop 0
	s_nop 0
	s_movk_i32 s6, 0x2800
	s_mov_b32 s7, 0x125000
	s_nop 0
	v_mov_b32_e32 v194, v250
	s_lshl_b32 s4, s54, 5
	v_lshl_add_u32 v198, v213, 3, s4
	v_ashrrev_i32_e32 v199, 31, v198
	v_mov_b32_e32 v196, v251
	v_add_u32_e32 v129, 0xffffc000, v160
	v_lshrrev_b32_e32 v129, 6, v129
	v_cmp_gt_i32_e32 vcc, s94, v160
	v_ashrrev_i32_e32 v128, 11, v160
	v_add_u32_e32 v129, 8, v129
	v_cndmask_b32_e32 v128, v129, v128, vcc
	v_mov_b32 v136, 0
	v_lshlrev_b64 v[132:133], 2, v[198:199]
	v_add_u32_e32 v130, v136, v128
	v_mov_b64_e32 v[128:129], s[60:61]
	v_mad_i64_i32 v[130:131], s[4:5], v130, s6, v[128:129]
	v_lshl_add_u64 v[130:131], v[130:131], 0, v[132:133]
	v_lshl_add_u64 v[134:135], v[130:131], 0, s[8:9]
	v_add_co_u32_e32 v130, vcc, s7, v130
	s_nop 1
	v_addc_co_u32_e32 v131, vcc, 0, v131, vcc
	global_load_dwordx4 v[152:155], v[130:131], off offset:3072
	global_load_dwordx4 v[156:159], v[134:135], off offset:16
	global_load_dwordx4 v[144:147], v[134:135], off offset:528
	global_load_dwordx4 v[148:151], v[134:135], off offset:512
	v_add_u32_e32 v131, 0xffffc080, v160
	v_lshrrev_b32_e32 v131, 6, v131
	v_cmp_gt_i32_e32 vcc, s94, v174
	v_ashrrev_i32_e32 v130, 11, v174
	v_add_u32_e32 v131, 8, v131
	v_cndmask_b32_e32 v130, v131, v130, vcc
	v_add_u32_e32 v130, v136, v130
	v_mad_i64_i32 v[128:129], s[4:5], v130, s6, v[128:129]
	v_lshl_add_u64 v[128:129], v[128:129], 0, v[132:133]
	v_lshl_add_u64 v[132:133], v[128:129], 0, s[8:9]
	v_add_co_u32_e32 v128, vcc, s7, v128
	v_readlane_b32 s4, v254, 53
	s_nop 0
	v_addc_co_u32_e32 v129, vcc, 0, v129, vcc
	global_load_dwordx4 v[140:143], v[128:129], off offset:3072
	global_load_dwordx4 v[136:139], v[132:133], off offset:16
	s_nop 0
	global_load_dwordx4 v[128:131], v[132:133], off offset:528
	s_nop 0
	global_load_dwordx4 v[132:135], v[132:133], off offset:512
	v_readlane_b32 s5, v254, 54
	s_waitcnt vmcnt(7)
	v_pk_fma_f32 v[202:203], v[126:127], v[172:173], v[154:155] op_sel_hi:[1,0,1]
	v_lshl_add_u64 v[198:199], v[198:199], 1, s[4:5]
	v_lshl_add_u64 v[204:205], v[198:199], 0, v[200:201]
	v_pk_fma_f32 v[200:201], v[124:125], v[172:173], v[152:153] op_sel_hi:[1,0,1]
	s_mov_b32 s4, 0x3e000000
	s_waitcnt vmcnt(6)
	v_pk_fma_f32 v[206:207], v[120:121], v[172:173], v[156:157] op_sel_hi:[1,0,1]
	v_pk_fma_f32 v[216:217], v[122:123], v[172:173], v[158:159] op_sel_hi:[1,0,1]
	v_pk_mul_f32 v[200:201], v[200:201], s[4:5] op_sel_hi:[1,0]
	v_pk_mul_f32 v[202:203], v[202:203], s[4:5] op_sel_hi:[1,0]
	v_pk_mul_f32 v[206:207], v[206:207], s[4:5] op_sel_hi:[1,0]
	v_pk_mul_f32 v[216:217], v[216:217], s[4:5] op_sel_hi:[1,0]
	v_cvt_pk_bf16_f32 v200, v200, v201
	v_cvt_pk_bf16_f32 v201, v202, v203
	v_cvt_pk_bf16_f32 v202, v206, v207
	v_cvt_pk_bf16_f32 v203, v216, v217
	global_store_dwordx4 v[204:205], v[200:203], off
	s_waitcnt vmcnt(6)
	v_pk_fma_f32 v[206:207], v[112:113], v[172:173], v[144:145] op_sel_hi:[1,0,1]
	v_lshl_add_u64 v[168:169], v[198:199], 0, v[168:169]
	s_waitcnt vmcnt(5)
; DI u32x4 pack8(const float* v) { u32x4 w; w.x = pk2(v[0], v[1]); w.y = pk2(v[2], v[3]); w.z = pk2(v[4], v[5]); w.w = pk2(v[6], v[7]); return w; }
; DI float silu(float x) { return x * __builtin_amdgcn_rcpf(1.f + ex2(-x * LOG2E)); }
;     template <int PN> DI void body(AccRef acc, const Unit& u, int wr, int wc, int fr, int fq) const {
;     ...
; #pragma unroll
;                 for (int bj = 0; bj < 2; ++bj)
; #pragma unroll
;                     for (int n = 0; n < 2; ++n)
; #pragma unroll
;                         for (int j = 0; j < 4; ++j) v[bj][4 * n + j] = acc[ai][bj][m][n][j] * rinv + cvh[ai][bj][n][j];
;     ...
;                 } else if constexpr (PN == 5 || PN == 6 || PN == 7) {
;                     bf16_t* dst = PN == 5 ? rv : (PN == 6 ? rg : sq);
; #pragma unroll
;                     for (int bj = 0; bj < 2; ++bj) {
;                         if constexpr (PN == 6) {
; #pragma unroll
;                             for (int j = 0; j < 8; ++j) v[bj][j] = silu(v[bj][j]);
;                         }
;                         if constexpr (PN == 7) {
; #pragma unroll
;                             for (int j = 0; j < 8; ++j) v[bj][j] *= 0.125f;
;                         }
;                         *(u32x4*)(dst + (size_t)row * 256 + bj * 128 + cl) = pack8(v[bj]);
;                     }
	v_pk_fma_f32 v[200:201], v[116:117], v[172:173], v[148:149] op_sel_hi:[1,0,1]
	v_pk_fma_f32 v[202:203], v[118:119], v[172:173], v[150:151] op_sel_hi:[1,0,1]
	v_pk_fma_f32 v[172:173], v[114:115], v[172:173], v[146:147] op_sel_hi:[1,0,1]
	v_pk_mul_f32 v[200:201], v[200:201], s[4:5] op_sel_hi:[1,0]
	v_pk_mul_f32 v[202:203], v[202:203], s[4:5] op_sel_hi:[1,0]
	v_pk_mul_f32 v[206:207], v[206:207], s[4:5] op_sel_hi:[1,0]
	v_pk_mul_f32 v[172:173], v[172:173], s[4:5] op_sel_hi:[1,0]
	v_cvt_pk_bf16_f32 v200, v200, v201
	v_cvt_pk_bf16_f32 v201, v202, v203
	v_cvt_pk_bf16_f32 v202, v206, v207
	v_cvt_pk_bf16_f32 v203, v172, v173
	global_store_dwordx4 v[204:205], v[200:203], off offset:256
	v_pk_fma_f32 v[172:173], v[108:109], v[162:163], v[152:153] op_sel_hi:[1,0,1]
	s_nop 0
	v_pk_fma_f32 v[200:201], v[110:111], v[162:163], v[154:155] op_sel_hi:[1,0,1]
	v_pk_mul_f32 v[172:173], v[172:173], s[4:5] op_sel_hi:[1,0]
	v_pk_mul_f32 v[202:203], v[200:201], s[4:5] op_sel_hi:[1,0]
	v_pk_fma_f32 v[200:201], v[104:105], v[162:163], v[156:157] op_sel_hi:[1,0,1]
	s_nop 0
	v_pk_mul_f32 v[204:205], v[200:201], s[4:5] op_sel_hi:[1,0]
	v_pk_fma_f32 v[200:201], v[106:107], v[162:163], v[158:159] op_sel_hi:[1,0,1]
	s_nop 0
	v_pk_mul_f32 v[206:207], v[200:201], s[4:5] op_sel_hi:[1,0]
	v_cvt_pk_bf16_f32 v200, v172, v173
	v_cvt_pk_bf16_f32 v201, v202, v203
	v_cvt_pk_bf16_f32 v202, v204, v205
	v_cvt_pk_bf16_f32 v203, v206, v207
	global_store_dwordx4 v[168:169], v[200:203], off
	v_pk_fma_f32 v[172:173], v[100:101], v[162:163], v[148:149] op_sel_hi:[1,0,1]
	s_nop 0
	v_pk_fma_f32 v[200:201], v[102:103], v[162:163], v[150:151] op_sel_hi:[1,0,1]
	v_pk_mul_f32 v[172:173], v[172:173], s[4:5] op_sel_hi:[1,0]
	v_pk_mul_f32 v[202:203], v[200:201], s[4:5] op_sel_hi:[1,0]
	v_pk_fma_f32 v[200:201], v[96:97], v[162:163], v[144:145] op_sel_hi:[1,0,1]
	v_pk_fma_f32 v[162:163], v[98:99], v[162:163], v[146:147] op_sel_hi:[1,0,1]
	v_pk_mul_f32 v[204:205], v[200:201], s[4:5] op_sel_hi:[1,0]
	v_pk_mul_f32 v[162:163], v[162:163], s[4:5] op_sel_hi:[1,0]
	v_cvt_pk_bf16_f32 v200, v172, v173
	v_cvt_pk_bf16_f32 v201, v202, v203
	v_cvt_pk_bf16_f32 v202, v204, v205
	v_cvt_pk_bf16_f32 v203, v162, v163
	v_lshlrev_b64 v[162:163], 9, v[164:165]
	global_store_dwordx4 v[168:169], v[200:203], off offset:256
	v_lshl_add_u64 v[168:169], v[198:199], 0, v[162:163]
	v_pk_fma_f32 v[162:163], v[92:93], v[170:171], v[152:153] op_sel_hi:[1,0,1]
	v_pk_fma_f32 v[164:165], v[94:95], v[170:171], v[154:155] op_sel_hi:[1,0,1]
	v_pk_fma_f32 v[172:173], v[88:89], v[170:171], v[156:157] op_sel_hi:[1,0,1]
	v_pk_fma_f32 v[200:201], v[90:91], v[170:171], v[158:159] op_sel_hi:[1,0,1]
	v_pk_mul_f32 v[162:163], v[162:163], s[4:5] op_sel_hi:[1,0]
	v_pk_mul_f32 v[164:165], v[164:165], s[4:5] op_sel_hi:[1,0]
	v_pk_mul_f32 v[172:173], v[172:173], s[4:5] op_sel_hi:[1,0]
	v_pk_mul_f32 v[200:201], v[200:201], s[4:5] op_sel_hi:[1,0]
	v_cvt_pk_bf16_f32 v162, v162, v163
	v_cvt_pk_bf16_f32 v163, v164, v165
	v_cvt_pk_bf16_f32 v164, v172, v173
	v_cvt_pk_bf16_f32 v165, v200, v201
	global_store_dwordx4 v[168:169], v[162:165], off
	v_pk_fma_f32 v[172:173], v[80:81], v[170:171], v[144:145] op_sel_hi:[1,0,1]
	v_pk_fma_f32 v[152:153], v[76:77], v[190:191], v[152:153] op_sel_hi:[1,0,1]
	v_pk_fma_f32 v[162:163], v[84:85], v[170:171], v[148:149] op_sel_hi:[1,0,1]
	v_pk_fma_f32 v[164:165], v[86:87], v[170:171], v[150:151] op_sel_hi:[1,0,1]
	v_pk_fma_f32 v[170:171], v[82:83], v[170:171], v[146:147] op_sel_hi:[1,0,1]
	v_pk_mul_f32 v[162:163], v[162:163], s[4:5] op_sel_hi:[1,0]
	v_pk_mul_f32 v[164:165], v[164:165], s[4:5] op_sel_hi:[1,0]
	v_pk_mul_f32 v[172:173], v[172:173], s[4:5] op_sel_hi:[1,0]
	v_pk_mul_f32 v[170:171], v[170:171], s[4:5] op_sel_hi:[1,0]
	v_cvt_pk_bf16_f32 v162, v162, v163
	v_cvt_pk_bf16_f32 v163, v164, v165
	v_cvt_pk_bf16_f32 v164, v172, v173
	v_cvt_pk_bf16_f32 v165, v170, v171
	v_pk_fma_f32 v[154:155], v[78:79], v[190:191], v[154:155] op_sel_hi:[1,0,1]
	v_pk_fma_f32 v[156:157], v[72:73], v[190:191], v[156:157] op_sel_hi:[1,0,1]
	v_pk_fma_f32 v[158:159], v[74:75], v[190:191], v[158:159] op_sel_hi:[1,0,1]
	global_store_dwordx4 v[168:169], v[162:165], off offset:256
	v_pk_mul_f32 v[152:153], v[152:153], s[4:5] op_sel_hi:[1,0]
	v_pk_mul_f32 v[154:155], v[154:155], s[4:5] op_sel_hi:[1,0]
	v_lshlrev_b64 v[162:163], 9, v[166:167]
	v_pk_mul_f32 v[156:157], v[156:157], s[4:5] op_sel_hi:[1,0]
	v_pk_mul_f32 v[158:159], v[158:159], s[4:5] op_sel_hi:[1,0]
	v_lshl_add_u64 v[162:163], v[198:199], 0, v[162:163]
	v_cvt_pk_bf16_f32 v152, v152, v153
	v_cvt_pk_bf16_f32 v153, v154, v155
	v_cvt_pk_bf16_f32 v154, v156, v157
	v_cvt_pk_bf16_f32 v155, v158, v159
	v_pk_fma_f32 v[144:145], v[64:65], v[190:191], v[144:145] op_sel_hi:[1,0,1]
	global_store_dwordx4 v[162:163], v[152:155], off
	v_pk_fma_f32 v[148:149], v[68:69], v[190:191], v[148:149] op_sel_hi:[1,0,1]
	v_pk_fma_f32 v[150:151], v[70:71], v[190:191], v[150:151] op_sel_hi:[1,0,1]
	v_pk_mul_f32 v[152:153], v[144:145], s[4:5] op_sel_hi:[1,0]
	v_pk_fma_f32 v[144:145], v[66:67], v[190:191], v[146:147] op_sel_hi:[1,0,1]
	v_pk_mul_f32 v[148:149], v[148:149], s[4:5] op_sel_hi:[1,0]
	v_pk_mul_f32 v[150:151], v[150:151], s[4:5] op_sel_hi:[1,0]
	v_pk_mul_f32 v[154:155], v[144:145], s[4:5] op_sel_hi:[1,0]
	v_cvt_pk_bf16_f32 v144, v148, v149
	v_cvt_pk_bf16_f32 v145, v150, v151
	v_cvt_pk_bf16_f32 v146, v152, v153
	v_cvt_pk_bf16_f32 v147, v154, v155
	global_store_dwordx4 v[162:163], v[144:147], off offset:256
	s_waitcnt vmcnt(10)
; DI u32x4 pack8(const float* v) { u32x4 w; w.x = pk2(v[0], v[1]); w.y = pk2(v[2], v[3]); w.z = pk2(v[4], v[5]); w.w = pk2(v[6], v[7]); return w; }
; DI float silu(float x) { return x * __builtin_amdgcn_rcpf(1.f + ex2(-x * LOG2E)); }
;     template <int PN> DI void body(AccRef acc, const Unit& u, int wr, int wc, int fr, int fq) const {
;     ...
; #pragma unroll
;                 for (int bj = 0; bj < 2; ++bj)
; #pragma unroll
;                     for (int n = 0; n < 2; ++n)
; #pragma unroll
;                         for (int j = 0; j < 4; ++j) v[bj][4 * n + j] = acc[ai][bj][m][n][j] * rinv + cvh[ai][bj][n][j];
;     ...
;                 } else if constexpr (PN == 5 || PN == 6 || PN == 7) {
;                     bf16_t* dst = PN == 5 ? rv : (PN == 6 ? rg : sq);
; #pragma unroll
;                     for (int bj = 0; bj < 2; ++bj) {
;                         if constexpr (PN == 6) {
; #pragma unroll
;                             for (int j = 0; j < 8; ++j) v[bj][j] = silu(v[bj][j]);
;                         }
;                         if constexpr (PN == 7) {
; #pragma unroll
;                             for (int j = 0; j < 8; ++j) v[bj][j] *= 0.125f;
;                         }
;                         *(u32x4*)(dst + (size_t)row * 256 + bj * 128 + cl) = pack8(v[bj]);
;                     }
	v_pk_fma_f32 v[150:151], v[56:57], v[192:193], v[136:137] op_sel_hi:[1,0,1]
	v_pk_fma_f32 v[152:153], v[58:59], v[192:193], v[138:139] op_sel_hi:[1,0,1]
	v_lshlrev_b64 v[144:145], 9, v[174:175]
	v_lshl_add_u64 v[148:149], v[198:199], 0, v[144:145]
	v_pk_fma_f32 v[144:145], v[60:61], v[192:193], v[140:141] op_sel_hi:[1,0,1]
	v_pk_fma_f32 v[146:147], v[62:63], v[192:193], v[142:143] op_sel_hi:[1,0,1]
	v_pk_mul_f32 v[144:145], v[144:145], s[4:5] op_sel_hi:[1,0]
	v_pk_mul_f32 v[146:147], v[146:147], s[4:5] op_sel_hi:[1,0]
	v_pk_mul_f32 v[150:151], v[150:151], s[4:5] op_sel_hi:[1,0]
	v_pk_mul_f32 v[152:153], v[152:153], s[4:5] op_sel_hi:[1,0]
	v_cvt_pk_bf16_f32 v144, v144, v145
	v_cvt_pk_bf16_f32 v145, v146, v147
	v_cvt_pk_bf16_f32 v146, v150, v151
	v_cvt_pk_bf16_f32 v147, v152, v153
	global_store_dwordx4 v[148:149], v[144:147], off
	s_waitcnt vmcnt(10)
	v_pk_fma_f32 v[150:151], v[48:49], v[192:193], v[128:129] op_sel_hi:[1,0,1]
	v_pk_fma_f32 v[152:153], v[50:51], v[192:193], v[130:131] op_sel_hi:[1,0,1]
	s_waitcnt vmcnt(9)
	v_pk_fma_f32 v[144:145], v[52:53], v[192:193], v[132:133] op_sel_hi:[1,0,1]
	v_pk_fma_f32 v[146:147], v[54:55], v[192:193], v[134:135] op_sel_hi:[1,0,1]
	v_pk_mul_f32 v[144:145], v[144:145], s[4:5] op_sel_hi:[1,0]
	v_pk_mul_f32 v[146:147], v[146:147], s[4:5] op_sel_hi:[1,0]
	v_pk_mul_f32 v[150:151], v[150:151], s[4:5] op_sel_hi:[1,0]
	v_pk_mul_f32 v[152:153], v[152:153], s[4:5] op_sel_hi:[1,0]
	v_cvt_pk_bf16_f32 v144, v144, v145
	v_cvt_pk_bf16_f32 v145, v146, v147
	v_cvt_pk_bf16_f32 v146, v150, v151
	v_cvt_pk_bf16_f32 v147, v152, v153
	global_store_dwordx4 v[148:149], v[144:147], off offset:256
	v_pk_fma_f32 v[150:151], v[40:41], v[188:189], v[136:137] op_sel_hi:[1,0,1]
	v_pk_fma_f32 v[152:153], v[42:43], v[188:189], v[138:139] op_sel_hi:[1,0,1]
	v_add_u32_e32 v144, 0x90, v160
	v_ashrrev_i32_e32 v145, 31, v144
	v_lshlrev_b64 v[144:145], 9, v[144:145]
	v_lshl_add_u64 v[148:149], v[198:199], 0, v[144:145]
	v_pk_fma_f32 v[144:145], v[44:45], v[188:189], v[140:141] op_sel_hi:[1,0,1]
	v_pk_fma_f32 v[146:147], v[46:47], v[188:189], v[142:143] op_sel_hi:[1,0,1]
	v_pk_mul_f32 v[144:145], v[144:145], s[4:5] op_sel_hi:[1,0]
	v_pk_mul_f32 v[146:147], v[146:147], s[4:5] op_sel_hi:[1,0]
	v_pk_mul_f32 v[150:151], v[150:151], s[4:5] op_sel_hi:[1,0]
	v_pk_mul_f32 v[152:153], v[152:153], s[4:5] op_sel_hi:[1,0]
	v_cvt_pk_bf16_f32 v144, v144, v145
	v_cvt_pk_bf16_f32 v145, v146, v147
	v_cvt_pk_bf16_f32 v146, v150, v151
	v_cvt_pk_bf16_f32 v147, v152, v153
	global_store_dwordx4 v[148:149], v[144:147], off
	v_pk_fma_f32 v[150:151], v[28:29], v[188:189], v[128:129] op_sel_hi:[1,0,1]
	v_pk_fma_f32 v[152:153], v[30:31], v[188:189], v[130:131] op_sel_hi:[1,0,1]
	v_pk_fma_f32 v[144:145], v[36:37], v[188:189], v[132:133] op_sel_hi:[1,0,1]
	v_pk_fma_f32 v[146:147], v[38:39], v[188:189], v[134:135] op_sel_hi:[1,0,1]
	v_pk_mul_f32 v[144:145], v[144:145], s[4:5] op_sel_hi:[1,0]
	v_pk_mul_f32 v[146:147], v[146:147], s[4:5] op_sel_hi:[1,0]
	v_pk_mul_f32 v[150:151], v[150:151], s[4:5] op_sel_hi:[1,0]
	v_pk_mul_f32 v[152:153], v[152:153], s[4:5] op_sel_hi:[1,0]
	v_cvt_pk_bf16_f32 v144, v144, v145
	v_cvt_pk_bf16_f32 v145, v146, v147
	v_cvt_pk_bf16_f32 v146, v150, v151
	v_cvt_pk_bf16_f32 v147, v152, v153
	global_store_dwordx4 v[148:149], v[144:147], off offset:256
	v_pk_fma_f32 v[150:151], v[24:25], v[194:195], v[136:137] op_sel_hi:[1,0,1]
	v_pk_fma_f32 v[152:153], v[26:27], v[194:195], v[138:139] op_sel_hi:[1,0,1]
	v_add_u32_e32 v144, 0xa0, v160
	v_ashrrev_i32_e32 v145, 31, v144
	v_lshlrev_b64 v[144:145], 9, v[144:145]
	v_lshl_add_u64 v[148:149], v[198:199], 0, v[144:145]
	v_pk_fma_f32 v[144:145], v[32:33], v[194:195], v[140:141] op_sel_hi:[1,0,1]
	v_pk_fma_f32 v[146:147], v[34:35], v[194:195], v[142:143] op_sel_hi:[1,0,1]
	v_pk_mul_f32 v[144:145], v[144:145], s[4:5] op_sel_hi:[1,0]
	v_pk_mul_f32 v[146:147], v[146:147], s[4:5] op_sel_hi:[1,0]
	v_pk_mul_f32 v[150:151], v[150:151], s[4:5] op_sel_hi:[1,0]
	v_pk_mul_f32 v[152:153], v[152:153], s[4:5] op_sel_hi:[1,0]
	v_cvt_pk_bf16_f32 v144, v144, v145
	v_cvt_pk_bf16_f32 v145, v146, v147
	v_cvt_pk_bf16_f32 v146, v150, v151
	v_cvt_pk_bf16_f32 v147, v152, v153
	global_store_dwordx4 v[148:149], v[144:147], off
	v_pk_fma_f32 v[150:151], v[16:17], v[194:195], v[128:129] op_sel_hi:[1,0,1]
	v_pk_fma_f32 v[152:153], v[18:19], v[194:195], v[130:131] op_sel_hi:[1,0,1]
	v_pk_fma_f32 v[144:145], v[20:21], v[194:195], v[132:133] op_sel_hi:[1,0,1]
	v_pk_fma_f32 v[146:147], v[22:23], v[194:195], v[134:135] op_sel_hi:[1,0,1]
	v_pk_mul_f32 v[144:145], v[144:145], s[4:5] op_sel_hi:[1,0]
	v_pk_mul_f32 v[146:147], v[146:147], s[4:5] op_sel_hi:[1,0]
	v_pk_mul_f32 v[150:151], v[150:151], s[4:5] op_sel_hi:[1,0]
	v_pk_mul_f32 v[152:153], v[152:153], s[4:5] op_sel_hi:[1,0]
	v_cvt_pk_bf16_f32 v144, v144, v145
	v_cvt_pk_bf16_f32 v145, v146, v147
	v_cvt_pk_bf16_f32 v146, v150, v151
	v_cvt_pk_bf16_f32 v147, v152, v153
	global_store_dwordx4 v[148:149], v[144:147], off offset:256
	v_pk_fma_f32 v[136:137], v[8:9], v[196:197], v[136:137] op_sel_hi:[1,0,1]
	v_pk_fma_f32 v[140:141], v[12:13], v[196:197], v[140:141] op_sel_hi:[1,0,1]
	v_add_u32_e32 v144, 0xb0, v160
	v_ashrrev_i32_e32 v145, 31, v144
	v_pk_fma_f32 v[142:143], v[14:15], v[196:197], v[142:143] op_sel_hi:[1,0,1]
	v_pk_mul_f32 v[146:147], v[136:137], s[4:5] op_sel_hi:[1,0]
	v_pk_fma_f32 v[136:137], v[10:11], v[196:197], v[138:139] op_sel_hi:[1,0,1]
	v_lshlrev_b64 v[144:145], 9, v[144:145]
	v_pk_mul_f32 v[140:141], v[140:141], s[4:5] op_sel_hi:[1,0]
	v_pk_mul_f32 v[142:143], v[142:143], s[4:5] op_sel_hi:[1,0]
	v_pk_mul_f32 v[148:149], v[136:137], s[4:5] op_sel_hi:[1,0]
	v_lshl_add_u64 v[144:145], v[198:199], 0, v[144:145]
	v_cvt_pk_bf16_f32 v136, v140, v141
	v_cvt_pk_bf16_f32 v137, v142, v143
	v_cvt_pk_bf16_f32 v138, v146, v147
	v_cvt_pk_bf16_f32 v139, v148, v149
	v_pk_fma_f32 v[128:129], v[0:1], v[196:197], v[128:129] op_sel_hi:[1,0,1]
	global_store_dwordx4 v[144:145], v[136:139], off
	v_pk_fma_f32 v[132:133], v[4:5], v[196:197], v[132:133] op_sel_hi:[1,0,1]
	v_pk_fma_f32 v[134:135], v[6:7], v[196:197], v[134:135] op_sel_hi:[1,0,1]
	v_pk_mul_f32 v[136:137], v[128:129], s[4:5] op_sel_hi:[1,0]
	v_pk_fma_f32 v[128:129], v[2:3], v[196:197], v[130:131] op_sel_hi:[1,0,1]
	v_pk_mul_f32 v[132:133], v[132:133], s[4:5] op_sel_hi:[1,0]
	v_pk_mul_f32 v[134:135], v[134:135], s[4:5] op_sel_hi:[1,0]
	v_pk_mul_f32 v[138:139], v[128:129], s[4:5] op_sel_hi:[1,0]
	v_cvt_pk_bf16_f32 v128, v132, v133
	v_cvt_pk_bf16_f32 v129, v134, v135
	v_cvt_pk_bf16_f32 v130, v136, v137
	v_cvt_pk_bf16_f32 v131, v138, v139
	global_store_dwordx4 v[144:145], v[128:131], off offset:256

; DI float silu(float x) { return x * __builtin_amdgcn_rcpf(1.f + ex2(-x * LOG2E)); }
;     template <int PN> DI void body(AccRef acc, const Unit& u, int wr, int wc, int fr, int fq) const {
;     ...
;         float rinvh[2][4];
;         f32x4 cvh[2][2][2];
;         int zdep = 0;
; #pragma unroll
;         for (int ai = 0; ai < 2; ++ai) {
;             const int rb_ = u.pm * 256 + ai * 128 + wr * 64 + fr;
; #pragma unroll
;             for (int m = 0; m < 4; ++m) rinvh[ai][m] = rsqrtf(sum16(ssq + (size_t)(rb_ + 16 * m + zdep) * 16) * (1.f / 1024.f) + EPS);
;             asm volatile("v_mov_b32 %0, 0" : "=v"(zdep) : "v"(rinvh[ai][0]), "v"(rinvh[ai][1]), "v"(rinvh[ai][2]), "v"(rinvh[ai][3]));
;         }
; #pragma unroll
;         for (int ai = 0; ai < 2; ++ai) {
;             const int rb_ = u.pm * 256 + ai * 128 + wr * 64 + fr;
;             int mb_, p_, k_; row_info(rb_, mb_, p_, k_);
; #pragma unroll
;             for (int bj = 0; bj < 2; ++bj)
; #pragma unroll
;                 for (int n = 0; n < 2; ++n) cvh[ai][bj][n] = *(const f32x4*)(cv + (size_t)(mb_ + zdep) * NIN + PN * 256 + bj * 128 + cl + 4 * n);
;         }
; #pragma unroll
;         for (int ai = 0; ai < 2; ++ai) {
;             const int rb = u.pm * 256 + ai * 128 + wr * 64 + fr;
;             int mb, pos0, kv0; row_info(rb, mb, pos0, kv0);
; #pragma unroll
;             for (int m = 0; m < 4; ++m) {
;                 const int row = rb + 16 * m, pos = pos0 + 16 * m, kvrow = kv0 + 16 * m;
;                 const float rinv = rinvh[ai][m];
;                 float v[2][8];
; #pragma unroll
;                 for (int bj = 0; bj < 2; ++bj)
; #pragma unroll
;                     for (int n = 0; n < 2; ++n)
; #pragma unroll
;                         for (int j = 0; j < 4; ++j) v[bj][4 * n + j] = acc[ai][bj][m][n][j] * rinv + cvh[ai][bj][n][j];
;     ...
;                 } else if constexpr (PN == 5 || PN == 6 || PN == 7) {
;                     bf16_t* dst = PN == 5 ? rv : (PN == 6 ? rg : sq);
; #pragma unroll
;                     for (int bj = 0; bj < 2; ++bj) {
;                         if constexpr (PN == 6) {
; #pragma unroll
;                             for (int j = 0; j < 8; ++j) v[bj][j] = silu(v[bj][j]);
;                         }
;                         if constexpr (PN == 7) {
; #pragma unroll
;                             for (int j = 0; j < 8; ++j) v[bj][j] *= 0.125f;
;                         }
.LBB0_1735:
	s_and_b64 vcc, exec, s[4:5]
	s_cbranch_vccz .LBB0_1737
	s_lshl_b32 s4, s43, 6
	s_lshl_b32 s5, s34, 8
	s_add_i32 s4, s4, s5
	v_add_u32_e32 v160, s4, v214
	v_ashrrev_i32_e32 v161, 31, v160
	v_lshlrev_b64 v[128:129], 6, v[160:161]
	v_lshl_add_u64 v[140:141], s[70:71], 0, v[128:129]
	s_nop 0
	v_add_u32_e32 v196, 16, v160
	v_ashrrev_i32_e32 v197, 31, v196
	s_mov_b32 s4, 0x358637bd
	s_mov_b32 s6, 0x3a800000
	v_add_u32_e32 v194, 32, v160
	v_ashrrev_i32_e32 v195, 31, v194
	v_add_u32_e32 v188, 48, v160
	v_ashrrev_i32_e32 v189, 31, v188
	v_add_u32_e32 v172, 0x80, v160
	s_mov_b64 s[8:9], 0x125800
	v_lshlrev_b64 v[200:201], 9, v[160:161]
	v_ashrrev_i32_e32 v173, 31, v172
	s_nop 0
	v_lshlrev_b64 v[128:129], 6, v[196:197]
	v_lshl_add_u64 v[140:141], s[70:71], 0, v[128:129]
	s_nop 0
	v_lshlrev_b64 v[196:197], 9, v[196:197]
	s_nop 0
	v_mov_b64_e32 v[128:129], s[4:5]
	s_nop 0
	s_nop 0
	s_nop 0
	v_mov_b32_e32 v198, v244
	s_nop 0
	v_mov_b32_e32 v190, v245
	v_lshlrev_b64 v[130:131], 6, v[194:195]
	v_lshl_add_u64 v[142:143], s[70:71], 0, v[130:131]
	s_nop 0
	s_nop 0
	v_lshlrev_b64 v[130:131], 6, v[188:189]
	v_lshl_add_u64 v[142:143], s[70:71], 0, v[130:131]
	s_nop 0
	v_lshlrev_b64 v[188:189], 9, v[188:189]
	s_nop 0
	s_nop 0
	s_nop 0
	s_nop 0
	s_nop 0
	v_mov_b32_e32 v192, v246
	s_nop 0
	v_mov_b32_e32 v174, v247
	v_mov_b32 v130, 0
	s_nop 0
	v_add_u32_e32 v130, v130, v172
	v_ashrrev_i32_e32 v131, 31, v130
	v_lshlrev_b64 v[132:133], 6, v[130:131]
	v_lshl_add_u64 v[144:145], s[70:71], 0, v[132:133]
	s_nop 0
	s_nop 0
	v_add_u32_e32 v132, 16, v130
	v_ashrrev_i32_e32 v133, 31, v132
	v_lshlrev_b64 v[132:133], 6, v[132:133]
	v_lshl_add_u64 v[144:145], s[70:71], 0, v[132:133]
	s_nop 0
	s_nop 0
	s_nop 0
	s_nop 0
	s_nop 0
	s_nop 0
	v_mov_b32_e32 v170, v248
	s_nop 0
	v_mov_b32_e32 v164, v249
	v_add_u32_e32 v132, 32, v130
	v_ashrrev_i32_e32 v133, 31, v132
	v_lshlrev_b64 v[132:133], 6, v[132:133]
	v_lshl_add_u64 v[144:145], s[70:71], 0, v[132:133]
	s_nop 0
	v_add_u32_e32 v130, 48, v130
	v_ashrrev_i32_e32 v131, 31, v130
	v_lshlrev_b64 v[130:131], 6, v[130:131]
	v_lshl_add_u64 v[142:143], s[70:71], 0, v[130:131]
	s_nop 0
	s_nop 0
	s_nop 0
	s_movk_i32 s6, 0x2800
	s_mov_b32 s7, 0x125000
	s_nop 0
	v_mov_b32_e32 v166, v250
	s_lshl_b32 s4, s54, 5
	v_lshl_add_u32 v168, v213, 3, s4
	v_ashrrev_i32_e32 v169, 31, v168
	v_mov_b32_e32 v162, v251
	v_add_u32_e32 v129, 0xffffc000, v160
	v_lshrrev_b32_e32 v129, 6, v129
	v_cmp_gt_i32_e32 vcc, s94, v160
	v_ashrrev_i32_e32 v128, 11, v160
	v_add_u32_e32 v129, 8, v129
	v_cndmask_b32_e32 v128, v129, v128, vcc
	v_mov_b32 v136, 0
	v_lshlrev_b64 v[132:133], 2, v[168:169]
	v_add_u32_e32 v130, v136, v128
	v_mov_b64_e32 v[128:129], s[60:61]
	v_mad_i64_i32 v[130:131], s[4:5], v130, s6, v[128:129]
	v_lshl_add_u64 v[130:131], v[130:131], 0, v[132:133]
	v_lshl_add_u64 v[134:135], v[130:131], 0, s[8:9]
	v_add_co_u32_e32 v130, vcc, s7, v130
	s_nop 1
	v_addc_co_u32_e32 v131, vcc, 0, v131, vcc
	global_load_dwordx4 v[156:159], v[130:131], off offset:2048
	global_load_dwordx4 v[152:155], v[134:135], off offset:16
	global_load_dwordx4 v[144:147], v[134:135], off offset:528
	global_load_dwordx4 v[148:151], v[134:135], off offset:512
	v_add_u32_e32 v131, 0xffffc080, v160
	v_lshrrev_b32_e32 v131, 6, v131
	v_cmp_gt_i32_e32 vcc, s94, v172
	v_ashrrev_i32_e32 v130, 11, v172
	v_add_u32_e32 v131, 8, v131
	v_cndmask_b32_e32 v130, v131, v130, vcc
	v_add_u32_e32 v130, v136, v130
	v_mad_i64_i32 v[128:129], s[4:5], v130, s6, v[128:129]
	v_readlane_b32 s4, v254, 46
	v_lshl_add_u64 v[128:129], v[128:129], 0, v[132:133]
	v_readlane_b32 s5, v254, 47
	v_lshl_add_u64 v[132:133], v[128:129], 0, s[8:9]
	v_add_co_u32_e32 v128, vcc, s7, v128
	v_lshl_add_u64 v[168:169], v[168:169], 1, s[4:5]
	s_nop 0
	v_addc_co_u32_e32 v129, vcc, 0, v129, vcc
	v_lshl_add_u64 v[200:201], v[168:169], 0, v[200:201]
	global_load_dwordx4 v[140:143], v[128:129], off offset:2048
	global_load_dwordx4 v[136:139], v[132:133], off offset:16
	s_nop 0
	global_load_dwordx4 v[128:131], v[132:133], off offset:528
	s_nop 0
	global_load_dwordx4 v[132:135], v[132:133], off offset:512
	v_lshl_add_u64 v[196:197], v[168:169], 0, v[196:197]
	v_lshl_add_u64 v[188:189], v[168:169], 0, v[188:189]
	s_waitcnt vmcnt(7)
	v_pk_fma_f32 v[202:203], v[124:125], v[198:199], v[156:157] op_sel_hi:[1,0,1]
	s_nop 0
	v_mul_f32_e32 v161, 0xbfb8aa3b, v202
	v_exp_f32_e32 v161, v161
	s_nop 0
	v_add_f32_e32 v161, 1.0, v161
	v_rcp_f32_e32 v204, v161
	v_mul_f32_e32 v161, 0xbfb8aa3b, v203
	v_exp_f32_e32 v161, v161
	s_nop 0
	v_add_f32_e32 v161, 1.0, v161
	v_rcp_f32_e32 v205, v161
	s_nop 0
	v_pk_mul_f32 v[202:203], v[202:203], v[204:205]
	v_pk_fma_f32 v[204:205], v[126:127], v[198:199], v[158:159] op_sel_hi:[1,0,1]
	v_cvt_pk_bf16_f32 v202, v202, v203
	v_mul_f32_e32 v161, 0xbfb8aa3b, v204
	v_exp_f32_e32 v161, v161
	s_nop 0
	v_add_f32_e32 v161, 1.0, v161
	v_rcp_f32_e32 v206, v161
	v_mul_f32_e32 v161, 0xbfb8aa3b, v205
	v_exp_f32_e32 v161, v161
	s_nop 0
	v_add_f32_e32 v161, 1.0, v161
	v_rcp_f32_e32 v207, v161
	s_nop 0
	v_pk_mul_f32 v[204:205], v[204:205], v[206:207]
	s_waitcnt vmcnt(6)
	v_pk_fma_f32 v[206:207], v[120:121], v[198:199], v[152:153] op_sel_hi:[1,0,1]
	v_cvt_pk_bf16_f32 v203, v204, v205
	v_mul_f32_e32 v161, 0xbfb8aa3b, v206
	v_exp_f32_e32 v161, v161
	s_nop 0
	v_add_f32_e32 v161, 1.0, v161
	v_rcp_f32_e32 v216, v161
	v_mul_f32_e32 v161, 0xbfb8aa3b, v207
	v_exp_f32_e32 v161, v161
	s_nop 0
	v_add_f32_e32 v161, 1.0, v161
	v_rcp_f32_e32 v217, v161
	s_nop 0
	v_pk_mul_f32 v[206:207], v[206:207], v[216:217]
	v_pk_fma_f32 v[216:217], v[122:123], v[198:199], v[154:155] op_sel_hi:[1,0,1]
	v_cvt_pk_bf16_f32 v204, v206, v207
	v_mul_f32_e32 v161, 0xbfb8aa3b, v216
	v_exp_f32_e32 v161, v161
	s_nop 0
	v_add_f32_e32 v161, 1.0, v161
	v_rcp_f32_e32 v218, v161
	v_mul_f32_e32 v161, 0xbfb8aa3b, v217
	v_exp_f32_e32 v161, v161
	s_nop 0
	v_add_f32_e32 v161, 1.0, v161
	v_rcp_f32_e32 v219, v161
	s_nop 0
	v_pk_mul_f32 v[216:217], v[216:217], v[218:219]
	s_nop 0
	v_cvt_pk_bf16_f32 v205, v216, v217
	global_store_dwordx4 v[200:201], v[202:205], off
	s_waitcnt vmcnt(5)
; DI u32x4 pack8(const float* v) { u32x4 w; w.x = pk2(v[0], v[1]); w.y = pk2(v[2], v[3]); w.z = pk2(v[4], v[5]); w.w = pk2(v[6], v[7]); return w; }
; DI float ex2(float x) { return __builtin_amdgcn_exp2f(x); }
; DI float silu(float x) { return x * __builtin_amdgcn_rcpf(1.f + ex2(-x * LOG2E)); }
;     template <int PN> DI void body(AccRef acc, const Unit& u, int wr, int wc, int fr, int fq) const {
;     ...
;                 } else if constexpr (PN == 5 || PN == 6 || PN == 7) {
;                     bf16_t* dst = PN == 5 ? rv : (PN == 6 ? rg : sq);
; #pragma unroll
;                     for (int bj = 0; bj < 2; ++bj) {
;                         if constexpr (PN == 6) {
; #pragma unroll
;                             for (int j = 0; j < 8; ++j) v[bj][j] = silu(v[bj][j]);
;                         }
;                         if constexpr (PN == 7) {
; #pragma unroll
;                             for (int j = 0; j < 8; ++j) v[bj][j] *= 0.125f;
;                         }
;                         *(u32x4*)(dst + (size_t)row * 256 + bj * 128 + cl) = pack8(v[bj]);
;                     }
	s_nop 0
	v_pk_fma_f32 v[202:203], v[116:117], v[198:199], v[148:149] op_sel_hi:[1,0,1]
	s_nop 0
	v_mul_f32_e32 v161, 0xbfb8aa3b, v202
	v_exp_f32_e32 v161, v161
	s_nop 0
	v_add_f32_e32 v161, 1.0, v161
	v_rcp_f32_e32 v204, v161
	v_mul_f32_e32 v161, 0xbfb8aa3b, v203
	v_exp_f32_e32 v161, v161
	s_nop 0
	v_add_f32_e32 v161, 1.0, v161
	v_rcp_f32_e32 v205, v161
	s_nop 0
	v_pk_mul_f32 v[202:203], v[202:203], v[204:205]
	v_pk_fma_f32 v[204:205], v[118:119], v[198:199], v[150:151] op_sel_hi:[1,0,1]
	v_cvt_pk_bf16_f32 v202, v202, v203
	v_mul_f32_e32 v161, 0xbfb8aa3b, v204
	v_exp_f32_e32 v161, v161
	s_nop 0
	v_add_f32_e32 v161, 1.0, v161
	v_rcp_f32_e32 v206, v161
	v_mul_f32_e32 v161, 0xbfb8aa3b, v205
	v_exp_f32_e32 v161, v161
	s_nop 0
	v_add_f32_e32 v161, 1.0, v161
	v_rcp_f32_e32 v207, v161
	s_nop 0
	v_pk_mul_f32 v[204:205], v[204:205], v[206:207]
	v_pk_fma_f32 v[206:207], v[112:113], v[198:199], v[144:145] op_sel_hi:[1,0,1]
	v_pk_fma_f32 v[198:199], v[114:115], v[198:199], v[146:147] op_sel_hi:[1,0,1]
	v_mul_f32_e32 v161, 0xbfb8aa3b, v206
	v_exp_f32_e32 v161, v161
	v_cvt_pk_bf16_f32 v203, v204, v205
	v_add_f32_e32 v161, 1.0, v161
	v_rcp_f32_e32 v216, v161
	v_mul_f32_e32 v161, 0xbfb8aa3b, v207
	v_exp_f32_e32 v161, v161
	s_nop 0
	v_add_f32_e32 v161, 1.0, v161
	v_rcp_f32_e32 v217, v161
	v_mul_f32_e32 v161, 0xbfb8aa3b, v198
	v_exp_f32_e32 v161, v161
	v_pk_mul_f32 v[206:207], v[206:207], v[216:217]
	s_nop 0
	v_cvt_pk_bf16_f32 v204, v206, v207
	v_add_f32_e32 v161, 1.0, v161
	v_rcp_f32_e32 v216, v161
	v_mul_f32_e32 v161, 0xbfb8aa3b, v199
	v_exp_f32_e32 v161, v161
	s_nop 0
	v_add_f32_e32 v161, 1.0, v161
	v_rcp_f32_e32 v217, v161
	s_nop 0
	v_pk_mul_f32 v[198:199], v[198:199], v[216:217]
	s_nop 0
	v_cvt_pk_bf16_f32 v205, v198, v199
	v_pk_fma_f32 v[198:199], v[108:109], v[190:191], v[156:157] op_sel_hi:[1,0,1]
	global_store_dwordx4 v[200:201], v[202:205], off offset:256
	v_mul_f32_e32 v161, 0xbfb8aa3b, v198
	v_exp_f32_e32 v161, v161
	s_nop 0
	v_add_f32_e32 v161, 1.0, v161
	v_rcp_f32_e32 v200, v161
	v_mul_f32_e32 v161, 0xbfb8aa3b, v199
	v_exp_f32_e32 v161, v161
	s_nop 0
	v_add_f32_e32 v161, 1.0, v161
	v_rcp_f32_e32 v201, v161
	s_nop 0
	v_pk_mul_f32 v[198:199], v[198:199], v[200:201]
	v_pk_fma_f32 v[200:201], v[110:111], v[190:191], v[158:159] op_sel_hi:[1,0,1]
	v_cvt_pk_bf16_f32 v198, v198, v199
	v_mul_f32_e32 v161, 0xbfb8aa3b, v200
	v_exp_f32_e32 v161, v161
	s_nop 0
	v_add_f32_e32 v161, 1.0, v161
	v_rcp_f32_e32 v202, v161
	v_mul_f32_e32 v161, 0xbfb8aa3b, v201
	v_exp_f32_e32 v161, v161
	s_nop 0
	v_add_f32_e32 v161, 1.0, v161
	v_rcp_f32_e32 v203, v161
	s_nop 0
	v_pk_mul_f32 v[200:201], v[200:201], v[202:203]
	v_pk_fma_f32 v[202:203], v[104:105], v[190:191], v[152:153] op_sel_hi:[1,0,1]
	v_cvt_pk_bf16_f32 v199, v200, v201
	v_mul_f32_e32 v161, 0xbfb8aa3b, v202
	v_exp_f32_e32 v161, v161
	s_nop 0
	v_add_f32_e32 v161, 1.0, v161
	v_rcp_f32_e32 v204, v161
	v_mul_f32_e32 v161, 0xbfb8aa3b, v203
	v_exp_f32_e32 v161, v161
	s_nop 0
	v_add_f32_e32 v161, 1.0, v161
	v_rcp_f32_e32 v205, v161
	s_nop 0
	v_pk_mul_f32 v[202:203], v[202:203], v[204:205]
	v_pk_fma_f32 v[204:205], v[106:107], v[190:191], v[154:155] op_sel_hi:[1,0,1]
	v_cvt_pk_bf16_f32 v200, v202, v203
	v_mul_f32_e32 v161, 0xbfb8aa3b, v204
	v_exp_f32_e32 v161, v161
	s_nop 0
	v_add_f32_e32 v161, 1.0, v161
	v_rcp_f32_e32 v206, v161
	v_mul_f32_e32 v161, 0xbfb8aa3b, v205
	v_exp_f32_e32 v161, v161
	s_nop 0
	v_add_f32_e32 v161, 1.0, v161
	v_rcp_f32_e32 v207, v161
	s_nop 0
	v_pk_mul_f32 v[204:205], v[204:205], v[206:207]
	s_nop 0
	v_cvt_pk_bf16_f32 v201, v204, v205
	global_store_dwordx4 v[196:197], v[198:201], off
	s_nop 1
	v_pk_fma_f32 v[198:199], v[100:101], v[190:191], v[148:149] op_sel_hi:[1,0,1]
	s_nop 0
	v_mul_f32_e32 v161, 0xbfb8aa3b, v198
	v_exp_f32_e32 v161, v161
	s_nop 0
	v_add_f32_e32 v161, 1.0, v161
	v_rcp_f32_e32 v200, v161
	v_mul_f32_e32 v161, 0xbfb8aa3b, v199
	v_exp_f32_e32 v161, v161
	s_nop 0
	v_add_f32_e32 v161, 1.0, v161
	v_rcp_f32_e32 v201, v161
	s_nop 0
	v_pk_mul_f32 v[198:199], v[198:199], v[200:201]
	v_pk_fma_f32 v[200:201], v[102:103], v[190:191], v[150:151] op_sel_hi:[1,0,1]
	v_cvt_pk_bf16_f32 v198, v198, v199
	v_mul_f32_e32 v161, 0xbfb8aa3b, v200
	v_exp_f32_e32 v161, v161
	s_nop 0
	v_add_f32_e32 v161, 1.0, v161
	v_rcp_f32_e32 v202, v161
	v_mul_f32_e32 v161, 0xbfb8aa3b, v201
	v_exp_f32_e32 v161, v161
	s_nop 0
	v_add_f32_e32 v161, 1.0, v161
	v_rcp_f32_e32 v203, v161
	s_nop 0
	v_pk_mul_f32 v[200:201], v[200:201], v[202:203]
	v_pk_fma_f32 v[202:203], v[96:97], v[190:191], v[144:145] op_sel_hi:[1,0,1]
	v_pk_fma_f32 v[190:191], v[98:99], v[190:191], v[146:147] op_sel_hi:[1,0,1]
	v_mul_f32_e32 v161, 0xbfb8aa3b, v202
	v_exp_f32_e32 v161, v161
	v_cvt_pk_bf16_f32 v199, v200, v201
	v_add_f32_e32 v161, 1.0, v161
	v_rcp_f32_e32 v204, v161
	v_mul_f32_e32 v161, 0xbfb8aa3b, v203
	v_exp_f32_e32 v161, v161
	s_nop 0
	v_add_f32_e32 v161, 1.0, v161
	v_rcp_f32_e32 v205, v161
	v_mul_f32_e32 v161, 0xbfb8aa3b, v190
	v_exp_f32_e32 v161, v161
	v_pk_mul_f32 v[202:203], v[202:203], v[204:205]
	s_nop 0
	v_cvt_pk_bf16_f32 v200, v202, v203
	v_add_f32_e32 v161, 1.0, v161
	v_rcp_f32_e32 v204, v161
	v_mul_f32_e32 v161, 0xbfb8aa3b, v191
	v_exp_f32_e32 v161, v161
	s_nop 0
	v_add_f32_e32 v161, 1.0, v161
	v_rcp_f32_e32 v205, v161
	s_nop 0
	v_pk_mul_f32 v[190:191], v[190:191], v[204:205]
	s_nop 0
	v_cvt_pk_bf16_f32 v201, v190, v191
	v_lshlrev_b64 v[190:191], 9, v[194:195]
	v_pk_fma_f32 v[194:195], v[92:93], v[192:193], v[156:157] op_sel_hi:[1,0,1]
	global_store_dwordx4 v[196:197], v[198:201], off offset:256
	v_mul_f32_e32 v161, 0xbfb8aa3b, v194
	v_exp_f32_e32 v161, v161
	v_lshl_add_u64 v[190:191], v[168:169], 0, v[190:191]
; DI u32x4 pack8(const float* v) { u32x4 w; w.x = pk2(v[0], v[1]); w.y = pk2(v[2], v[3]); w.z = pk2(v[4], v[5]); w.w = pk2(v[6], v[7]); return w; }
; DI float ex2(float x) { return __builtin_amdgcn_exp2f(x); }
; DI float silu(float x) { return x * __builtin_amdgcn_rcpf(1.f + ex2(-x * LOG2E)); }
;     template <int PN> DI void body(AccRef acc, const Unit& u, int wr, int wc, int fr, int fq) const {
;     ...
;                 } else if constexpr (PN == 5 || PN == 6 || PN == 7) {
;                     bf16_t* dst = PN == 5 ? rv : (PN == 6 ? rg : sq);
; #pragma unroll
;                     for (int bj = 0; bj < 2; ++bj) {
;                         if constexpr (PN == 6) {
; #pragma unroll
;                             for (int j = 0; j < 8; ++j) v[bj][j] = silu(v[bj][j]);
;                         }
;                         if constexpr (PN == 7) {
; #pragma unroll
;                             for (int j = 0; j < 8; ++j) v[bj][j] *= 0.125f;
;                         }
;                         *(u32x4*)(dst + (size_t)row * 256 + bj * 128 + cl) = pack8(v[bj]);
;                     }
	v_pk_fma_f32 v[156:157], v[76:77], v[174:175], v[156:157] op_sel_hi:[1,0,1]
	v_add_f32_e32 v161, 1.0, v161
	v_rcp_f32_e32 v196, v161
	v_mul_f32_e32 v161, 0xbfb8aa3b, v195
	v_exp_f32_e32 v161, v161
	s_nop 0
	v_add_f32_e32 v161, 1.0, v161
	v_rcp_f32_e32 v197, v161
	s_nop 0
	v_pk_mul_f32 v[194:195], v[194:195], v[196:197]
	v_pk_fma_f32 v[196:197], v[94:95], v[192:193], v[158:159] op_sel_hi:[1,0,1]
	v_cvt_pk_bf16_f32 v194, v194, v195
	v_mul_f32_e32 v161, 0xbfb8aa3b, v196
	v_exp_f32_e32 v161, v161
	v_pk_fma_f32 v[158:159], v[78:79], v[174:175], v[158:159] op_sel_hi:[1,0,1]
	v_add_f32_e32 v161, 1.0, v161
	v_rcp_f32_e32 v198, v161
	v_mul_f32_e32 v161, 0xbfb8aa3b, v197
	v_exp_f32_e32 v161, v161
	s_nop 0
	v_add_f32_e32 v161, 1.0, v161
	v_rcp_f32_e32 v199, v161
	s_nop 0
	v_pk_mul_f32 v[196:197], v[196:197], v[198:199]
	v_pk_fma_f32 v[198:199], v[88:89], v[192:193], v[152:153] op_sel_hi:[1,0,1]
	v_cvt_pk_bf16_f32 v195, v196, v197
	v_mul_f32_e32 v161, 0xbfb8aa3b, v198
	v_exp_f32_e32 v161, v161
	v_pk_fma_f32 v[152:153], v[72:73], v[174:175], v[152:153] op_sel_hi:[1,0,1]
	v_add_f32_e32 v161, 1.0, v161
	v_rcp_f32_e32 v200, v161
	v_mul_f32_e32 v161, 0xbfb8aa3b, v199
	v_exp_f32_e32 v161, v161
	s_nop 0
	v_add_f32_e32 v161, 1.0, v161
	v_rcp_f32_e32 v201, v161
	s_nop 0
	v_pk_mul_f32 v[198:199], v[198:199], v[200:201]
	v_pk_fma_f32 v[200:201], v[90:91], v[192:193], v[154:155] op_sel_hi:[1,0,1]
	v_cvt_pk_bf16_f32 v196, v198, v199
	v_mul_f32_e32 v161, 0xbfb8aa3b, v200
	v_exp_f32_e32 v161, v161
	s_nop 0
	v_add_f32_e32 v161, 1.0, v161
	v_rcp_f32_e32 v202, v161
	v_mul_f32_e32 v161, 0xbfb8aa3b, v201
	v_exp_f32_e32 v161, v161
	s_nop 0
	v_add_f32_e32 v161, 1.0, v161
	v_rcp_f32_e32 v203, v161
	s_nop 0
	v_pk_mul_f32 v[200:201], v[200:201], v[202:203]
	s_nop 0
	v_cvt_pk_bf16_f32 v197, v200, v201
	global_store_dwordx4 v[190:191], v[194:197], off
	s_nop 1
	v_pk_fma_f32 v[194:195], v[84:85], v[192:193], v[148:149] op_sel_hi:[1,0,1]
	v_pk_fma_f32 v[148:149], v[68:69], v[174:175], v[148:149] op_sel_hi:[1,0,1]
	v_mul_f32_e32 v161, 0xbfb8aa3b, v194
	v_exp_f32_e32 v161, v161
	s_nop 0
	v_add_f32_e32 v161, 1.0, v161
	v_rcp_f32_e32 v196, v161
	v_mul_f32_e32 v161, 0xbfb8aa3b, v195
	v_exp_f32_e32 v161, v161
	s_nop 0
	v_add_f32_e32 v161, 1.0, v161
	v_rcp_f32_e32 v197, v161
	s_nop 0
	v_pk_mul_f32 v[194:195], v[194:195], v[196:197]
	v_pk_fma_f32 v[196:197], v[86:87], v[192:193], v[150:151] op_sel_hi:[1,0,1]
	v_pk_fma_f32 v[150:151], v[70:71], v[174:175], v[150:151] op_sel_hi:[1,0,1]
	v_mul_f32_e32 v161, 0xbfb8aa3b, v196
	v_exp_f32_e32 v161, v161
	s_nop 0
	v_add_f32_e32 v161, 1.0, v161
	v_rcp_f32_e32 v198, v161
	v_mul_f32_e32 v161, 0xbfb8aa3b, v197
	v_exp_f32_e32 v161, v161
	s_nop 0
	v_add_f32_e32 v161, 1.0, v161
	v_rcp_f32_e32 v199, v161
	s_nop 0
	v_pk_mul_f32 v[196:197], v[196:197], v[198:199]
	v_pk_fma_f32 v[198:199], v[80:81], v[192:193], v[144:145] op_sel_hi:[1,0,1]
	v_pk_fma_f32 v[192:193], v[82:83], v[192:193], v[146:147] op_sel_hi:[1,0,1]
	v_mul_f32_e32 v161, 0xbfb8aa3b, v198
	v_exp_f32_e32 v161, v161
	v_pk_fma_f32 v[144:145], v[64:65], v[174:175], v[144:145] op_sel_hi:[1,0,1]
	v_add_f32_e32 v161, 1.0, v161
	v_rcp_f32_e32 v200, v161
	v_mul_f32_e32 v161, 0xbfb8aa3b, v199
	v_exp_f32_e32 v161, v161
	s_nop 0
	v_add_f32_e32 v161, 1.0, v161
	v_rcp_f32_e32 v201, v161
	v_mul_f32_e32 v161, 0xbfb8aa3b, v192
	v_exp_f32_e32 v161, v161
	v_pk_mul_f32 v[198:199], v[198:199], v[200:201]
	v_add_f32_e32 v161, 1.0, v161
	v_rcp_f32_e32 v200, v161
	v_mul_f32_e32 v161, 0xbfb8aa3b, v193
	v_exp_f32_e32 v161, v161
	s_nop 0
	v_add_f32_e32 v161, 1.0, v161
	v_rcp_f32_e32 v201, v161
	v_mul_f32_e32 v161, 0xbfb8aa3b, v156
	v_exp_f32_e32 v161, v161
	v_pk_mul_f32 v[200:201], v[192:193], v[200:201]
	v_cvt_pk_bf16_f32 v192, v194, v195
	v_cvt_pk_bf16_f32 v193, v196, v197
	v_cvt_pk_bf16_f32 v194, v198, v199
	v_cvt_pk_bf16_f32 v195, v200, v201
	v_add_f32_e32 v161, 1.0, v161
	global_store_dwordx4 v[190:191], v[192:195], off offset:256
	v_rcp_f32_e32 v190, v161
	v_mul_f32_e32 v161, 0xbfb8aa3b, v157
	v_exp_f32_e32 v161, v161
	s_nop 0
	v_add_f32_e32 v161, 1.0, v161
	v_rcp_f32_e32 v191, v161
	v_mul_f32_e32 v161, 0xbfb8aa3b, v158
	v_exp_f32_e32 v161, v161
	v_pk_mul_f32 v[156:157], v[156:157], v[190:191]
	v_add_f32_e32 v161, 1.0, v161
	v_rcp_f32_e32 v190, v161
	v_mul_f32_e32 v161, 0xbfb8aa3b, v159
	v_exp_f32_e32 v161, v161
	s_nop 0
	v_add_f32_e32 v161, 1.0, v161
	v_rcp_f32_e32 v191, v161
	v_mul_f32_e32 v161, 0xbfb8aa3b, v152
	v_exp_f32_e32 v161, v161
	v_pk_mul_f32 v[158:159], v[158:159], v[190:191]
	v_add_f32_e32 v161, 1.0, v161
	v_rcp_f32_e32 v190, v161
	v_mul_f32_e32 v161, 0xbfb8aa3b, v153
	v_exp_f32_e32 v161, v161
	s_nop 0
	v_add_f32_e32 v161, 1.0, v161
	v_rcp_f32_e32 v191, v161
	s_nop 0
	v_pk_mul_f32 v[190:191], v[152:153], v[190:191]
	v_pk_fma_f32 v[152:153], v[74:75], v[174:175], v[154:155] op_sel_hi:[1,0,1]
	s_nop 0
	v_mul_f32_e32 v154, 0xbfb8aa3b, v152
	v_mul_f32_e32 v155, 0xbfb8aa3b, v153
	v_exp_f32_e32 v154, v154
	v_exp_f32_e32 v155, v155
	v_add_f32_e32 v154, 1.0, v154
	v_add_f32_e32 v155, 1.0, v155
	v_rcp_f32_e32 v154, v154
	v_rcp_f32_e32 v155, v155
	s_nop 0
	v_pk_mul_f32 v[192:193], v[152:153], v[154:155]
	v_cvt_pk_bf16_f32 v152, v156, v157
	v_cvt_pk_bf16_f32 v153, v158, v159
	v_cvt_pk_bf16_f32 v154, v190, v191
	v_cvt_pk_bf16_f32 v155, v192, v193
	global_store_dwordx4 v[188:189], v[152:155], off
	s_nop 1
	v_mul_f32_e32 v152, 0xbfb8aa3b, v148
	v_mul_f32_e32 v153, 0xbfb8aa3b, v149
	v_exp_f32_e32 v152, v152
	v_exp_f32_e32 v153, v153
	v_add_f32_e32 v152, 1.0, v152
	v_add_f32_e32 v153, 1.0, v153
	v_rcp_f32_e32 v152, v152
	v_rcp_f32_e32 v153, v153
	s_nop 0
	v_pk_mul_f32 v[148:149], v[148:149], v[152:153]
	v_mul_f32_e32 v152, 0xbfb8aa3b, v150
	v_mul_f32_e32 v153, 0xbfb8aa3b, v151
	v_exp_f32_e32 v152, v152
	v_exp_f32_e32 v153, v153
	v_add_f32_e32 v152, 1.0, v152
	v_add_f32_e32 v153, 1.0, v153
	v_rcp_f32_e32 v152, v152
	v_rcp_f32_e32 v153, v153
	s_nop 0
	v_pk_mul_f32 v[150:151], v[150:151], v[152:153]
	v_mul_f32_e32 v152, 0xbfb8aa3b, v144
	v_mul_f32_e32 v153, 0xbfb8aa3b, v145
	v_exp_f32_e32 v152, v152
	v_exp_f32_e32 v153, v153
	v_add_f32_e32 v152, 1.0, v152
	v_add_f32_e32 v153, 1.0, v153
	v_rcp_f32_e32 v152, v152
	v_rcp_f32_e32 v153, v153
	s_nop 0
	v_pk_mul_f32 v[152:153], v[144:145], v[152:153]
	v_pk_fma_f32 v[144:145], v[66:67], v[174:175], v[146:147] op_sel_hi:[1,0,1]
	s_nop 0
	v_mul_f32_e32 v146, 0xbfb8aa3b, v144
	v_mul_f32_e32 v147, 0xbfb8aa3b, v145
	v_exp_f32_e32 v146, v146
	v_exp_f32_e32 v147, v147
	v_add_f32_e32 v146, 1.0, v146
	v_add_f32_e32 v147, 1.0, v147
	v_rcp_f32_e32 v146, v146
	v_rcp_f32_e32 v147, v147
	s_nop 0
	v_pk_mul_f32 v[154:155], v[144:145], v[146:147]
	v_cvt_pk_bf16_f32 v144, v148, v149
	v_cvt_pk_bf16_f32 v145, v150, v151
	v_cvt_pk_bf16_f32 v146, v152, v153
	v_cvt_pk_bf16_f32 v147, v154, v155
	global_store_dwordx4 v[188:189], v[144:147], off offset:256
	s_waitcnt vmcnt(11)
; DI u32x4 pack8(const float* v) { u32x4 w; w.x = pk2(v[0], v[1]); w.y = pk2(v[2], v[3]); w.z = pk2(v[4], v[5]); w.w = pk2(v[6], v[7]); return w; }
; DI float ex2(float x) { return __builtin_amdgcn_exp2f(x); }
; DI float silu(float x) { return x * __builtin_amdgcn_rcpf(1.f + ex2(-x * LOG2E)); }
;     template <int PN> DI void body(AccRef acc, const Unit& u, int wr, int wc, int fr, int fq) const {
;     ...
;                 } else if constexpr (PN == 5 || PN == 6 || PN == 7) {
;                     bf16_t* dst = PN == 5 ? rv : (PN == 6 ? rg : sq);
; #pragma unroll
;                     for (int bj = 0; bj < 2; ++bj) {
;                         if constexpr (PN == 6) {
; #pragma unroll
;                             for (int j = 0; j < 8; ++j) v[bj][j] = silu(v[bj][j]);
;                         }
;                         if constexpr (PN == 7) {
; #pragma unroll
;                             for (int j = 0; j < 8; ++j) v[bj][j] *= 0.125f;
;                         }
;                         *(u32x4*)(dst + (size_t)row * 256 + bj * 128 + cl) = pack8(v[bj]);
;                     }
	s_nop 0
	v_pk_fma_f32 v[146:147], v[60:61], v[170:171], v[140:141] op_sel_hi:[1,0,1]
	v_lshlrev_b64 v[144:145], 9, v[172:173]
	v_mul_f32_e32 v148, 0xbfb8aa3b, v146
	v_mul_f32_e32 v149, 0xbfb8aa3b, v147
	v_exp_f32_e32 v148, v148
	v_exp_f32_e32 v149, v149
	v_lshl_add_u64 v[144:145], v[168:169], 0, v[144:145]
	v_add_f32_e32 v148, 1.0, v148
	v_add_f32_e32 v149, 1.0, v149
	v_rcp_f32_e32 v148, v148
	v_rcp_f32_e32 v149, v149
	s_nop 0
	v_pk_mul_f32 v[146:147], v[146:147], v[148:149]
	v_pk_fma_f32 v[148:149], v[62:63], v[170:171], v[142:143] op_sel_hi:[1,0,1]
	v_cvt_pk_bf16_f32 v146, v146, v147
	v_mul_f32_e32 v150, 0xbfb8aa3b, v148
	v_mul_f32_e32 v151, 0xbfb8aa3b, v149
	v_exp_f32_e32 v150, v150
	v_exp_f32_e32 v151, v151
	v_add_f32_e32 v150, 1.0, v150
	v_add_f32_e32 v151, 1.0, v151
	v_rcp_f32_e32 v150, v150
	v_rcp_f32_e32 v151, v151
	s_nop 0
	v_pk_mul_f32 v[148:149], v[148:149], v[150:151]
	s_waitcnt vmcnt(10)
	v_pk_fma_f32 v[150:151], v[56:57], v[170:171], v[136:137] op_sel_hi:[1,0,1]
	v_cvt_pk_bf16_f32 v147, v148, v149
	v_mul_f32_e32 v152, 0xbfb8aa3b, v150
	v_mul_f32_e32 v153, 0xbfb8aa3b, v151
	v_exp_f32_e32 v152, v152
	v_exp_f32_e32 v153, v153
	v_add_f32_e32 v152, 1.0, v152
	v_add_f32_e32 v153, 1.0, v153
	v_rcp_f32_e32 v152, v152
	v_rcp_f32_e32 v153, v153
	s_nop 0
	v_pk_mul_f32 v[150:151], v[150:151], v[152:153]
	v_pk_fma_f32 v[152:153], v[58:59], v[170:171], v[138:139] op_sel_hi:[1,0,1]
	v_cvt_pk_bf16_f32 v148, v150, v151
	v_mul_f32_e32 v154, 0xbfb8aa3b, v152
	v_mul_f32_e32 v155, 0xbfb8aa3b, v153
	v_exp_f32_e32 v154, v154
	v_exp_f32_e32 v155, v155
	v_add_f32_e32 v154, 1.0, v154
	v_add_f32_e32 v155, 1.0, v155
	v_rcp_f32_e32 v154, v154
	v_rcp_f32_e32 v155, v155
	s_nop 0
	v_pk_mul_f32 v[152:153], v[152:153], v[154:155]
	s_nop 0
	v_cvt_pk_bf16_f32 v149, v152, v153
	global_store_dwordx4 v[144:145], v[146:149], off
	s_waitcnt vmcnt(9)
	s_nop 0
	v_pk_fma_f32 v[146:147], v[52:53], v[170:171], v[132:133] op_sel_hi:[1,0,1]
	s_nop 0
	v_mul_f32_e32 v148, 0xbfb8aa3b, v146
	v_mul_f32_e32 v149, 0xbfb8aa3b, v147
	v_exp_f32_e32 v148, v148
	v_exp_f32_e32 v149, v149
	v_add_f32_e32 v148, 1.0, v148
	v_add_f32_e32 v149, 1.0, v149
	v_rcp_f32_e32 v148, v148
	v_rcp_f32_e32 v149, v149
	s_nop 0
	v_pk_mul_f32 v[146:147], v[146:147], v[148:149]
	v_pk_fma_f32 v[148:149], v[54:55], v[170:171], v[134:135] op_sel_hi:[1,0,1]
	v_cvt_pk_bf16_f32 v146, v146, v147
	v_mul_f32_e32 v150, 0xbfb8aa3b, v148
	v_mul_f32_e32 v151, 0xbfb8aa3b, v149
	v_exp_f32_e32 v150, v150
	v_exp_f32_e32 v151, v151
	v_add_f32_e32 v150, 1.0, v150
	v_add_f32_e32 v151, 1.0, v151
	v_rcp_f32_e32 v150, v150
	v_rcp_f32_e32 v151, v151
	s_nop 0
	v_pk_mul_f32 v[148:149], v[148:149], v[150:151]
	v_pk_fma_f32 v[150:151], v[48:49], v[170:171], v[128:129] op_sel_hi:[1,0,1]
	v_cvt_pk_bf16_f32 v147, v148, v149
	v_mul_f32_e32 v152, 0xbfb8aa3b, v150
	v_mul_f32_e32 v153, 0xbfb8aa3b, v151
	v_exp_f32_e32 v152, v152
	v_exp_f32_e32 v153, v153
	v_add_f32_e32 v152, 1.0, v152
	v_add_f32_e32 v153, 1.0, v153
	v_rcp_f32_e32 v152, v152
	v_rcp_f32_e32 v153, v153
	s_nop 0
	v_pk_mul_f32 v[150:151], v[150:151], v[152:153]
	v_pk_fma_f32 v[152:153], v[50:51], v[170:171], v[130:131] op_sel_hi:[1,0,1]
	v_cvt_pk_bf16_f32 v148, v150, v151
	v_mul_f32_e32 v154, 0xbfb8aa3b, v152
	v_mul_f32_e32 v155, 0xbfb8aa3b, v153
	v_exp_f32_e32 v154, v154
	v_exp_f32_e32 v155, v155
	v_add_f32_e32 v154, 1.0, v154
	v_add_f32_e32 v155, 1.0, v155
	v_rcp_f32_e32 v154, v154
	v_rcp_f32_e32 v155, v155
	s_nop 0
	v_pk_mul_f32 v[152:153], v[152:153], v[154:155]
	s_nop 0
	v_cvt_pk_bf16_f32 v149, v152, v153
	global_store_dwordx4 v[144:145], v[146:149], off offset:256
	v_add_u32_e32 v144, 0x90, v160
	v_ashrrev_i32_e32 v145, 31, v144
	v_pk_fma_f32 v[146:147], v[44:45], v[164:165], v[140:141] op_sel_hi:[1,0,1]
	v_lshlrev_b64 v[144:145], 9, v[144:145]
	v_mul_f32_e32 v148, 0xbfb8aa3b, v146
	v_mul_f32_e32 v149, 0xbfb8aa3b, v147
	v_exp_f32_e32 v148, v148
	v_exp_f32_e32 v149, v149
	v_lshl_add_u64 v[144:145], v[168:169], 0, v[144:145]
	v_add_f32_e32 v148, 1.0, v148
	v_add_f32_e32 v149, 1.0, v149
	v_rcp_f32_e32 v148, v148
	v_rcp_f32_e32 v149, v149
	s_nop 0
	v_pk_mul_f32 v[146:147], v[146:147], v[148:149]
	v_pk_fma_f32 v[148:149], v[46:47], v[164:165], v[142:143] op_sel_hi:[1,0,1]
	v_cvt_pk_bf16_f32 v146, v146, v147
	v_mul_f32_e32 v150, 0xbfb8aa3b, v148
	v_mul_f32_e32 v151, 0xbfb8aa3b, v149
	v_exp_f32_e32 v150, v150
	v_exp_f32_e32 v151, v151
	v_add_f32_e32 v150, 1.0, v150
	v_add_f32_e32 v151, 1.0, v151
	v_rcp_f32_e32 v150, v150
	v_rcp_f32_e32 v151, v151
	s_nop 0
	v_pk_mul_f32 v[148:149], v[148:149], v[150:151]
	v_pk_fma_f32 v[150:151], v[40:41], v[164:165], v[136:137] op_sel_hi:[1,0,1]
	v_cvt_pk_bf16_f32 v147, v148, v149
	v_mul_f32_e32 v152, 0xbfb8aa3b, v150
	v_mul_f32_e32 v153, 0xbfb8aa3b, v151
	v_exp_f32_e32 v152, v152
	v_exp_f32_e32 v153, v153
	v_add_f32_e32 v152, 1.0, v152
	v_add_f32_e32 v153, 1.0, v153
	v_rcp_f32_e32 v152, v152
	v_rcp_f32_e32 v153, v153
	s_nop 0
	v_pk_mul_f32 v[150:151], v[150:151], v[152:153]
	v_pk_fma_f32 v[152:153], v[42:43], v[164:165], v[138:139] op_sel_hi:[1,0,1]
	v_cvt_pk_bf16_f32 v148, v150, v151
	v_mul_f32_e32 v154, 0xbfb8aa3b, v152
	v_mul_f32_e32 v155, 0xbfb8aa3b, v153
	v_exp_f32_e32 v154, v154
	v_exp_f32_e32 v155, v155
	v_add_f32_e32 v154, 1.0, v154
	v_add_f32_e32 v155, 1.0, v155
	v_rcp_f32_e32 v154, v154
	v_rcp_f32_e32 v155, v155
	s_nop 0
	v_pk_mul_f32 v[152:153], v[152:153], v[154:155]
	s_nop 0
	v_cvt_pk_bf16_f32 v149, v152, v153
	global_store_dwordx4 v[144:145], v[146:149], off
	s_nop 1
	v_pk_fma_f32 v[146:147], v[36:37], v[164:165], v[132:133] op_sel_hi:[1,0,1]
	s_nop 0
	v_mul_f32_e32 v148, 0xbfb8aa3b, v146
	v_mul_f32_e32 v149, 0xbfb8aa3b, v147
; DI u32x4 pack8(const float* v) { u32x4 w; w.x = pk2(v[0], v[1]); w.y = pk2(v[2], v[3]); w.z = pk2(v[4], v[5]); w.w = pk2(v[6], v[7]); return w; }
; DI float ex2(float x) { return __builtin_amdgcn_exp2f(x); }
; DI float silu(float x) { return x * __builtin_amdgcn_rcpf(1.f + ex2(-x * LOG2E)); }
;     template <int PN> DI void body(AccRef acc, const Unit& u, int wr, int wc, int fr, int fq) const {
;     ...
;                 } else if constexpr (PN == 5 || PN == 6 || PN == 7) {
;                     bf16_t* dst = PN == 5 ? rv : (PN == 6 ? rg : sq);
; #pragma unroll
;                     for (int bj = 0; bj < 2; ++bj) {
;                         if constexpr (PN == 6) {
; #pragma unroll
;                             for (int j = 0; j < 8; ++j) v[bj][j] = silu(v[bj][j]);
;                         }
;                         if constexpr (PN == 7) {
; #pragma unroll
;                             for (int j = 0; j < 8; ++j) v[bj][j] *= 0.125f;
;                         }
;                         *(u32x4*)(dst + (size_t)row * 256 + bj * 128 + cl) = pack8(v[bj]);
;                     }
	v_exp_f32_e32 v148, v148
	v_exp_f32_e32 v149, v149
	v_add_f32_e32 v148, 1.0, v148
	v_add_f32_e32 v149, 1.0, v149
	v_rcp_f32_e32 v148, v148
	v_rcp_f32_e32 v149, v149
	s_nop 0
	v_pk_mul_f32 v[146:147], v[146:147], v[148:149]
	v_pk_fma_f32 v[148:149], v[38:39], v[164:165], v[134:135] op_sel_hi:[1,0,1]
	v_cvt_pk_bf16_f32 v146, v146, v147
	v_mul_f32_e32 v150, 0xbfb8aa3b, v148
	v_mul_f32_e32 v151, 0xbfb8aa3b, v149
	v_exp_f32_e32 v150, v150
	v_exp_f32_e32 v151, v151
	v_add_f32_e32 v150, 1.0, v150
	v_add_f32_e32 v151, 1.0, v151
	v_rcp_f32_e32 v150, v150
	v_rcp_f32_e32 v151, v151
	s_nop 0
	v_pk_mul_f32 v[148:149], v[148:149], v[150:151]
	v_pk_fma_f32 v[150:151], v[28:29], v[164:165], v[128:129] op_sel_hi:[1,0,1]
	v_cvt_pk_bf16_f32 v147, v148, v149
	v_mul_f32_e32 v152, 0xbfb8aa3b, v150
	v_mul_f32_e32 v153, 0xbfb8aa3b, v151
	v_exp_f32_e32 v152, v152
	v_exp_f32_e32 v153, v153
	v_add_f32_e32 v152, 1.0, v152
	v_add_f32_e32 v153, 1.0, v153
	v_rcp_f32_e32 v152, v152
	v_rcp_f32_e32 v153, v153
	s_nop 0
	v_pk_mul_f32 v[150:151], v[150:151], v[152:153]
	v_pk_fma_f32 v[152:153], v[30:31], v[164:165], v[130:131] op_sel_hi:[1,0,1]
	v_cvt_pk_bf16_f32 v148, v150, v151
	v_mul_f32_e32 v154, 0xbfb8aa3b, v152
	v_mul_f32_e32 v155, 0xbfb8aa3b, v153
	v_exp_f32_e32 v154, v154
	v_exp_f32_e32 v155, v155
	v_add_f32_e32 v154, 1.0, v154
	v_add_f32_e32 v155, 1.0, v155
	v_rcp_f32_e32 v154, v154
	v_rcp_f32_e32 v155, v155
	s_nop 0
	v_pk_mul_f32 v[152:153], v[152:153], v[154:155]
	s_nop 0
	v_cvt_pk_bf16_f32 v149, v152, v153
	global_store_dwordx4 v[144:145], v[146:149], off offset:256
	v_add_u32_e32 v144, 0xa0, v160
	v_ashrrev_i32_e32 v145, 31, v144
	v_pk_fma_f32 v[146:147], v[32:33], v[166:167], v[140:141] op_sel_hi:[1,0,1]
	v_lshlrev_b64 v[144:145], 9, v[144:145]
	v_mul_f32_e32 v148, 0xbfb8aa3b, v146
	v_mul_f32_e32 v149, 0xbfb8aa3b, v147
	v_exp_f32_e32 v148, v148
	v_exp_f32_e32 v149, v149
	v_lshl_add_u64 v[144:145], v[168:169], 0, v[144:145]
	v_pk_fma_f32 v[140:141], v[12:13], v[162:163], v[140:141] op_sel_hi:[1,0,1]
	v_add_f32_e32 v148, 1.0, v148
	v_add_f32_e32 v149, 1.0, v149
	v_rcp_f32_e32 v148, v148
	v_rcp_f32_e32 v149, v149
	s_nop 0
	v_pk_mul_f32 v[146:147], v[146:147], v[148:149]
	v_pk_fma_f32 v[148:149], v[34:35], v[166:167], v[142:143] op_sel_hi:[1,0,1]
	v_cvt_pk_bf16_f32 v146, v146, v147
	v_mul_f32_e32 v150, 0xbfb8aa3b, v148
	v_mul_f32_e32 v151, 0xbfb8aa3b, v149
	v_exp_f32_e32 v150, v150
	v_exp_f32_e32 v151, v151
	v_pk_fma_f32 v[142:143], v[14:15], v[162:163], v[142:143] op_sel_hi:[1,0,1]
	v_add_f32_e32 v150, 1.0, v150
	v_add_f32_e32 v151, 1.0, v151
	v_rcp_f32_e32 v150, v150
	v_rcp_f32_e32 v151, v151
	s_nop 0
	v_pk_mul_f32 v[148:149], v[148:149], v[150:151]
	v_pk_fma_f32 v[150:151], v[24:25], v[166:167], v[136:137] op_sel_hi:[1,0,1]
	v_cvt_pk_bf16_f32 v147, v148, v149
	v_mul_f32_e32 v152, 0xbfb8aa3b, v150
	v_mul_f32_e32 v153, 0xbfb8aa3b, v151
	v_exp_f32_e32 v152, v152
	v_exp_f32_e32 v153, v153
	v_pk_fma_f32 v[136:137], v[8:9], v[162:163], v[136:137] op_sel_hi:[1,0,1]
	v_add_f32_e32 v152, 1.0, v152
	v_add_f32_e32 v153, 1.0, v153
	v_rcp_f32_e32 v152, v152
	v_rcp_f32_e32 v153, v153
	s_nop 0
	v_pk_mul_f32 v[150:151], v[150:151], v[152:153]
	v_pk_fma_f32 v[152:153], v[26:27], v[166:167], v[138:139] op_sel_hi:[1,0,1]
	v_cvt_pk_bf16_f32 v148, v150, v151
	v_mul_f32_e32 v154, 0xbfb8aa3b, v152
	v_mul_f32_e32 v155, 0xbfb8aa3b, v153
	v_exp_f32_e32 v154, v154
	v_exp_f32_e32 v155, v155
	v_add_f32_e32 v154, 1.0, v154
	v_add_f32_e32 v155, 1.0, v155
	v_rcp_f32_e32 v154, v154
	v_rcp_f32_e32 v155, v155
	s_nop 0
	v_pk_mul_f32 v[152:153], v[152:153], v[154:155]
	s_nop 0
	v_cvt_pk_bf16_f32 v149, v152, v153
	global_store_dwordx4 v[144:145], v[146:149], off
	s_nop 1
	v_pk_fma_f32 v[146:147], v[20:21], v[166:167], v[132:133] op_sel_hi:[1,0,1]
	v_pk_fma_f32 v[132:133], v[4:5], v[162:163], v[132:133] op_sel_hi:[1,0,1]
	v_mul_f32_e32 v148, 0xbfb8aa3b, v146
	v_mul_f32_e32 v149, 0xbfb8aa3b, v147
	v_exp_f32_e32 v148, v148
	v_exp_f32_e32 v149, v149
	v_add_f32_e32 v148, 1.0, v148
	v_add_f32_e32 v149, 1.0, v149
	v_rcp_f32_e32 v148, v148
	v_rcp_f32_e32 v149, v149
	s_nop 0
	v_pk_mul_f32 v[146:147], v[146:147], v[148:149]
	v_pk_fma_f32 v[148:149], v[22:23], v[166:167], v[134:135] op_sel_hi:[1,0,1]
	v_cvt_pk_bf16_f32 v146, v146, v147
	v_mul_f32_e32 v150, 0xbfb8aa3b, v148
	v_mul_f32_e32 v151, 0xbfb8aa3b, v149
	v_exp_f32_e32 v150, v150
	v_exp_f32_e32 v151, v151
; DI u32x4 pack8(const float* v) { u32x4 w; w.x = pk2(v[0], v[1]); w.y = pk2(v[2], v[3]); w.z = pk2(v[4], v[5]); w.w = pk2(v[6], v[7]); return w; }
; DI float ex2(float x) { return __builtin_amdgcn_exp2f(x); }
; DI float silu(float x) { return x * __builtin_amdgcn_rcpf(1.f + ex2(-x * LOG2E)); }
;     template <int PN> DI void body(AccRef acc, const Unit& u, int wr, int wc, int fr, int fq) const {
;     ...
;                 } else if constexpr (PN == 5 || PN == 6 || PN == 7) {
;                     bf16_t* dst = PN == 5 ? rv : (PN == 6 ? rg : sq);
; #pragma unroll
;                     for (int bj = 0; bj < 2; ++bj) {
;                         if constexpr (PN == 6) {
; #pragma unroll
;                             for (int j = 0; j < 8; ++j) v[bj][j] = silu(v[bj][j]);
;                         }
;                         if constexpr (PN == 7) {
; #pragma unroll
;                             for (int j = 0; j < 8; ++j) v[bj][j] *= 0.125f;
;                         }
;                         *(u32x4*)(dst + (size_t)row * 256 + bj * 128 + cl) = pack8(v[bj]);
;                     }
	v_pk_fma_f32 v[134:135], v[6:7], v[162:163], v[134:135] op_sel_hi:[1,0,1]
	v_add_f32_e32 v150, 1.0, v150
	v_add_f32_e32 v151, 1.0, v151
	v_rcp_f32_e32 v150, v150
	v_rcp_f32_e32 v151, v151
	s_nop 0
	v_pk_mul_f32 v[148:149], v[148:149], v[150:151]
	v_pk_fma_f32 v[150:151], v[16:17], v[166:167], v[128:129] op_sel_hi:[1,0,1]
	v_cvt_pk_bf16_f32 v147, v148, v149
	v_mul_f32_e32 v152, 0xbfb8aa3b, v150
	v_mul_f32_e32 v153, 0xbfb8aa3b, v151
	v_exp_f32_e32 v152, v152
	v_exp_f32_e32 v153, v153
	v_pk_fma_f32 v[128:129], v[0:1], v[162:163], v[128:129] op_sel_hi:[1,0,1]
	v_add_f32_e32 v152, 1.0, v152
	v_add_f32_e32 v153, 1.0, v153
	v_rcp_f32_e32 v152, v152
	v_rcp_f32_e32 v153, v153
	s_nop 0
	v_pk_mul_f32 v[150:151], v[150:151], v[152:153]
	v_pk_fma_f32 v[152:153], v[18:19], v[166:167], v[130:131] op_sel_hi:[1,0,1]
	v_cvt_pk_bf16_f32 v148, v150, v151
	v_mul_f32_e32 v154, 0xbfb8aa3b, v152
	v_mul_f32_e32 v155, 0xbfb8aa3b, v153
	v_exp_f32_e32 v154, v154
	v_exp_f32_e32 v155, v155
	v_add_f32_e32 v154, 1.0, v154
	v_add_f32_e32 v155, 1.0, v155
	v_rcp_f32_e32 v154, v154
	v_rcp_f32_e32 v155, v155
	s_nop 0
	v_pk_mul_f32 v[152:153], v[152:153], v[154:155]
	s_nop 0
	v_cvt_pk_bf16_f32 v149, v152, v153
	global_store_dwordx4 v[144:145], v[146:149], off offset:256
	v_add_u32_e32 v144, 0xb0, v160
	v_ashrrev_i32_e32 v145, 31, v144
	v_mul_f32_e32 v146, 0xbfb8aa3b, v140
	v_mul_f32_e32 v147, 0xbfb8aa3b, v141
	v_exp_f32_e32 v146, v146
	v_exp_f32_e32 v147, v147
	v_lshlrev_b64 v[144:145], 9, v[144:145]
	v_lshl_add_u64 v[144:145], v[168:169], 0, v[144:145]
	v_add_f32_e32 v146, 1.0, v146
	v_add_f32_e32 v147, 1.0, v147
	v_rcp_f32_e32 v146, v146
	v_rcp_f32_e32 v147, v147
	s_nop 0
	v_pk_mul_f32 v[140:141], v[140:141], v[146:147]
	v_mul_f32_e32 v146, 0xbfb8aa3b, v142
	v_mul_f32_e32 v147, 0xbfb8aa3b, v143
	v_exp_f32_e32 v146, v146
	v_exp_f32_e32 v147, v147
	v_add_f32_e32 v146, 1.0, v146
	v_add_f32_e32 v147, 1.0, v147
	v_rcp_f32_e32 v146, v146
	v_rcp_f32_e32 v147, v147
	s_nop 0
	v_pk_mul_f32 v[142:143], v[142:143], v[146:147]
	v_mul_f32_e32 v146, 0xbfb8aa3b, v136
	v_mul_f32_e32 v147, 0xbfb8aa3b, v137
	v_exp_f32_e32 v146, v146
	v_exp_f32_e32 v147, v147
	v_add_f32_e32 v146, 1.0, v146
	v_add_f32_e32 v147, 1.0, v147
	v_rcp_f32_e32 v146, v146
	v_rcp_f32_e32 v147, v147
	s_nop 0
	v_pk_mul_f32 v[146:147], v[136:137], v[146:147]
	v_pk_fma_f32 v[136:137], v[10:11], v[162:163], v[138:139] op_sel_hi:[1,0,1]
	s_nop 0
	v_mul_f32_e32 v138, 0xbfb8aa3b, v136
	v_mul_f32_e32 v139, 0xbfb8aa3b, v137
	v_exp_f32_e32 v138, v138
	v_exp_f32_e32 v139, v139
	v_add_f32_e32 v138, 1.0, v138
	v_add_f32_e32 v139, 1.0, v139
	v_rcp_f32_e32 v138, v138
	v_rcp_f32_e32 v139, v139
	s_nop 0
	v_pk_mul_f32 v[148:149], v[136:137], v[138:139]
	v_cvt_pk_bf16_f32 v136, v140, v141
	v_cvt_pk_bf16_f32 v137, v142, v143
	v_cvt_pk_bf16_f32 v138, v146, v147
	v_cvt_pk_bf16_f32 v139, v148, v149
	global_store_dwordx4 v[144:145], v[136:139], off
	s_nop 1
	v_mul_f32_e32 v136, 0xbfb8aa3b, v132
	v_mul_f32_e32 v137, 0xbfb8aa3b, v133
	v_exp_f32_e32 v136, v136
	v_exp_f32_e32 v137, v137
	v_add_f32_e32 v136, 1.0, v136
	v_add_f32_e32 v137, 1.0, v137
	v_rcp_f32_e32 v136, v136
	v_rcp_f32_e32 v137, v137
	s_nop 0
	v_pk_mul_f32 v[132:133], v[132:133], v[136:137]
	v_mul_f32_e32 v136, 0xbfb8aa3b, v134
	v_mul_f32_e32 v137, 0xbfb8aa3b, v135
	v_exp_f32_e32 v136, v136
	v_exp_f32_e32 v137, v137
	v_add_f32_e32 v136, 1.0, v136
	v_add_f32_e32 v137, 1.0, v137
	v_rcp_f32_e32 v136, v136
	v_rcp_f32_e32 v137, v137
	s_nop 0
	v_pk_mul_f32 v[134:135], v[134:135], v[136:137]
	v_mul_f32_e32 v136, 0xbfb8aa3b, v128
	v_mul_f32_e32 v137, 0xbfb8aa3b, v129
	v_exp_f32_e32 v136, v136
	v_exp_f32_e32 v137, v137
	v_add_f32_e32 v136, 1.0, v136
	v_add_f32_e32 v137, 1.0, v137
	v_rcp_f32_e32 v136, v136
	v_rcp_f32_e32 v137, v137
	s_nop 0
	v_pk_mul_f32 v[136:137], v[128:129], v[136:137]
	v_pk_fma_f32 v[128:129], v[2:3], v[162:163], v[130:131] op_sel_hi:[1,0,1]
	s_nop 0
	v_mul_f32_e32 v130, 0xbfb8aa3b, v128
	v_mul_f32_e32 v131, 0xbfb8aa3b, v129
	v_exp_f32_e32 v130, v130
	v_exp_f32_e32 v131, v131
	v_add_f32_e32 v130, 1.0, v130
	v_add_f32_e32 v131, 1.0, v131
	v_rcp_f32_e32 v130, v130
	v_rcp_f32_e32 v131, v131
	s_nop 0
	v_pk_mul_f32 v[138:139], v[128:129], v[130:131]
	v_cvt_pk_bf16_f32 v128, v132, v133
	v_cvt_pk_bf16_f32 v129, v134, v135
	v_cvt_pk_bf16_f32 v130, v136, v137
	v_cvt_pk_bf16_f32 v131, v138, v139
	global_store_dwordx4 v[144:145], v[128:131], off offset:256

; DI float silu(float x) { return x * __builtin_amdgcn_rcpf(1.f + ex2(-x * LOG2E)); }
;     template <int PN> DI void body(AccRef acc, const Unit& u, int wr, int wc, int fr, int fq) const {
;     ...
;         float rinvh[2][4];
;         f32x4 cvh[2][2][2];
;         int zdep = 0;
; #pragma unroll
;         for (int ai = 0; ai < 2; ++ai) {
;             const int rb_ = u.pm * 256 + ai * 128 + wr * 64 + fr;
; #pragma unroll
;             for (int m = 0; m < 4; ++m) rinvh[ai][m] = rsqrtf(sum16(ssq + (size_t)(rb_ + 16 * m + zdep) * 16) * (1.f / 1024.f) + EPS);
;             asm volatile("v_mov_b32 %0, 0" : "=v"(zdep) : "v"(rinvh[ai][0]), "v"(rinvh[ai][1]), "v"(rinvh[ai][2]), "v"(rinvh[ai][3]));
;         }
; #pragma unroll
;         for (int ai = 0; ai < 2; ++ai) {
;             const int rb_ = u.pm * 256 + ai * 128 + wr * 64 + fr;
;             int mb_, p_, k_; row_info(rb_, mb_, p_, k_);
; #pragma unroll
;             for (int bj = 0; bj < 2; ++bj)
; #pragma unroll
;                 for (int n = 0; n < 2; ++n) cvh[ai][bj][n] = *(const f32x4*)(cv + (size_t)(mb_ + zdep) * NIN + PN * 256 + bj * 128 + cl + 4 * n);
;         }
; #pragma unroll
;         for (int ai = 0; ai < 2; ++ai) {
;             const int rb = u.pm * 256 + ai * 128 + wr * 64 + fr;
;             int mb, pos0, kv0; row_info(rb, mb, pos0, kv0);
; #pragma unroll
;             for (int m = 0; m < 4; ++m) {
;                 const int row = rb + 16 * m, pos = pos0 + 16 * m, kvrow = kv0 + 16 * m;
;                 const float rinv = rinvh[ai][m];
;                 float v[2][8];
; #pragma unroll
;                 for (int bj = 0; bj < 2; ++bj)
; #pragma unroll
;                     for (int n = 0; n < 2; ++n)
; #pragma unroll
;                         for (int j = 0; j < 4; ++j) v[bj][4 * n + j] = acc[ai][bj][m][n][j] * rinv + cvh[ai][bj][n][j];
;     ...
;                 } else if constexpr (PN == 5 || PN == 6 || PN == 7) {
;                     bf16_t* dst = PN == 5 ? rv : (PN == 6 ? rg : sq);
; #pragma unroll
;                     for (int bj = 0; bj < 2; ++bj) {
;                         if constexpr (PN == 6) {
; #pragma unroll
;                             for (int j = 0; j < 8; ++j) v[bj][j] = silu(v[bj][j]);
;                         }
;                         if constexpr (PN == 7) {
; #pragma unroll
;                             for (int j = 0; j < 8; ++j) v[bj][j] *= 0.125f;
;                         }
.LBB0_1738:
	s_and_b64 vcc, exec, s[4:5]
	s_cbranch_vccz .LBB0_1743
	s_cmp_gt_i32 s66, 4
	s_mov_b64 s[4:5], -1
	s_cbranch_scc0 .LBB0_1741
	s_lshl_b32 s4, s43, 6
	s_lshl_b32 s5, s34, 8
	s_add_i32 s4, s4, s5
	v_add_u32_e32 v160, s4, v214
	v_ashrrev_i32_e32 v161, 31, v160
	v_lshlrev_b64 v[128:129], 6, v[160:161]
	v_lshl_add_u64 v[140:141], s[70:71], 0, v[128:129]
	s_nop 0
	v_add_u32_e32 v166, 16, v160
	v_ashrrev_i32_e32 v167, 31, v166
	s_mov_b32 s4, 0x358637bd
	s_mov_b32 s6, 0x3a800000
	v_add_u32_e32 v162, 32, v160
	v_ashrrev_i32_e32 v163, 31, v162
	v_add_u32_e32 v164, 48, v160
	v_ashrrev_i32_e32 v165, 31, v164
	v_add_u32_e32 v174, 0x80, v160
	s_mov_b64 s[8:9], 0x125400
	v_lshlrev_b64 v[222:223], 9, v[160:161]
	v_ashrrev_i32_e32 v175, 31, v174
	s_nop 0
	v_lshlrev_b64 v[128:129], 6, v[166:167]
	v_lshl_add_u64 v[140:141], s[70:71], 0, v[128:129]
	s_nop 0
	v_lshlrev_b64 v[166:167], 9, v[166:167]
	s_nop 0
	v_mov_b64_e32 v[128:129], s[4:5]
	s_nop 0
	s_nop 0
	s_nop 0
	v_mov_b32_e32 v170, v244
	s_nop 0
	v_mov_b32_e32 v168, v245
	v_lshlrev_b64 v[130:131], 6, v[162:163]
	v_lshl_add_u64 v[142:143], s[70:71], 0, v[130:131]
	s_nop 0
	v_lshlrev_b64 v[162:163], 9, v[162:163]
	s_nop 0
	v_lshlrev_b64 v[130:131], 6, v[164:165]
	v_lshl_add_u64 v[142:143], s[70:71], 0, v[130:131]
	s_nop 0
	s_nop 0
	s_nop 0
	s_nop 0
	s_nop 0
	s_nop 0
	v_mov_b32_e32 v172, v246
	s_nop 0
	v_mov_b32_e32 v188, v247
	v_mov_b32 v130, 0
	s_nop 0
	v_add_u32_e32 v130, v130, v174
	v_ashrrev_i32_e32 v131, 31, v130
	v_lshlrev_b64 v[132:133], 6, v[130:131]
	v_lshl_add_u64 v[144:145], s[70:71], 0, v[132:133]
	s_nop 0
	s_nop 0
	v_add_u32_e32 v132, 16, v130
	v_ashrrev_i32_e32 v133, 31, v132
	v_lshlrev_b64 v[132:133], 6, v[132:133]
	v_lshl_add_u64 v[144:145], s[70:71], 0, v[132:133]
	s_nop 0
	s_nop 0
	s_nop 0
	s_nop 0
	s_nop 0
	s_nop 0
	v_mov_b32_e32 v192, v248
	s_nop 0
	v_mov_b32_e32 v190, v249
	v_add_u32_e32 v132, 32, v130
	v_ashrrev_i32_e32 v133, 31, v132
	v_lshlrev_b64 v[132:133], 6, v[132:133]
	v_lshl_add_u64 v[144:145], s[70:71], 0, v[132:133]
	s_nop 0
	v_add_u32_e32 v130, 48, v130
	v_ashrrev_i32_e32 v131, 31, v130
	v_lshlrev_b64 v[130:131], 6, v[130:131]
	v_lshl_add_u64 v[142:143], s[70:71], 0, v[130:131]
	s_nop 0
	s_nop 0
	s_nop 0
	s_movk_i32 s6, 0x2800
	s_mov_b32 s7, 0x125000
	s_nop 0
	v_mov_b32_e32 v194, v250
	s_lshl_b32 s4, s54, 5
	v_lshl_add_u32 v198, v213, 3, s4
	v_ashrrev_i32_e32 v199, 31, v198
	v_mov_b32_e32 v196, v251
	v_add_u32_e32 v129, 0xffffc000, v160
	v_lshrrev_b32_e32 v129, 6, v129
	v_cmp_gt_i32_e32 vcc, s94, v160
	v_ashrrev_i32_e32 v128, 11, v160
	v_add_u32_e32 v129, 8, v129
	v_cndmask_b32_e32 v128, v129, v128, vcc
	v_mov_b32 v136, 0
	v_lshlrev_b64 v[132:133], 2, v[198:199]
	v_add_u32_e32 v130, v136, v128
	v_mov_b64_e32 v[128:129], s[60:61]
	v_mad_i64_i32 v[130:131], s[4:5], v130, s6, v[128:129]
	v_lshl_add_u64 v[130:131], v[130:131], 0, v[132:133]
	v_lshl_add_u64 v[134:135], v[130:131], 0, s[8:9]
	v_add_co_u32_e32 v130, vcc, s7, v130
	s_nop 1
	v_addc_co_u32_e32 v131, vcc, 0, v131, vcc
	global_load_dwordx4 v[148:151], v[130:131], off offset:1024
	global_load_dwordx4 v[152:155], v[134:135], off offset:16
	global_load_dwordx4 v[144:147], v[134:135], off offset:528
	global_load_dwordx4 v[156:159], v[134:135], off offset:512
	v_add_u32_e32 v131, 0xffffc080, v160
	v_lshrrev_b32_e32 v131, 6, v131
	v_cmp_gt_i32_e32 vcc, s94, v174
	v_ashrrev_i32_e32 v130, 11, v174
	v_add_u32_e32 v131, 8, v131
	v_cndmask_b32_e32 v130, v131, v130, vcc
	v_add_u32_e32 v130, v136, v130
	v_mad_i64_i32 v[128:129], s[4:5], v130, s6, v[128:129]
	v_lshl_add_u64 v[128:129], v[128:129], 0, v[132:133]
	v_lshl_add_u64 v[132:133], v[128:129], 0, s[8:9]
	v_add_co_u32_e32 v128, vcc, s7, v128
	v_readlane_b32 s4, v254, 42
	s_nop 0
	v_addc_co_u32_e32 v129, vcc, 0, v129, vcc
	global_load_dwordx4 v[140:143], v[128:129], off offset:1024
	global_load_dwordx4 v[136:139], v[132:133], off offset:16
	s_nop 0
	global_load_dwordx4 v[128:131], v[132:133], off offset:528
	s_nop 0
	global_load_dwordx4 v[132:135], v[132:133], off offset:512
	v_readlane_b32 s5, v254, 43
	s_waitcnt vmcnt(7)
	v_pk_fma_f32 v[200:201], v[124:125], v[170:171], v[148:149] op_sel_hi:[1,0,1]
	v_lshl_add_u64 v[198:199], v[198:199], 1, s[4:5]
	v_pk_fma_f32 v[202:203], v[126:127], v[170:171], v[150:151] op_sel_hi:[1,0,1]
	s_waitcnt vmcnt(6)
	v_pk_fma_f32 v[204:205], v[120:121], v[170:171], v[152:153] op_sel_hi:[1,0,1]
	v_pk_fma_f32 v[206:207], v[122:123], v[170:171], v[154:155] op_sel_hi:[1,0,1]
	s_waitcnt vmcnt(4)
; DI u32x4 pack8(const float* v) { u32x4 w; w.x = pk2(v[0], v[1]); w.y = pk2(v[2], v[3]); w.z = pk2(v[4], v[5]); w.w = pk2(v[6], v[7]); return w; }
; DI float silu(float x) { return x * __builtin_amdgcn_rcpf(1.f + ex2(-x * LOG2E)); }
;     template <int PN> DI void body(AccRef acc, const Unit& u, int wr, int wc, int fr, int fq) const {
;     ...
; #pragma unroll
;         for (int ai = 0; ai < 2; ++ai) {
;             const int rb = u.pm * 256 + ai * 128 + wr * 64 + fr;
;             int mb, pos0, kv0; row_info(rb, mb, pos0, kv0);
; #pragma unroll
;             for (int m = 0; m < 4; ++m) {
;                 const int row = rb + 16 * m, pos = pos0 + 16 * m, kvrow = kv0 + 16 * m;
;                 const float rinv = rinvh[ai][m];
;                 float v[2][8];
; #pragma unroll
;                 for (int bj = 0; bj < 2; ++bj)
; #pragma unroll
;                     for (int n = 0; n < 2; ++n)
; #pragma unroll
;                         for (int j = 0; j < 4; ++j) v[bj][4 * n + j] = acc[ai][bj][m][n][j] * rinv + cvh[ai][bj][n][j];
;     ...
;                 } else if constexpr (PN == 5 || PN == 6 || PN == 7) {
;                     bf16_t* dst = PN == 5 ? rv : (PN == 6 ? rg : sq);
; #pragma unroll
;                     for (int bj = 0; bj < 2; ++bj) {
;                         if constexpr (PN == 6) {
; #pragma unroll
;                             for (int j = 0; j < 8; ++j) v[bj][j] = silu(v[bj][j]);
;                         }
;                         if constexpr (PN == 7) {
; #pragma unroll
;                             for (int j = 0; j < 8; ++j) v[bj][j] *= 0.125f;
;                         }
;                         *(u32x4*)(dst + (size_t)row * 256 + bj * 128 + cl) = pack8(v[bj]);
;                     }
	v_pk_fma_f32 v[216:217], v[116:117], v[170:171], v[156:157] op_sel_hi:[1,0,1]
	v_pk_fma_f32 v[218:219], v[118:119], v[170:171], v[158:159] op_sel_hi:[1,0,1]
	v_pk_fma_f32 v[220:221], v[112:113], v[170:171], v[144:145] op_sel_hi:[1,0,1]
	v_pk_fma_f32 v[170:171], v[114:115], v[170:171], v[146:147] op_sel_hi:[1,0,1]
	v_lshl_add_u64 v[222:223], v[198:199], 0, v[222:223]
	v_cvt_pk_bf16_f32 v200, v200, v201
	v_cvt_pk_bf16_f32 v201, v202, v203
	v_cvt_pk_bf16_f32 v202, v204, v205
	v_cvt_pk_bf16_f32 v203, v206, v207
	global_store_dwordx4 v[222:223], v[200:203], off
	v_pk_fma_f32 v[204:205], v[110:111], v[168:169], v[150:151] op_sel_hi:[1,0,1]
	v_pk_fma_f32 v[206:207], v[104:105], v[168:169], v[152:153] op_sel_hi:[1,0,1]
	v_cvt_pk_bf16_f32 v200, v216, v217
	v_cvt_pk_bf16_f32 v201, v218, v219
	v_cvt_pk_bf16_f32 v202, v220, v221
	v_cvt_pk_bf16_f32 v203, v170, v171
	global_store_dwordx4 v[222:223], v[200:203], off offset:256
	v_pk_fma_f32 v[216:217], v[106:107], v[168:169], v[154:155] op_sel_hi:[1,0,1]
	v_pk_fma_f32 v[218:219], v[100:101], v[168:169], v[156:157] op_sel_hi:[1,0,1]
	v_pk_fma_f32 v[202:203], v[108:109], v[168:169], v[148:149] op_sel_hi:[1,0,1]
	v_pk_fma_f32 v[200:201], v[102:103], v[168:169], v[158:159] op_sel_hi:[1,0,1]
	v_pk_fma_f32 v[170:171], v[96:97], v[168:169], v[144:145] op_sel_hi:[1,0,1]
	v_pk_fma_f32 v[168:169], v[98:99], v[168:169], v[146:147] op_sel_hi:[1,0,1]
	v_lshl_add_u64 v[166:167], v[198:199], 0, v[166:167]
	v_cvt_pk_bf16_f32 v202, v202, v203
	v_cvt_pk_bf16_f32 v203, v204, v205
	v_cvt_pk_bf16_f32 v204, v206, v207
	v_cvt_pk_bf16_f32 v205, v216, v217
	global_store_dwordx4 v[166:167], v[202:205], off
	v_pk_fma_f32 v[206:207], v[80:81], v[172:173], v[144:145] op_sel_hi:[1,0,1]
	v_lshl_add_u64 v[162:163], v[198:199], 0, v[162:163]
	v_cvt_pk_bf16_f32 v202, v218, v219
	v_cvt_pk_bf16_f32 v203, v200, v201
	v_cvt_pk_bf16_f32 v204, v170, v171
	v_cvt_pk_bf16_f32 v205, v168, v169
	global_store_dwordx4 v[166:167], v[202:205], off offset:256
	v_pk_fma_f32 v[166:167], v[92:93], v[172:173], v[148:149] op_sel_hi:[1,0,1]
	v_pk_fma_f32 v[168:169], v[94:95], v[172:173], v[150:151] op_sel_hi:[1,0,1]
	v_pk_fma_f32 v[170:171], v[88:89], v[172:173], v[152:153] op_sel_hi:[1,0,1]
	v_pk_fma_f32 v[200:201], v[90:91], v[172:173], v[154:155] op_sel_hi:[1,0,1]
	v_pk_fma_f32 v[202:203], v[84:85], v[172:173], v[156:157] op_sel_hi:[1,0,1]
	v_pk_fma_f32 v[204:205], v[86:87], v[172:173], v[158:159] op_sel_hi:[1,0,1]
	v_pk_fma_f32 v[172:173], v[82:83], v[172:173], v[146:147] op_sel_hi:[1,0,1]
	v_cvt_pk_bf16_f32 v166, v166, v167
	v_cvt_pk_bf16_f32 v167, v168, v169
	v_cvt_pk_bf16_f32 v168, v170, v171
	v_cvt_pk_bf16_f32 v169, v200, v201
	global_store_dwordx4 v[162:163], v[166:169], off
	v_pk_fma_f32 v[148:149], v[76:77], v[188:189], v[148:149] op_sel_hi:[1,0,1]
	v_pk_fma_f32 v[150:151], v[78:79], v[188:189], v[150:151] op_sel_hi:[1,0,1]
	v_cvt_pk_bf16_f32 v166, v202, v203
	v_cvt_pk_bf16_f32 v167, v204, v205
	v_cvt_pk_bf16_f32 v168, v206, v207
	v_cvt_pk_bf16_f32 v169, v172, v173
	global_store_dwordx4 v[162:163], v[166:169], off offset:256
	v_pk_fma_f32 v[152:153], v[72:73], v[188:189], v[152:153] op_sel_hi:[1,0,1]
	v_pk_fma_f32 v[154:155], v[74:75], v[188:189], v[154:155] op_sel_hi:[1,0,1]
	v_pk_fma_f32 v[162:163], v[64:65], v[188:189], v[144:145] op_sel_hi:[1,0,1]
	v_lshlrev_b64 v[144:145], 9, v[164:165]
	v_pk_fma_f32 v[156:157], v[68:69], v[188:189], v[156:157] op_sel_hi:[1,0,1]
	v_pk_fma_f32 v[158:159], v[70:71], v[188:189], v[158:159] op_sel_hi:[1,0,1]
	v_pk_fma_f32 v[166:167], v[66:67], v[188:189], v[146:147] op_sel_hi:[1,0,1]
	v_lshl_add_u64 v[164:165], v[198:199], 0, v[144:145]
	v_cvt_pk_bf16_f32 v144, v148, v149
	v_cvt_pk_bf16_f32 v145, v150, v151
	v_cvt_pk_bf16_f32 v146, v152, v153
	v_cvt_pk_bf16_f32 v147, v154, v155
	global_store_dwordx4 v[164:165], v[144:147], off
	s_waitcnt vmcnt(9)
	v_pk_fma_f32 v[148:149], v[56:57], v[192:193], v[136:137] op_sel_hi:[1,0,1]
	v_pk_fma_f32 v[150:151], v[58:59], v[192:193], v[138:139] op_sel_hi:[1,0,1]
	v_cvt_pk_bf16_f32 v144, v156, v157
	v_cvt_pk_bf16_f32 v145, v158, v159
	v_cvt_pk_bf16_f32 v146, v162, v163
	v_cvt_pk_bf16_f32 v147, v166, v167
	global_store_dwordx4 v[164:165], v[144:147], off offset:256
	v_lshlrev_b64 v[162:163], 9, v[174:175]
	s_waitcnt vmcnt(8)
; DI u32x4 pack8(const float* v) { u32x4 w; w.x = pk2(v[0], v[1]); w.y = pk2(v[2], v[3]); w.z = pk2(v[4], v[5]); w.w = pk2(v[6], v[7]); return w; }
; DI float silu(float x) { return x * __builtin_amdgcn_rcpf(1.f + ex2(-x * LOG2E)); }
;     template <int PN> DI void body(AccRef acc, const Unit& u, int wr, int wc, int fr, int fq) const {
;     ...
; #pragma unroll
;         for (int ai = 0; ai < 2; ++ai) {
;             const int rb = u.pm * 256 + ai * 128 + wr * 64 + fr;
;             int mb, pos0, kv0; row_info(rb, mb, pos0, kv0);
; #pragma unroll
;             for (int m = 0; m < 4; ++m) {
;                 const int row = rb + 16 * m, pos = pos0 + 16 * m, kvrow = kv0 + 16 * m;
;                 const float rinv = rinvh[ai][m];
;                 float v[2][8];
; #pragma unroll
;                 for (int bj = 0; bj < 2; ++bj)
; #pragma unroll
;                     for (int n = 0; n < 2; ++n)
; #pragma unroll
;                         for (int j = 0; j < 4; ++j) v[bj][4 * n + j] = acc[ai][bj][m][n][j] * rinv + cvh[ai][bj][n][j];
;     ...
;                 } else if constexpr (PN == 5 || PN == 6 || PN == 7) {
;                     bf16_t* dst = PN == 5 ? rv : (PN == 6 ? rg : sq);
; #pragma unroll
;                     for (int bj = 0; bj < 2; ++bj) {
;                         if constexpr (PN == 6) {
; #pragma unroll
;                             for (int j = 0; j < 8; ++j) v[bj][j] = silu(v[bj][j]);
;                         }
;                         if constexpr (PN == 7) {
; #pragma unroll
;                             for (int j = 0; j < 8; ++j) v[bj][j] *= 0.125f;
;                         }
;                         *(u32x4*)(dst + (size_t)row * 256 + bj * 128 + cl) = pack8(v[bj]);
;                     }
	v_pk_fma_f32 v[152:153], v[52:53], v[192:193], v[132:133] op_sel_hi:[1,0,1]
	v_pk_fma_f32 v[144:145], v[60:61], v[192:193], v[140:141] op_sel_hi:[1,0,1]
	v_pk_fma_f32 v[146:147], v[62:63], v[192:193], v[142:143] op_sel_hi:[1,0,1]
	v_pk_fma_f32 v[154:155], v[54:55], v[192:193], v[134:135] op_sel_hi:[1,0,1]
	v_pk_fma_f32 v[156:157], v[48:49], v[192:193], v[128:129] op_sel_hi:[1,0,1]
	v_pk_fma_f32 v[158:159], v[50:51], v[192:193], v[130:131] op_sel_hi:[1,0,1]
	v_lshl_add_u64 v[162:163], v[198:199], 0, v[162:163]
	v_cvt_pk_bf16_f32 v144, v144, v145
	v_cvt_pk_bf16_f32 v145, v146, v147
	v_cvt_pk_bf16_f32 v146, v148, v149
	v_cvt_pk_bf16_f32 v147, v150, v151
	global_store_dwordx4 v[162:163], v[144:147], off
	v_pk_fma_f32 v[148:149], v[40:41], v[190:191], v[136:137] op_sel_hi:[1,0,1]
	v_pk_fma_f32 v[150:151], v[42:43], v[190:191], v[138:139] op_sel_hi:[1,0,1]
	v_cvt_pk_bf16_f32 v144, v152, v153
	v_cvt_pk_bf16_f32 v145, v154, v155
	v_cvt_pk_bf16_f32 v146, v156, v157
	v_cvt_pk_bf16_f32 v147, v158, v159
	global_store_dwordx4 v[162:163], v[144:147], off offset:256
	v_add_u32_e32 v162, 0x90, v160
	v_ashrrev_i32_e32 v163, 31, v162
	v_pk_fma_f32 v[144:145], v[44:45], v[190:191], v[140:141] op_sel_hi:[1,0,1]
	v_pk_fma_f32 v[146:147], v[46:47], v[190:191], v[142:143] op_sel_hi:[1,0,1]
	v_lshlrev_b64 v[162:163], 9, v[162:163]
	v_pk_fma_f32 v[152:153], v[36:37], v[190:191], v[132:133] op_sel_hi:[1,0,1]
	v_pk_fma_f32 v[154:155], v[38:39], v[190:191], v[134:135] op_sel_hi:[1,0,1]
	v_pk_fma_f32 v[156:157], v[28:29], v[190:191], v[128:129] op_sel_hi:[1,0,1]
	v_pk_fma_f32 v[158:159], v[30:31], v[190:191], v[130:131] op_sel_hi:[1,0,1]
	v_lshl_add_u64 v[162:163], v[198:199], 0, v[162:163]
	v_cvt_pk_bf16_f32 v144, v144, v145
	v_cvt_pk_bf16_f32 v145, v146, v147
	v_cvt_pk_bf16_f32 v146, v148, v149
	v_cvt_pk_bf16_f32 v147, v150, v151
	global_store_dwordx4 v[162:163], v[144:147], off
	v_pk_fma_f32 v[148:149], v[24:25], v[194:195], v[136:137] op_sel_hi:[1,0,1]
	v_pk_fma_f32 v[150:151], v[26:27], v[194:195], v[138:139] op_sel_hi:[1,0,1]
	v_cvt_pk_bf16_f32 v144, v152, v153
	v_cvt_pk_bf16_f32 v145, v154, v155
	v_cvt_pk_bf16_f32 v146, v156, v157
	v_cvt_pk_bf16_f32 v147, v158, v159
	global_store_dwordx4 v[162:163], v[144:147], off offset:256
	v_add_u32_e32 v162, 0xa0, v160
	v_ashrrev_i32_e32 v163, 31, v162
	v_pk_fma_f32 v[144:145], v[32:33], v[194:195], v[140:141] op_sel_hi:[1,0,1]
	v_pk_fma_f32 v[146:147], v[34:35], v[194:195], v[142:143] op_sel_hi:[1,0,1]
	v_lshlrev_b64 v[162:163], 9, v[162:163]
	v_pk_fma_f32 v[152:153], v[20:21], v[194:195], v[132:133] op_sel_hi:[1,0,1]
	v_pk_fma_f32 v[154:155], v[22:23], v[194:195], v[134:135] op_sel_hi:[1,0,1]
	v_pk_fma_f32 v[156:157], v[16:17], v[194:195], v[128:129] op_sel_hi:[1,0,1]
	v_pk_fma_f32 v[158:159], v[18:19], v[194:195], v[130:131] op_sel_hi:[1,0,1]
	v_lshl_add_u64 v[162:163], v[198:199], 0, v[162:163]
	v_cvt_pk_bf16_f32 v144, v144, v145
	v_cvt_pk_bf16_f32 v145, v146, v147
	v_cvt_pk_bf16_f32 v146, v148, v149
	v_cvt_pk_bf16_f32 v147, v150, v151
	global_store_dwordx4 v[162:163], v[144:147], off
	v_pk_fma_f32 v[140:141], v[12:13], v[196:197], v[140:141] op_sel_hi:[1,0,1]
	v_pk_fma_f32 v[142:143], v[14:15], v[196:197], v[142:143] op_sel_hi:[1,0,1]
	v_cvt_pk_bf16_f32 v144, v152, v153
	v_cvt_pk_bf16_f32 v145, v154, v155
	v_cvt_pk_bf16_f32 v146, v156, v157
	v_cvt_pk_bf16_f32 v147, v158, v159
	global_store_dwordx4 v[162:163], v[144:147], off offset:256
	v_pk_fma_f32 v[136:137], v[8:9], v[196:197], v[136:137] op_sel_hi:[1,0,1]
	v_pk_fma_f32 v[138:139], v[10:11], v[196:197], v[138:139] op_sel_hi:[1,0,1]
	v_pk_fma_f32 v[144:145], v[0:1], v[196:197], v[128:129] op_sel_hi:[1,0,1]
	v_add_u32_e32 v128, 0xb0, v160
	v_ashrrev_i32_e32 v129, 31, v128
	v_lshlrev_b64 v[128:129], 9, v[128:129]
	v_pk_fma_f32 v[132:133], v[4:5], v[196:197], v[132:133] op_sel_hi:[1,0,1]
	v_pk_fma_f32 v[134:135], v[6:7], v[196:197], v[134:135] op_sel_hi:[1,0,1]
	v_pk_fma_f32 v[146:147], v[2:3], v[196:197], v[130:131] op_sel_hi:[1,0,1]
	v_lshl_add_u64 v[148:149], v[198:199], 0, v[128:129]
	v_cvt_pk_bf16_f32 v128, v140, v141
	v_cvt_pk_bf16_f32 v129, v142, v143
	v_cvt_pk_bf16_f32 v130, v136, v137
	v_cvt_pk_bf16_f32 v131, v138, v139
	global_store_dwordx4 v[148:149], v[128:131], off
	s_mov_b64 s[4:5], 0
	s_nop 0
	v_cvt_pk_bf16_f32 v128, v132, v133
	v_cvt_pk_bf16_f32 v129, v134, v135
	v_cvt_pk_bf16_f32 v130, v144, v145
	v_cvt_pk_bf16_f32 v131, v146, v147
	global_store_dwordx4 v[148:149], v[128:131], off offset:256
; DI float ex2(float x) { return __builtin_amdgcn_exp2f(x); }
;     template <int PN> DI void body(AccRef acc, const Unit& u, int wr, int wc, int fr, int fq) const {
;     ...
; #pragma unroll
;         for (int ai = 0; ai < 2; ++ai) {
;             const int rb_ = u.pm * 256 + ai * 128 + wr * 64 + fr;
; #pragma unroll
;             for (int m = 0; m < 4; ++m) rinvh[ai][m] = rsqrtf(sum16(ssq + (size_t)(rb_ + 16 * m + zdep) * 16) * (1.f / 1024.f) + EPS);
;             asm volatile("v_mov_b32 %0, 0" : "=v"(zdep) : "v"(rinvh[ai][0]), "v"(rinvh[ai][1]), "v"(rinvh[ai][2]), "v"(rinvh[ai][3]));
;         }
; #pragma unroll
;         for (int ai = 0; ai < 2; ++ai) {
;             const int rb_ = u.pm * 256 + ai * 128 + wr * 64 + fr;
;             int mb_, p_, k_; row_info(rb_, mb_, p_, k_);
; #pragma unroll
;             for (int bj = 0; bj < 2; ++bj)
; #pragma unroll
;                 for (int n = 0; n < 2; ++n) cvh[ai][bj][n] = *(const f32x4*)(cv + (size_t)(mb_ + zdep) * NIN + PN * 256 + bj * 128 + cl + 4 * n);
;         }
; #pragma unroll
;         for (int ai = 0; ai < 2; ++ai) {
;             const int rb = u.pm * 256 + ai * 128 + wr * 64 + fr;
;             int mb, pos0, kv0; row_info(rb, mb, pos0, kv0);
; #pragma unroll
;             for (int m = 0; m < 4; ++m) {
;                 const int row = rb + 16 * m, pos = pos0 + 16 * m, kvrow = kv0 + 16 * m;
;                 const float rinv = rinvh[ai][m];
;                 float v[2][8];
; #pragma unroll
;                 for (int bj = 0; bj < 2; ++bj)
; #pragma unroll
;                     for (int n = 0; n < 2; ++n)
; #pragma unroll
;                         for (int j = 0; j < 4; ++j) v[bj][4 * n + j] = acc[ai][bj][m][n][j] * rinv + cvh[ai][bj][n][j];
;     ...
;                 } else if constexpr (PN == 3 || PN == 4) {
;                     bf16_t* dst = PN == 3 ? rq : rk;
;                     const float sc = PN == 3 ? 0.125f : 1.f;
; #pragma unroll
;                     for (int bj = 0; bj < 2; ++bj) {
;                         const int head = 2 * bj + (wc >> 1), i0 = 16 * (wc & 1) + 4 * fq;
;                         float o1[4], o2[4];
; #pragma unroll
;                         for (int j = 0; j < 4; ++j) { float sn, cs; sincos_rev((float)pos * ex2(-(float)(i0 + j) * KEXP64), sn, cs);
;                             o1[j] = (v[bj][j] * cs - v[bj][4 + j] * sn) * sc; o2[j] = (v[bj][j] * sn + v[bj][4 + j] * cs) * sc; }
.LBB0_1741:
	s_andn2_b64 vcc, exec, s[4:5]
	s_cbranch_vccnz .LBB0_1743
	s_lshl_b32 s4, s43, 6
	s_lshl_b32 s5, s34, 8
	s_add_i32 s4, s4, s5
	v_add_u32_e32 v160, s4, v214
	v_add_u32_e32 v164, 16, v160
	v_ashrrev_i32_e32 v161, 31, v160
	v_ashrrev_i32_e32 v165, 31, v164
	v_lshlrev_b64 v[128:129], 6, v[160:161]
	v_lshlrev_b64 v[144:145], 6, v[164:165]
	v_add_u32_e32 v166, 32, v160
	v_lshl_add_u64 v[140:141], s[70:71], 0, v[128:129]
	v_lshl_add_u64 v[144:145], s[70:71], 0, v[144:145]
	v_ashrrev_i32_e32 v167, 31, v166
	s_nop 0
	s_nop 0
	v_lshlrev_b64 v[144:145], 6, v[166:167]
	v_add_u32_e32 v162, 48, v160
	v_lshl_add_u64 v[144:145], s[70:71], 0, v[144:145]
	v_ashrrev_i32_e32 v163, 31, v162
	v_lshlrev_b64 v[144:145], 6, v[162:163]
	v_lshl_add_u64 v[144:145], s[70:71], 0, v[144:145]
	s_mov_b32 s4, 0x358637bd
	v_mov_b64_e32 v[144:145], s[4:5]
	s_mov_b32 s12, 0x3a800000
	s_mov_b64 s[16:17], 0x125000
	v_readlane_b32 s22, v254, 44
	v_readlane_b32 s23, v254, 45
	v_lshlrev_b64 v[164:165], 9, v[164:165]
	v_lshlrev_b64 v[162:163], 9, v[162:163]
	v_lshl_add_u64 v[164:165], s[22:23], 0, v[164:165]
	v_lshl_add_u64 v[162:163], s[22:23], 0, v[162:163]
	v_mov_b32_e32 v190, v245
	v_mov_b32_e32 v174, v246
	v_add_u32_e32 v168, 0x80, v160
	v_mov_b32_e32 v194, v244
	v_mov_b32_e32 v170, v247
	v_mov_b32 v128, 0
	s_lshl_b32 s8, s54, 5
	v_add_u32_e32 v158, v128, v168
	v_add_u32_e32 v146, 16, v158
	v_ashrrev_i32_e32 v159, 31, v158
	v_ashrrev_i32_e32 v147, 31, v146
	v_lshlrev_b64 v[128:129], 6, v[158:159]
	v_lshlrev_b64 v[146:147], 6, v[146:147]
	v_lshl_add_u64 v[140:141], s[70:71], 0, v[128:129]
	v_lshl_add_u64 v[172:173], s[70:71], 0, v[146:147]
	s_nop 0
	s_nop 0
	v_add_u32_e32 v172, 32, v158
	v_ashrrev_i32_e32 v173, 31, v172
	v_add_u32_e32 v158, 48, v158
	v_lshlrev_b64 v[172:173], 6, v[172:173]
	v_ashrrev_i32_e32 v159, 31, v158
	v_lshl_add_u64 v[172:173], s[70:71], 0, v[172:173]
	v_lshlrev_b64 v[158:159], 6, v[158:159]
	v_lshl_add_u64 v[158:159], s[70:71], 0, v[158:159]
	s_movk_i32 s9, 0x2800
	v_mov_b32_e32 v196, v248
	v_mov_b32_e32 v192, v249
	v_mov_b32_e32 v188, v250
	v_mov_b32_e32 v172, v251
	v_add_u32_e32 v129, 0xffffc000, v160
	v_lshrrev_b32_e32 v129, 6, v129
	v_ashrrev_i32_e32 v128, 11, v160
	v_add_u32_e32 v129, 8, v129
	v_cmp_gt_i32_e64 s[4:5], s94, v160
	v_lshl_add_u32 v130, v213, 3, s8
	v_mov_b32 v136, 0
	v_ashrrev_i32_e32 v131, 31, v130
	v_cndmask_b32_e64 v128, v129, v128, s[4:5]
	v_add_u32_e32 v132, v136, v128
	v_mov_b64_e32 v[128:129], s[60:61]
	v_mad_i64_i32 v[132:133], s[6:7], v132, s9, v[128:129]
	v_lshlrev_b64 v[130:131], 2, v[130:131]
	v_lshl_add_u64 v[132:133], v[132:133], 0, v[130:131]
	s_mov_b32 s12, 0x125000
	v_lshl_add_u64 v[134:135], v[132:133], 0, s[16:17]
	v_add_co_u32_e32 v132, vcc, s12, v132
	s_lshl_b32 s6, s54, 4
	s_nop 0
	v_addc_co_u32_e32 v133, vcc, 0, v133, vcc
	global_load_dwordx4 v[144:147], v[132:133], off
	global_load_dwordx4 v[148:151], v[134:135], off offset:16
	global_load_dwordx4 v[156:159], v[134:135], off offset:512
	global_load_dwordx4 v[152:155], v[134:135], off offset:528
	s_and_b32 s7, s6, 16
	v_lshl_add_u32 v198, v213, 2, s7
	v_cvt_f32_i32_e32 v138, v198
	v_or_b32_e32 v139, 1, v198
	v_mov_b32_e32 v132, 0x400
	v_cvt_f32_i32_e32 v139, v139
	v_and_or_b32 v169, v214, 63, v132
	v_add_u32_e32 v132, 0xffffc080, v160
	v_and_b32_e32 v137, 0x7ff, v160
	v_lshrrev_b32_e32 v140, 6, v132
	v_lshlrev_b64 v[132:133], 9, v[160:161]
	v_or_b32_e32 v134, 2, v198
	v_lshl_add_u64 v[200:201], s[22:23], 0, v[132:133]
	v_cndmask_b32_e64 v189, v169, v137, s[4:5]
	v_mul_f32_e32 v133, 0xbed49a78, v138
	v_cvt_f32_i32_e32 v134, v134
	v_cvt_f32_u32_e32 v191, v189
	v_exp_f32_e32 v161, v133
	v_mul_f32_e32 v133, 0xbed49a78, v139
	v_or_b32_e32 v175, 3, v198
	v_exp_f32_e32 v173, v133
	v_cvt_f32_i32_e32 v175, v175
	v_mul_f32_e32 v134, 0xbed49a78, v134
	v_mul_f32_e32 v133, v161, v191
	v_exp_f32_e32 v171, v134
	v_mul_f32_e32 v133, 0.15915494, v133
	v_mul_f32_e32 v134, v173, v191
	v_mul_f32_e32 v175, 0xbed49a78, v175
	v_fract_f32_e32 v133, v133
	v_mul_f32_e32 v134, 0.15915494, v134
	v_exp_f32_e32 v175, v175
	v_sin_f32_e32 v202, v133
	v_cos_f32_e32 v204, v133
	v_fract_f32_e32 v133, v134
	v_sin_f32_e32 v203, v133
	v_cos_f32_e32 v205, v133
	v_ashrrev_i32_e32 v135, 11, v168
	v_add_u32_e32 v140, 8, v140
	v_cmp_gt_i32_e32 vcc, s94, v168
	v_mul_f32_e32 v193, v171, v191
	v_mul_f32_e32 v191, v175, v191
	v_cndmask_b32_e32 v132, v140, v135, vcc
	v_mul_f32_e32 v193, 0.15915494, v193
	v_mul_f32_e32 v191, 0.15915494, v191
	v_add_u32_e32 v132, v136, v132
	v_fract_f32_e32 v193, v193
	v_fract_f32_e32 v191, v191
	v_mad_i64_i32 v[128:129], s[4:5], v132, s9, v[128:129]
	v_cos_f32_e32 v220, v193
	v_cos_f32_e32 v221, v191
	v_lshl_add_u64 v[128:129], v[128:129], 0, v[130:131]
	s_and_b32 s6, s8, 0xffffffc0
	v_lshl_add_u64 v[132:133], v[128:129], 0, s[16:17]
	v_add_co_u32_e64 v128, s[4:5], s12, v128
	s_ashr_i32 s7, s6, 31
	s_nop 0
	v_addc_co_u32_e64 v129, s[4:5], 0, v129, s[4:5]
	v_ashrrev_i32_e32 v199, 31, v198
	s_lshl_b64 s[4:5], s[6:7], 1
	v_lshl_add_u64 v[200:201], v[200:201], 0, s[4:5]
	v_lshlrev_b64 v[198:199], 1, v[198:199]
	v_lshl_add_u64 v[200:201], v[200:201], 0, v[198:199]
	global_load_dwordx4 v[140:143], v[128:129], off
	s_nop 0
	global_load_dwordx4 v[128:131], v[132:133], off offset:528
	global_load_dwordx4 v[136:139], v[132:133], off offset:16
	s_nop 0
	global_load_dwordx4 v[132:135], v[132:133], off offset:512
	v_lshl_add_u64 v[164:165], v[164:165], 0, s[4:5]
	v_lshl_add_u64 v[164:165], v[164:165], 0, v[198:199]
	s_waitcnt vmcnt(7)
	v_pk_fma_f32 v[206:207], v[124:125], v[194:195], v[144:145] op_sel_hi:[1,0,1]
	s_waitcnt vmcnt(6)
; DI u32x2 pack4(const float* v) { u32x2 w; w.x = pk2(v[0], v[1]); w.y = pk2(v[2], v[3]); return w; }
; DI float ex2(float x) { return __builtin_amdgcn_exp2f(x); }
; DI void sincos_rev(float ang, float& s, float& c) { float rev = ang * 0.15915494309189535f; rev = __builtin_amdgcn_fractf(rev); s = __builtin_amdgcn_sinf(rev); c = __builtin_amdgcn_cosf(rev); }
;     template <int PN> DI void body(AccRef acc, const Unit& u, int wr, int wc, int fr, int fq) const {
;     ...
;                 } else if constexpr (PN == 3 || PN == 4) {
;                     bf16_t* dst = PN == 3 ? rq : rk;
;                     const float sc = PN == 3 ? 0.125f : 1.f;
; #pragma unroll
;                     for (int bj = 0; bj < 2; ++bj) {
;                         const int head = 2 * bj + (wc >> 1), i0 = 16 * (wc & 1) + 4 * fq;
;                         float o1[4], o2[4];
; #pragma unroll
;                         for (int j = 0; j < 4; ++j) { float sn, cs; sincos_rev((float)pos * ex2(-(float)(i0 + j) * KEXP64), sn, cs);
;                             o1[j] = (v[bj][j] * cs - v[bj][4 + j] * sn) * sc; o2[j] = (v[bj][j] * sn + v[bj][4 + j] * cs) * sc; }
;                         *(u32x2*)(dst + (size_t)row * 256 + head * 64 + i0) = pack4(o1);
;                         *(u32x2*)(dst + (size_t)row * 256 + head * 64 + 32 + i0) = pack4(o2);
;                     }
	v_pk_fma_f32 v[216:217], v[120:121], v[194:195], v[148:149] op_sel_hi:[1,0,1]
	v_pk_fma_f32 v[228:229], v[122:123], v[194:195], v[150:151] op_sel_hi:[1,0,1]
	v_pk_mul_f32 v[218:219], v[204:205], v[216:217]
	v_pk_mul_f32 v[216:217], v[202:203], v[216:217]
	v_pk_fma_f32 v[218:219], v[202:203], v[206:207], v[218:219]
	v_pk_fma_f32 v[206:207], v[204:205], v[206:207], v[216:217] neg_lo:[0,0,1] neg_hi:[0,0,1]
	v_sin_f32_e32 v216, v193
	v_sin_f32_e32 v217, v191
	v_pk_fma_f32 v[222:223], v[126:127], v[194:195], v[146:147] op_sel_hi:[1,0,1]
	v_pk_mul_f32 v[230:231], v[220:221], v[228:229]
	v_cvt_pk_bf16_f32 v206, v206, v207
	v_pk_mul_f32 v[228:229], v[216:217], v[228:229]
	v_pk_fma_f32 v[230:231], v[216:217], v[222:223], v[230:231]
	v_pk_fma_f32 v[222:223], v[220:221], v[222:223], v[228:229] neg_lo:[0,0,1] neg_hi:[0,0,1]
	v_add_u32_e32 v191, 16, v189
	v_cvt_pk_bf16_f32 v207, v222, v223
	global_store_dwordx2 v[200:201], v[206:207], off
	v_cvt_pk_bf16_f32 v206, v218, v219
	v_cvt_pk_bf16_f32 v207, v230, v231
	s_waitcnt vmcnt(5)
	v_pk_fma_f32 v[218:219], v[112:113], v[194:195], v[152:153] op_sel_hi:[1,0,1]
	v_cvt_f32_u32_e32 v191, v191
	global_store_dwordx2 v[200:201], v[206:207], off offset:64
	v_pk_fma_f32 v[206:207], v[116:117], v[194:195], v[156:157] op_sel_hi:[1,0,1]
	v_pk_mul_f32 v[222:223], v[204:205], v[218:219]
	v_mul_f32_e32 v193, v161, v191
	v_pk_fma_f32 v[222:223], v[202:203], v[206:207], v[222:223]
	v_pk_mul_f32 v[202:203], v[202:203], v[218:219]
	v_mul_f32_e32 v193, 0.15915494, v193
	v_pk_fma_f32 v[202:203], v[204:205], v[206:207], v[202:203] neg_lo:[0,0,1] neg_hi:[0,0,1]
	v_pk_fma_f32 v[204:205], v[118:119], v[194:195], v[158:159] op_sel_hi:[1,0,1]
	v_pk_fma_f32 v[194:195], v[114:115], v[194:195], v[154:155] op_sel_hi:[1,0,1]
	v_cvt_pk_bf16_f32 v202, v202, v203
	v_pk_mul_f32 v[206:207], v[220:221], v[194:195]
	v_pk_mul_f32 v[194:195], v[216:217], v[194:195]
	v_pk_fma_f32 v[206:207], v[216:217], v[204:205], v[206:207]
	v_pk_fma_f32 v[194:195], v[220:221], v[204:205], v[194:195] neg_lo:[0,0,1] neg_hi:[0,0,1]
	v_fract_f32_e32 v193, v193
	v_cvt_pk_bf16_f32 v203, v194, v195
	v_cvt_pk_bf16_f32 v194, v222, v223
	v_cvt_pk_bf16_f32 v195, v206, v207
	global_store_dwordx2 v[200:201], v[202:203], off offset:256
	global_store_dwordx2 v[200:201], v[194:195], off offset:320
	v_sin_f32_e32 v194, v193
	v_cos_f32_e32 v200, v193
	v_mul_f32_e32 v193, v173, v191
	v_mul_f32_e32 v193, 0.15915494, v193
	v_fract_f32_e32 v193, v193
	v_cos_f32_e32 v201, v193
	v_sin_f32_e32 v195, v193
	v_pk_fma_f32 v[202:203], v[108:109], v[190:191], v[144:145] op_sel_hi:[1,0,1]
	v_pk_fma_f32 v[204:205], v[104:105], v[190:191], v[148:149] op_sel_hi:[1,0,1]
	v_mul_f32_e32 v193, v171, v191
	v_mul_f32_e32 v191, v175, v191
	v_mul_f32_e32 v193, 0.15915494, v193
	v_mul_f32_e32 v191, 0.15915494, v191
	v_pk_mul_f32 v[206:207], v[200:201], v[204:205]
	v_pk_mul_f32 v[204:205], v[194:195], v[204:205]
	v_fract_f32_e32 v193, v193
	v_fract_f32_e32 v191, v191
	v_pk_fma_f32 v[206:207], v[194:195], v[202:203], v[206:207]
	v_pk_fma_f32 v[202:203], v[200:201], v[202:203], v[204:205] neg_lo:[0,0,1] neg_hi:[0,0,1]
	v_sin_f32_e32 v204, v193
	v_cos_f32_e32 v216, v193
	v_cos_f32_e32 v217, v191
	v_sin_f32_e32 v205, v191
	v_pk_fma_f32 v[220:221], v[106:107], v[190:191], v[150:151] op_sel_hi:[1,0,1]
	v_pk_fma_f32 v[218:219], v[110:111], v[190:191], v[146:147] op_sel_hi:[1,0,1]
	v_pk_mul_f32 v[222:223], v[216:217], v[220:221]
	v_pk_mul_f32 v[220:221], v[204:205], v[220:221]
	v_pk_fma_f32 v[222:223], v[204:205], v[218:219], v[222:223]
	v_pk_fma_f32 v[218:219], v[216:217], v[218:219], v[220:221] neg_lo:[0,0,1] neg_hi:[0,0,1]
	v_cvt_pk_bf16_f32 v202, v202, v203
	v_cvt_pk_bf16_f32 v203, v218, v219
	global_store_dwordx2 v[164:165], v[202:203], off
	v_cvt_pk_bf16_f32 v202, v206, v207
	v_cvt_pk_bf16_f32 v203, v222, v223
	v_pk_fma_f32 v[206:207], v[96:97], v[190:191], v[152:153] op_sel_hi:[1,0,1]
	global_store_dwordx2 v[164:165], v[202:203], off offset:64
	v_pk_fma_f32 v[202:203], v[100:101], v[190:191], v[156:157] op_sel_hi:[1,0,1]
	v_pk_mul_f32 v[218:219], v[200:201], v[206:207]
	v_add_u32_e32 v193, 32, v189
	v_pk_fma_f32 v[218:219], v[194:195], v[202:203], v[218:219]
	v_pk_mul_f32 v[194:195], v[194:195], v[206:207]
	v_cvt_f32_u32_e32 v193, v193
	v_pk_fma_f32 v[194:195], v[200:201], v[202:203], v[194:195] neg_lo:[0,0,1] neg_hi:[0,0,1]
	v_pk_fma_f32 v[200:201], v[102:103], v[190:191], v[158:159] op_sel_hi:[1,0,1]
	v_pk_fma_f32 v[190:191], v[98:99], v[190:191], v[154:155] op_sel_hi:[1,0,1]
	v_cvt_pk_bf16_f32 v194, v194, v195
	v_pk_mul_f32 v[202:203], v[216:217], v[190:191]
	v_pk_mul_f32 v[190:191], v[204:205], v[190:191]
	v_pk_fma_f32 v[202:203], v[204:205], v[200:201], v[202:203]
	v_pk_fma_f32 v[190:191], v[216:217], v[200:201], v[190:191] neg_lo:[0,0,1] neg_hi:[0,0,1]
	v_mul_f32_e32 v197, v171, v193
	v_cvt_pk_bf16_f32 v195, v190, v191
	v_cvt_pk_bf16_f32 v190, v218, v219
	v_cvt_pk_bf16_f32 v191, v202, v203
	global_store_dwordx2 v[164:165], v[194:195], off offset:256
	global_store_dwordx2 v[164:165], v[190:191], off offset:320
	v_lshlrev_b64 v[164:165], 9, v[166:167]
	v_mul_f32_e32 v166, v161, v193
	v_mul_f32_e32 v166, 0.15915494, v166
	v_fract_f32_e32 v167, v166
	v_sin_f32_e32 v166, v167
	v_cos_f32_e32 v190, v167
	v_mul_f32_e32 v167, v173, v193
	v_mul_f32_e32 v167, 0.15915494, v167
	v_fract_f32_e32 v167, v167
	v_cos_f32_e32 v191, v167
	v_sin_f32_e32 v167, v167
	v_mul_f32_e32 v193, v175, v193
	v_pk_fma_f32 v[200:201], v[88:89], v[174:175], v[148:149] op_sel_hi:[1,0,1]
	v_mul_f32_e32 v197, 0.15915494, v197
	v_mul_f32_e32 v193, 0.15915494, v193
	v_pk_fma_f32 v[194:195], v[92:93], v[174:175], v[144:145] op_sel_hi:[1,0,1]
; DI u32x2 pack4(const float* v) { u32x2 w; w.x = pk2(v[0], v[1]); w.y = pk2(v[2], v[3]); return w; }
; DI float ex2(float x) { return __builtin_amdgcn_exp2f(x); }
; DI void sincos_rev(float ang, float& s, float& c) { float rev = ang * 0.15915494309189535f; rev = __builtin_amdgcn_fractf(rev); s = __builtin_amdgcn_sinf(rev); c = __builtin_amdgcn_cosf(rev); }
;     template <int PN> DI void body(AccRef acc, const Unit& u, int wr, int wc, int fr, int fq) const {
;     ...
;                 } else if constexpr (PN == 3 || PN == 4) {
;                     bf16_t* dst = PN == 3 ? rq : rk;
;                     const float sc = PN == 3 ? 0.125f : 1.f;
; #pragma unroll
;                     for (int bj = 0; bj < 2; ++bj) {
;                         const int head = 2 * bj + (wc >> 1), i0 = 16 * (wc & 1) + 4 * fq;
;                         float o1[4], o2[4];
; #pragma unroll
;                         for (int j = 0; j < 4; ++j) { float sn, cs; sincos_rev((float)pos * ex2(-(float)(i0 + j) * KEXP64), sn, cs);
;                             o1[j] = (v[bj][j] * cs - v[bj][4 + j] * sn) * sc; o2[j] = (v[bj][j] * sn + v[bj][4 + j] * cs) * sc; }
;                         *(u32x2*)(dst + (size_t)row * 256 + head * 64 + i0) = pack4(o1);
;                         *(u32x2*)(dst + (size_t)row * 256 + head * 64 + 32 + i0) = pack4(o2);
;                     }
	v_pk_mul_f32 v[202:203], v[190:191], v[200:201]
	v_pk_mul_f32 v[200:201], v[166:167], v[200:201]
	v_fract_f32_e32 v197, v197
	v_fract_f32_e32 v193, v193
	v_pk_fma_f32 v[202:203], v[166:167], v[194:195], v[202:203]
	v_pk_fma_f32 v[194:195], v[190:191], v[194:195], v[200:201] neg_lo:[0,0,1] neg_hi:[0,0,1]
	v_sin_f32_e32 v200, v197
	v_cos_f32_e32 v204, v197
	v_cos_f32_e32 v205, v193
	v_sin_f32_e32 v201, v193
	v_pk_fma_f32 v[216:217], v[90:91], v[174:175], v[150:151] op_sel_hi:[1,0,1]
	v_lshl_add_u64 v[164:165], s[22:23], 0, v[164:165]
	v_pk_fma_f32 v[206:207], v[94:95], v[174:175], v[146:147] op_sel_hi:[1,0,1]
	v_pk_mul_f32 v[218:219], v[204:205], v[216:217]
	v_pk_mul_f32 v[216:217], v[200:201], v[216:217]
	v_pk_fma_f32 v[218:219], v[200:201], v[206:207], v[218:219]
	v_pk_fma_f32 v[206:207], v[204:205], v[206:207], v[216:217] neg_lo:[0,0,1] neg_hi:[0,0,1]
	v_lshl_add_u64 v[164:165], v[164:165], 0, s[4:5]
	v_cvt_pk_bf16_f32 v194, v194, v195
	v_cvt_pk_bf16_f32 v195, v206, v207
	v_lshl_add_u64 v[164:165], v[164:165], 0, v[198:199]
	global_store_dwordx2 v[164:165], v[194:195], off
	v_cvt_pk_bf16_f32 v194, v202, v203
	v_cvt_pk_bf16_f32 v195, v218, v219
	v_pk_fma_f32 v[202:203], v[80:81], v[174:175], v[152:153] op_sel_hi:[1,0,1]
	global_store_dwordx2 v[164:165], v[194:195], off offset:64
	v_pk_fma_f32 v[194:195], v[84:85], v[174:175], v[156:157] op_sel_hi:[1,0,1]
	v_pk_mul_f32 v[206:207], v[190:191], v[202:203]
	v_pk_fma_f32 v[148:149], v[72:73], v[170:171], v[148:149] op_sel_hi:[1,0,1]
	v_pk_fma_f32 v[206:207], v[166:167], v[194:195], v[206:207]
	v_pk_mul_f32 v[166:167], v[166:167], v[202:203]
	v_pk_fma_f32 v[144:145], v[76:77], v[170:171], v[144:145] op_sel_hi:[1,0,1]
	v_pk_fma_f32 v[166:167], v[190:191], v[194:195], v[166:167] neg_lo:[0,0,1] neg_hi:[0,0,1]
	v_pk_fma_f32 v[190:191], v[86:87], v[174:175], v[158:159] op_sel_hi:[1,0,1]
	v_pk_fma_f32 v[194:195], v[82:83], v[174:175], v[154:155] op_sel_hi:[1,0,1]
	v_add_u32_e32 v174, 48, v189
	v_pk_mul_f32 v[202:203], v[204:205], v[194:195]
	v_pk_mul_f32 v[194:195], v[200:201], v[194:195]
	v_cvt_f32_u32_e32 v174, v174
	v_pk_fma_f32 v[202:203], v[200:201], v[190:191], v[202:203]
	v_pk_fma_f32 v[190:191], v[204:205], v[190:191], v[194:195] neg_lo:[0,0,1] neg_hi:[0,0,1]
	v_cvt_pk_bf16_f32 v166, v166, v167
	v_cvt_pk_bf16_f32 v167, v190, v191
	global_store_dwordx2 v[164:165], v[166:167], off offset:256
	v_cvt_pk_bf16_f32 v166, v206, v207
	v_cvt_pk_bf16_f32 v167, v202, v203
	global_store_dwordx2 v[164:165], v[166:167], off offset:320
	v_mul_f32_e32 v164, v161, v174
	v_mul_f32_e32 v164, 0.15915494, v164
	v_fract_f32_e32 v165, v164
	v_sin_f32_e32 v164, v165
	v_cos_f32_e32 v166, v165
	v_mul_f32_e32 v165, v173, v174
	v_mul_f32_e32 v165, 0.15915494, v165
	v_fract_f32_e32 v165, v165
	v_cos_f32_e32 v167, v165
	v_sin_f32_e32 v165, v165
	v_pk_fma_f32 v[150:151], v[74:75], v[170:171], v[150:151] op_sel_hi:[1,0,1]
	v_pk_fma_f32 v[146:147], v[78:79], v[170:171], v[146:147] op_sel_hi:[1,0,1]
	v_pk_mul_f32 v[190:191], v[166:167], v[148:149]
	v_pk_mul_f32 v[148:149], v[164:165], v[148:149]
	v_pk_fma_f32 v[190:191], v[164:165], v[144:145], v[190:191]
	v_pk_fma_f32 v[144:145], v[166:167], v[144:145], v[148:149] neg_lo:[0,0,1] neg_hi:[0,0,1]
	v_mul_f32_e32 v148, v171, v174
	v_mul_f32_e32 v148, 0.15915494, v148
	v_fract_f32_e32 v149, v148
	v_sin_f32_e32 v148, v149
	v_cos_f32_e32 v194, v149
	v_mul_f32_e32 v149, v175, v174
	v_mul_f32_e32 v149, 0.15915494, v149
	v_fract_f32_e32 v149, v149
	v_cos_f32_e32 v195, v149
	v_sin_f32_e32 v149, v149
	v_cvt_pk_bf16_f32 v144, v144, v145
	v_pk_fma_f32 v[154:155], v[66:67], v[170:171], v[154:155] op_sel_hi:[1,0,1]
	v_pk_mul_f32 v[200:201], v[194:195], v[150:151]
	v_pk_mul_f32 v[150:151], v[148:149], v[150:151]
	v_pk_fma_f32 v[200:201], v[148:149], v[146:147], v[200:201]
	v_pk_fma_f32 v[146:147], v[194:195], v[146:147], v[150:151] neg_lo:[0,0,1] neg_hi:[0,0,1]
	v_pk_fma_f32 v[150:151], v[64:65], v[170:171], v[152:153] op_sel_hi:[1,0,1]
	v_cvt_pk_bf16_f32 v145, v146, v147
	v_lshl_add_u64 v[146:147], v[162:163], 0, s[4:5]
	v_lshl_add_u64 v[146:147], v[146:147], 0, v[198:199]
	global_store_dwordx2 v[146:147], v[144:145], off
	v_cvt_pk_bf16_f32 v144, v190, v191
	v_cvt_pk_bf16_f32 v145, v200, v201
	global_store_dwordx2 v[146:147], v[144:145], off offset:64
	v_pk_fma_f32 v[144:145], v[68:69], v[170:171], v[156:157] op_sel_hi:[1,0,1]
	v_pk_mul_f32 v[152:153], v[166:167], v[150:151]
	v_pk_mul_f32 v[150:151], v[164:165], v[150:151]
	v_pk_fma_f32 v[152:153], v[164:165], v[144:145], v[152:153]
	v_pk_fma_f32 v[144:145], v[166:167], v[144:145], v[150:151] neg_lo:[0,0,1] neg_hi:[0,0,1]
	v_pk_fma_f32 v[150:151], v[70:71], v[170:171], v[158:159] op_sel_hi:[1,0,1]
	v_pk_mul_f32 v[156:157], v[194:195], v[154:155]
	v_cvt_pk_bf16_f32 v144, v144, v145
	v_pk_fma_f32 v[156:157], v[148:149], v[150:151], v[156:157]
	v_pk_mul_f32 v[148:149], v[148:149], v[154:155]
	s_waitcnt vmcnt(15)
; DI u32x2 pack4(const float* v) { u32x2 w; w.x = pk2(v[0], v[1]); w.y = pk2(v[2], v[3]); return w; }
; DI float ex2(float x) { return __builtin_amdgcn_exp2f(x); }
; DI void sincos_rev(float ang, float& s, float& c) { float rev = ang * 0.15915494309189535f; rev = __builtin_amdgcn_fractf(rev); s = __builtin_amdgcn_sinf(rev); c = __builtin_amdgcn_cosf(rev); }
;     template <int PN> DI void body(AccRef acc, const Unit& u, int wr, int wc, int fr, int fq) const {
;     ...
;                 } else if constexpr (PN == 3 || PN == 4) {
;                     bf16_t* dst = PN == 3 ? rq : rk;
;                     const float sc = PN == 3 ? 0.125f : 1.f;
; #pragma unroll
;                     for (int bj = 0; bj < 2; ++bj) {
;                         const int head = 2 * bj + (wc >> 1), i0 = 16 * (wc & 1) + 4 * fq;
;                         float o1[4], o2[4];
; #pragma unroll
;                         for (int j = 0; j < 4; ++j) { float sn, cs; sincos_rev((float)pos * ex2(-(float)(i0 + j) * KEXP64), sn, cs);
;                             o1[j] = (v[bj][j] * cs - v[bj][4 + j] * sn) * sc; o2[j] = (v[bj][j] * sn + v[bj][4 + j] * cs) * sc; }
;                         *(u32x2*)(dst + (size_t)row * 256 + head * 64 + i0) = pack4(o1);
;                         *(u32x2*)(dst + (size_t)row * 256 + head * 64 + 32 + i0) = pack4(o2);
;                     }
	v_pk_fma_f32 v[162:163], v[58:59], v[196:197], v[138:139] op_sel_hi:[1,0,1]
	v_pk_fma_f32 v[148:149], v[194:195], v[150:151], v[148:149] neg_lo:[0,0,1] neg_hi:[0,0,1]
	v_pk_fma_f32 v[150:151], v[60:61], v[196:197], v[140:141] op_sel_hi:[1,0,1]
	v_cvt_pk_bf16_f32 v145, v148, v149
	global_store_dwordx2 v[146:147], v[144:145], off offset:256
	v_cvt_pk_bf16_f32 v144, v152, v153
	v_cvt_pk_bf16_f32 v145, v156, v157
	global_store_dwordx2 v[146:147], v[144:145], off offset:320
	v_and_b32_e32 v144, 0x7ff, v168
	v_cndmask_b32_e32 v166, v169, v144, vcc
	v_cvt_f32_u32_e32 v157, v166
	v_pk_fma_f32 v[152:153], v[56:57], v[196:197], v[136:137] op_sel_hi:[1,0,1]
	v_ashrrev_i32_e32 v169, 31, v168
	v_lshlrev_b64 v[144:145], 9, v[168:169]
	v_mul_f32_e32 v146, v161, v157
	v_mul_f32_e32 v146, 0.15915494, v146
	v_fract_f32_e32 v147, v146
	v_sin_f32_e32 v146, v147
	v_cos_f32_e32 v148, v147
	v_mul_f32_e32 v147, v173, v157
	v_mul_f32_e32 v147, 0.15915494, v147
	v_fract_f32_e32 v147, v147
	v_cos_f32_e32 v149, v147
	v_sin_f32_e32 v147, v147
	v_lshl_add_u64 v[144:145], s[22:23], 0, v[144:145]
	v_pk_fma_f32 v[158:159], v[62:63], v[196:197], v[142:143] op_sel_hi:[1,0,1]
	v_pk_mul_f32 v[154:155], v[148:149], v[152:153]
	v_pk_mul_f32 v[152:153], v[146:147], v[152:153]
	v_pk_fma_f32 v[154:155], v[146:147], v[150:151], v[154:155]
	v_pk_fma_f32 v[150:151], v[148:149], v[150:151], v[152:153] neg_lo:[0,0,1] neg_hi:[0,0,1]
	v_mul_f32_e32 v152, v171, v157
	v_mul_f32_e32 v152, 0.15915494, v152
	v_fract_f32_e32 v153, v152
	v_sin_f32_e32 v152, v153
	v_cos_f32_e32 v156, v153
	v_mul_f32_e32 v153, v175, v157
	v_mul_f32_e32 v153, 0.15915494, v153
	v_fract_f32_e32 v153, v153
	v_cos_f32_e32 v157, v153
	v_sin_f32_e32 v153, v153
	v_lshl_add_u64 v[144:145], v[144:145], 0, s[4:5]
	v_cvt_pk_bf16_f32 v150, v150, v151
	v_pk_mul_f32 v[164:165], v[156:157], v[162:163]
	v_pk_mul_f32 v[162:163], v[152:153], v[162:163]
	v_pk_fma_f32 v[164:165], v[152:153], v[158:159], v[164:165]
	v_pk_fma_f32 v[158:159], v[156:157], v[158:159], v[162:163] neg_lo:[0,0,1] neg_hi:[0,0,1]
	v_lshl_add_u64 v[144:145], v[144:145], 0, v[198:199]
	v_cvt_pk_bf16_f32 v151, v158, v159
	global_store_dwordx2 v[144:145], v[150:151], off
	v_cvt_pk_bf16_f32 v150, v154, v155
	v_cvt_pk_bf16_f32 v151, v164, v165
	v_pk_fma_f32 v[154:155], v[48:49], v[196:197], v[128:129] op_sel_hi:[1,0,1]
	global_store_dwordx2 v[144:145], v[150:151], off offset:64
	s_waitcnt vmcnt(18)
	v_pk_fma_f32 v[150:151], v[52:53], v[196:197], v[132:133] op_sel_hi:[1,0,1]
	v_pk_mul_f32 v[158:159], v[148:149], v[154:155]
	v_pk_fma_f32 v[162:163], v[42:43], v[192:193], v[138:139] op_sel_hi:[1,0,1]
	v_pk_fma_f32 v[158:159], v[146:147], v[150:151], v[158:159]
	v_pk_mul_f32 v[146:147], v[146:147], v[154:155]
	s_nop 0
	v_pk_fma_f32 v[146:147], v[148:149], v[150:151], v[146:147] neg_lo:[0,0,1] neg_hi:[0,0,1]
	v_pk_fma_f32 v[150:151], v[50:51], v[196:197], v[130:131] op_sel_hi:[1,0,1]
	v_pk_fma_f32 v[148:149], v[54:55], v[196:197], v[134:135] op_sel_hi:[1,0,1]
	v_pk_mul_f32 v[154:155], v[156:157], v[150:151]
	v_pk_mul_f32 v[150:151], v[152:153], v[150:151]
	v_pk_fma_f32 v[154:155], v[152:153], v[148:149], v[154:155]
	v_pk_fma_f32 v[148:149], v[156:157], v[148:149], v[150:151] neg_lo:[0,0,1] neg_hi:[0,0,1]
	v_cvt_pk_bf16_f32 v146, v146, v147
	v_cvt_pk_bf16_f32 v147, v148, v149
	global_store_dwordx2 v[144:145], v[146:147], off offset:256
	v_cvt_pk_bf16_f32 v146, v158, v159
	v_cvt_pk_bf16_f32 v147, v154, v155
	global_store_dwordx2 v[144:145], v[146:147], off offset:320
	v_add_u32_e32 v145, 16, v166
	v_cvt_f32_u32_e32 v157, v145
	v_pk_fma_f32 v[152:153], v[40:41], v[192:193], v[136:137] op_sel_hi:[1,0,1]
	v_pk_fma_f32 v[150:151], v[44:45], v[192:193], v[140:141] op_sel_hi:[1,0,1]
	v_add_u32_e32 v144, 0x90, v160
	v_mul_f32_e32 v146, v161, v157
	v_mul_f32_e32 v146, 0.15915494, v146
	v_fract_f32_e32 v147, v146
	v_sin_f32_e32 v146, v147
	v_cos_f32_e32 v148, v147
	v_mul_f32_e32 v147, v173, v157
	v_mul_f32_e32 v147, 0.15915494, v147
	v_fract_f32_e32 v147, v147
	v_cos_f32_e32 v149, v147
	v_sin_f32_e32 v147, v147
	v_ashrrev_i32_e32 v145, 31, v144
	v_lshlrev_b64 v[144:145], 9, v[144:145]
	v_pk_mul_f32 v[154:155], v[148:149], v[152:153]
	v_pk_mul_f32 v[152:153], v[146:147], v[152:153]
	v_pk_fma_f32 v[154:155], v[146:147], v[150:151], v[154:155]
	v_pk_fma_f32 v[150:151], v[148:149], v[150:151], v[152:153] neg_lo:[0,0,1] neg_hi:[0,0,1]
	v_mul_f32_e32 v152, v171, v157
	v_mul_f32_e32 v152, 0.15915494, v152
	v_fract_f32_e32 v153, v152
	v_sin_f32_e32 v152, v153
	v_cos_f32_e32 v156, v153
	v_mul_f32_e32 v153, v175, v157
	v_mul_f32_e32 v153, 0.15915494, v153
	v_fract_f32_e32 v153, v153
	v_cos_f32_e32 v157, v153
	v_sin_f32_e32 v153, v153
	v_lshl_add_u64 v[144:145], s[22:23], 0, v[144:145]
	v_pk_fma_f32 v[158:159], v[46:47], v[192:193], v[142:143] op_sel_hi:[1,0,1]
	v_pk_mul_f32 v[164:165], v[156:157], v[162:163]
	v_pk_mul_f32 v[162:163], v[152:153], v[162:163]
	v_pk_fma_f32 v[164:165], v[152:153], v[158:159], v[164:165]
	v_pk_fma_f32 v[158:159], v[156:157], v[158:159], v[162:163] neg_lo:[0,0,1] neg_hi:[0,0,1]
	v_lshl_add_u64 v[144:145], v[144:145], 0, s[4:5]
	v_cvt_pk_bf16_f32 v150, v150, v151
	v_cvt_pk_bf16_f32 v151, v158, v159
	v_lshl_add_u64 v[144:145], v[144:145], 0, v[198:199]
	global_store_dwordx2 v[144:145], v[150:151], off
	v_cvt_pk_bf16_f32 v150, v154, v155
	v_cvt_pk_bf16_f32 v151, v164, v165
	v_pk_fma_f32 v[154:155], v[28:29], v[192:193], v[128:129] op_sel_hi:[1,0,1]
	global_store_dwordx2 v[144:145], v[150:151], off offset:64
	v_pk_fma_f32 v[150:151], v[36:37], v[192:193], v[132:133] op_sel_hi:[1,0,1]
	v_pk_mul_f32 v[158:159], v[148:149], v[154:155]
; DI u32x2 pack4(const float* v) { u32x2 w; w.x = pk2(v[0], v[1]); w.y = pk2(v[2], v[3]); return w; }
; DI float ex2(float x) { return __builtin_amdgcn_exp2f(x); }
; DI void sincos_rev(float ang, float& s, float& c) { float rev = ang * 0.15915494309189535f; rev = __builtin_amdgcn_fractf(rev); s = __builtin_amdgcn_sinf(rev); c = __builtin_amdgcn_cosf(rev); }
;     template <int PN> DI void body(AccRef acc, const Unit& u, int wr, int wc, int fr, int fq) const {
;     ...
;                 } else if constexpr (PN == 3 || PN == 4) {
;                     bf16_t* dst = PN == 3 ? rq : rk;
;                     const float sc = PN == 3 ? 0.125f : 1.f;
; #pragma unroll
;                     for (int bj = 0; bj < 2; ++bj) {
;                         const int head = 2 * bj + (wc >> 1), i0 = 16 * (wc & 1) + 4 * fq;
;                         float o1[4], o2[4];
; #pragma unroll
;                         for (int j = 0; j < 4; ++j) { float sn, cs; sincos_rev((float)pos * ex2(-(float)(i0 + j) * KEXP64), sn, cs);
;                             o1[j] = (v[bj][j] * cs - v[bj][4 + j] * sn) * sc; o2[j] = (v[bj][j] * sn + v[bj][4 + j] * cs) * sc; }
;                         *(u32x2*)(dst + (size_t)row * 256 + head * 64 + i0) = pack4(o1);
;                         *(u32x2*)(dst + (size_t)row * 256 + head * 64 + 32 + i0) = pack4(o2);
;                     }
	v_pk_fma_f32 v[162:163], v[26:27], v[188:189], v[138:139] op_sel_hi:[1,0,1]
	v_pk_fma_f32 v[158:159], v[146:147], v[150:151], v[158:159]
	v_pk_mul_f32 v[146:147], v[146:147], v[154:155]
	v_pk_fma_f32 v[138:139], v[10:11], v[172:173], v[138:139] op_sel_hi:[1,0,1]
	v_pk_fma_f32 v[146:147], v[148:149], v[150:151], v[146:147] neg_lo:[0,0,1] neg_hi:[0,0,1]
	v_pk_fma_f32 v[150:151], v[30:31], v[192:193], v[130:131] op_sel_hi:[1,0,1]
	v_pk_fma_f32 v[148:149], v[38:39], v[192:193], v[134:135] op_sel_hi:[1,0,1]
	v_pk_mul_f32 v[154:155], v[156:157], v[150:151]
	v_pk_mul_f32 v[150:151], v[152:153], v[150:151]
	v_pk_fma_f32 v[154:155], v[152:153], v[148:149], v[154:155]
	v_pk_fma_f32 v[148:149], v[156:157], v[148:149], v[150:151] neg_lo:[0,0,1] neg_hi:[0,0,1]
	v_cvt_pk_bf16_f32 v146, v146, v147
	v_cvt_pk_bf16_f32 v147, v148, v149
	global_store_dwordx2 v[144:145], v[146:147], off offset:256
	v_cvt_pk_bf16_f32 v146, v158, v159
	v_cvt_pk_bf16_f32 v147, v154, v155
	global_store_dwordx2 v[144:145], v[146:147], off offset:320
	v_add_u32_e32 v145, 32, v166
	v_cvt_f32_u32_e32 v157, v145
	v_pk_fma_f32 v[152:153], v[24:25], v[188:189], v[136:137] op_sel_hi:[1,0,1]
	v_pk_fma_f32 v[150:151], v[32:33], v[188:189], v[140:141] op_sel_hi:[1,0,1]
	v_add_u32_e32 v144, 0xa0, v160
	v_mul_f32_e32 v146, v161, v157
	v_mul_f32_e32 v146, 0.15915494, v146
	v_fract_f32_e32 v147, v146
	v_sin_f32_e32 v146, v147
	v_cos_f32_e32 v148, v147
	v_mul_f32_e32 v147, v173, v157
	v_mul_f32_e32 v147, 0.15915494, v147
	v_fract_f32_e32 v147, v147
	v_cos_f32_e32 v149, v147
	v_sin_f32_e32 v147, v147
	v_ashrrev_i32_e32 v145, 31, v144
	v_lshlrev_b64 v[144:145], 9, v[144:145]
	v_pk_mul_f32 v[154:155], v[148:149], v[152:153]
	v_pk_mul_f32 v[152:153], v[146:147], v[152:153]
	v_pk_fma_f32 v[154:155], v[146:147], v[150:151], v[154:155]
	v_pk_fma_f32 v[150:151], v[148:149], v[150:151], v[152:153] neg_lo:[0,0,1] neg_hi:[0,0,1]
	v_mul_f32_e32 v152, v171, v157
	v_mul_f32_e32 v152, 0.15915494, v152
	v_fract_f32_e32 v153, v152
	v_sin_f32_e32 v152, v153
	v_cos_f32_e32 v156, v153
	v_mul_f32_e32 v153, v175, v157
	v_mul_f32_e32 v153, 0.15915494, v153
	v_fract_f32_e32 v153, v153
	v_cos_f32_e32 v157, v153
	v_sin_f32_e32 v153, v153
	v_lshl_add_u64 v[144:145], s[22:23], 0, v[144:145]
	v_pk_fma_f32 v[158:159], v[34:35], v[188:189], v[142:143] op_sel_hi:[1,0,1]
	v_pk_mul_f32 v[164:165], v[156:157], v[162:163]
	v_pk_mul_f32 v[162:163], v[152:153], v[162:163]
	v_pk_fma_f32 v[164:165], v[152:153], v[158:159], v[164:165]
	v_pk_fma_f32 v[158:159], v[156:157], v[158:159], v[162:163] neg_lo:[0,0,1] neg_hi:[0,0,1]
	v_lshl_add_u64 v[144:145], v[144:145], 0, s[4:5]
	v_cvt_pk_bf16_f32 v150, v150, v151
	v_cvt_pk_bf16_f32 v151, v158, v159
	v_lshl_add_u64 v[144:145], v[144:145], 0, v[198:199]
	global_store_dwordx2 v[144:145], v[150:151], off
	v_cvt_pk_bf16_f32 v150, v154, v155
	v_cvt_pk_bf16_f32 v151, v164, v165
	v_pk_fma_f32 v[154:155], v[16:17], v[188:189], v[128:129] op_sel_hi:[1,0,1]
	global_store_dwordx2 v[144:145], v[150:151], off offset:64
	v_pk_fma_f32 v[150:151], v[20:21], v[188:189], v[132:133] op_sel_hi:[1,0,1]
	v_pk_mul_f32 v[158:159], v[148:149], v[154:155]
	v_pk_fma_f32 v[136:137], v[8:9], v[172:173], v[136:137] op_sel_hi:[1,0,1]
	v_pk_fma_f32 v[158:159], v[146:147], v[150:151], v[158:159]
	v_pk_mul_f32 v[146:147], v[146:147], v[154:155]
	v_pk_fma_f32 v[140:141], v[12:13], v[172:173], v[140:141] op_sel_hi:[1,0,1]
	v_pk_fma_f32 v[146:147], v[148:149], v[150:151], v[146:147] neg_lo:[0,0,1] neg_hi:[0,0,1]
	v_pk_fma_f32 v[150:151], v[18:19], v[188:189], v[130:131] op_sel_hi:[1,0,1]
	v_pk_fma_f32 v[148:149], v[22:23], v[188:189], v[134:135] op_sel_hi:[1,0,1]
	v_pk_mul_f32 v[154:155], v[156:157], v[150:151]
	v_pk_mul_f32 v[150:151], v[152:153], v[150:151]
	v_pk_fma_f32 v[154:155], v[152:153], v[148:149], v[154:155]
	v_pk_fma_f32 v[148:149], v[156:157], v[148:149], v[150:151] neg_lo:[0,0,1] neg_hi:[0,0,1]
	v_cvt_pk_bf16_f32 v146, v146, v147
	v_cvt_pk_bf16_f32 v147, v148, v149
	global_store_dwordx2 v[144:145], v[146:147], off offset:256
	v_cvt_pk_bf16_f32 v146, v158, v159
	v_cvt_pk_bf16_f32 v147, v154, v155
	global_store_dwordx2 v[144:145], v[146:147], off offset:320
	v_add_u32_e32 v145, 48, v166
	v_cvt_f32_u32_e32 v153, v145
	v_add_u32_e32 v144, 0xb0, v160
	v_ashrrev_i32_e32 v145, 31, v144
	v_lshlrev_b64 v[144:145], 9, v[144:145]
	v_mul_f32_e32 v146, v161, v153
	v_mul_f32_e32 v146, 0.15915494, v146
	v_fract_f32_e32 v147, v146
	v_sin_f32_e32 v146, v147
	v_cos_f32_e32 v148, v147
	v_mul_f32_e32 v147, v173, v153
	v_mul_f32_e32 v147, 0.15915494, v147
	v_fract_f32_e32 v147, v147
	v_cos_f32_e32 v149, v147
	v_sin_f32_e32 v147, v147
	v_pk_fma_f32 v[142:143], v[14:15], v[172:173], v[142:143] op_sel_hi:[1,0,1]
	v_lshl_add_u64 v[144:145], s[22:23], 0, v[144:145]
	v_pk_mul_f32 v[150:151], v[148:149], v[136:137]
	v_pk_mul_f32 v[136:137], v[146:147], v[136:137]
	v_pk_fma_f32 v[150:151], v[146:147], v[140:141], v[150:151]
	v_pk_fma_f32 v[136:137], v[148:149], v[140:141], v[136:137] neg_lo:[0,0,1] neg_hi:[0,0,1]
	v_mul_f32_e32 v140, v171, v153
	v_mul_f32_e32 v140, 0.15915494, v140
	v_fract_f32_e32 v141, v140
	v_sin_f32_e32 v140, v141
	v_cos_f32_e32 v152, v141
	v_mul_f32_e32 v141, v175, v153
	v_mul_f32_e32 v141, 0.15915494, v141
	v_fract_f32_e32 v141, v141
	v_cos_f32_e32 v153, v141
	v_sin_f32_e32 v141, v141
	v_cvt_pk_bf16_f32 v136, v136, v137
	v_pk_fma_f32 v[128:129], v[0:1], v[172:173], v[128:129] op_sel_hi:[1,0,1]
	v_pk_mul_f32 v[154:155], v[152:153], v[138:139]
	v_pk_mul_f32 v[138:139], v[140:141], v[138:139]
	v_pk_fma_f32 v[154:155], v[140:141], v[142:143], v[154:155]
	v_pk_fma_f32 v[138:139], v[152:153], v[142:143], v[138:139] neg_lo:[0,0,1] neg_hi:[0,0,1]
	v_pk_fma_f32 v[132:133], v[4:5], v[172:173], v[132:133] op_sel_hi:[1,0,1]
	v_cvt_pk_bf16_f32 v137, v138, v139
	v_lshl_add_u64 v[138:139], v[144:145], 0, s[4:5]
	v_lshl_add_u64 v[138:139], v[138:139], 0, v[198:199]
	global_store_dwordx2 v[138:139], v[136:137], off
	v_cvt_pk_bf16_f32 v136, v150, v151
	v_cvt_pk_bf16_f32 v137, v154, v155
	global_store_dwordx2 v[138:139], v[136:137], off offset:64
	v_pk_mul_f32 v[136:137], v[148:149], v[128:129]
	v_pk_mul_f32 v[128:129], v[146:147], v[128:129]
	v_pk_fma_f32 v[130:131], v[2:3], v[172:173], v[130:131] op_sel_hi:[1,0,1]
	v_pk_fma_f32 v[136:137], v[146:147], v[132:133], v[136:137]
	v_pk_fma_f32 v[128:129], v[148:149], v[132:133], v[128:129] neg_lo:[0,0,1] neg_hi:[0,0,1]
	v_pk_fma_f32 v[132:133], v[6:7], v[172:173], v[134:135] op_sel_hi:[1,0,1]
	v_pk_mul_f32 v[134:135], v[152:153], v[130:131]
	v_pk_mul_f32 v[130:131], v[140:141], v[130:131]
	v_pk_fma_f32 v[134:135], v[140:141], v[132:133], v[134:135]
	v_pk_fma_f32 v[130:131], v[152:153], v[132:133], v[130:131] neg_lo:[0,0,1] neg_hi:[0,0,1]
	v_cvt_pk_bf16_f32 v128, v128, v129
	v_cvt_pk_bf16_f32 v129, v130, v131
	global_store_dwordx2 v[138:139], v[128:129], off offset:256
	v_cvt_pk_bf16_f32 v128, v136, v137
	v_cvt_pk_bf16_f32 v129, v134, v135
	global_store_dwordx2 v[138:139], v[128:129], off offset:320

;     template <int PN> DI void body(AccRef acc, const Unit& u, int wr, int wc, int fr, int fq) const {
;     ...
; #pragma unroll
;         for (int ai = 0; ai < 2; ++ai) {
;             const int rb_ = u.pm * 256 + ai * 128 + wr * 64 + fr;
; #pragma unroll
;             for (int m = 0; m < 4; ++m) rinvh[ai][m] = rsqrtf(sum16(ssq + (size_t)(rb_ + 16 * m + zdep) * 16) * (1.f / 1024.f) + EPS);
;             asm volatile("v_mov_b32 %0, 0" : "=v"(zdep) : "v"(rinvh[ai][0]), "v"(rinvh[ai][1]), "v"(rinvh[ai][2]), "v"(rinvh[ai][3]));
;         }
; #pragma unroll
;         for (int ai = 0; ai < 2; ++ai) {
;             const int rb_ = u.pm * 256 + ai * 128 + wr * 64 + fr;
;             int mb_, p_, k_; row_info(rb_, mb_, p_, k_);
; #pragma unroll
;             for (int bj = 0; bj < 2; ++bj)
; #pragma unroll
;                 for (int n = 0; n < 2; ++n) cvh[ai][bj][n] = *(const f32x4*)(cv + (size_t)(mb_ + zdep) * NIN + PN * 256 + bj * 128 + cl + 4 * n);
;         }
; #pragma unroll
;         for (int ai = 0; ai < 2; ++ai) {
;             const int rb = u.pm * 256 + ai * 128 + wr * 64 + fr;
;             int mb, pos0, kv0; row_info(rb, mb, pos0, kv0);
; #pragma unroll
;             for (int m = 0; m < 4; ++m) {
;                 const int row = rb + 16 * m, pos = pos0 + 16 * m, kvrow = kv0 + 16 * m;
;                 const float rinv = rinvh[ai][m];
;                 float v[2][8];
; #pragma unroll
;                 for (int bj = 0; bj < 2; ++bj)
; #pragma unroll
;                     for (int n = 0; n < 2; ++n)
; #pragma unroll
;                         for (int j = 0; j < 4; ++j) v[bj][4 * n + j] = acc[ai][bj][m][n][j] * rinv + cvh[ai][bj][n][j];
;     ...
;                 } else if constexpr (PN == 3 || PN == 4) {
;                     bf16_t* dst = PN == 3 ? rq : rk;
;                     const float sc = PN == 3 ? 0.125f : 1.f;
; #pragma unroll
;                     for (int bj = 0; bj < 2; ++bj) {
;     DI void operator()(AccRef acc, const Unit& u, int wr, int wc, int fr, int fq) const {
;         switch (u.pn) {
;             case 0: body<0>(acc, u, wr, wc, fr, fq); break;
;             case 1: body<1>(acc, u, wr, wc, fr, fq); break;
;             case 2: body<2>(acc, u, wr, wc, fr, fq); break;
;             case 3: body<3>(acc, u, wr, wc, fr, fq); break;
;             case 4: body<4>(acc, u, wr, wc, fr, fq); break;
.LBB0_1744:
	s_and_b64 vcc, exec, s[4:5]
	s_cbranch_vccz .LBB0_1808
	s_cmp_gt_i32 s66, 1
	s_mov_b64 s[4:5], -1
	s_cbranch_scc0 .LBB0_1787
	s_cmp_gt_i32 s66, 2
	s_cbranch_scc0 .LBB0_1748
	s_lshl_b32 s4, s43, 6
	s_lshl_b32 s5, s34, 8
	s_add_i32 s4, s4, s5
	v_add_u32_e32 v160, s4, v214
	v_add_u32_e32 v164, 16, v160
	v_ashrrev_i32_e32 v161, 31, v160
	v_ashrrev_i32_e32 v165, 31, v164
	v_lshlrev_b64 v[128:129], 6, v[160:161]
	v_lshlrev_b64 v[144:145], 6, v[164:165]
	v_add_u32_e32 v166, 32, v160
	v_lshl_add_u64 v[140:141], s[70:71], 0, v[128:129]
	v_lshl_add_u64 v[144:145], s[70:71], 0, v[144:145]
	v_ashrrev_i32_e32 v167, 31, v166
	s_nop 0
	s_nop 0
	v_lshlrev_b64 v[144:145], 6, v[166:167]
	v_add_u32_e32 v162, 48, v160
	v_lshl_add_u64 v[144:145], s[70:71], 0, v[144:145]
	v_ashrrev_i32_e32 v163, 31, v162
	v_lshlrev_b64 v[144:145], 6, v[162:163]
	v_lshl_add_u64 v[144:145], s[70:71], 0, v[144:145]
	s_mov_b32 s4, 0x358637bd
	v_mov_b64_e32 v[144:145], s[4:5]
	s_mov_b32 s10, 0x3a800000
	s_mov_b64 s[12:13], 0x124c00
	v_readlane_b32 s16, v254, 48
	v_readlane_b32 s17, v254, 49
	v_lshlrev_b64 v[164:165], 9, v[164:165]
	v_lshlrev_b64 v[162:163], 9, v[162:163]
	v_lshl_add_u64 v[164:165], s[16:17], 0, v[164:165]
	v_lshl_add_u64 v[162:163], s[16:17], 0, v[162:163]
	v_mov_b32_e32 v190, v245
	v_mov_b32_e32 v174, v246
	v_add_u32_e32 v168, 0x80, v160
	v_mov_b32_e32 v194, v244
	v_mov_b32_e32 v170, v247
	v_mov_b32 v128, 0
	s_lshl_b32 s8, s54, 5
	v_add_u32_e32 v158, v128, v168
	v_add_u32_e32 v146, 16, v158
	v_ashrrev_i32_e32 v159, 31, v158
	v_ashrrev_i32_e32 v147, 31, v146
	v_lshlrev_b64 v[128:129], 6, v[158:159]
	v_lshlrev_b64 v[146:147], 6, v[146:147]
	v_lshl_add_u64 v[140:141], s[70:71], 0, v[128:129]
	v_lshl_add_u64 v[172:173], s[70:71], 0, v[146:147]
	s_nop 0
	s_nop 0
	v_add_u32_e32 v172, 32, v158
	v_ashrrev_i32_e32 v173, 31, v172
	v_add_u32_e32 v158, 48, v158
	v_lshlrev_b64 v[172:173], 6, v[172:173]
	v_ashrrev_i32_e32 v159, 31, v158
	v_lshl_add_u64 v[172:173], s[70:71], 0, v[172:173]
	v_lshlrev_b64 v[158:159], 6, v[158:159]
	v_lshl_add_u64 v[158:159], s[70:71], 0, v[158:159]
	s_movk_i32 s9, 0x2800
	v_mov_b32_e32 v196, v248
	v_mov_b32_e32 v192, v249
	v_mov_b32_e32 v188, v250
	v_mov_b32_e32 v172, v251
	v_add_u32_e32 v129, 0xffffc000, v160
	v_lshrrev_b32_e32 v129, 6, v129
	v_ashrrev_i32_e32 v128, 11, v160
	v_add_u32_e32 v129, 8, v129
	v_cmp_gt_i32_e64 s[4:5], s94, v160
	v_lshl_add_u32 v130, v213, 3, s8
	v_mov_b32 v136, 0
	v_ashrrev_i32_e32 v131, 31, v130
	v_cndmask_b32_e64 v128, v129, v128, s[4:5]
	v_add_u32_e32 v132, v136, v128
	v_mov_b64_e32 v[128:129], s[60:61]
	v_mad_i64_i32 v[132:133], s[6:7], v132, s9, v[128:129]
	v_lshlrev_b64 v[130:131], 2, v[130:131]
	v_lshl_add_u64 v[132:133], v[132:133], 0, v[130:131]
	s_mov_b32 s10, 0x124000
	v_lshl_add_u64 v[134:135], v[132:133], 0, s[12:13]
	v_add_co_u32_e32 v132, vcc, s10, v132
	s_lshl_b32 s6, s54, 4
	s_nop 0
	v_addc_co_u32_e32 v133, vcc, 0, v133, vcc
	global_load_dwordx4 v[144:147], v[132:133], off offset:3072
	global_load_dwordx4 v[148:151], v[134:135], off offset:16
	global_load_dwordx4 v[156:159], v[134:135], off offset:512
	global_load_dwordx4 v[152:155], v[134:135], off offset:528
	s_and_b32 s7, s6, 16
	v_lshl_add_u32 v198, v213, 2, s7
	v_cvt_f32_i32_e32 v138, v198
	v_or_b32_e32 v139, 1, v198
	v_mov_b32_e32 v132, 0x400
	v_cvt_f32_i32_e32 v134, v139
	v_and_or_b32 v169, v214, 63, v132
	v_add_u32_e32 v132, 0xffffc080, v160
	v_and_b32_e32 v137, 0x7ff, v160
	v_lshrrev_b32_e32 v142, 6, v132
	v_lshlrev_b64 v[132:133], 9, v[160:161]
	v_lshl_add_u64 v[200:201], s[16:17], 0, v[132:133]
	v_cndmask_b32_e64 v189, v169, v137, s[4:5]
	v_mul_f32_e32 v133, 0xbed49a78, v138
	v_cvt_f32_u32_e32 v191, v189
	v_exp_f32_e32 v171, v133
	v_mul_f32_e32 v133, 0xbed49a78, v134
	v_or_b32_e32 v140, 2, v198
	v_exp_f32_e32 v161, v133
	v_or_b32_e32 v175, 3, v198
	v_cvt_f32_i32_e32 v135, v140
	v_cvt_f32_i32_e32 v175, v175
	v_mul_f32_e32 v133, v171, v191
	v_mul_f32_e32 v133, 0.15915494, v133
	v_mul_f32_e32 v134, v161, v191
	v_mul_f32_e32 v173, 0xbed49a78, v135
	v_fract_f32_e32 v133, v133
	v_mul_f32_e32 v134, 0.15915494, v134
	v_mul_f32_e32 v175, 0xbed49a78, v175
	v_sin_f32_e32 v202, v133
	v_cos_f32_e32 v204, v133
	v_fract_f32_e32 v133, v134
	v_exp_f32_e32 v173, v173
	v_exp_f32_e32 v175, v175
	v_cos_f32_e32 v205, v133
	v_sin_f32_e32 v203, v133
	v_mul_f32_e32 v193, v173, v191
	v_mul_f32_e32 v191, v175, v191
	v_ashrrev_i32_e32 v141, 11, v168
	v_add_u32_e32 v139, 8, v142
	v_cmp_gt_i32_e32 vcc, s94, v168
	v_mul_f32_e32 v193, 0.15915494, v193
	v_mul_f32_e32 v191, 0.15915494, v191
	s_and_b32 s6, s8, 0xffffffc0
	v_cndmask_b32_e32 v132, v139, v141, vcc
	s_mov_b32 s8, 0x3e000000
	v_fract_f32_e32 v193, v193
	v_fract_f32_e32 v191, v191
	v_add_u32_e32 v132, v136, v132
	v_cos_f32_e32 v220, v193
	v_cos_f32_e32 v221, v191
	v_mad_i64_i32 v[128:129], s[4:5], v132, s9, v[128:129]
	v_lshl_add_u64 v[128:129], v[128:129], 0, v[130:131]
	v_lshl_add_u64 v[132:133], v[128:129], 0, s[12:13]
	v_add_co_u32_e64 v128, s[4:5], s10, v128
	s_ashr_i32 s7, s6, 31
	s_nop 0
	v_addc_co_u32_e64 v129, s[4:5], 0, v129, s[4:5]
	v_ashrrev_i32_e32 v199, 31, v198
	s_lshl_b64 s[4:5], s[6:7], 1
	v_lshl_add_u64 v[200:201], v[200:201], 0, s[4:5]
	v_lshlrev_b64 v[198:199], 1, v[198:199]
	v_lshl_add_u64 v[200:201], v[200:201], 0, v[198:199]
	global_load_dwordx4 v[140:143], v[128:129], off offset:3072
	s_nop 0
	global_load_dwordx4 v[128:131], v[132:133], off offset:528
	global_load_dwordx4 v[136:139], v[132:133], off offset:16
	s_nop 0
	global_load_dwordx4 v[132:135], v[132:133], off offset:512
	v_lshl_add_u64 v[164:165], v[164:165], 0, s[4:5]
	v_lshl_add_u64 v[164:165], v[164:165], 0, v[198:199]
	s_waitcnt vmcnt(7)
; DI u32x2 pack4(const float* v) { u32x2 w; w.x = pk2(v[0], v[1]); w.y = pk2(v[2], v[3]); return w; }
; DI float ex2(float x) { return __builtin_amdgcn_exp2f(x); }
; DI void sincos_rev(float ang, float& s, float& c) { float rev = ang * 0.15915494309189535f; rev = __builtin_amdgcn_fractf(rev); s = __builtin_amdgcn_sinf(rev); c = __builtin_amdgcn_cosf(rev); }
;     template <int PN> DI void body(AccRef acc, const Unit& u, int wr, int wc, int fr, int fq) const {
;     ...
;                 } else if constexpr (PN == 3 || PN == 4) {
;                     bf16_t* dst = PN == 3 ? rq : rk;
;                     const float sc = PN == 3 ? 0.125f : 1.f;
; #pragma unroll
;                     for (int bj = 0; bj < 2; ++bj) {
;                         const int head = 2 * bj + (wc >> 1), i0 = 16 * (wc & 1) + 4 * fq;
;                         float o1[4], o2[4];
; #pragma unroll
;                         for (int j = 0; j < 4; ++j) { float sn, cs; sincos_rev((float)pos * ex2(-(float)(i0 + j) * KEXP64), sn, cs);
;                             o1[j] = (v[bj][j] * cs - v[bj][4 + j] * sn) * sc; o2[j] = (v[bj][j] * sn + v[bj][4 + j] * cs) * sc; }
;                         *(u32x2*)(dst + (size_t)row * 256 + head * 64 + i0) = pack4(o1);
;                         *(u32x2*)(dst + (size_t)row * 256 + head * 64 + 32 + i0) = pack4(o2);
;                     }
	v_pk_fma_f32 v[206:207], v[124:125], v[194:195], v[144:145] op_sel_hi:[1,0,1]
	s_waitcnt vmcnt(6)
	v_pk_fma_f32 v[216:217], v[120:121], v[194:195], v[148:149] op_sel_hi:[1,0,1]
	v_pk_fma_f32 v[228:229], v[122:123], v[194:195], v[150:151] op_sel_hi:[1,0,1]
	v_pk_mul_f32 v[218:219], v[204:205], v[216:217]
	v_pk_mul_f32 v[216:217], v[202:203], v[216:217]
	v_pk_fma_f32 v[218:219], v[202:203], v[206:207], v[218:219]
	v_pk_fma_f32 v[206:207], v[204:205], v[206:207], v[216:217] neg_lo:[0,0,1] neg_hi:[0,0,1]
	v_pk_mul_f32 v[216:217], v[218:219], s[8:9] op_sel_hi:[1,0]
	v_sin_f32_e32 v218, v193
	v_sin_f32_e32 v219, v191
	v_pk_fma_f32 v[222:223], v[126:127], v[194:195], v[146:147] op_sel_hi:[1,0,1]
	v_pk_mul_f32 v[230:231], v[220:221], v[228:229]
	v_pk_mul_f32 v[206:207], v[206:207], s[8:9] op_sel_hi:[1,0]
	v_pk_mul_f32 v[228:229], v[218:219], v[228:229]
	v_pk_fma_f32 v[230:231], v[218:219], v[222:223], v[230:231]
	v_pk_fma_f32 v[222:223], v[220:221], v[222:223], v[228:229] neg_lo:[0,0,1] neg_hi:[0,0,1]
	v_pk_mul_f32 v[230:231], v[230:231], s[8:9] op_sel_hi:[1,0]
	v_pk_mul_f32 v[222:223], v[222:223], s[8:9] op_sel_hi:[1,0]
	v_cvt_pk_bf16_f32 v206, v206, v207
	v_cvt_pk_bf16_f32 v207, v222, v223
	global_store_dwordx2 v[200:201], v[206:207], off
	v_cvt_pk_bf16_f32 v206, v216, v217
	v_cvt_pk_bf16_f32 v207, v230, v231
	s_waitcnt vmcnt(5)
	v_pk_fma_f32 v[216:217], v[112:113], v[194:195], v[152:153] op_sel_hi:[1,0,1]
	v_add_u32_e32 v191, 16, v189
	global_store_dwordx2 v[200:201], v[206:207], off offset:64
	v_pk_fma_f32 v[206:207], v[116:117], v[194:195], v[156:157] op_sel_hi:[1,0,1]
	v_pk_mul_f32 v[222:223], v[204:205], v[216:217]
	v_cvt_f32_u32_e32 v191, v191
	v_pk_fma_f32 v[222:223], v[202:203], v[206:207], v[222:223]
	v_pk_mul_f32 v[202:203], v[202:203], v[216:217]
	v_pk_mul_f32 v[222:223], v[222:223], s[8:9] op_sel_hi:[1,0]
	v_pk_fma_f32 v[202:203], v[204:205], v[206:207], v[202:203] neg_lo:[0,0,1] neg_hi:[0,0,1]
	v_pk_fma_f32 v[204:205], v[118:119], v[194:195], v[158:159] op_sel_hi:[1,0,1]
	v_pk_fma_f32 v[194:195], v[114:115], v[194:195], v[154:155] op_sel_hi:[1,0,1]
	v_mul_f32_e32 v193, v171, v191
	v_pk_mul_f32 v[206:207], v[220:221], v[194:195]
	v_pk_mul_f32 v[194:195], v[218:219], v[194:195]
	v_pk_fma_f32 v[206:207], v[218:219], v[204:205], v[206:207]
	v_pk_fma_f32 v[194:195], v[220:221], v[204:205], v[194:195] neg_lo:[0,0,1] neg_hi:[0,0,1]
	v_pk_mul_f32 v[202:203], v[202:203], s[8:9] op_sel_hi:[1,0]
	v_pk_mul_f32 v[206:207], v[206:207], s[8:9] op_sel_hi:[1,0]
	v_pk_mul_f32 v[194:195], v[194:195], s[8:9] op_sel_hi:[1,0]
	v_mul_f32_e32 v193, 0.15915494, v193
	v_cvt_pk_bf16_f32 v202, v202, v203
	v_cvt_pk_bf16_f32 v203, v194, v195
	v_cvt_pk_bf16_f32 v194, v222, v223
	v_cvt_pk_bf16_f32 v195, v206, v207
	v_fract_f32_e32 v193, v193
	global_store_dwordx2 v[200:201], v[202:203], off offset:256
	global_store_dwordx2 v[200:201], v[194:195], off offset:320
	v_sin_f32_e32 v194, v193
	v_cos_f32_e32 v200, v193
	v_mul_f32_e32 v193, v161, v191
	v_mul_f32_e32 v193, 0.15915494, v193
	v_fract_f32_e32 v193, v193
	v_cos_f32_e32 v201, v193
	v_sin_f32_e32 v195, v193
	v_pk_fma_f32 v[202:203], v[108:109], v[190:191], v[144:145] op_sel_hi:[1,0,1]
	v_pk_fma_f32 v[204:205], v[104:105], v[190:191], v[148:149] op_sel_hi:[1,0,1]
	v_mul_f32_e32 v193, v173, v191
	v_mul_f32_e32 v191, v175, v191
	v_mul_f32_e32 v193, 0.15915494, v193
	v_mul_f32_e32 v191, 0.15915494, v191
	v_pk_mul_f32 v[206:207], v[200:201], v[204:205]
	v_pk_mul_f32 v[204:205], v[194:195], v[204:205]
	v_fract_f32_e32 v193, v193
	v_fract_f32_e32 v191, v191
	v_pk_fma_f32 v[206:207], v[194:195], v[202:203], v[206:207]
	v_pk_fma_f32 v[202:203], v[200:201], v[202:203], v[204:205] neg_lo:[0,0,1] neg_hi:[0,0,1]
	v_sin_f32_e32 v204, v193
	v_cos_f32_e32 v216, v193
	v_cos_f32_e32 v217, v191
	v_sin_f32_e32 v205, v191
	v_pk_fma_f32 v[220:221], v[106:107], v[190:191], v[150:151] op_sel_hi:[1,0,1]
	v_pk_fma_f32 v[218:219], v[110:111], v[190:191], v[146:147] op_sel_hi:[1,0,1]
	v_pk_mul_f32 v[222:223], v[216:217], v[220:221]
	v_pk_mul_f32 v[220:221], v[204:205], v[220:221]
	v_pk_fma_f32 v[222:223], v[204:205], v[218:219], v[222:223]
	v_pk_fma_f32 v[218:219], v[216:217], v[218:219], v[220:221] neg_lo:[0,0,1] neg_hi:[0,0,1]
	v_pk_mul_f32 v[202:203], v[202:203], s[8:9] op_sel_hi:[1,0]
	v_pk_mul_f32 v[218:219], v[218:219], s[8:9] op_sel_hi:[1,0]
	v_pk_mul_f32 v[206:207], v[206:207], s[8:9] op_sel_hi:[1,0]
	v_pk_mul_f32 v[222:223], v[222:223], s[8:9] op_sel_hi:[1,0]
	v_cvt_pk_bf16_f32 v202, v202, v203
	v_cvt_pk_bf16_f32 v203, v218, v219
	global_store_dwordx2 v[164:165], v[202:203], off
	v_cvt_pk_bf16_f32 v202, v206, v207
	v_cvt_pk_bf16_f32 v203, v222, v223
	v_pk_fma_f32 v[206:207], v[96:97], v[190:191], v[152:153] op_sel_hi:[1,0,1]
	global_store_dwordx2 v[164:165], v[202:203], off offset:64
	v_pk_fma_f32 v[202:203], v[100:101], v[190:191], v[156:157] op_sel_hi:[1,0,1]
	v_pk_mul_f32 v[218:219], v[200:201], v[206:207]
	v_add_u32_e32 v193, 32, v189
	v_pk_fma_f32 v[218:219], v[194:195], v[202:203], v[218:219]
	v_pk_mul_f32 v[194:195], v[194:195], v[206:207]
	v_cvt_f32_u32_e32 v193, v193
	v_pk_fma_f32 v[194:195], v[200:201], v[202:203], v[194:195] neg_lo:[0,0,1] neg_hi:[0,0,1]
	v_pk_fma_f32 v[200:201], v[102:103], v[190:191], v[158:159] op_sel_hi:[1,0,1]
	v_pk_fma_f32 v[190:191], v[98:99], v[190:191], v[154:155] op_sel_hi:[1,0,1]
	v_pk_mul_f32 v[218:219], v[218:219], s[8:9] op_sel_hi:[1,0]
	v_pk_mul_f32 v[202:203], v[216:217], v[190:191]
	v_pk_mul_f32 v[190:191], v[204:205], v[190:191]
	v_pk_fma_f32 v[202:203], v[204:205], v[200:201], v[202:203]
	v_pk_fma_f32 v[190:191], v[216:217], v[200:201], v[190:191] neg_lo:[0,0,1] neg_hi:[0,0,1]
; DI u32x2 pack4(const float* v) { u32x2 w; w.x = pk2(v[0], v[1]); w.y = pk2(v[2], v[3]); return w; }
; DI float ex2(float x) { return __builtin_amdgcn_exp2f(x); }
; DI void sincos_rev(float ang, float& s, float& c) { float rev = ang * 0.15915494309189535f; rev = __builtin_amdgcn_fractf(rev); s = __builtin_amdgcn_sinf(rev); c = __builtin_amdgcn_cosf(rev); }
;     template <int PN> DI void body(AccRef acc, const Unit& u, int wr, int wc, int fr, int fq) const {
;     ...
;                 } else if constexpr (PN == 3 || PN == 4) {
;                     bf16_t* dst = PN == 3 ? rq : rk;
;                     const float sc = PN == 3 ? 0.125f : 1.f;
; #pragma unroll
;                     for (int bj = 0; bj < 2; ++bj) {
;                         const int head = 2 * bj + (wc >> 1), i0 = 16 * (wc & 1) + 4 * fq;
;                         float o1[4], o2[4];
; #pragma unroll
;                         for (int j = 0; j < 4; ++j) { float sn, cs; sincos_rev((float)pos * ex2(-(float)(i0 + j) * KEXP64), sn, cs);
;                             o1[j] = (v[bj][j] * cs - v[bj][4 + j] * sn) * sc; o2[j] = (v[bj][j] * sn + v[bj][4 + j] * cs) * sc; }
;                         *(u32x2*)(dst + (size_t)row * 256 + head * 64 + i0) = pack4(o1);
;                         *(u32x2*)(dst + (size_t)row * 256 + head * 64 + 32 + i0) = pack4(o2);
;                     }
	v_pk_mul_f32 v[194:195], v[194:195], s[8:9] op_sel_hi:[1,0]
	v_pk_mul_f32 v[202:203], v[202:203], s[8:9] op_sel_hi:[1,0]
	v_pk_mul_f32 v[190:191], v[190:191], s[8:9] op_sel_hi:[1,0]
	v_cvt_pk_bf16_f32 v194, v194, v195
	v_cvt_pk_bf16_f32 v195, v190, v191
	v_cvt_pk_bf16_f32 v190, v218, v219
	v_cvt_pk_bf16_f32 v191, v202, v203
	global_store_dwordx2 v[164:165], v[194:195], off offset:256
	global_store_dwordx2 v[164:165], v[190:191], off offset:320
	v_lshlrev_b64 v[164:165], 9, v[166:167]
	v_mul_f32_e32 v166, v171, v193
	v_mul_f32_e32 v166, 0.15915494, v166
	v_fract_f32_e32 v167, v166
	v_sin_f32_e32 v166, v167
	v_cos_f32_e32 v190, v167
	v_mul_f32_e32 v167, v161, v193
	v_mul_f32_e32 v167, 0.15915494, v167
	v_fract_f32_e32 v167, v167
	v_cos_f32_e32 v191, v167
	v_sin_f32_e32 v167, v167
	v_mul_f32_e32 v197, v173, v193
	v_mul_f32_e32 v193, v175, v193
	v_pk_fma_f32 v[200:201], v[88:89], v[174:175], v[148:149] op_sel_hi:[1,0,1]
	v_mul_f32_e32 v197, 0.15915494, v197
	v_mul_f32_e32 v193, 0.15915494, v193
	v_pk_fma_f32 v[194:195], v[92:93], v[174:175], v[144:145] op_sel_hi:[1,0,1]
	v_pk_mul_f32 v[202:203], v[190:191], v[200:201]
	v_pk_mul_f32 v[200:201], v[166:167], v[200:201]
	v_fract_f32_e32 v197, v197
	v_fract_f32_e32 v193, v193
	v_pk_fma_f32 v[202:203], v[166:167], v[194:195], v[202:203]
	v_pk_fma_f32 v[194:195], v[190:191], v[194:195], v[200:201] neg_lo:[0,0,1] neg_hi:[0,0,1]
	v_sin_f32_e32 v200, v197
	v_cos_f32_e32 v204, v197
	v_cos_f32_e32 v205, v193
	v_sin_f32_e32 v201, v193
	v_pk_fma_f32 v[216:217], v[90:91], v[174:175], v[150:151] op_sel_hi:[1,0,1]
	v_pk_fma_f32 v[206:207], v[94:95], v[174:175], v[146:147] op_sel_hi:[1,0,1]
	v_pk_mul_f32 v[218:219], v[204:205], v[216:217]
	v_pk_mul_f32 v[216:217], v[200:201], v[216:217]
	v_lshl_add_u64 v[164:165], s[16:17], 0, v[164:165]
	v_pk_fma_f32 v[218:219], v[200:201], v[206:207], v[218:219]
	v_pk_fma_f32 v[206:207], v[204:205], v[206:207], v[216:217] neg_lo:[0,0,1] neg_hi:[0,0,1]
	v_pk_mul_f32 v[194:195], v[194:195], s[8:9] op_sel_hi:[1,0]
	v_pk_mul_f32 v[206:207], v[206:207], s[8:9] op_sel_hi:[1,0]
	v_lshl_add_u64 v[164:165], v[164:165], 0, s[4:5]
	v_pk_mul_f32 v[202:203], v[202:203], s[8:9] op_sel_hi:[1,0]
	v_pk_mul_f32 v[218:219], v[218:219], s[8:9] op_sel_hi:[1,0]
	v_cvt_pk_bf16_f32 v194, v194, v195
	v_cvt_pk_bf16_f32 v195, v206, v207
	v_lshl_add_u64 v[164:165], v[164:165], 0, v[198:199]
	global_store_dwordx2 v[164:165], v[194:195], off
	v_cvt_pk_bf16_f32 v194, v202, v203
	v_cvt_pk_bf16_f32 v195, v218, v219
	v_pk_fma_f32 v[202:203], v[80:81], v[174:175], v[152:153] op_sel_hi:[1,0,1]
	global_store_dwordx2 v[164:165], v[194:195], off offset:64
	v_pk_fma_f32 v[194:195], v[84:85], v[174:175], v[156:157] op_sel_hi:[1,0,1]
	v_pk_mul_f32 v[206:207], v[190:191], v[202:203]
	v_pk_fma_f32 v[148:149], v[72:73], v[170:171], v[148:149] op_sel_hi:[1,0,1]
	v_pk_fma_f32 v[206:207], v[166:167], v[194:195], v[206:207]
	v_pk_mul_f32 v[166:167], v[166:167], v[202:203]
	v_pk_mul_f32 v[206:207], v[206:207], s[8:9] op_sel_hi:[1,0]
	v_pk_fma_f32 v[166:167], v[190:191], v[194:195], v[166:167] neg_lo:[0,0,1] neg_hi:[0,0,1]
	v_pk_fma_f32 v[194:195], v[82:83], v[174:175], v[154:155] op_sel_hi:[1,0,1]
	v_pk_fma_f32 v[190:191], v[86:87], v[174:175], v[158:159] op_sel_hi:[1,0,1]
	v_pk_mul_f32 v[202:203], v[204:205], v[194:195]
	v_pk_mul_f32 v[194:195], v[200:201], v[194:195]
	v_add_u32_e32 v174, 48, v189
	v_pk_fma_f32 v[202:203], v[200:201], v[190:191], v[202:203]
	v_pk_fma_f32 v[190:191], v[204:205], v[190:191], v[194:195] neg_lo:[0,0,1] neg_hi:[0,0,1]
	v_cvt_f32_u32_e32 v174, v174
	v_pk_mul_f32 v[166:167], v[166:167], s[8:9] op_sel_hi:[1,0]
	v_pk_mul_f32 v[190:191], v[190:191], s[8:9] op_sel_hi:[1,0]
	v_pk_mul_f32 v[202:203], v[202:203], s[8:9] op_sel_hi:[1,0]
	v_cvt_pk_bf16_f32 v166, v166, v167
	v_cvt_pk_bf16_f32 v167, v190, v191
	global_store_dwordx2 v[164:165], v[166:167], off offset:256
	v_cvt_pk_bf16_f32 v166, v206, v207
	v_cvt_pk_bf16_f32 v167, v202, v203
	global_store_dwordx2 v[164:165], v[166:167], off offset:320
	v_mul_f32_e32 v164, v171, v174
	v_mul_f32_e32 v164, 0.15915494, v164
	v_fract_f32_e32 v165, v164
	v_sin_f32_e32 v164, v165
	v_cos_f32_e32 v166, v165
	v_mul_f32_e32 v165, v161, v174
	v_mul_f32_e32 v165, 0.15915494, v165
	v_fract_f32_e32 v165, v165
	v_cos_f32_e32 v167, v165
	v_sin_f32_e32 v165, v165
	v_pk_fma_f32 v[144:145], v[76:77], v[170:171], v[144:145] op_sel_hi:[1,0,1]
	v_pk_fma_f32 v[150:151], v[74:75], v[170:171], v[150:151] op_sel_hi:[1,0,1]
	v_pk_mul_f32 v[190:191], v[166:167], v[148:149]
	v_pk_mul_f32 v[148:149], v[164:165], v[148:149]
	v_pk_fma_f32 v[190:191], v[164:165], v[144:145], v[190:191]
	v_pk_fma_f32 v[144:145], v[166:167], v[144:145], v[148:149] neg_lo:[0,0,1] neg_hi:[0,0,1]
	v_mul_f32_e32 v148, v173, v174
	v_mul_f32_e32 v148, 0.15915494, v148
	v_fract_f32_e32 v149, v148
	v_sin_f32_e32 v148, v149
	v_cos_f32_e32 v194, v149
	v_mul_f32_e32 v149, v175, v174
	v_mul_f32_e32 v149, 0.15915494, v149
	v_fract_f32_e32 v149, v149
	v_cos_f32_e32 v195, v149
	v_sin_f32_e32 v149, v149
	v_pk_fma_f32 v[146:147], v[78:79], v[170:171], v[146:147] op_sel_hi:[1,0,1]
	v_pk_mul_f32 v[144:145], v[144:145], s[8:9] op_sel_hi:[1,0]
	v_pk_mul_f32 v[200:201], v[194:195], v[150:151]
	v_pk_mul_f32 v[150:151], v[148:149], v[150:151]
	v_pk_fma_f32 v[200:201], v[148:149], v[146:147], v[200:201]
	v_pk_fma_f32 v[146:147], v[194:195], v[146:147], v[150:151] neg_lo:[0,0,1] neg_hi:[0,0,1]
	v_cvt_pk_bf16_f32 v144, v144, v145
	v_pk_mul_f32 v[146:147], v[146:147], s[8:9] op_sel_hi:[1,0]
	v_pk_mul_f32 v[190:191], v[190:191], s[8:9] op_sel_hi:[1,0]
	v_cvt_pk_bf16_f32 v145, v146, v147
	v_lshl_add_u64 v[146:147], v[162:163], 0, s[4:5]
; DI u32x2 pack4(const float* v) { u32x2 w; w.x = pk2(v[0], v[1]); w.y = pk2(v[2], v[3]); return w; }
; DI float ex2(float x) { return __builtin_amdgcn_exp2f(x); }
; DI void sincos_rev(float ang, float& s, float& c) { float rev = ang * 0.15915494309189535f; rev = __builtin_amdgcn_fractf(rev); s = __builtin_amdgcn_sinf(rev); c = __builtin_amdgcn_cosf(rev); }
;     template <int PN> DI void body(AccRef acc, const Unit& u, int wr, int wc, int fr, int fq) const {
;     ...
;                 } else if constexpr (PN == 3 || PN == 4) {
;                     bf16_t* dst = PN == 3 ? rq : rk;
;                     const float sc = PN == 3 ? 0.125f : 1.f;
; #pragma unroll
;                     for (int bj = 0; bj < 2; ++bj) {
;                         const int head = 2 * bj + (wc >> 1), i0 = 16 * (wc & 1) + 4 * fq;
;                         float o1[4], o2[4];
; #pragma unroll
;                         for (int j = 0; j < 4; ++j) { float sn, cs; sincos_rev((float)pos * ex2(-(float)(i0 + j) * KEXP64), sn, cs);
;                             o1[j] = (v[bj][j] * cs - v[bj][4 + j] * sn) * sc; o2[j] = (v[bj][j] * sn + v[bj][4 + j] * cs) * sc; }
;                         *(u32x2*)(dst + (size_t)row * 256 + head * 64 + i0) = pack4(o1);
;                         *(u32x2*)(dst + (size_t)row * 256 + head * 64 + 32 + i0) = pack4(o2);
;                     }
	v_pk_mul_f32 v[200:201], v[200:201], s[8:9] op_sel_hi:[1,0]
	v_lshl_add_u64 v[146:147], v[146:147], 0, v[198:199]
	global_store_dwordx2 v[146:147], v[144:145], off
	v_cvt_pk_bf16_f32 v144, v190, v191
	v_cvt_pk_bf16_f32 v145, v200, v201
	v_pk_fma_f32 v[150:151], v[64:65], v[170:171], v[152:153] op_sel_hi:[1,0,1]
	global_store_dwordx2 v[146:147], v[144:145], off offset:64
	v_pk_fma_f32 v[144:145], v[68:69], v[170:171], v[156:157] op_sel_hi:[1,0,1]
	v_pk_mul_f32 v[152:153], v[166:167], v[150:151]
	v_pk_mul_f32 v[150:151], v[164:165], v[150:151]
	v_pk_fma_f32 v[154:155], v[66:67], v[170:171], v[154:155] op_sel_hi:[1,0,1]
	v_pk_fma_f32 v[152:153], v[164:165], v[144:145], v[152:153]
	v_pk_fma_f32 v[144:145], v[166:167], v[144:145], v[150:151] neg_lo:[0,0,1] neg_hi:[0,0,1]
	v_pk_fma_f32 v[150:151], v[70:71], v[170:171], v[158:159] op_sel_hi:[1,0,1]
	v_pk_mul_f32 v[156:157], v[194:195], v[154:155]
	v_pk_mul_f32 v[144:145], v[144:145], s[8:9] op_sel_hi:[1,0]
	v_pk_fma_f32 v[156:157], v[148:149], v[150:151], v[156:157]
	v_pk_mul_f32 v[148:149], v[148:149], v[154:155]
	v_pk_mul_f32 v[152:153], v[152:153], s[8:9] op_sel_hi:[1,0]
	v_pk_fma_f32 v[148:149], v[194:195], v[150:151], v[148:149] neg_lo:[0,0,1] neg_hi:[0,0,1]
	v_pk_mul_f32 v[156:157], v[156:157], s[8:9] op_sel_hi:[1,0]
	v_pk_mul_f32 v[148:149], v[148:149], s[8:9] op_sel_hi:[1,0]
	v_cvt_pk_bf16_f32 v144, v144, v145
	v_cvt_pk_bf16_f32 v145, v148, v149
	global_store_dwordx2 v[146:147], v[144:145], off offset:256
	v_cvt_pk_bf16_f32 v144, v152, v153
	v_cvt_pk_bf16_f32 v145, v156, v157
	global_store_dwordx2 v[146:147], v[144:145], off offset:320
	v_and_b32_e32 v144, 0x7ff, v168
	v_cndmask_b32_e32 v166, v169, v144, vcc
	v_cvt_f32_u32_e32 v157, v166
	s_waitcnt vmcnt(17)
	v_pk_fma_f32 v[152:153], v[56:57], v[196:197], v[136:137] op_sel_hi:[1,0,1]
	v_pk_fma_f32 v[150:151], v[60:61], v[196:197], v[140:141] op_sel_hi:[1,0,1]
	v_ashrrev_i32_e32 v169, 31, v168
	v_mul_f32_e32 v146, v171, v157
	v_mul_f32_e32 v146, 0.15915494, v146
	v_fract_f32_e32 v147, v146
	v_sin_f32_e32 v146, v147
	v_cos_f32_e32 v148, v147
	v_mul_f32_e32 v147, v161, v157
	v_mul_f32_e32 v147, 0.15915494, v147
	v_fract_f32_e32 v147, v147
	v_cos_f32_e32 v149, v147
	v_sin_f32_e32 v147, v147
	v_pk_fma_f32 v[162:163], v[58:59], v[196:197], v[138:139] op_sel_hi:[1,0,1]
	v_lshlrev_b64 v[144:145], 9, v[168:169]
	v_pk_mul_f32 v[154:155], v[148:149], v[152:153]
	v_pk_mul_f32 v[152:153], v[146:147], v[152:153]
	v_pk_fma_f32 v[154:155], v[146:147], v[150:151], v[154:155]
	v_pk_fma_f32 v[150:151], v[148:149], v[150:151], v[152:153] neg_lo:[0,0,1] neg_hi:[0,0,1]
	v_mul_f32_e32 v152, v173, v157
	v_mul_f32_e32 v152, 0.15915494, v152
	v_fract_f32_e32 v153, v152
	v_sin_f32_e32 v152, v153
	v_cos_f32_e32 v156, v153
	v_mul_f32_e32 v153, v175, v157
	v_mul_f32_e32 v153, 0.15915494, v153
	v_fract_f32_e32 v153, v153
	v_cos_f32_e32 v157, v153
	v_sin_f32_e32 v153, v153
	v_pk_fma_f32 v[158:159], v[62:63], v[196:197], v[142:143] op_sel_hi:[1,0,1]
	v_lshl_add_u64 v[144:145], s[16:17], 0, v[144:145]
	v_pk_mul_f32 v[164:165], v[156:157], v[162:163]
	v_pk_mul_f32 v[162:163], v[152:153], v[162:163]
	v_pk_fma_f32 v[164:165], v[152:153], v[158:159], v[164:165]
	v_pk_fma_f32 v[158:159], v[156:157], v[158:159], v[162:163] neg_lo:[0,0,1] neg_hi:[0,0,1]
	v_pk_mul_f32 v[150:151], v[150:151], s[8:9] op_sel_hi:[1,0]
	v_pk_mul_f32 v[158:159], v[158:159], s[8:9] op_sel_hi:[1,0]
	v_lshl_add_u64 v[144:145], v[144:145], 0, s[4:5]
	v_pk_mul_f32 v[154:155], v[154:155], s[8:9] op_sel_hi:[1,0]
	v_pk_mul_f32 v[164:165], v[164:165], s[8:9] op_sel_hi:[1,0]
	v_cvt_pk_bf16_f32 v150, v150, v151
	v_cvt_pk_bf16_f32 v151, v158, v159
	v_lshl_add_u64 v[144:145], v[144:145], 0, v[198:199]
	global_store_dwordx2 v[144:145], v[150:151], off
	v_cvt_pk_bf16_f32 v150, v154, v155
	v_cvt_pk_bf16_f32 v151, v164, v165
	v_pk_fma_f32 v[154:155], v[48:49], v[196:197], v[128:129] op_sel_hi:[1,0,1]
	global_store_dwordx2 v[144:145], v[150:151], off offset:64
	s_waitcnt vmcnt(18)
	v_pk_fma_f32 v[150:151], v[52:53], v[196:197], v[132:133] op_sel_hi:[1,0,1]
	v_pk_mul_f32 v[158:159], v[148:149], v[154:155]
	v_pk_fma_f32 v[162:163], v[42:43], v[192:193], v[138:139] op_sel_hi:[1,0,1]
	v_pk_fma_f32 v[158:159], v[146:147], v[150:151], v[158:159]
	v_pk_mul_f32 v[146:147], v[146:147], v[154:155]
	v_pk_mul_f32 v[158:159], v[158:159], s[8:9] op_sel_hi:[1,0]
	v_pk_fma_f32 v[146:147], v[148:149], v[150:151], v[146:147] neg_lo:[0,0,1] neg_hi:[0,0,1]
	v_pk_fma_f32 v[150:151], v[50:51], v[196:197], v[130:131] op_sel_hi:[1,0,1]
	v_pk_fma_f32 v[148:149], v[54:55], v[196:197], v[134:135] op_sel_hi:[1,0,1]
	v_pk_mul_f32 v[154:155], v[156:157], v[150:151]
	v_pk_mul_f32 v[150:151], v[152:153], v[150:151]
	v_pk_fma_f32 v[154:155], v[152:153], v[148:149], v[154:155]
	v_pk_fma_f32 v[148:149], v[156:157], v[148:149], v[150:151] neg_lo:[0,0,1] neg_hi:[0,0,1]
	v_pk_mul_f32 v[146:147], v[146:147], s[8:9] op_sel_hi:[1,0]
	v_pk_mul_f32 v[148:149], v[148:149], s[8:9] op_sel_hi:[1,0]
	v_pk_mul_f32 v[154:155], v[154:155], s[8:9] op_sel_hi:[1,0]
	v_cvt_pk_bf16_f32 v146, v146, v147
	v_cvt_pk_bf16_f32 v147, v148, v149
	global_store_dwordx2 v[144:145], v[146:147], off offset:256
	v_cvt_pk_bf16_f32 v146, v158, v159
	v_cvt_pk_bf16_f32 v147, v154, v155
	global_store_dwordx2 v[144:145], v[146:147], off offset:320
	v_add_u32_e32 v145, 16, v166
	v_cvt_f32_u32_e32 v157, v145
	v_pk_fma_f32 v[152:153], v[40:41], v[192:193], v[136:137] op_sel_hi:[1,0,1]
	v_pk_fma_f32 v[150:151], v[44:45], v[192:193], v[140:141] op_sel_hi:[1,0,1]
	v_add_u32_e32 v144, 0x90, v160
	v_mul_f32_e32 v146, v171, v157
	v_mul_f32_e32 v146, 0.15915494, v146
	v_fract_f32_e32 v147, v146
; DI u32x2 pack4(const float* v) { u32x2 w; w.x = pk2(v[0], v[1]); w.y = pk2(v[2], v[3]); return w; }
; DI float ex2(float x) { return __builtin_amdgcn_exp2f(x); }
; DI void sincos_rev(float ang, float& s, float& c) { float rev = ang * 0.15915494309189535f; rev = __builtin_amdgcn_fractf(rev); s = __builtin_amdgcn_sinf(rev); c = __builtin_amdgcn_cosf(rev); }
;     template <int PN> DI void body(AccRef acc, const Unit& u, int wr, int wc, int fr, int fq) const {
;     ...
;                 } else if constexpr (PN == 3 || PN == 4) {
;                     bf16_t* dst = PN == 3 ? rq : rk;
;                     const float sc = PN == 3 ? 0.125f : 1.f;
; #pragma unroll
;                     for (int bj = 0; bj < 2; ++bj) {
;                         const int head = 2 * bj + (wc >> 1), i0 = 16 * (wc & 1) + 4 * fq;
;                         float o1[4], o2[4];
; #pragma unroll
;                         for (int j = 0; j < 4; ++j) { float sn, cs; sincos_rev((float)pos * ex2(-(float)(i0 + j) * KEXP64), sn, cs);
;                             o1[j] = (v[bj][j] * cs - v[bj][4 + j] * sn) * sc; o2[j] = (v[bj][j] * sn + v[bj][4 + j] * cs) * sc; }
;                         *(u32x2*)(dst + (size_t)row * 256 + head * 64 + i0) = pack4(o1);
;                         *(u32x2*)(dst + (size_t)row * 256 + head * 64 + 32 + i0) = pack4(o2);
;                     }
	v_sin_f32_e32 v146, v147
	v_cos_f32_e32 v148, v147
	v_mul_f32_e32 v147, v161, v157
	v_mul_f32_e32 v147, 0.15915494, v147
	v_fract_f32_e32 v147, v147
	v_cos_f32_e32 v149, v147
	v_sin_f32_e32 v147, v147
	v_ashrrev_i32_e32 v145, 31, v144
	v_lshlrev_b64 v[144:145], 9, v[144:145]
	v_pk_mul_f32 v[154:155], v[148:149], v[152:153]
	v_pk_mul_f32 v[152:153], v[146:147], v[152:153]
	v_pk_fma_f32 v[154:155], v[146:147], v[150:151], v[154:155]
	v_pk_fma_f32 v[150:151], v[148:149], v[150:151], v[152:153] neg_lo:[0,0,1] neg_hi:[0,0,1]
	v_mul_f32_e32 v152, v173, v157
	v_mul_f32_e32 v152, 0.15915494, v152
	v_fract_f32_e32 v153, v152
	v_sin_f32_e32 v152, v153
	v_cos_f32_e32 v156, v153
	v_mul_f32_e32 v153, v175, v157
	v_mul_f32_e32 v153, 0.15915494, v153
	v_fract_f32_e32 v153, v153
	v_cos_f32_e32 v157, v153
	v_sin_f32_e32 v153, v153
	v_pk_fma_f32 v[158:159], v[46:47], v[192:193], v[142:143] op_sel_hi:[1,0,1]
	v_lshl_add_u64 v[144:145], s[16:17], 0, v[144:145]
	v_pk_mul_f32 v[164:165], v[156:157], v[162:163]
	v_pk_mul_f32 v[162:163], v[152:153], v[162:163]
	v_pk_fma_f32 v[164:165], v[152:153], v[158:159], v[164:165]
	v_pk_fma_f32 v[158:159], v[156:157], v[158:159], v[162:163] neg_lo:[0,0,1] neg_hi:[0,0,1]
	v_pk_mul_f32 v[150:151], v[150:151], s[8:9] op_sel_hi:[1,0]
	v_pk_mul_f32 v[158:159], v[158:159], s[8:9] op_sel_hi:[1,0]
	v_lshl_add_u64 v[144:145], v[144:145], 0, s[4:5]
	v_pk_mul_f32 v[154:155], v[154:155], s[8:9] op_sel_hi:[1,0]
	v_pk_mul_f32 v[164:165], v[164:165], s[8:9] op_sel_hi:[1,0]
	v_cvt_pk_bf16_f32 v150, v150, v151
	v_cvt_pk_bf16_f32 v151, v158, v159
	v_lshl_add_u64 v[144:145], v[144:145], 0, v[198:199]
	global_store_dwordx2 v[144:145], v[150:151], off
	v_cvt_pk_bf16_f32 v150, v154, v155
	v_cvt_pk_bf16_f32 v151, v164, v165
	v_pk_fma_f32 v[154:155], v[28:29], v[192:193], v[128:129] op_sel_hi:[1,0,1]
	global_store_dwordx2 v[144:145], v[150:151], off offset:64
	v_pk_fma_f32 v[150:151], v[36:37], v[192:193], v[132:133] op_sel_hi:[1,0,1]
	v_pk_mul_f32 v[158:159], v[148:149], v[154:155]
	v_pk_fma_f32 v[162:163], v[26:27], v[188:189], v[138:139] op_sel_hi:[1,0,1]
	v_pk_fma_f32 v[158:159], v[146:147], v[150:151], v[158:159]
	v_pk_mul_f32 v[146:147], v[146:147], v[154:155]
	v_pk_mul_f32 v[158:159], v[158:159], s[8:9] op_sel_hi:[1,0]
	v_pk_fma_f32 v[146:147], v[148:149], v[150:151], v[146:147] neg_lo:[0,0,1] neg_hi:[0,0,1]
	v_pk_fma_f32 v[150:151], v[30:31], v[192:193], v[130:131] op_sel_hi:[1,0,1]
	v_pk_fma_f32 v[148:149], v[38:39], v[192:193], v[134:135] op_sel_hi:[1,0,1]
	v_pk_mul_f32 v[154:155], v[156:157], v[150:151]
	v_pk_mul_f32 v[150:151], v[152:153], v[150:151]
	v_pk_fma_f32 v[154:155], v[152:153], v[148:149], v[154:155]
	v_pk_fma_f32 v[148:149], v[156:157], v[148:149], v[150:151] neg_lo:[0,0,1] neg_hi:[0,0,1]
	v_pk_mul_f32 v[146:147], v[146:147], s[8:9] op_sel_hi:[1,0]
	v_pk_mul_f32 v[148:149], v[148:149], s[8:9] op_sel_hi:[1,0]
	v_pk_mul_f32 v[154:155], v[154:155], s[8:9] op_sel_hi:[1,0]
	v_cvt_pk_bf16_f32 v146, v146, v147
	v_cvt_pk_bf16_f32 v147, v148, v149
	global_store_dwordx2 v[144:145], v[146:147], off offset:256
	v_cvt_pk_bf16_f32 v146, v158, v159
	v_cvt_pk_bf16_f32 v147, v154, v155
	global_store_dwordx2 v[144:145], v[146:147], off offset:320
	v_add_u32_e32 v145, 32, v166
	v_cvt_f32_u32_e32 v157, v145
	v_pk_fma_f32 v[152:153], v[24:25], v[188:189], v[136:137] op_sel_hi:[1,0,1]
	v_pk_fma_f32 v[150:151], v[32:33], v[188:189], v[140:141] op_sel_hi:[1,0,1]
	v_add_u32_e32 v144, 0xa0, v160
	v_mul_f32_e32 v146, v171, v157
	v_mul_f32_e32 v146, 0.15915494, v146
	v_fract_f32_e32 v147, v146
	v_sin_f32_e32 v146, v147
	v_cos_f32_e32 v148, v147
	v_mul_f32_e32 v147, v161, v157
	v_mul_f32_e32 v147, 0.15915494, v147
	v_fract_f32_e32 v147, v147
	v_cos_f32_e32 v149, v147
	v_sin_f32_e32 v147, v147
	v_ashrrev_i32_e32 v145, 31, v144
	v_lshlrev_b64 v[144:145], 9, v[144:145]
	v_pk_mul_f32 v[154:155], v[148:149], v[152:153]
	v_pk_mul_f32 v[152:153], v[146:147], v[152:153]
	v_pk_fma_f32 v[154:155], v[146:147], v[150:151], v[154:155]
	v_pk_fma_f32 v[150:151], v[148:149], v[150:151], v[152:153] neg_lo:[0,0,1] neg_hi:[0,0,1]
	v_mul_f32_e32 v152, v173, v157
	v_mul_f32_e32 v152, 0.15915494, v152
	v_fract_f32_e32 v153, v152
	v_sin_f32_e32 v152, v153
	v_cos_f32_e32 v156, v153
	v_mul_f32_e32 v153, v175, v157
	v_mul_f32_e32 v153, 0.15915494, v153
	v_fract_f32_e32 v153, v153
	v_cos_f32_e32 v157, v153
	v_sin_f32_e32 v153, v153
	v_pk_fma_f32 v[158:159], v[34:35], v[188:189], v[142:143] op_sel_hi:[1,0,1]
	v_lshl_add_u64 v[144:145], s[16:17], 0, v[144:145]
	v_pk_mul_f32 v[164:165], v[156:157], v[162:163]
	v_pk_mul_f32 v[162:163], v[152:153], v[162:163]
	v_pk_fma_f32 v[164:165], v[152:153], v[158:159], v[164:165]
	v_pk_fma_f32 v[158:159], v[156:157], v[158:159], v[162:163] neg_lo:[0,0,1] neg_hi:[0,0,1]
	v_pk_mul_f32 v[150:151], v[150:151], s[8:9] op_sel_hi:[1,0]
	v_pk_mul_f32 v[158:159], v[158:159], s[8:9] op_sel_hi:[1,0]
	v_lshl_add_u64 v[144:145], v[144:145], 0, s[4:5]
	v_pk_mul_f32 v[154:155], v[154:155], s[8:9] op_sel_hi:[1,0]
	v_pk_mul_f32 v[164:165], v[164:165], s[8:9] op_sel_hi:[1,0]
	v_cvt_pk_bf16_f32 v150, v150, v151
	v_cvt_pk_bf16_f32 v151, v158, v159
	v_lshl_add_u64 v[144:145], v[144:145], 0, v[198:199]
	global_store_dwordx2 v[144:145], v[150:151], off
	v_cvt_pk_bf16_f32 v150, v154, v155
	v_cvt_pk_bf16_f32 v151, v164, v165
	v_pk_fma_f32 v[154:155], v[16:17], v[188:189], v[128:129] op_sel_hi:[1,0,1]
	global_store_dwordx2 v[144:145], v[150:151], off offset:64
	v_pk_fma_f32 v[150:151], v[20:21], v[188:189], v[132:133] op_sel_hi:[1,0,1]
	v_pk_mul_f32 v[158:159], v[148:149], v[154:155]
	v_pk_fma_f32 v[136:137], v[8:9], v[172:173], v[136:137] op_sel_hi:[1,0,1]
; DI u32x2 pack4(const float* v) { u32x2 w; w.x = pk2(v[0], v[1]); w.y = pk2(v[2], v[3]); return w; }
; DI float ex2(float x) { return __builtin_amdgcn_exp2f(x); }
; DI void sincos_rev(float ang, float& s, float& c) { float rev = ang * 0.15915494309189535f; rev = __builtin_amdgcn_fractf(rev); s = __builtin_amdgcn_sinf(rev); c = __builtin_amdgcn_cosf(rev); }
;     template <int PN> DI void body(AccRef acc, const Unit& u, int wr, int wc, int fr, int fq) const {
;     ...
;                 } else if constexpr (PN == 3 || PN == 4) {
;                     bf16_t* dst = PN == 3 ? rq : rk;
;                     const float sc = PN == 3 ? 0.125f : 1.f;
; #pragma unroll
;                     for (int bj = 0; bj < 2; ++bj) {
;                         const int head = 2 * bj + (wc >> 1), i0 = 16 * (wc & 1) + 4 * fq;
;                         float o1[4], o2[4];
; #pragma unroll
;                         for (int j = 0; j < 4; ++j) { float sn, cs; sincos_rev((float)pos * ex2(-(float)(i0 + j) * KEXP64), sn, cs);
;                             o1[j] = (v[bj][j] * cs - v[bj][4 + j] * sn) * sc; o2[j] = (v[bj][j] * sn + v[bj][4 + j] * cs) * sc; }
;                         *(u32x2*)(dst + (size_t)row * 256 + head * 64 + i0) = pack4(o1);
;                         *(u32x2*)(dst + (size_t)row * 256 + head * 64 + 32 + i0) = pack4(o2);
;                     }
	v_pk_fma_f32 v[158:159], v[146:147], v[150:151], v[158:159]
	v_pk_mul_f32 v[146:147], v[146:147], v[154:155]
	v_pk_mul_f32 v[158:159], v[158:159], s[8:9] op_sel_hi:[1,0]
	v_pk_fma_f32 v[146:147], v[148:149], v[150:151], v[146:147] neg_lo:[0,0,1] neg_hi:[0,0,1]
	v_pk_fma_f32 v[150:151], v[18:19], v[188:189], v[130:131] op_sel_hi:[1,0,1]
	v_pk_fma_f32 v[148:149], v[22:23], v[188:189], v[134:135] op_sel_hi:[1,0,1]
	v_pk_mul_f32 v[154:155], v[156:157], v[150:151]
	v_pk_mul_f32 v[150:151], v[152:153], v[150:151]
	v_pk_fma_f32 v[154:155], v[152:153], v[148:149], v[154:155]
	v_pk_fma_f32 v[148:149], v[156:157], v[148:149], v[150:151] neg_lo:[0,0,1] neg_hi:[0,0,1]
	v_pk_mul_f32 v[146:147], v[146:147], s[8:9] op_sel_hi:[1,0]
	v_pk_mul_f32 v[148:149], v[148:149], s[8:9] op_sel_hi:[1,0]
	v_pk_mul_f32 v[154:155], v[154:155], s[8:9] op_sel_hi:[1,0]
	v_cvt_pk_bf16_f32 v146, v146, v147
	v_cvt_pk_bf16_f32 v147, v148, v149
	global_store_dwordx2 v[144:145], v[146:147], off offset:256
	v_cvt_pk_bf16_f32 v146, v158, v159
	v_cvt_pk_bf16_f32 v147, v154, v155
	global_store_dwordx2 v[144:145], v[146:147], off offset:320
	v_add_u32_e32 v145, 48, v166
	v_cvt_f32_u32_e32 v153, v145
	v_pk_fma_f32 v[140:141], v[12:13], v[172:173], v[140:141] op_sel_hi:[1,0,1]
	v_add_u32_e32 v144, 0xb0, v160
	v_pk_fma_f32 v[138:139], v[10:11], v[172:173], v[138:139] op_sel_hi:[1,0,1]
	v_mul_f32_e32 v146, v171, v153
	v_mul_f32_e32 v146, 0.15915494, v146
	v_fract_f32_e32 v147, v146
	v_sin_f32_e32 v146, v147
	v_cos_f32_e32 v148, v147
	v_mul_f32_e32 v147, v161, v153
	v_mul_f32_e32 v147, 0.15915494, v147
	v_fract_f32_e32 v147, v147
	v_cos_f32_e32 v149, v147
	v_sin_f32_e32 v147, v147
	v_ashrrev_i32_e32 v145, 31, v144
	v_pk_fma_f32 v[142:143], v[14:15], v[172:173], v[142:143] op_sel_hi:[1,0,1]
	v_pk_mul_f32 v[150:151], v[148:149], v[136:137]
	v_pk_mul_f32 v[136:137], v[146:147], v[136:137]
	v_pk_fma_f32 v[150:151], v[146:147], v[140:141], v[150:151]
	v_pk_fma_f32 v[136:137], v[148:149], v[140:141], v[136:137] neg_lo:[0,0,1] neg_hi:[0,0,1]
	v_mul_f32_e32 v140, v173, v153
	v_mul_f32_e32 v140, 0.15915494, v140
	v_fract_f32_e32 v141, v140
	v_sin_f32_e32 v140, v141
	v_cos_f32_e32 v152, v141
	v_mul_f32_e32 v141, v175, v153
	v_mul_f32_e32 v141, 0.15915494, v141
	v_fract_f32_e32 v141, v141
	v_cos_f32_e32 v153, v141
	v_sin_f32_e32 v141, v141
	v_lshlrev_b64 v[144:145], 9, v[144:145]
	v_lshl_add_u64 v[144:145], s[16:17], 0, v[144:145]
	v_pk_mul_f32 v[154:155], v[152:153], v[138:139]
	v_pk_mul_f32 v[138:139], v[140:141], v[138:139]
	v_pk_mul_f32 v[136:137], v[136:137], s[8:9] op_sel_hi:[1,0]
	v_pk_fma_f32 v[138:139], v[152:153], v[142:143], v[138:139] neg_lo:[0,0,1] neg_hi:[0,0,1]
	v_pk_fma_f32 v[154:155], v[140:141], v[142:143], v[154:155]
	v_pk_mul_f32 v[138:139], v[138:139], s[8:9] op_sel_hi:[1,0]
	v_cvt_pk_bf16_f32 v136, v136, v137
	v_cvt_pk_bf16_f32 v137, v138, v139
	v_lshl_add_u64 v[138:139], v[144:145], 0, s[4:5]
	v_pk_mul_f32 v[150:151], v[150:151], s[8:9] op_sel_hi:[1,0]
	v_pk_mul_f32 v[154:155], v[154:155], s[8:9] op_sel_hi:[1,0]
	v_lshl_add_u64 v[138:139], v[138:139], 0, v[198:199]
	global_store_dwordx2 v[138:139], v[136:137], off
	v_cvt_pk_bf16_f32 v136, v150, v151
	v_cvt_pk_bf16_f32 v137, v154, v155
	v_pk_fma_f32 v[128:129], v[0:1], v[172:173], v[128:129] op_sel_hi:[1,0,1]
	global_store_dwordx2 v[138:139], v[136:137], off offset:64
	v_pk_fma_f32 v[132:133], v[4:5], v[172:173], v[132:133] op_sel_hi:[1,0,1]
	v_pk_mul_f32 v[136:137], v[148:149], v[128:129]
	v_pk_mul_f32 v[128:129], v[146:147], v[128:129]
	v_pk_fma_f32 v[130:131], v[2:3], v[172:173], v[130:131] op_sel_hi:[1,0,1]
	v_pk_fma_f32 v[136:137], v[146:147], v[132:133], v[136:137]
	v_pk_fma_f32 v[128:129], v[148:149], v[132:133], v[128:129] neg_lo:[0,0,1] neg_hi:[0,0,1]
	v_pk_fma_f32 v[132:133], v[6:7], v[172:173], v[134:135] op_sel_hi:[1,0,1]
	v_pk_mul_f32 v[134:135], v[152:153], v[130:131]
	v_pk_mul_f32 v[130:131], v[140:141], v[130:131]
	v_pk_mul_f32 v[128:129], v[128:129], s[8:9] op_sel_hi:[1,0]
	v_pk_fma_f32 v[130:131], v[152:153], v[132:133], v[130:131] neg_lo:[0,0,1] neg_hi:[0,0,1]
	v_pk_fma_f32 v[134:135], v[140:141], v[132:133], v[134:135]
	v_pk_mul_f32 v[130:131], v[130:131], s[8:9] op_sel_hi:[1,0]
	v_pk_mul_f32 v[136:137], v[136:137], s[8:9] op_sel_hi:[1,0]
	v_pk_mul_f32 v[134:135], v[134:135], s[8:9] op_sel_hi:[1,0]
	v_cvt_pk_bf16_f32 v128, v128, v129
	v_cvt_pk_bf16_f32 v129, v130, v131
	global_store_dwordx2 v[138:139], v[128:129], off offset:256
	v_cvt_pk_bf16_f32 v128, v136, v137
	v_cvt_pk_bf16_f32 v129, v134, v135
	global_store_dwordx2 v[138:139], v[128:129], off offset:320
	s_mov_b64 s[4:5], 0
; DI u32x4 pack8(const float* v) { u32x4 w; w.x = pk2(v[0], v[1]); w.y = pk2(v[2], v[3]); w.z = pk2(v[4], v[5]); w.w = pk2(v[6], v[7]); return w; }
; DI float sum16(const float* p) { const f32x4* q = (const f32x4*)p; f32x4 a = q[0], b = q[1], c = q[2], d = q[3]; f32x4 s = (a + b) + (c + d); return (s[0] + s[1]) + (s[2] + s[3]); }
;     template <int PN> DI void body(AccRef acc, const Unit& u, int wr, int wc, int fr, int fq) const {
;     ...
; #pragma unroll
;         for (int ai = 0; ai < 2; ++ai) {
;             const int rb_ = u.pm * 256 + ai * 128 + wr * 64 + fr;
; #pragma unroll
;             for (int m = 0; m < 4; ++m) rinvh[ai][m] = rsqrtf(sum16(ssq + (size_t)(rb_ + 16 * m + zdep) * 16) * (1.f / 1024.f) + EPS);
;             asm volatile("v_mov_b32 %0, 0" : "=v"(zdep) : "v"(rinvh[ai][0]), "v"(rinvh[ai][1]), "v"(rinvh[ai][2]), "v"(rinvh[ai][3]));
;         }
; #pragma unroll
;         for (int ai = 0; ai < 2; ++ai) {
;             const int rb_ = u.pm * 256 + ai * 128 + wr * 64 + fr;
;             int mb_, p_, k_; row_info(rb_, mb_, p_, k_);
; #pragma unroll
;             for (int bj = 0; bj < 2; ++bj)
; #pragma unroll
;                 for (int n = 0; n < 2; ++n) cvh[ai][bj][n] = *(const f32x4*)(cv + (size_t)(mb_ + zdep) * NIN + PN * 256 + bj * 128 + cl + 4 * n);
;         }
; #pragma unroll
;         for (int ai = 0; ai < 2; ++ai) {
;             const int rb = u.pm * 256 + ai * 128 + wr * 64 + fr;
;             int mb, pos0, kv0; row_info(rb, mb, pos0, kv0);
; #pragma unroll
;             for (int m = 0; m < 4; ++m) {
;                 const int row = rb + 16 * m, pos = pos0 + 16 * m, kvrow = kv0 + 16 * m;
;                 const float rinv = rinvh[ai][m];
;                 float v[2][8];
; #pragma unroll
;                 for (int bj = 0; bj < 2; ++bj)
; #pragma unroll
;                     for (int n = 0; n < 2; ++n)
; #pragma unroll
;                         for (int j = 0; j < 4; ++j) v[bj][4 * n + j] = acc[ai][bj][m][n][j] * rinv + cvh[ai][bj][n][j];
;     ...
;                 } else if constexpr (PN == 2) {
;                     float s = 0.f;
;                     *(u32x4*)(zq + (size_t)row * 384 + 256 + cl) = pack8(v[0]);
; #pragma unroll
;                     for (int j = 0; j < 8; ++j) s += v[0][j] * v[0][j];
;                     s = xor16_32(s);
;                     if (fq == 0) ssqq[(size_t)row * 8 + 4 + wc] = s;
.LBB0_1748:
	s_andn2_b64 vcc, exec, s[4:5]
	s_cbranch_vccnz .LBB0_1786
	s_lshl_b32 s4, s43, 6
	s_lshl_b32 s5, s34, 8
	s_add_i32 s4, s4, s5
	v_add_u32_e32 v160, s4, v214
	v_add_u32_e32 v190, 16, v160
	v_ashrrev_i32_e32 v161, 31, v160
	v_ashrrev_i32_e32 v191, 31, v190
	v_lshlrev_b64 v[128:129], 6, v[160:161]
	v_lshlrev_b64 v[144:145], 6, v[190:191]
	v_add_u32_e32 v174, 32, v160
	v_lshl_add_u64 v[140:141], s[70:71], 0, v[128:129]
	v_lshl_add_u64 v[144:145], s[70:71], 0, v[144:145]
	v_ashrrev_i32_e32 v175, 31, v174
	s_nop 0
	s_nop 0
	v_lshlrev_b64 v[144:145], 6, v[174:175]
	v_add_u32_e32 v172, 48, v160
	v_lshl_add_u64 v[144:145], s[70:71], 0, v[144:145]
	v_ashrrev_i32_e32 v173, 31, v172
	v_lshlrev_b64 v[144:145], 6, v[172:173]
	v_lshl_add_u64 v[144:145], s[70:71], 0, v[144:145]
	s_mov_b32 s4, 0x358637bd
	v_mov_b64_e32 v[144:145], s[4:5]
	s_mov_b32 s10, 0x3a800000
	s_mov_b64 s[12:13], 0x124800
	v_mov_b32_e32 v202, v245
	v_mov_b32_e32 v196, v246
	v_add_u32_e32 v162, 0x80, v160
	v_mov_b32_e32 v204, v244
	v_mov_b32_e32 v192, v247
	v_mov_b32 v128, 0
	v_cmp_gt_i32_e64 s[8:9], s94, v162
	v_add_u32_e32 v158, v128, v162
	v_ashrrev_i32_e32 v159, 31, v158
	v_add_u32_e32 v146, 16, v158
	v_lshlrev_b64 v[128:129], 6, v[158:159]
	v_ashrrev_i32_e32 v147, 31, v146
	v_add_u32_e32 v168, 32, v158
	v_lshl_add_u64 v[140:141], s[70:71], 0, v[128:129]
	v_lshlrev_b64 v[146:147], 6, v[146:147]
	v_ashrrev_i32_e32 v169, 31, v168
	v_add_u32_e32 v158, 48, v158
	s_nop 0
	v_lshl_add_u64 v[164:165], s[70:71], 0, v[146:147]
	v_lshlrev_b64 v[168:169], 6, v[168:169]
	v_ashrrev_i32_e32 v159, 31, v158
	s_nop 0
	v_lshl_add_u64 v[188:189], s[70:71], 0, v[168:169]
	v_lshlrev_b64 v[158:159], 6, v[158:159]
	v_lshl_add_u64 v[158:159], s[70:71], 0, v[158:159]
	v_mov_b32_e32 v194, v248
	v_mov_b32_e32 v188, v249
	v_mov_b32_e32 v170, v250
	v_mov_b32_e32 v166, v251
	v_add_u32_e32 v129, 0xffffc000, v160
	v_lshrrev_b32_e32 v164, 6, v129
	s_lshl_b32 s4, s54, 5
	v_ashrrev_i32_e32 v128, 11, v160
	v_add_u32_e32 v129, 8, v164
	v_cmp_gt_i32_e64 s[6:7], s94, v160
	v_lshl_add_u32 v168, v213, 3, s4
	v_mov_b32 v136, 0
	v_ashrrev_i32_e32 v169, 31, v168
	v_cndmask_b32_e64 v128, v129, v128, s[6:7]
	v_add_u32_e32 v130, v136, v128
	v_mov_b64_e32 v[128:129], s[60:61]
	s_movk_i32 s10, 0x2800
	v_mad_i64_i32 v[130:131], s[4:5], v130, s10, v[128:129]
	v_lshlrev_b64 v[132:133], 2, v[168:169]
	v_lshl_add_u64 v[130:131], v[130:131], 0, v[132:133]
	s_mov_b32 s4, 0x124000
	v_lshl_add_u64 v[134:135], v[130:131], 0, s[12:13]
	v_add_co_u32_e32 v130, vcc, s4, v130
	v_add_u32_e32 v171, 0xffffc080, v160
	s_nop 0
	v_addc_co_u32_e32 v131, vcc, 0, v131, vcc
	v_lshrrev_b32_e32 v163, 6, v171
	global_load_dwordx4 v[152:155], v[130:131], off offset:2048
	global_load_dwordx4 v[144:147], v[134:135], off offset:528
	global_load_dwordx4 v[156:159], v[134:135], off offset:16
	global_load_dwordx4 v[148:151], v[134:135], off offset:512
	v_ashrrev_i32_e32 v130, 11, v162
	v_add_u32_e32 v131, 8, v163
	v_cndmask_b32_e64 v130, v131, v130, s[8:9]
	v_add_u32_e32 v130, v136, v130
	v_mad_i64_i32 v[128:129], s[4:5], v130, s10, v[128:129]
	v_lshl_add_u64 v[128:129], v[128:129], 0, v[132:133]
	v_lshl_add_u64 v[132:133], v[128:129], 0, s[12:13]
	v_add_co_u32_e32 v128, vcc, 0x124000, v128
	s_movk_i32 s4, 0x3fff
	s_nop 0
	v_addc_co_u32_e32 v129, vcc, 0, v129, vcc
	global_load_dwordx4 v[136:139], v[128:129], off offset:2048
	s_nop 0
	global_load_dwordx4 v[128:131], v[132:133], off offset:528
	global_load_dwordx4 v[140:143], v[132:133], off offset:16
	s_nop 0
	global_load_dwordx4 v[132:135], v[132:133], off offset:512
	v_and_b32_e32 v165, 63, v214
	v_cmp_lt_i32_e32 vcc, s4, v160
	v_cmp_lt_i32_e64 s[10:11], s4, v162
	v_or_b32_e32 v198, 0x4400, v165
	s_and_saveexec_b64 s[4:5], vcc
	s_xor_b64 s[4:5], exec, s[4:5]
	s_movk_i32 s12, 0x440
	v_mad_u64_u32 v[200:201], s[12:13], v164, s12, v[198:199]
	s_or_saveexec_b64 s[4:5], s[4:5]
	v_or_b32_e32 v199, 0x400, v165
	v_mov_b32_e32 v189, v199
	s_xor_b64 exec, exec, s[4:5]
	v_and_b32_e32 v189, 0x7ff, v160
	v_mov_b32_e32 v200, v160
	s_or_b64 exec, exec, s[4:5]
	v_lshlrev_b32_e32 v164, 2, v214
	v_lshl_add_u32 v164, v213, 6, v164
	v_xor_b32_e32 v206, 64, v164
	v_xor_b32_e32 v167, 0x80, v164
	s_waitcnt vmcnt(7)
	v_pk_fma_f32 v[164:165], v[124:125], v[204:205], v[152:153] op_sel_hi:[1,0,1]
	v_pk_fma_f32 v[220:221], v[126:127], v[204:205], v[154:155] op_sel_hi:[1,0,1]
	v_cvt_pk_bf16_f32 v216, v164, v165
	v_pk_mul_f32 v[164:165], v[164:165], v[164:165]
	v_cvt_pk_bf16_f32 v217, v220, v221
	v_pk_mul_f32 v[220:221], v[220:221], v[220:221]
	v_add_f32_e32 v164, v164, v165
	s_waitcnt vmcnt(5)
	v_pk_fma_f32 v[222:223], v[120:121], v[204:205], v[156:157] op_sel_hi:[1,0,1]
	v_add_f32_e32 v164, v220, v164
	v_cvt_pk_bf16_f32 v218, v222, v223
	v_pk_mul_f32 v[222:223], v[222:223], v[222:223]
	v_add_f32_e32 v164, v221, v164
	v_pk_fma_f32 v[228:229], v[122:123], v[204:205], v[158:159] op_sel_hi:[1,0,1]
	v_add_f32_e32 v164, v222, v164
	v_cvt_pk_bf16_f32 v219, v228, v229
	v_pk_mul_f32 v[228:229], v[228:229], v[228:229]
	v_add_f32_e32 v164, v223, v164
	v_add_f32_e32 v164, v228, v164
	v_add_f32_e32 v193, v229, v164
	s_ashr_i32 s55, s54, 31
	ds_bpermute_b32 v195, v206, v193
	s_lshl_b64 s[12:13], s[54:55], 2
	s_add_u32 s16, s95, s12
	v_readlane_b32 s12, v254, 50
	s_addc_u32 s17, s12, s13
	v_mov_b64_e32 v[164:165], s[14:15]
	s_movk_i32 s12, 0x300
	v_mad_i64_i32 v[164:165], s[12:13], v160, s12, v[164:165]
	v_lshl_add_u64 v[220:221], v[168:169], 1, v[164:165]
	s_waitcnt lgkmcnt(0)
	v_add_f32_e32 v164, v193, v195
	ds_bpermute_b32 v165, v167, v164
	s_mov_b32 s12, 0x4720000
	v_add_co_u32_e32 v220, vcc, s12, v220
	v_cmp_eq_u32_e64 s[4:5], 0, v213
	s_nop 0
	v_addc_co_u32_e32 v221, vcc, 0, v221, vcc
	global_store_dwordx4 v[220:221], v[216:219], off offset:512
	s_and_saveexec_b64 s[12:13], s[4:5]
	s_cbranch_execz .LBB0_1755
	v_lshlrev_b64 v[216:217], 5, v[160:161]
	v_lshl_add_u64 v[216:217], s[16:17], 0, v[216:217]
	s_waitcnt lgkmcnt(0)
	v_add_f32_e32 v164, v164, v165
	global_store_dword v[216:217], v164, off

;     template <int PN> DI void body(AccRef acc, const Unit& u, int wr, int wc, int fr, int fq) const {
;     ...
; #pragma unroll
;         for (int ai = 0; ai < 2; ++ai) {
;             const int rb_ = u.pm * 256 + ai * 128 + wr * 64 + fr;
; #pragma unroll
;             for (int m = 0; m < 4; ++m) rinvh[ai][m] = rsqrtf(sum16(ssq + (size_t)(rb_ + 16 * m + zdep) * 16) * (1.f / 1024.f) + EPS);
;             asm volatile("v_mov_b32 %0, 0" : "=v"(zdep) : "v"(rinvh[ai][0]), "v"(rinvh[ai][1]), "v"(rinvh[ai][2]), "v"(rinvh[ai][3]));
;         }
; #pragma unroll
;         for (int ai = 0; ai < 2; ++ai) {
;             const int rb_ = u.pm * 256 + ai * 128 + wr * 64 + fr;
;             int mb_, p_, k_; row_info(rb_, mb_, p_, k_);
; #pragma unroll
;             for (int bj = 0; bj < 2; ++bj)
; #pragma unroll
;                 for (int n = 0; n < 2; ++n) cvh[ai][bj][n] = *(const f32x4*)(cv + (size_t)(mb_ + zdep) * NIN + PN * 256 + bj * 128 + cl + 4 * n);
;         }
; #pragma unroll
;         for (int ai = 0; ai < 2; ++ai) {
;             const int rb = u.pm * 256 + ai * 128 + wr * 64 + fr;
;             int mb, pos0, kv0; row_info(rb, mb, pos0, kv0);
; #pragma unroll
;             for (int m = 0; m < 4; ++m) {
;                 const int row = rb + 16 * m, pos = pos0 + 16 * m, kvrow = kv0 + 16 * m;
;                 const float rinv = rinvh[ai][m];
;                 float v[2][8];
; #pragma unroll
;                 for (int bj = 0; bj < 2; ++bj)
; #pragma unroll
;                     for (int n = 0; n < 2; ++n)
; #pragma unroll
;                         for (int j = 0; j < 4; ++j) v[bj][4 * n + j] = acc[ai][bj][m][n][j] * rinv + cvh[ai][bj][n][j];
;                 if constexpr (PN == 0) {
;                     float s = 0.f;
; #pragma unroll
;                     for (int bj = 0; bj < 2; ++bj) {
;                         *(u32x4*)(zkv + (size_t)row * 256 + bj * 128 + cl) = pack8(v[bj]);
; #pragma unroll
;                         for (int j = 0; j < 8; ++j) s += v[bj][j] * v[bj][j];
;                     }
;                     s = xor16_32(s);
;                     if (fq == 0) { ssqkv[(size_t)row * 4 + wc] = s; *(LAS float*)(xl + ((ai * 128 + wr * 64 + 16 * m + fr) * 4 + wc) * 4) = s; }
;                 } else if constexpr (PN == 1) {
;                     float s = 0.f;
; #pragma unroll
;                     for (int bj = 0; bj < 2; ++bj) {
.LBB0_1787:
	s_andn2_b64 vcc, exec, s[4:5]
	s_mov_b64 s[10:11], 0
	s_cbranch_vccnz .LBB0_1808
	s_cmp_gt_i32 s66, 0
	s_mov_b64 s[4:5], -1
	s_cbranch_scc0 .LBB0_1806
	s_lshl_b32 s4, s54, 5
	v_lshl_add_u32 v190, v213, 3, s4
	s_lshl_b32 s4, s43, 6
	s_lshl_b32 s5, s34, 8
	s_add_i32 s4, s4, s5
	v_add_u32_e32 v160, s4, v214
	v_ashrrev_i32_e32 v161, 31, v160
	v_lshlrev_b64 v[128:129], 6, v[160:161]
	v_lshl_add_u64 v[140:141], s[70:71], 0, v[128:129]
	s_waitcnt lgkmcnt(0)
	s_nop 0
	v_add_u32_e32 v164, 16, v160
	v_ashrrev_i32_e32 v165, 31, v164
	s_mov_b32 s4, 0x358637bd
	s_mov_b32 s6, 0x3a800000
	v_add_u32_e32 v166, 32, v160
	v_ashrrev_i32_e32 v167, 31, v166
	v_add_u32_e32 v162, 48, v160
	v_ashrrev_i32_e32 v163, 31, v162
	v_add_u32_e32 v168, 0x80, v160
	v_ashrrev_i32_e32 v191, 31, v190
	s_mov_b64 s[8:9], 0x124400
	v_lshlrev_b32_e32 v169, 2, v214
	v_lshl_add_u32 v169, v213, 6, v169
	v_xor_b32_e32 v173, 64, v169
	v_xor_b32_e32 v171, 0x80, v169
	s_ashr_i32 s55, s54, 31
	s_nop 0
	v_lshlrev_b64 v[128:129], 6, v[164:165]
	v_lshl_add_u64 v[140:141], s[70:71], 0, v[128:129]
	s_nop 0
	s_nop 0
	v_mov_b64_e32 v[128:129], s[4:5]
	s_nop 0
	s_nop 0
	s_nop 0
	v_mov_b32_e32 v194, v244
	s_nop 0
	v_mov_b32_e32 v172, v245
	v_lshlrev_b64 v[130:131], 6, v[166:167]
	v_lshl_add_u64 v[142:143], s[70:71], 0, v[130:131]
	s_nop 0
	s_nop 0
	v_lshlrev_b64 v[130:131], 6, v[162:163]
	v_lshl_add_u64 v[142:143], s[70:71], 0, v[130:131]
	s_nop 0
	s_nop 0
	s_nop 0
	s_nop 0
	s_nop 0
	s_nop 0
	v_mov_b32_e32 v196, v246
	s_nop 0
	v_mov_b32_e32 v192, v247
	v_mov_b32 v130, 0
	s_nop 0
	v_add_u32_e32 v130, v130, v168
	v_ashrrev_i32_e32 v131, 31, v130
	v_lshlrev_b64 v[132:133], 6, v[130:131]
	v_lshl_add_u64 v[144:145], s[70:71], 0, v[132:133]
	s_nop 0
	s_nop 0
	v_add_u32_e32 v132, 16, v130
	v_ashrrev_i32_e32 v133, 31, v132
	v_lshlrev_b64 v[132:133], 6, v[132:133]
	v_lshl_add_u64 v[144:145], s[70:71], 0, v[132:133]
	s_nop 0
	s_nop 0
	s_nop 0
	s_nop 0
	s_nop 0
	s_nop 0
	v_mov_b32_e32 v174, v248
	s_nop 0
	v_mov_b32_e32 v170, v249
	v_add_u32_e32 v132, 32, v130
	v_ashrrev_i32_e32 v133, 31, v132
	v_lshlrev_b64 v[132:133], 6, v[132:133]
	v_lshl_add_u64 v[144:145], s[70:71], 0, v[132:133]
	s_nop 0
	v_add_u32_e32 v130, 48, v130
	v_ashrrev_i32_e32 v131, 31, v130
	v_lshlrev_b64 v[130:131], 6, v[130:131]
	v_lshl_add_u64 v[142:143], s[70:71], 0, v[130:131]
	s_nop 0
	s_nop 0
	v_lshlrev_b64 v[132:133], 2, v[190:191]
	s_movk_i32 s6, 0x2800
	s_mov_b32 s7, 0x124000
	s_nop 0
	v_mov_b32_e32 v198, v250
	s_nop 0
	v_mov_b32_e32 v188, v251
	v_add_u32_e32 v129, 0xffffc000, v160
	v_lshrrev_b32_e32 v129, 6, v129
	v_cmp_gt_i32_e32 vcc, s94, v160
	v_ashrrev_i32_e32 v128, 11, v160
	v_add_u32_e32 v129, 8, v129
	v_cndmask_b32_e32 v128, v129, v128, vcc
	v_mov_b32 v136, 0
	s_nop 0
	v_add_u32_e32 v130, v136, v128
	v_mov_b64_e32 v[128:129], s[60:61]
	v_mad_i64_i32 v[130:131], s[4:5], v130, s6, v[128:129]
	v_lshl_add_u64 v[130:131], v[130:131], 0, v[132:133]
	v_lshl_add_u64 v[134:135], v[130:131], 0, s[8:9]
	v_add_co_u32_e32 v130, vcc, s7, v130
	s_nop 1
	v_addc_co_u32_e32 v131, vcc, 0, v131, vcc
	global_load_dwordx4 v[148:151], v[130:131], off offset:1024
	global_load_dwordx4 v[152:155], v[134:135], off offset:16
	global_load_dwordx4 v[144:147], v[134:135], off offset:528
	global_load_dwordx4 v[156:159], v[134:135], off offset:512
	v_add_u32_e32 v131, 0xffffc080, v160
	v_lshrrev_b32_e32 v131, 6, v131
	v_cmp_gt_i32_e32 vcc, s94, v168
	v_ashrrev_i32_e32 v130, 11, v168
	v_add_u32_e32 v131, 8, v131
	v_cndmask_b32_e32 v130, v131, v130, vcc
	v_add_u32_e32 v130, v136, v130
	v_mad_i64_i32 v[128:129], s[4:5], v130, s6, v[128:129]
	v_lshl_add_u64 v[128:129], v[128:129], 0, v[132:133]
	v_lshl_add_u64 v[140:141], v[128:129], 0, s[8:9]
	v_add_co_u32_e32 v128, vcc, s7, v128
	v_readlane_b32 s4, v254, 51
	s_nop 0
	v_addc_co_u32_e32 v129, vcc, 0, v129, vcc
	global_load_dwordx4 v[136:139], v[128:129], off offset:1024
	global_load_dwordx4 v[132:135], v[140:141], off offset:16
	s_nop 0
	global_load_dwordx4 v[128:131], v[140:141], off offset:528
	s_nop 0
	global_load_dwordx4 v[140:143], v[140:141], off offset:512
	v_readlane_b32 s5, v254, 52
	s_movk_i32 s6, 0x300
	v_cmp_eq_u32_e32 vcc, 0, v213
	v_lshl_add_u64 v[190:191], v[190:191], 1, s[4:5]
	v_mad_i64_i32 v[230:231], s[6:7], v160, s6, v[190:191]
	s_lshl_b64 s[4:5], s[54:55], 2
	s_add_u32 s4, s79, s4
	s_addc_u32 s5, s93, s5
	s_waitcnt vmcnt(7)
	v_pk_fma_f32 v[204:205], v[124:125], v[194:195], v[148:149] op_sel_hi:[1,0,1]
	v_pk_fma_f32 v[206:207], v[126:127], v[194:195], v[150:151] op_sel_hi:[1,0,1]
	v_cvt_pk_bf16_f32 v200, v204, v205
	v_pk_mul_f32 v[204:205], v[204:205], v[204:205]
	v_cvt_pk_bf16_f32 v201, v206, v207
	v_pk_mul_f32 v[206:207], v[206:207], v[206:207]
	v_add_f32_e32 v169, v204, v205
	s_waitcnt vmcnt(6)
	v_pk_fma_f32 v[216:217], v[120:121], v[194:195], v[152:153] op_sel_hi:[1,0,1]
	v_add_f32_e32 v169, v206, v169
	v_cvt_pk_bf16_f32 v202, v216, v217
	v_pk_mul_f32 v[216:217], v[216:217], v[216:217]
	v_add_f32_e32 v169, v207, v169
	v_pk_fma_f32 v[218:219], v[122:123], v[194:195], v[154:155] op_sel_hi:[1,0,1]
	v_add_f32_e32 v169, v216, v169
	s_waitcnt vmcnt(4)
	v_pk_fma_f32 v[220:221], v[116:117], v[194:195], v[156:157] op_sel_hi:[1,0,1]
	v_pk_fma_f32 v[222:223], v[118:119], v[194:195], v[158:159] op_sel_hi:[1,0,1]
	v_pk_fma_f32 v[228:229], v[112:113], v[194:195], v[144:145] op_sel_hi:[1,0,1]
	v_pk_fma_f32 v[194:195], v[114:115], v[194:195], v[146:147] op_sel_hi:[1,0,1]
	v_cvt_pk_bf16_f32 v203, v218, v219
	v_pk_mul_f32 v[218:219], v[218:219], v[218:219]
	v_add_f32_e32 v169, v217, v169
	global_store_dwordx4 v[230:231], v[200:203], off
	v_add_f32_e32 v169, v218, v169
	v_add_f32_e32 v169, v219, v169
	v_cvt_pk_bf16_f32 v200, v220, v221
	v_cvt_pk_bf16_f32 v201, v222, v223
	v_cvt_pk_bf16_f32 v202, v228, v229
	v_cvt_pk_bf16_f32 v203, v194, v195
	global_store_dwordx4 v[230:231], v[200:203], off offset:256
	v_pk_mul_f32 v[194:195], v[194:195], v[194:195]
	s_nop 0
	v_pk_mul_f32 v[200:201], v[220:221], v[220:221]
	v_pk_mul_f32 v[202:203], v[222:223], v[222:223]
	v_add_f32_e32 v169, v200, v169
	v_add_f32_e32 v169, v201, v169
	v_add_f32_e32 v169, v202, v169
	v_pk_mul_f32 v[220:221], v[228:229], v[228:229]
	v_add_f32_e32 v169, v203, v169
	v_add_f32_e32 v169, v220, v169
	v_add_f32_e32 v169, v221, v169
	v_add_f32_e32 v169, v194, v169
	v_add_f32_e32 v169, v195, v169
	ds_bpermute_b32 v175, v173, v169
	s_waitcnt lgkmcnt(0)
	v_add_f32_e32 v169, v169, v175
	ds_bpermute_b32 v175, v171, v169
	s_and_saveexec_b64 s[6:7], vcc
	s_cbranch_execz .LBB0_1791
	v_lshlrev_b64 v[194:195], 5, v[160:161]
	v_lshl_add_u64 v[194:195], s[4:5], 0, v[194:195]
	s_waitcnt lgkmcnt(0)
	v_add_f32_e32 v161, v169, v175
	global_store_dword v[194:195], v161, off

; DI float sum16(const float* p) { const f32x4* q = (const f32x4*)p; f32x4 a = q[0], b = q[1], c = q[2], d = q[3]; f32x4 s = (a + b) + (c + d); return (s[0] + s[1]) + (s[2] + s[3]); }
;     template <int PN> DI void body(AccRef acc, const Unit& u, int wr, int wc, int fr, int fq) const {
;     ...
; #pragma unroll
;         for (int ai = 0; ai < 2; ++ai) {
;             const int rb_ = u.pm * 256 + ai * 128 + wr * 64 + fr;
; #pragma unroll
;             for (int m = 0; m < 4; ++m) rinvh[ai][m] = rsqrtf(sum16(ssq + (size_t)(rb_ + 16 * m + zdep) * 16) * (1.f / 1024.f) + EPS);
;             asm volatile("v_mov_b32 %0, 0" : "=v"(zdep) : "v"(rinvh[ai][0]), "v"(rinvh[ai][1]), "v"(rinvh[ai][2]), "v"(rinvh[ai][3]));
;         }
; #pragma unroll
;         for (int ai = 0; ai < 2; ++ai) {
;             const int rb_ = u.pm * 256 + ai * 128 + wr * 64 + fr;
;             int mb_, p_, k_; row_info(rb_, mb_, p_, k_);
; #pragma unroll
;             for (int bj = 0; bj < 2; ++bj)
; #pragma unroll
;                 for (int n = 0; n < 2; ++n) cvh[ai][bj][n] = *(const f32x4*)(cv + (size_t)(mb_ + zdep) * NIN + PN * 256 + bj * 128 + cl + 4 * n);
;         }
; #pragma unroll
;         for (int ai = 0; ai < 2; ++ai) {
;             const int rb = u.pm * 256 + ai * 128 + wr * 64 + fr;
;             int mb, pos0, kv0; row_info(rb, mb, pos0, kv0);
; #pragma unroll
;             for (int m = 0; m < 4; ++m) {
;                 const int row = rb + 16 * m, pos = pos0 + 16 * m, kvrow = kv0 + 16 * m;
;                 const float rinv = rinvh[ai][m];
;                 float v[2][8];
; #pragma unroll
;                 for (int bj = 0; bj < 2; ++bj)
; #pragma unroll
;                     for (int n = 0; n < 2; ++n)
; #pragma unroll
;                         for (int j = 0; j < 4; ++j) v[bj][4 * n + j] = acc[ai][bj][m][n][j] * rinv + cvh[ai][bj][n][j];
;     ...
;                 } else {
;                     float* lo = orow(out, l, row, PN == 8 ? O_PSK : O_PSV, PN == 8 ? O_SSK : O_SSV, 256);
; #pragma unroll
;                     for (int bj = 0; bj < 2; ++bj) {
;                         *(f32x4*)(lo + bj * 128 + cl) = (f32x4){v[bj][0], v[bj][1], v[bj][2], v[bj][3]};
;                         *(f32x4*)(lo + bj * 128 + cl + 4) = (f32x4){v[bj][4], v[bj][5], v[bj][6], v[bj][7]};
;                     }
.LBB0_1808:
	s_and_b64 vcc, exec, s[80:81]
	s_cbranch_vccz .LBB0_1827
	s_lshl_b32 s4, s43, 6
	s_lshl_b32 s5, s34, 8
	s_add_i32 s4, s4, s5
	v_add_u32_e32 v160, s4, v214
	v_ashrrev_i32_e32 v161, 31, v160
	v_lshlrev_b64 v[128:129], 6, v[160:161]
	v_lshl_add_u64 v[140:141], s[70:71], 0, v[128:129]
	s_waitcnt lgkmcnt(0)
	s_nop 0
	v_add_u32_e32 v190, 16, v160
	v_ashrrev_i32_e32 v191, 31, v190
	s_mov_b32 s4, 0x358637bd
	s_mov_b32 s6, 0x3a800000
	v_add_u32_e32 v166, 32, v160
	v_ashrrev_i32_e32 v167, 31, v166
	v_add_u32_e32 v168, 48, v160
	v_ashrrev_i32_e32 v169, 31, v168
	v_add_u32_e32 v164, 0x80, v160
	s_movk_i32 s8, 0x2800
	s_mov_b64 s[10:11], 0x126400
	s_mov_b32 s9, 0x126000
	v_add_u32_e32 v163, 0xffffc080, v160
	v_mov_b32_e32 v165, 0xffffc400
	v_mov_b32_e32 v171, 0x4000
	s_nop 0
	v_lshlrev_b64 v[128:129], 6, v[190:191]
	v_lshl_add_u64 v[140:141], s[70:71], 0, v[128:129]
	s_nop 0
	s_nop 0
	v_mov_b64_e32 v[128:129], s[4:5]
	s_nop 0
	s_nop 0
	s_nop 0
	v_mov_b32_e32 v192, v244
	s_nop 0
	v_mov_b32_e32 v162, v245
	v_lshlrev_b64 v[130:131], 6, v[166:167]
	v_lshl_add_u64 v[142:143], s[70:71], 0, v[130:131]
	s_nop 0
	s_nop 0
	v_lshlrev_b64 v[130:131], 6, v[168:169]
	v_lshl_add_u64 v[142:143], s[70:71], 0, v[130:131]
	s_nop 0
	s_nop 0
	s_nop 0
	s_nop 0
	s_nop 0
	s_nop 0
	v_mov_b32_e32 v172, v246
	s_nop 0
	v_mov_b32_e32 v188, v247
	v_mov_b32 v130, 0
	s_nop 0
	v_add_u32_e32 v130, v130, v164
	v_ashrrev_i32_e32 v131, 31, v130
	v_lshlrev_b64 v[132:133], 6, v[130:131]
	v_lshl_add_u64 v[144:145], s[70:71], 0, v[132:133]
	s_nop 0
	s_nop 0
	v_add_u32_e32 v132, 16, v130
	v_ashrrev_i32_e32 v133, 31, v132
	v_lshlrev_b64 v[132:133], 6, v[132:133]
	v_lshl_add_u64 v[144:145], s[70:71], 0, v[132:133]
	s_nop 0
	s_nop 0
	s_nop 0
	s_nop 0
	s_nop 0
	s_nop 0
	v_mov_b32_e32 v174, v248
	s_nop 0
	v_mov_b32_e32 v170, v249
	v_add_u32_e32 v132, 32, v130
	v_ashrrev_i32_e32 v133, 31, v132
	v_lshlrev_b64 v[132:133], 6, v[132:133]
	v_lshl_add_u64 v[144:145], s[70:71], 0, v[132:133]
	s_nop 0
	v_add_u32_e32 v130, 48, v130
	v_ashrrev_i32_e32 v131, 31, v130
	v_lshlrev_b64 v[130:131], 6, v[130:131]
	v_lshl_add_u64 v[142:143], s[70:71], 0, v[130:131]
	s_nop 0
	s_nop 0
	s_nop 0
	s_nop 0
	s_nop 0
	s_nop 0
	v_mov_b32_e32 v196, v250
	s_lshl_b32 s4, s54, 5
	v_lshl_add_u32 v198, v213, 3, s4
	v_cmp_gt_i32_e64 s[4:5], s94, v160
	v_mov_b32_e32 v194, v251
	v_add_u32_e32 v129, 0xffffc000, v160
	v_lshrrev_b32_e32 v129, 6, v129
	v_ashrrev_i32_e32 v128, 11, v160
	v_add_u32_e32 v129, 8, v129
	v_cndmask_b32_e64 v128, v129, v128, s[4:5]
	v_mov_b32 v134, 0
	v_ashrrev_i32_e32 v199, 31, v198
	v_add_u32_e32 v130, v134, v128
	v_mov_b64_e32 v[128:129], s[60:61]
	v_mad_i64_i32 v[130:131], s[6:7], v130, s8, v[128:129]
	v_lshlrev_b64 v[200:201], 2, v[198:199]
	v_lshl_add_u64 v[130:131], v[130:131], 0, v[200:201]
	v_lshl_add_u64 v[132:133], v[130:131], 0, s[10:11]
	v_add_co_u32_e32 v130, vcc, s9, v130
	s_movk_i32 s6, 0x3fff
	s_nop 0
	v_addc_co_u32_e32 v131, vcc, 0, v131, vcc
	global_load_dwordx4 v[152:155], v[130:131], off offset:1024
	global_load_dwordx4 v[156:159], v[132:133], off offset:16
	global_load_dwordx4 v[144:147], v[132:133], off offset:528
	global_load_dwordx4 v[148:151], v[132:133], off offset:512
	v_lshrrev_b32_e32 v131, 6, v163
	v_cmp_lt_i32_e32 vcc, s6, v164
	v_cmp_gt_i32_e64 s[6:7], s94, v164
	v_ashrrev_i32_e32 v130, 11, v164
	v_add_u32_e32 v131, 8, v131
	v_cndmask_b32_e64 v130, v131, v130, s[6:7]
	v_add_u32_e32 v130, v134, v130
	v_mad_i64_i32 v[128:129], s[6:7], v130, s8, v[128:129]
	v_lshl_add_u64 v[128:129], v[128:129], 0, v[200:201]
	v_lshl_add_u64 v[132:133], v[128:129], 0, s[10:11]
	v_add_co_u32_e64 v128, s[6:7], s9, v128
	v_cndmask_b32_e64 v203, -1, 0, s[4:5]
	s_nop 0
	v_addc_co_u32_e64 v129, s[6:7], 0, v129, s[6:7]
	global_load_dwordx4 v[140:143], v[128:129], off offset:1024
	global_load_dwordx4 v[136:139], v[132:133], off offset:16
	s_nop 0
	global_load_dwordx4 v[128:131], v[132:133], off offset:528
	s_nop 0
	global_load_dwordx4 v[132:135], v[132:133], off offset:512
	v_cndmask_b32_e64 v202, v165, v171, s[4:5]
	v_mov_b32_e32 v165, 0xad98000
	v_mov_b32_e32 v171, 0x8800000
	v_lshl_add_u64 v[202:203], v[202:203], 0, v[160:161]
	v_cndmask_b32_e64 v224, v165, v171, s[4:5]
	v_lshl_add_u64 v[204:205], s[84:85], 0, v[224:225]
	v_lshlrev_b64 v[202:203], 10, v[202:203]
	v_lshl_add_u64 v[202:203], v[204:205], 0, v[202:203]
	v_lshl_add_u64 v[206:207], v[202:203], 0, v[200:201]
	s_movk_i32 s6, 0xc410
	v_mov_b32_e32 v224, v160
	s_mov_b32 s7, -1
	v_cmp_gt_i32_e64 s[4:5], s82, v160
	s_movk_i32 s8, 0xc420
	s_mov_b32 s9, -1
	s_waitcnt vmcnt(7)
	v_pk_fma_f32 v[204:205], v[126:127], v[192:193], v[154:155] op_sel_hi:[1,0,1]
	v_pk_fma_f32 v[202:203], v[124:125], v[192:193], v[152:153] op_sel_hi:[1,0,1]
	global_store_dwordx4 v[206:207], v[202:205], off
	s_waitcnt vmcnt(7)
	s_nop 0
	v_pk_fma_f32 v[204:205], v[122:123], v[192:193], v[158:159] op_sel_hi:[1,0,1]
	v_pk_fma_f32 v[202:203], v[120:121], v[192:193], v[156:157] op_sel_hi:[1,0,1]
	global_store_dwordx4 v[206:207], v[202:205], off offset:16
	s_waitcnt vmcnt(6)
;     template <int PN> DI void body(AccRef acc, const Unit& u, int wr, int wc, int fr, int fq) const {
;     ...
;                 } else {
;                     float* lo = orow(out, l, row, PN == 8 ? O_PSK : O_PSV, PN == 8 ? O_SSK : O_SSV, 256);
; #pragma unroll
;                     for (int bj = 0; bj < 2; ++bj) {
;                         *(f32x4*)(lo + bj * 128 + cl) = (f32x4){v[bj][0], v[bj][1], v[bj][2], v[bj][3]};
;                         *(f32x4*)(lo + bj * 128 + cl + 4) = (f32x4){v[bj][4], v[bj][5], v[bj][6], v[bj][7]};
;                     }
	s_nop 0
	v_pk_fma_f32 v[204:205], v[118:119], v[192:193], v[150:151] op_sel_hi:[1,0,1]
	v_pk_fma_f32 v[202:203], v[116:117], v[192:193], v[148:149] op_sel_hi:[1,0,1]
	global_store_dwordx4 v[206:207], v[202:205], off offset:512
	s_nop 1
	v_pk_fma_f32 v[204:205], v[114:115], v[192:193], v[146:147] op_sel_hi:[1,0,1]
	v_pk_fma_f32 v[202:203], v[112:113], v[192:193], v[144:145] op_sel_hi:[1,0,1]
	v_lshl_add_u64 v[192:193], v[224:225], 0, s[6:7]
	s_mov_b64 s[6:7], 0x4000
	v_lshl_add_u64 v[190:191], v[190:191], 0, s[6:7]
	v_cndmask_b32_e64 v191, v193, v191, s[4:5]
	v_cndmask_b32_e64 v190, v192, v190, s[4:5]
	v_cndmask_b32_e64 v192, v165, v171, s[4:5]
	v_mov_b32_e32 v193, v225
	v_lshl_add_u64 v[192:193], s[84:85], 0, v[192:193]
	v_lshlrev_b64 v[190:191], 10, v[190:191]
	v_lshl_add_u64 v[190:191], v[192:193], 0, v[190:191]
	global_store_dwordx4 v[206:207], v[202:205], off offset:528
	v_pk_fma_f32 v[192:193], v[110:111], v[162:163], v[154:155] op_sel_hi:[1,0,1]
	v_cmp_gt_i32_e64 s[4:5], s83, v160
	v_lshl_add_u64 v[202:203], v[190:191], 0, v[200:201]
	v_pk_fma_f32 v[190:191], v[108:109], v[162:163], v[152:153] op_sel_hi:[1,0,1]
	global_store_dwordx4 v[202:203], v[190:193], off
	v_lshl_add_u64 v[166:167], v[166:167], 0, s[6:7]
	s_nop 0
	v_pk_fma_f32 v[192:193], v[106:107], v[162:163], v[158:159] op_sel_hi:[1,0,1]
	v_pk_fma_f32 v[190:191], v[104:105], v[162:163], v[156:157] op_sel_hi:[1,0,1]
	global_store_dwordx4 v[202:203], v[190:193], off offset:16
	s_nop 1
	v_pk_fma_f32 v[192:193], v[102:103], v[162:163], v[150:151] op_sel_hi:[1,0,1]
	v_pk_fma_f32 v[190:191], v[100:101], v[162:163], v[148:149] op_sel_hi:[1,0,1]
	global_store_dwordx4 v[202:203], v[190:193], off offset:512
	s_nop 1
	v_pk_fma_f32 v[192:193], v[98:99], v[162:163], v[146:147] op_sel_hi:[1,0,1]
	v_pk_fma_f32 v[190:191], v[96:97], v[162:163], v[144:145] op_sel_hi:[1,0,1]
	global_store_dwordx4 v[202:203], v[190:193], off offset:528
	s_nop 1
	v_lshl_add_u64 v[190:191], v[224:225], 0, s[8:9]
	v_cndmask_b32_e64 v167, v191, v167, s[4:5]
	v_cndmask_b32_e64 v166, v190, v166, s[4:5]
	v_cndmask_b32_e64 v190, v165, v171, s[4:5]
	v_mov_b32_e32 v191, v225
	v_lshl_add_u64 v[190:191], s[84:85], 0, v[190:191]
	v_lshlrev_b64 v[166:167], 10, v[166:167]
	v_lshl_add_u64 v[166:167], v[190:191], 0, v[166:167]
	v_lshl_add_u64 v[166:167], v[166:167], 0, v[200:201]
	v_pk_fma_f32 v[192:193], v[94:95], v[172:173], v[154:155] op_sel_hi:[1,0,1]
	v_pk_fma_f32 v[190:191], v[92:93], v[172:173], v[152:153] op_sel_hi:[1,0,1]
	global_store_dwordx4 v[166:167], v[190:193], off
	s_movk_i32 s8, 0xc430
	s_mov_b32 s9, -1
	v_pk_fma_f32 v[192:193], v[90:91], v[172:173], v[158:159] op_sel_hi:[1,0,1]
	v_pk_fma_f32 v[190:191], v[88:89], v[172:173], v[156:157] op_sel_hi:[1,0,1]
	global_store_dwordx4 v[166:167], v[190:193], off offset:16
	v_cmp_gt_i32_e64 s[4:5], s92, v160
	v_lshl_add_u64 v[160:161], v[224:225], 0, s[8:9]
	v_pk_fma_f32 v[192:193], v[86:87], v[172:173], v[150:151] op_sel_hi:[1,0,1]
	v_pk_fma_f32 v[190:191], v[84:85], v[172:173], v[148:149] op_sel_hi:[1,0,1]
	global_store_dwordx4 v[166:167], v[190:193], off offset:512
	v_pk_fma_f32 v[154:155], v[78:79], v[188:189], v[154:155] op_sel_hi:[1,0,1]
	v_pk_fma_f32 v[152:153], v[76:77], v[188:189], v[152:153] op_sel_hi:[1,0,1]
	v_pk_fma_f32 v[192:193], v[82:83], v[172:173], v[146:147] op_sel_hi:[1,0,1]
	v_pk_fma_f32 v[190:191], v[80:81], v[172:173], v[144:145] op_sel_hi:[1,0,1]
	global_store_dwordx4 v[166:167], v[190:193], off offset:528
	v_lshl_add_u64 v[166:167], v[168:169], 0, s[6:7]
	v_cndmask_b32_e64 v161, v161, v167, s[4:5]
	v_cndmask_b32_e64 v160, v160, v166, s[4:5]
	v_cndmask_b32_e64 v166, v165, v171, s[4:5]
	v_mov_b32_e32 v167, v225
	v_lshl_add_u64 v[166:167], s[84:85], 0, v[166:167]
	v_lshlrev_b64 v[160:161], 10, v[160:161]
	v_lshl_add_u64 v[160:161], v[166:167], 0, v[160:161]
	v_lshl_add_u64 v[160:161], v[160:161], 0, v[200:201]
	global_store_dwordx4 v[160:161], v[152:155], off
	v_pk_fma_f32 v[150:151], v[70:71], v[188:189], v[150:151] op_sel_hi:[1,0,1]
	v_pk_fma_f32 v[148:149], v[68:69], v[188:189], v[148:149] op_sel_hi:[1,0,1]
	v_pk_fma_f32 v[154:155], v[74:75], v[188:189], v[158:159] op_sel_hi:[1,0,1]
	v_pk_fma_f32 v[152:153], v[72:73], v[188:189], v[156:157] op_sel_hi:[1,0,1]
	v_pk_fma_f32 v[146:147], v[66:67], v[188:189], v[146:147] op_sel_hi:[1,0,1]
	v_pk_fma_f32 v[144:145], v[64:65], v[188:189], v[144:145] op_sel_hi:[1,0,1]
	global_store_dwordx4 v[160:161], v[152:155], off offset:16
	global_store_dwordx4 v[160:161], v[148:151], off offset:512
	global_store_dwordx4 v[160:161], v[144:147], off offset:528
	s_and_saveexec_b64 s[4:5], vcc
	s_xor_b64 s[4:5], exec, s[4:5]
	v_add_u32_e32 v144, 0x400, v163
	v_mov_b32_e32 v145, v225
	s_or_saveexec_b64 s[4:5], s[4:5]
	v_mov_b64_e32 v[146:147], 0x2b66000
	s_xor_b64 exec, exec, s[4:5]
	v_ashrrev_i32_e32 v165, 31, v164
	v_lshl_add_u64 v[144:145], v[164:165], 0, s[6:7]
	v_mov_b64_e32 v[146:147], 0x2200000
	s_or_b64 exec, exec, s[4:5]
	v_lshlrev_b32_e32 v146, 2, v146
	v_mov_b32_e32 v147, v225
	v_lshl_add_u64 v[146:147], s[84:85], 0, v[146:147]
	v_lshlrev_b64 v[144:145], 10, v[144:145]
	v_lshl_add_u64 v[144:145], v[146:147], 0, v[144:145]
	v_lshl_add_u64 v[148:149], v[198:199], 2, v[144:145]
	s_waitcnt vmcnt(19)
	v_pk_fma_f32 v[146:147], v[62:63], v[174:175], v[142:143] op_sel_hi:[1,0,1]
	v_pk_fma_f32 v[144:145], v[60:61], v[174:175], v[140:141] op_sel_hi:[1,0,1]
	global_store_dwordx4 v[148:149], v[144:147], off
	s_movk_i32 s4, 0x3fef
	v_cmp_lt_i32_e32 vcc, s4, v164
	s_waitcnt vmcnt(19)
;     template <int PN> DI void body(AccRef acc, const Unit& u, int wr, int wc, int fr, int fq) const {
;     ...
;                 } else {
;                     float* lo = orow(out, l, row, PN == 8 ? O_PSK : O_PSV, PN == 8 ? O_SSK : O_SSV, 256);
; #pragma unroll
;                     for (int bj = 0; bj < 2; ++bj) {
;                         *(f32x4*)(lo + bj * 128 + cl) = (f32x4){v[bj][0], v[bj][1], v[bj][2], v[bj][3]};
;                         *(f32x4*)(lo + bj * 128 + cl + 4) = (f32x4){v[bj][4], v[bj][5], v[bj][6], v[bj][7]};
;                     }
	v_pk_fma_f32 v[146:147], v[58:59], v[174:175], v[138:139] op_sel_hi:[1,0,1]
	v_pk_fma_f32 v[144:145], v[56:57], v[174:175], v[136:137] op_sel_hi:[1,0,1]
	global_store_dwordx4 v[148:149], v[144:147], off offset:16
	s_waitcnt vmcnt(18)
	s_nop 0
	v_pk_fma_f32 v[146:147], v[54:55], v[174:175], v[134:135] op_sel_hi:[1,0,1]
	v_pk_fma_f32 v[144:145], v[52:53], v[174:175], v[132:133] op_sel_hi:[1,0,1]
	global_store_dwordx4 v[148:149], v[144:147], off offset:512
	s_nop 1
	v_pk_fma_f32 v[146:147], v[50:51], v[174:175], v[130:131] op_sel_hi:[1,0,1]
	v_pk_fma_f32 v[144:145], v[48:49], v[174:175], v[128:129] op_sel_hi:[1,0,1]
	global_store_dwordx4 v[148:149], v[144:147], off offset:528
	s_and_saveexec_b64 s[4:5], vcc
	s_xor_b64 s[4:5], exec, s[4:5]
	s_movk_i32 s6, 0xc490
	s_mov_b32 s7, -1
	v_lshl_add_u64 v[144:145], v[224:225], 0, s[6:7]
	s_or_saveexec_b64 s[4:5], s[4:5]
	v_mov_b64_e32 v[146:147], 0x2b66000
	s_xor_b64 exec, exec, s[4:5]
	v_add_u32_e32 v144, 0x90, v224
	v_ashrrev_i32_e32 v145, 31, v144
	s_mov_b64 s[6:7], 0x4000
	v_lshl_add_u64 v[144:145], v[144:145], 0, s[6:7]
	v_mov_b64_e32 v[146:147], 0x2200000
	s_or_b64 exec, exec, s[4:5]
	v_lshlrev_b32_e32 v146, 2, v146
	v_mov_b32_e32 v147, v225
	v_lshl_add_u64 v[146:147], s[84:85], 0, v[146:147]
	v_lshlrev_b64 v[144:145], 10, v[144:145]
	v_lshl_add_u64 v[144:145], v[146:147], 0, v[144:145]
	v_lshl_add_u64 v[148:149], v[198:199], 2, v[144:145]
	v_pk_fma_f32 v[146:147], v[46:47], v[170:171], v[142:143] op_sel_hi:[1,0,1]
	v_pk_fma_f32 v[144:145], v[44:45], v[170:171], v[140:141] op_sel_hi:[1,0,1]
	global_store_dwordx4 v[148:149], v[144:147], off
	s_movk_i32 s4, 0x3fdf
	v_cmp_lt_i32_e32 vcc, s4, v164
	v_pk_fma_f32 v[146:147], v[42:43], v[170:171], v[138:139] op_sel_hi:[1,0,1]
	v_pk_fma_f32 v[144:145], v[40:41], v[170:171], v[136:137] op_sel_hi:[1,0,1]
	global_store_dwordx4 v[148:149], v[144:147], off offset:16
	s_nop 1
	v_pk_fma_f32 v[146:147], v[38:39], v[170:171], v[134:135] op_sel_hi:[1,0,1]
	v_pk_fma_f32 v[144:145], v[36:37], v[170:171], v[132:133] op_sel_hi:[1,0,1]
	global_store_dwordx4 v[148:149], v[144:147], off offset:512
	s_nop 1
	v_pk_fma_f32 v[146:147], v[30:31], v[170:171], v[130:131] op_sel_hi:[1,0,1]
	v_pk_fma_f32 v[144:145], v[28:29], v[170:171], v[128:129] op_sel_hi:[1,0,1]
	global_store_dwordx4 v[148:149], v[144:147], off offset:528
	s_and_saveexec_b64 s[4:5], vcc
	s_xor_b64 s[4:5], exec, s[4:5]
	s_movk_i32 s6, 0xc4a0
	s_mov_b32 s7, -1
	v_lshl_add_u64 v[144:145], v[224:225], 0, s[6:7]
	s_or_saveexec_b64 s[4:5], s[4:5]
	v_mov_b64_e32 v[146:147], 0x2b66000
	s_xor_b64 exec, exec, s[4:5]
	v_add_u32_e32 v144, 0xa0, v224
	v_ashrrev_i32_e32 v145, 31, v144
	s_mov_b64 s[6:7], 0x4000
	v_lshl_add_u64 v[144:145], v[144:145], 0, s[6:7]
	v_mov_b64_e32 v[146:147], 0x2200000
	s_or_b64 exec, exec, s[4:5]
	v_lshlrev_b32_e32 v146, 2, v146
	v_mov_b32_e32 v147, v225
	v_lshl_add_u64 v[146:147], s[84:85], 0, v[146:147]
	v_lshlrev_b64 v[144:145], 10, v[144:145]
	v_lshl_add_u64 v[144:145], v[146:147], 0, v[144:145]
	v_lshl_add_u64 v[148:149], v[198:199], 2, v[144:145]
	v_pk_fma_f32 v[146:147], v[34:35], v[196:197], v[142:143] op_sel_hi:[1,0,1]
	v_pk_fma_f32 v[144:145], v[32:33], v[196:197], v[140:141] op_sel_hi:[1,0,1]
	global_store_dwordx4 v[148:149], v[144:147], off
	s_movk_i32 s4, 0x3fcf
	v_cmp_lt_i32_e32 vcc, s4, v164
	v_pk_fma_f32 v[146:147], v[26:27], v[196:197], v[138:139] op_sel_hi:[1,0,1]
	v_pk_fma_f32 v[144:145], v[24:25], v[196:197], v[136:137] op_sel_hi:[1,0,1]
	global_store_dwordx4 v[148:149], v[144:147], off offset:16
	s_nop 1
	v_pk_fma_f32 v[146:147], v[22:23], v[196:197], v[134:135] op_sel_hi:[1,0,1]
	v_pk_fma_f32 v[144:145], v[20:21], v[196:197], v[132:133] op_sel_hi:[1,0,1]
	global_store_dwordx4 v[148:149], v[144:147], off offset:512
	s_nop 1
	v_pk_fma_f32 v[146:147], v[18:19], v[196:197], v[130:131] op_sel_hi:[1,0,1]
	v_pk_fma_f32 v[144:145], v[16:17], v[196:197], v[128:129] op_sel_hi:[1,0,1]
	global_store_dwordx4 v[148:149], v[144:147], off offset:528
	s_and_saveexec_b64 s[4:5], vcc
	s_xor_b64 s[4:5], exec, s[4:5]
	s_movk_i32 s6, 0xc4b0
	s_mov_b32 s7, -1
	v_lshl_add_u64 v[144:145], v[224:225], 0, s[6:7]
	s_or_saveexec_b64 s[4:5], s[4:5]
	v_mov_b64_e32 v[146:147], 0x2b66000
	s_xor_b64 exec, exec, s[4:5]
	v_add_u32_e32 v144, 0xb0, v224
	v_ashrrev_i32_e32 v145, 31, v144
	s_mov_b64 s[6:7], 0x4000
	v_lshl_add_u64 v[144:145], v[144:145], 0, s[6:7]
	v_mov_b64_e32 v[146:147], 0x2200000
	s_or_b64 exec, exec, s[4:5]
	v_lshlrev_b32_e32 v224, 2, v146
	v_lshl_add_u64 v[146:147], s[84:85], 0, v[224:225]
	v_lshlrev_b64 v[144:145], 10, v[144:145]
	v_lshl_add_u64 v[144:145], v[146:147], 0, v[144:145]
	v_lshl_add_u64 v[144:145], v[198:199], 2, v[144:145]
	v_pk_fma_f32 v[142:143], v[14:15], v[194:195], v[142:143] op_sel_hi:[1,0,1]
	v_pk_fma_f32 v[140:141], v[12:13], v[194:195], v[140:141] op_sel_hi:[1,0,1]
	v_pk_fma_f32 v[138:139], v[10:11], v[194:195], v[138:139] op_sel_hi:[1,0,1]
	v_pk_fma_f32 v[136:137], v[8:9], v[194:195], v[136:137] op_sel_hi:[1,0,1]
	v_pk_fma_f32 v[134:135], v[6:7], v[194:195], v[134:135] op_sel_hi:[1,0,1]
	v_pk_fma_f32 v[132:133], v[4:5], v[194:195], v[132:133] op_sel_hi:[1,0,1]
	v_pk_fma_f32 v[130:131], v[2:3], v[194:195], v[130:131] op_sel_hi:[1,0,1]
	v_pk_fma_f32 v[128:129], v[0:1], v[194:195], v[128:129] op_sel_hi:[1,0,1]
	global_store_dwordx4 v[144:145], v[140:143], off
	global_store_dwordx4 v[144:145], v[136:139], off offset:16
	global_store_dwordx4 v[144:145], v[132:135], off offset:512
	global_store_dwordx4 v[144:145], v[128:131], off offset:528

; #define LAS __attribute__((address_space(3)))
; DI u32x4 pack8(const float* v) { u32x4 w; w.x = pk2(v[0], v[1]); w.y = pk2(v[2], v[3]); w.z = pk2(v[4], v[5]); w.w = pk2(v[6], v[7]); return w; }
;     template <int PN> DI void body(AccRef acc, const Unit& u, int wr, int wc, int fr, int fq) const {
;     ...
;         for (int ai = 0; ai < 2; ++ai) {
;             const int rb_ = u.pm * 256 + ai * 128 + wr * 64 + fr;
; #pragma unroll
;             for (int m = 0; m < 4; ++m) rinvh[ai][m] = rsqrtf(sum16(ssq + (size_t)(rb_ + 16 * m + zdep) * 16) * (1.f / 1024.f) + EPS);
;             asm volatile("v_mov_b32 %0, 0" : "=v"(zdep) : "v"(rinvh[ai][0]), "v"(rinvh[ai][1]), "v"(rinvh[ai][2]), "v"(rinvh[ai][3]));
;         }
; #pragma unroll
;         for (int ai = 0; ai < 2; ++ai) {
;             const int rb_ = u.pm * 256 + ai * 128 + wr * 64 + fr;
;             int mb_, p_, k_; row_info(rb_, mb_, p_, k_);
; #pragma unroll
;             for (int bj = 0; bj < 2; ++bj)
; #pragma unroll
;                 for (int n = 0; n < 2; ++n) cvh[ai][bj][n] = *(const f32x4*)(cv + (size_t)(mb_ + zdep) * NIN + PN * 256 + bj * 128 + cl + 4 * n);
;         }
; #pragma unroll
;         for (int ai = 0; ai < 2; ++ai) {
;             const int rb = u.pm * 256 + ai * 128 + wr * 64 + fr;
;             int mb, pos0, kv0; row_info(rb, mb, pos0, kv0);
; #pragma unroll
;             for (int m = 0; m < 4; ++m) {
;                 const int row = rb + 16 * m, pos = pos0 + 16 * m, kvrow = kv0 + 16 * m;
;                 const float rinv = rinvh[ai][m];
;                 float v[2][8];
; #pragma unroll
;                 for (int bj = 0; bj < 2; ++bj)
; #pragma unroll
;                     for (int n = 0; n < 2; ++n)
; #pragma unroll
;                         for (int j = 0; j < 4; ++j) v[bj][4 * n + j] = acc[ai][bj][m][n][j] * rinv + cvh[ai][bj][n][j];
;                 if constexpr (PN == 0) {
;                     float s = 0.f;
; #pragma unroll
;                     for (int bj = 0; bj < 2; ++bj) {
;                         *(u32x4*)(zkv + (size_t)row * 256 + bj * 128 + cl) = pack8(v[bj]);
; #pragma unroll
;                         for (int j = 0; j < 8; ++j) s += v[bj][j] * v[bj][j];
;                     }
;                     s = xor16_32(s);
;                     if (fq == 0) { ssqkv[(size_t)row * 4 + wc] = s; *(LAS float*)(xl + ((ai * 128 + wr * 64 + 16 * m + fr) * 4 + wc) * 4) = s; }
.LBB0_1827:
	s_and_b64 vcc, exec, s[10:11]
	s_cbranch_vccz .LBB0_1826
	v_lshl_add_u32 v164, s43, 6, v214
	s_lshl_b32 s6, s34, 8
	v_add_u32_e32 v192, s6, v164
	v_ashrrev_i32_e32 v193, 31, v192
	v_lshlrev_b64 v[128:129], 6, v[192:193]
	v_lshl_add_u64 v[140:141], s[70:71], 0, v[128:129]
	s_waitcnt lgkmcnt(0)
	s_nop 0
	v_add_u32_e32 v206, 16, v192
	v_ashrrev_i32_e32 v207, 31, v206
	s_mov_b32 s4, 0x358637bd
	s_mov_b32 s8, 0x3a800000
	v_add_u32_e32 v204, 32, v192
	v_ashrrev_i32_e32 v205, 31, v204
	v_add_u32_e32 v194, 48, v192
	v_ashrrev_i32_e32 v195, 31, v194
	v_add_u32_e32 v189, 0x80, v164
	v_add_u32_e32 v190, s6, v189
	s_movk_i32 s6, 0x2800
	v_lshlrev_b64 v[168:169], 9, v[192:193]
	v_lshlrev_b32_e32 v165, 2, v214
	v_lshl_add_u32 v165, v213, 6, v165
	v_xor_b32_e32 v166, 64, v165
	v_xor_b32_e32 v165, 0x80, v165
	s_ashr_i32 s55, s54, 31
	s_nop 0
	v_lshlrev_b64 v[128:129], 6, v[206:207]
	v_lshl_add_u64 v[140:141], s[70:71], 0, v[128:129]
	s_nop 0
	s_nop 0
	v_mov_b64_e32 v[128:129], s[4:5]
	s_nop 0
	s_nop 0
	s_nop 0
	v_mov_b32_e32 v212, v244
	s_nop 0
	v_mov_b32_e32 v196, v245
	v_lshlrev_b64 v[130:131], 6, v[204:205]
	v_lshl_add_u64 v[142:143], s[70:71], 0, v[130:131]
	s_nop 0
	s_nop 0
	v_lshlrev_b64 v[130:131], 6, v[194:195]
	v_lshl_add_u64 v[142:143], s[70:71], 0, v[130:131]
	s_nop 0
	s_nop 0
	s_nop 0
	s_nop 0
	s_nop 0
	s_nop 0
	v_mov_b32_e32 v208, v246
	s_nop 0
	v_mov_b32_e32 v200, v247
	v_mov_b32 v130, 0
	s_nop 0
	v_add_u32_e32 v130, v130, v190
	v_ashrrev_i32_e32 v131, 31, v130
	v_lshlrev_b64 v[132:133], 6, v[130:131]
	v_lshl_add_u64 v[144:145], s[70:71], 0, v[132:133]
	s_nop 0
	s_nop 0
	v_add_u32_e32 v132, 16, v130
	v_ashrrev_i32_e32 v133, 31, v132
	v_lshlrev_b64 v[132:133], 6, v[132:133]
	v_lshl_add_u64 v[144:145], s[70:71], 0, v[132:133]
	s_nop 0
	s_nop 0
	s_nop 0
	s_nop 0
	s_nop 0
	s_nop 0
	v_mov_b32_e32 v202, v248
	s_nop 0
	v_mov_b32_e32 v198, v249
	v_add_u32_e32 v132, 32, v130
	v_ashrrev_i32_e32 v133, 31, v132
	v_lshlrev_b64 v[132:133], 6, v[132:133]
	v_lshl_add_u64 v[144:145], s[70:71], 0, v[132:133]
	s_nop 0
	v_add_u32_e32 v130, 48, v130
	v_ashrrev_i32_e32 v131, 31, v130
	v_lshlrev_b64 v[130:131], 6, v[130:131]
	v_lshl_add_u64 v[142:143], s[70:71], 0, v[130:131]
	s_nop 0
	s_nop 0
	s_nop 0
	v_add_u32_e32 v131, 0xffffc000, v192
	v_lshrrev_b32_e32 v131, 6, v131
	v_add_u32_e32 v131, 8, v131
	s_lshl_b64 s[8:9], s[54:55], 2
	v_mov_b32_e32 v210, v250
	s_lshl_b32 s4, s54, 5
	v_lshl_add_u32 v160, v213, 3, s4
	v_ashrrev_i32_e32 v130, 11, v192
	v_mov_b32_e32 v188, v251
	v_cmp_gt_i32_e32 vcc, s94, v192
	v_ashrrev_i32_e32 v161, 31, v160
	v_mov_b32 v132, 0
	v_lshl_add_u64 v[128:129], v[160:161], 2, s[62:63]
	v_cndmask_b32_e32 v130, v131, v130, vcc
	v_add_u32_e32 v130, v132, v130
	v_mad_i64_i32 v[130:131], s[4:5], v130, s6, v[128:129]
	global_load_dwordx4 v[148:151], v[130:131], off offset:16
	global_load_dwordx4 v[156:159], v[130:131], off
	global_load_dwordx4 v[144:147], v[130:131], off offset:528
	global_load_dwordx4 v[152:155], v[130:131], off offset:512
	v_add_u32_e32 v131, 0xffffc080, v192
	v_add_u32_e32 v130, 0x80, v192
	v_lshrrev_b32_e32 v131, 6, v131
	v_cmp_gt_i32_e64 s[4:5], s94, v130
	v_ashrrev_i32_e32 v130, 11, v130
	v_add_u32_e32 v131, 8, v131
	v_cndmask_b32_e64 v130, v131, v130, s[4:5]
	v_add_u32_e32 v130, v132, v130
	v_mad_i64_i32 v[132:133], s[4:5], v130, s6, v[128:129]
	global_load_dwordx4 v[136:139], v[132:133], off offset:16
	global_load_dwordx4 v[140:143], v[132:133], off
	global_load_dwordx4 v[128:131], v[132:133], off offset:528
	s_nop 0
	global_load_dwordx4 v[132:135], v[132:133], off offset:512
	v_lshl_add_u64 v[162:163], v[160:161], 1, s[86:87]
	v_lshl_add_u64 v[230:231], v[162:163], 0, v[168:169]
	s_add_u32 s8, s73, s8
	v_cmp_ne_u32_e64 s[4:5], 0, v213
	v_cmp_eq_u32_e64 s[6:7], 0, v213
	s_addc_u32 s9, s67, s9
	s_lshl_b32 s12, s54, 2
	s_waitcnt vmcnt(7)
	v_pk_fma_f32 v[214:215], v[120:121], v[212:213], v[148:149] op_sel_hi:[1,0,1]
	s_waitcnt vmcnt(6)
	v_pk_fma_f32 v[172:173], v[124:125], v[212:213], v[156:157] op_sel_hi:[1,0,1]
	v_pk_fma_f32 v[174:175], v[126:127], v[212:213], v[158:159] op_sel_hi:[1,0,1]
	v_cvt_pk_bf16_f32 v168, v172, v173
	v_pk_mul_f32 v[172:173], v[172:173], v[172:173]
	v_cvt_pk_bf16_f32 v169, v174, v175
	v_pk_mul_f32 v[174:175], v[174:175], v[174:175]
	v_add_f32_e32 v167, v172, v173
	v_add_f32_e32 v167, v174, v167
	v_cvt_pk_bf16_f32 v170, v214, v215
	v_pk_mul_f32 v[214:215], v[214:215], v[214:215]
	v_add_f32_e32 v167, v175, v167
	v_pk_fma_f32 v[216:217], v[122:123], v[212:213], v[150:151] op_sel_hi:[1,0,1]
	v_add_f32_e32 v167, v214, v167
	s_waitcnt vmcnt(4)
	v_pk_fma_f32 v[218:219], v[116:117], v[212:213], v[152:153] op_sel_hi:[1,0,1]
	v_pk_fma_f32 v[220:221], v[118:119], v[212:213], v[154:155] op_sel_hi:[1,0,1]
	v_pk_fma_f32 v[222:223], v[112:113], v[212:213], v[144:145] op_sel_hi:[1,0,1]
	v_pk_fma_f32 v[228:229], v[114:115], v[212:213], v[146:147] op_sel_hi:[1,0,1]
	v_cvt_pk_bf16_f32 v171, v216, v217
	v_pk_mul_f32 v[216:217], v[216:217], v[216:217]
	v_add_f32_e32 v167, v215, v167
	global_store_dwordx4 v[230:231], v[168:171], off
	v_add_f32_e32 v167, v216, v167
	v_add_f32_e32 v167, v217, v167
	v_cvt_pk_bf16_f32 v168, v218, v219
	v_cvt_pk_bf16_f32 v169, v220, v221
	v_cvt_pk_bf16_f32 v170, v222, v223
	v_cvt_pk_bf16_f32 v171, v228, v229
	global_store_dwordx4 v[230:231], v[168:171], off offset:256
	s_nop 1
	v_pk_mul_f32 v[168:169], v[218:219], v[218:219]
	v_pk_mul_f32 v[170:171], v[220:221], v[220:221]
	v_add_f32_e32 v167, v168, v167
	v_add_f32_e32 v167, v169, v167
	v_add_f32_e32 v167, v170, v167
	v_pk_mul_f32 v[218:219], v[222:223], v[222:223]
	v_add_f32_e32 v167, v171, v167
	v_add_f32_e32 v167, v218, v167
	v_pk_mul_f32 v[220:221], v[228:229], v[228:229]
	v_add_f32_e32 v167, v219, v167
	v_add_f32_e32 v167, v220, v167
	v_add_f32_e32 v167, v221, v167
	ds_bpermute_b32 v168, v166, v167
	s_waitcnt lgkmcnt(0)
	v_add_f32_e32 v167, v167, v168
	ds_bpermute_b32 v168, v165, v167
	s_and_saveexec_b64 s[10:11], s[6:7]
	s_cbranch_execz .LBB0_1830
	s_add_i32 s13, s12, 0
	v_lshl_add_u32 v169, v164, 4, s13
	v_add_u32_e32 v169, 0x20000, v169
	v_lshl_add_u64 v[170:171], v[192:193], 4, s[8:9]
	s_waitcnt lgkmcnt(0)
	v_add_f32_e32 v167, v167, v168
	global_store_dword v[170:171], v167, off
	ds_write_b32 v169, v167

; DI float sum16(const float* p) { const f32x4* q = (const f32x4*)p; f32x4 a = q[0], b = q[1], c = q[2], d = q[3]; f32x4 s = (a + b) + (c + d); return (s[0] + s[1]) + (s[2] + s[3]); }
;     template <int PN> DI void body(AccRef acc, const Unit& u, int wr, int wc, int fr, int fq) const {
;     ...
;         for (int ai = 0; ai < 2; ++ai) {
;             const int rb_ = u.pm * 256 + ai * 128 + wr * 64 + fr;
; #pragma unroll
;             for (int m = 0; m < 4; ++m) rinvh[ai][m] = rsqrtf(sum16(ssq + (size_t)(rb_ + 16 * m + zdep) * 16) * (1.f / 1024.f) + EPS);
;             asm volatile("v_mov_b32 %0, 0" : "=v"(zdep) : "v"(rinvh[ai][0]), "v"(rinvh[ai][1]), "v"(rinvh[ai][2]), "v"(rinvh[ai][3]));
;         }
;     DI void operator()(AccRef acc, const Unit& u, int wr, int wc, int fr, int fq) const {
;         switch (u.pn) {
;             case 0: body<0>(acc, u, wr, wc, fr, fq); break;
;             case 1: body<1>(acc, u, wr, wc, fr, fq); break;
;             case 2: body<2>(acc, u, wr, wc, fr, fq); break;
;             case 3: body<3>(acc, u, wr, wc, fr, fq); break;
;             case 4: body<4>(acc, u, wr, wc, fr, fq); break;
;             case 5: body<5>(acc, u, wr, wc, fr, fq); break;
;             case 6: body<6>(acc, u, wr, wc, fr, fq); break;
;             case 7: body<7>(acc, u, wr, wc, fr, fq); break;
;             case 8: body<8>(acc, u, wr, wc, fr, fq); break;
;             default: body<9>(acc, u, wr, wc, fr, fq); break;
.LBB0_1878:
	v_readlane_b32 s2, v253, 32
	v_mbcnt_lo_u32_b32 v128, -1, 0
	v_mbcnt_hi_u32_b32 v128, -1, v128
	s_mov_b32 s60, s39
	v_and_b32_e32 v214, 15, v128
	v_bfe_u32 v213, v128, 4, 2
	s_mov_b32 s43, s29
	s_lshl_b32 s22, s43, 6
	s_lshl_b32 s23, s34, 8
	s_add_i32 s22, s22, s23
	v_add_u32_e32 v244, s22, v214
	v_lshlrev_b32_e32 v244, 6, v244
	v_lshl_add_u32 v244, v213, 4, v244
	global_load_dwordx4 v[228:231], v244, s[70:71]
	global_load_dwordx4 v[232:235], v244, s[70:71] offset:1024
	global_load_dwordx4 v[236:239], v244, s[70:71] offset:2048
	global_load_dwordx4 v[240:243], v244, s[70:71] offset:3072
	v_add_u32_e32 v244, 0x2000, v244
	global_load_dwordx4 v[216:219], v244, s[70:71]
	global_load_dwordx4 v[220:223], v244, s[70:71] offset:1024
	global_load_dwordx4 v[142:145], v244, s[70:71] offset:2048
	global_load_dwordx4 v[146:149], v244, s[70:71] offset:3072
	v_mov_b32_e32 v245, 0x3a800000
	s_waitcnt vmcnt(4)
	v_pk_add_f32 v[228:229], v[228:229], v[230:231]
	v_pk_add_f32 v[232:233], v[232:233], v[234:235]
	v_pk_add_f32 v[236:237], v[236:237], v[238:239]
	v_pk_add_f32 v[240:241], v[240:241], v[242:243]
	v_add_f32_e32 v228, v228, v229
	v_add_f32_e32 v232, v232, v233
	v_add_f32_e32 v236, v236, v237
	v_add_f32_e32 v240, v240, v241
	v_mov_b32_e32 v229, v228
	v_mov_b32_e32 v233, v232
	v_mov_b32_e32 v237, v236
	v_mov_b32_e32 v241, v240
	s_waitcnt vmcnt(0)
	v_pk_add_f32 v[216:217], v[216:217], v[218:219]
	v_pk_add_f32 v[220:221], v[220:221], v[222:223]
	v_pk_add_f32 v[142:143], v[142:143], v[144:145]
	v_pk_add_f32 v[146:147], v[146:147], v[148:149]
	v_add_f32_e32 v216, v216, v217
	v_add_f32_e32 v220, v220, v221
	v_add_f32_e32 v142, v142, v143
	v_add_f32_e32 v146, v146, v147
	v_mov_b32_e32 v217, v216
	v_mov_b32_e32 v221, v220
	v_mov_b32_e32 v143, v142
	v_mov_b32_e32 v147, v146
	s_nop 1
	v_permlane32_swap_b32_e32 v228, v229
	v_permlane32_swap_b32_e32 v232, v233
	v_permlane32_swap_b32_e32 v236, v237
	v_permlane32_swap_b32_e32 v240, v241
	v_permlane32_swap_b32_e32 v216, v217
	v_permlane32_swap_b32_e32 v220, v221
	v_permlane32_swap_b32_e32 v142, v143
	v_permlane32_swap_b32_e32 v146, v147
	v_add_f32_e32 v228, v228, v229
	v_add_f32_e32 v232, v232, v233
	v_add_f32_e32 v236, v236, v237
	v_add_f32_e32 v240, v240, v241
	v_add_f32_e32 v216, v216, v217
	v_add_f32_e32 v220, v220, v221
	v_add_f32_e32 v142, v142, v143
	v_add_f32_e32 v146, v146, v147
	v_mov_b32_e32 v229, v228
	v_mov_b32_e32 v233, v232
	v_mov_b32_e32 v237, v236
	v_mov_b32_e32 v241, v240
	v_mov_b32_e32 v217, v216
	v_mov_b32_e32 v221, v220
	v_mov_b32_e32 v143, v142
	v_mov_b32_e32 v147, v146
	s_nop 1
	v_permlane16_swap_b32_e32 v228, v229
	v_permlane16_swap_b32_e32 v232, v233
	v_permlane16_swap_b32_e32 v236, v237
	v_permlane16_swap_b32_e32 v240, v241
	v_permlane16_swap_b32_e32 v216, v217
	v_permlane16_swap_b32_e32 v220, v221
	v_permlane16_swap_b32_e32 v142, v143
	v_permlane16_swap_b32_e32 v146, v147
	v_add_f32_e32 v228, v228, v229
	v_add_f32_e32 v232, v232, v233
	v_add_f32_e32 v236, v236, v237
	v_add_f32_e32 v240, v240, v241
	v_add_f32_e32 v216, v216, v217
	v_add_f32_e32 v220, v220, v221
	v_add_f32_e32 v142, v142, v143
	v_add_f32_e32 v146, v146, v147
	v_fmaak_f32 v228, v245, v228, 0x358637bd
	v_fmaak_f32 v232, v245, v232, 0x358637bd
	v_fmaak_f32 v236, v245, v236, 0x358637bd
	v_fmaak_f32 v240, v245, v240, 0x358637bd
	v_fmaak_f32 v216, v245, v216, 0x358637bd
	v_fmaak_f32 v220, v245, v220, 0x358637bd
	v_fmaak_f32 v142, v245, v142, 0x358637bd
	v_fmaak_f32 v146, v245, v146, 0x358637bd
	v_rsq_f32_e32 v244, v228
	v_rsq_f32_e32 v245, v232
	v_rsq_f32_e32 v246, v236
	v_rsq_f32_e32 v247, v240
	v_rsq_f32_e32 v248, v216
	v_rsq_f32_e32 v249, v220
	v_rsq_f32_e32 v250, v142
	v_rsq_f32_e32 v251, v146
	s_mov_b64 s[2:3], -1
	s_mov_b64 s[8:9], 0
	s_cmp_lt_i32 s66, 4
	s_mov_b64 s[80:81], 0
	s_cbranch_scc1 .LBB0_1913
	s_cmp_gt_i32 s66, 5
	s_cbranch_scc0 .LBB0_1907
	s_cmp_gt_i32 s66, 6
	s_cbranch_scc0 .LBB0_1904
	s_cmp_gt_i32 s66, 7
	s_cbranch_scc0 .LBB0_1901
	s_cmp_eq_u32 s66, 8
	s_mov_b64 s[80:81], -1
	s_cbranch_scc0 .LBB0_1900
	s_lshl_b32 s2, s43, 6
	s_lshl_b32 s3, s34, 8
	s_add_i32 s2, s2, s3
	v_add_u32_e32 v160, s2, v214
	v_ashrrev_i32_e32 v161, 31, v160
	v_lshlrev_b64 v[128:129], 6, v[160:161]
	v_lshl_add_u64 v[140:141], s[70:71], 0, v[128:129]
	s_nop 0
	v_add_u32_e32 v190, 16, v160
	v_ashrrev_i32_e32 v191, 31, v190
	s_mov_b32 s2, 0x358637bd
	s_mov_b32 s4, 0x3a800000
	v_add_u32_e32 v166, 32, v160
	v_ashrrev_i32_e32 v167, 31, v166
	v_add_u32_e32 v168, 48, v160
	v_ashrrev_i32_e32 v169, 31, v168
	v_add_u32_e32 v164, 0x80, v160
	s_movk_i32 s6, 0x2800
	s_mov_b64 s[12:13], 0x126000
	s_mov_b32 s7, 0x126000
	v_add_u32_e32 v163, 0xffffc080, v160
	v_mov_b32_e32 v165, 0xffffc400
	v_mov_b32_e32 v171, 0x4000
	s_nop 0
	v_lshlrev_b64 v[128:129], 6, v[190:191]
	v_lshl_add_u64 v[140:141], s[70:71], 0, v[128:129]
	s_nop 0
	s_nop 0
	v_mov_b64_e32 v[128:129], s[2:3]
	s_nop 0
	s_nop 0
	s_nop 0
	v_mov_b32_e32 v192, v244
	s_nop 0
	v_mov_b32_e32 v162, v245
	v_lshlrev_b64 v[130:131], 6, v[166:167]
	v_lshl_add_u64 v[142:143], s[70:71], 0, v[130:131]
	s_nop 0
	s_nop 0
	v_lshlrev_b64 v[130:131], 6, v[168:169]
	v_lshl_add_u64 v[142:143], s[70:71], 0, v[130:131]
	s_nop 0
	s_nop 0
	s_nop 0
	s_nop 0
	s_nop 0
	s_nop 0
	v_mov_b32_e32 v172, v246
	s_nop 0
	v_mov_b32_e32 v188, v247
	v_mov_b32 v130, 0
	s_nop 0
	v_add_u32_e32 v130, v130, v164
	v_ashrrev_i32_e32 v131, 31, v130
	v_lshlrev_b64 v[132:133], 6, v[130:131]
	v_lshl_add_u64 v[144:145], s[70:71], 0, v[132:133]
	s_nop 0
	s_nop 0
	v_add_u32_e32 v132, 16, v130
	v_ashrrev_i32_e32 v133, 31, v132
	v_lshlrev_b64 v[132:133], 6, v[132:133]
	v_lshl_add_u64 v[144:145], s[70:71], 0, v[132:133]
	s_nop 0
	s_nop 0
;     template <int PN> DI void body(AccRef acc, const Unit& u, int wr, int wc, int fr, int fq) const {
;     ...
; #pragma unroll
;         for (int ai = 0; ai < 2; ++ai) {
;             const int rb_ = u.pm * 256 + ai * 128 + wr * 64 + fr;
;             int mb_, p_, k_; row_info(rb_, mb_, p_, k_);
; #pragma unroll
;             for (int bj = 0; bj < 2; ++bj)
; #pragma unroll
;                 for (int n = 0; n < 2; ++n) cvh[ai][bj][n] = *(const f32x4*)(cv + (size_t)(mb_ + zdep) * NIN + PN * 256 + bj * 128 + cl + 4 * n);
;         }
; #pragma unroll
;         for (int ai = 0; ai < 2; ++ai) {
;             const int rb = u.pm * 256 + ai * 128 + wr * 64 + fr;
;             int mb, pos0, kv0; row_info(rb, mb, pos0, kv0);
; #pragma unroll
;             for (int m = 0; m < 4; ++m) {
;                 const int row = rb + 16 * m, pos = pos0 + 16 * m, kvrow = kv0 + 16 * m;
;                 const float rinv = rinvh[ai][m];
;                 float v[2][8];
; #pragma unroll
;                 for (int bj = 0; bj < 2; ++bj)
; #pragma unroll
;                     for (int n = 0; n < 2; ++n)
; #pragma unroll
;                         for (int j = 0; j < 4; ++j) v[bj][4 * n + j] = acc[ai][bj][m][n][j] * rinv + cvh[ai][bj][n][j];
;     ...
;                 } else {
;                     float* lo = orow(out, l, row, PN == 8 ? O_PSK : O_PSV, PN == 8 ? O_SSK : O_SSV, 256);
; #pragma unroll
;                     for (int bj = 0; bj < 2; ++bj) {
;                         *(f32x4*)(lo + bj * 128 + cl) = (f32x4){v[bj][0], v[bj][1], v[bj][2], v[bj][3]};
;                         *(f32x4*)(lo + bj * 128 + cl + 4) = (f32x4){v[bj][4], v[bj][5], v[bj][6], v[bj][7]};
;                     }
	s_nop 0
	s_nop 0
	s_nop 0
	s_nop 0
	v_mov_b32_e32 v174, v248
	s_nop 0
	v_mov_b32_e32 v170, v249
	v_add_u32_e32 v132, 32, v130
	v_ashrrev_i32_e32 v133, 31, v132
	v_lshlrev_b64 v[132:133], 6, v[132:133]
	v_lshl_add_u64 v[144:145], s[70:71], 0, v[132:133]
	s_nop 0
	v_add_u32_e32 v130, 48, v130
	v_ashrrev_i32_e32 v131, 31, v130
	v_lshlrev_b64 v[130:131], 6, v[130:131]
	v_lshl_add_u64 v[142:143], s[70:71], 0, v[130:131]
	s_nop 0
	s_nop 0
	s_nop 0
	s_nop 0
	s_nop 0
	s_nop 0
	v_mov_b32_e32 v196, v250
	s_lshl_b32 s2, s60, 5
	v_lshl_add_u32 v198, v213, 3, s2
	v_cmp_gt_i32_e64 s[2:3], s94, v160
	v_mov_b32_e32 v194, v251
	v_add_u32_e32 v129, 0xffffc000, v160
	v_lshrrev_b32_e32 v129, 6, v129
	v_ashrrev_i32_e32 v128, 11, v160
	v_add_u32_e32 v129, 8, v129
	v_cndmask_b32_e64 v128, v129, v128, s[2:3]
	v_mov_b32 v134, 0
	v_ashrrev_i32_e32 v199, 31, v198
	v_add_u32_e32 v130, v134, v128
	v_mov_b64_e32 v[128:129], s[74:75]
	v_mad_i64_i32 v[130:131], s[4:5], v130, s6, v[128:129]
	v_lshlrev_b64 v[200:201], 2, v[198:199]
	v_lshl_add_u64 v[130:131], v[130:131], 0, v[200:201]
	v_lshl_add_u64 v[132:133], v[130:131], 0, s[12:13]
	v_add_co_u32_e32 v130, vcc, s7, v130
	s_movk_i32 s4, 0x3fff
	s_nop 0
	v_addc_co_u32_e32 v131, vcc, 0, v131, vcc
	global_load_dwordx4 v[152:155], v[130:131], off
	global_load_dwordx4 v[156:159], v[132:133], off offset:16
	global_load_dwordx4 v[144:147], v[132:133], off offset:528
	global_load_dwordx4 v[148:151], v[132:133], off offset:512
	v_lshrrev_b32_e32 v131, 6, v163
	v_cmp_lt_i32_e32 vcc, s4, v164
	v_cmp_gt_i32_e64 s[4:5], s94, v164
	v_ashrrev_i32_e32 v130, 11, v164
	v_add_u32_e32 v131, 8, v131
	v_cndmask_b32_e64 v130, v131, v130, s[4:5]
	v_add_u32_e32 v130, v134, v130
	v_mad_i64_i32 v[128:129], s[4:5], v130, s6, v[128:129]
	v_lshl_add_u64 v[128:129], v[128:129], 0, v[200:201]
	v_lshl_add_u64 v[132:133], v[128:129], 0, s[12:13]
	v_add_co_u32_e64 v128, s[4:5], s7, v128
	v_cndmask_b32_e64 v203, -1, 0, s[2:3]
	s_nop 0
	v_addc_co_u32_e64 v129, s[4:5], 0, v129, s[4:5]
	global_load_dwordx4 v[140:143], v[128:129], off
	global_load_dwordx4 v[136:139], v[132:133], off offset:16
	s_nop 0
	global_load_dwordx4 v[128:131], v[132:133], off offset:528
	s_nop 0
	global_load_dwordx4 v[132:135], v[132:133], off offset:512
	v_cndmask_b32_e64 v202, v165, v171, s[2:3]
	v_mov_b32_e32 v165, 0xab98000
	v_mov_b32_e32 v171, 0x6800000
	v_lshl_add_u64 v[202:203], v[202:203], 0, v[160:161]
	v_cndmask_b32_e64 v224, v165, v171, s[2:3]
	v_lshl_add_u64 v[204:205], s[84:85], 0, v[224:225]
	v_lshlrev_b64 v[202:203], 10, v[202:203]
	v_lshl_add_u64 v[202:203], v[204:205], 0, v[202:203]
	v_lshl_add_u64 v[206:207], v[202:203], 0, v[200:201]
	s_movk_i32 s4, 0xc410
	v_mov_b32_e32 v224, v160
	s_mov_b32 s5, -1
	v_cmp_gt_i32_e64 s[2:3], s82, v160
	s_movk_i32 s6, 0xc420
	s_mov_b32 s7, -1
	s_waitcnt vmcnt(7)
	v_pk_fma_f32 v[204:205], v[126:127], v[192:193], v[154:155] op_sel_hi:[1,0,1]
	v_pk_fma_f32 v[202:203], v[124:125], v[192:193], v[152:153] op_sel_hi:[1,0,1]
	global_store_dwordx4 v[206:207], v[202:205], off
	s_waitcnt vmcnt(7)
	s_nop 0
	v_pk_fma_f32 v[204:205], v[122:123], v[192:193], v[158:159] op_sel_hi:[1,0,1]
	v_pk_fma_f32 v[202:203], v[120:121], v[192:193], v[156:157] op_sel_hi:[1,0,1]
	global_store_dwordx4 v[206:207], v[202:205], off offset:16
	s_waitcnt vmcnt(6)
	s_nop 0
	v_pk_fma_f32 v[204:205], v[118:119], v[192:193], v[150:151] op_sel_hi:[1,0,1]
	v_pk_fma_f32 v[202:203], v[116:117], v[192:193], v[148:149] op_sel_hi:[1,0,1]
	global_store_dwordx4 v[206:207], v[202:205], off offset:512
	s_nop 1
	v_pk_fma_f32 v[204:205], v[114:115], v[192:193], v[146:147] op_sel_hi:[1,0,1]
	v_pk_fma_f32 v[202:203], v[112:113], v[192:193], v[144:145] op_sel_hi:[1,0,1]
	v_lshl_add_u64 v[192:193], v[224:225], 0, s[4:5]
	s_mov_b64 s[4:5], 0x4000
	v_lshl_add_u64 v[190:191], v[190:191], 0, s[4:5]
	v_cndmask_b32_e64 v191, v193, v191, s[2:3]
	v_cndmask_b32_e64 v190, v192, v190, s[2:3]
	v_cndmask_b32_e64 v192, v165, v171, s[2:3]
	v_mov_b32_e32 v193, v225
	v_lshl_add_u64 v[192:193], s[84:85], 0, v[192:193]
	v_lshlrev_b64 v[190:191], 10, v[190:191]
	v_lshl_add_u64 v[190:191], v[192:193], 0, v[190:191]
	global_store_dwordx4 v[206:207], v[202:205], off offset:528
	v_pk_fma_f32 v[192:193], v[110:111], v[162:163], v[154:155] op_sel_hi:[1,0,1]
	v_cmp_gt_i32_e64 s[2:3], s83, v160
	v_lshl_add_u64 v[202:203], v[190:191], 0, v[200:201]
	v_pk_fma_f32 v[190:191], v[108:109], v[162:163], v[152:153] op_sel_hi:[1,0,1]
	global_store_dwordx4 v[202:203], v[190:193], off
	v_lshl_add_u64 v[166:167], v[166:167], 0, s[4:5]
	s_nop 0
	v_pk_fma_f32 v[192:193], v[106:107], v[162:163], v[158:159] op_sel_hi:[1,0,1]
	v_pk_fma_f32 v[190:191], v[104:105], v[162:163], v[156:157] op_sel_hi:[1,0,1]
	global_store_dwordx4 v[202:203], v[190:193], off offset:16
	s_nop 1
	v_pk_fma_f32 v[192:193], v[102:103], v[162:163], v[150:151] op_sel_hi:[1,0,1]
	v_pk_fma_f32 v[190:191], v[100:101], v[162:163], v[148:149] op_sel_hi:[1,0,1]
	global_store_dwordx4 v[202:203], v[190:193], off offset:512
	s_nop 1
	v_pk_fma_f32 v[192:193], v[98:99], v[162:163], v[146:147] op_sel_hi:[1,0,1]
	v_pk_fma_f32 v[190:191], v[96:97], v[162:163], v[144:145] op_sel_hi:[1,0,1]
	global_store_dwordx4 v[202:203], v[190:193], off offset:528
	s_nop 1
	v_lshl_add_u64 v[190:191], v[224:225], 0, s[6:7]
	v_cndmask_b32_e64 v167, v191, v167, s[2:3]
	v_cndmask_b32_e64 v166, v190, v166, s[2:3]
	v_cndmask_b32_e64 v190, v165, v171, s[2:3]
	v_mov_b32_e32 v191, v225
	v_lshl_add_u64 v[190:191], s[84:85], 0, v[190:191]
	v_lshlrev_b64 v[166:167], 10, v[166:167]
	v_lshl_add_u64 v[166:167], v[190:191], 0, v[166:167]
	v_lshl_add_u64 v[166:167], v[166:167], 0, v[200:201]
;     template <int PN> DI void body(AccRef acc, const Unit& u, int wr, int wc, int fr, int fq) const {
;     ...
;                 } else {
;                     float* lo = orow(out, l, row, PN == 8 ? O_PSK : O_PSV, PN == 8 ? O_SSK : O_SSV, 256);
; #pragma unroll
;                     for (int bj = 0; bj < 2; ++bj) {
;                         *(f32x4*)(lo + bj * 128 + cl) = (f32x4){v[bj][0], v[bj][1], v[bj][2], v[bj][3]};
;                         *(f32x4*)(lo + bj * 128 + cl + 4) = (f32x4){v[bj][4], v[bj][5], v[bj][6], v[bj][7]};
;                     }
	v_pk_fma_f32 v[192:193], v[94:95], v[172:173], v[154:155] op_sel_hi:[1,0,1]
	v_pk_fma_f32 v[190:191], v[92:93], v[172:173], v[152:153] op_sel_hi:[1,0,1]
	global_store_dwordx4 v[166:167], v[190:193], off
	s_movk_i32 s6, 0xc430
	s_mov_b32 s7, -1
	v_pk_fma_f32 v[192:193], v[90:91], v[172:173], v[158:159] op_sel_hi:[1,0,1]
	v_pk_fma_f32 v[190:191], v[88:89], v[172:173], v[156:157] op_sel_hi:[1,0,1]
	global_store_dwordx4 v[166:167], v[190:193], off offset:16
	v_cmp_gt_i32_e64 s[2:3], s92, v160
	v_lshl_add_u64 v[160:161], v[224:225], 0, s[6:7]
	v_pk_fma_f32 v[192:193], v[86:87], v[172:173], v[150:151] op_sel_hi:[1,0,1]
	v_pk_fma_f32 v[190:191], v[84:85], v[172:173], v[148:149] op_sel_hi:[1,0,1]
	global_store_dwordx4 v[166:167], v[190:193], off offset:512
	v_pk_fma_f32 v[154:155], v[78:79], v[188:189], v[154:155] op_sel_hi:[1,0,1]
	v_pk_fma_f32 v[152:153], v[76:77], v[188:189], v[152:153] op_sel_hi:[1,0,1]
	v_pk_fma_f32 v[192:193], v[82:83], v[172:173], v[146:147] op_sel_hi:[1,0,1]
	v_pk_fma_f32 v[190:191], v[80:81], v[172:173], v[144:145] op_sel_hi:[1,0,1]
	global_store_dwordx4 v[166:167], v[190:193], off offset:528
	v_lshl_add_u64 v[166:167], v[168:169], 0, s[4:5]
	v_cndmask_b32_e64 v161, v161, v167, s[2:3]
	v_cndmask_b32_e64 v160, v160, v166, s[2:3]
	v_cndmask_b32_e64 v166, v165, v171, s[2:3]
	v_mov_b32_e32 v167, v225
	v_lshl_add_u64 v[166:167], s[84:85], 0, v[166:167]
	v_lshlrev_b64 v[160:161], 10, v[160:161]
	v_lshl_add_u64 v[160:161], v[166:167], 0, v[160:161]
	v_lshl_add_u64 v[160:161], v[160:161], 0, v[200:201]
	global_store_dwordx4 v[160:161], v[152:155], off
	v_pk_fma_f32 v[150:151], v[70:71], v[188:189], v[150:151] op_sel_hi:[1,0,1]
	v_pk_fma_f32 v[148:149], v[68:69], v[188:189], v[148:149] op_sel_hi:[1,0,1]
	v_pk_fma_f32 v[154:155], v[74:75], v[188:189], v[158:159] op_sel_hi:[1,0,1]
	v_pk_fma_f32 v[152:153], v[72:73], v[188:189], v[156:157] op_sel_hi:[1,0,1]
	v_pk_fma_f32 v[146:147], v[66:67], v[188:189], v[146:147] op_sel_hi:[1,0,1]
	v_pk_fma_f32 v[144:145], v[64:65], v[188:189], v[144:145] op_sel_hi:[1,0,1]
	global_store_dwordx4 v[160:161], v[152:155], off offset:16
	global_store_dwordx4 v[160:161], v[148:151], off offset:512
	global_store_dwordx4 v[160:161], v[144:147], off offset:528
	s_and_saveexec_b64 s[2:3], vcc
	s_xor_b64 s[2:3], exec, s[2:3]
	v_add_u32_e32 v144, 0x400, v163
	v_mov_b32_e32 v145, v225
	s_or_saveexec_b64 s[2:3], s[2:3]
	v_mov_b64_e32 v[146:147], 0x2ae6000
	s_xor_b64 exec, exec, s[2:3]
	v_ashrrev_i32_e32 v165, 31, v164
	v_lshl_add_u64 v[144:145], v[164:165], 0, s[4:5]
	v_mov_b64_e32 v[146:147], 0x1a00000
	s_or_b64 exec, exec, s[2:3]
	v_lshlrev_b32_e32 v146, 2, v146
	v_mov_b32_e32 v147, v225
	v_lshl_add_u64 v[146:147], s[84:85], 0, v[146:147]
	v_lshlrev_b64 v[144:145], 10, v[144:145]
	v_lshl_add_u64 v[144:145], v[146:147], 0, v[144:145]
	v_lshl_add_u64 v[148:149], v[198:199], 2, v[144:145]
	s_waitcnt vmcnt(19)
	v_pk_fma_f32 v[146:147], v[62:63], v[174:175], v[142:143] op_sel_hi:[1,0,1]
	v_pk_fma_f32 v[144:145], v[60:61], v[174:175], v[140:141] op_sel_hi:[1,0,1]
	global_store_dwordx4 v[148:149], v[144:147], off
	s_movk_i32 s2, 0x3fef
	v_cmp_lt_i32_e32 vcc, s2, v164
	s_waitcnt vmcnt(19)
	v_pk_fma_f32 v[146:147], v[58:59], v[174:175], v[138:139] op_sel_hi:[1,0,1]
	v_pk_fma_f32 v[144:145], v[56:57], v[174:175], v[136:137] op_sel_hi:[1,0,1]
	global_store_dwordx4 v[148:149], v[144:147], off offset:16
	s_waitcnt vmcnt(18)
;     template <int PN> DI void body(AccRef acc, const Unit& u, int wr, int wc, int fr, int fq) const {
;     ...
;                 } else {
;                     float* lo = orow(out, l, row, PN == 8 ? O_PSK : O_PSV, PN == 8 ? O_SSK : O_SSV, 256);
; #pragma unroll
;                     for (int bj = 0; bj < 2; ++bj) {
;                         *(f32x4*)(lo + bj * 128 + cl) = (f32x4){v[bj][0], v[bj][1], v[bj][2], v[bj][3]};
;                         *(f32x4*)(lo + bj * 128 + cl + 4) = (f32x4){v[bj][4], v[bj][5], v[bj][6], v[bj][7]};
;                     }
	s_nop 0
	v_pk_fma_f32 v[146:147], v[54:55], v[174:175], v[134:135] op_sel_hi:[1,0,1]
	v_pk_fma_f32 v[144:145], v[52:53], v[174:175], v[132:133] op_sel_hi:[1,0,1]
	global_store_dwordx4 v[148:149], v[144:147], off offset:512
	s_nop 1
	v_pk_fma_f32 v[146:147], v[50:51], v[174:175], v[130:131] op_sel_hi:[1,0,1]
	v_pk_fma_f32 v[144:145], v[48:49], v[174:175], v[128:129] op_sel_hi:[1,0,1]
	global_store_dwordx4 v[148:149], v[144:147], off offset:528
	s_and_saveexec_b64 s[2:3], vcc
	s_xor_b64 s[2:3], exec, s[2:3]
	s_movk_i32 s4, 0xc490
	s_mov_b32 s5, -1
	v_lshl_add_u64 v[144:145], v[224:225], 0, s[4:5]
	s_or_saveexec_b64 s[2:3], s[2:3]
	v_mov_b64_e32 v[146:147], 0x2ae6000
	s_xor_b64 exec, exec, s[2:3]
	v_add_u32_e32 v144, 0x90, v224
	v_ashrrev_i32_e32 v145, 31, v144
	s_mov_b64 s[4:5], 0x4000
	v_lshl_add_u64 v[144:145], v[144:145], 0, s[4:5]
	v_mov_b64_e32 v[146:147], 0x1a00000
	s_or_b64 exec, exec, s[2:3]
	v_lshlrev_b32_e32 v146, 2, v146
	v_mov_b32_e32 v147, v225
	v_lshl_add_u64 v[146:147], s[84:85], 0, v[146:147]
	v_lshlrev_b64 v[144:145], 10, v[144:145]
	v_lshl_add_u64 v[144:145], v[146:147], 0, v[144:145]
	v_lshl_add_u64 v[148:149], v[198:199], 2, v[144:145]
	v_pk_fma_f32 v[146:147], v[46:47], v[170:171], v[142:143] op_sel_hi:[1,0,1]
	v_pk_fma_f32 v[144:145], v[44:45], v[170:171], v[140:141] op_sel_hi:[1,0,1]
	global_store_dwordx4 v[148:149], v[144:147], off
	s_movk_i32 s2, 0x3fdf
	v_cmp_lt_i32_e32 vcc, s2, v164
	v_pk_fma_f32 v[146:147], v[42:43], v[170:171], v[138:139] op_sel_hi:[1,0,1]
	v_pk_fma_f32 v[144:145], v[40:41], v[170:171], v[136:137] op_sel_hi:[1,0,1]
	global_store_dwordx4 v[148:149], v[144:147], off offset:16
	s_nop 1
	v_pk_fma_f32 v[146:147], v[38:39], v[170:171], v[134:135] op_sel_hi:[1,0,1]
	v_pk_fma_f32 v[144:145], v[36:37], v[170:171], v[132:133] op_sel_hi:[1,0,1]
	global_store_dwordx4 v[148:149], v[144:147], off offset:512
	s_nop 1
	v_pk_fma_f32 v[146:147], v[30:31], v[170:171], v[130:131] op_sel_hi:[1,0,1]
	v_pk_fma_f32 v[144:145], v[28:29], v[170:171], v[128:129] op_sel_hi:[1,0,1]
	global_store_dwordx4 v[148:149], v[144:147], off offset:528
	s_and_saveexec_b64 s[2:3], vcc
	s_xor_b64 s[2:3], exec, s[2:3]
	s_movk_i32 s4, 0xc4a0
	s_mov_b32 s5, -1
	v_lshl_add_u64 v[144:145], v[224:225], 0, s[4:5]
	s_or_saveexec_b64 s[2:3], s[2:3]
	v_mov_b64_e32 v[146:147], 0x2ae6000
	s_xor_b64 exec, exec, s[2:3]
	v_add_u32_e32 v144, 0xa0, v224
	v_ashrrev_i32_e32 v145, 31, v144
	s_mov_b64 s[4:5], 0x4000
	v_lshl_add_u64 v[144:145], v[144:145], 0, s[4:5]
	v_mov_b64_e32 v[146:147], 0x1a00000
	s_or_b64 exec, exec, s[2:3]
	v_lshlrev_b32_e32 v146, 2, v146
	v_mov_b32_e32 v147, v225
	v_lshl_add_u64 v[146:147], s[84:85], 0, v[146:147]
	v_lshlrev_b64 v[144:145], 10, v[144:145]
	v_lshl_add_u64 v[144:145], v[146:147], 0, v[144:145]
	v_lshl_add_u64 v[148:149], v[198:199], 2, v[144:145]
	v_pk_fma_f32 v[146:147], v[34:35], v[196:197], v[142:143] op_sel_hi:[1,0,1]
	v_pk_fma_f32 v[144:145], v[32:33], v[196:197], v[140:141] op_sel_hi:[1,0,1]
	global_store_dwordx4 v[148:149], v[144:147], off
	s_movk_i32 s2, 0x3fcf
	v_cmp_lt_i32_e32 vcc, s2, v164
	v_pk_fma_f32 v[146:147], v[26:27], v[196:197], v[138:139] op_sel_hi:[1,0,1]
	v_pk_fma_f32 v[144:145], v[24:25], v[196:197], v[136:137] op_sel_hi:[1,0,1]
	global_store_dwordx4 v[148:149], v[144:147], off offset:16
	s_nop 1
	v_pk_fma_f32 v[146:147], v[22:23], v[196:197], v[134:135] op_sel_hi:[1,0,1]
	v_pk_fma_f32 v[144:145], v[20:21], v[196:197], v[132:133] op_sel_hi:[1,0,1]
	global_store_dwordx4 v[148:149], v[144:147], off offset:512
	s_nop 1
	v_pk_fma_f32 v[146:147], v[18:19], v[196:197], v[130:131] op_sel_hi:[1,0,1]
	v_pk_fma_f32 v[144:145], v[16:17], v[196:197], v[128:129] op_sel_hi:[1,0,1]
	global_store_dwordx4 v[148:149], v[144:147], off offset:528
	s_and_saveexec_b64 s[2:3], vcc
	s_xor_b64 s[2:3], exec, s[2:3]
	s_movk_i32 s4, 0xc4b0
	s_mov_b32 s5, -1
	v_lshl_add_u64 v[144:145], v[224:225], 0, s[4:5]
	s_or_saveexec_b64 s[2:3], s[2:3]
	v_mov_b64_e32 v[146:147], 0x2ae6000
	s_xor_b64 exec, exec, s[2:3]
	v_add_u32_e32 v144, 0xb0, v224
	v_ashrrev_i32_e32 v145, 31, v144
	s_mov_b64 s[4:5], 0x4000
	v_lshl_add_u64 v[144:145], v[144:145], 0, s[4:5]
	v_mov_b64_e32 v[146:147], 0x1a00000
	s_or_b64 exec, exec, s[2:3]
	v_lshlrev_b32_e32 v224, 2, v146
	v_lshl_add_u64 v[146:147], s[84:85], 0, v[224:225]
	v_lshlrev_b64 v[144:145], 10, v[144:145]
	v_lshl_add_u64 v[144:145], v[146:147], 0, v[144:145]
	v_lshl_add_u64 v[144:145], v[198:199], 2, v[144:145]
	v_pk_fma_f32 v[142:143], v[14:15], v[194:195], v[142:143] op_sel_hi:[1,0,1]
	v_pk_fma_f32 v[140:141], v[12:13], v[194:195], v[140:141] op_sel_hi:[1,0,1]
	v_pk_fma_f32 v[138:139], v[10:11], v[194:195], v[138:139] op_sel_hi:[1,0,1]
	v_pk_fma_f32 v[136:137], v[8:9], v[194:195], v[136:137] op_sel_hi:[1,0,1]
	v_pk_fma_f32 v[134:135], v[6:7], v[194:195], v[134:135] op_sel_hi:[1,0,1]
	v_pk_fma_f32 v[132:133], v[4:5], v[194:195], v[132:133] op_sel_hi:[1,0,1]
	v_pk_fma_f32 v[130:131], v[2:3], v[194:195], v[130:131] op_sel_hi:[1,0,1]
	v_pk_fma_f32 v[128:129], v[0:1], v[194:195], v[128:129] op_sel_hi:[1,0,1]
	s_mov_b64 s[80:81], 0
	global_store_dwordx4 v[144:145], v[140:143], off
	global_store_dwordx4 v[144:145], v[136:139], off offset:16
	global_store_dwordx4 v[144:145], v[132:135], off offset:512
	global_store_dwordx4 v[144:145], v[128:131], off offset:528

; DI u32x4 pack8(const float* v) { u32x4 w; w.x = pk2(v[0], v[1]); w.y = pk2(v[2], v[3]); w.z = pk2(v[4], v[5]); w.w = pk2(v[6], v[7]); return w; }
; DI float silu(float x) { return x * __builtin_amdgcn_rcpf(1.f + ex2(-x * LOG2E)); }
;     template <int PN> DI void body(AccRef acc, const Unit& u, int wr, int wc, int fr, int fq) const {
;     ...
; #pragma unroll
;         for (int ai = 0; ai < 2; ++ai) {
;             const int rb_ = u.pm * 256 + ai * 128 + wr * 64 + fr;
;             int mb_, p_, k_; row_info(rb_, mb_, p_, k_);
; #pragma unroll
;             for (int bj = 0; bj < 2; ++bj)
; #pragma unroll
;                 for (int n = 0; n < 2; ++n) cvh[ai][bj][n] = *(const f32x4*)(cv + (size_t)(mb_ + zdep) * NIN + PN * 256 + bj * 128 + cl + 4 * n);
;         }
; #pragma unroll
;         for (int ai = 0; ai < 2; ++ai) {
;             const int rb = u.pm * 256 + ai * 128 + wr * 64 + fr;
;             int mb, pos0, kv0; row_info(rb, mb, pos0, kv0);
; #pragma unroll
;             for (int m = 0; m < 4; ++m) {
;                 const int row = rb + 16 * m, pos = pos0 + 16 * m, kvrow = kv0 + 16 * m;
;                 const float rinv = rinvh[ai][m];
;                 float v[2][8];
; #pragma unroll
;                 for (int bj = 0; bj < 2; ++bj)
; #pragma unroll
;                     for (int n = 0; n < 2; ++n)
; #pragma unroll
;                         for (int j = 0; j < 4; ++j) v[bj][4 * n + j] = acc[ai][bj][m][n][j] * rinv + cvh[ai][bj][n][j];
;     ...
;                 } else if constexpr (PN == 5 || PN == 6 || PN == 7) {
;                     bf16_t* dst = PN == 5 ? rv : (PN == 6 ? rg : sq);
; #pragma unroll
;                     for (int bj = 0; bj < 2; ++bj) {
;                         if constexpr (PN == 6) {
; #pragma unroll
;                             for (int j = 0; j < 8; ++j) v[bj][j] = silu(v[bj][j]);
;                         }
;                         if constexpr (PN == 7) {
; #pragma unroll
;                             for (int j = 0; j < 8; ++j) v[bj][j] *= 0.125f;
;                         }
;                         *(u32x4*)(dst + (size_t)row * 256 + bj * 128 + cl) = pack8(v[bj]);
;                     }
.LBB0_1901:
	s_and_b64 vcc, exec, s[2:3]
	s_cbranch_vccz .LBB0_1903
	s_lshl_b32 s2, s43, 6
	s_lshl_b32 s3, s34, 8
	s_add_i32 s2, s2, s3
	v_add_u32_e32 v160, s2, v214
	v_ashrrev_i32_e32 v161, 31, v160
	v_lshlrev_b64 v[128:129], 6, v[160:161]
	v_lshl_add_u64 v[140:141], s[70:71], 0, v[128:129]
	s_nop 0
	v_add_u32_e32 v168, 16, v160
	v_ashrrev_i32_e32 v169, 31, v168
	s_mov_b32 s2, 0x358637bd
	s_mov_b32 s4, 0x3a800000
	v_add_u32_e32 v164, 32, v160
	v_ashrrev_i32_e32 v165, 31, v164
	v_add_u32_e32 v166, 48, v160
	v_ashrrev_i32_e32 v167, 31, v166
	v_add_u32_e32 v174, 0x80, v160
	s_mov_b64 s[6:7], 0x125c00
	v_lshlrev_b64 v[200:201], 9, v[160:161]
	v_ashrrev_i32_e32 v175, 31, v174
	s_nop 0
	v_lshlrev_b64 v[128:129], 6, v[168:169]
	v_lshl_add_u64 v[140:141], s[70:71], 0, v[128:129]
	s_nop 0
	v_lshlrev_b64 v[168:169], 9, v[168:169]
	s_nop 0
	v_mov_b64_e32 v[128:129], s[2:3]
	s_nop 0
	s_nop 0
	s_nop 0
	v_mov_b32_e32 v172, v244
	s_nop 0
	v_mov_b32_e32 v162, v245
	v_lshlrev_b64 v[130:131], 6, v[164:165]
	v_lshl_add_u64 v[142:143], s[70:71], 0, v[130:131]
	s_nop 0
	s_nop 0
	v_lshlrev_b64 v[130:131], 6, v[166:167]
	v_lshl_add_u64 v[142:143], s[70:71], 0, v[130:131]
	s_nop 0
	s_nop 0
	s_nop 0
	s_nop 0
	s_nop 0
	s_nop 0
	v_mov_b32_e32 v170, v246
	s_nop 0
	v_mov_b32_e32 v190, v247
	v_mov_b32 v130, 0
	s_nop 0
	v_add_u32_e32 v130, v130, v174
	v_ashrrev_i32_e32 v131, 31, v130
	v_lshlrev_b64 v[132:133], 6, v[130:131]
	v_lshl_add_u64 v[144:145], s[70:71], 0, v[132:133]
	s_nop 0
	s_nop 0
	v_add_u32_e32 v132, 16, v130
	v_ashrrev_i32_e32 v133, 31, v132
	v_lshlrev_b64 v[132:133], 6, v[132:133]
	v_lshl_add_u64 v[144:145], s[70:71], 0, v[132:133]
	s_nop 0
	s_nop 0
	s_nop 0
	s_nop 0
	s_nop 0
	s_nop 0
	v_mov_b32_e32 v192, v248
	s_nop 0
	v_mov_b32_e32 v188, v249
	v_add_u32_e32 v132, 32, v130
	v_ashrrev_i32_e32 v133, 31, v132
	v_lshlrev_b64 v[132:133], 6, v[132:133]
	v_lshl_add_u64 v[144:145], s[70:71], 0, v[132:133]
	s_nop 0
	v_add_u32_e32 v130, 48, v130
	v_ashrrev_i32_e32 v131, 31, v130
	v_lshlrev_b64 v[130:131], 6, v[130:131]
	v_lshl_add_u64 v[142:143], s[70:71], 0, v[130:131]
	s_nop 0
	s_nop 0
	s_nop 0
	s_movk_i32 s4, 0x2800
	s_mov_b32 s5, 0x125000
	s_nop 0
	v_mov_b32_e32 v194, v250
	s_lshl_b32 s2, s60, 5
	v_lshl_add_u32 v198, v213, 3, s2
	v_ashrrev_i32_e32 v199, 31, v198
	v_mov_b32_e32 v196, v251
	v_add_u32_e32 v129, 0xffffc000, v160
	v_lshrrev_b32_e32 v129, 6, v129
	v_cmp_gt_i32_e32 vcc, s94, v160
	v_ashrrev_i32_e32 v128, 11, v160
	v_add_u32_e32 v129, 8, v129
	v_cndmask_b32_e32 v128, v129, v128, vcc
	v_mov_b32 v136, 0
	v_lshlrev_b64 v[132:133], 2, v[198:199]
	v_add_u32_e32 v130, v136, v128
	v_mov_b64_e32 v[128:129], s[74:75]
	v_mad_i64_i32 v[130:131], s[2:3], v130, s4, v[128:129]
	v_lshl_add_u64 v[130:131], v[130:131], 0, v[132:133]
	v_lshl_add_u64 v[134:135], v[130:131], 0, s[6:7]
	v_add_co_u32_e32 v130, vcc, s5, v130
	s_nop 1
	v_addc_co_u32_e32 v131, vcc, 0, v131, vcc
	global_load_dwordx4 v[152:155], v[130:131], off offset:3072
	global_load_dwordx4 v[156:159], v[134:135], off offset:16
	global_load_dwordx4 v[144:147], v[134:135], off offset:528
	global_load_dwordx4 v[148:151], v[134:135], off offset:512
	v_add_u32_e32 v131, 0xffffc080, v160
	v_lshrrev_b32_e32 v131, 6, v131
	v_cmp_gt_i32_e32 vcc, s94, v174
	v_ashrrev_i32_e32 v130, 11, v174
	v_add_u32_e32 v131, 8, v131
	v_cndmask_b32_e32 v130, v131, v130, vcc
	v_add_u32_e32 v130, v136, v130
	v_mad_i64_i32 v[128:129], s[2:3], v130, s4, v[128:129]
	v_lshl_add_u64 v[128:129], v[128:129], 0, v[132:133]
	v_lshl_add_u64 v[132:133], v[128:129], 0, s[6:7]
	v_add_co_u32_e32 v128, vcc, s5, v128
	v_readlane_b32 s2, v254, 53
	s_nop 0
	v_addc_co_u32_e32 v129, vcc, 0, v129, vcc
	global_load_dwordx4 v[140:143], v[128:129], off offset:3072
	global_load_dwordx4 v[136:139], v[132:133], off offset:16
	s_nop 0
	global_load_dwordx4 v[128:131], v[132:133], off offset:528
	s_nop 0
	global_load_dwordx4 v[132:135], v[132:133], off offset:512
	v_readlane_b32 s3, v254, 54
	s_waitcnt vmcnt(7)
	v_pk_fma_f32 v[202:203], v[126:127], v[172:173], v[154:155] op_sel_hi:[1,0,1]
	v_lshl_add_u64 v[198:199], v[198:199], 1, s[2:3]
	v_lshl_add_u64 v[204:205], v[198:199], 0, v[200:201]
	v_pk_fma_f32 v[200:201], v[124:125], v[172:173], v[152:153] op_sel_hi:[1,0,1]
	s_mov_b32 s2, 0x3e000000
	s_waitcnt vmcnt(6)
	v_pk_fma_f32 v[206:207], v[120:121], v[172:173], v[156:157] op_sel_hi:[1,0,1]
	v_pk_fma_f32 v[216:217], v[122:123], v[172:173], v[158:159] op_sel_hi:[1,0,1]
	v_pk_mul_f32 v[200:201], v[200:201], s[2:3] op_sel_hi:[1,0]
	v_pk_mul_f32 v[202:203], v[202:203], s[2:3] op_sel_hi:[1,0]
	v_pk_mul_f32 v[206:207], v[206:207], s[2:3] op_sel_hi:[1,0]
	v_pk_mul_f32 v[216:217], v[216:217], s[2:3] op_sel_hi:[1,0]
	v_cvt_pk_bf16_f32 v200, v200, v201
	v_cvt_pk_bf16_f32 v201, v202, v203
	v_cvt_pk_bf16_f32 v202, v206, v207
	v_cvt_pk_bf16_f32 v203, v216, v217
	global_store_dwordx4 v[204:205], v[200:203], off
	s_waitcnt vmcnt(6)
	v_pk_fma_f32 v[206:207], v[112:113], v[172:173], v[144:145] op_sel_hi:[1,0,1]
	v_lshl_add_u64 v[168:169], v[198:199], 0, v[168:169]
	s_waitcnt vmcnt(5)
; DI u32x4 pack8(const float* v) { u32x4 w; w.x = pk2(v[0], v[1]); w.y = pk2(v[2], v[3]); w.z = pk2(v[4], v[5]); w.w = pk2(v[6], v[7]); return w; }
; DI float silu(float x) { return x * __builtin_amdgcn_rcpf(1.f + ex2(-x * LOG2E)); }
;     template <int PN> DI void body(AccRef acc, const Unit& u, int wr, int wc, int fr, int fq) const {
;     ...
;                 } else if constexpr (PN == 5 || PN == 6 || PN == 7) {
;                     bf16_t* dst = PN == 5 ? rv : (PN == 6 ? rg : sq);
; #pragma unroll
;                     for (int bj = 0; bj < 2; ++bj) {
;                         if constexpr (PN == 6) {
; #pragma unroll
;                             for (int j = 0; j < 8; ++j) v[bj][j] = silu(v[bj][j]);
;                         }
;                         if constexpr (PN == 7) {
; #pragma unroll
;                             for (int j = 0; j < 8; ++j) v[bj][j] *= 0.125f;
;                         }
;                         *(u32x4*)(dst + (size_t)row * 256 + bj * 128 + cl) = pack8(v[bj]);
;                     }
	v_pk_fma_f32 v[200:201], v[116:117], v[172:173], v[148:149] op_sel_hi:[1,0,1]
	v_pk_fma_f32 v[202:203], v[118:119], v[172:173], v[150:151] op_sel_hi:[1,0,1]
	v_pk_fma_f32 v[172:173], v[114:115], v[172:173], v[146:147] op_sel_hi:[1,0,1]
	v_pk_mul_f32 v[200:201], v[200:201], s[2:3] op_sel_hi:[1,0]
	v_pk_mul_f32 v[202:203], v[202:203], s[2:3] op_sel_hi:[1,0]
	v_pk_mul_f32 v[206:207], v[206:207], s[2:3] op_sel_hi:[1,0]
	v_pk_mul_f32 v[172:173], v[172:173], s[2:3] op_sel_hi:[1,0]
	v_cvt_pk_bf16_f32 v200, v200, v201
	v_cvt_pk_bf16_f32 v201, v202, v203
	v_cvt_pk_bf16_f32 v202, v206, v207
	v_cvt_pk_bf16_f32 v203, v172, v173
	global_store_dwordx4 v[204:205], v[200:203], off offset:256
	v_pk_fma_f32 v[172:173], v[108:109], v[162:163], v[152:153] op_sel_hi:[1,0,1]
	s_nop 0
	v_pk_fma_f32 v[200:201], v[110:111], v[162:163], v[154:155] op_sel_hi:[1,0,1]
	v_pk_mul_f32 v[172:173], v[172:173], s[2:3] op_sel_hi:[1,0]
	v_pk_mul_f32 v[202:203], v[200:201], s[2:3] op_sel_hi:[1,0]
	v_pk_fma_f32 v[200:201], v[104:105], v[162:163], v[156:157] op_sel_hi:[1,0,1]
	s_nop 0
	v_pk_mul_f32 v[204:205], v[200:201], s[2:3] op_sel_hi:[1,0]
	v_pk_fma_f32 v[200:201], v[106:107], v[162:163], v[158:159] op_sel_hi:[1,0,1]
	s_nop 0
	v_pk_mul_f32 v[206:207], v[200:201], s[2:3] op_sel_hi:[1,0]
	v_cvt_pk_bf16_f32 v200, v172, v173
	v_cvt_pk_bf16_f32 v201, v202, v203
	v_cvt_pk_bf16_f32 v202, v204, v205
	v_cvt_pk_bf16_f32 v203, v206, v207
	global_store_dwordx4 v[168:169], v[200:203], off
	v_pk_fma_f32 v[172:173], v[100:101], v[162:163], v[148:149] op_sel_hi:[1,0,1]
	s_nop 0
	v_pk_fma_f32 v[200:201], v[102:103], v[162:163], v[150:151] op_sel_hi:[1,0,1]
	v_pk_mul_f32 v[172:173], v[172:173], s[2:3] op_sel_hi:[1,0]
	v_pk_mul_f32 v[202:203], v[200:201], s[2:3] op_sel_hi:[1,0]
	v_pk_fma_f32 v[200:201], v[96:97], v[162:163], v[144:145] op_sel_hi:[1,0,1]
	v_pk_fma_f32 v[162:163], v[98:99], v[162:163], v[146:147] op_sel_hi:[1,0,1]
	v_pk_mul_f32 v[204:205], v[200:201], s[2:3] op_sel_hi:[1,0]
	v_pk_mul_f32 v[162:163], v[162:163], s[2:3] op_sel_hi:[1,0]
	v_cvt_pk_bf16_f32 v200, v172, v173
	v_cvt_pk_bf16_f32 v201, v202, v203
	v_cvt_pk_bf16_f32 v202, v204, v205
	v_cvt_pk_bf16_f32 v203, v162, v163
	v_lshlrev_b64 v[162:163], 9, v[164:165]
	global_store_dwordx4 v[168:169], v[200:203], off offset:256
	v_lshl_add_u64 v[168:169], v[198:199], 0, v[162:163]
	v_pk_fma_f32 v[162:163], v[92:93], v[170:171], v[152:153] op_sel_hi:[1,0,1]
	v_pk_fma_f32 v[164:165], v[94:95], v[170:171], v[154:155] op_sel_hi:[1,0,1]
	v_pk_fma_f32 v[172:173], v[88:89], v[170:171], v[156:157] op_sel_hi:[1,0,1]
	v_pk_fma_f32 v[200:201], v[90:91], v[170:171], v[158:159] op_sel_hi:[1,0,1]
	v_pk_mul_f32 v[162:163], v[162:163], s[2:3] op_sel_hi:[1,0]
	v_pk_mul_f32 v[164:165], v[164:165], s[2:3] op_sel_hi:[1,0]
	v_pk_mul_f32 v[172:173], v[172:173], s[2:3] op_sel_hi:[1,0]
	v_pk_mul_f32 v[200:201], v[200:201], s[2:3] op_sel_hi:[1,0]
	v_cvt_pk_bf16_f32 v162, v162, v163
	v_cvt_pk_bf16_f32 v163, v164, v165
	v_cvt_pk_bf16_f32 v164, v172, v173
	v_cvt_pk_bf16_f32 v165, v200, v201
	global_store_dwordx4 v[168:169], v[162:165], off
	v_pk_fma_f32 v[172:173], v[80:81], v[170:171], v[144:145] op_sel_hi:[1,0,1]
	v_pk_fma_f32 v[152:153], v[76:77], v[190:191], v[152:153] op_sel_hi:[1,0,1]
	v_pk_fma_f32 v[162:163], v[84:85], v[170:171], v[148:149] op_sel_hi:[1,0,1]
	v_pk_fma_f32 v[164:165], v[86:87], v[170:171], v[150:151] op_sel_hi:[1,0,1]
	v_pk_fma_f32 v[170:171], v[82:83], v[170:171], v[146:147] op_sel_hi:[1,0,1]
	v_pk_mul_f32 v[162:163], v[162:163], s[2:3] op_sel_hi:[1,0]
	v_pk_mul_f32 v[164:165], v[164:165], s[2:3] op_sel_hi:[1,0]
	v_pk_mul_f32 v[172:173], v[172:173], s[2:3] op_sel_hi:[1,0]
	v_pk_mul_f32 v[170:171], v[170:171], s[2:3] op_sel_hi:[1,0]
	v_cvt_pk_bf16_f32 v162, v162, v163
	v_cvt_pk_bf16_f32 v163, v164, v165
	v_cvt_pk_bf16_f32 v164, v172, v173
	v_cvt_pk_bf16_f32 v165, v170, v171
	v_pk_fma_f32 v[154:155], v[78:79], v[190:191], v[154:155] op_sel_hi:[1,0,1]
	v_pk_fma_f32 v[156:157], v[72:73], v[190:191], v[156:157] op_sel_hi:[1,0,1]
	v_pk_fma_f32 v[158:159], v[74:75], v[190:191], v[158:159] op_sel_hi:[1,0,1]
	global_store_dwordx4 v[168:169], v[162:165], off offset:256
	v_pk_mul_f32 v[152:153], v[152:153], s[2:3] op_sel_hi:[1,0]
	v_pk_mul_f32 v[154:155], v[154:155], s[2:3] op_sel_hi:[1,0]
	v_lshlrev_b64 v[162:163], 9, v[166:167]
	v_pk_mul_f32 v[156:157], v[156:157], s[2:3] op_sel_hi:[1,0]
	v_pk_mul_f32 v[158:159], v[158:159], s[2:3] op_sel_hi:[1,0]
	v_lshl_add_u64 v[162:163], v[198:199], 0, v[162:163]
	v_cvt_pk_bf16_f32 v152, v152, v153
	v_cvt_pk_bf16_f32 v153, v154, v155
	v_cvt_pk_bf16_f32 v154, v156, v157
	v_cvt_pk_bf16_f32 v155, v158, v159
	v_pk_fma_f32 v[144:145], v[64:65], v[190:191], v[144:145] op_sel_hi:[1,0,1]
	global_store_dwordx4 v[162:163], v[152:155], off
	v_pk_fma_f32 v[148:149], v[68:69], v[190:191], v[148:149] op_sel_hi:[1,0,1]
	v_pk_fma_f32 v[150:151], v[70:71], v[190:191], v[150:151] op_sel_hi:[1,0,1]
	v_pk_mul_f32 v[152:153], v[144:145], s[2:3] op_sel_hi:[1,0]
	v_pk_fma_f32 v[144:145], v[66:67], v[190:191], v[146:147] op_sel_hi:[1,0,1]
	v_pk_mul_f32 v[148:149], v[148:149], s[2:3] op_sel_hi:[1,0]
	v_pk_mul_f32 v[150:151], v[150:151], s[2:3] op_sel_hi:[1,0]
	v_pk_mul_f32 v[154:155], v[144:145], s[2:3] op_sel_hi:[1,0]
	v_cvt_pk_bf16_f32 v144, v148, v149
	v_cvt_pk_bf16_f32 v145, v150, v151
	v_cvt_pk_bf16_f32 v146, v152, v153
	v_cvt_pk_bf16_f32 v147, v154, v155
	global_store_dwordx4 v[162:163], v[144:147], off offset:256
	s_waitcnt vmcnt(10)
; DI u32x4 pack8(const float* v) { u32x4 w; w.x = pk2(v[0], v[1]); w.y = pk2(v[2], v[3]); w.z = pk2(v[4], v[5]); w.w = pk2(v[6], v[7]); return w; }
; DI float silu(float x) { return x * __builtin_amdgcn_rcpf(1.f + ex2(-x * LOG2E)); }
;     template <int PN> DI void body(AccRef acc, const Unit& u, int wr, int wc, int fr, int fq) const {
;     ...
;                 } else if constexpr (PN == 5 || PN == 6 || PN == 7) {
;                     bf16_t* dst = PN == 5 ? rv : (PN == 6 ? rg : sq);
; #pragma unroll
;                     for (int bj = 0; bj < 2; ++bj) {
;                         if constexpr (PN == 6) {
; #pragma unroll
;                             for (int j = 0; j < 8; ++j) v[bj][j] = silu(v[bj][j]);
;                         }
;                         if constexpr (PN == 7) {
; #pragma unroll
;                             for (int j = 0; j < 8; ++j) v[bj][j] *= 0.125f;
;                         }
;                         *(u32x4*)(dst + (size_t)row * 256 + bj * 128 + cl) = pack8(v[bj]);
;                     }
	v_pk_fma_f32 v[150:151], v[56:57], v[192:193], v[136:137] op_sel_hi:[1,0,1]
	v_pk_fma_f32 v[152:153], v[58:59], v[192:193], v[138:139] op_sel_hi:[1,0,1]
	v_lshlrev_b64 v[144:145], 9, v[174:175]
	v_lshl_add_u64 v[148:149], v[198:199], 0, v[144:145]
	v_pk_fma_f32 v[144:145], v[60:61], v[192:193], v[140:141] op_sel_hi:[1,0,1]
	v_pk_fma_f32 v[146:147], v[62:63], v[192:193], v[142:143] op_sel_hi:[1,0,1]
	v_pk_mul_f32 v[144:145], v[144:145], s[2:3] op_sel_hi:[1,0]
	v_pk_mul_f32 v[146:147], v[146:147], s[2:3] op_sel_hi:[1,0]
	v_pk_mul_f32 v[150:151], v[150:151], s[2:3] op_sel_hi:[1,0]
	v_pk_mul_f32 v[152:153], v[152:153], s[2:3] op_sel_hi:[1,0]
	v_cvt_pk_bf16_f32 v144, v144, v145
	v_cvt_pk_bf16_f32 v145, v146, v147
	v_cvt_pk_bf16_f32 v146, v150, v151
	v_cvt_pk_bf16_f32 v147, v152, v153
	global_store_dwordx4 v[148:149], v[144:147], off
	s_waitcnt vmcnt(10)
	v_pk_fma_f32 v[150:151], v[48:49], v[192:193], v[128:129] op_sel_hi:[1,0,1]
	v_pk_fma_f32 v[152:153], v[50:51], v[192:193], v[130:131] op_sel_hi:[1,0,1]
	s_waitcnt vmcnt(9)
	v_pk_fma_f32 v[144:145], v[52:53], v[192:193], v[132:133] op_sel_hi:[1,0,1]
	v_pk_fma_f32 v[146:147], v[54:55], v[192:193], v[134:135] op_sel_hi:[1,0,1]
	v_pk_mul_f32 v[144:145], v[144:145], s[2:3] op_sel_hi:[1,0]
	v_pk_mul_f32 v[146:147], v[146:147], s[2:3] op_sel_hi:[1,0]
	v_pk_mul_f32 v[150:151], v[150:151], s[2:3] op_sel_hi:[1,0]
	v_pk_mul_f32 v[152:153], v[152:153], s[2:3] op_sel_hi:[1,0]
	v_cvt_pk_bf16_f32 v144, v144, v145
	v_cvt_pk_bf16_f32 v145, v146, v147
	v_cvt_pk_bf16_f32 v146, v150, v151
	v_cvt_pk_bf16_f32 v147, v152, v153
	global_store_dwordx4 v[148:149], v[144:147], off offset:256
	v_pk_fma_f32 v[150:151], v[40:41], v[188:189], v[136:137] op_sel_hi:[1,0,1]
	v_pk_fma_f32 v[152:153], v[42:43], v[188:189], v[138:139] op_sel_hi:[1,0,1]
	v_add_u32_e32 v144, 0x90, v160
	v_ashrrev_i32_e32 v145, 31, v144
	v_lshlrev_b64 v[144:145], 9, v[144:145]
	v_lshl_add_u64 v[148:149], v[198:199], 0, v[144:145]
	v_pk_fma_f32 v[144:145], v[44:45], v[188:189], v[140:141] op_sel_hi:[1,0,1]
	v_pk_fma_f32 v[146:147], v[46:47], v[188:189], v[142:143] op_sel_hi:[1,0,1]
	v_pk_mul_f32 v[144:145], v[144:145], s[2:3] op_sel_hi:[1,0]
	v_pk_mul_f32 v[146:147], v[146:147], s[2:3] op_sel_hi:[1,0]
	v_pk_mul_f32 v[150:151], v[150:151], s[2:3] op_sel_hi:[1,0]
	v_pk_mul_f32 v[152:153], v[152:153], s[2:3] op_sel_hi:[1,0]
	v_cvt_pk_bf16_f32 v144, v144, v145
	v_cvt_pk_bf16_f32 v145, v146, v147
	v_cvt_pk_bf16_f32 v146, v150, v151
	v_cvt_pk_bf16_f32 v147, v152, v153
	global_store_dwordx4 v[148:149], v[144:147], off
	v_pk_fma_f32 v[150:151], v[28:29], v[188:189], v[128:129] op_sel_hi:[1,0,1]
	v_pk_fma_f32 v[152:153], v[30:31], v[188:189], v[130:131] op_sel_hi:[1,0,1]
	v_pk_fma_f32 v[144:145], v[36:37], v[188:189], v[132:133] op_sel_hi:[1,0,1]
	v_pk_fma_f32 v[146:147], v[38:39], v[188:189], v[134:135] op_sel_hi:[1,0,1]
	v_pk_mul_f32 v[144:145], v[144:145], s[2:3] op_sel_hi:[1,0]
	v_pk_mul_f32 v[146:147], v[146:147], s[2:3] op_sel_hi:[1,0]
	v_pk_mul_f32 v[150:151], v[150:151], s[2:3] op_sel_hi:[1,0]
	v_pk_mul_f32 v[152:153], v[152:153], s[2:3] op_sel_hi:[1,0]
	v_cvt_pk_bf16_f32 v144, v144, v145
	v_cvt_pk_bf16_f32 v145, v146, v147
	v_cvt_pk_bf16_f32 v146, v150, v151
	v_cvt_pk_bf16_f32 v147, v152, v153
	global_store_dwordx4 v[148:149], v[144:147], off offset:256
	v_pk_fma_f32 v[150:151], v[24:25], v[194:195], v[136:137] op_sel_hi:[1,0,1]
	v_pk_fma_f32 v[152:153], v[26:27], v[194:195], v[138:139] op_sel_hi:[1,0,1]
	v_add_u32_e32 v144, 0xa0, v160
	v_ashrrev_i32_e32 v145, 31, v144
	v_lshlrev_b64 v[144:145], 9, v[144:145]
	v_lshl_add_u64 v[148:149], v[198:199], 0, v[144:145]
	v_pk_fma_f32 v[144:145], v[32:33], v[194:195], v[140:141] op_sel_hi:[1,0,1]
	v_pk_fma_f32 v[146:147], v[34:35], v[194:195], v[142:143] op_sel_hi:[1,0,1]
	v_pk_mul_f32 v[144:145], v[144:145], s[2:3] op_sel_hi:[1,0]
	v_pk_mul_f32 v[146:147], v[146:147], s[2:3] op_sel_hi:[1,0]
	v_pk_mul_f32 v[150:151], v[150:151], s[2:3] op_sel_hi:[1,0]
	v_pk_mul_f32 v[152:153], v[152:153], s[2:3] op_sel_hi:[1,0]
	v_cvt_pk_bf16_f32 v144, v144, v145
	v_cvt_pk_bf16_f32 v145, v146, v147
	v_cvt_pk_bf16_f32 v146, v150, v151
	v_cvt_pk_bf16_f32 v147, v152, v153
	global_store_dwordx4 v[148:149], v[144:147], off
	v_pk_fma_f32 v[150:151], v[16:17], v[194:195], v[128:129] op_sel_hi:[1,0,1]
	v_pk_fma_f32 v[152:153], v[18:19], v[194:195], v[130:131] op_sel_hi:[1,0,1]
	v_pk_fma_f32 v[144:145], v[20:21], v[194:195], v[132:133] op_sel_hi:[1,0,1]
	v_pk_fma_f32 v[146:147], v[22:23], v[194:195], v[134:135] op_sel_hi:[1,0,1]
	v_pk_mul_f32 v[144:145], v[144:145], s[2:3] op_sel_hi:[1,0]
	v_pk_mul_f32 v[146:147], v[146:147], s[2:3] op_sel_hi:[1,0]
	v_pk_mul_f32 v[150:151], v[150:151], s[2:3] op_sel_hi:[1,0]
	v_pk_mul_f32 v[152:153], v[152:153], s[2:3] op_sel_hi:[1,0]
	v_cvt_pk_bf16_f32 v144, v144, v145
	v_cvt_pk_bf16_f32 v145, v146, v147
	v_cvt_pk_bf16_f32 v146, v150, v151
	v_cvt_pk_bf16_f32 v147, v152, v153
	global_store_dwordx4 v[148:149], v[144:147], off offset:256
	v_pk_fma_f32 v[136:137], v[8:9], v[196:197], v[136:137] op_sel_hi:[1,0,1]
	v_pk_fma_f32 v[140:141], v[12:13], v[196:197], v[140:141] op_sel_hi:[1,0,1]
	v_add_u32_e32 v144, 0xb0, v160
	v_ashrrev_i32_e32 v145, 31, v144
	v_pk_fma_f32 v[142:143], v[14:15], v[196:197], v[142:143] op_sel_hi:[1,0,1]
	v_pk_mul_f32 v[146:147], v[136:137], s[2:3] op_sel_hi:[1,0]
	v_pk_fma_f32 v[136:137], v[10:11], v[196:197], v[138:139] op_sel_hi:[1,0,1]
	v_lshlrev_b64 v[144:145], 9, v[144:145]
	v_pk_mul_f32 v[140:141], v[140:141], s[2:3] op_sel_hi:[1,0]
	v_pk_mul_f32 v[142:143], v[142:143], s[2:3] op_sel_hi:[1,0]
	v_pk_mul_f32 v[148:149], v[136:137], s[2:3] op_sel_hi:[1,0]
	v_lshl_add_u64 v[144:145], v[198:199], 0, v[144:145]
	v_cvt_pk_bf16_f32 v136, v140, v141
	v_cvt_pk_bf16_f32 v137, v142, v143
	v_cvt_pk_bf16_f32 v138, v146, v147
	v_cvt_pk_bf16_f32 v139, v148, v149
	v_pk_fma_f32 v[128:129], v[0:1], v[196:197], v[128:129] op_sel_hi:[1,0,1]
	global_store_dwordx4 v[144:145], v[136:139], off
	v_pk_fma_f32 v[132:133], v[4:5], v[196:197], v[132:133] op_sel_hi:[1,0,1]
	v_pk_fma_f32 v[134:135], v[6:7], v[196:197], v[134:135] op_sel_hi:[1,0,1]
	v_pk_mul_f32 v[136:137], v[128:129], s[2:3] op_sel_hi:[1,0]
	v_pk_fma_f32 v[128:129], v[2:3], v[196:197], v[130:131] op_sel_hi:[1,0,1]
	v_pk_mul_f32 v[132:133], v[132:133], s[2:3] op_sel_hi:[1,0]
	v_pk_mul_f32 v[134:135], v[134:135], s[2:3] op_sel_hi:[1,0]
	v_pk_mul_f32 v[138:139], v[128:129], s[2:3] op_sel_hi:[1,0]
	v_cvt_pk_bf16_f32 v128, v132, v133
	v_cvt_pk_bf16_f32 v129, v134, v135
	v_cvt_pk_bf16_f32 v130, v136, v137
	v_cvt_pk_bf16_f32 v131, v138, v139
	global_store_dwordx4 v[144:145], v[128:131], off offset:256

; DI u32x4 pack8(const float* v) { u32x4 w; w.x = pk2(v[0], v[1]); w.y = pk2(v[2], v[3]); w.z = pk2(v[4], v[5]); w.w = pk2(v[6], v[7]); return w; }
; DI float silu(float x) { return x * __builtin_amdgcn_rcpf(1.f + ex2(-x * LOG2E)); }
;     template <int PN> DI void body(AccRef acc, const Unit& u, int wr, int wc, int fr, int fq) const {
;     ...
; #pragma unroll
;         for (int ai = 0; ai < 2; ++ai) {
;             const int rb_ = u.pm * 256 + ai * 128 + wr * 64 + fr;
;             int mb_, p_, k_; row_info(rb_, mb_, p_, k_);
; #pragma unroll
;             for (int bj = 0; bj < 2; ++bj)
; #pragma unroll
;                 for (int n = 0; n < 2; ++n) cvh[ai][bj][n] = *(const f32x4*)(cv + (size_t)(mb_ + zdep) * NIN + PN * 256 + bj * 128 + cl + 4 * n);
;         }
; #pragma unroll
;         for (int ai = 0; ai < 2; ++ai) {
;             const int rb = u.pm * 256 + ai * 128 + wr * 64 + fr;
;             int mb, pos0, kv0; row_info(rb, mb, pos0, kv0);
; #pragma unroll
;             for (int m = 0; m < 4; ++m) {
;                 const int row = rb + 16 * m, pos = pos0 + 16 * m, kvrow = kv0 + 16 * m;
;                 const float rinv = rinvh[ai][m];
;                 float v[2][8];
; #pragma unroll
;                 for (int bj = 0; bj < 2; ++bj)
; #pragma unroll
;                     for (int n = 0; n < 2; ++n)
; #pragma unroll
;                         for (int j = 0; j < 4; ++j) v[bj][4 * n + j] = acc[ai][bj][m][n][j] * rinv + cvh[ai][bj][n][j];
;     ...
;                 } else if constexpr (PN == 5 || PN == 6 || PN == 7) {
;                     bf16_t* dst = PN == 5 ? rv : (PN == 6 ? rg : sq);
; #pragma unroll
;                     for (int bj = 0; bj < 2; ++bj) {
;                         if constexpr (PN == 6) {
; #pragma unroll
;                             for (int j = 0; j < 8; ++j) v[bj][j] = silu(v[bj][j]);
;                         }
;                         if constexpr (PN == 7) {
; #pragma unroll
;                             for (int j = 0; j < 8; ++j) v[bj][j] *= 0.125f;
;                         }
;                         *(u32x4*)(dst + (size_t)row * 256 + bj * 128 + cl) = pack8(v[bj]);
;                     }
.LBB0_1904:
	s_and_b64 vcc, exec, s[2:3]
	s_cbranch_vccz .LBB0_1906
	s_lshl_b32 s2, s43, 6
	s_lshl_b32 s3, s34, 8
	s_add_i32 s2, s2, s3
	v_add_u32_e32 v160, s2, v214
	v_ashrrev_i32_e32 v161, 31, v160
	v_lshlrev_b64 v[128:129], 6, v[160:161]
	v_lshl_add_u64 v[140:141], s[70:71], 0, v[128:129]
	s_nop 0
	v_add_u32_e32 v196, 16, v160
	v_ashrrev_i32_e32 v197, 31, v196
	s_mov_b32 s2, 0x358637bd
	s_mov_b32 s4, 0x3a800000
	v_add_u32_e32 v194, 32, v160
	v_ashrrev_i32_e32 v195, 31, v194
	v_add_u32_e32 v188, 48, v160
	v_ashrrev_i32_e32 v189, 31, v188
	v_add_u32_e32 v172, 0x80, v160
	s_mov_b64 s[6:7], 0x125800
	v_lshlrev_b64 v[200:201], 9, v[160:161]
	v_ashrrev_i32_e32 v173, 31, v172
	s_nop 0
	v_lshlrev_b64 v[128:129], 6, v[196:197]
	v_lshl_add_u64 v[140:141], s[70:71], 0, v[128:129]
	s_nop 0
	v_lshlrev_b64 v[196:197], 9, v[196:197]
	s_nop 0
	v_mov_b64_e32 v[128:129], s[2:3]
	s_nop 0
	s_nop 0
	s_nop 0
	v_mov_b32_e32 v198, v244
	s_nop 0
	v_mov_b32_e32 v190, v245
	v_lshlrev_b64 v[130:131], 6, v[194:195]
	v_lshl_add_u64 v[142:143], s[70:71], 0, v[130:131]
	s_nop 0
	s_nop 0
	v_lshlrev_b64 v[130:131], 6, v[188:189]
	v_lshl_add_u64 v[142:143], s[70:71], 0, v[130:131]
	s_nop 0
	v_lshlrev_b64 v[188:189], 9, v[188:189]
	s_nop 0
	s_nop 0
	s_nop 0
	s_nop 0
	s_nop 0
	v_mov_b32_e32 v192, v246
	s_nop 0
	v_mov_b32_e32 v174, v247
	v_mov_b32 v130, 0
	s_nop 0
	v_add_u32_e32 v130, v130, v172
	v_ashrrev_i32_e32 v131, 31, v130
	v_lshlrev_b64 v[132:133], 6, v[130:131]
	v_lshl_add_u64 v[144:145], s[70:71], 0, v[132:133]
	s_nop 0
	s_nop 0
	v_add_u32_e32 v132, 16, v130
	v_ashrrev_i32_e32 v133, 31, v132
	v_lshlrev_b64 v[132:133], 6, v[132:133]
	v_lshl_add_u64 v[144:145], s[70:71], 0, v[132:133]
	s_nop 0
	s_nop 0
	s_nop 0
	s_nop 0
	s_nop 0
	s_nop 0
	v_mov_b32_e32 v170, v248
	s_nop 0
	v_mov_b32_e32 v164, v249
	v_add_u32_e32 v132, 32, v130
	v_ashrrev_i32_e32 v133, 31, v132
	v_lshlrev_b64 v[132:133], 6, v[132:133]
	v_lshl_add_u64 v[144:145], s[70:71], 0, v[132:133]
	s_nop 0
	v_add_u32_e32 v130, 48, v130
	v_ashrrev_i32_e32 v131, 31, v130
	v_lshlrev_b64 v[130:131], 6, v[130:131]
	v_lshl_add_u64 v[142:143], s[70:71], 0, v[130:131]
	s_nop 0
	s_nop 0
	s_nop 0
	s_movk_i32 s4, 0x2800
	s_mov_b32 s5, 0x125000
	s_nop 0
	v_mov_b32_e32 v166, v250
	s_lshl_b32 s2, s60, 5
	v_lshl_add_u32 v168, v213, 3, s2
	v_ashrrev_i32_e32 v169, 31, v168
	v_mov_b32_e32 v162, v251
	v_add_u32_e32 v129, 0xffffc000, v160
	v_lshrrev_b32_e32 v129, 6, v129
	v_cmp_gt_i32_e32 vcc, s94, v160
	v_ashrrev_i32_e32 v128, 11, v160
	v_add_u32_e32 v129, 8, v129
	v_cndmask_b32_e32 v128, v129, v128, vcc
	v_mov_b32 v136, 0
	v_lshlrev_b64 v[132:133], 2, v[168:169]
	v_add_u32_e32 v130, v136, v128
	v_mov_b64_e32 v[128:129], s[74:75]
	v_mad_i64_i32 v[130:131], s[2:3], v130, s4, v[128:129]
	v_lshl_add_u64 v[130:131], v[130:131], 0, v[132:133]
	v_lshl_add_u64 v[134:135], v[130:131], 0, s[6:7]
	v_add_co_u32_e32 v130, vcc, s5, v130
	s_nop 1
	v_addc_co_u32_e32 v131, vcc, 0, v131, vcc
	global_load_dwordx4 v[156:159], v[130:131], off offset:2048
	global_load_dwordx4 v[152:155], v[134:135], off offset:16
	global_load_dwordx4 v[144:147], v[134:135], off offset:528
	global_load_dwordx4 v[148:151], v[134:135], off offset:512
	v_add_u32_e32 v131, 0xffffc080, v160
	v_lshrrev_b32_e32 v131, 6, v131
	v_cmp_gt_i32_e32 vcc, s94, v172
	v_ashrrev_i32_e32 v130, 11, v172
	v_add_u32_e32 v131, 8, v131
	v_cndmask_b32_e32 v130, v131, v130, vcc
	v_add_u32_e32 v130, v136, v130
	v_mad_i64_i32 v[128:129], s[2:3], v130, s4, v[128:129]
	v_readlane_b32 s2, v254, 46
	v_lshl_add_u64 v[128:129], v[128:129], 0, v[132:133]
	v_readlane_b32 s3, v254, 47
	v_lshl_add_u64 v[132:133], v[128:129], 0, s[6:7]
	v_add_co_u32_e32 v128, vcc, s5, v128
	v_lshl_add_u64 v[168:169], v[168:169], 1, s[2:3]
	s_nop 0
	v_addc_co_u32_e32 v129, vcc, 0, v129, vcc
	v_lshl_add_u64 v[200:201], v[168:169], 0, v[200:201]
	global_load_dwordx4 v[140:143], v[128:129], off offset:2048
	global_load_dwordx4 v[136:139], v[132:133], off offset:16
	s_nop 0
	global_load_dwordx4 v[128:131], v[132:133], off offset:528
	s_nop 0
	global_load_dwordx4 v[132:135], v[132:133], off offset:512
	v_lshl_add_u64 v[196:197], v[168:169], 0, v[196:197]
	v_lshl_add_u64 v[188:189], v[168:169], 0, v[188:189]
	s_waitcnt vmcnt(7)
	v_pk_fma_f32 v[202:203], v[124:125], v[198:199], v[156:157] op_sel_hi:[1,0,1]
	s_nop 0
	v_mul_f32_e32 v161, 0xbfb8aa3b, v202
	v_exp_f32_e32 v161, v161
	s_nop 0
	v_add_f32_e32 v161, 1.0, v161
	v_rcp_f32_e32 v204, v161
	v_mul_f32_e32 v161, 0xbfb8aa3b, v203
	v_exp_f32_e32 v161, v161
	s_nop 0
	v_add_f32_e32 v161, 1.0, v161
	v_rcp_f32_e32 v205, v161
	s_nop 0
	v_pk_mul_f32 v[202:203], v[202:203], v[204:205]
	v_pk_fma_f32 v[204:205], v[126:127], v[198:199], v[158:159] op_sel_hi:[1,0,1]
	v_cvt_pk_bf16_f32 v202, v202, v203
	v_mul_f32_e32 v161, 0xbfb8aa3b, v204
	v_exp_f32_e32 v161, v161
	s_nop 0
	v_add_f32_e32 v161, 1.0, v161
	v_rcp_f32_e32 v206, v161
	v_mul_f32_e32 v161, 0xbfb8aa3b, v205
	v_exp_f32_e32 v161, v161
	s_nop 0
	v_add_f32_e32 v161, 1.0, v161
	v_rcp_f32_e32 v207, v161
	s_nop 0
	v_pk_mul_f32 v[204:205], v[204:205], v[206:207]
	s_waitcnt vmcnt(6)
	v_pk_fma_f32 v[206:207], v[120:121], v[198:199], v[152:153] op_sel_hi:[1,0,1]
	v_cvt_pk_bf16_f32 v203, v204, v205
	v_mul_f32_e32 v161, 0xbfb8aa3b, v206
	v_exp_f32_e32 v161, v161
	s_nop 0
	v_add_f32_e32 v161, 1.0, v161
	v_rcp_f32_e32 v216, v161
	v_mul_f32_e32 v161, 0xbfb8aa3b, v207
	v_exp_f32_e32 v161, v161
	s_nop 0
	v_add_f32_e32 v161, 1.0, v161
	v_rcp_f32_e32 v217, v161
	s_nop 0
	v_pk_mul_f32 v[206:207], v[206:207], v[216:217]
	v_pk_fma_f32 v[216:217], v[122:123], v[198:199], v[154:155] op_sel_hi:[1,0,1]
	v_cvt_pk_bf16_f32 v204, v206, v207
	v_mul_f32_e32 v161, 0xbfb8aa3b, v216
	v_exp_f32_e32 v161, v161
	s_nop 0
	v_add_f32_e32 v161, 1.0, v161
	v_rcp_f32_e32 v218, v161
	v_mul_f32_e32 v161, 0xbfb8aa3b, v217
	v_exp_f32_e32 v161, v161
	s_nop 0
	v_add_f32_e32 v161, 1.0, v161
	v_rcp_f32_e32 v219, v161
	s_nop 0
	v_pk_mul_f32 v[216:217], v[216:217], v[218:219]
	s_nop 0
	v_cvt_pk_bf16_f32 v205, v216, v217
	global_store_dwordx4 v[200:201], v[202:205], off
	s_waitcnt vmcnt(5)
; DI u32x4 pack8(const float* v) { u32x4 w; w.x = pk2(v[0], v[1]); w.y = pk2(v[2], v[3]); w.z = pk2(v[4], v[5]); w.w = pk2(v[6], v[7]); return w; }
; DI float silu(float x) { return x * __builtin_amdgcn_rcpf(1.f + ex2(-x * LOG2E)); }
;     template <int PN> DI void body(AccRef acc, const Unit& u, int wr, int wc, int fr, int fq) const {
;     ...
;                 } else if constexpr (PN == 5 || PN == 6 || PN == 7) {
;                     bf16_t* dst = PN == 5 ? rv : (PN == 6 ? rg : sq);
; #pragma unroll
;                     for (int bj = 0; bj < 2; ++bj) {
;                         if constexpr (PN == 6) {
; #pragma unroll
;                             for (int j = 0; j < 8; ++j) v[bj][j] = silu(v[bj][j]);
;                         }
;                         if constexpr (PN == 7) {
; #pragma unroll
;                             for (int j = 0; j < 8; ++j) v[bj][j] *= 0.125f;
;                         }
;                         *(u32x4*)(dst + (size_t)row * 256 + bj * 128 + cl) = pack8(v[bj]);
;                     }
	s_nop 0
	v_pk_fma_f32 v[202:203], v[116:117], v[198:199], v[148:149] op_sel_hi:[1,0,1]
	s_nop 0
	v_mul_f32_e32 v161, 0xbfb8aa3b, v202
	v_exp_f32_e32 v161, v161
	s_nop 0
	v_add_f32_e32 v161, 1.0, v161
	v_rcp_f32_e32 v204, v161
	v_mul_f32_e32 v161, 0xbfb8aa3b, v203
	v_exp_f32_e32 v161, v161
	s_nop 0
	v_add_f32_e32 v161, 1.0, v161
	v_rcp_f32_e32 v205, v161
	s_nop 0
	v_pk_mul_f32 v[202:203], v[202:203], v[204:205]
	v_pk_fma_f32 v[204:205], v[118:119], v[198:199], v[150:151] op_sel_hi:[1,0,1]
	v_cvt_pk_bf16_f32 v202, v202, v203
	v_mul_f32_e32 v161, 0xbfb8aa3b, v204
	v_exp_f32_e32 v161, v161
	s_nop 0
	v_add_f32_e32 v161, 1.0, v161
	v_rcp_f32_e32 v206, v161
	v_mul_f32_e32 v161, 0xbfb8aa3b, v205
	v_exp_f32_e32 v161, v161
	s_nop 0
	v_add_f32_e32 v161, 1.0, v161
	v_rcp_f32_e32 v207, v161
	s_nop 0
	v_pk_mul_f32 v[204:205], v[204:205], v[206:207]
	v_pk_fma_f32 v[206:207], v[112:113], v[198:199], v[144:145] op_sel_hi:[1,0,1]
	v_pk_fma_f32 v[198:199], v[114:115], v[198:199], v[146:147] op_sel_hi:[1,0,1]
	v_mul_f32_e32 v161, 0xbfb8aa3b, v206
	v_exp_f32_e32 v161, v161
	v_cvt_pk_bf16_f32 v203, v204, v205
	v_add_f32_e32 v161, 1.0, v161
	v_rcp_f32_e32 v216, v161
	v_mul_f32_e32 v161, 0xbfb8aa3b, v207
	v_exp_f32_e32 v161, v161
	s_nop 0
	v_add_f32_e32 v161, 1.0, v161
	v_rcp_f32_e32 v217, v161
	v_mul_f32_e32 v161, 0xbfb8aa3b, v198
	v_exp_f32_e32 v161, v161
	v_pk_mul_f32 v[206:207], v[206:207], v[216:217]
	s_nop 0
	v_cvt_pk_bf16_f32 v204, v206, v207
	v_add_f32_e32 v161, 1.0, v161
	v_rcp_f32_e32 v216, v161
	v_mul_f32_e32 v161, 0xbfb8aa3b, v199
	v_exp_f32_e32 v161, v161
	s_nop 0
	v_add_f32_e32 v161, 1.0, v161
	v_rcp_f32_e32 v217, v161
	s_nop 0
	v_pk_mul_f32 v[198:199], v[198:199], v[216:217]
	s_nop 0
	v_cvt_pk_bf16_f32 v205, v198, v199
	v_pk_fma_f32 v[198:199], v[108:109], v[190:191], v[156:157] op_sel_hi:[1,0,1]
	global_store_dwordx4 v[200:201], v[202:205], off offset:256
	v_mul_f32_e32 v161, 0xbfb8aa3b, v198
	v_exp_f32_e32 v161, v161
	s_nop 0
	v_add_f32_e32 v161, 1.0, v161
	v_rcp_f32_e32 v200, v161
	v_mul_f32_e32 v161, 0xbfb8aa3b, v199
	v_exp_f32_e32 v161, v161
	s_nop 0
	v_add_f32_e32 v161, 1.0, v161
	v_rcp_f32_e32 v201, v161
	s_nop 0
	v_pk_mul_f32 v[198:199], v[198:199], v[200:201]
	v_pk_fma_f32 v[200:201], v[110:111], v[190:191], v[158:159] op_sel_hi:[1,0,1]
	v_cvt_pk_bf16_f32 v198, v198, v199
	v_mul_f32_e32 v161, 0xbfb8aa3b, v200
	v_exp_f32_e32 v161, v161
	s_nop 0
	v_add_f32_e32 v161, 1.0, v161
	v_rcp_f32_e32 v202, v161
	v_mul_f32_e32 v161, 0xbfb8aa3b, v201
	v_exp_f32_e32 v161, v161
	s_nop 0
	v_add_f32_e32 v161, 1.0, v161
	v_rcp_f32_e32 v203, v161
	s_nop 0
	v_pk_mul_f32 v[200:201], v[200:201], v[202:203]
	v_pk_fma_f32 v[202:203], v[104:105], v[190:191], v[152:153] op_sel_hi:[1,0,1]
	v_cvt_pk_bf16_f32 v199, v200, v201
	v_mul_f32_e32 v161, 0xbfb8aa3b, v202
	v_exp_f32_e32 v161, v161
	s_nop 0
	v_add_f32_e32 v161, 1.0, v161
	v_rcp_f32_e32 v204, v161
	v_mul_f32_e32 v161, 0xbfb8aa3b, v203
	v_exp_f32_e32 v161, v161
	s_nop 0
	v_add_f32_e32 v161, 1.0, v161
	v_rcp_f32_e32 v205, v161
	s_nop 0
	v_pk_mul_f32 v[202:203], v[202:203], v[204:205]
	v_pk_fma_f32 v[204:205], v[106:107], v[190:191], v[154:155] op_sel_hi:[1,0,1]
	v_cvt_pk_bf16_f32 v200, v202, v203
	v_mul_f32_e32 v161, 0xbfb8aa3b, v204
	v_exp_f32_e32 v161, v161
	s_nop 0
	v_add_f32_e32 v161, 1.0, v161
	v_rcp_f32_e32 v206, v161
	v_mul_f32_e32 v161, 0xbfb8aa3b, v205
	v_exp_f32_e32 v161, v161
	s_nop 0
	v_add_f32_e32 v161, 1.0, v161
	v_rcp_f32_e32 v207, v161
	s_nop 0
	v_pk_mul_f32 v[204:205], v[204:205], v[206:207]
	s_nop 0
	v_cvt_pk_bf16_f32 v201, v204, v205
	global_store_dwordx4 v[196:197], v[198:201], off
	s_nop 1
	v_pk_fma_f32 v[198:199], v[100:101], v[190:191], v[148:149] op_sel_hi:[1,0,1]
	s_nop 0
	v_mul_f32_e32 v161, 0xbfb8aa3b, v198
	v_exp_f32_e32 v161, v161
	s_nop 0
	v_add_f32_e32 v161, 1.0, v161
	v_rcp_f32_e32 v200, v161
	v_mul_f32_e32 v161, 0xbfb8aa3b, v199
	v_exp_f32_e32 v161, v161
	s_nop 0
	v_add_f32_e32 v161, 1.0, v161
	v_rcp_f32_e32 v201, v161
	s_nop 0
	v_pk_mul_f32 v[198:199], v[198:199], v[200:201]
	v_pk_fma_f32 v[200:201], v[102:103], v[190:191], v[150:151] op_sel_hi:[1,0,1]
	v_cvt_pk_bf16_f32 v198, v198, v199
	v_mul_f32_e32 v161, 0xbfb8aa3b, v200
	v_exp_f32_e32 v161, v161
	s_nop 0
	v_add_f32_e32 v161, 1.0, v161
	v_rcp_f32_e32 v202, v161
	v_mul_f32_e32 v161, 0xbfb8aa3b, v201
	v_exp_f32_e32 v161, v161
	s_nop 0
	v_add_f32_e32 v161, 1.0, v161
	v_rcp_f32_e32 v203, v161
	s_nop 0
	v_pk_mul_f32 v[200:201], v[200:201], v[202:203]
	v_pk_fma_f32 v[202:203], v[96:97], v[190:191], v[144:145] op_sel_hi:[1,0,1]
	v_pk_fma_f32 v[190:191], v[98:99], v[190:191], v[146:147] op_sel_hi:[1,0,1]
	v_mul_f32_e32 v161, 0xbfb8aa3b, v202
	v_exp_f32_e32 v161, v161
	v_cvt_pk_bf16_f32 v199, v200, v201
	v_add_f32_e32 v161, 1.0, v161
	v_rcp_f32_e32 v204, v161
	v_mul_f32_e32 v161, 0xbfb8aa3b, v203
	v_exp_f32_e32 v161, v161
	s_nop 0
	v_add_f32_e32 v161, 1.0, v161
	v_rcp_f32_e32 v205, v161
	v_mul_f32_e32 v161, 0xbfb8aa3b, v190
	v_exp_f32_e32 v161, v161
	v_pk_mul_f32 v[202:203], v[202:203], v[204:205]
	s_nop 0
	v_cvt_pk_bf16_f32 v200, v202, v203
	v_add_f32_e32 v161, 1.0, v161
	v_rcp_f32_e32 v204, v161
	v_mul_f32_e32 v161, 0xbfb8aa3b, v191
	v_exp_f32_e32 v161, v161
	s_nop 0
	v_add_f32_e32 v161, 1.0, v161
	v_rcp_f32_e32 v205, v161
	s_nop 0
	v_pk_mul_f32 v[190:191], v[190:191], v[204:205]
	s_nop 0
	v_cvt_pk_bf16_f32 v201, v190, v191
	v_lshlrev_b64 v[190:191], 9, v[194:195]
	v_pk_fma_f32 v[194:195], v[92:93], v[192:193], v[156:157] op_sel_hi:[1,0,1]
	global_store_dwordx4 v[196:197], v[198:201], off offset:256
	v_mul_f32_e32 v161, 0xbfb8aa3b, v194
	v_exp_f32_e32 v161, v161
	v_lshl_add_u64 v[190:191], v[168:169], 0, v[190:191]
; DI u32x4 pack8(const float* v) { u32x4 w; w.x = pk2(v[0], v[1]); w.y = pk2(v[2], v[3]); w.z = pk2(v[4], v[5]); w.w = pk2(v[6], v[7]); return w; }
; DI float silu(float x) { return x * __builtin_amdgcn_rcpf(1.f + ex2(-x * LOG2E)); }
;     template <int PN> DI void body(AccRef acc, const Unit& u, int wr, int wc, int fr, int fq) const {
;     ...
;                 } else if constexpr (PN == 5 || PN == 6 || PN == 7) {
;                     bf16_t* dst = PN == 5 ? rv : (PN == 6 ? rg : sq);
; #pragma unroll
;                     for (int bj = 0; bj < 2; ++bj) {
;                         if constexpr (PN == 6) {
; #pragma unroll
;                             for (int j = 0; j < 8; ++j) v[bj][j] = silu(v[bj][j]);
;                         }
;                         if constexpr (PN == 7) {
; #pragma unroll
;                             for (int j = 0; j < 8; ++j) v[bj][j] *= 0.125f;
;                         }
;                         *(u32x4*)(dst + (size_t)row * 256 + bj * 128 + cl) = pack8(v[bj]);
;                     }
	v_pk_fma_f32 v[156:157], v[76:77], v[174:175], v[156:157] op_sel_hi:[1,0,1]
	v_add_f32_e32 v161, 1.0, v161
	v_rcp_f32_e32 v196, v161
	v_mul_f32_e32 v161, 0xbfb8aa3b, v195
	v_exp_f32_e32 v161, v161
	s_nop 0
	v_add_f32_e32 v161, 1.0, v161
	v_rcp_f32_e32 v197, v161
	s_nop 0
	v_pk_mul_f32 v[194:195], v[194:195], v[196:197]
	v_pk_fma_f32 v[196:197], v[94:95], v[192:193], v[158:159] op_sel_hi:[1,0,1]
	v_cvt_pk_bf16_f32 v194, v194, v195
	v_mul_f32_e32 v161, 0xbfb8aa3b, v196
	v_exp_f32_e32 v161, v161
	v_pk_fma_f32 v[158:159], v[78:79], v[174:175], v[158:159] op_sel_hi:[1,0,1]
	v_add_f32_e32 v161, 1.0, v161
	v_rcp_f32_e32 v198, v161
	v_mul_f32_e32 v161, 0xbfb8aa3b, v197
	v_exp_f32_e32 v161, v161
	s_nop 0
	v_add_f32_e32 v161, 1.0, v161
	v_rcp_f32_e32 v199, v161
	s_nop 0
	v_pk_mul_f32 v[196:197], v[196:197], v[198:199]
	v_pk_fma_f32 v[198:199], v[88:89], v[192:193], v[152:153] op_sel_hi:[1,0,1]
	v_cvt_pk_bf16_f32 v195, v196, v197
	v_mul_f32_e32 v161, 0xbfb8aa3b, v198
	v_exp_f32_e32 v161, v161
	v_pk_fma_f32 v[152:153], v[72:73], v[174:175], v[152:153] op_sel_hi:[1,0,1]
	v_add_f32_e32 v161, 1.0, v161
	v_rcp_f32_e32 v200, v161
	v_mul_f32_e32 v161, 0xbfb8aa3b, v199
	v_exp_f32_e32 v161, v161
	s_nop 0
	v_add_f32_e32 v161, 1.0, v161
	v_rcp_f32_e32 v201, v161
	s_nop 0
	v_pk_mul_f32 v[198:199], v[198:199], v[200:201]
	v_pk_fma_f32 v[200:201], v[90:91], v[192:193], v[154:155] op_sel_hi:[1,0,1]
	v_cvt_pk_bf16_f32 v196, v198, v199
	v_mul_f32_e32 v161, 0xbfb8aa3b, v200
	v_exp_f32_e32 v161, v161
	s_nop 0
	v_add_f32_e32 v161, 1.0, v161
	v_rcp_f32_e32 v202, v161
	v_mul_f32_e32 v161, 0xbfb8aa3b, v201
	v_exp_f32_e32 v161, v161
	s_nop 0
	v_add_f32_e32 v161, 1.0, v161
	v_rcp_f32_e32 v203, v161
	s_nop 0
	v_pk_mul_f32 v[200:201], v[200:201], v[202:203]
	s_nop 0
	v_cvt_pk_bf16_f32 v197, v200, v201
	global_store_dwordx4 v[190:191], v[194:197], off
	s_nop 1
	v_pk_fma_f32 v[194:195], v[84:85], v[192:193], v[148:149] op_sel_hi:[1,0,1]
	v_pk_fma_f32 v[148:149], v[68:69], v[174:175], v[148:149] op_sel_hi:[1,0,1]
	v_mul_f32_e32 v161, 0xbfb8aa3b, v194
	v_exp_f32_e32 v161, v161
	s_nop 0
	v_add_f32_e32 v161, 1.0, v161
	v_rcp_f32_e32 v196, v161
	v_mul_f32_e32 v161, 0xbfb8aa3b, v195
	v_exp_f32_e32 v161, v161
	s_nop 0
	v_add_f32_e32 v161, 1.0, v161
	v_rcp_f32_e32 v197, v161
	s_nop 0
	v_pk_mul_f32 v[194:195], v[194:195], v[196:197]
	v_pk_fma_f32 v[196:197], v[86:87], v[192:193], v[150:151] op_sel_hi:[1,0,1]
	v_pk_fma_f32 v[150:151], v[70:71], v[174:175], v[150:151] op_sel_hi:[1,0,1]
	v_mul_f32_e32 v161, 0xbfb8aa3b, v196
	v_exp_f32_e32 v161, v161
	s_nop 0
	v_add_f32_e32 v161, 1.0, v161
	v_rcp_f32_e32 v198, v161
	v_mul_f32_e32 v161, 0xbfb8aa3b, v197
	v_exp_f32_e32 v161, v161
	s_nop 0
	v_add_f32_e32 v161, 1.0, v161
	v_rcp_f32_e32 v199, v161
	s_nop 0
	v_pk_mul_f32 v[196:197], v[196:197], v[198:199]
	v_pk_fma_f32 v[198:199], v[80:81], v[192:193], v[144:145] op_sel_hi:[1,0,1]
	v_pk_fma_f32 v[192:193], v[82:83], v[192:193], v[146:147] op_sel_hi:[1,0,1]
	v_mul_f32_e32 v161, 0xbfb8aa3b, v198
	v_exp_f32_e32 v161, v161
	v_pk_fma_f32 v[144:145], v[64:65], v[174:175], v[144:145] op_sel_hi:[1,0,1]
	v_add_f32_e32 v161, 1.0, v161
	v_rcp_f32_e32 v200, v161
	v_mul_f32_e32 v161, 0xbfb8aa3b, v199
	v_exp_f32_e32 v161, v161
	s_nop 0
	v_add_f32_e32 v161, 1.0, v161
	v_rcp_f32_e32 v201, v161
	v_mul_f32_e32 v161, 0xbfb8aa3b, v192
	v_exp_f32_e32 v161, v161
	v_pk_mul_f32 v[198:199], v[198:199], v[200:201]
	v_add_f32_e32 v161, 1.0, v161
	v_rcp_f32_e32 v200, v161
	v_mul_f32_e32 v161, 0xbfb8aa3b, v193
	v_exp_f32_e32 v161, v161
	s_nop 0
	v_add_f32_e32 v161, 1.0, v161
	v_rcp_f32_e32 v201, v161
	v_mul_f32_e32 v161, 0xbfb8aa3b, v156
	v_exp_f32_e32 v161, v161
	v_pk_mul_f32 v[200:201], v[192:193], v[200:201]
	v_cvt_pk_bf16_f32 v192, v194, v195
	v_cvt_pk_bf16_f32 v193, v196, v197
	v_cvt_pk_bf16_f32 v194, v198, v199
	v_cvt_pk_bf16_f32 v195, v200, v201
	v_add_f32_e32 v161, 1.0, v161
	global_store_dwordx4 v[190:191], v[192:195], off offset:256
	v_rcp_f32_e32 v190, v161
	v_mul_f32_e32 v161, 0xbfb8aa3b, v157
	v_exp_f32_e32 v161, v161
	s_nop 0
	v_add_f32_e32 v161, 1.0, v161
	v_rcp_f32_e32 v191, v161
	v_mul_f32_e32 v161, 0xbfb8aa3b, v158
	v_exp_f32_e32 v161, v161
	v_pk_mul_f32 v[156:157], v[156:157], v[190:191]
	v_add_f32_e32 v161, 1.0, v161
	v_rcp_f32_e32 v190, v161
	v_mul_f32_e32 v161, 0xbfb8aa3b, v159
	v_exp_f32_e32 v161, v161
	s_nop 0
	v_add_f32_e32 v161, 1.0, v161
	v_rcp_f32_e32 v191, v161
	v_mul_f32_e32 v161, 0xbfb8aa3b, v152
	v_exp_f32_e32 v161, v161
	v_pk_mul_f32 v[158:159], v[158:159], v[190:191]
	v_add_f32_e32 v161, 1.0, v161
	v_rcp_f32_e32 v190, v161
	v_mul_f32_e32 v161, 0xbfb8aa3b, v153
	v_exp_f32_e32 v161, v161
	s_nop 0
	v_add_f32_e32 v161, 1.0, v161
	v_rcp_f32_e32 v191, v161
	s_nop 0
	v_pk_mul_f32 v[190:191], v[152:153], v[190:191]
	v_pk_fma_f32 v[152:153], v[74:75], v[174:175], v[154:155] op_sel_hi:[1,0,1]
	s_nop 0
	v_mul_f32_e32 v154, 0xbfb8aa3b, v152
	v_mul_f32_e32 v155, 0xbfb8aa3b, v153
	v_exp_f32_e32 v154, v154
	v_exp_f32_e32 v155, v155
	v_add_f32_e32 v154, 1.0, v154
	v_add_f32_e32 v155, 1.0, v155
	v_rcp_f32_e32 v154, v154
	v_rcp_f32_e32 v155, v155
	s_nop 0
	v_pk_mul_f32 v[192:193], v[152:153], v[154:155]
	v_cvt_pk_bf16_f32 v152, v156, v157
	v_cvt_pk_bf16_f32 v153, v158, v159
	v_cvt_pk_bf16_f32 v154, v190, v191
	v_cvt_pk_bf16_f32 v155, v192, v193
	global_store_dwordx4 v[188:189], v[152:155], off
	s_nop 1
	v_mul_f32_e32 v152, 0xbfb8aa3b, v148
	v_mul_f32_e32 v153, 0xbfb8aa3b, v149
	v_exp_f32_e32 v152, v152
	v_exp_f32_e32 v153, v153
	v_add_f32_e32 v152, 1.0, v152
	v_add_f32_e32 v153, 1.0, v153
	v_rcp_f32_e32 v152, v152
	v_rcp_f32_e32 v153, v153
	s_nop 0
	v_pk_mul_f32 v[148:149], v[148:149], v[152:153]
	v_mul_f32_e32 v152, 0xbfb8aa3b, v150
	v_mul_f32_e32 v153, 0xbfb8aa3b, v151
	v_exp_f32_e32 v152, v152
	v_exp_f32_e32 v153, v153
	v_add_f32_e32 v152, 1.0, v152
	v_add_f32_e32 v153, 1.0, v153
	v_rcp_f32_e32 v152, v152
	v_rcp_f32_e32 v153, v153
	s_nop 0
	v_pk_mul_f32 v[150:151], v[150:151], v[152:153]
	v_mul_f32_e32 v152, 0xbfb8aa3b, v144
	v_mul_f32_e32 v153, 0xbfb8aa3b, v145
	v_exp_f32_e32 v152, v152
	v_exp_f32_e32 v153, v153
	v_add_f32_e32 v152, 1.0, v152
	v_add_f32_e32 v153, 1.0, v153
	v_rcp_f32_e32 v152, v152
	v_rcp_f32_e32 v153, v153
	s_nop 0
	v_pk_mul_f32 v[152:153], v[144:145], v[152:153]
	v_pk_fma_f32 v[144:145], v[66:67], v[174:175], v[146:147] op_sel_hi:[1,0,1]
	s_nop 0
	v_mul_f32_e32 v146, 0xbfb8aa3b, v144
	v_mul_f32_e32 v147, 0xbfb8aa3b, v145
	v_exp_f32_e32 v146, v146
	v_exp_f32_e32 v147, v147
	v_add_f32_e32 v146, 1.0, v146
	v_add_f32_e32 v147, 1.0, v147
	v_rcp_f32_e32 v146, v146
	v_rcp_f32_e32 v147, v147
	s_nop 0
	v_pk_mul_f32 v[154:155], v[144:145], v[146:147]
	v_cvt_pk_bf16_f32 v144, v148, v149
	v_cvt_pk_bf16_f32 v145, v150, v151
	v_cvt_pk_bf16_f32 v146, v152, v153
	v_cvt_pk_bf16_f32 v147, v154, v155
	global_store_dwordx4 v[188:189], v[144:147], off offset:256
	s_waitcnt vmcnt(11)
; DI u32x4 pack8(const float* v) { u32x4 w; w.x = pk2(v[0], v[1]); w.y = pk2(v[2], v[3]); w.z = pk2(v[4], v[5]); w.w = pk2(v[6], v[7]); return w; }
; DI float silu(float x) { return x * __builtin_amdgcn_rcpf(1.f + ex2(-x * LOG2E)); }
;     template <int PN> DI void body(AccRef acc, const Unit& u, int wr, int wc, int fr, int fq) const {
;     ...
;                 } else if constexpr (PN == 5 || PN == 6 || PN == 7) {
;                     bf16_t* dst = PN == 5 ? rv : (PN == 6 ? rg : sq);
; #pragma unroll
;                     for (int bj = 0; bj < 2; ++bj) {
;                         if constexpr (PN == 6) {
; #pragma unroll
;                             for (int j = 0; j < 8; ++j) v[bj][j] = silu(v[bj][j]);
;                         }
;                         if constexpr (PN == 7) {
; #pragma unroll
;                             for (int j = 0; j < 8; ++j) v[bj][j] *= 0.125f;
;                         }
;                         *(u32x4*)(dst + (size_t)row * 256 + bj * 128 + cl) = pack8(v[bj]);
;                     }
	s_nop 0
	v_pk_fma_f32 v[146:147], v[60:61], v[170:171], v[140:141] op_sel_hi:[1,0,1]
	v_lshlrev_b64 v[144:145], 9, v[172:173]
	v_mul_f32_e32 v148, 0xbfb8aa3b, v146
	v_mul_f32_e32 v149, 0xbfb8aa3b, v147
	v_exp_f32_e32 v148, v148
	v_exp_f32_e32 v149, v149
	v_lshl_add_u64 v[144:145], v[168:169], 0, v[144:145]
	v_add_f32_e32 v148, 1.0, v148
	v_add_f32_e32 v149, 1.0, v149
	v_rcp_f32_e32 v148, v148
	v_rcp_f32_e32 v149, v149
	s_nop 0
	v_pk_mul_f32 v[146:147], v[146:147], v[148:149]
	v_pk_fma_f32 v[148:149], v[62:63], v[170:171], v[142:143] op_sel_hi:[1,0,1]
	v_cvt_pk_bf16_f32 v146, v146, v147
	v_mul_f32_e32 v150, 0xbfb8aa3b, v148
	v_mul_f32_e32 v151, 0xbfb8aa3b, v149
	v_exp_f32_e32 v150, v150
	v_exp_f32_e32 v151, v151
	v_add_f32_e32 v150, 1.0, v150
	v_add_f32_e32 v151, 1.0, v151
	v_rcp_f32_e32 v150, v150
	v_rcp_f32_e32 v151, v151
	s_nop 0
	v_pk_mul_f32 v[148:149], v[148:149], v[150:151]
	s_waitcnt vmcnt(10)
	v_pk_fma_f32 v[150:151], v[56:57], v[170:171], v[136:137] op_sel_hi:[1,0,1]
	v_cvt_pk_bf16_f32 v147, v148, v149
	v_mul_f32_e32 v152, 0xbfb8aa3b, v150
	v_mul_f32_e32 v153, 0xbfb8aa3b, v151
	v_exp_f32_e32 v152, v152
	v_exp_f32_e32 v153, v153
	v_add_f32_e32 v152, 1.0, v152
	v_add_f32_e32 v153, 1.0, v153
	v_rcp_f32_e32 v152, v152
	v_rcp_f32_e32 v153, v153
	s_nop 0
	v_pk_mul_f32 v[150:151], v[150:151], v[152:153]
	v_pk_fma_f32 v[152:153], v[58:59], v[170:171], v[138:139] op_sel_hi:[1,0,1]
	v_cvt_pk_bf16_f32 v148, v150, v151
	v_mul_f32_e32 v154, 0xbfb8aa3b, v152
	v_mul_f32_e32 v155, 0xbfb8aa3b, v153
	v_exp_f32_e32 v154, v154
	v_exp_f32_e32 v155, v155
	v_add_f32_e32 v154, 1.0, v154
	v_add_f32_e32 v155, 1.0, v155
	v_rcp_f32_e32 v154, v154
	v_rcp_f32_e32 v155, v155
	s_nop 0
	v_pk_mul_f32 v[152:153], v[152:153], v[154:155]
	s_nop 0
	v_cvt_pk_bf16_f32 v149, v152, v153
	global_store_dwordx4 v[144:145], v[146:149], off
	s_waitcnt vmcnt(9)
	s_nop 0
	v_pk_fma_f32 v[146:147], v[52:53], v[170:171], v[132:133] op_sel_hi:[1,0,1]
	s_nop 0
	v_mul_f32_e32 v148, 0xbfb8aa3b, v146
	v_mul_f32_e32 v149, 0xbfb8aa3b, v147
	v_exp_f32_e32 v148, v148
	v_exp_f32_e32 v149, v149
	v_add_f32_e32 v148, 1.0, v148
	v_add_f32_e32 v149, 1.0, v149
	v_rcp_f32_e32 v148, v148
	v_rcp_f32_e32 v149, v149
	s_nop 0
	v_pk_mul_f32 v[146:147], v[146:147], v[148:149]
	v_pk_fma_f32 v[148:149], v[54:55], v[170:171], v[134:135] op_sel_hi:[1,0,1]
	v_cvt_pk_bf16_f32 v146, v146, v147
	v_mul_f32_e32 v150, 0xbfb8aa3b, v148
	v_mul_f32_e32 v151, 0xbfb8aa3b, v149
	v_exp_f32_e32 v150, v150
	v_exp_f32_e32 v151, v151
	v_add_f32_e32 v150, 1.0, v150
	v_add_f32_e32 v151, 1.0, v151
	v_rcp_f32_e32 v150, v150
	v_rcp_f32_e32 v151, v151
	s_nop 0
	v_pk_mul_f32 v[148:149], v[148:149], v[150:151]
	v_pk_fma_f32 v[150:151], v[48:49], v[170:171], v[128:129] op_sel_hi:[1,0,1]
	v_cvt_pk_bf16_f32 v147, v148, v149
	v_mul_f32_e32 v152, 0xbfb8aa3b, v150
	v_mul_f32_e32 v153, 0xbfb8aa3b, v151
	v_exp_f32_e32 v152, v152
	v_exp_f32_e32 v153, v153
	v_add_f32_e32 v152, 1.0, v152
	v_add_f32_e32 v153, 1.0, v153
	v_rcp_f32_e32 v152, v152
	v_rcp_f32_e32 v153, v153
	s_nop 0
	v_pk_mul_f32 v[150:151], v[150:151], v[152:153]
	v_pk_fma_f32 v[152:153], v[50:51], v[170:171], v[130:131] op_sel_hi:[1,0,1]
	v_cvt_pk_bf16_f32 v148, v150, v151
	v_mul_f32_e32 v154, 0xbfb8aa3b, v152
	v_mul_f32_e32 v155, 0xbfb8aa3b, v153
	v_exp_f32_e32 v154, v154
	v_exp_f32_e32 v155, v155
	v_add_f32_e32 v154, 1.0, v154
	v_add_f32_e32 v155, 1.0, v155
	v_rcp_f32_e32 v154, v154
	v_rcp_f32_e32 v155, v155
	s_nop 0
	v_pk_mul_f32 v[152:153], v[152:153], v[154:155]
	s_nop 0
	v_cvt_pk_bf16_f32 v149, v152, v153
	global_store_dwordx4 v[144:145], v[146:149], off offset:256
	v_add_u32_e32 v144, 0x90, v160
	v_ashrrev_i32_e32 v145, 31, v144
	v_pk_fma_f32 v[146:147], v[44:45], v[164:165], v[140:141] op_sel_hi:[1,0,1]
	v_lshlrev_b64 v[144:145], 9, v[144:145]
	v_mul_f32_e32 v148, 0xbfb8aa3b, v146
	v_mul_f32_e32 v149, 0xbfb8aa3b, v147
	v_exp_f32_e32 v148, v148
	v_exp_f32_e32 v149, v149
	v_lshl_add_u64 v[144:145], v[168:169], 0, v[144:145]
	v_add_f32_e32 v148, 1.0, v148
	v_add_f32_e32 v149, 1.0, v149
	v_rcp_f32_e32 v148, v148
	v_rcp_f32_e32 v149, v149
	s_nop 0
	v_pk_mul_f32 v[146:147], v[146:147], v[148:149]
	v_pk_fma_f32 v[148:149], v[46:47], v[164:165], v[142:143] op_sel_hi:[1,0,1]
	v_cvt_pk_bf16_f32 v146, v146, v147
	v_mul_f32_e32 v150, 0xbfb8aa3b, v148
	v_mul_f32_e32 v151, 0xbfb8aa3b, v149
	v_exp_f32_e32 v150, v150
	v_exp_f32_e32 v151, v151
	v_add_f32_e32 v150, 1.0, v150
	v_add_f32_e32 v151, 1.0, v151
	v_rcp_f32_e32 v150, v150
	v_rcp_f32_e32 v151, v151
	s_nop 0
	v_pk_mul_f32 v[148:149], v[148:149], v[150:151]
	v_pk_fma_f32 v[150:151], v[40:41], v[164:165], v[136:137] op_sel_hi:[1,0,1]
	v_cvt_pk_bf16_f32 v147, v148, v149
	v_mul_f32_e32 v152, 0xbfb8aa3b, v150
	v_mul_f32_e32 v153, 0xbfb8aa3b, v151
	v_exp_f32_e32 v152, v152
	v_exp_f32_e32 v153, v153
	v_add_f32_e32 v152, 1.0, v152
	v_add_f32_e32 v153, 1.0, v153
	v_rcp_f32_e32 v152, v152
	v_rcp_f32_e32 v153, v153
	s_nop 0
	v_pk_mul_f32 v[150:151], v[150:151], v[152:153]
	v_pk_fma_f32 v[152:153], v[42:43], v[164:165], v[138:139] op_sel_hi:[1,0,1]
	v_cvt_pk_bf16_f32 v148, v150, v151
	v_mul_f32_e32 v154, 0xbfb8aa3b, v152
	v_mul_f32_e32 v155, 0xbfb8aa3b, v153
	v_exp_f32_e32 v154, v154
	v_exp_f32_e32 v155, v155
	v_add_f32_e32 v154, 1.0, v154
	v_add_f32_e32 v155, 1.0, v155
	v_rcp_f32_e32 v154, v154
	v_rcp_f32_e32 v155, v155
	s_nop 0
	v_pk_mul_f32 v[152:153], v[152:153], v[154:155]
	s_nop 0
	v_cvt_pk_bf16_f32 v149, v152, v153
	global_store_dwordx4 v[144:145], v[146:149], off
	s_nop 1
	v_pk_fma_f32 v[146:147], v[36:37], v[164:165], v[132:133] op_sel_hi:[1,0,1]
	s_nop 0
	v_mul_f32_e32 v148, 0xbfb8aa3b, v146
	v_mul_f32_e32 v149, 0xbfb8aa3b, v147
; DI u32x4 pack8(const float* v) { u32x4 w; w.x = pk2(v[0], v[1]); w.y = pk2(v[2], v[3]); w.z = pk2(v[4], v[5]); w.w = pk2(v[6], v[7]); return w; }
; DI float silu(float x) { return x * __builtin_amdgcn_rcpf(1.f + ex2(-x * LOG2E)); }
;     template <int PN> DI void body(AccRef acc, const Unit& u, int wr, int wc, int fr, int fq) const {
;     ...
;                 } else if constexpr (PN == 5 || PN == 6 || PN == 7) {
;                     bf16_t* dst = PN == 5 ? rv : (PN == 6 ? rg : sq);
; #pragma unroll
;                     for (int bj = 0; bj < 2; ++bj) {
;                         if constexpr (PN == 6) {
; #pragma unroll
;                             for (int j = 0; j < 8; ++j) v[bj][j] = silu(v[bj][j]);
;                         }
;                         if constexpr (PN == 7) {
; #pragma unroll
;                             for (int j = 0; j < 8; ++j) v[bj][j] *= 0.125f;
;                         }
;                         *(u32x4*)(dst + (size_t)row * 256 + bj * 128 + cl) = pack8(v[bj]);
;                     }
	v_exp_f32_e32 v148, v148
	v_exp_f32_e32 v149, v149
	v_add_f32_e32 v148, 1.0, v148
	v_add_f32_e32 v149, 1.0, v149
	v_rcp_f32_e32 v148, v148
	v_rcp_f32_e32 v149, v149
	s_nop 0
	v_pk_mul_f32 v[146:147], v[146:147], v[148:149]
	v_pk_fma_f32 v[148:149], v[38:39], v[164:165], v[134:135] op_sel_hi:[1,0,1]
	v_cvt_pk_bf16_f32 v146, v146, v147
	v_mul_f32_e32 v150, 0xbfb8aa3b, v148
	v_mul_f32_e32 v151, 0xbfb8aa3b, v149
	v_exp_f32_e32 v150, v150
	v_exp_f32_e32 v151, v151
	v_add_f32_e32 v150, 1.0, v150
	v_add_f32_e32 v151, 1.0, v151
	v_rcp_f32_e32 v150, v150
	v_rcp_f32_e32 v151, v151
	s_nop 0
	v_pk_mul_f32 v[148:149], v[148:149], v[150:151]
	v_pk_fma_f32 v[150:151], v[28:29], v[164:165], v[128:129] op_sel_hi:[1,0,1]
	v_cvt_pk_bf16_f32 v147, v148, v149
	v_mul_f32_e32 v152, 0xbfb8aa3b, v150
	v_mul_f32_e32 v153, 0xbfb8aa3b, v151
	v_exp_f32_e32 v152, v152
	v_exp_f32_e32 v153, v153
	v_add_f32_e32 v152, 1.0, v152
	v_add_f32_e32 v153, 1.0, v153
	v_rcp_f32_e32 v152, v152
	v_rcp_f32_e32 v153, v153
	s_nop 0
	v_pk_mul_f32 v[150:151], v[150:151], v[152:153]
	v_pk_fma_f32 v[152:153], v[30:31], v[164:165], v[130:131] op_sel_hi:[1,0,1]
	v_cvt_pk_bf16_f32 v148, v150, v151
	v_mul_f32_e32 v154, 0xbfb8aa3b, v152
	v_mul_f32_e32 v155, 0xbfb8aa3b, v153
	v_exp_f32_e32 v154, v154
	v_exp_f32_e32 v155, v155
	v_add_f32_e32 v154, 1.0, v154
	v_add_f32_e32 v155, 1.0, v155
	v_rcp_f32_e32 v154, v154
	v_rcp_f32_e32 v155, v155
	s_nop 0
	v_pk_mul_f32 v[152:153], v[152:153], v[154:155]
	s_nop 0
	v_cvt_pk_bf16_f32 v149, v152, v153
	global_store_dwordx4 v[144:145], v[146:149], off offset:256
	v_add_u32_e32 v144, 0xa0, v160
	v_ashrrev_i32_e32 v145, 31, v144
	v_pk_fma_f32 v[146:147], v[32:33], v[166:167], v[140:141] op_sel_hi:[1,0,1]
	v_lshlrev_b64 v[144:145], 9, v[144:145]
	v_mul_f32_e32 v148, 0xbfb8aa3b, v146
	v_mul_f32_e32 v149, 0xbfb8aa3b, v147
	v_exp_f32_e32 v148, v148
	v_exp_f32_e32 v149, v149
	v_lshl_add_u64 v[144:145], v[168:169], 0, v[144:145]
	v_pk_fma_f32 v[140:141], v[12:13], v[162:163], v[140:141] op_sel_hi:[1,0,1]
	v_add_f32_e32 v148, 1.0, v148
	v_add_f32_e32 v149, 1.0, v149
	v_rcp_f32_e32 v148, v148
	v_rcp_f32_e32 v149, v149
	s_nop 0
	v_pk_mul_f32 v[146:147], v[146:147], v[148:149]
	v_pk_fma_f32 v[148:149], v[34:35], v[166:167], v[142:143] op_sel_hi:[1,0,1]
	v_cvt_pk_bf16_f32 v146, v146, v147
	v_mul_f32_e32 v150, 0xbfb8aa3b, v148
	v_mul_f32_e32 v151, 0xbfb8aa3b, v149
	v_exp_f32_e32 v150, v150
	v_exp_f32_e32 v151, v151
	v_pk_fma_f32 v[142:143], v[14:15], v[162:163], v[142:143] op_sel_hi:[1,0,1]
	v_add_f32_e32 v150, 1.0, v150
	v_add_f32_e32 v151, 1.0, v151
	v_rcp_f32_e32 v150, v150
	v_rcp_f32_e32 v151, v151
	s_nop 0
	v_pk_mul_f32 v[148:149], v[148:149], v[150:151]
	v_pk_fma_f32 v[150:151], v[24:25], v[166:167], v[136:137] op_sel_hi:[1,0,1]
	v_cvt_pk_bf16_f32 v147, v148, v149
	v_mul_f32_e32 v152, 0xbfb8aa3b, v150
	v_mul_f32_e32 v153, 0xbfb8aa3b, v151
	v_exp_f32_e32 v152, v152
	v_exp_f32_e32 v153, v153
	v_pk_fma_f32 v[136:137], v[8:9], v[162:163], v[136:137] op_sel_hi:[1,0,1]
	v_add_f32_e32 v152, 1.0, v152
	v_add_f32_e32 v153, 1.0, v153
	v_rcp_f32_e32 v152, v152
	v_rcp_f32_e32 v153, v153
	s_nop 0
	v_pk_mul_f32 v[150:151], v[150:151], v[152:153]
	v_pk_fma_f32 v[152:153], v[26:27], v[166:167], v[138:139] op_sel_hi:[1,0,1]
	v_cvt_pk_bf16_f32 v148, v150, v151
	v_mul_f32_e32 v154, 0xbfb8aa3b, v152
	v_mul_f32_e32 v155, 0xbfb8aa3b, v153
	v_exp_f32_e32 v154, v154
	v_exp_f32_e32 v155, v155
	v_add_f32_e32 v154, 1.0, v154
	v_add_f32_e32 v155, 1.0, v155
	v_rcp_f32_e32 v154, v154
	v_rcp_f32_e32 v155, v155
	s_nop 0
	v_pk_mul_f32 v[152:153], v[152:153], v[154:155]
	s_nop 0
	v_cvt_pk_bf16_f32 v149, v152, v153
	global_store_dwordx4 v[144:145], v[146:149], off
	s_nop 1
	v_pk_fma_f32 v[146:147], v[20:21], v[166:167], v[132:133] op_sel_hi:[1,0,1]
	v_pk_fma_f32 v[132:133], v[4:5], v[162:163], v[132:133] op_sel_hi:[1,0,1]
	v_mul_f32_e32 v148, 0xbfb8aa3b, v146
	v_mul_f32_e32 v149, 0xbfb8aa3b, v147
	v_exp_f32_e32 v148, v148
	v_exp_f32_e32 v149, v149
	v_add_f32_e32 v148, 1.0, v148
	v_add_f32_e32 v149, 1.0, v149
	v_rcp_f32_e32 v148, v148
	v_rcp_f32_e32 v149, v149
	s_nop 0
	v_pk_mul_f32 v[146:147], v[146:147], v[148:149]
	v_pk_fma_f32 v[148:149], v[22:23], v[166:167], v[134:135] op_sel_hi:[1,0,1]
	v_cvt_pk_bf16_f32 v146, v146, v147
	v_mul_f32_e32 v150, 0xbfb8aa3b, v148
	v_mul_f32_e32 v151, 0xbfb8aa3b, v149
	v_exp_f32_e32 v150, v150
	v_exp_f32_e32 v151, v151
; DI u32x4 pack8(const float* v) { u32x4 w; w.x = pk2(v[0], v[1]); w.y = pk2(v[2], v[3]); w.z = pk2(v[4], v[5]); w.w = pk2(v[6], v[7]); return w; }
; DI float silu(float x) { return x * __builtin_amdgcn_rcpf(1.f + ex2(-x * LOG2E)); }
;     template <int PN> DI void body(AccRef acc, const Unit& u, int wr, int wc, int fr, int fq) const {
;     ...
;                 } else if constexpr (PN == 5 || PN == 6 || PN == 7) {
;                     bf16_t* dst = PN == 5 ? rv : (PN == 6 ? rg : sq);
; #pragma unroll
;                     for (int bj = 0; bj < 2; ++bj) {
;                         if constexpr (PN == 6) {
; #pragma unroll
;                             for (int j = 0; j < 8; ++j) v[bj][j] = silu(v[bj][j]);
;                         }
;                         if constexpr (PN == 7) {
; #pragma unroll
;                             for (int j = 0; j < 8; ++j) v[bj][j] *= 0.125f;
;                         }
;                         *(u32x4*)(dst + (size_t)row * 256 + bj * 128 + cl) = pack8(v[bj]);
;                     }
	v_pk_fma_f32 v[134:135], v[6:7], v[162:163], v[134:135] op_sel_hi:[1,0,1]
	v_add_f32_e32 v150, 1.0, v150
	v_add_f32_e32 v151, 1.0, v151
	v_rcp_f32_e32 v150, v150
	v_rcp_f32_e32 v151, v151
	s_nop 0
	v_pk_mul_f32 v[148:149], v[148:149], v[150:151]
	v_pk_fma_f32 v[150:151], v[16:17], v[166:167], v[128:129] op_sel_hi:[1,0,1]
	v_cvt_pk_bf16_f32 v147, v148, v149
	v_mul_f32_e32 v152, 0xbfb8aa3b, v150
	v_mul_f32_e32 v153, 0xbfb8aa3b, v151
	v_exp_f32_e32 v152, v152
	v_exp_f32_e32 v153, v153
	v_pk_fma_f32 v[128:129], v[0:1], v[162:163], v[128:129] op_sel_hi:[1,0,1]
	v_add_f32_e32 v152, 1.0, v152
	v_add_f32_e32 v153, 1.0, v153
	v_rcp_f32_e32 v152, v152
	v_rcp_f32_e32 v153, v153
	s_nop 0
	v_pk_mul_f32 v[150:151], v[150:151], v[152:153]
	v_pk_fma_f32 v[152:153], v[18:19], v[166:167], v[130:131] op_sel_hi:[1,0,1]
	v_cvt_pk_bf16_f32 v148, v150, v151
	v_mul_f32_e32 v154, 0xbfb8aa3b, v152
	v_mul_f32_e32 v155, 0xbfb8aa3b, v153
	v_exp_f32_e32 v154, v154
	v_exp_f32_e32 v155, v155
	v_add_f32_e32 v154, 1.0, v154
	v_add_f32_e32 v155, 1.0, v155
	v_rcp_f32_e32 v154, v154
	v_rcp_f32_e32 v155, v155
	s_nop 0
	v_pk_mul_f32 v[152:153], v[152:153], v[154:155]
	s_nop 0
	v_cvt_pk_bf16_f32 v149, v152, v153
	global_store_dwordx4 v[144:145], v[146:149], off offset:256
	v_add_u32_e32 v144, 0xb0, v160
	v_ashrrev_i32_e32 v145, 31, v144
	v_mul_f32_e32 v146, 0xbfb8aa3b, v140
	v_mul_f32_e32 v147, 0xbfb8aa3b, v141
	v_exp_f32_e32 v146, v146
	v_exp_f32_e32 v147, v147
	v_lshlrev_b64 v[144:145], 9, v[144:145]
	v_lshl_add_u64 v[144:145], v[168:169], 0, v[144:145]
	v_add_f32_e32 v146, 1.0, v146
	v_add_f32_e32 v147, 1.0, v147
	v_rcp_f32_e32 v146, v146
	v_rcp_f32_e32 v147, v147
	s_nop 0
	v_pk_mul_f32 v[140:141], v[140:141], v[146:147]
	v_mul_f32_e32 v146, 0xbfb8aa3b, v142
	v_mul_f32_e32 v147, 0xbfb8aa3b, v143
	v_exp_f32_e32 v146, v146
	v_exp_f32_e32 v147, v147
	v_add_f32_e32 v146, 1.0, v146
	v_add_f32_e32 v147, 1.0, v147
	v_rcp_f32_e32 v146, v146
	v_rcp_f32_e32 v147, v147
	s_nop 0
	v_pk_mul_f32 v[142:143], v[142:143], v[146:147]
	v_mul_f32_e32 v146, 0xbfb8aa3b, v136
	v_mul_f32_e32 v147, 0xbfb8aa3b, v137
	v_exp_f32_e32 v146, v146
	v_exp_f32_e32 v147, v147
	v_add_f32_e32 v146, 1.0, v146
	v_add_f32_e32 v147, 1.0, v147
	v_rcp_f32_e32 v146, v146
	v_rcp_f32_e32 v147, v147
	s_nop 0
	v_pk_mul_f32 v[146:147], v[136:137], v[146:147]
	v_pk_fma_f32 v[136:137], v[10:11], v[162:163], v[138:139] op_sel_hi:[1,0,1]
	s_nop 0
	v_mul_f32_e32 v138, 0xbfb8aa3b, v136
	v_mul_f32_e32 v139, 0xbfb8aa3b, v137
	v_exp_f32_e32 v138, v138
	v_exp_f32_e32 v139, v139
	v_add_f32_e32 v138, 1.0, v138
	v_add_f32_e32 v139, 1.0, v139
	v_rcp_f32_e32 v138, v138
	v_rcp_f32_e32 v139, v139
	s_nop 0
	v_pk_mul_f32 v[148:149], v[136:137], v[138:139]
	v_cvt_pk_bf16_f32 v136, v140, v141
	v_cvt_pk_bf16_f32 v137, v142, v143
	v_cvt_pk_bf16_f32 v138, v146, v147
	v_cvt_pk_bf16_f32 v139, v148, v149
	global_store_dwordx4 v[144:145], v[136:139], off
	s_nop 1
	v_mul_f32_e32 v136, 0xbfb8aa3b, v132
	v_mul_f32_e32 v137, 0xbfb8aa3b, v133
	v_exp_f32_e32 v136, v136
	v_exp_f32_e32 v137, v137
	v_add_f32_e32 v136, 1.0, v136
	v_add_f32_e32 v137, 1.0, v137
	v_rcp_f32_e32 v136, v136
	v_rcp_f32_e32 v137, v137
	s_nop 0
	v_pk_mul_f32 v[132:133], v[132:133], v[136:137]
	v_mul_f32_e32 v136, 0xbfb8aa3b, v134
	v_mul_f32_e32 v137, 0xbfb8aa3b, v135
	v_exp_f32_e32 v136, v136
	v_exp_f32_e32 v137, v137
	v_add_f32_e32 v136, 1.0, v136
	v_add_f32_e32 v137, 1.0, v137
	v_rcp_f32_e32 v136, v136
	v_rcp_f32_e32 v137, v137
	s_nop 0
	v_pk_mul_f32 v[134:135], v[134:135], v[136:137]
	v_mul_f32_e32 v136, 0xbfb8aa3b, v128
	v_mul_f32_e32 v137, 0xbfb8aa3b, v129
	v_exp_f32_e32 v136, v136
	v_exp_f32_e32 v137, v137
	v_add_f32_e32 v136, 1.0, v136
	v_add_f32_e32 v137, 1.0, v137
	v_rcp_f32_e32 v136, v136
	v_rcp_f32_e32 v137, v137
	s_nop 0
	v_pk_mul_f32 v[136:137], v[128:129], v[136:137]
	v_pk_fma_f32 v[128:129], v[2:3], v[162:163], v[130:131] op_sel_hi:[1,0,1]
	s_nop 0
	v_mul_f32_e32 v130, 0xbfb8aa3b, v128
	v_mul_f32_e32 v131, 0xbfb8aa3b, v129
	v_exp_f32_e32 v130, v130
	v_exp_f32_e32 v131, v131
	v_add_f32_e32 v130, 1.0, v130
	v_add_f32_e32 v131, 1.0, v131
	v_rcp_f32_e32 v130, v130
	v_rcp_f32_e32 v131, v131
	s_nop 0
	v_pk_mul_f32 v[138:139], v[128:129], v[130:131]
	v_cvt_pk_bf16_f32 v128, v132, v133
	v_cvt_pk_bf16_f32 v129, v134, v135
	v_cvt_pk_bf16_f32 v130, v136, v137
	v_cvt_pk_bf16_f32 v131, v138, v139
	global_store_dwordx4 v[144:145], v[128:131], off offset:256

; DI float sum16(const float* p) { const f32x4* q = (const f32x4*)p; f32x4 a = q[0], b = q[1], c = q[2], d = q[3]; f32x4 s = (a + b) + (c + d); return (s[0] + s[1]) + (s[2] + s[3]); }
;     template <int PN> DI void body(AccRef acc, const Unit& u, int wr, int wc, int fr, int fq) const {
;     ...
;         for (int ai = 0; ai < 2; ++ai) {
;             const int rb_ = u.pm * 256 + ai * 128 + wr * 64 + fr;
; #pragma unroll
;             for (int m = 0; m < 4; ++m) rinvh[ai][m] = rsqrtf(sum16(ssq + (size_t)(rb_ + 16 * m + zdep) * 16) * (1.f / 1024.f) + EPS);
;             asm volatile("v_mov_b32 %0, 0" : "=v"(zdep) : "v"(rinvh[ai][0]), "v"(rinvh[ai][1]), "v"(rinvh[ai][2]), "v"(rinvh[ai][3]));
;         }
; #pragma unroll
;         for (int ai = 0; ai < 2; ++ai) {
;             const int rb_ = u.pm * 256 + ai * 128 + wr * 64 + fr;
;             int mb_, p_, k_; row_info(rb_, mb_, p_, k_);
; #pragma unroll
;             for (int bj = 0; bj < 2; ++bj)
; #pragma unroll
;                 for (int n = 0; n < 2; ++n) cvh[ai][bj][n] = *(const f32x4*)(cv + (size_t)(mb_ + zdep) * NIN + PN * 256 + bj * 128 + cl + 4 * n);
;         }
; #pragma unroll
;         for (int ai = 0; ai < 2; ++ai) {
;             const int rb = u.pm * 256 + ai * 128 + wr * 64 + fr;
;             int mb, pos0, kv0; row_info(rb, mb, pos0, kv0);
; #pragma unroll
;             for (int m = 0; m < 4; ++m) {
;                 const int row = rb + 16 * m, pos = pos0 + 16 * m, kvrow = kv0 + 16 * m;
;                 const float rinv = rinvh[ai][m];
;                 float v[2][8];
; #pragma unroll
;                 for (int bj = 0; bj < 2; ++bj)
; #pragma unroll
;                     for (int n = 0; n < 2; ++n)
; #pragma unroll
;                         for (int j = 0; j < 4; ++j) v[bj][4 * n + j] = acc[ai][bj][m][n][j] * rinv + cvh[ai][bj][n][j];
.LBB0_1907:
	s_and_b64 vcc, exec, s[2:3]
	s_cbranch_vccz .LBB0_1912
	s_cmp_gt_i32 s66, 4
	s_mov_b64 s[2:3], -1
	s_cbranch_scc0 .LBB0_1910
	s_lshl_b32 s2, s43, 6
	s_lshl_b32 s3, s34, 8
	s_add_i32 s2, s2, s3
	v_add_u32_e32 v160, s2, v214
	v_ashrrev_i32_e32 v161, 31, v160
	v_lshlrev_b64 v[128:129], 6, v[160:161]
	v_lshl_add_u64 v[140:141], s[70:71], 0, v[128:129]
	s_nop 0
	v_add_u32_e32 v166, 16, v160
	v_ashrrev_i32_e32 v167, 31, v166
	s_mov_b32 s2, 0x358637bd
	s_mov_b32 s4, 0x3a800000
	v_add_u32_e32 v162, 32, v160
	v_ashrrev_i32_e32 v163, 31, v162
	v_add_u32_e32 v164, 48, v160
	v_ashrrev_i32_e32 v165, 31, v164
	v_add_u32_e32 v174, 0x80, v160
	s_mov_b64 s[6:7], 0x125400
	v_lshlrev_b64 v[222:223], 9, v[160:161]
	v_ashrrev_i32_e32 v175, 31, v174
	s_nop 0
	v_lshlrev_b64 v[128:129], 6, v[166:167]
	v_lshl_add_u64 v[140:141], s[70:71], 0, v[128:129]
	s_nop 0
	v_lshlrev_b64 v[166:167], 9, v[166:167]
	s_nop 0
	v_mov_b64_e32 v[128:129], s[2:3]
	s_nop 0
	s_nop 0
	s_nop 0
	v_mov_b32_e32 v170, v244
	s_nop 0
	v_mov_b32_e32 v168, v245
	v_lshlrev_b64 v[130:131], 6, v[162:163]
	v_lshl_add_u64 v[142:143], s[70:71], 0, v[130:131]
	s_nop 0
	v_lshlrev_b64 v[162:163], 9, v[162:163]
	s_nop 0
	v_lshlrev_b64 v[130:131], 6, v[164:165]
	v_lshl_add_u64 v[142:143], s[70:71], 0, v[130:131]
	s_nop 0
	s_nop 0
	s_nop 0
	s_nop 0
	s_nop 0
	s_nop 0
	v_mov_b32_e32 v172, v246
	s_nop 0
	v_mov_b32_e32 v188, v247
	v_mov_b32 v130, 0
	s_nop 0
	v_add_u32_e32 v130, v130, v174
	v_ashrrev_i32_e32 v131, 31, v130
	v_lshlrev_b64 v[132:133], 6, v[130:131]
	v_lshl_add_u64 v[144:145], s[70:71], 0, v[132:133]
	s_nop 0
	s_nop 0
	v_add_u32_e32 v132, 16, v130
	v_ashrrev_i32_e32 v133, 31, v132
	v_lshlrev_b64 v[132:133], 6, v[132:133]
	v_lshl_add_u64 v[144:145], s[70:71], 0, v[132:133]
	s_nop 0
	s_nop 0
	s_nop 0
	s_nop 0
	s_nop 0
	s_nop 0
	v_mov_b32_e32 v192, v248
	s_nop 0
	v_mov_b32_e32 v190, v249
	v_add_u32_e32 v132, 32, v130
	v_ashrrev_i32_e32 v133, 31, v132
	v_lshlrev_b64 v[132:133], 6, v[132:133]
	v_lshl_add_u64 v[144:145], s[70:71], 0, v[132:133]
	s_nop 0
	v_add_u32_e32 v130, 48, v130
	v_ashrrev_i32_e32 v131, 31, v130
	v_lshlrev_b64 v[130:131], 6, v[130:131]
	v_lshl_add_u64 v[142:143], s[70:71], 0, v[130:131]
	s_nop 0
	s_nop 0
	s_nop 0
	s_movk_i32 s4, 0x2800
	s_mov_b32 s5, 0x125000
	s_nop 0
	v_mov_b32_e32 v194, v250
	s_lshl_b32 s2, s60, 5
	v_lshl_add_u32 v198, v213, 3, s2
	v_ashrrev_i32_e32 v199, 31, v198
	v_mov_b32_e32 v196, v251
	v_add_u32_e32 v129, 0xffffc000, v160
	v_lshrrev_b32_e32 v129, 6, v129
	v_cmp_gt_i32_e32 vcc, s94, v160
	v_ashrrev_i32_e32 v128, 11, v160
	v_add_u32_e32 v129, 8, v129
	v_cndmask_b32_e32 v128, v129, v128, vcc
	v_mov_b32 v136, 0
	v_lshlrev_b64 v[132:133], 2, v[198:199]
	v_add_u32_e32 v130, v136, v128
	v_mov_b64_e32 v[128:129], s[74:75]
	v_mad_i64_i32 v[130:131], s[2:3], v130, s4, v[128:129]
	v_lshl_add_u64 v[130:131], v[130:131], 0, v[132:133]
	v_lshl_add_u64 v[134:135], v[130:131], 0, s[6:7]
	v_add_co_u32_e32 v130, vcc, s5, v130
	s_nop 1
	v_addc_co_u32_e32 v131, vcc, 0, v131, vcc
	global_load_dwordx4 v[148:151], v[130:131], off offset:1024
	global_load_dwordx4 v[152:155], v[134:135], off offset:16
	global_load_dwordx4 v[144:147], v[134:135], off offset:528
	global_load_dwordx4 v[156:159], v[134:135], off offset:512
	v_add_u32_e32 v131, 0xffffc080, v160
	v_lshrrev_b32_e32 v131, 6, v131
	v_cmp_gt_i32_e32 vcc, s94, v174
	v_ashrrev_i32_e32 v130, 11, v174
	v_add_u32_e32 v131, 8, v131
	v_cndmask_b32_e32 v130, v131, v130, vcc
	v_add_u32_e32 v130, v136, v130
	v_mad_i64_i32 v[128:129], s[2:3], v130, s4, v[128:129]
	v_lshl_add_u64 v[128:129], v[128:129], 0, v[132:133]
	v_lshl_add_u64 v[132:133], v[128:129], 0, s[6:7]
	v_add_co_u32_e32 v128, vcc, s5, v128
	v_readlane_b32 s2, v254, 42
	s_nop 0
	v_addc_co_u32_e32 v129, vcc, 0, v129, vcc
	global_load_dwordx4 v[140:143], v[128:129], off offset:1024
	global_load_dwordx4 v[136:139], v[132:133], off offset:16
	s_nop 0
	global_load_dwordx4 v[128:131], v[132:133], off offset:528
	s_nop 0
	global_load_dwordx4 v[132:135], v[132:133], off offset:512
	v_readlane_b32 s3, v254, 43
	s_waitcnt vmcnt(7)
	v_pk_fma_f32 v[200:201], v[124:125], v[170:171], v[148:149] op_sel_hi:[1,0,1]
	v_lshl_add_u64 v[198:199], v[198:199], 1, s[2:3]
	v_pk_fma_f32 v[202:203], v[126:127], v[170:171], v[150:151] op_sel_hi:[1,0,1]
	s_waitcnt vmcnt(6)
	v_pk_fma_f32 v[204:205], v[120:121], v[170:171], v[152:153] op_sel_hi:[1,0,1]
	v_pk_fma_f32 v[206:207], v[122:123], v[170:171], v[154:155] op_sel_hi:[1,0,1]
	s_waitcnt vmcnt(4)
; DI u32x4 pack8(const float* v) { u32x4 w; w.x = pk2(v[0], v[1]); w.y = pk2(v[2], v[3]); w.z = pk2(v[4], v[5]); w.w = pk2(v[6], v[7]); return w; }
; DI float silu(float x) { return x * __builtin_amdgcn_rcpf(1.f + ex2(-x * LOG2E)); }
;     template <int PN> DI void body(AccRef acc, const Unit& u, int wr, int wc, int fr, int fq) const {
;     ...
;         for (int ai = 0; ai < 2; ++ai) {
;             const int rb = u.pm * 256 + ai * 128 + wr * 64 + fr;
;             int mb, pos0, kv0; row_info(rb, mb, pos0, kv0);
; #pragma unroll
;             for (int m = 0; m < 4; ++m) {
;                 const int row = rb + 16 * m, pos = pos0 + 16 * m, kvrow = kv0 + 16 * m;
;                 const float rinv = rinvh[ai][m];
;                 float v[2][8];
; #pragma unroll
;                 for (int bj = 0; bj < 2; ++bj)
; #pragma unroll
;                     for (int n = 0; n < 2; ++n)
; #pragma unroll
;                         for (int j = 0; j < 4; ++j) v[bj][4 * n + j] = acc[ai][bj][m][n][j] * rinv + cvh[ai][bj][n][j];
;     ...
;                 } else if constexpr (PN == 5 || PN == 6 || PN == 7) {
;                     bf16_t* dst = PN == 5 ? rv : (PN == 6 ? rg : sq);
; #pragma unroll
;                     for (int bj = 0; bj < 2; ++bj) {
;                         if constexpr (PN == 6) {
; #pragma unroll
;                             for (int j = 0; j < 8; ++j) v[bj][j] = silu(v[bj][j]);
;                         }
;                         if constexpr (PN == 7) {
; #pragma unroll
;                             for (int j = 0; j < 8; ++j) v[bj][j] *= 0.125f;
;                         }
;                         *(u32x4*)(dst + (size_t)row * 256 + bj * 128 + cl) = pack8(v[bj]);
;                     }
	v_pk_fma_f32 v[216:217], v[116:117], v[170:171], v[156:157] op_sel_hi:[1,0,1]
	v_pk_fma_f32 v[218:219], v[118:119], v[170:171], v[158:159] op_sel_hi:[1,0,1]
	v_pk_fma_f32 v[220:221], v[112:113], v[170:171], v[144:145] op_sel_hi:[1,0,1]
	v_pk_fma_f32 v[170:171], v[114:115], v[170:171], v[146:147] op_sel_hi:[1,0,1]
	v_lshl_add_u64 v[222:223], v[198:199], 0, v[222:223]
	v_cvt_pk_bf16_f32 v200, v200, v201
	v_cvt_pk_bf16_f32 v201, v202, v203
	v_cvt_pk_bf16_f32 v202, v204, v205
	v_cvt_pk_bf16_f32 v203, v206, v207
	global_store_dwordx4 v[222:223], v[200:203], off
	v_pk_fma_f32 v[204:205], v[110:111], v[168:169], v[150:151] op_sel_hi:[1,0,1]
	v_pk_fma_f32 v[206:207], v[104:105], v[168:169], v[152:153] op_sel_hi:[1,0,1]
	v_cvt_pk_bf16_f32 v200, v216, v217
	v_cvt_pk_bf16_f32 v201, v218, v219
	v_cvt_pk_bf16_f32 v202, v220, v221
	v_cvt_pk_bf16_f32 v203, v170, v171
	global_store_dwordx4 v[222:223], v[200:203], off offset:256
	v_pk_fma_f32 v[216:217], v[106:107], v[168:169], v[154:155] op_sel_hi:[1,0,1]
	v_pk_fma_f32 v[218:219], v[100:101], v[168:169], v[156:157] op_sel_hi:[1,0,1]
	v_pk_fma_f32 v[202:203], v[108:109], v[168:169], v[148:149] op_sel_hi:[1,0,1]
	v_pk_fma_f32 v[200:201], v[102:103], v[168:169], v[158:159] op_sel_hi:[1,0,1]
	v_pk_fma_f32 v[170:171], v[96:97], v[168:169], v[144:145] op_sel_hi:[1,0,1]
	v_pk_fma_f32 v[168:169], v[98:99], v[168:169], v[146:147] op_sel_hi:[1,0,1]
	v_lshl_add_u64 v[166:167], v[198:199], 0, v[166:167]
	v_cvt_pk_bf16_f32 v202, v202, v203
	v_cvt_pk_bf16_f32 v203, v204, v205
	v_cvt_pk_bf16_f32 v204, v206, v207
	v_cvt_pk_bf16_f32 v205, v216, v217
	global_store_dwordx4 v[166:167], v[202:205], off
	v_pk_fma_f32 v[206:207], v[80:81], v[172:173], v[144:145] op_sel_hi:[1,0,1]
	v_lshl_add_u64 v[162:163], v[198:199], 0, v[162:163]
	v_cvt_pk_bf16_f32 v202, v218, v219
	v_cvt_pk_bf16_f32 v203, v200, v201
	v_cvt_pk_bf16_f32 v204, v170, v171
	v_cvt_pk_bf16_f32 v205, v168, v169
	global_store_dwordx4 v[166:167], v[202:205], off offset:256
	v_pk_fma_f32 v[166:167], v[92:93], v[172:173], v[148:149] op_sel_hi:[1,0,1]
	v_pk_fma_f32 v[168:169], v[94:95], v[172:173], v[150:151] op_sel_hi:[1,0,1]
	v_pk_fma_f32 v[170:171], v[88:89], v[172:173], v[152:153] op_sel_hi:[1,0,1]
	v_pk_fma_f32 v[200:201], v[90:91], v[172:173], v[154:155] op_sel_hi:[1,0,1]
	v_pk_fma_f32 v[202:203], v[84:85], v[172:173], v[156:157] op_sel_hi:[1,0,1]
	v_pk_fma_f32 v[204:205], v[86:87], v[172:173], v[158:159] op_sel_hi:[1,0,1]
	v_pk_fma_f32 v[172:173], v[82:83], v[172:173], v[146:147] op_sel_hi:[1,0,1]
	v_cvt_pk_bf16_f32 v166, v166, v167
	v_cvt_pk_bf16_f32 v167, v168, v169
	v_cvt_pk_bf16_f32 v168, v170, v171
	v_cvt_pk_bf16_f32 v169, v200, v201
	global_store_dwordx4 v[162:163], v[166:169], off
	v_pk_fma_f32 v[148:149], v[76:77], v[188:189], v[148:149] op_sel_hi:[1,0,1]
	v_pk_fma_f32 v[150:151], v[78:79], v[188:189], v[150:151] op_sel_hi:[1,0,1]
	v_cvt_pk_bf16_f32 v166, v202, v203
	v_cvt_pk_bf16_f32 v167, v204, v205
	v_cvt_pk_bf16_f32 v168, v206, v207
	v_cvt_pk_bf16_f32 v169, v172, v173
	global_store_dwordx4 v[162:163], v[166:169], off offset:256
	v_pk_fma_f32 v[152:153], v[72:73], v[188:189], v[152:153] op_sel_hi:[1,0,1]
	v_pk_fma_f32 v[154:155], v[74:75], v[188:189], v[154:155] op_sel_hi:[1,0,1]
	v_pk_fma_f32 v[162:163], v[64:65], v[188:189], v[144:145] op_sel_hi:[1,0,1]
	v_lshlrev_b64 v[144:145], 9, v[164:165]
	v_pk_fma_f32 v[156:157], v[68:69], v[188:189], v[156:157] op_sel_hi:[1,0,1]
	v_pk_fma_f32 v[158:159], v[70:71], v[188:189], v[158:159] op_sel_hi:[1,0,1]
	v_pk_fma_f32 v[166:167], v[66:67], v[188:189], v[146:147] op_sel_hi:[1,0,1]
	v_lshl_add_u64 v[164:165], v[198:199], 0, v[144:145]
	v_cvt_pk_bf16_f32 v144, v148, v149
	v_cvt_pk_bf16_f32 v145, v150, v151
	v_cvt_pk_bf16_f32 v146, v152, v153
	v_cvt_pk_bf16_f32 v147, v154, v155
	global_store_dwordx4 v[164:165], v[144:147], off
	s_waitcnt vmcnt(9)
	v_pk_fma_f32 v[148:149], v[56:57], v[192:193], v[136:137] op_sel_hi:[1,0,1]
	v_pk_fma_f32 v[150:151], v[58:59], v[192:193], v[138:139] op_sel_hi:[1,0,1]
	v_cvt_pk_bf16_f32 v144, v156, v157
	v_cvt_pk_bf16_f32 v145, v158, v159
	v_cvt_pk_bf16_f32 v146, v162, v163
	v_cvt_pk_bf16_f32 v147, v166, v167
	global_store_dwordx4 v[164:165], v[144:147], off offset:256
	v_lshlrev_b64 v[162:163], 9, v[174:175]
	s_waitcnt vmcnt(8)
; DI u32x4 pack8(const float* v) { u32x4 w; w.x = pk2(v[0], v[1]); w.y = pk2(v[2], v[3]); w.z = pk2(v[4], v[5]); w.w = pk2(v[6], v[7]); return w; }
; DI float silu(float x) { return x * __builtin_amdgcn_rcpf(1.f + ex2(-x * LOG2E)); }
;     template <int PN> DI void body(AccRef acc, const Unit& u, int wr, int wc, int fr, int fq) const {
;     ...
;         for (int ai = 0; ai < 2; ++ai) {
;             const int rb = u.pm * 256 + ai * 128 + wr * 64 + fr;
;             int mb, pos0, kv0; row_info(rb, mb, pos0, kv0);
; #pragma unroll
;             for (int m = 0; m < 4; ++m) {
;                 const int row = rb + 16 * m, pos = pos0 + 16 * m, kvrow = kv0 + 16 * m;
;                 const float rinv = rinvh[ai][m];
;                 float v[2][8];
; #pragma unroll
;                 for (int bj = 0; bj < 2; ++bj)
; #pragma unroll
;                     for (int n = 0; n < 2; ++n)
; #pragma unroll
;                         for (int j = 0; j < 4; ++j) v[bj][4 * n + j] = acc[ai][bj][m][n][j] * rinv + cvh[ai][bj][n][j];
;     ...
;                 } else if constexpr (PN == 5 || PN == 6 || PN == 7) {
;                     bf16_t* dst = PN == 5 ? rv : (PN == 6 ? rg : sq);
; #pragma unroll
;                     for (int bj = 0; bj < 2; ++bj) {
;                         if constexpr (PN == 6) {
; #pragma unroll
;                             for (int j = 0; j < 8; ++j) v[bj][j] = silu(v[bj][j]);
;                         }
;                         if constexpr (PN == 7) {
; #pragma unroll
;                             for (int j = 0; j < 8; ++j) v[bj][j] *= 0.125f;
;                         }
;                         *(u32x4*)(dst + (size_t)row * 256 + bj * 128 + cl) = pack8(v[bj]);
;                     }
	v_pk_fma_f32 v[152:153], v[52:53], v[192:193], v[132:133] op_sel_hi:[1,0,1]
	v_pk_fma_f32 v[144:145], v[60:61], v[192:193], v[140:141] op_sel_hi:[1,0,1]
	v_pk_fma_f32 v[146:147], v[62:63], v[192:193], v[142:143] op_sel_hi:[1,0,1]
	v_pk_fma_f32 v[154:155], v[54:55], v[192:193], v[134:135] op_sel_hi:[1,0,1]
	v_pk_fma_f32 v[156:157], v[48:49], v[192:193], v[128:129] op_sel_hi:[1,0,1]
	v_pk_fma_f32 v[158:159], v[50:51], v[192:193], v[130:131] op_sel_hi:[1,0,1]
	v_lshl_add_u64 v[162:163], v[198:199], 0, v[162:163]
	v_cvt_pk_bf16_f32 v144, v144, v145
	v_cvt_pk_bf16_f32 v145, v146, v147
	v_cvt_pk_bf16_f32 v146, v148, v149
	v_cvt_pk_bf16_f32 v147, v150, v151
	global_store_dwordx4 v[162:163], v[144:147], off
	v_pk_fma_f32 v[148:149], v[40:41], v[190:191], v[136:137] op_sel_hi:[1,0,1]
	v_pk_fma_f32 v[150:151], v[42:43], v[190:191], v[138:139] op_sel_hi:[1,0,1]
	v_cvt_pk_bf16_f32 v144, v152, v153
	v_cvt_pk_bf16_f32 v145, v154, v155
	v_cvt_pk_bf16_f32 v146, v156, v157
	v_cvt_pk_bf16_f32 v147, v158, v159
	global_store_dwordx4 v[162:163], v[144:147], off offset:256
	v_add_u32_e32 v162, 0x90, v160
	v_ashrrev_i32_e32 v163, 31, v162
	v_pk_fma_f32 v[144:145], v[44:45], v[190:191], v[140:141] op_sel_hi:[1,0,1]
	v_pk_fma_f32 v[146:147], v[46:47], v[190:191], v[142:143] op_sel_hi:[1,0,1]
	v_lshlrev_b64 v[162:163], 9, v[162:163]
	v_pk_fma_f32 v[152:153], v[36:37], v[190:191], v[132:133] op_sel_hi:[1,0,1]
	v_pk_fma_f32 v[154:155], v[38:39], v[190:191], v[134:135] op_sel_hi:[1,0,1]
	v_pk_fma_f32 v[156:157], v[28:29], v[190:191], v[128:129] op_sel_hi:[1,0,1]
	v_pk_fma_f32 v[158:159], v[30:31], v[190:191], v[130:131] op_sel_hi:[1,0,1]
	v_lshl_add_u64 v[162:163], v[198:199], 0, v[162:163]
	v_cvt_pk_bf16_f32 v144, v144, v145
	v_cvt_pk_bf16_f32 v145, v146, v147
	v_cvt_pk_bf16_f32 v146, v148, v149
	v_cvt_pk_bf16_f32 v147, v150, v151
	global_store_dwordx4 v[162:163], v[144:147], off
	v_pk_fma_f32 v[148:149], v[24:25], v[194:195], v[136:137] op_sel_hi:[1,0,1]
	v_pk_fma_f32 v[150:151], v[26:27], v[194:195], v[138:139] op_sel_hi:[1,0,1]
	v_cvt_pk_bf16_f32 v144, v152, v153
	v_cvt_pk_bf16_f32 v145, v154, v155
	v_cvt_pk_bf16_f32 v146, v156, v157
	v_cvt_pk_bf16_f32 v147, v158, v159
	global_store_dwordx4 v[162:163], v[144:147], off offset:256
	v_add_u32_e32 v162, 0xa0, v160
	v_ashrrev_i32_e32 v163, 31, v162
	v_pk_fma_f32 v[144:145], v[32:33], v[194:195], v[140:141] op_sel_hi:[1,0,1]
	v_pk_fma_f32 v[146:147], v[34:35], v[194:195], v[142:143] op_sel_hi:[1,0,1]
	v_lshlrev_b64 v[162:163], 9, v[162:163]
	v_pk_fma_f32 v[152:153], v[20:21], v[194:195], v[132:133] op_sel_hi:[1,0,1]
	v_pk_fma_f32 v[154:155], v[22:23], v[194:195], v[134:135] op_sel_hi:[1,0,1]
	v_pk_fma_f32 v[156:157], v[16:17], v[194:195], v[128:129] op_sel_hi:[1,0,1]
	v_pk_fma_f32 v[158:159], v[18:19], v[194:195], v[130:131] op_sel_hi:[1,0,1]
	v_lshl_add_u64 v[162:163], v[198:199], 0, v[162:163]
	v_cvt_pk_bf16_f32 v144, v144, v145
	v_cvt_pk_bf16_f32 v145, v146, v147
	v_cvt_pk_bf16_f32 v146, v148, v149
	v_cvt_pk_bf16_f32 v147, v150, v151
	global_store_dwordx4 v[162:163], v[144:147], off
	v_pk_fma_f32 v[140:141], v[12:13], v[196:197], v[140:141] op_sel_hi:[1,0,1]
	v_pk_fma_f32 v[142:143], v[14:15], v[196:197], v[142:143] op_sel_hi:[1,0,1]
	v_cvt_pk_bf16_f32 v144, v152, v153
	v_cvt_pk_bf16_f32 v145, v154, v155
	v_cvt_pk_bf16_f32 v146, v156, v157
	v_cvt_pk_bf16_f32 v147, v158, v159
	global_store_dwordx4 v[162:163], v[144:147], off offset:256
	v_pk_fma_f32 v[136:137], v[8:9], v[196:197], v[136:137] op_sel_hi:[1,0,1]
	v_pk_fma_f32 v[138:139], v[10:11], v[196:197], v[138:139] op_sel_hi:[1,0,1]
	v_pk_fma_f32 v[144:145], v[0:1], v[196:197], v[128:129] op_sel_hi:[1,0,1]
	v_add_u32_e32 v128, 0xb0, v160
	v_ashrrev_i32_e32 v129, 31, v128
	v_lshlrev_b64 v[128:129], 9, v[128:129]
	v_pk_fma_f32 v[132:133], v[4:5], v[196:197], v[132:133] op_sel_hi:[1,0,1]
	v_pk_fma_f32 v[134:135], v[6:7], v[196:197], v[134:135] op_sel_hi:[1,0,1]
	v_pk_fma_f32 v[146:147], v[2:3], v[196:197], v[130:131] op_sel_hi:[1,0,1]
	v_lshl_add_u64 v[148:149], v[198:199], 0, v[128:129]
	v_cvt_pk_bf16_f32 v128, v140, v141
	v_cvt_pk_bf16_f32 v129, v142, v143
	v_cvt_pk_bf16_f32 v130, v136, v137
	v_cvt_pk_bf16_f32 v131, v138, v139
	global_store_dwordx4 v[148:149], v[128:131], off
	s_mov_b64 s[2:3], 0
	s_nop 0
	v_cvt_pk_bf16_f32 v128, v132, v133
	v_cvt_pk_bf16_f32 v129, v134, v135
	v_cvt_pk_bf16_f32 v130, v144, v145
	v_cvt_pk_bf16_f32 v131, v146, v147
	global_store_dwordx4 v[148:149], v[128:131], off offset:256
; DI float ex2(float x) { return __builtin_amdgcn_exp2f(x); }
;     template <int PN> DI void body(AccRef acc, const Unit& u, int wr, int wc, int fr, int fq) const {
;     ...
;         for (int ai = 0; ai < 2; ++ai) {
;             const int rb_ = u.pm * 256 + ai * 128 + wr * 64 + fr;
; #pragma unroll
;             for (int m = 0; m < 4; ++m) rinvh[ai][m] = rsqrtf(sum16(ssq + (size_t)(rb_ + 16 * m + zdep) * 16) * (1.f / 1024.f) + EPS);
;             asm volatile("v_mov_b32 %0, 0" : "=v"(zdep) : "v"(rinvh[ai][0]), "v"(rinvh[ai][1]), "v"(rinvh[ai][2]), "v"(rinvh[ai][3]));
;         }
; #pragma unroll
;         for (int ai = 0; ai < 2; ++ai) {
;             const int rb_ = u.pm * 256 + ai * 128 + wr * 64 + fr;
;             int mb_, p_, k_; row_info(rb_, mb_, p_, k_);
; #pragma unroll
;             for (int bj = 0; bj < 2; ++bj)
; #pragma unroll
;                 for (int n = 0; n < 2; ++n) cvh[ai][bj][n] = *(const f32x4*)(cv + (size_t)(mb_ + zdep) * NIN + PN * 256 + bj * 128 + cl + 4 * n);
;         }
; #pragma unroll
;         for (int ai = 0; ai < 2; ++ai) {
;             const int rb = u.pm * 256 + ai * 128 + wr * 64 + fr;
;             int mb, pos0, kv0; row_info(rb, mb, pos0, kv0);
; #pragma unroll
;             for (int m = 0; m < 4; ++m) {
;                 const int row = rb + 16 * m, pos = pos0 + 16 * m, kvrow = kv0 + 16 * m;
;                 const float rinv = rinvh[ai][m];
;                 float v[2][8];
; #pragma unroll
;                 for (int bj = 0; bj < 2; ++bj)
; #pragma unroll
;                     for (int n = 0; n < 2; ++n)
; #pragma unroll
;                         for (int j = 0; j < 4; ++j) v[bj][4 * n + j] = acc[ai][bj][m][n][j] * rinv + cvh[ai][bj][n][j];
;     ...
;                 } else if constexpr (PN == 3 || PN == 4) {
;                     bf16_t* dst = PN == 3 ? rq : rk;
;                     const float sc = PN == 3 ? 0.125f : 1.f;
; #pragma unroll
;                     for (int bj = 0; bj < 2; ++bj) {
;                         const int head = 2 * bj + (wc >> 1), i0 = 16 * (wc & 1) + 4 * fq;
;                         float o1[4], o2[4];
; #pragma unroll
;                         for (int j = 0; j < 4; ++j) { float sn, cs; sincos_rev((float)pos * ex2(-(float)(i0 + j) * KEXP64), sn, cs);
;                             o1[j] = (v[bj][j] * cs - v[bj][4 + j] * sn) * sc; o2[j] = (v[bj][j] * sn + v[bj][4 + j] * cs) * sc; }
.LBB0_1910:
	s_andn2_b64 vcc, exec, s[2:3]
	s_cbranch_vccnz .LBB0_1912
	s_lshl_b32 s2, s43, 6
	s_lshl_b32 s3, s34, 8
	s_add_i32 s2, s2, s3
	v_add_u32_e32 v160, s2, v214
	v_add_u32_e32 v164, 16, v160
	v_ashrrev_i32_e32 v161, 31, v160
	v_ashrrev_i32_e32 v165, 31, v164
	v_lshlrev_b64 v[128:129], 6, v[160:161]
	v_lshlrev_b64 v[144:145], 6, v[164:165]
	v_add_u32_e32 v166, 32, v160
	v_lshl_add_u64 v[140:141], s[70:71], 0, v[128:129]
	v_lshl_add_u64 v[144:145], s[70:71], 0, v[144:145]
	v_ashrrev_i32_e32 v167, 31, v166
	s_nop 0
	s_nop 0
	v_lshlrev_b64 v[144:145], 6, v[166:167]
	v_add_u32_e32 v162, 48, v160
	v_lshl_add_u64 v[144:145], s[70:71], 0, v[144:145]
	v_ashrrev_i32_e32 v163, 31, v162
	v_lshlrev_b64 v[144:145], 6, v[162:163]
	v_lshl_add_u64 v[144:145], s[70:71], 0, v[144:145]
	s_mov_b32 s2, 0x358637bd
	v_mov_b64_e32 v[144:145], s[2:3]
	s_mov_b32 s12, 0x3a800000
	s_mov_b64 s[16:17], 0x125000
	v_readlane_b32 s22, v254, 44
	v_readlane_b32 s23, v254, 45
	v_lshlrev_b64 v[164:165], 9, v[164:165]
	v_lshlrev_b64 v[162:163], 9, v[162:163]
	v_lshl_add_u64 v[164:165], s[22:23], 0, v[164:165]
	v_lshl_add_u64 v[162:163], s[22:23], 0, v[162:163]
	v_mov_b32_e32 v190, v245
	v_mov_b32_e32 v174, v246
	v_add_u32_e32 v168, 0x80, v160
	v_mov_b32_e32 v194, v244
	v_mov_b32_e32 v170, v247
	v_mov_b32 v128, 0
	s_lshl_b32 s6, s60, 5
	v_add_u32_e32 v158, v128, v168
	v_add_u32_e32 v146, 16, v158
	v_ashrrev_i32_e32 v159, 31, v158
	v_ashrrev_i32_e32 v147, 31, v146
	v_lshlrev_b64 v[128:129], 6, v[158:159]
	v_lshlrev_b64 v[146:147], 6, v[146:147]
	v_lshl_add_u64 v[140:141], s[70:71], 0, v[128:129]
	v_lshl_add_u64 v[172:173], s[70:71], 0, v[146:147]
	s_nop 0
	s_nop 0
	v_add_u32_e32 v172, 32, v158
	v_ashrrev_i32_e32 v173, 31, v172
	v_add_u32_e32 v158, 48, v158
	v_lshlrev_b64 v[172:173], 6, v[172:173]
	v_ashrrev_i32_e32 v159, 31, v158
	v_lshl_add_u64 v[172:173], s[70:71], 0, v[172:173]
	v_lshlrev_b64 v[158:159], 6, v[158:159]
	v_lshl_add_u64 v[158:159], s[70:71], 0, v[158:159]
	s_movk_i32 s7, 0x2800
	v_mov_b32_e32 v196, v248
	v_mov_b32_e32 v192, v249
	v_mov_b32_e32 v188, v250
	v_mov_b32_e32 v172, v251
	v_add_u32_e32 v129, 0xffffc000, v160
	v_lshrrev_b32_e32 v129, 6, v129
	v_ashrrev_i32_e32 v128, 11, v160
	v_add_u32_e32 v129, 8, v129
	v_cmp_gt_i32_e64 s[2:3], s94, v160
	v_lshl_add_u32 v130, v213, 3, s6
	v_mov_b32 v136, 0
	v_ashrrev_i32_e32 v131, 31, v130
	v_cndmask_b32_e64 v128, v129, v128, s[2:3]
	v_add_u32_e32 v132, v136, v128
	v_mov_b64_e32 v[128:129], s[74:75]
	v_mad_i64_i32 v[132:133], s[4:5], v132, s7, v[128:129]
	v_lshlrev_b64 v[130:131], 2, v[130:131]
	v_lshl_add_u64 v[132:133], v[132:133], 0, v[130:131]
	s_mov_b32 s12, 0x125000
	v_lshl_add_u64 v[134:135], v[132:133], 0, s[16:17]
	v_add_co_u32_e32 v132, vcc, s12, v132
	s_lshl_b32 s4, s60, 4
	s_nop 0
	v_addc_co_u32_e32 v133, vcc, 0, v133, vcc
	global_load_dwordx4 v[144:147], v[132:133], off
	global_load_dwordx4 v[148:151], v[134:135], off offset:16
	global_load_dwordx4 v[156:159], v[134:135], off offset:512
	global_load_dwordx4 v[152:155], v[134:135], off offset:528
	s_and_b32 s5, s4, 16
	v_lshl_add_u32 v198, v213, 2, s5
	v_cvt_f32_i32_e32 v138, v198
	v_or_b32_e32 v139, 1, v198
	v_mov_b32_e32 v132, 0x400
	v_cvt_f32_i32_e32 v139, v139
	v_and_or_b32 v169, v214, 63, v132
	v_add_u32_e32 v132, 0xffffc080, v160
	v_and_b32_e32 v137, 0x7ff, v160
	v_lshrrev_b32_e32 v140, 6, v132
	v_lshlrev_b64 v[132:133], 9, v[160:161]
	v_or_b32_e32 v134, 2, v198
	v_lshl_add_u64 v[200:201], s[22:23], 0, v[132:133]
	v_cndmask_b32_e64 v189, v169, v137, s[2:3]
	v_mul_f32_e32 v133, 0xbed49a78, v138
	v_cvt_f32_i32_e32 v134, v134
	v_cvt_f32_u32_e32 v191, v189
	v_exp_f32_e32 v161, v133
	v_mul_f32_e32 v133, 0xbed49a78, v139
	v_or_b32_e32 v175, 3, v198
	v_exp_f32_e32 v173, v133
	v_cvt_f32_i32_e32 v175, v175
	v_mul_f32_e32 v134, 0xbed49a78, v134
	v_mul_f32_e32 v133, v161, v191
	v_exp_f32_e32 v171, v134
	v_mul_f32_e32 v133, 0.15915494, v133
	v_mul_f32_e32 v134, v173, v191
	v_mul_f32_e32 v175, 0xbed49a78, v175
	v_fract_f32_e32 v133, v133
	v_mul_f32_e32 v134, 0.15915494, v134
	v_exp_f32_e32 v175, v175
	v_sin_f32_e32 v202, v133
	v_cos_f32_e32 v204, v133
	v_fract_f32_e32 v133, v134
	v_sin_f32_e32 v203, v133
	v_cos_f32_e32 v205, v133
	v_ashrrev_i32_e32 v135, 11, v168
	v_add_u32_e32 v140, 8, v140
	v_cmp_gt_i32_e32 vcc, s94, v168
	v_mul_f32_e32 v193, v171, v191
	v_mul_f32_e32 v191, v175, v191
	v_cndmask_b32_e32 v132, v140, v135, vcc
	v_mul_f32_e32 v193, 0.15915494, v193
	v_mul_f32_e32 v191, 0.15915494, v191
	v_add_u32_e32 v132, v136, v132
	v_fract_f32_e32 v193, v193
	v_fract_f32_e32 v191, v191
	v_mad_i64_i32 v[128:129], s[2:3], v132, s7, v[128:129]
	v_cos_f32_e32 v220, v193
	v_cos_f32_e32 v221, v191
	v_lshl_add_u64 v[128:129], v[128:129], 0, v[130:131]
	s_and_b32 s4, s6, 0xffffffc0
	v_lshl_add_u64 v[132:133], v[128:129], 0, s[16:17]
	v_add_co_u32_e64 v128, s[2:3], s12, v128
	s_ashr_i32 s5, s4, 31
	s_nop 0
	v_addc_co_u32_e64 v129, s[2:3], 0, v129, s[2:3]
	v_ashrrev_i32_e32 v199, 31, v198
	s_lshl_b64 s[2:3], s[4:5], 1
	v_lshl_add_u64 v[200:201], v[200:201], 0, s[2:3]
	v_lshlrev_b64 v[198:199], 1, v[198:199]
	v_lshl_add_u64 v[200:201], v[200:201], 0, v[198:199]
	global_load_dwordx4 v[140:143], v[128:129], off
	s_nop 0
	global_load_dwordx4 v[128:131], v[132:133], off offset:528
	global_load_dwordx4 v[136:139], v[132:133], off offset:16
	s_nop 0
	global_load_dwordx4 v[132:135], v[132:133], off offset:512
	v_lshl_add_u64 v[164:165], v[164:165], 0, s[2:3]
	v_lshl_add_u64 v[164:165], v[164:165], 0, v[198:199]
	s_waitcnt vmcnt(7)
	v_pk_fma_f32 v[206:207], v[124:125], v[194:195], v[144:145] op_sel_hi:[1,0,1]
	s_waitcnt vmcnt(6)
; DI u32x2 pack4(const float* v) { u32x2 w; w.x = pk2(v[0], v[1]); w.y = pk2(v[2], v[3]); return w; }
; DI float ex2(float x) { return __builtin_amdgcn_exp2f(x); }
; DI void sincos_rev(float ang, float& s, float& c) { float rev = ang * 0.15915494309189535f; rev = __builtin_amdgcn_fractf(rev); s = __builtin_amdgcn_sinf(rev); c = __builtin_amdgcn_cosf(rev); }
;     template <int PN> DI void body(AccRef acc, const Unit& u, int wr, int wc, int fr, int fq) const {
;     ...
;                 } else if constexpr (PN == 3 || PN == 4) {
;                     bf16_t* dst = PN == 3 ? rq : rk;
;                     const float sc = PN == 3 ? 0.125f : 1.f;
; #pragma unroll
;                     for (int bj = 0; bj < 2; ++bj) {
;                         const int head = 2 * bj + (wc >> 1), i0 = 16 * (wc & 1) + 4 * fq;
;                         float o1[4], o2[4];
; #pragma unroll
;                         for (int j = 0; j < 4; ++j) { float sn, cs; sincos_rev((float)pos * ex2(-(float)(i0 + j) * KEXP64), sn, cs);
;                             o1[j] = (v[bj][j] * cs - v[bj][4 + j] * sn) * sc; o2[j] = (v[bj][j] * sn + v[bj][4 + j] * cs) * sc; }
;                         *(u32x2*)(dst + (size_t)row * 256 + head * 64 + i0) = pack4(o1);
;                         *(u32x2*)(dst + (size_t)row * 256 + head * 64 + 32 + i0) = pack4(o2);
;                     }
	v_pk_fma_f32 v[216:217], v[120:121], v[194:195], v[148:149] op_sel_hi:[1,0,1]
	v_pk_fma_f32 v[228:229], v[122:123], v[194:195], v[150:151] op_sel_hi:[1,0,1]
	v_pk_mul_f32 v[218:219], v[204:205], v[216:217]
	v_pk_mul_f32 v[216:217], v[202:203], v[216:217]
	v_pk_fma_f32 v[218:219], v[202:203], v[206:207], v[218:219]
	v_pk_fma_f32 v[206:207], v[204:205], v[206:207], v[216:217] neg_lo:[0,0,1] neg_hi:[0,0,1]
	v_sin_f32_e32 v216, v193
	v_sin_f32_e32 v217, v191
	v_pk_fma_f32 v[222:223], v[126:127], v[194:195], v[146:147] op_sel_hi:[1,0,1]
	v_pk_mul_f32 v[230:231], v[220:221], v[228:229]
	v_cvt_pk_bf16_f32 v206, v206, v207
	v_pk_mul_f32 v[228:229], v[216:217], v[228:229]
	v_pk_fma_f32 v[230:231], v[216:217], v[222:223], v[230:231]
	v_pk_fma_f32 v[222:223], v[220:221], v[222:223], v[228:229] neg_lo:[0,0,1] neg_hi:[0,0,1]
	v_add_u32_e32 v191, 16, v189
	v_cvt_pk_bf16_f32 v207, v222, v223
	global_store_dwordx2 v[200:201], v[206:207], off
	v_cvt_pk_bf16_f32 v206, v218, v219
	v_cvt_pk_bf16_f32 v207, v230, v231
	s_waitcnt vmcnt(5)
	v_pk_fma_f32 v[218:219], v[112:113], v[194:195], v[152:153] op_sel_hi:[1,0,1]
	v_cvt_f32_u32_e32 v191, v191
	global_store_dwordx2 v[200:201], v[206:207], off offset:64
	v_pk_fma_f32 v[206:207], v[116:117], v[194:195], v[156:157] op_sel_hi:[1,0,1]
	v_pk_mul_f32 v[222:223], v[204:205], v[218:219]
	v_mul_f32_e32 v193, v161, v191
	v_pk_fma_f32 v[222:223], v[202:203], v[206:207], v[222:223]
	v_pk_mul_f32 v[202:203], v[202:203], v[218:219]
	v_mul_f32_e32 v193, 0.15915494, v193
	v_pk_fma_f32 v[202:203], v[204:205], v[206:207], v[202:203] neg_lo:[0,0,1] neg_hi:[0,0,1]
	v_pk_fma_f32 v[204:205], v[118:119], v[194:195], v[158:159] op_sel_hi:[1,0,1]
	v_pk_fma_f32 v[194:195], v[114:115], v[194:195], v[154:155] op_sel_hi:[1,0,1]
	v_cvt_pk_bf16_f32 v202, v202, v203
	v_pk_mul_f32 v[206:207], v[220:221], v[194:195]
	v_pk_mul_f32 v[194:195], v[216:217], v[194:195]
	v_pk_fma_f32 v[206:207], v[216:217], v[204:205], v[206:207]
	v_pk_fma_f32 v[194:195], v[220:221], v[204:205], v[194:195] neg_lo:[0,0,1] neg_hi:[0,0,1]
	v_fract_f32_e32 v193, v193
	v_cvt_pk_bf16_f32 v203, v194, v195
	v_cvt_pk_bf16_f32 v194, v222, v223
	v_cvt_pk_bf16_f32 v195, v206, v207
	global_store_dwordx2 v[200:201], v[202:203], off offset:256
	global_store_dwordx2 v[200:201], v[194:195], off offset:320
	v_sin_f32_e32 v194, v193
	v_cos_f32_e32 v200, v193
	v_mul_f32_e32 v193, v173, v191
	v_mul_f32_e32 v193, 0.15915494, v193
	v_fract_f32_e32 v193, v193
	v_cos_f32_e32 v201, v193
	v_sin_f32_e32 v195, v193
	v_pk_fma_f32 v[202:203], v[108:109], v[190:191], v[144:145] op_sel_hi:[1,0,1]
	v_pk_fma_f32 v[204:205], v[104:105], v[190:191], v[148:149] op_sel_hi:[1,0,1]
	v_mul_f32_e32 v193, v171, v191
	v_mul_f32_e32 v191, v175, v191
	v_mul_f32_e32 v193, 0.15915494, v193
	v_mul_f32_e32 v191, 0.15915494, v191
	v_pk_mul_f32 v[206:207], v[200:201], v[204:205]
	v_pk_mul_f32 v[204:205], v[194:195], v[204:205]
	v_fract_f32_e32 v193, v193
	v_fract_f32_e32 v191, v191
	v_pk_fma_f32 v[206:207], v[194:195], v[202:203], v[206:207]
	v_pk_fma_f32 v[202:203], v[200:201], v[202:203], v[204:205] neg_lo:[0,0,1] neg_hi:[0,0,1]
	v_sin_f32_e32 v204, v193
	v_cos_f32_e32 v216, v193
	v_cos_f32_e32 v217, v191
	v_sin_f32_e32 v205, v191
	v_pk_fma_f32 v[220:221], v[106:107], v[190:191], v[150:151] op_sel_hi:[1,0,1]
	v_pk_fma_f32 v[218:219], v[110:111], v[190:191], v[146:147] op_sel_hi:[1,0,1]
	v_pk_mul_f32 v[222:223], v[216:217], v[220:221]
	v_pk_mul_f32 v[220:221], v[204:205], v[220:221]
	v_pk_fma_f32 v[222:223], v[204:205], v[218:219], v[222:223]
	v_pk_fma_f32 v[218:219], v[216:217], v[218:219], v[220:221] neg_lo:[0,0,1] neg_hi:[0,0,1]
	v_cvt_pk_bf16_f32 v202, v202, v203
	v_cvt_pk_bf16_f32 v203, v218, v219
	global_store_dwordx2 v[164:165], v[202:203], off
	v_cvt_pk_bf16_f32 v202, v206, v207
	v_cvt_pk_bf16_f32 v203, v222, v223
	v_pk_fma_f32 v[206:207], v[96:97], v[190:191], v[152:153] op_sel_hi:[1,0,1]
	global_store_dwordx2 v[164:165], v[202:203], off offset:64
	v_pk_fma_f32 v[202:203], v[100:101], v[190:191], v[156:157] op_sel_hi:[1,0,1]
	v_pk_mul_f32 v[218:219], v[200:201], v[206:207]
	v_add_u32_e32 v193, 32, v189
	v_pk_fma_f32 v[218:219], v[194:195], v[202:203], v[218:219]
	v_pk_mul_f32 v[194:195], v[194:195], v[206:207]
	v_cvt_f32_u32_e32 v193, v193
	v_pk_fma_f32 v[194:195], v[200:201], v[202:203], v[194:195] neg_lo:[0,0,1] neg_hi:[0,0,1]
	v_pk_fma_f32 v[200:201], v[102:103], v[190:191], v[158:159] op_sel_hi:[1,0,1]
	v_pk_fma_f32 v[190:191], v[98:99], v[190:191], v[154:155] op_sel_hi:[1,0,1]
	v_cvt_pk_bf16_f32 v194, v194, v195
	v_pk_mul_f32 v[202:203], v[216:217], v[190:191]
	v_pk_mul_f32 v[190:191], v[204:205], v[190:191]
	v_pk_fma_f32 v[202:203], v[204:205], v[200:201], v[202:203]
	v_pk_fma_f32 v[190:191], v[216:217], v[200:201], v[190:191] neg_lo:[0,0,1] neg_hi:[0,0,1]
	v_mul_f32_e32 v197, v171, v193
	v_cvt_pk_bf16_f32 v195, v190, v191
	v_cvt_pk_bf16_f32 v190, v218, v219
	v_cvt_pk_bf16_f32 v191, v202, v203
	global_store_dwordx2 v[164:165], v[194:195], off offset:256
	global_store_dwordx2 v[164:165], v[190:191], off offset:320
	v_lshlrev_b64 v[164:165], 9, v[166:167]
	v_mul_f32_e32 v166, v161, v193
	v_mul_f32_e32 v166, 0.15915494, v166
	v_fract_f32_e32 v167, v166
	v_sin_f32_e32 v166, v167
	v_cos_f32_e32 v190, v167
	v_mul_f32_e32 v167, v173, v193
	v_mul_f32_e32 v167, 0.15915494, v167
	v_fract_f32_e32 v167, v167
	v_cos_f32_e32 v191, v167
	v_sin_f32_e32 v167, v167
	v_mul_f32_e32 v193, v175, v193
	v_pk_fma_f32 v[200:201], v[88:89], v[174:175], v[148:149] op_sel_hi:[1,0,1]
	v_mul_f32_e32 v197, 0.15915494, v197
	v_mul_f32_e32 v193, 0.15915494, v193
	v_pk_fma_f32 v[194:195], v[92:93], v[174:175], v[144:145] op_sel_hi:[1,0,1]
; DI u32x2 pack4(const float* v) { u32x2 w; w.x = pk2(v[0], v[1]); w.y = pk2(v[2], v[3]); return w; }
; DI float ex2(float x) { return __builtin_amdgcn_exp2f(x); }
; DI void sincos_rev(float ang, float& s, float& c) { float rev = ang * 0.15915494309189535f; rev = __builtin_amdgcn_fractf(rev); s = __builtin_amdgcn_sinf(rev); c = __builtin_amdgcn_cosf(rev); }
;     template <int PN> DI void body(AccRef acc, const Unit& u, int wr, int wc, int fr, int fq) const {
;     ...
;                 } else if constexpr (PN == 3 || PN == 4) {
;                     bf16_t* dst = PN == 3 ? rq : rk;
;                     const float sc = PN == 3 ? 0.125f : 1.f;
; #pragma unroll
;                     for (int bj = 0; bj < 2; ++bj) {
;                         const int head = 2 * bj + (wc >> 1), i0 = 16 * (wc & 1) + 4 * fq;
;                         float o1[4], o2[4];
; #pragma unroll
;                         for (int j = 0; j < 4; ++j) { float sn, cs; sincos_rev((float)pos * ex2(-(float)(i0 + j) * KEXP64), sn, cs);
;                             o1[j] = (v[bj][j] * cs - v[bj][4 + j] * sn) * sc; o2[j] = (v[bj][j] * sn + v[bj][4 + j] * cs) * sc; }
;                         *(u32x2*)(dst + (size_t)row * 256 + head * 64 + i0) = pack4(o1);
;                         *(u32x2*)(dst + (size_t)row * 256 + head * 64 + 32 + i0) = pack4(o2);
;                     }
	v_pk_mul_f32 v[202:203], v[190:191], v[200:201]
	v_pk_mul_f32 v[200:201], v[166:167], v[200:201]
	v_fract_f32_e32 v197, v197
	v_fract_f32_e32 v193, v193
	v_pk_fma_f32 v[202:203], v[166:167], v[194:195], v[202:203]
	v_pk_fma_f32 v[194:195], v[190:191], v[194:195], v[200:201] neg_lo:[0,0,1] neg_hi:[0,0,1]
	v_sin_f32_e32 v200, v197
	v_cos_f32_e32 v204, v197
	v_cos_f32_e32 v205, v193
	v_sin_f32_e32 v201, v193
	v_pk_fma_f32 v[216:217], v[90:91], v[174:175], v[150:151] op_sel_hi:[1,0,1]
	v_lshl_add_u64 v[164:165], s[22:23], 0, v[164:165]
	v_pk_fma_f32 v[206:207], v[94:95], v[174:175], v[146:147] op_sel_hi:[1,0,1]
	v_pk_mul_f32 v[218:219], v[204:205], v[216:217]
	v_pk_mul_f32 v[216:217], v[200:201], v[216:217]
	v_pk_fma_f32 v[218:219], v[200:201], v[206:207], v[218:219]
	v_pk_fma_f32 v[206:207], v[204:205], v[206:207], v[216:217] neg_lo:[0,0,1] neg_hi:[0,0,1]
	v_lshl_add_u64 v[164:165], v[164:165], 0, s[2:3]
	v_cvt_pk_bf16_f32 v194, v194, v195
	v_cvt_pk_bf16_f32 v195, v206, v207
	v_lshl_add_u64 v[164:165], v[164:165], 0, v[198:199]
	global_store_dwordx2 v[164:165], v[194:195], off
	v_cvt_pk_bf16_f32 v194, v202, v203
	v_cvt_pk_bf16_f32 v195, v218, v219
	v_pk_fma_f32 v[202:203], v[80:81], v[174:175], v[152:153] op_sel_hi:[1,0,1]
	global_store_dwordx2 v[164:165], v[194:195], off offset:64
	v_pk_fma_f32 v[194:195], v[84:85], v[174:175], v[156:157] op_sel_hi:[1,0,1]
	v_pk_mul_f32 v[206:207], v[190:191], v[202:203]
	v_pk_fma_f32 v[148:149], v[72:73], v[170:171], v[148:149] op_sel_hi:[1,0,1]
	v_pk_fma_f32 v[206:207], v[166:167], v[194:195], v[206:207]
	v_pk_mul_f32 v[166:167], v[166:167], v[202:203]
	v_pk_fma_f32 v[144:145], v[76:77], v[170:171], v[144:145] op_sel_hi:[1,0,1]
	v_pk_fma_f32 v[166:167], v[190:191], v[194:195], v[166:167] neg_lo:[0,0,1] neg_hi:[0,0,1]
	v_pk_fma_f32 v[190:191], v[86:87], v[174:175], v[158:159] op_sel_hi:[1,0,1]
	v_pk_fma_f32 v[194:195], v[82:83], v[174:175], v[154:155] op_sel_hi:[1,0,1]
	v_add_u32_e32 v174, 48, v189
	v_pk_mul_f32 v[202:203], v[204:205], v[194:195]
	v_pk_mul_f32 v[194:195], v[200:201], v[194:195]
	v_cvt_f32_u32_e32 v174, v174
	v_pk_fma_f32 v[202:203], v[200:201], v[190:191], v[202:203]
	v_pk_fma_f32 v[190:191], v[204:205], v[190:191], v[194:195] neg_lo:[0,0,1] neg_hi:[0,0,1]
	v_cvt_pk_bf16_f32 v166, v166, v167
	v_cvt_pk_bf16_f32 v167, v190, v191
	global_store_dwordx2 v[164:165], v[166:167], off offset:256
	v_cvt_pk_bf16_f32 v166, v206, v207
	v_cvt_pk_bf16_f32 v167, v202, v203
	global_store_dwordx2 v[164:165], v[166:167], off offset:320
	v_mul_f32_e32 v164, v161, v174
	v_mul_f32_e32 v164, 0.15915494, v164
	v_fract_f32_e32 v165, v164
	v_sin_f32_e32 v164, v165
	v_cos_f32_e32 v166, v165
	v_mul_f32_e32 v165, v173, v174
	v_mul_f32_e32 v165, 0.15915494, v165
	v_fract_f32_e32 v165, v165
	v_cos_f32_e32 v167, v165
	v_sin_f32_e32 v165, v165
	v_pk_fma_f32 v[150:151], v[74:75], v[170:171], v[150:151] op_sel_hi:[1,0,1]
	v_pk_fma_f32 v[146:147], v[78:79], v[170:171], v[146:147] op_sel_hi:[1,0,1]
	v_pk_mul_f32 v[190:191], v[166:167], v[148:149]
	v_pk_mul_f32 v[148:149], v[164:165], v[148:149]
	v_pk_fma_f32 v[190:191], v[164:165], v[144:145], v[190:191]
	v_pk_fma_f32 v[144:145], v[166:167], v[144:145], v[148:149] neg_lo:[0,0,1] neg_hi:[0,0,1]
	v_mul_f32_e32 v148, v171, v174
	v_mul_f32_e32 v148, 0.15915494, v148
	v_fract_f32_e32 v149, v148
	v_sin_f32_e32 v148, v149
	v_cos_f32_e32 v194, v149
	v_mul_f32_e32 v149, v175, v174
	v_mul_f32_e32 v149, 0.15915494, v149
	v_fract_f32_e32 v149, v149
	v_cos_f32_e32 v195, v149
	v_sin_f32_e32 v149, v149
	v_cvt_pk_bf16_f32 v144, v144, v145
	v_pk_fma_f32 v[154:155], v[66:67], v[170:171], v[154:155] op_sel_hi:[1,0,1]
	v_pk_mul_f32 v[200:201], v[194:195], v[150:151]
	v_pk_mul_f32 v[150:151], v[148:149], v[150:151]
	v_pk_fma_f32 v[200:201], v[148:149], v[146:147], v[200:201]
	v_pk_fma_f32 v[146:147], v[194:195], v[146:147], v[150:151] neg_lo:[0,0,1] neg_hi:[0,0,1]
	v_pk_fma_f32 v[150:151], v[64:65], v[170:171], v[152:153] op_sel_hi:[1,0,1]
	v_cvt_pk_bf16_f32 v145, v146, v147
	v_lshl_add_u64 v[146:147], v[162:163], 0, s[2:3]
	v_lshl_add_u64 v[146:147], v[146:147], 0, v[198:199]
	global_store_dwordx2 v[146:147], v[144:145], off
	v_cvt_pk_bf16_f32 v144, v190, v191
	v_cvt_pk_bf16_f32 v145, v200, v201
	global_store_dwordx2 v[146:147], v[144:145], off offset:64
	v_pk_fma_f32 v[144:145], v[68:69], v[170:171], v[156:157] op_sel_hi:[1,0,1]
	v_pk_mul_f32 v[152:153], v[166:167], v[150:151]
	v_pk_mul_f32 v[150:151], v[164:165], v[150:151]
	v_pk_fma_f32 v[152:153], v[164:165], v[144:145], v[152:153]
	v_pk_fma_f32 v[144:145], v[166:167], v[144:145], v[150:151] neg_lo:[0,0,1] neg_hi:[0,0,1]
	v_pk_fma_f32 v[150:151], v[70:71], v[170:171], v[158:159] op_sel_hi:[1,0,1]
	v_pk_mul_f32 v[156:157], v[194:195], v[154:155]
	v_cvt_pk_bf16_f32 v144, v144, v145
	v_pk_fma_f32 v[156:157], v[148:149], v[150:151], v[156:157]
	v_pk_mul_f32 v[148:149], v[148:149], v[154:155]
	s_waitcnt vmcnt(15)
; DI u32x2 pack4(const float* v) { u32x2 w; w.x = pk2(v[0], v[1]); w.y = pk2(v[2], v[3]); return w; }
; DI float ex2(float x) { return __builtin_amdgcn_exp2f(x); }
; DI void sincos_rev(float ang, float& s, float& c) { float rev = ang * 0.15915494309189535f; rev = __builtin_amdgcn_fractf(rev); s = __builtin_amdgcn_sinf(rev); c = __builtin_amdgcn_cosf(rev); }
;     template <int PN> DI void body(AccRef acc, const Unit& u, int wr, int wc, int fr, int fq) const {
;     ...
;                 } else if constexpr (PN == 3 || PN == 4) {
;                     bf16_t* dst = PN == 3 ? rq : rk;
;                     const float sc = PN == 3 ? 0.125f : 1.f;
; #pragma unroll
;                     for (int bj = 0; bj < 2; ++bj) {
;                         const int head = 2 * bj + (wc >> 1), i0 = 16 * (wc & 1) + 4 * fq;
;                         float o1[4], o2[4];
; #pragma unroll
;                         for (int j = 0; j < 4; ++j) { float sn, cs; sincos_rev((float)pos * ex2(-(float)(i0 + j) * KEXP64), sn, cs);
;                             o1[j] = (v[bj][j] * cs - v[bj][4 + j] * sn) * sc; o2[j] = (v[bj][j] * sn + v[bj][4 + j] * cs) * sc; }
;                         *(u32x2*)(dst + (size_t)row * 256 + head * 64 + i0) = pack4(o1);
;                         *(u32x2*)(dst + (size_t)row * 256 + head * 64 + 32 + i0) = pack4(o2);
;                     }
	v_pk_fma_f32 v[162:163], v[58:59], v[196:197], v[138:139] op_sel_hi:[1,0,1]
	v_pk_fma_f32 v[148:149], v[194:195], v[150:151], v[148:149] neg_lo:[0,0,1] neg_hi:[0,0,1]
	v_pk_fma_f32 v[150:151], v[60:61], v[196:197], v[140:141] op_sel_hi:[1,0,1]
	v_cvt_pk_bf16_f32 v145, v148, v149
	global_store_dwordx2 v[146:147], v[144:145], off offset:256
	v_cvt_pk_bf16_f32 v144, v152, v153
	v_cvt_pk_bf16_f32 v145, v156, v157
	global_store_dwordx2 v[146:147], v[144:145], off offset:320
	v_and_b32_e32 v144, 0x7ff, v168
	v_cndmask_b32_e32 v166, v169, v144, vcc
	v_cvt_f32_u32_e32 v157, v166
	v_pk_fma_f32 v[152:153], v[56:57], v[196:197], v[136:137] op_sel_hi:[1,0,1]
	v_ashrrev_i32_e32 v169, 31, v168
	v_lshlrev_b64 v[144:145], 9, v[168:169]
	v_mul_f32_e32 v146, v161, v157
	v_mul_f32_e32 v146, 0.15915494, v146
	v_fract_f32_e32 v147, v146
	v_sin_f32_e32 v146, v147
	v_cos_f32_e32 v148, v147
	v_mul_f32_e32 v147, v173, v157
	v_mul_f32_e32 v147, 0.15915494, v147
	v_fract_f32_e32 v147, v147
	v_cos_f32_e32 v149, v147
	v_sin_f32_e32 v147, v147
	v_lshl_add_u64 v[144:145], s[22:23], 0, v[144:145]
	v_pk_fma_f32 v[158:159], v[62:63], v[196:197], v[142:143] op_sel_hi:[1,0,1]
	v_pk_mul_f32 v[154:155], v[148:149], v[152:153]
	v_pk_mul_f32 v[152:153], v[146:147], v[152:153]
	v_pk_fma_f32 v[154:155], v[146:147], v[150:151], v[154:155]
	v_pk_fma_f32 v[150:151], v[148:149], v[150:151], v[152:153] neg_lo:[0,0,1] neg_hi:[0,0,1]
	v_mul_f32_e32 v152, v171, v157
	v_mul_f32_e32 v152, 0.15915494, v152
	v_fract_f32_e32 v153, v152
	v_sin_f32_e32 v152, v153
	v_cos_f32_e32 v156, v153
	v_mul_f32_e32 v153, v175, v157
	v_mul_f32_e32 v153, 0.15915494, v153
	v_fract_f32_e32 v153, v153
	v_cos_f32_e32 v157, v153
	v_sin_f32_e32 v153, v153
	v_lshl_add_u64 v[144:145], v[144:145], 0, s[2:3]
	v_cvt_pk_bf16_f32 v150, v150, v151
	v_pk_mul_f32 v[164:165], v[156:157], v[162:163]
	v_pk_mul_f32 v[162:163], v[152:153], v[162:163]
	v_pk_fma_f32 v[164:165], v[152:153], v[158:159], v[164:165]
	v_pk_fma_f32 v[158:159], v[156:157], v[158:159], v[162:163] neg_lo:[0,0,1] neg_hi:[0,0,1]
	v_lshl_add_u64 v[144:145], v[144:145], 0, v[198:199]
	v_cvt_pk_bf16_f32 v151, v158, v159
	global_store_dwordx2 v[144:145], v[150:151], off
	v_cvt_pk_bf16_f32 v150, v154, v155
	v_cvt_pk_bf16_f32 v151, v164, v165
	v_pk_fma_f32 v[154:155], v[48:49], v[196:197], v[128:129] op_sel_hi:[1,0,1]
	global_store_dwordx2 v[144:145], v[150:151], off offset:64
	s_waitcnt vmcnt(18)
	v_pk_fma_f32 v[150:151], v[52:53], v[196:197], v[132:133] op_sel_hi:[1,0,1]
	v_pk_mul_f32 v[158:159], v[148:149], v[154:155]
	v_pk_fma_f32 v[162:163], v[42:43], v[192:193], v[138:139] op_sel_hi:[1,0,1]
	v_pk_fma_f32 v[158:159], v[146:147], v[150:151], v[158:159]
	v_pk_mul_f32 v[146:147], v[146:147], v[154:155]
	s_nop 0
	v_pk_fma_f32 v[146:147], v[148:149], v[150:151], v[146:147] neg_lo:[0,0,1] neg_hi:[0,0,1]
	v_pk_fma_f32 v[150:151], v[50:51], v[196:197], v[130:131] op_sel_hi:[1,0,1]
	v_pk_fma_f32 v[148:149], v[54:55], v[196:197], v[134:135] op_sel_hi:[1,0,1]
	v_pk_mul_f32 v[154:155], v[156:157], v[150:151]
	v_pk_mul_f32 v[150:151], v[152:153], v[150:151]
	v_pk_fma_f32 v[154:155], v[152:153], v[148:149], v[154:155]
	v_pk_fma_f32 v[148:149], v[156:157], v[148:149], v[150:151] neg_lo:[0,0,1] neg_hi:[0,0,1]
	v_cvt_pk_bf16_f32 v146, v146, v147
	v_cvt_pk_bf16_f32 v147, v148, v149
	global_store_dwordx2 v[144:145], v[146:147], off offset:256
	v_cvt_pk_bf16_f32 v146, v158, v159
	v_cvt_pk_bf16_f32 v147, v154, v155
	global_store_dwordx2 v[144:145], v[146:147], off offset:320
	v_add_u32_e32 v145, 16, v166
	v_cvt_f32_u32_e32 v157, v145
	v_pk_fma_f32 v[152:153], v[40:41], v[192:193], v[136:137] op_sel_hi:[1,0,1]
	v_pk_fma_f32 v[150:151], v[44:45], v[192:193], v[140:141] op_sel_hi:[1,0,1]
	v_add_u32_e32 v144, 0x90, v160
	v_mul_f32_e32 v146, v161, v157
	v_mul_f32_e32 v146, 0.15915494, v146
	v_fract_f32_e32 v147, v146
	v_sin_f32_e32 v146, v147
	v_cos_f32_e32 v148, v147
	v_mul_f32_e32 v147, v173, v157
	v_mul_f32_e32 v147, 0.15915494, v147
	v_fract_f32_e32 v147, v147
	v_cos_f32_e32 v149, v147
	v_sin_f32_e32 v147, v147
	v_ashrrev_i32_e32 v145, 31, v144
	v_lshlrev_b64 v[144:145], 9, v[144:145]
	v_pk_mul_f32 v[154:155], v[148:149], v[152:153]
	v_pk_mul_f32 v[152:153], v[146:147], v[152:153]
	v_pk_fma_f32 v[154:155], v[146:147], v[150:151], v[154:155]
	v_pk_fma_f32 v[150:151], v[148:149], v[150:151], v[152:153] neg_lo:[0,0,1] neg_hi:[0,0,1]
	v_mul_f32_e32 v152, v171, v157
	v_mul_f32_e32 v152, 0.15915494, v152
	v_fract_f32_e32 v153, v152
	v_sin_f32_e32 v152, v153
	v_cos_f32_e32 v156, v153
	v_mul_f32_e32 v153, v175, v157
	v_mul_f32_e32 v153, 0.15915494, v153
	v_fract_f32_e32 v153, v153
	v_cos_f32_e32 v157, v153
	v_sin_f32_e32 v153, v153
	v_lshl_add_u64 v[144:145], s[22:23], 0, v[144:145]
	v_pk_fma_f32 v[158:159], v[46:47], v[192:193], v[142:143] op_sel_hi:[1,0,1]
	v_pk_mul_f32 v[164:165], v[156:157], v[162:163]
	v_pk_mul_f32 v[162:163], v[152:153], v[162:163]
	v_pk_fma_f32 v[164:165], v[152:153], v[158:159], v[164:165]
	v_pk_fma_f32 v[158:159], v[156:157], v[158:159], v[162:163] neg_lo:[0,0,1] neg_hi:[0,0,1]
	v_lshl_add_u64 v[144:145], v[144:145], 0, s[2:3]
	v_cvt_pk_bf16_f32 v150, v150, v151
	v_cvt_pk_bf16_f32 v151, v158, v159
	v_lshl_add_u64 v[144:145], v[144:145], 0, v[198:199]
	global_store_dwordx2 v[144:145], v[150:151], off
	v_cvt_pk_bf16_f32 v150, v154, v155
	v_cvt_pk_bf16_f32 v151, v164, v165
	v_pk_fma_f32 v[154:155], v[28:29], v[192:193], v[128:129] op_sel_hi:[1,0,1]
	global_store_dwordx2 v[144:145], v[150:151], off offset:64
	v_pk_fma_f32 v[150:151], v[36:37], v[192:193], v[132:133] op_sel_hi:[1,0,1]
	v_pk_mul_f32 v[158:159], v[148:149], v[154:155]
; DI u32x2 pack4(const float* v) { u32x2 w; w.x = pk2(v[0], v[1]); w.y = pk2(v[2], v[3]); return w; }
; DI float ex2(float x) { return __builtin_amdgcn_exp2f(x); }
; DI void sincos_rev(float ang, float& s, float& c) { float rev = ang * 0.15915494309189535f; rev = __builtin_amdgcn_fractf(rev); s = __builtin_amdgcn_sinf(rev); c = __builtin_amdgcn_cosf(rev); }
;     template <int PN> DI void body(AccRef acc, const Unit& u, int wr, int wc, int fr, int fq) const {
;     ...
;                 } else if constexpr (PN == 3 || PN == 4) {
;                     bf16_t* dst = PN == 3 ? rq : rk;
;                     const float sc = PN == 3 ? 0.125f : 1.f;
; #pragma unroll
;                     for (int bj = 0; bj < 2; ++bj) {
;                         const int head = 2 * bj + (wc >> 1), i0 = 16 * (wc & 1) + 4 * fq;
;                         float o1[4], o2[4];
; #pragma unroll
;                         for (int j = 0; j < 4; ++j) { float sn, cs; sincos_rev((float)pos * ex2(-(float)(i0 + j) * KEXP64), sn, cs);
;                             o1[j] = (v[bj][j] * cs - v[bj][4 + j] * sn) * sc; o2[j] = (v[bj][j] * sn + v[bj][4 + j] * cs) * sc; }
;                         *(u32x2*)(dst + (size_t)row * 256 + head * 64 + i0) = pack4(o1);
;                         *(u32x2*)(dst + (size_t)row * 256 + head * 64 + 32 + i0) = pack4(o2);
;                     }
	v_pk_fma_f32 v[162:163], v[26:27], v[188:189], v[138:139] op_sel_hi:[1,0,1]
	v_pk_fma_f32 v[158:159], v[146:147], v[150:151], v[158:159]
	v_pk_mul_f32 v[146:147], v[146:147], v[154:155]
	v_pk_fma_f32 v[138:139], v[10:11], v[172:173], v[138:139] op_sel_hi:[1,0,1]
	v_pk_fma_f32 v[146:147], v[148:149], v[150:151], v[146:147] neg_lo:[0,0,1] neg_hi:[0,0,1]
	v_pk_fma_f32 v[150:151], v[30:31], v[192:193], v[130:131] op_sel_hi:[1,0,1]
	v_pk_fma_f32 v[148:149], v[38:39], v[192:193], v[134:135] op_sel_hi:[1,0,1]
	v_pk_mul_f32 v[154:155], v[156:157], v[150:151]
	v_pk_mul_f32 v[150:151], v[152:153], v[150:151]
	v_pk_fma_f32 v[154:155], v[152:153], v[148:149], v[154:155]
	v_pk_fma_f32 v[148:149], v[156:157], v[148:149], v[150:151] neg_lo:[0,0,1] neg_hi:[0,0,1]
	v_cvt_pk_bf16_f32 v146, v146, v147
	v_cvt_pk_bf16_f32 v147, v148, v149
	global_store_dwordx2 v[144:145], v[146:147], off offset:256
	v_cvt_pk_bf16_f32 v146, v158, v159
	v_cvt_pk_bf16_f32 v147, v154, v155
	global_store_dwordx2 v[144:145], v[146:147], off offset:320
	v_add_u32_e32 v145, 32, v166
	v_cvt_f32_u32_e32 v157, v145
	v_pk_fma_f32 v[152:153], v[24:25], v[188:189], v[136:137] op_sel_hi:[1,0,1]
	v_pk_fma_f32 v[150:151], v[32:33], v[188:189], v[140:141] op_sel_hi:[1,0,1]
	v_add_u32_e32 v144, 0xa0, v160
	v_mul_f32_e32 v146, v161, v157
	v_mul_f32_e32 v146, 0.15915494, v146
	v_fract_f32_e32 v147, v146
	v_sin_f32_e32 v146, v147
	v_cos_f32_e32 v148, v147
	v_mul_f32_e32 v147, v173, v157
	v_mul_f32_e32 v147, 0.15915494, v147
	v_fract_f32_e32 v147, v147
	v_cos_f32_e32 v149, v147
	v_sin_f32_e32 v147, v147
	v_ashrrev_i32_e32 v145, 31, v144
	v_lshlrev_b64 v[144:145], 9, v[144:145]
	v_pk_mul_f32 v[154:155], v[148:149], v[152:153]
	v_pk_mul_f32 v[152:153], v[146:147], v[152:153]
	v_pk_fma_f32 v[154:155], v[146:147], v[150:151], v[154:155]
	v_pk_fma_f32 v[150:151], v[148:149], v[150:151], v[152:153] neg_lo:[0,0,1] neg_hi:[0,0,1]
	v_mul_f32_e32 v152, v171, v157
	v_mul_f32_e32 v152, 0.15915494, v152
	v_fract_f32_e32 v153, v152
	v_sin_f32_e32 v152, v153
	v_cos_f32_e32 v156, v153
	v_mul_f32_e32 v153, v175, v157
	v_mul_f32_e32 v153, 0.15915494, v153
	v_fract_f32_e32 v153, v153
	v_cos_f32_e32 v157, v153
	v_sin_f32_e32 v153, v153
	v_lshl_add_u64 v[144:145], s[22:23], 0, v[144:145]
	v_pk_fma_f32 v[158:159], v[34:35], v[188:189], v[142:143] op_sel_hi:[1,0,1]
	v_pk_mul_f32 v[164:165], v[156:157], v[162:163]
	v_pk_mul_f32 v[162:163], v[152:153], v[162:163]
	v_pk_fma_f32 v[164:165], v[152:153], v[158:159], v[164:165]
	v_pk_fma_f32 v[158:159], v[156:157], v[158:159], v[162:163] neg_lo:[0,0,1] neg_hi:[0,0,1]
	v_lshl_add_u64 v[144:145], v[144:145], 0, s[2:3]
	v_cvt_pk_bf16_f32 v150, v150, v151
	v_cvt_pk_bf16_f32 v151, v158, v159
	v_lshl_add_u64 v[144:145], v[144:145], 0, v[198:199]
	global_store_dwordx2 v[144:145], v[150:151], off
	v_cvt_pk_bf16_f32 v150, v154, v155
	v_cvt_pk_bf16_f32 v151, v164, v165
	v_pk_fma_f32 v[154:155], v[16:17], v[188:189], v[128:129] op_sel_hi:[1,0,1]
	global_store_dwordx2 v[144:145], v[150:151], off offset:64
	v_pk_fma_f32 v[150:151], v[20:21], v[188:189], v[132:133] op_sel_hi:[1,0,1]
	v_pk_mul_f32 v[158:159], v[148:149], v[154:155]
	v_pk_fma_f32 v[136:137], v[8:9], v[172:173], v[136:137] op_sel_hi:[1,0,1]
	v_pk_fma_f32 v[158:159], v[146:147], v[150:151], v[158:159]
	v_pk_mul_f32 v[146:147], v[146:147], v[154:155]
	v_pk_fma_f32 v[140:141], v[12:13], v[172:173], v[140:141] op_sel_hi:[1,0,1]
	v_pk_fma_f32 v[146:147], v[148:149], v[150:151], v[146:147] neg_lo:[0,0,1] neg_hi:[0,0,1]
	v_pk_fma_f32 v[150:151], v[18:19], v[188:189], v[130:131] op_sel_hi:[1,0,1]
	v_pk_fma_f32 v[148:149], v[22:23], v[188:189], v[134:135] op_sel_hi:[1,0,1]
	v_pk_mul_f32 v[154:155], v[156:157], v[150:151]
	v_pk_mul_f32 v[150:151], v[152:153], v[150:151]
	v_pk_fma_f32 v[154:155], v[152:153], v[148:149], v[154:155]
	v_pk_fma_f32 v[148:149], v[156:157], v[148:149], v[150:151] neg_lo:[0,0,1] neg_hi:[0,0,1]
	v_cvt_pk_bf16_f32 v146, v146, v147
	v_cvt_pk_bf16_f32 v147, v148, v149
	global_store_dwordx2 v[144:145], v[146:147], off offset:256
	v_cvt_pk_bf16_f32 v146, v158, v159
	v_cvt_pk_bf16_f32 v147, v154, v155
	global_store_dwordx2 v[144:145], v[146:147], off offset:320
	v_add_u32_e32 v145, 48, v166
	v_cvt_f32_u32_e32 v153, v145
	v_add_u32_e32 v144, 0xb0, v160
	v_ashrrev_i32_e32 v145, 31, v144
	v_lshlrev_b64 v[144:145], 9, v[144:145]
	v_mul_f32_e32 v146, v161, v153
	v_mul_f32_e32 v146, 0.15915494, v146
	v_fract_f32_e32 v147, v146
	v_sin_f32_e32 v146, v147
	v_cos_f32_e32 v148, v147
	v_mul_f32_e32 v147, v173, v153
	v_mul_f32_e32 v147, 0.15915494, v147
	v_fract_f32_e32 v147, v147
	v_cos_f32_e32 v149, v147
	v_sin_f32_e32 v147, v147
	v_pk_fma_f32 v[142:143], v[14:15], v[172:173], v[142:143] op_sel_hi:[1,0,1]
	v_lshl_add_u64 v[144:145], s[22:23], 0, v[144:145]
	v_pk_mul_f32 v[150:151], v[148:149], v[136:137]
	v_pk_mul_f32 v[136:137], v[146:147], v[136:137]
	v_pk_fma_f32 v[150:151], v[146:147], v[140:141], v[150:151]
	v_pk_fma_f32 v[136:137], v[148:149], v[140:141], v[136:137] neg_lo:[0,0,1] neg_hi:[0,0,1]
	v_mul_f32_e32 v140, v171, v153
	v_mul_f32_e32 v140, 0.15915494, v140
	v_fract_f32_e32 v141, v140
	v_sin_f32_e32 v140, v141
	v_cos_f32_e32 v152, v141
	v_mul_f32_e32 v141, v175, v153
	v_mul_f32_e32 v141, 0.15915494, v141
	v_fract_f32_e32 v141, v141
	v_cos_f32_e32 v153, v141
	v_sin_f32_e32 v141, v141
	v_cvt_pk_bf16_f32 v136, v136, v137
	v_pk_fma_f32 v[128:129], v[0:1], v[172:173], v[128:129] op_sel_hi:[1,0,1]
	v_pk_mul_f32 v[154:155], v[152:153], v[138:139]
	v_pk_mul_f32 v[138:139], v[140:141], v[138:139]
	v_pk_fma_f32 v[154:155], v[140:141], v[142:143], v[154:155]
	v_pk_fma_f32 v[138:139], v[152:153], v[142:143], v[138:139] neg_lo:[0,0,1] neg_hi:[0,0,1]
	v_pk_fma_f32 v[132:133], v[4:5], v[172:173], v[132:133] op_sel_hi:[1,0,1]
	v_cvt_pk_bf16_f32 v137, v138, v139
	v_lshl_add_u64 v[138:139], v[144:145], 0, s[2:3]
	v_lshl_add_u64 v[138:139], v[138:139], 0, v[198:199]
	global_store_dwordx2 v[138:139], v[136:137], off
	v_cvt_pk_bf16_f32 v136, v150, v151
	v_cvt_pk_bf16_f32 v137, v154, v155
	global_store_dwordx2 v[138:139], v[136:137], off offset:64
	v_pk_mul_f32 v[136:137], v[148:149], v[128:129]
	v_pk_mul_f32 v[128:129], v[146:147], v[128:129]
	v_pk_fma_f32 v[130:131], v[2:3], v[172:173], v[130:131] op_sel_hi:[1,0,1]
	v_pk_fma_f32 v[136:137], v[146:147], v[132:133], v[136:137]
	v_pk_fma_f32 v[128:129], v[148:149], v[132:133], v[128:129] neg_lo:[0,0,1] neg_hi:[0,0,1]
	v_pk_fma_f32 v[132:133], v[6:7], v[172:173], v[134:135] op_sel_hi:[1,0,1]
	v_pk_mul_f32 v[134:135], v[152:153], v[130:131]
	v_pk_mul_f32 v[130:131], v[140:141], v[130:131]
	v_pk_fma_f32 v[134:135], v[140:141], v[132:133], v[134:135]
	v_pk_fma_f32 v[130:131], v[152:153], v[132:133], v[130:131] neg_lo:[0,0,1] neg_hi:[0,0,1]
	v_cvt_pk_bf16_f32 v128, v128, v129
	v_cvt_pk_bf16_f32 v129, v130, v131
	global_store_dwordx2 v[138:139], v[128:129], off offset:256
	v_cvt_pk_bf16_f32 v128, v136, v137
	v_cvt_pk_bf16_f32 v129, v134, v135
	global_store_dwordx2 v[138:139], v[128:129], off offset:320

; DI float ex2(float x) { return __builtin_amdgcn_exp2f(x); }
;     template <int PN> DI void body(AccRef acc, const Unit& u, int wr, int wc, int fr, int fq) const {
;     ...
;         for (int ai = 0; ai < 2; ++ai) {
;             const int rb_ = u.pm * 256 + ai * 128 + wr * 64 + fr;
; #pragma unroll
;             for (int m = 0; m < 4; ++m) rinvh[ai][m] = rsqrtf(sum16(ssq + (size_t)(rb_ + 16 * m + zdep) * 16) * (1.f / 1024.f) + EPS);
;             asm volatile("v_mov_b32 %0, 0" : "=v"(zdep) : "v"(rinvh[ai][0]), "v"(rinvh[ai][1]), "v"(rinvh[ai][2]), "v"(rinvh[ai][3]));
;         }
; #pragma unroll
;         for (int ai = 0; ai < 2; ++ai) {
;             const int rb_ = u.pm * 256 + ai * 128 + wr * 64 + fr;
;             int mb_, p_, k_; row_info(rb_, mb_, p_, k_);
; #pragma unroll
;             for (int bj = 0; bj < 2; ++bj)
; #pragma unroll
;                 for (int n = 0; n < 2; ++n) cvh[ai][bj][n] = *(const f32x4*)(cv + (size_t)(mb_ + zdep) * NIN + PN * 256 + bj * 128 + cl + 4 * n);
;         }
; #pragma unroll
;         for (int ai = 0; ai < 2; ++ai) {
;             const int rb = u.pm * 256 + ai * 128 + wr * 64 + fr;
;             int mb, pos0, kv0; row_info(rb, mb, pos0, kv0);
; #pragma unroll
;             for (int m = 0; m < 4; ++m) {
;                 const int row = rb + 16 * m, pos = pos0 + 16 * m, kvrow = kv0 + 16 * m;
;                 const float rinv = rinvh[ai][m];
;                 float v[2][8];
; #pragma unroll
;                 for (int bj = 0; bj < 2; ++bj)
; #pragma unroll
;                     for (int n = 0; n < 2; ++n)
; #pragma unroll
;                         for (int j = 0; j < 4; ++j) v[bj][4 * n + j] = acc[ai][bj][m][n][j] * rinv + cvh[ai][bj][n][j];
;     ...
;                 } else if constexpr (PN == 3 || PN == 4) {
;                     bf16_t* dst = PN == 3 ? rq : rk;
;                     const float sc = PN == 3 ? 0.125f : 1.f;
; #pragma unroll
;                     for (int bj = 0; bj < 2; ++bj) {
;                         const int head = 2 * bj + (wc >> 1), i0 = 16 * (wc & 1) + 4 * fq;
;                         float o1[4], o2[4];
; #pragma unroll
;                         for (int j = 0; j < 4; ++j) { float sn, cs; sincos_rev((float)pos * ex2(-(float)(i0 + j) * KEXP64), sn, cs);
;                             o1[j] = (v[bj][j] * cs - v[bj][4 + j] * sn) * sc; o2[j] = (v[bj][j] * sn + v[bj][4 + j] * cs) * sc; }
.LBB0_1913:
	s_and_b64 vcc, exec, s[2:3]
	s_cbranch_vccz .LBB0_1977
	s_cmp_gt_i32 s66, 1
	s_mov_b64 s[2:3], -1
	s_cbranch_scc0 .LBB0_1956
	s_cmp_gt_i32 s66, 2
	s_cbranch_scc0 .LBB0_1917
	s_lshl_b32 s2, s43, 6
	s_lshl_b32 s3, s34, 8
	s_add_i32 s2, s2, s3
	v_add_u32_e32 v160, s2, v214
	v_add_u32_e32 v164, 16, v160
	v_ashrrev_i32_e32 v161, 31, v160
	v_ashrrev_i32_e32 v165, 31, v164
	v_lshlrev_b64 v[128:129], 6, v[160:161]
	v_lshlrev_b64 v[144:145], 6, v[164:165]
	v_add_u32_e32 v166, 32, v160
	v_lshl_add_u64 v[140:141], s[70:71], 0, v[128:129]
	v_lshl_add_u64 v[144:145], s[70:71], 0, v[144:145]
	v_ashrrev_i32_e32 v167, 31, v166
	s_nop 0
	s_nop 0
	v_lshlrev_b64 v[144:145], 6, v[166:167]
	v_add_u32_e32 v162, 48, v160
	v_lshl_add_u64 v[144:145], s[70:71], 0, v[144:145]
	v_ashrrev_i32_e32 v163, 31, v162
	v_lshlrev_b64 v[144:145], 6, v[162:163]
	v_lshl_add_u64 v[144:145], s[70:71], 0, v[144:145]
	s_mov_b32 s2, 0x358637bd
	v_mov_b64_e32 v[144:145], s[2:3]
	s_mov_b32 s8, 0x3a800000
	s_mov_b64 s[12:13], 0x124c00
	v_readlane_b32 s16, v254, 48
	v_readlane_b32 s17, v254, 49
	v_lshlrev_b64 v[164:165], 9, v[164:165]
	v_lshlrev_b64 v[162:163], 9, v[162:163]
	v_lshl_add_u64 v[164:165], s[16:17], 0, v[164:165]
	v_lshl_add_u64 v[162:163], s[16:17], 0, v[162:163]
	v_mov_b32_e32 v190, v245
	v_mov_b32_e32 v174, v246
	v_add_u32_e32 v168, 0x80, v160
	v_mov_b32_e32 v194, v244
	v_mov_b32_e32 v170, v247
	v_mov_b32 v128, 0
	s_lshl_b32 s6, s60, 5
	v_add_u32_e32 v158, v128, v168
	v_add_u32_e32 v146, 16, v158
	v_ashrrev_i32_e32 v159, 31, v158
	v_ashrrev_i32_e32 v147, 31, v146
	v_lshlrev_b64 v[128:129], 6, v[158:159]
	v_lshlrev_b64 v[146:147], 6, v[146:147]
	v_lshl_add_u64 v[140:141], s[70:71], 0, v[128:129]
	v_lshl_add_u64 v[172:173], s[70:71], 0, v[146:147]
	s_nop 0
	s_nop 0
	v_add_u32_e32 v172, 32, v158
	v_ashrrev_i32_e32 v173, 31, v172
	v_add_u32_e32 v158, 48, v158
	v_lshlrev_b64 v[172:173], 6, v[172:173]
	v_ashrrev_i32_e32 v159, 31, v158
	v_lshl_add_u64 v[172:173], s[70:71], 0, v[172:173]
	v_lshlrev_b64 v[158:159], 6, v[158:159]
	v_lshl_add_u64 v[158:159], s[70:71], 0, v[158:159]
	s_movk_i32 s7, 0x2800
	v_mov_b32_e32 v196, v248
	v_mov_b32_e32 v192, v249
	v_mov_b32_e32 v188, v250
	v_mov_b32_e32 v172, v251
	v_add_u32_e32 v129, 0xffffc000, v160
	v_lshrrev_b32_e32 v129, 6, v129
	v_ashrrev_i32_e32 v128, 11, v160
	v_add_u32_e32 v129, 8, v129
	v_cmp_gt_i32_e64 s[2:3], s94, v160
	v_lshl_add_u32 v130, v213, 3, s6
	v_mov_b32 v136, 0
	v_ashrrev_i32_e32 v131, 31, v130
	v_cndmask_b32_e64 v128, v129, v128, s[2:3]
	v_add_u32_e32 v132, v136, v128
	v_mov_b64_e32 v[128:129], s[74:75]
	v_mad_i64_i32 v[132:133], s[4:5], v132, s7, v[128:129]
	v_lshlrev_b64 v[130:131], 2, v[130:131]
	v_lshl_add_u64 v[132:133], v[132:133], 0, v[130:131]
	s_mov_b32 s8, 0x124000
	v_lshl_add_u64 v[134:135], v[132:133], 0, s[12:13]
	v_add_co_u32_e32 v132, vcc, s8, v132
	s_lshl_b32 s4, s60, 4
	s_nop 0
	v_addc_co_u32_e32 v133, vcc, 0, v133, vcc
	global_load_dwordx4 v[144:147], v[132:133], off offset:3072
	global_load_dwordx4 v[148:151], v[134:135], off offset:16
	global_load_dwordx4 v[156:159], v[134:135], off offset:512
	global_load_dwordx4 v[152:155], v[134:135], off offset:528
	s_and_b32 s5, s4, 16
	v_lshl_add_u32 v198, v213, 2, s5
	v_cvt_f32_i32_e32 v138, v198
	v_or_b32_e32 v139, 1, v198
	v_mov_b32_e32 v132, 0x400
	v_cvt_f32_i32_e32 v134, v139
	v_and_or_b32 v169, v214, 63, v132
	v_add_u32_e32 v132, 0xffffc080, v160
	v_and_b32_e32 v137, 0x7ff, v160
	v_lshrrev_b32_e32 v142, 6, v132
	v_lshlrev_b64 v[132:133], 9, v[160:161]
	v_lshl_add_u64 v[200:201], s[16:17], 0, v[132:133]
	v_cndmask_b32_e64 v189, v169, v137, s[2:3]
	v_mul_f32_e32 v133, 0xbed49a78, v138
	v_cvt_f32_u32_e32 v191, v189
	v_exp_f32_e32 v171, v133
	v_mul_f32_e32 v133, 0xbed49a78, v134
	v_or_b32_e32 v140, 2, v198
	v_exp_f32_e32 v161, v133
	v_or_b32_e32 v175, 3, v198
	v_cvt_f32_i32_e32 v135, v140
	v_cvt_f32_i32_e32 v175, v175
	v_mul_f32_e32 v133, v171, v191
	v_mul_f32_e32 v133, 0.15915494, v133
	v_mul_f32_e32 v134, v161, v191
	v_mul_f32_e32 v173, 0xbed49a78, v135
	v_fract_f32_e32 v133, v133
	v_mul_f32_e32 v134, 0.15915494, v134
	v_mul_f32_e32 v175, 0xbed49a78, v175
	v_sin_f32_e32 v202, v133
	v_cos_f32_e32 v204, v133
	v_fract_f32_e32 v133, v134
	v_exp_f32_e32 v173, v173
	v_exp_f32_e32 v175, v175
	v_cos_f32_e32 v205, v133
	v_sin_f32_e32 v203, v133
	v_mul_f32_e32 v193, v173, v191
	v_mul_f32_e32 v191, v175, v191
	v_ashrrev_i32_e32 v141, 11, v168
	v_add_u32_e32 v139, 8, v142
	v_cmp_gt_i32_e32 vcc, s94, v168
	v_mul_f32_e32 v193, 0.15915494, v193
	v_mul_f32_e32 v191, 0.15915494, v191
	s_and_b32 s4, s6, 0xffffffc0
	v_cndmask_b32_e32 v132, v139, v141, vcc
	s_mov_b32 s6, 0x3e000000
	v_fract_f32_e32 v193, v193
	v_fract_f32_e32 v191, v191
	v_add_u32_e32 v132, v136, v132
	v_cos_f32_e32 v220, v193
	v_cos_f32_e32 v221, v191
	v_mad_i64_i32 v[128:129], s[2:3], v132, s7, v[128:129]
	v_lshl_add_u64 v[128:129], v[128:129], 0, v[130:131]
	v_lshl_add_u64 v[132:133], v[128:129], 0, s[12:13]
	v_add_co_u32_e64 v128, s[2:3], s8, v128
	s_ashr_i32 s5, s4, 31
	s_nop 0
	v_addc_co_u32_e64 v129, s[2:3], 0, v129, s[2:3]
	v_ashrrev_i32_e32 v199, 31, v198
	s_lshl_b64 s[2:3], s[4:5], 1
	v_lshl_add_u64 v[200:201], v[200:201], 0, s[2:3]
	v_lshlrev_b64 v[198:199], 1, v[198:199]
	v_lshl_add_u64 v[200:201], v[200:201], 0, v[198:199]
	global_load_dwordx4 v[140:143], v[128:129], off offset:3072
	s_nop 0
	global_load_dwordx4 v[128:131], v[132:133], off offset:528
	global_load_dwordx4 v[136:139], v[132:133], off offset:16
	s_nop 0
	global_load_dwordx4 v[132:135], v[132:133], off offset:512
	v_lshl_add_u64 v[164:165], v[164:165], 0, s[2:3]
	v_lshl_add_u64 v[164:165], v[164:165], 0, v[198:199]
	s_waitcnt vmcnt(7)
; DI u32x2 pack4(const float* v) { u32x2 w; w.x = pk2(v[0], v[1]); w.y = pk2(v[2], v[3]); return w; }
; DI float ex2(float x) { return __builtin_amdgcn_exp2f(x); }
; DI void sincos_rev(float ang, float& s, float& c) { float rev = ang * 0.15915494309189535f; rev = __builtin_amdgcn_fractf(rev); s = __builtin_amdgcn_sinf(rev); c = __builtin_amdgcn_cosf(rev); }
;     template <int PN> DI void body(AccRef acc, const Unit& u, int wr, int wc, int fr, int fq) const {
;     ...
;                 } else if constexpr (PN == 3 || PN == 4) {
;                     bf16_t* dst = PN == 3 ? rq : rk;
;                     const float sc = PN == 3 ? 0.125f : 1.f;
; #pragma unroll
;                     for (int bj = 0; bj < 2; ++bj) {
;                         const int head = 2 * bj + (wc >> 1), i0 = 16 * (wc & 1) + 4 * fq;
;                         float o1[4], o2[4];
; #pragma unroll
;                         for (int j = 0; j < 4; ++j) { float sn, cs; sincos_rev((float)pos * ex2(-(float)(i0 + j) * KEXP64), sn, cs);
;                             o1[j] = (v[bj][j] * cs - v[bj][4 + j] * sn) * sc; o2[j] = (v[bj][j] * sn + v[bj][4 + j] * cs) * sc; }
;                         *(u32x2*)(dst + (size_t)row * 256 + head * 64 + i0) = pack4(o1);
;                         *(u32x2*)(dst + (size_t)row * 256 + head * 64 + 32 + i0) = pack4(o2);
;                     }
	v_pk_fma_f32 v[206:207], v[124:125], v[194:195], v[144:145] op_sel_hi:[1,0,1]
	s_waitcnt vmcnt(6)
	v_pk_fma_f32 v[216:217], v[120:121], v[194:195], v[148:149] op_sel_hi:[1,0,1]
	v_pk_fma_f32 v[228:229], v[122:123], v[194:195], v[150:151] op_sel_hi:[1,0,1]
	v_pk_mul_f32 v[218:219], v[204:205], v[216:217]
	v_pk_mul_f32 v[216:217], v[202:203], v[216:217]
	v_pk_fma_f32 v[218:219], v[202:203], v[206:207], v[218:219]
	v_pk_fma_f32 v[206:207], v[204:205], v[206:207], v[216:217] neg_lo:[0,0,1] neg_hi:[0,0,1]
	v_pk_mul_f32 v[216:217], v[218:219], s[6:7] op_sel_hi:[1,0]
	v_sin_f32_e32 v218, v193
	v_sin_f32_e32 v219, v191
	v_pk_fma_f32 v[222:223], v[126:127], v[194:195], v[146:147] op_sel_hi:[1,0,1]
	v_pk_mul_f32 v[230:231], v[220:221], v[228:229]
	v_pk_mul_f32 v[206:207], v[206:207], s[6:7] op_sel_hi:[1,0]
	v_pk_mul_f32 v[228:229], v[218:219], v[228:229]
	v_pk_fma_f32 v[230:231], v[218:219], v[222:223], v[230:231]
	v_pk_fma_f32 v[222:223], v[220:221], v[222:223], v[228:229] neg_lo:[0,0,1] neg_hi:[0,0,1]
	v_pk_mul_f32 v[230:231], v[230:231], s[6:7] op_sel_hi:[1,0]
	v_pk_mul_f32 v[222:223], v[222:223], s[6:7] op_sel_hi:[1,0]
	v_cvt_pk_bf16_f32 v206, v206, v207
	v_cvt_pk_bf16_f32 v207, v222, v223
	global_store_dwordx2 v[200:201], v[206:207], off
	v_cvt_pk_bf16_f32 v206, v216, v217
	v_cvt_pk_bf16_f32 v207, v230, v231
	s_waitcnt vmcnt(5)
	v_pk_fma_f32 v[216:217], v[112:113], v[194:195], v[152:153] op_sel_hi:[1,0,1]
	v_add_u32_e32 v191, 16, v189
	global_store_dwordx2 v[200:201], v[206:207], off offset:64
	v_pk_fma_f32 v[206:207], v[116:117], v[194:195], v[156:157] op_sel_hi:[1,0,1]
	v_pk_mul_f32 v[222:223], v[204:205], v[216:217]
	v_cvt_f32_u32_e32 v191, v191
	v_pk_fma_f32 v[222:223], v[202:203], v[206:207], v[222:223]
	v_pk_mul_f32 v[202:203], v[202:203], v[216:217]
	v_pk_mul_f32 v[222:223], v[222:223], s[6:7] op_sel_hi:[1,0]
	v_pk_fma_f32 v[202:203], v[204:205], v[206:207], v[202:203] neg_lo:[0,0,1] neg_hi:[0,0,1]
	v_pk_fma_f32 v[204:205], v[118:119], v[194:195], v[158:159] op_sel_hi:[1,0,1]
	v_pk_fma_f32 v[194:195], v[114:115], v[194:195], v[154:155] op_sel_hi:[1,0,1]
	v_mul_f32_e32 v193, v171, v191
	v_pk_mul_f32 v[206:207], v[220:221], v[194:195]
	v_pk_mul_f32 v[194:195], v[218:219], v[194:195]
	v_pk_fma_f32 v[206:207], v[218:219], v[204:205], v[206:207]
	v_pk_fma_f32 v[194:195], v[220:221], v[204:205], v[194:195] neg_lo:[0,0,1] neg_hi:[0,0,1]
	v_pk_mul_f32 v[202:203], v[202:203], s[6:7] op_sel_hi:[1,0]
	v_pk_mul_f32 v[206:207], v[206:207], s[6:7] op_sel_hi:[1,0]
	v_pk_mul_f32 v[194:195], v[194:195], s[6:7] op_sel_hi:[1,0]
	v_mul_f32_e32 v193, 0.15915494, v193
	v_cvt_pk_bf16_f32 v202, v202, v203
	v_cvt_pk_bf16_f32 v203, v194, v195
	v_cvt_pk_bf16_f32 v194, v222, v223
	v_cvt_pk_bf16_f32 v195, v206, v207
	v_fract_f32_e32 v193, v193
	global_store_dwordx2 v[200:201], v[202:203], off offset:256
	global_store_dwordx2 v[200:201], v[194:195], off offset:320
	v_sin_f32_e32 v194, v193
	v_cos_f32_e32 v200, v193
	v_mul_f32_e32 v193, v161, v191
	v_mul_f32_e32 v193, 0.15915494, v193
	v_fract_f32_e32 v193, v193
	v_cos_f32_e32 v201, v193
	v_sin_f32_e32 v195, v193
	v_pk_fma_f32 v[202:203], v[108:109], v[190:191], v[144:145] op_sel_hi:[1,0,1]
	v_pk_fma_f32 v[204:205], v[104:105], v[190:191], v[148:149] op_sel_hi:[1,0,1]
	v_mul_f32_e32 v193, v173, v191
	v_mul_f32_e32 v191, v175, v191
	v_mul_f32_e32 v193, 0.15915494, v193
	v_mul_f32_e32 v191, 0.15915494, v191
	v_pk_mul_f32 v[206:207], v[200:201], v[204:205]
	v_pk_mul_f32 v[204:205], v[194:195], v[204:205]
	v_fract_f32_e32 v193, v193
	v_fract_f32_e32 v191, v191
	v_pk_fma_f32 v[206:207], v[194:195], v[202:203], v[206:207]
	v_pk_fma_f32 v[202:203], v[200:201], v[202:203], v[204:205] neg_lo:[0,0,1] neg_hi:[0,0,1]
	v_sin_f32_e32 v204, v193
	v_cos_f32_e32 v216, v193
	v_cos_f32_e32 v217, v191
	v_sin_f32_e32 v205, v191
	v_pk_fma_f32 v[220:221], v[106:107], v[190:191], v[150:151] op_sel_hi:[1,0,1]
	v_pk_fma_f32 v[218:219], v[110:111], v[190:191], v[146:147] op_sel_hi:[1,0,1]
	v_pk_mul_f32 v[222:223], v[216:217], v[220:221]
	v_pk_mul_f32 v[220:221], v[204:205], v[220:221]
	v_pk_fma_f32 v[222:223], v[204:205], v[218:219], v[222:223]
	v_pk_fma_f32 v[218:219], v[216:217], v[218:219], v[220:221] neg_lo:[0,0,1] neg_hi:[0,0,1]
	v_pk_mul_f32 v[202:203], v[202:203], s[6:7] op_sel_hi:[1,0]
	v_pk_mul_f32 v[218:219], v[218:219], s[6:7] op_sel_hi:[1,0]
	v_pk_mul_f32 v[206:207], v[206:207], s[6:7] op_sel_hi:[1,0]
	v_pk_mul_f32 v[222:223], v[222:223], s[6:7] op_sel_hi:[1,0]
	v_cvt_pk_bf16_f32 v202, v202, v203
	v_cvt_pk_bf16_f32 v203, v218, v219
	global_store_dwordx2 v[164:165], v[202:203], off
	v_cvt_pk_bf16_f32 v202, v206, v207
	v_cvt_pk_bf16_f32 v203, v222, v223
	v_pk_fma_f32 v[206:207], v[96:97], v[190:191], v[152:153] op_sel_hi:[1,0,1]
	global_store_dwordx2 v[164:165], v[202:203], off offset:64
	v_pk_fma_f32 v[202:203], v[100:101], v[190:191], v[156:157] op_sel_hi:[1,0,1]
	v_pk_mul_f32 v[218:219], v[200:201], v[206:207]
	v_add_u32_e32 v193, 32, v189
	v_pk_fma_f32 v[218:219], v[194:195], v[202:203], v[218:219]
	v_pk_mul_f32 v[194:195], v[194:195], v[206:207]
	v_cvt_f32_u32_e32 v193, v193
	v_pk_fma_f32 v[194:195], v[200:201], v[202:203], v[194:195] neg_lo:[0,0,1] neg_hi:[0,0,1]
	v_pk_fma_f32 v[200:201], v[102:103], v[190:191], v[158:159] op_sel_hi:[1,0,1]
	v_pk_fma_f32 v[190:191], v[98:99], v[190:191], v[154:155] op_sel_hi:[1,0,1]
	v_pk_mul_f32 v[218:219], v[218:219], s[6:7] op_sel_hi:[1,0]
	v_pk_mul_f32 v[202:203], v[216:217], v[190:191]
	v_pk_mul_f32 v[190:191], v[204:205], v[190:191]
	v_pk_fma_f32 v[202:203], v[204:205], v[200:201], v[202:203]
	v_pk_fma_f32 v[190:191], v[216:217], v[200:201], v[190:191] neg_lo:[0,0,1] neg_hi:[0,0,1]
; DI u32x2 pack4(const float* v) { u32x2 w; w.x = pk2(v[0], v[1]); w.y = pk2(v[2], v[3]); return w; }
; DI float ex2(float x) { return __builtin_amdgcn_exp2f(x); }
; DI void sincos_rev(float ang, float& s, float& c) { float rev = ang * 0.15915494309189535f; rev = __builtin_amdgcn_fractf(rev); s = __builtin_amdgcn_sinf(rev); c = __builtin_amdgcn_cosf(rev); }
;     template <int PN> DI void body(AccRef acc, const Unit& u, int wr, int wc, int fr, int fq) const {
;     ...
;                 } else if constexpr (PN == 3 || PN == 4) {
;                     bf16_t* dst = PN == 3 ? rq : rk;
;                     const float sc = PN == 3 ? 0.125f : 1.f;
; #pragma unroll
;                     for (int bj = 0; bj < 2; ++bj) {
;                         const int head = 2 * bj + (wc >> 1), i0 = 16 * (wc & 1) + 4 * fq;
;                         float o1[4], o2[4];
; #pragma unroll
;                         for (int j = 0; j < 4; ++j) { float sn, cs; sincos_rev((float)pos * ex2(-(float)(i0 + j) * KEXP64), sn, cs);
;                             o1[j] = (v[bj][j] * cs - v[bj][4 + j] * sn) * sc; o2[j] = (v[bj][j] * sn + v[bj][4 + j] * cs) * sc; }
;                         *(u32x2*)(dst + (size_t)row * 256 + head * 64 + i0) = pack4(o1);
;                         *(u32x2*)(dst + (size_t)row * 256 + head * 64 + 32 + i0) = pack4(o2);
;                     }
	v_pk_mul_f32 v[194:195], v[194:195], s[6:7] op_sel_hi:[1,0]
	v_pk_mul_f32 v[202:203], v[202:203], s[6:7] op_sel_hi:[1,0]
	v_pk_mul_f32 v[190:191], v[190:191], s[6:7] op_sel_hi:[1,0]
	v_cvt_pk_bf16_f32 v194, v194, v195
	v_cvt_pk_bf16_f32 v195, v190, v191
	v_cvt_pk_bf16_f32 v190, v218, v219
	v_cvt_pk_bf16_f32 v191, v202, v203
	global_store_dwordx2 v[164:165], v[194:195], off offset:256
	global_store_dwordx2 v[164:165], v[190:191], off offset:320
	v_lshlrev_b64 v[164:165], 9, v[166:167]
	v_mul_f32_e32 v166, v171, v193
	v_mul_f32_e32 v166, 0.15915494, v166
	v_fract_f32_e32 v167, v166
	v_sin_f32_e32 v166, v167
	v_cos_f32_e32 v190, v167
	v_mul_f32_e32 v167, v161, v193
	v_mul_f32_e32 v167, 0.15915494, v167
	v_fract_f32_e32 v167, v167
	v_cos_f32_e32 v191, v167
	v_sin_f32_e32 v167, v167
	v_mul_f32_e32 v197, v173, v193
	v_mul_f32_e32 v193, v175, v193
	v_pk_fma_f32 v[200:201], v[88:89], v[174:175], v[148:149] op_sel_hi:[1,0,1]
	v_mul_f32_e32 v197, 0.15915494, v197
	v_mul_f32_e32 v193, 0.15915494, v193
	v_pk_fma_f32 v[194:195], v[92:93], v[174:175], v[144:145] op_sel_hi:[1,0,1]
	v_pk_mul_f32 v[202:203], v[190:191], v[200:201]
	v_pk_mul_f32 v[200:201], v[166:167], v[200:201]
	v_fract_f32_e32 v197, v197
	v_fract_f32_e32 v193, v193
	v_pk_fma_f32 v[202:203], v[166:167], v[194:195], v[202:203]
	v_pk_fma_f32 v[194:195], v[190:191], v[194:195], v[200:201] neg_lo:[0,0,1] neg_hi:[0,0,1]
	v_sin_f32_e32 v200, v197
	v_cos_f32_e32 v204, v197
	v_cos_f32_e32 v205, v193
	v_sin_f32_e32 v201, v193
	v_pk_fma_f32 v[216:217], v[90:91], v[174:175], v[150:151] op_sel_hi:[1,0,1]
	v_pk_fma_f32 v[206:207], v[94:95], v[174:175], v[146:147] op_sel_hi:[1,0,1]
	v_pk_mul_f32 v[218:219], v[204:205], v[216:217]
	v_pk_mul_f32 v[216:217], v[200:201], v[216:217]
	v_lshl_add_u64 v[164:165], s[16:17], 0, v[164:165]
	v_pk_fma_f32 v[218:219], v[200:201], v[206:207], v[218:219]
	v_pk_fma_f32 v[206:207], v[204:205], v[206:207], v[216:217] neg_lo:[0,0,1] neg_hi:[0,0,1]
	v_pk_mul_f32 v[194:195], v[194:195], s[6:7] op_sel_hi:[1,0]
	v_pk_mul_f32 v[206:207], v[206:207], s[6:7] op_sel_hi:[1,0]
	v_lshl_add_u64 v[164:165], v[164:165], 0, s[2:3]
	v_pk_mul_f32 v[202:203], v[202:203], s[6:7] op_sel_hi:[1,0]
	v_pk_mul_f32 v[218:219], v[218:219], s[6:7] op_sel_hi:[1,0]
	v_cvt_pk_bf16_f32 v194, v194, v195
	v_cvt_pk_bf16_f32 v195, v206, v207
	v_lshl_add_u64 v[164:165], v[164:165], 0, v[198:199]
	global_store_dwordx2 v[164:165], v[194:195], off
	v_cvt_pk_bf16_f32 v194, v202, v203
	v_cvt_pk_bf16_f32 v195, v218, v219
	v_pk_fma_f32 v[202:203], v[80:81], v[174:175], v[152:153] op_sel_hi:[1,0,1]
	global_store_dwordx2 v[164:165], v[194:195], off offset:64
	v_pk_fma_f32 v[194:195], v[84:85], v[174:175], v[156:157] op_sel_hi:[1,0,1]
	v_pk_mul_f32 v[206:207], v[190:191], v[202:203]
	v_pk_fma_f32 v[148:149], v[72:73], v[170:171], v[148:149] op_sel_hi:[1,0,1]
	v_pk_fma_f32 v[206:207], v[166:167], v[194:195], v[206:207]
	v_pk_mul_f32 v[166:167], v[166:167], v[202:203]
	v_pk_mul_f32 v[206:207], v[206:207], s[6:7] op_sel_hi:[1,0]
	v_pk_fma_f32 v[166:167], v[190:191], v[194:195], v[166:167] neg_lo:[0,0,1] neg_hi:[0,0,1]
	v_pk_fma_f32 v[194:195], v[82:83], v[174:175], v[154:155] op_sel_hi:[1,0,1]
	v_pk_fma_f32 v[190:191], v[86:87], v[174:175], v[158:159] op_sel_hi:[1,0,1]
	v_pk_mul_f32 v[202:203], v[204:205], v[194:195]
	v_pk_mul_f32 v[194:195], v[200:201], v[194:195]
	v_add_u32_e32 v174, 48, v189
	v_pk_fma_f32 v[202:203], v[200:201], v[190:191], v[202:203]
	v_pk_fma_f32 v[190:191], v[204:205], v[190:191], v[194:195] neg_lo:[0,0,1] neg_hi:[0,0,1]
	v_cvt_f32_u32_e32 v174, v174
	v_pk_mul_f32 v[166:167], v[166:167], s[6:7] op_sel_hi:[1,0]
	v_pk_mul_f32 v[190:191], v[190:191], s[6:7] op_sel_hi:[1,0]
	v_pk_mul_f32 v[202:203], v[202:203], s[6:7] op_sel_hi:[1,0]
	v_cvt_pk_bf16_f32 v166, v166, v167
	v_cvt_pk_bf16_f32 v167, v190, v191
	global_store_dwordx2 v[164:165], v[166:167], off offset:256
	v_cvt_pk_bf16_f32 v166, v206, v207
	v_cvt_pk_bf16_f32 v167, v202, v203
	global_store_dwordx2 v[164:165], v[166:167], off offset:320
	v_mul_f32_e32 v164, v171, v174
	v_mul_f32_e32 v164, 0.15915494, v164
	v_fract_f32_e32 v165, v164
	v_sin_f32_e32 v164, v165
	v_cos_f32_e32 v166, v165
	v_mul_f32_e32 v165, v161, v174
	v_mul_f32_e32 v165, 0.15915494, v165
	v_fract_f32_e32 v165, v165
	v_cos_f32_e32 v167, v165
	v_sin_f32_e32 v165, v165
	v_pk_fma_f32 v[144:145], v[76:77], v[170:171], v[144:145] op_sel_hi:[1,0,1]
	v_pk_fma_f32 v[150:151], v[74:75], v[170:171], v[150:151] op_sel_hi:[1,0,1]
	v_pk_mul_f32 v[190:191], v[166:167], v[148:149]
	v_pk_mul_f32 v[148:149], v[164:165], v[148:149]
	v_pk_fma_f32 v[190:191], v[164:165], v[144:145], v[190:191]
	v_pk_fma_f32 v[144:145], v[166:167], v[144:145], v[148:149] neg_lo:[0,0,1] neg_hi:[0,0,1]
	v_mul_f32_e32 v148, v173, v174
	v_mul_f32_e32 v148, 0.15915494, v148
	v_fract_f32_e32 v149, v148
	v_sin_f32_e32 v148, v149
	v_cos_f32_e32 v194, v149
	v_mul_f32_e32 v149, v175, v174
	v_mul_f32_e32 v149, 0.15915494, v149
	v_fract_f32_e32 v149, v149
	v_cos_f32_e32 v195, v149
	v_sin_f32_e32 v149, v149
	v_pk_fma_f32 v[146:147], v[78:79], v[170:171], v[146:147] op_sel_hi:[1,0,1]
	v_pk_mul_f32 v[144:145], v[144:145], s[6:7] op_sel_hi:[1,0]
	v_pk_mul_f32 v[200:201], v[194:195], v[150:151]
	v_pk_mul_f32 v[150:151], v[148:149], v[150:151]
	v_pk_fma_f32 v[200:201], v[148:149], v[146:147], v[200:201]
	v_pk_fma_f32 v[146:147], v[194:195], v[146:147], v[150:151] neg_lo:[0,0,1] neg_hi:[0,0,1]
	v_cvt_pk_bf16_f32 v144, v144, v145
	v_pk_mul_f32 v[146:147], v[146:147], s[6:7] op_sel_hi:[1,0]
	v_pk_mul_f32 v[190:191], v[190:191], s[6:7] op_sel_hi:[1,0]
	v_cvt_pk_bf16_f32 v145, v146, v147
	v_lshl_add_u64 v[146:147], v[162:163], 0, s[2:3]
; DI u32x2 pack4(const float* v) { u32x2 w; w.x = pk2(v[0], v[1]); w.y = pk2(v[2], v[3]); return w; }
; DI float ex2(float x) { return __builtin_amdgcn_exp2f(x); }
; DI void sincos_rev(float ang, float& s, float& c) { float rev = ang * 0.15915494309189535f; rev = __builtin_amdgcn_fractf(rev); s = __builtin_amdgcn_sinf(rev); c = __builtin_amdgcn_cosf(rev); }
;     template <int PN> DI void body(AccRef acc, const Unit& u, int wr, int wc, int fr, int fq) const {
;     ...
;                 } else if constexpr (PN == 3 || PN == 4) {
;                     bf16_t* dst = PN == 3 ? rq : rk;
;                     const float sc = PN == 3 ? 0.125f : 1.f;
; #pragma unroll
;                     for (int bj = 0; bj < 2; ++bj) {
;                         const int head = 2 * bj + (wc >> 1), i0 = 16 * (wc & 1) + 4 * fq;
;                         float o1[4], o2[4];
; #pragma unroll
;                         for (int j = 0; j < 4; ++j) { float sn, cs; sincos_rev((float)pos * ex2(-(float)(i0 + j) * KEXP64), sn, cs);
;                             o1[j] = (v[bj][j] * cs - v[bj][4 + j] * sn) * sc; o2[j] = (v[bj][j] * sn + v[bj][4 + j] * cs) * sc; }
;                         *(u32x2*)(dst + (size_t)row * 256 + head * 64 + i0) = pack4(o1);
;                         *(u32x2*)(dst + (size_t)row * 256 + head * 64 + 32 + i0) = pack4(o2);
;                     }
	v_pk_mul_f32 v[200:201], v[200:201], s[6:7] op_sel_hi:[1,0]
	v_lshl_add_u64 v[146:147], v[146:147], 0, v[198:199]
	global_store_dwordx2 v[146:147], v[144:145], off
	v_cvt_pk_bf16_f32 v144, v190, v191
	v_cvt_pk_bf16_f32 v145, v200, v201
	v_pk_fma_f32 v[150:151], v[64:65], v[170:171], v[152:153] op_sel_hi:[1,0,1]
	global_store_dwordx2 v[146:147], v[144:145], off offset:64
	v_pk_fma_f32 v[144:145], v[68:69], v[170:171], v[156:157] op_sel_hi:[1,0,1]
	v_pk_mul_f32 v[152:153], v[166:167], v[150:151]
	v_pk_mul_f32 v[150:151], v[164:165], v[150:151]
	v_pk_fma_f32 v[154:155], v[66:67], v[170:171], v[154:155] op_sel_hi:[1,0,1]
	v_pk_fma_f32 v[152:153], v[164:165], v[144:145], v[152:153]
	v_pk_fma_f32 v[144:145], v[166:167], v[144:145], v[150:151] neg_lo:[0,0,1] neg_hi:[0,0,1]
	v_pk_fma_f32 v[150:151], v[70:71], v[170:171], v[158:159] op_sel_hi:[1,0,1]
	v_pk_mul_f32 v[156:157], v[194:195], v[154:155]
	v_pk_mul_f32 v[144:145], v[144:145], s[6:7] op_sel_hi:[1,0]
	v_pk_fma_f32 v[156:157], v[148:149], v[150:151], v[156:157]
	v_pk_mul_f32 v[148:149], v[148:149], v[154:155]
	v_pk_mul_f32 v[152:153], v[152:153], s[6:7] op_sel_hi:[1,0]
	v_pk_fma_f32 v[148:149], v[194:195], v[150:151], v[148:149] neg_lo:[0,0,1] neg_hi:[0,0,1]
	v_pk_mul_f32 v[156:157], v[156:157], s[6:7] op_sel_hi:[1,0]
	v_pk_mul_f32 v[148:149], v[148:149], s[6:7] op_sel_hi:[1,0]
	v_cvt_pk_bf16_f32 v144, v144, v145
	v_cvt_pk_bf16_f32 v145, v148, v149
	global_store_dwordx2 v[146:147], v[144:145], off offset:256
	v_cvt_pk_bf16_f32 v144, v152, v153
	v_cvt_pk_bf16_f32 v145, v156, v157
	global_store_dwordx2 v[146:147], v[144:145], off offset:320
	v_and_b32_e32 v144, 0x7ff, v168
	v_cndmask_b32_e32 v166, v169, v144, vcc
	v_cvt_f32_u32_e32 v157, v166
	s_waitcnt vmcnt(17)
	v_pk_fma_f32 v[152:153], v[56:57], v[196:197], v[136:137] op_sel_hi:[1,0,1]
	v_pk_fma_f32 v[150:151], v[60:61], v[196:197], v[140:141] op_sel_hi:[1,0,1]
	v_ashrrev_i32_e32 v169, 31, v168
	v_mul_f32_e32 v146, v171, v157
	v_mul_f32_e32 v146, 0.15915494, v146
	v_fract_f32_e32 v147, v146
	v_sin_f32_e32 v146, v147
	v_cos_f32_e32 v148, v147
	v_mul_f32_e32 v147, v161, v157
	v_mul_f32_e32 v147, 0.15915494, v147
	v_fract_f32_e32 v147, v147
	v_cos_f32_e32 v149, v147
	v_sin_f32_e32 v147, v147
	v_pk_fma_f32 v[162:163], v[58:59], v[196:197], v[138:139] op_sel_hi:[1,0,1]
	v_lshlrev_b64 v[144:145], 9, v[168:169]
	v_pk_mul_f32 v[154:155], v[148:149], v[152:153]
	v_pk_mul_f32 v[152:153], v[146:147], v[152:153]
	v_pk_fma_f32 v[154:155], v[146:147], v[150:151], v[154:155]
	v_pk_fma_f32 v[150:151], v[148:149], v[150:151], v[152:153] neg_lo:[0,0,1] neg_hi:[0,0,1]
	v_mul_f32_e32 v152, v173, v157
	v_mul_f32_e32 v152, 0.15915494, v152
	v_fract_f32_e32 v153, v152
	v_sin_f32_e32 v152, v153
	v_cos_f32_e32 v156, v153
	v_mul_f32_e32 v153, v175, v157
	v_mul_f32_e32 v153, 0.15915494, v153
	v_fract_f32_e32 v153, v153
	v_cos_f32_e32 v157, v153
	v_sin_f32_e32 v153, v153
	v_pk_fma_f32 v[158:159], v[62:63], v[196:197], v[142:143] op_sel_hi:[1,0,1]
	v_lshl_add_u64 v[144:145], s[16:17], 0, v[144:145]
	v_pk_mul_f32 v[164:165], v[156:157], v[162:163]
	v_pk_mul_f32 v[162:163], v[152:153], v[162:163]
	v_pk_fma_f32 v[164:165], v[152:153], v[158:159], v[164:165]
	v_pk_fma_f32 v[158:159], v[156:157], v[158:159], v[162:163] neg_lo:[0,0,1] neg_hi:[0,0,1]
	v_pk_mul_f32 v[150:151], v[150:151], s[6:7] op_sel_hi:[1,0]
	v_pk_mul_f32 v[158:159], v[158:159], s[6:7] op_sel_hi:[1,0]
	v_lshl_add_u64 v[144:145], v[144:145], 0, s[2:3]
	v_pk_mul_f32 v[154:155], v[154:155], s[6:7] op_sel_hi:[1,0]
	v_pk_mul_f32 v[164:165], v[164:165], s[6:7] op_sel_hi:[1,0]
	v_cvt_pk_bf16_f32 v150, v150, v151
	v_cvt_pk_bf16_f32 v151, v158, v159
	v_lshl_add_u64 v[144:145], v[144:145], 0, v[198:199]
	global_store_dwordx2 v[144:145], v[150:151], off
	v_cvt_pk_bf16_f32 v150, v154, v155
	v_cvt_pk_bf16_f32 v151, v164, v165
	v_pk_fma_f32 v[154:155], v[48:49], v[196:197], v[128:129] op_sel_hi:[1,0,1]
	global_store_dwordx2 v[144:145], v[150:151], off offset:64
	s_waitcnt vmcnt(18)
	v_pk_fma_f32 v[150:151], v[52:53], v[196:197], v[132:133] op_sel_hi:[1,0,1]
	v_pk_mul_f32 v[158:159], v[148:149], v[154:155]
	v_pk_fma_f32 v[162:163], v[42:43], v[192:193], v[138:139] op_sel_hi:[1,0,1]
	v_pk_fma_f32 v[158:159], v[146:147], v[150:151], v[158:159]
	v_pk_mul_f32 v[146:147], v[146:147], v[154:155]
	v_pk_mul_f32 v[158:159], v[158:159], s[6:7] op_sel_hi:[1,0]
	v_pk_fma_f32 v[146:147], v[148:149], v[150:151], v[146:147] neg_lo:[0,0,1] neg_hi:[0,0,1]
	v_pk_fma_f32 v[150:151], v[50:51], v[196:197], v[130:131] op_sel_hi:[1,0,1]
	v_pk_fma_f32 v[148:149], v[54:55], v[196:197], v[134:135] op_sel_hi:[1,0,1]
	v_pk_mul_f32 v[154:155], v[156:157], v[150:151]
	v_pk_mul_f32 v[150:151], v[152:153], v[150:151]
	v_pk_fma_f32 v[154:155], v[152:153], v[148:149], v[154:155]
	v_pk_fma_f32 v[148:149], v[156:157], v[148:149], v[150:151] neg_lo:[0,0,1] neg_hi:[0,0,1]
	v_pk_mul_f32 v[146:147], v[146:147], s[6:7] op_sel_hi:[1,0]
	v_pk_mul_f32 v[148:149], v[148:149], s[6:7] op_sel_hi:[1,0]
	v_pk_mul_f32 v[154:155], v[154:155], s[6:7] op_sel_hi:[1,0]
	v_cvt_pk_bf16_f32 v146, v146, v147
	v_cvt_pk_bf16_f32 v147, v148, v149
	global_store_dwordx2 v[144:145], v[146:147], off offset:256
	v_cvt_pk_bf16_f32 v146, v158, v159
	v_cvt_pk_bf16_f32 v147, v154, v155
	global_store_dwordx2 v[144:145], v[146:147], off offset:320
	v_add_u32_e32 v145, 16, v166
	v_cvt_f32_u32_e32 v157, v145
	v_pk_fma_f32 v[152:153], v[40:41], v[192:193], v[136:137] op_sel_hi:[1,0,1]
	v_pk_fma_f32 v[150:151], v[44:45], v[192:193], v[140:141] op_sel_hi:[1,0,1]
	v_add_u32_e32 v144, 0x90, v160
	v_mul_f32_e32 v146, v171, v157
	v_mul_f32_e32 v146, 0.15915494, v146
	v_fract_f32_e32 v147, v146
; DI u32x2 pack4(const float* v) { u32x2 w; w.x = pk2(v[0], v[1]); w.y = pk2(v[2], v[3]); return w; }
; DI float ex2(float x) { return __builtin_amdgcn_exp2f(x); }
; DI void sincos_rev(float ang, float& s, float& c) { float rev = ang * 0.15915494309189535f; rev = __builtin_amdgcn_fractf(rev); s = __builtin_amdgcn_sinf(rev); c = __builtin_amdgcn_cosf(rev); }
;     template <int PN> DI void body(AccRef acc, const Unit& u, int wr, int wc, int fr, int fq) const {
;     ...
;                 } else if constexpr (PN == 3 || PN == 4) {
;                     bf16_t* dst = PN == 3 ? rq : rk;
;                     const float sc = PN == 3 ? 0.125f : 1.f;
; #pragma unroll
;                     for (int bj = 0; bj < 2; ++bj) {
;                         const int head = 2 * bj + (wc >> 1), i0 = 16 * (wc & 1) + 4 * fq;
;                         float o1[4], o2[4];
; #pragma unroll
;                         for (int j = 0; j < 4; ++j) { float sn, cs; sincos_rev((float)pos * ex2(-(float)(i0 + j) * KEXP64), sn, cs);
;                             o1[j] = (v[bj][j] * cs - v[bj][4 + j] * sn) * sc; o2[j] = (v[bj][j] * sn + v[bj][4 + j] * cs) * sc; }
;                         *(u32x2*)(dst + (size_t)row * 256 + head * 64 + i0) = pack4(o1);
;                         *(u32x2*)(dst + (size_t)row * 256 + head * 64 + 32 + i0) = pack4(o2);
;                     }
	v_sin_f32_e32 v146, v147
	v_cos_f32_e32 v148, v147
	v_mul_f32_e32 v147, v161, v157
	v_mul_f32_e32 v147, 0.15915494, v147
	v_fract_f32_e32 v147, v147
	v_cos_f32_e32 v149, v147
	v_sin_f32_e32 v147, v147
	v_ashrrev_i32_e32 v145, 31, v144
	v_lshlrev_b64 v[144:145], 9, v[144:145]
	v_pk_mul_f32 v[154:155], v[148:149], v[152:153]
	v_pk_mul_f32 v[152:153], v[146:147], v[152:153]
	v_pk_fma_f32 v[154:155], v[146:147], v[150:151], v[154:155]
	v_pk_fma_f32 v[150:151], v[148:149], v[150:151], v[152:153] neg_lo:[0,0,1] neg_hi:[0,0,1]
	v_mul_f32_e32 v152, v173, v157
	v_mul_f32_e32 v152, 0.15915494, v152
	v_fract_f32_e32 v153, v152
	v_sin_f32_e32 v152, v153
	v_cos_f32_e32 v156, v153
	v_mul_f32_e32 v153, v175, v157
	v_mul_f32_e32 v153, 0.15915494, v153
	v_fract_f32_e32 v153, v153
	v_cos_f32_e32 v157, v153
	v_sin_f32_e32 v153, v153
	v_pk_fma_f32 v[158:159], v[46:47], v[192:193], v[142:143] op_sel_hi:[1,0,1]
	v_lshl_add_u64 v[144:145], s[16:17], 0, v[144:145]
	v_pk_mul_f32 v[164:165], v[156:157], v[162:163]
	v_pk_mul_f32 v[162:163], v[152:153], v[162:163]
	v_pk_fma_f32 v[164:165], v[152:153], v[158:159], v[164:165]
	v_pk_fma_f32 v[158:159], v[156:157], v[158:159], v[162:163] neg_lo:[0,0,1] neg_hi:[0,0,1]
	v_pk_mul_f32 v[150:151], v[150:151], s[6:7] op_sel_hi:[1,0]
	v_pk_mul_f32 v[158:159], v[158:159], s[6:7] op_sel_hi:[1,0]
	v_lshl_add_u64 v[144:145], v[144:145], 0, s[2:3]
	v_pk_mul_f32 v[154:155], v[154:155], s[6:7] op_sel_hi:[1,0]
	v_pk_mul_f32 v[164:165], v[164:165], s[6:7] op_sel_hi:[1,0]
	v_cvt_pk_bf16_f32 v150, v150, v151
	v_cvt_pk_bf16_f32 v151, v158, v159
	v_lshl_add_u64 v[144:145], v[144:145], 0, v[198:199]
	global_store_dwordx2 v[144:145], v[150:151], off
	v_cvt_pk_bf16_f32 v150, v154, v155
	v_cvt_pk_bf16_f32 v151, v164, v165
	v_pk_fma_f32 v[154:155], v[28:29], v[192:193], v[128:129] op_sel_hi:[1,0,1]
	global_store_dwordx2 v[144:145], v[150:151], off offset:64
	v_pk_fma_f32 v[150:151], v[36:37], v[192:193], v[132:133] op_sel_hi:[1,0,1]
	v_pk_mul_f32 v[158:159], v[148:149], v[154:155]
	v_pk_fma_f32 v[162:163], v[26:27], v[188:189], v[138:139] op_sel_hi:[1,0,1]
	v_pk_fma_f32 v[158:159], v[146:147], v[150:151], v[158:159]
	v_pk_mul_f32 v[146:147], v[146:147], v[154:155]
	v_pk_mul_f32 v[158:159], v[158:159], s[6:7] op_sel_hi:[1,0]
	v_pk_fma_f32 v[146:147], v[148:149], v[150:151], v[146:147] neg_lo:[0,0,1] neg_hi:[0,0,1]
	v_pk_fma_f32 v[150:151], v[30:31], v[192:193], v[130:131] op_sel_hi:[1,0,1]
	v_pk_fma_f32 v[148:149], v[38:39], v[192:193], v[134:135] op_sel_hi:[1,0,1]
	v_pk_mul_f32 v[154:155], v[156:157], v[150:151]
	v_pk_mul_f32 v[150:151], v[152:153], v[150:151]
	v_pk_fma_f32 v[154:155], v[152:153], v[148:149], v[154:155]
	v_pk_fma_f32 v[148:149], v[156:157], v[148:149], v[150:151] neg_lo:[0,0,1] neg_hi:[0,0,1]
	v_pk_mul_f32 v[146:147], v[146:147], s[6:7] op_sel_hi:[1,0]
	v_pk_mul_f32 v[148:149], v[148:149], s[6:7] op_sel_hi:[1,0]
	v_pk_mul_f32 v[154:155], v[154:155], s[6:7] op_sel_hi:[1,0]
	v_cvt_pk_bf16_f32 v146, v146, v147
	v_cvt_pk_bf16_f32 v147, v148, v149
	global_store_dwordx2 v[144:145], v[146:147], off offset:256
	v_cvt_pk_bf16_f32 v146, v158, v159
	v_cvt_pk_bf16_f32 v147, v154, v155
	global_store_dwordx2 v[144:145], v[146:147], off offset:320
	v_add_u32_e32 v145, 32, v166
	v_cvt_f32_u32_e32 v157, v145
	v_pk_fma_f32 v[152:153], v[24:25], v[188:189], v[136:137] op_sel_hi:[1,0,1]
	v_pk_fma_f32 v[150:151], v[32:33], v[188:189], v[140:141] op_sel_hi:[1,0,1]
	v_add_u32_e32 v144, 0xa0, v160
	v_mul_f32_e32 v146, v171, v157
	v_mul_f32_e32 v146, 0.15915494, v146
	v_fract_f32_e32 v147, v146
	v_sin_f32_e32 v146, v147
	v_cos_f32_e32 v148, v147
	v_mul_f32_e32 v147, v161, v157
	v_mul_f32_e32 v147, 0.15915494, v147
	v_fract_f32_e32 v147, v147
	v_cos_f32_e32 v149, v147
	v_sin_f32_e32 v147, v147
	v_ashrrev_i32_e32 v145, 31, v144
	v_lshlrev_b64 v[144:145], 9, v[144:145]
	v_pk_mul_f32 v[154:155], v[148:149], v[152:153]
	v_pk_mul_f32 v[152:153], v[146:147], v[152:153]
	v_pk_fma_f32 v[154:155], v[146:147], v[150:151], v[154:155]
	v_pk_fma_f32 v[150:151], v[148:149], v[150:151], v[152:153] neg_lo:[0,0,1] neg_hi:[0,0,1]
	v_mul_f32_e32 v152, v173, v157
	v_mul_f32_e32 v152, 0.15915494, v152
	v_fract_f32_e32 v153, v152
	v_sin_f32_e32 v152, v153
	v_cos_f32_e32 v156, v153
	v_mul_f32_e32 v153, v175, v157
	v_mul_f32_e32 v153, 0.15915494, v153
	v_fract_f32_e32 v153, v153
	v_cos_f32_e32 v157, v153
	v_sin_f32_e32 v153, v153
	v_pk_fma_f32 v[158:159], v[34:35], v[188:189], v[142:143] op_sel_hi:[1,0,1]
	v_lshl_add_u64 v[144:145], s[16:17], 0, v[144:145]
	v_pk_mul_f32 v[164:165], v[156:157], v[162:163]
	v_pk_mul_f32 v[162:163], v[152:153], v[162:163]
	v_pk_fma_f32 v[164:165], v[152:153], v[158:159], v[164:165]
	v_pk_fma_f32 v[158:159], v[156:157], v[158:159], v[162:163] neg_lo:[0,0,1] neg_hi:[0,0,1]
	v_pk_mul_f32 v[150:151], v[150:151], s[6:7] op_sel_hi:[1,0]
	v_pk_mul_f32 v[158:159], v[158:159], s[6:7] op_sel_hi:[1,0]
	v_lshl_add_u64 v[144:145], v[144:145], 0, s[2:3]
	v_pk_mul_f32 v[154:155], v[154:155], s[6:7] op_sel_hi:[1,0]
	v_pk_mul_f32 v[164:165], v[164:165], s[6:7] op_sel_hi:[1,0]
	v_cvt_pk_bf16_f32 v150, v150, v151
	v_cvt_pk_bf16_f32 v151, v158, v159
	v_lshl_add_u64 v[144:145], v[144:145], 0, v[198:199]
	global_store_dwordx2 v[144:145], v[150:151], off
	v_cvt_pk_bf16_f32 v150, v154, v155
	v_cvt_pk_bf16_f32 v151, v164, v165
	v_pk_fma_f32 v[154:155], v[16:17], v[188:189], v[128:129] op_sel_hi:[1,0,1]
	global_store_dwordx2 v[144:145], v[150:151], off offset:64
	v_pk_fma_f32 v[150:151], v[20:21], v[188:189], v[132:133] op_sel_hi:[1,0,1]
	v_pk_mul_f32 v[158:159], v[148:149], v[154:155]
	v_pk_fma_f32 v[136:137], v[8:9], v[172:173], v[136:137] op_sel_hi:[1,0,1]
; DI u32x2 pack4(const float* v) { u32x2 w; w.x = pk2(v[0], v[1]); w.y = pk2(v[2], v[3]); return w; }
; DI float ex2(float x) { return __builtin_amdgcn_exp2f(x); }
; DI void sincos_rev(float ang, float& s, float& c) { float rev = ang * 0.15915494309189535f; rev = __builtin_amdgcn_fractf(rev); s = __builtin_amdgcn_sinf(rev); c = __builtin_amdgcn_cosf(rev); }
;     template <int PN> DI void body(AccRef acc, const Unit& u, int wr, int wc, int fr, int fq) const {
;     ...
;                 } else if constexpr (PN == 3 || PN == 4) {
;                     bf16_t* dst = PN == 3 ? rq : rk;
;                     const float sc = PN == 3 ? 0.125f : 1.f;
; #pragma unroll
;                     for (int bj = 0; bj < 2; ++bj) {
;                         const int head = 2 * bj + (wc >> 1), i0 = 16 * (wc & 1) + 4 * fq;
;                         float o1[4], o2[4];
; #pragma unroll
;                         for (int j = 0; j < 4; ++j) { float sn, cs; sincos_rev((float)pos * ex2(-(float)(i0 + j) * KEXP64), sn, cs);
;                             o1[j] = (v[bj][j] * cs - v[bj][4 + j] * sn) * sc; o2[j] = (v[bj][j] * sn + v[bj][4 + j] * cs) * sc; }
;                         *(u32x2*)(dst + (size_t)row * 256 + head * 64 + i0) = pack4(o1);
;                         *(u32x2*)(dst + (size_t)row * 256 + head * 64 + 32 + i0) = pack4(o2);
;                     }
	v_pk_fma_f32 v[158:159], v[146:147], v[150:151], v[158:159]
	v_pk_mul_f32 v[146:147], v[146:147], v[154:155]
	v_pk_mul_f32 v[158:159], v[158:159], s[6:7] op_sel_hi:[1,0]
	v_pk_fma_f32 v[146:147], v[148:149], v[150:151], v[146:147] neg_lo:[0,0,1] neg_hi:[0,0,1]
	v_pk_fma_f32 v[150:151], v[18:19], v[188:189], v[130:131] op_sel_hi:[1,0,1]
	v_pk_fma_f32 v[148:149], v[22:23], v[188:189], v[134:135] op_sel_hi:[1,0,1]
	v_pk_mul_f32 v[154:155], v[156:157], v[150:151]
	v_pk_mul_f32 v[150:151], v[152:153], v[150:151]
	v_pk_fma_f32 v[154:155], v[152:153], v[148:149], v[154:155]
	v_pk_fma_f32 v[148:149], v[156:157], v[148:149], v[150:151] neg_lo:[0,0,1] neg_hi:[0,0,1]
	v_pk_mul_f32 v[146:147], v[146:147], s[6:7] op_sel_hi:[1,0]
	v_pk_mul_f32 v[148:149], v[148:149], s[6:7] op_sel_hi:[1,0]
	v_pk_mul_f32 v[154:155], v[154:155], s[6:7] op_sel_hi:[1,0]
	v_cvt_pk_bf16_f32 v146, v146, v147
	v_cvt_pk_bf16_f32 v147, v148, v149
	global_store_dwordx2 v[144:145], v[146:147], off offset:256
	v_cvt_pk_bf16_f32 v146, v158, v159
	v_cvt_pk_bf16_f32 v147, v154, v155
	global_store_dwordx2 v[144:145], v[146:147], off offset:320
	v_add_u32_e32 v145, 48, v166
	v_cvt_f32_u32_e32 v153, v145
	v_pk_fma_f32 v[140:141], v[12:13], v[172:173], v[140:141] op_sel_hi:[1,0,1]
	v_add_u32_e32 v144, 0xb0, v160
	v_pk_fma_f32 v[138:139], v[10:11], v[172:173], v[138:139] op_sel_hi:[1,0,1]
	v_mul_f32_e32 v146, v171, v153
	v_mul_f32_e32 v146, 0.15915494, v146
	v_fract_f32_e32 v147, v146
	v_sin_f32_e32 v146, v147
	v_cos_f32_e32 v148, v147
	v_mul_f32_e32 v147, v161, v153
	v_mul_f32_e32 v147, 0.15915494, v147
	v_fract_f32_e32 v147, v147
	v_cos_f32_e32 v149, v147
	v_sin_f32_e32 v147, v147
	v_ashrrev_i32_e32 v145, 31, v144
	v_pk_fma_f32 v[142:143], v[14:15], v[172:173], v[142:143] op_sel_hi:[1,0,1]
	v_pk_mul_f32 v[150:151], v[148:149], v[136:137]
	v_pk_mul_f32 v[136:137], v[146:147], v[136:137]
	v_pk_fma_f32 v[150:151], v[146:147], v[140:141], v[150:151]
	v_pk_fma_f32 v[136:137], v[148:149], v[140:141], v[136:137] neg_lo:[0,0,1] neg_hi:[0,0,1]
	v_mul_f32_e32 v140, v173, v153
	v_mul_f32_e32 v140, 0.15915494, v140
	v_fract_f32_e32 v141, v140
	v_sin_f32_e32 v140, v141
	v_cos_f32_e32 v152, v141
	v_mul_f32_e32 v141, v175, v153
	v_mul_f32_e32 v141, 0.15915494, v141
	v_fract_f32_e32 v141, v141
	v_cos_f32_e32 v153, v141
	v_sin_f32_e32 v141, v141
	v_lshlrev_b64 v[144:145], 9, v[144:145]
	v_lshl_add_u64 v[144:145], s[16:17], 0, v[144:145]
	v_pk_mul_f32 v[154:155], v[152:153], v[138:139]
	v_pk_mul_f32 v[138:139], v[140:141], v[138:139]
	v_pk_mul_f32 v[136:137], v[136:137], s[6:7] op_sel_hi:[1,0]
	v_pk_fma_f32 v[138:139], v[152:153], v[142:143], v[138:139] neg_lo:[0,0,1] neg_hi:[0,0,1]
	v_pk_fma_f32 v[154:155], v[140:141], v[142:143], v[154:155]
	v_pk_mul_f32 v[138:139], v[138:139], s[6:7] op_sel_hi:[1,0]
	v_cvt_pk_bf16_f32 v136, v136, v137
	v_cvt_pk_bf16_f32 v137, v138, v139
	v_lshl_add_u64 v[138:139], v[144:145], 0, s[2:3]
	v_pk_mul_f32 v[150:151], v[150:151], s[6:7] op_sel_hi:[1,0]
	v_pk_mul_f32 v[154:155], v[154:155], s[6:7] op_sel_hi:[1,0]
	v_lshl_add_u64 v[138:139], v[138:139], 0, v[198:199]
	global_store_dwordx2 v[138:139], v[136:137], off
	v_cvt_pk_bf16_f32 v136, v150, v151
	v_cvt_pk_bf16_f32 v137, v154, v155
	v_pk_fma_f32 v[128:129], v[0:1], v[172:173], v[128:129] op_sel_hi:[1,0,1]
	global_store_dwordx2 v[138:139], v[136:137], off offset:64
	v_pk_fma_f32 v[132:133], v[4:5], v[172:173], v[132:133] op_sel_hi:[1,0,1]
	v_pk_mul_f32 v[136:137], v[148:149], v[128:129]
	v_pk_mul_f32 v[128:129], v[146:147], v[128:129]
	v_pk_fma_f32 v[130:131], v[2:3], v[172:173], v[130:131] op_sel_hi:[1,0,1]
	v_pk_fma_f32 v[136:137], v[146:147], v[132:133], v[136:137]
	v_pk_fma_f32 v[128:129], v[148:149], v[132:133], v[128:129] neg_lo:[0,0,1] neg_hi:[0,0,1]
	v_pk_fma_f32 v[132:133], v[6:7], v[172:173], v[134:135] op_sel_hi:[1,0,1]
	v_pk_mul_f32 v[134:135], v[152:153], v[130:131]
	v_pk_mul_f32 v[130:131], v[140:141], v[130:131]
	v_pk_mul_f32 v[128:129], v[128:129], s[6:7] op_sel_hi:[1,0]
	v_pk_fma_f32 v[130:131], v[152:153], v[132:133], v[130:131] neg_lo:[0,0,1] neg_hi:[0,0,1]
	v_pk_fma_f32 v[134:135], v[140:141], v[132:133], v[134:135]
	v_pk_mul_f32 v[130:131], v[130:131], s[6:7] op_sel_hi:[1,0]
	v_pk_mul_f32 v[136:137], v[136:137], s[6:7] op_sel_hi:[1,0]
	v_pk_mul_f32 v[134:135], v[134:135], s[6:7] op_sel_hi:[1,0]
	v_cvt_pk_bf16_f32 v128, v128, v129
	v_cvt_pk_bf16_f32 v129, v130, v131
	global_store_dwordx2 v[138:139], v[128:129], off offset:256
	v_cvt_pk_bf16_f32 v128, v136, v137
	v_cvt_pk_bf16_f32 v129, v134, v135
	global_store_dwordx2 v[138:139], v[128:129], off offset:320
	s_mov_b64 s[2:3], 0
; DI u32x4 pack8(const float* v) { u32x4 w; w.x = pk2(v[0], v[1]); w.y = pk2(v[2], v[3]); w.z = pk2(v[4], v[5]); w.w = pk2(v[6], v[7]); return w; }
; DI u32x2 pack4(const float* v) { u32x2 w; w.x = pk2(v[0], v[1]); w.y = pk2(v[2], v[3]); return w; }
;     template <int PN> DI void body(AccRef acc, const Unit& u, int wr, int wc, int fr, int fq) const {
;     ...
;         for (int ai = 0; ai < 2; ++ai) {
;             const int rb_ = u.pm * 256 + ai * 128 + wr * 64 + fr;
; #pragma unroll
;             for (int m = 0; m < 4; ++m) rinvh[ai][m] = rsqrtf(sum16(ssq + (size_t)(rb_ + 16 * m + zdep) * 16) * (1.f / 1024.f) + EPS);
;             asm volatile("v_mov_b32 %0, 0" : "=v"(zdep) : "v"(rinvh[ai][0]), "v"(rinvh[ai][1]), "v"(rinvh[ai][2]), "v"(rinvh[ai][3]));
;         }
; #pragma unroll
;         for (int ai = 0; ai < 2; ++ai) {
;             const int rb_ = u.pm * 256 + ai * 128 + wr * 64 + fr;
;             int mb_, p_, k_; row_info(rb_, mb_, p_, k_);
; #pragma unroll
;             for (int bj = 0; bj < 2; ++bj)
; #pragma unroll
;                 for (int n = 0; n < 2; ++n) cvh[ai][bj][n] = *(const f32x4*)(cv + (size_t)(mb_ + zdep) * NIN + PN * 256 + bj * 128 + cl + 4 * n);
;         }
;     ...
;                 } else if constexpr (PN == 2) {
;                     float s = 0.f;
;                     *(u32x4*)(zq + (size_t)row * 384 + 256 + cl) = pack8(v[0]);
; #pragma unroll
;                     for (int j = 0; j < 8; ++j) s += v[0][j] * v[0][j];
;                     s = xor16_32(s);
;                     if (fq == 0) ssqq[(size_t)row * 8 + 4 + wc] = s;
;                     if (wc == 0) {
;                         float o1[4], o2[4];
; #pragma unroll
;                         for (int j = 0; j < 4; ++j) { const int i = 4 * fq + j; float sn, cs; sincos_rev((float)pos * ex2(-(float)i * KEXP32), sn, cs);
;                             o1[j] = v[1][j] * cs - v[1][4 + j] * sn; o2[j] = v[1][j] * sn + v[1][4 + j] * cs; }
;                         float* ko = orow(out, l, row, O_PKR, O_SKR, 32);
;                         *(f32x4*)(ko + 4 * fq) = (f32x4){o1[0], o1[1], o1[2], o1[3]};
;                         *(f32x4*)(ko + 16 + 4 * fq) = (f32x4){o2[0], o2[1], o2[2], o2[3]};
;                         *(u32x2*)(kr + (size_t)kvrow * 32 + 4 * fq) = pack4(o1);
;                         *(u32x2*)(kr + (size_t)kvrow * 32 + 16 + 4 * fq) = pack4(o2);
;                     }
.LBB0_1917:
	s_andn2_b64 vcc, exec, s[2:3]
	s_cbranch_vccnz .LBB0_1955
	s_lshl_b32 s2, s43, 6
	s_lshl_b32 s3, s34, 8
	s_add_i32 s2, s2, s3
	v_add_u32_e32 v160, s2, v214
	v_add_u32_e32 v190, 16, v160
	v_ashrrev_i32_e32 v161, 31, v160
	v_ashrrev_i32_e32 v191, 31, v190
	v_lshlrev_b64 v[128:129], 6, v[160:161]
	v_lshlrev_b64 v[144:145], 6, v[190:191]
	v_add_u32_e32 v174, 32, v160
	v_lshl_add_u64 v[140:141], s[70:71], 0, v[128:129]
	v_lshl_add_u64 v[144:145], s[70:71], 0, v[144:145]
	v_ashrrev_i32_e32 v175, 31, v174
	s_nop 0
	s_nop 0
	v_lshlrev_b64 v[144:145], 6, v[174:175]
	v_add_u32_e32 v172, 48, v160
	v_lshl_add_u64 v[144:145], s[70:71], 0, v[144:145]
	v_ashrrev_i32_e32 v173, 31, v172
	v_lshlrev_b64 v[144:145], 6, v[172:173]
	v_lshl_add_u64 v[144:145], s[70:71], 0, v[144:145]
	s_mov_b32 s2, 0x358637bd
	v_mov_b64_e32 v[144:145], s[2:3]
	s_mov_b32 s8, 0x3a800000
	s_mov_b64 s[12:13], 0x124800
	v_mov_b32_e32 v202, v245
	v_mov_b32_e32 v196, v246
	v_add_u32_e32 v162, 0x80, v160
	v_mov_b32_e32 v204, v244
	v_mov_b32_e32 v192, v247
	v_mov_b32 v128, 0
	v_cmp_gt_i32_e64 s[6:7], s94, v162
	v_add_u32_e32 v158, v128, v162
	v_ashrrev_i32_e32 v159, 31, v158
	v_add_u32_e32 v146, 16, v158
	v_lshlrev_b64 v[128:129], 6, v[158:159]
	v_ashrrev_i32_e32 v147, 31, v146
	v_add_u32_e32 v168, 32, v158
	v_lshl_add_u64 v[140:141], s[70:71], 0, v[128:129]
	v_lshlrev_b64 v[146:147], 6, v[146:147]
	v_ashrrev_i32_e32 v169, 31, v168
	v_add_u32_e32 v158, 48, v158
	s_nop 0
	v_lshl_add_u64 v[164:165], s[70:71], 0, v[146:147]
	v_lshlrev_b64 v[168:169], 6, v[168:169]
	v_ashrrev_i32_e32 v159, 31, v158
	s_nop 0
	v_lshl_add_u64 v[188:189], s[70:71], 0, v[168:169]
	v_lshlrev_b64 v[158:159], 6, v[158:159]
	v_lshl_add_u64 v[158:159], s[70:71], 0, v[158:159]
	v_mov_b32_e32 v194, v248
	v_mov_b32_e32 v188, v249
	v_mov_b32_e32 v170, v250
	v_mov_b32_e32 v166, v251
	v_add_u32_e32 v129, 0xffffc000, v160
	v_lshrrev_b32_e32 v164, 6, v129
	s_lshl_b32 s2, s60, 5
	v_ashrrev_i32_e32 v128, 11, v160
	v_add_u32_e32 v129, 8, v164
	v_cmp_gt_i32_e64 s[4:5], s94, v160
	v_lshl_add_u32 v168, v213, 3, s2
	v_mov_b32 v136, 0
	v_ashrrev_i32_e32 v169, 31, v168
	v_cndmask_b32_e64 v128, v129, v128, s[4:5]
	v_add_u32_e32 v130, v136, v128
	v_mov_b64_e32 v[128:129], s[74:75]
	s_movk_i32 s8, 0x2800
	v_mad_i64_i32 v[130:131], s[2:3], v130, s8, v[128:129]
	v_lshlrev_b64 v[132:133], 2, v[168:169]
	v_lshl_add_u64 v[130:131], v[130:131], 0, v[132:133]
	s_mov_b32 s2, 0x124000
	v_lshl_add_u64 v[134:135], v[130:131], 0, s[12:13]
	v_add_co_u32_e32 v130, vcc, s2, v130
	v_add_u32_e32 v171, 0xffffc080, v160
	s_nop 0
	v_addc_co_u32_e32 v131, vcc, 0, v131, vcc
	v_lshrrev_b32_e32 v163, 6, v171
	global_load_dwordx4 v[152:155], v[130:131], off offset:2048
	global_load_dwordx4 v[144:147], v[134:135], off offset:528
	global_load_dwordx4 v[156:159], v[134:135], off offset:16
	global_load_dwordx4 v[148:151], v[134:135], off offset:512
	v_ashrrev_i32_e32 v130, 11, v162
	v_add_u32_e32 v131, 8, v163
	v_cndmask_b32_e64 v130, v131, v130, s[6:7]
	v_add_u32_e32 v130, v136, v130
	v_mad_i64_i32 v[128:129], s[2:3], v130, s8, v[128:129]
	v_lshl_add_u64 v[128:129], v[128:129], 0, v[132:133]
	v_lshl_add_u64 v[132:133], v[128:129], 0, s[12:13]
	v_add_co_u32_e32 v128, vcc, 0x124000, v128
	s_movk_i32 s2, 0x3fff
	s_nop 0
	v_addc_co_u32_e32 v129, vcc, 0, v129, vcc
	global_load_dwordx4 v[136:139], v[128:129], off offset:2048
	s_nop 0
	global_load_dwordx4 v[128:131], v[132:133], off offset:528
	global_load_dwordx4 v[140:143], v[132:133], off offset:16
	s_nop 0
	global_load_dwordx4 v[132:135], v[132:133], off offset:512
	v_and_b32_e32 v165, 63, v214
	v_cmp_lt_i32_e32 vcc, s2, v160
	v_cmp_lt_i32_e64 s[8:9], s2, v162
	v_or_b32_e32 v198, 0x4400, v165
	s_and_saveexec_b64 s[2:3], vcc
	s_xor_b64 s[2:3], exec, s[2:3]
	s_movk_i32 s12, 0x440
	v_mad_u64_u32 v[200:201], s[12:13], v164, s12, v[198:199]
	s_or_saveexec_b64 s[2:3], s[2:3]
	v_or_b32_e32 v199, 0x400, v165
	v_mov_b32_e32 v189, v199
	s_xor_b64 exec, exec, s[2:3]
	v_and_b32_e32 v189, 0x7ff, v160
	v_mov_b32_e32 v200, v160
	s_or_b64 exec, exec, s[2:3]
	v_lshlrev_b32_e32 v164, 2, v214
	v_lshl_add_u32 v164, v213, 6, v164
	v_xor_b32_e32 v206, 64, v164
	v_xor_b32_e32 v167, 0x80, v164
	s_waitcnt vmcnt(7)
	v_pk_fma_f32 v[164:165], v[124:125], v[204:205], v[152:153] op_sel_hi:[1,0,1]
	v_pk_fma_f32 v[220:221], v[126:127], v[204:205], v[154:155] op_sel_hi:[1,0,1]
	v_cvt_pk_bf16_f32 v216, v164, v165
	v_pk_mul_f32 v[164:165], v[164:165], v[164:165]
	v_cvt_pk_bf16_f32 v217, v220, v221
	v_pk_mul_f32 v[220:221], v[220:221], v[220:221]
	v_add_f32_e32 v164, v164, v165
	s_waitcnt vmcnt(5)
	v_pk_fma_f32 v[222:223], v[120:121], v[204:205], v[156:157] op_sel_hi:[1,0,1]
	v_add_f32_e32 v164, v220, v164
	v_cvt_pk_bf16_f32 v218, v222, v223
	v_pk_mul_f32 v[222:223], v[222:223], v[222:223]
	v_add_f32_e32 v164, v221, v164
	v_pk_fma_f32 v[228:229], v[122:123], v[204:205], v[158:159] op_sel_hi:[1,0,1]
	v_add_f32_e32 v164, v222, v164
	v_cvt_pk_bf16_f32 v219, v228, v229
	v_pk_mul_f32 v[228:229], v[228:229], v[228:229]
	v_add_f32_e32 v164, v223, v164
	v_add_f32_e32 v164, v228, v164
	v_add_f32_e32 v193, v229, v164
	s_ashr_i32 s61, s60, 31
	ds_bpermute_b32 v195, v206, v193
	s_lshl_b64 s[12:13], s[60:61], 2
	v_readlane_b32 s16, v254, 51
	s_add_u32 s16, s16, s12
	v_readlane_b32 s12, v254, 50
	s_addc_u32 s17, s12, s13
	v_mov_b64_e32 v[164:165], s[14:15]
	s_movk_i32 s12, 0x300
	v_mad_i64_i32 v[164:165], s[12:13], v160, s12, v[164:165]
	v_lshl_add_u64 v[220:221], v[168:169], 1, v[164:165]
	s_waitcnt lgkmcnt(0)
	v_add_f32_e32 v164, v193, v195
	ds_bpermute_b32 v165, v167, v164
	s_mov_b32 s12, 0x4720000
	v_add_co_u32_e32 v220, vcc, s12, v220
	v_cmp_eq_u32_e64 s[2:3], 0, v213
	s_nop 0
	v_addc_co_u32_e32 v221, vcc, 0, v221, vcc
	global_store_dwordx4 v[220:221], v[216:219], off offset:512
	s_and_saveexec_b64 s[12:13], s[2:3]
	s_cbranch_execz .LBB0_1924
	v_lshlrev_b64 v[216:217], 5, v[160:161]
	v_lshl_add_u64 v[216:217], s[16:17], 0, v[216:217]
	s_waitcnt lgkmcnt(0)
	v_add_f32_e32 v164, v164, v165
	global_store_dword v[216:217], v164, off

; DI u32x4 pack8(const float* v) { u32x4 w; w.x = pk2(v[0], v[1]); w.y = pk2(v[2], v[3]); w.z = pk2(v[4], v[5]); w.w = pk2(v[6], v[7]); return w; }
; DI float sum16(const float* p) { const f32x4* q = (const f32x4*)p; f32x4 a = q[0], b = q[1], c = q[2], d = q[3]; f32x4 s = (a + b) + (c + d); return (s[0] + s[1]) + (s[2] + s[3]); }
; #define xor16_32(s) xor16_32_l((s), fr + 16 * fq)
;     template <int PN> DI void body(AccRef acc, const Unit& u, int wr, int wc, int fr, int fq) const {
;     ...
;         for (int ai = 0; ai < 2; ++ai) {
;             const int rb_ = u.pm * 256 + ai * 128 + wr * 64 + fr;
; #pragma unroll
;             for (int m = 0; m < 4; ++m) rinvh[ai][m] = rsqrtf(sum16(ssq + (size_t)(rb_ + 16 * m + zdep) * 16) * (1.f / 1024.f) + EPS);
;             asm volatile("v_mov_b32 %0, 0" : "=v"(zdep) : "v"(rinvh[ai][0]), "v"(rinvh[ai][1]), "v"(rinvh[ai][2]), "v"(rinvh[ai][3]));
;         }
; #pragma unroll
;         for (int ai = 0; ai < 2; ++ai) {
;             const int rb_ = u.pm * 256 + ai * 128 + wr * 64 + fr;
;             int mb_, p_, k_; row_info(rb_, mb_, p_, k_);
; #pragma unroll
;             for (int bj = 0; bj < 2; ++bj)
; #pragma unroll
;                 for (int n = 0; n < 2; ++n) cvh[ai][bj][n] = *(const f32x4*)(cv + (size_t)(mb_ + zdep) * NIN + PN * 256 + bj * 128 + cl + 4 * n);
;         }
;     ...
;                 } else if constexpr (PN == 1) {
;                     float s = 0.f;
; #pragma unroll
;                     for (int bj = 0; bj < 2; ++bj) {
;                         *(u32x4*)(zq + (size_t)row * 384 + bj * 128 + cl) = pack8(v[bj]);
; #pragma unroll
;                         for (int j = 0; j < 8; ++j) s += v[bj][j] * v[bj][j];
;                     }
;                     s = xor16_32(s);
;                     if (fq == 0) ssqq[(size_t)row * 8 + wc] = s;
.LBB0_1956:
	s_andn2_b64 vcc, exec, s[2:3]
	s_mov_b64 s[8:9], 0
	s_cbranch_vccnz .LBB0_1977
	s_cmp_gt_i32 s66, 0
	s_mov_b64 s[2:3], -1
	s_cbranch_scc0 .LBB0_1975
	s_lshl_b32 s2, s60, 5
	v_lshl_add_u32 v190, v213, 3, s2
	s_lshl_b32 s2, s43, 6
	s_lshl_b32 s3, s34, 8
	s_add_i32 s2, s2, s3
	v_add_u32_e32 v160, s2, v214
	v_ashrrev_i32_e32 v161, 31, v160
	v_lshlrev_b64 v[128:129], 6, v[160:161]
	v_lshl_add_u64 v[140:141], s[70:71], 0, v[128:129]
	s_waitcnt lgkmcnt(0)
	s_nop 0
	v_add_u32_e32 v164, 16, v160
	v_ashrrev_i32_e32 v165, 31, v164
	s_mov_b32 s2, 0x358637bd
	s_mov_b32 s4, 0x3a800000
	v_add_u32_e32 v166, 32, v160
	v_ashrrev_i32_e32 v167, 31, v166
	v_add_u32_e32 v162, 48, v160
	v_ashrrev_i32_e32 v163, 31, v162
	v_add_u32_e32 v168, 0x80, v160
	v_ashrrev_i32_e32 v191, 31, v190
	s_mov_b64 s[6:7], 0x124400
	v_lshlrev_b32_e32 v169, 2, v214
	v_lshl_add_u32 v169, v213, 6, v169
	v_xor_b32_e32 v173, 64, v169
	v_xor_b32_e32 v171, 0x80, v169
	s_ashr_i32 s61, s60, 31
	s_nop 0
	v_lshlrev_b64 v[128:129], 6, v[164:165]
	v_lshl_add_u64 v[140:141], s[70:71], 0, v[128:129]
	s_nop 0
	s_nop 0
	v_mov_b64_e32 v[128:129], s[2:3]
	s_nop 0
	s_nop 0
	s_nop 0
	v_mov_b32_e32 v194, v244
	s_nop 0
	v_mov_b32_e32 v172, v245
	v_lshlrev_b64 v[130:131], 6, v[166:167]
	v_lshl_add_u64 v[142:143], s[70:71], 0, v[130:131]
	s_nop 0
	s_nop 0
	v_lshlrev_b64 v[130:131], 6, v[162:163]
	v_lshl_add_u64 v[142:143], s[70:71], 0, v[130:131]
	s_nop 0
	s_nop 0
	s_nop 0
	s_nop 0
	s_nop 0
	s_nop 0
	v_mov_b32_e32 v196, v246
	s_nop 0
	v_mov_b32_e32 v192, v247
	v_mov_b32 v130, 0
	s_nop 0
	v_add_u32_e32 v130, v130, v168
	v_ashrrev_i32_e32 v131, 31, v130
	v_lshlrev_b64 v[132:133], 6, v[130:131]
	v_lshl_add_u64 v[144:145], s[70:71], 0, v[132:133]
	s_nop 0
	s_nop 0
	v_add_u32_e32 v132, 16, v130
	v_ashrrev_i32_e32 v133, 31, v132
	v_lshlrev_b64 v[132:133], 6, v[132:133]
	v_lshl_add_u64 v[144:145], s[70:71], 0, v[132:133]
	s_nop 0
	s_nop 0
	s_nop 0
	s_nop 0
	s_nop 0
	s_nop 0
	v_mov_b32_e32 v174, v248
	s_nop 0
	v_mov_b32_e32 v170, v249
	v_add_u32_e32 v132, 32, v130
	v_ashrrev_i32_e32 v133, 31, v132
	v_lshlrev_b64 v[132:133], 6, v[132:133]
	v_lshl_add_u64 v[144:145], s[70:71], 0, v[132:133]
	s_nop 0
	v_add_u32_e32 v130, 48, v130
	v_ashrrev_i32_e32 v131, 31, v130
	v_lshlrev_b64 v[130:131], 6, v[130:131]
	v_lshl_add_u64 v[142:143], s[70:71], 0, v[130:131]
	s_nop 0
	s_nop 0
	v_lshlrev_b64 v[132:133], 2, v[190:191]
	s_movk_i32 s4, 0x2800
	s_mov_b32 s5, 0x124000
	v_lshl_add_u64 v[190:191], v[190:191], 1, s[76:77]
	v_mov_b32_e32 v198, v250
	s_nop 0
	v_mov_b32_e32 v188, v251
	v_add_u32_e32 v129, 0xffffc000, v160
	v_lshrrev_b32_e32 v129, 6, v129
	v_cmp_gt_i32_e32 vcc, s94, v160
	v_ashrrev_i32_e32 v128, 11, v160
	v_add_u32_e32 v129, 8, v129
	v_cndmask_b32_e32 v128, v129, v128, vcc
	v_mov_b32 v136, 0
	s_nop 0
	v_add_u32_e32 v130, v136, v128
	v_mov_b64_e32 v[128:129], s[74:75]
	v_mad_i64_i32 v[130:131], s[2:3], v130, s4, v[128:129]
	v_lshl_add_u64 v[130:131], v[130:131], 0, v[132:133]
	v_lshl_add_u64 v[134:135], v[130:131], 0, s[6:7]
	v_add_co_u32_e32 v130, vcc, s5, v130
	s_nop 1
	v_addc_co_u32_e32 v131, vcc, 0, v131, vcc
	global_load_dwordx4 v[148:151], v[130:131], off offset:1024
	global_load_dwordx4 v[152:155], v[134:135], off offset:16
	global_load_dwordx4 v[144:147], v[134:135], off offset:528
	global_load_dwordx4 v[156:159], v[134:135], off offset:512
	v_add_u32_e32 v131, 0xffffc080, v160
	v_lshrrev_b32_e32 v131, 6, v131
	v_cmp_gt_i32_e32 vcc, s94, v168
	v_ashrrev_i32_e32 v130, 11, v168
	v_add_u32_e32 v131, 8, v131
	v_cndmask_b32_e32 v130, v131, v130, vcc
	v_add_u32_e32 v130, v136, v130
	v_mad_i64_i32 v[128:129], s[2:3], v130, s4, v[128:129]
	v_lshl_add_u64 v[128:129], v[128:129], 0, v[132:133]
	v_lshl_add_u64 v[140:141], v[128:129], 0, s[6:7]
	v_add_co_u32_e32 v128, vcc, s5, v128
	s_movk_i32 s4, 0x300
	s_nop 0
	v_addc_co_u32_e32 v129, vcc, 0, v129, vcc
	global_load_dwordx4 v[136:139], v[128:129], off offset:1024
	global_load_dwordx4 v[132:135], v[140:141], off offset:16
	s_nop 0
	global_load_dwordx4 v[128:131], v[140:141], off offset:528
	s_nop 0
	global_load_dwordx4 v[140:143], v[140:141], off offset:512
	v_mad_i64_i32 v[230:231], s[4:5], v160, s4, v[190:191]
	s_lshl_b64 s[2:3], s[60:61], 2
	s_add_u32 s2, s93, s2
	v_cmp_eq_u32_e32 vcc, 0, v213
	s_addc_u32 s3, s95, s3
	s_waitcnt vmcnt(7)
	v_pk_fma_f32 v[204:205], v[124:125], v[194:195], v[148:149] op_sel_hi:[1,0,1]
	v_pk_fma_f32 v[206:207], v[126:127], v[194:195], v[150:151] op_sel_hi:[1,0,1]
	v_cvt_pk_bf16_f32 v200, v204, v205
	v_pk_mul_f32 v[204:205], v[204:205], v[204:205]
	v_cvt_pk_bf16_f32 v201, v206, v207
	v_pk_mul_f32 v[206:207], v[206:207], v[206:207]
	v_add_f32_e32 v169, v204, v205
	s_waitcnt vmcnt(6)
	v_pk_fma_f32 v[216:217], v[120:121], v[194:195], v[152:153] op_sel_hi:[1,0,1]
	v_add_f32_e32 v169, v206, v169
	v_cvt_pk_bf16_f32 v202, v216, v217
	v_pk_mul_f32 v[216:217], v[216:217], v[216:217]
	v_add_f32_e32 v169, v207, v169
	v_pk_fma_f32 v[218:219], v[122:123], v[194:195], v[154:155] op_sel_hi:[1,0,1]
	v_add_f32_e32 v169, v216, v169
	s_waitcnt vmcnt(4)
	v_pk_fma_f32 v[220:221], v[116:117], v[194:195], v[156:157] op_sel_hi:[1,0,1]
	v_pk_fma_f32 v[222:223], v[118:119], v[194:195], v[158:159] op_sel_hi:[1,0,1]
	v_pk_fma_f32 v[228:229], v[112:113], v[194:195], v[144:145] op_sel_hi:[1,0,1]
	v_pk_fma_f32 v[194:195], v[114:115], v[194:195], v[146:147] op_sel_hi:[1,0,1]
	v_cvt_pk_bf16_f32 v203, v218, v219
	v_pk_mul_f32 v[218:219], v[218:219], v[218:219]
	v_add_f32_e32 v169, v217, v169
	global_store_dwordx4 v[230:231], v[200:203], off
	v_add_f32_e32 v169, v218, v169
	v_add_f32_e32 v169, v219, v169
	v_cvt_pk_bf16_f32 v200, v220, v221
	v_cvt_pk_bf16_f32 v201, v222, v223
	v_cvt_pk_bf16_f32 v202, v228, v229
	v_cvt_pk_bf16_f32 v203, v194, v195
	global_store_dwordx4 v[230:231], v[200:203], off offset:256
	v_pk_mul_f32 v[194:195], v[194:195], v[194:195]
	s_nop 0
	v_pk_mul_f32 v[200:201], v[220:221], v[220:221]
	v_pk_mul_f32 v[202:203], v[222:223], v[222:223]
	v_add_f32_e32 v169, v200, v169
	v_add_f32_e32 v169, v201, v169
	v_add_f32_e32 v169, v202, v169
	v_pk_mul_f32 v[220:221], v[228:229], v[228:229]
	v_add_f32_e32 v169, v203, v169
	v_add_f32_e32 v169, v220, v169
	v_add_f32_e32 v169, v221, v169
	v_add_f32_e32 v169, v194, v169
	v_add_f32_e32 v169, v195, v169
	ds_bpermute_b32 v175, v173, v169
	s_waitcnt lgkmcnt(0)
	v_add_f32_e32 v169, v169, v175
	ds_bpermute_b32 v175, v171, v169
	s_and_saveexec_b64 s[4:5], vcc
	s_cbranch_execz .LBB0_1960
	v_lshlrev_b64 v[194:195], 5, v[160:161]
	v_lshl_add_u64 v[194:195], s[2:3], 0, v[194:195]
	s_waitcnt lgkmcnt(0)
	v_add_f32_e32 v161, v169, v175
	global_store_dword v[194:195], v161, off

; DI float sum16(const float* p) { const f32x4* q = (const f32x4*)p; f32x4 a = q[0], b = q[1], c = q[2], d = q[3]; f32x4 s = (a + b) + (c + d); return (s[0] + s[1]) + (s[2] + s[3]); }
;     template <int PN> DI void body(AccRef acc, const Unit& u, int wr, int wc, int fr, int fq) const {
;     ...
;         for (int ai = 0; ai < 2; ++ai) {
;             const int rb_ = u.pm * 256 + ai * 128 + wr * 64 + fr;
; #pragma unroll
;             for (int m = 0; m < 4; ++m) rinvh[ai][m] = rsqrtf(sum16(ssq + (size_t)(rb_ + 16 * m + zdep) * 16) * (1.f / 1024.f) + EPS);
;             asm volatile("v_mov_b32 %0, 0" : "=v"(zdep) : "v"(rinvh[ai][0]), "v"(rinvh[ai][1]), "v"(rinvh[ai][2]), "v"(rinvh[ai][3]));
;         }
; #pragma unroll
;         for (int ai = 0; ai < 2; ++ai) {
;             const int rb_ = u.pm * 256 + ai * 128 + wr * 64 + fr;
;             int mb_, p_, k_; row_info(rb_, mb_, p_, k_);
; #pragma unroll
;             for (int bj = 0; bj < 2; ++bj)
; #pragma unroll
;                 for (int n = 0; n < 2; ++n) cvh[ai][bj][n] = *(const f32x4*)(cv + (size_t)(mb_ + zdep) * NIN + PN * 256 + bj * 128 + cl + 4 * n);
;         }
; #pragma unroll
;         for (int ai = 0; ai < 2; ++ai) {
;             const int rb = u.pm * 256 + ai * 128 + wr * 64 + fr;
;             int mb, pos0, kv0; row_info(rb, mb, pos0, kv0);
; #pragma unroll
;             for (int m = 0; m < 4; ++m) {
;                 const int row = rb + 16 * m, pos = pos0 + 16 * m, kvrow = kv0 + 16 * m;
;                 const float rinv = rinvh[ai][m];
;                 float v[2][8];
; #pragma unroll
;                 for (int bj = 0; bj < 2; ++bj)
; #pragma unroll
;                     for (int n = 0; n < 2; ++n)
; #pragma unroll
;                         for (int j = 0; j < 4; ++j) v[bj][4 * n + j] = acc[ai][bj][m][n][j] * rinv + cvh[ai][bj][n][j];
;     ...
;                 } else {
;                     float* lo = orow(out, l, row, PN == 8 ? O_PSK : O_PSV, PN == 8 ? O_SSK : O_SSV, 256);
; #pragma unroll
;                     for (int bj = 0; bj < 2; ++bj) {
;                         *(f32x4*)(lo + bj * 128 + cl) = (f32x4){v[bj][0], v[bj][1], v[bj][2], v[bj][3]};
;                         *(f32x4*)(lo + bj * 128 + cl + 4) = (f32x4){v[bj][4], v[bj][5], v[bj][6], v[bj][7]};
;                     }
.LBB0_1977:
	s_and_b64 vcc, exec, s[80:81]
	s_cbranch_vccz .LBB0_1996
	s_lshl_b32 s2, s43, 6
	s_lshl_b32 s3, s34, 8
	s_add_i32 s2, s2, s3
	v_add_u32_e32 v160, s2, v214
	v_ashrrev_i32_e32 v161, 31, v160
	v_lshlrev_b64 v[128:129], 6, v[160:161]
	v_lshl_add_u64 v[140:141], s[70:71], 0, v[128:129]
	s_waitcnt lgkmcnt(0)
	s_nop 0
	v_add_u32_e32 v190, 16, v160
	v_ashrrev_i32_e32 v191, 31, v190
	s_mov_b32 s2, 0x358637bd
	s_mov_b32 s4, 0x3a800000
	v_add_u32_e32 v166, 32, v160
	v_ashrrev_i32_e32 v167, 31, v166
	v_add_u32_e32 v168, 48, v160
	v_ashrrev_i32_e32 v169, 31, v168
	v_add_u32_e32 v164, 0x80, v160
	s_movk_i32 s6, 0x2800
	s_mov_b64 s[8:9], 0x126400
	s_mov_b32 s7, 0x126000
	v_add_u32_e32 v163, 0xffffc080, v160
	v_mov_b32_e32 v165, 0xffffc400
	v_mov_b32_e32 v171, 0x4000
	s_nop 0
	v_lshlrev_b64 v[128:129], 6, v[190:191]
	v_lshl_add_u64 v[140:141], s[70:71], 0, v[128:129]
	s_nop 0
	s_nop 0
	v_mov_b64_e32 v[128:129], s[2:3]
	s_nop 0
	s_nop 0
	s_nop 0
	v_mov_b32_e32 v192, v244
	s_nop 0
	v_mov_b32_e32 v162, v245
	v_lshlrev_b64 v[130:131], 6, v[166:167]
	v_lshl_add_u64 v[142:143], s[70:71], 0, v[130:131]
	s_nop 0
	s_nop 0
	v_lshlrev_b64 v[130:131], 6, v[168:169]
	v_lshl_add_u64 v[142:143], s[70:71], 0, v[130:131]
	s_nop 0
	s_nop 0
	s_nop 0
	s_nop 0
	s_nop 0
	s_nop 0
	v_mov_b32_e32 v172, v246
	s_nop 0
	v_mov_b32_e32 v188, v247
	v_mov_b32 v130, 0
	s_nop 0
	v_add_u32_e32 v130, v130, v164
	v_ashrrev_i32_e32 v131, 31, v130
	v_lshlrev_b64 v[132:133], 6, v[130:131]
	v_lshl_add_u64 v[144:145], s[70:71], 0, v[132:133]
	s_nop 0
	s_nop 0
	v_add_u32_e32 v132, 16, v130
	v_ashrrev_i32_e32 v133, 31, v132
	v_lshlrev_b64 v[132:133], 6, v[132:133]
	v_lshl_add_u64 v[144:145], s[70:71], 0, v[132:133]
	s_nop 0
	s_nop 0
	s_nop 0
	s_nop 0
	s_nop 0
	s_nop 0
	v_mov_b32_e32 v174, v248
	s_nop 0
	v_mov_b32_e32 v170, v249
	v_add_u32_e32 v132, 32, v130
	v_ashrrev_i32_e32 v133, 31, v132
	v_lshlrev_b64 v[132:133], 6, v[132:133]
	v_lshl_add_u64 v[144:145], s[70:71], 0, v[132:133]
	s_nop 0
	v_add_u32_e32 v130, 48, v130
	v_ashrrev_i32_e32 v131, 31, v130
	v_lshlrev_b64 v[130:131], 6, v[130:131]
	v_lshl_add_u64 v[142:143], s[70:71], 0, v[130:131]
	s_nop 0
	s_nop 0
	s_nop 0
	s_nop 0
	s_nop 0
	s_nop 0
	v_mov_b32_e32 v196, v250
	s_lshl_b32 s2, s60, 5
	v_lshl_add_u32 v198, v213, 3, s2
	v_cmp_gt_i32_e64 s[2:3], s94, v160
	v_mov_b32_e32 v194, v251
	v_add_u32_e32 v129, 0xffffc000, v160
	v_lshrrev_b32_e32 v129, 6, v129
	v_ashrrev_i32_e32 v128, 11, v160
	v_add_u32_e32 v129, 8, v129
	v_cndmask_b32_e64 v128, v129, v128, s[2:3]
	v_mov_b32 v134, 0
	v_ashrrev_i32_e32 v199, 31, v198
	v_add_u32_e32 v130, v134, v128
	v_mov_b64_e32 v[128:129], s[74:75]
	v_mad_i64_i32 v[130:131], s[4:5], v130, s6, v[128:129]
	v_lshlrev_b64 v[200:201], 2, v[198:199]
	v_lshl_add_u64 v[130:131], v[130:131], 0, v[200:201]
	v_lshl_add_u64 v[132:133], v[130:131], 0, s[8:9]
	v_add_co_u32_e32 v130, vcc, s7, v130
	s_movk_i32 s4, 0x3fff
	s_nop 0
	v_addc_co_u32_e32 v131, vcc, 0, v131, vcc
	global_load_dwordx4 v[152:155], v[130:131], off offset:1024
	global_load_dwordx4 v[156:159], v[132:133], off offset:16
	global_load_dwordx4 v[144:147], v[132:133], off offset:528
	global_load_dwordx4 v[148:151], v[132:133], off offset:512
	v_lshrrev_b32_e32 v131, 6, v163
	v_cmp_lt_i32_e32 vcc, s4, v164
	v_cmp_gt_i32_e64 s[4:5], s94, v164
	v_ashrrev_i32_e32 v130, 11, v164
	v_add_u32_e32 v131, 8, v131
	v_cndmask_b32_e64 v130, v131, v130, s[4:5]
	v_add_u32_e32 v130, v134, v130
	v_mad_i64_i32 v[128:129], s[4:5], v130, s6, v[128:129]
	v_lshl_add_u64 v[128:129], v[128:129], 0, v[200:201]
	v_lshl_add_u64 v[132:133], v[128:129], 0, s[8:9]
	v_add_co_u32_e64 v128, s[4:5], s7, v128
	v_cndmask_b32_e64 v203, -1, 0, s[2:3]
	s_nop 0
	v_addc_co_u32_e64 v129, s[4:5], 0, v129, s[4:5]
	global_load_dwordx4 v[140:143], v[128:129], off offset:1024
	global_load_dwordx4 v[136:139], v[132:133], off offset:16
	s_nop 0
	global_load_dwordx4 v[128:131], v[132:133], off offset:528
	s_nop 0
	global_load_dwordx4 v[132:135], v[132:133], off offset:512
	v_cndmask_b32_e64 v202, v165, v171, s[2:3]
	v_mov_b32_e32 v165, 0xad98000
	v_mov_b32_e32 v171, 0x8800000
	v_lshl_add_u64 v[202:203], v[202:203], 0, v[160:161]
	v_cndmask_b32_e64 v224, v165, v171, s[2:3]
	v_lshl_add_u64 v[204:205], s[84:85], 0, v[224:225]
	v_lshlrev_b64 v[202:203], 10, v[202:203]
	v_lshl_add_u64 v[202:203], v[204:205], 0, v[202:203]
	v_lshl_add_u64 v[206:207], v[202:203], 0, v[200:201]
	s_movk_i32 s4, 0xc410
	v_mov_b32_e32 v224, v160
	s_mov_b32 s5, -1
	v_cmp_gt_i32_e64 s[2:3], s82, v160
	s_movk_i32 s6, 0xc420
	s_mov_b32 s7, -1
	s_waitcnt vmcnt(7)
	v_pk_fma_f32 v[204:205], v[126:127], v[192:193], v[154:155] op_sel_hi:[1,0,1]
	v_pk_fma_f32 v[202:203], v[124:125], v[192:193], v[152:153] op_sel_hi:[1,0,1]
	global_store_dwordx4 v[206:207], v[202:205], off
	s_waitcnt vmcnt(7)
	s_nop 0
	v_pk_fma_f32 v[204:205], v[122:123], v[192:193], v[158:159] op_sel_hi:[1,0,1]
	v_pk_fma_f32 v[202:203], v[120:121], v[192:193], v[156:157] op_sel_hi:[1,0,1]
	global_store_dwordx4 v[206:207], v[202:205], off offset:16
	s_waitcnt vmcnt(6)
;     template <int PN> DI void body(AccRef acc, const Unit& u, int wr, int wc, int fr, int fq) const {
;     ...
;                 } else {
;                     float* lo = orow(out, l, row, PN == 8 ? O_PSK : O_PSV, PN == 8 ? O_SSK : O_SSV, 256);
; #pragma unroll
;                     for (int bj = 0; bj < 2; ++bj) {
;                         *(f32x4*)(lo + bj * 128 + cl) = (f32x4){v[bj][0], v[bj][1], v[bj][2], v[bj][3]};
;                         *(f32x4*)(lo + bj * 128 + cl + 4) = (f32x4){v[bj][4], v[bj][5], v[bj][6], v[bj][7]};
;                     }
	s_nop 0
	v_pk_fma_f32 v[204:205], v[118:119], v[192:193], v[150:151] op_sel_hi:[1,0,1]
	v_pk_fma_f32 v[202:203], v[116:117], v[192:193], v[148:149] op_sel_hi:[1,0,1]
	global_store_dwordx4 v[206:207], v[202:205], off offset:512
	s_nop 1
	v_pk_fma_f32 v[204:205], v[114:115], v[192:193], v[146:147] op_sel_hi:[1,0,1]
	v_pk_fma_f32 v[202:203], v[112:113], v[192:193], v[144:145] op_sel_hi:[1,0,1]
	v_lshl_add_u64 v[192:193], v[224:225], 0, s[4:5]
	s_mov_b64 s[4:5], 0x4000
	v_lshl_add_u64 v[190:191], v[190:191], 0, s[4:5]
	v_cndmask_b32_e64 v191, v193, v191, s[2:3]
	v_cndmask_b32_e64 v190, v192, v190, s[2:3]
	v_cndmask_b32_e64 v192, v165, v171, s[2:3]
	v_mov_b32_e32 v193, v225
	v_lshl_add_u64 v[192:193], s[84:85], 0, v[192:193]
	v_lshlrev_b64 v[190:191], 10, v[190:191]
	v_lshl_add_u64 v[190:191], v[192:193], 0, v[190:191]
	global_store_dwordx4 v[206:207], v[202:205], off offset:528
	v_pk_fma_f32 v[192:193], v[110:111], v[162:163], v[154:155] op_sel_hi:[1,0,1]
	v_cmp_gt_i32_e64 s[2:3], s83, v160
	v_lshl_add_u64 v[202:203], v[190:191], 0, v[200:201]
	v_pk_fma_f32 v[190:191], v[108:109], v[162:163], v[152:153] op_sel_hi:[1,0,1]
	global_store_dwordx4 v[202:203], v[190:193], off
	v_lshl_add_u64 v[166:167], v[166:167], 0, s[4:5]
	s_nop 0
	v_pk_fma_f32 v[192:193], v[106:107], v[162:163], v[158:159] op_sel_hi:[1,0,1]
	v_pk_fma_f32 v[190:191], v[104:105], v[162:163], v[156:157] op_sel_hi:[1,0,1]
	global_store_dwordx4 v[202:203], v[190:193], off offset:16
	s_nop 1
	v_pk_fma_f32 v[192:193], v[102:103], v[162:163], v[150:151] op_sel_hi:[1,0,1]
	v_pk_fma_f32 v[190:191], v[100:101], v[162:163], v[148:149] op_sel_hi:[1,0,1]
	global_store_dwordx4 v[202:203], v[190:193], off offset:512
	s_nop 1
	v_pk_fma_f32 v[192:193], v[98:99], v[162:163], v[146:147] op_sel_hi:[1,0,1]
	v_pk_fma_f32 v[190:191], v[96:97], v[162:163], v[144:145] op_sel_hi:[1,0,1]
	global_store_dwordx4 v[202:203], v[190:193], off offset:528
	s_nop 1
	v_lshl_add_u64 v[190:191], v[224:225], 0, s[6:7]
	v_cndmask_b32_e64 v167, v191, v167, s[2:3]
	v_cndmask_b32_e64 v166, v190, v166, s[2:3]
	v_cndmask_b32_e64 v190, v165, v171, s[2:3]
	v_mov_b32_e32 v191, v225
	v_lshl_add_u64 v[190:191], s[84:85], 0, v[190:191]
	v_lshlrev_b64 v[166:167], 10, v[166:167]
	v_lshl_add_u64 v[166:167], v[190:191], 0, v[166:167]
	v_lshl_add_u64 v[166:167], v[166:167], 0, v[200:201]
	v_pk_fma_f32 v[192:193], v[94:95], v[172:173], v[154:155] op_sel_hi:[1,0,1]
	v_pk_fma_f32 v[190:191], v[92:93], v[172:173], v[152:153] op_sel_hi:[1,0,1]
	global_store_dwordx4 v[166:167], v[190:193], off
	s_movk_i32 s6, 0xc430
	s_mov_b32 s7, -1
	v_pk_fma_f32 v[192:193], v[90:91], v[172:173], v[158:159] op_sel_hi:[1,0,1]
	v_pk_fma_f32 v[190:191], v[88:89], v[172:173], v[156:157] op_sel_hi:[1,0,1]
	global_store_dwordx4 v[166:167], v[190:193], off offset:16
	v_cmp_gt_i32_e64 s[2:3], s92, v160
	v_lshl_add_u64 v[160:161], v[224:225], 0, s[6:7]
	v_pk_fma_f32 v[192:193], v[86:87], v[172:173], v[150:151] op_sel_hi:[1,0,1]
	v_pk_fma_f32 v[190:191], v[84:85], v[172:173], v[148:149] op_sel_hi:[1,0,1]
	global_store_dwordx4 v[166:167], v[190:193], off offset:512
	v_pk_fma_f32 v[154:155], v[78:79], v[188:189], v[154:155] op_sel_hi:[1,0,1]
	v_pk_fma_f32 v[152:153], v[76:77], v[188:189], v[152:153] op_sel_hi:[1,0,1]
	v_pk_fma_f32 v[192:193], v[82:83], v[172:173], v[146:147] op_sel_hi:[1,0,1]
	v_pk_fma_f32 v[190:191], v[80:81], v[172:173], v[144:145] op_sel_hi:[1,0,1]
	global_store_dwordx4 v[166:167], v[190:193], off offset:528
	v_lshl_add_u64 v[166:167], v[168:169], 0, s[4:5]
	v_cndmask_b32_e64 v161, v161, v167, s[2:3]
	v_cndmask_b32_e64 v160, v160, v166, s[2:3]
	v_cndmask_b32_e64 v166, v165, v171, s[2:3]
	v_mov_b32_e32 v167, v225
	v_lshl_add_u64 v[166:167], s[84:85], 0, v[166:167]
	v_lshlrev_b64 v[160:161], 10, v[160:161]
	v_lshl_add_u64 v[160:161], v[166:167], 0, v[160:161]
	v_lshl_add_u64 v[160:161], v[160:161], 0, v[200:201]
	global_store_dwordx4 v[160:161], v[152:155], off
	v_pk_fma_f32 v[150:151], v[70:71], v[188:189], v[150:151] op_sel_hi:[1,0,1]
	v_pk_fma_f32 v[148:149], v[68:69], v[188:189], v[148:149] op_sel_hi:[1,0,1]
	v_pk_fma_f32 v[154:155], v[74:75], v[188:189], v[158:159] op_sel_hi:[1,0,1]
	v_pk_fma_f32 v[152:153], v[72:73], v[188:189], v[156:157] op_sel_hi:[1,0,1]
	v_pk_fma_f32 v[146:147], v[66:67], v[188:189], v[146:147] op_sel_hi:[1,0,1]
	v_pk_fma_f32 v[144:145], v[64:65], v[188:189], v[144:145] op_sel_hi:[1,0,1]
	global_store_dwordx4 v[160:161], v[152:155], off offset:16
	global_store_dwordx4 v[160:161], v[148:151], off offset:512
	global_store_dwordx4 v[160:161], v[144:147], off offset:528
	s_and_saveexec_b64 s[2:3], vcc
	s_xor_b64 s[2:3], exec, s[2:3]
	v_add_u32_e32 v144, 0x400, v163
	v_mov_b32_e32 v145, v225
	s_or_saveexec_b64 s[2:3], s[2:3]
	v_mov_b64_e32 v[146:147], 0x2b66000
	s_xor_b64 exec, exec, s[2:3]
	v_ashrrev_i32_e32 v165, 31, v164
	v_lshl_add_u64 v[144:145], v[164:165], 0, s[4:5]
	v_mov_b64_e32 v[146:147], 0x2200000
	s_or_b64 exec, exec, s[2:3]
	v_lshlrev_b32_e32 v146, 2, v146
	v_mov_b32_e32 v147, v225
	v_lshl_add_u64 v[146:147], s[84:85], 0, v[146:147]
	v_lshlrev_b64 v[144:145], 10, v[144:145]
	v_lshl_add_u64 v[144:145], v[146:147], 0, v[144:145]
	v_lshl_add_u64 v[148:149], v[198:199], 2, v[144:145]
	s_waitcnt vmcnt(19)
	v_pk_fma_f32 v[146:147], v[62:63], v[174:175], v[142:143] op_sel_hi:[1,0,1]
	v_pk_fma_f32 v[144:145], v[60:61], v[174:175], v[140:141] op_sel_hi:[1,0,1]
	global_store_dwordx4 v[148:149], v[144:147], off
	s_movk_i32 s2, 0x3fef
	v_cmp_lt_i32_e32 vcc, s2, v164
	s_waitcnt vmcnt(19)
;     template <int PN> DI void body(AccRef acc, const Unit& u, int wr, int wc, int fr, int fq) const {
;     ...
;                 } else {
;                     float* lo = orow(out, l, row, PN == 8 ? O_PSK : O_PSV, PN == 8 ? O_SSK : O_SSV, 256);
; #pragma unroll
;                     for (int bj = 0; bj < 2; ++bj) {
;                         *(f32x4*)(lo + bj * 128 + cl) = (f32x4){v[bj][0], v[bj][1], v[bj][2], v[bj][3]};
;                         *(f32x4*)(lo + bj * 128 + cl + 4) = (f32x4){v[bj][4], v[bj][5], v[bj][6], v[bj][7]};
;                     }
	v_pk_fma_f32 v[146:147], v[58:59], v[174:175], v[138:139] op_sel_hi:[1,0,1]
	v_pk_fma_f32 v[144:145], v[56:57], v[174:175], v[136:137] op_sel_hi:[1,0,1]
	global_store_dwordx4 v[148:149], v[144:147], off offset:16
	s_waitcnt vmcnt(18)
	s_nop 0
	v_pk_fma_f32 v[146:147], v[54:55], v[174:175], v[134:135] op_sel_hi:[1,0,1]
	v_pk_fma_f32 v[144:145], v[52:53], v[174:175], v[132:133] op_sel_hi:[1,0,1]
	global_store_dwordx4 v[148:149], v[144:147], off offset:512
	s_nop 1
	v_pk_fma_f32 v[146:147], v[50:51], v[174:175], v[130:131] op_sel_hi:[1,0,1]
	v_pk_fma_f32 v[144:145], v[48:49], v[174:175], v[128:129] op_sel_hi:[1,0,1]
	global_store_dwordx4 v[148:149], v[144:147], off offset:528
	s_and_saveexec_b64 s[2:3], vcc
	s_xor_b64 s[2:3], exec, s[2:3]
	s_movk_i32 s4, 0xc490
	s_mov_b32 s5, -1
	v_lshl_add_u64 v[144:145], v[224:225], 0, s[4:5]
	s_or_saveexec_b64 s[2:3], s[2:3]
	v_mov_b64_e32 v[146:147], 0x2b66000
	s_xor_b64 exec, exec, s[2:3]
	v_add_u32_e32 v144, 0x90, v224
	v_ashrrev_i32_e32 v145, 31, v144
	s_mov_b64 s[4:5], 0x4000
	v_lshl_add_u64 v[144:145], v[144:145], 0, s[4:5]
	v_mov_b64_e32 v[146:147], 0x2200000
	s_or_b64 exec, exec, s[2:3]
	v_lshlrev_b32_e32 v146, 2, v146
	v_mov_b32_e32 v147, v225
	v_lshl_add_u64 v[146:147], s[84:85], 0, v[146:147]
	v_lshlrev_b64 v[144:145], 10, v[144:145]
	v_lshl_add_u64 v[144:145], v[146:147], 0, v[144:145]
	v_lshl_add_u64 v[148:149], v[198:199], 2, v[144:145]
	v_pk_fma_f32 v[146:147], v[46:47], v[170:171], v[142:143] op_sel_hi:[1,0,1]
	v_pk_fma_f32 v[144:145], v[44:45], v[170:171], v[140:141] op_sel_hi:[1,0,1]
	global_store_dwordx4 v[148:149], v[144:147], off
	s_movk_i32 s2, 0x3fdf
	v_cmp_lt_i32_e32 vcc, s2, v164
	v_pk_fma_f32 v[146:147], v[42:43], v[170:171], v[138:139] op_sel_hi:[1,0,1]
	v_pk_fma_f32 v[144:145], v[40:41], v[170:171], v[136:137] op_sel_hi:[1,0,1]
	global_store_dwordx4 v[148:149], v[144:147], off offset:16
	s_nop 1
	v_pk_fma_f32 v[146:147], v[38:39], v[170:171], v[134:135] op_sel_hi:[1,0,1]
	v_pk_fma_f32 v[144:145], v[36:37], v[170:171], v[132:133] op_sel_hi:[1,0,1]
	global_store_dwordx4 v[148:149], v[144:147], off offset:512
	s_nop 1
	v_pk_fma_f32 v[146:147], v[30:31], v[170:171], v[130:131] op_sel_hi:[1,0,1]
	v_pk_fma_f32 v[144:145], v[28:29], v[170:171], v[128:129] op_sel_hi:[1,0,1]
	global_store_dwordx4 v[148:149], v[144:147], off offset:528
	s_and_saveexec_b64 s[2:3], vcc
	s_xor_b64 s[2:3], exec, s[2:3]
	s_movk_i32 s4, 0xc4a0
	s_mov_b32 s5, -1
	v_lshl_add_u64 v[144:145], v[224:225], 0, s[4:5]
	s_or_saveexec_b64 s[2:3], s[2:3]
	v_mov_b64_e32 v[146:147], 0x2b66000
	s_xor_b64 exec, exec, s[2:3]
	v_add_u32_e32 v144, 0xa0, v224
	v_ashrrev_i32_e32 v145, 31, v144
	s_mov_b64 s[4:5], 0x4000
	v_lshl_add_u64 v[144:145], v[144:145], 0, s[4:5]
	v_mov_b64_e32 v[146:147], 0x2200000
	s_or_b64 exec, exec, s[2:3]
	v_lshlrev_b32_e32 v146, 2, v146
	v_mov_b32_e32 v147, v225
	v_lshl_add_u64 v[146:147], s[84:85], 0, v[146:147]
	v_lshlrev_b64 v[144:145], 10, v[144:145]
	v_lshl_add_u64 v[144:145], v[146:147], 0, v[144:145]
	v_lshl_add_u64 v[148:149], v[198:199], 2, v[144:145]
	v_pk_fma_f32 v[146:147], v[34:35], v[196:197], v[142:143] op_sel_hi:[1,0,1]
	v_pk_fma_f32 v[144:145], v[32:33], v[196:197], v[140:141] op_sel_hi:[1,0,1]
	global_store_dwordx4 v[148:149], v[144:147], off
	s_movk_i32 s2, 0x3fcf
	v_cmp_lt_i32_e32 vcc, s2, v164
	v_pk_fma_f32 v[146:147], v[26:27], v[196:197], v[138:139] op_sel_hi:[1,0,1]
	v_pk_fma_f32 v[144:145], v[24:25], v[196:197], v[136:137] op_sel_hi:[1,0,1]
	global_store_dwordx4 v[148:149], v[144:147], off offset:16
	s_nop 1
	v_pk_fma_f32 v[146:147], v[22:23], v[196:197], v[134:135] op_sel_hi:[1,0,1]
	v_pk_fma_f32 v[144:145], v[20:21], v[196:197], v[132:133] op_sel_hi:[1,0,1]
	global_store_dwordx4 v[148:149], v[144:147], off offset:512
	s_nop 1
	v_pk_fma_f32 v[146:147], v[18:19], v[196:197], v[130:131] op_sel_hi:[1,0,1]
	v_pk_fma_f32 v[144:145], v[16:17], v[196:197], v[128:129] op_sel_hi:[1,0,1]
	global_store_dwordx4 v[148:149], v[144:147], off offset:528
	s_and_saveexec_b64 s[2:3], vcc
	s_xor_b64 s[2:3], exec, s[2:3]
	s_movk_i32 s4, 0xc4b0
	s_mov_b32 s5, -1
	v_lshl_add_u64 v[144:145], v[224:225], 0, s[4:5]
	s_or_saveexec_b64 s[2:3], s[2:3]
	v_mov_b64_e32 v[146:147], 0x2b66000
	s_xor_b64 exec, exec, s[2:3]
	v_add_u32_e32 v144, 0xb0, v224
	v_ashrrev_i32_e32 v145, 31, v144
	s_mov_b64 s[4:5], 0x4000
	v_lshl_add_u64 v[144:145], v[144:145], 0, s[4:5]
	v_mov_b64_e32 v[146:147], 0x2200000
	s_or_b64 exec, exec, s[2:3]
	v_lshlrev_b32_e32 v224, 2, v146
	v_lshl_add_u64 v[146:147], s[84:85], 0, v[224:225]
	v_lshlrev_b64 v[144:145], 10, v[144:145]
	v_lshl_add_u64 v[144:145], v[146:147], 0, v[144:145]
	v_lshl_add_u64 v[144:145], v[198:199], 2, v[144:145]
	v_pk_fma_f32 v[142:143], v[14:15], v[194:195], v[142:143] op_sel_hi:[1,0,1]
	v_pk_fma_f32 v[140:141], v[12:13], v[194:195], v[140:141] op_sel_hi:[1,0,1]
	v_pk_fma_f32 v[138:139], v[10:11], v[194:195], v[138:139] op_sel_hi:[1,0,1]
	v_pk_fma_f32 v[136:137], v[8:9], v[194:195], v[136:137] op_sel_hi:[1,0,1]
	v_pk_fma_f32 v[134:135], v[6:7], v[194:195], v[134:135] op_sel_hi:[1,0,1]
	v_pk_fma_f32 v[132:133], v[4:5], v[194:195], v[132:133] op_sel_hi:[1,0,1]
	v_pk_fma_f32 v[130:131], v[2:3], v[194:195], v[130:131] op_sel_hi:[1,0,1]
	v_pk_fma_f32 v[128:129], v[0:1], v[194:195], v[128:129] op_sel_hi:[1,0,1]
	global_store_dwordx4 v[144:145], v[140:143], off
	global_store_dwordx4 v[144:145], v[136:139], off offset:16
	global_store_dwordx4 v[144:145], v[132:135], off offset:512
	global_store_dwordx4 v[144:145], v[128:131], off offset:528

; #define LAS __attribute__((address_space(3)))
; DI u32x4 pack8(const float* v) { u32x4 w; w.x = pk2(v[0], v[1]); w.y = pk2(v[2], v[3]); w.z = pk2(v[4], v[5]); w.w = pk2(v[6], v[7]); return w; }
;     template <int PN> DI void body(AccRef acc, const Unit& u, int wr, int wc, int fr, int fq) const {
;     ...
;         for (int ai = 0; ai < 2; ++ai) {
;             const int rb_ = u.pm * 256 + ai * 128 + wr * 64 + fr;
; #pragma unroll
;             for (int m = 0; m < 4; ++m) rinvh[ai][m] = rsqrtf(sum16(ssq + (size_t)(rb_ + 16 * m + zdep) * 16) * (1.f / 1024.f) + EPS);
;             asm volatile("v_mov_b32 %0, 0" : "=v"(zdep) : "v"(rinvh[ai][0]), "v"(rinvh[ai][1]), "v"(rinvh[ai][2]), "v"(rinvh[ai][3]));
;         }
; #pragma unroll
;         for (int ai = 0; ai < 2; ++ai) {
;             const int rb_ = u.pm * 256 + ai * 128 + wr * 64 + fr;
;             int mb_, p_, k_; row_info(rb_, mb_, p_, k_);
; #pragma unroll
;             for (int bj = 0; bj < 2; ++bj)
; #pragma unroll
;                 for (int n = 0; n < 2; ++n) cvh[ai][bj][n] = *(const f32x4*)(cv + (size_t)(mb_ + zdep) * NIN + PN * 256 + bj * 128 + cl + 4 * n);
;         }
; #pragma unroll
;         for (int ai = 0; ai < 2; ++ai) {
;             const int rb = u.pm * 256 + ai * 128 + wr * 64 + fr;
;             int mb, pos0, kv0; row_info(rb, mb, pos0, kv0);
; #pragma unroll
;             for (int m = 0; m < 4; ++m) {
;                 const int row = rb + 16 * m, pos = pos0 + 16 * m, kvrow = kv0 + 16 * m;
;                 const float rinv = rinvh[ai][m];
;                 float v[2][8];
; #pragma unroll
;                 for (int bj = 0; bj < 2; ++bj)
; #pragma unroll
;                     for (int n = 0; n < 2; ++n)
; #pragma unroll
;                         for (int j = 0; j < 4; ++j) v[bj][4 * n + j] = acc[ai][bj][m][n][j] * rinv + cvh[ai][bj][n][j];
;                 if constexpr (PN == 0) {
;                     float s = 0.f;
; #pragma unroll
;                     for (int bj = 0; bj < 2; ++bj) {
;                         *(u32x4*)(zkv + (size_t)row * 256 + bj * 128 + cl) = pack8(v[bj]);
; #pragma unroll
;                         for (int j = 0; j < 8; ++j) s += v[bj][j] * v[bj][j];
;                     }
;                     s = xor16_32(s);
;                     if (fq == 0) { ssqkv[(size_t)row * 4 + wc] = s; *(LAS float*)(xl + ((ai * 128 + wr * 64 + 16 * m + fr) * 4 + wc) * 4) = s; }
.LBB0_1996:
	s_and_b64 vcc, exec, s[8:9]
	s_cbranch_vccz .LBB0_1995
	v_lshl_add_u32 v164, s43, 6, v214
	s_lshl_b32 s4, s34, 8
	v_add_u32_e32 v192, s4, v164
	v_ashrrev_i32_e32 v193, 31, v192
	v_lshlrev_b64 v[128:129], 6, v[192:193]
	v_lshl_add_u64 v[140:141], s[70:71], 0, v[128:129]
	s_waitcnt lgkmcnt(0)
	s_nop 0
	v_add_u32_e32 v206, 16, v192
	v_ashrrev_i32_e32 v207, 31, v206
	s_mov_b32 s2, 0x358637bd
	s_mov_b32 s6, 0x3a800000
	v_add_u32_e32 v204, 32, v192
	v_ashrrev_i32_e32 v205, 31, v204
	v_add_u32_e32 v194, 48, v192
	v_ashrrev_i32_e32 v195, 31, v194
	v_add_u32_e32 v189, 0x80, v164
	v_add_u32_e32 v190, s4, v189
	s_movk_i32 s4, 0x2800
	v_lshlrev_b64 v[168:169], 9, v[192:193]
	v_lshlrev_b32_e32 v165, 2, v214
	v_lshl_add_u32 v165, v213, 6, v165
	v_xor_b32_e32 v166, 64, v165
	v_xor_b32_e32 v165, 0x80, v165
	s_ashr_i32 s61, s60, 31
	s_nop 0
	v_lshlrev_b64 v[128:129], 6, v[206:207]
	v_lshl_add_u64 v[140:141], s[70:71], 0, v[128:129]
	s_nop 0
	s_nop 0
	v_mov_b64_e32 v[128:129], s[2:3]
	s_nop 0
	s_nop 0
	s_nop 0
	v_mov_b32_e32 v212, v244
	s_nop 0
	v_mov_b32_e32 v196, v245
	v_lshlrev_b64 v[130:131], 6, v[204:205]
	v_lshl_add_u64 v[142:143], s[70:71], 0, v[130:131]
	s_nop 0
	s_nop 0
	v_lshlrev_b64 v[130:131], 6, v[194:195]
	v_lshl_add_u64 v[142:143], s[70:71], 0, v[130:131]
	s_nop 0
	s_nop 0
	s_nop 0
	s_nop 0
	s_nop 0
	s_nop 0
	v_mov_b32_e32 v208, v246
	s_nop 0
	v_mov_b32_e32 v200, v247
	v_mov_b32 v130, 0
	s_nop 0
	v_add_u32_e32 v130, v130, v190
	v_ashrrev_i32_e32 v131, 31, v130
	v_lshlrev_b64 v[132:133], 6, v[130:131]
	v_lshl_add_u64 v[144:145], s[70:71], 0, v[132:133]
	s_nop 0
	s_nop 0
	v_add_u32_e32 v132, 16, v130
	v_ashrrev_i32_e32 v133, 31, v132
	v_lshlrev_b64 v[132:133], 6, v[132:133]
	v_lshl_add_u64 v[144:145], s[70:71], 0, v[132:133]
	s_nop 0
	s_nop 0
	s_nop 0
	s_nop 0
	s_nop 0
	s_nop 0
	v_mov_b32_e32 v202, v248
	s_nop 0
	v_mov_b32_e32 v198, v249
	v_add_u32_e32 v132, 32, v130
	v_ashrrev_i32_e32 v133, 31, v132
	v_lshlrev_b64 v[132:133], 6, v[132:133]
	v_lshl_add_u64 v[144:145], s[70:71], 0, v[132:133]
	s_nop 0
	v_add_u32_e32 v130, 48, v130
	v_ashrrev_i32_e32 v131, 31, v130
	v_lshlrev_b64 v[130:131], 6, v[130:131]
	v_lshl_add_u64 v[142:143], s[70:71], 0, v[130:131]
	s_nop 0
	s_nop 0
	s_nop 0
	v_add_u32_e32 v131, 0xffffc000, v192
	v_lshrrev_b32_e32 v131, 6, v131
	v_add_u32_e32 v131, 8, v131
	s_lshl_b64 s[6:7], s[60:61], 2
	v_mov_b32_e32 v210, v250
	s_lshl_b32 s2, s60, 5
	v_lshl_add_u32 v160, v213, 3, s2
	v_ashrrev_i32_e32 v130, 11, v192
	v_mov_b32_e32 v188, v251
	v_cmp_gt_i32_e32 vcc, s94, v192
	v_ashrrev_i32_e32 v161, 31, v160
	v_mov_b32 v132, 0
	v_lshl_add_u64 v[128:129], v[160:161], 2, s[62:63]
	v_cndmask_b32_e32 v130, v131, v130, vcc
	v_add_u32_e32 v130, v132, v130
	v_mad_i64_i32 v[130:131], s[2:3], v130, s4, v[128:129]
	global_load_dwordx4 v[148:151], v[130:131], off offset:16
	global_load_dwordx4 v[156:159], v[130:131], off
	global_load_dwordx4 v[144:147], v[130:131], off offset:528
	global_load_dwordx4 v[152:155], v[130:131], off offset:512
	v_add_u32_e32 v131, 0xffffc080, v192
	v_add_u32_e32 v130, 0x80, v192
	v_lshrrev_b32_e32 v131, 6, v131
	v_cmp_gt_i32_e64 s[2:3], s94, v130
	v_ashrrev_i32_e32 v130, 11, v130
	v_add_u32_e32 v131, 8, v131
	v_cndmask_b32_e64 v130, v131, v130, s[2:3]
	v_add_u32_e32 v130, v132, v130
	v_mad_i64_i32 v[132:133], s[2:3], v130, s4, v[128:129]
	global_load_dwordx4 v[136:139], v[132:133], off offset:16
	global_load_dwordx4 v[140:143], v[132:133], off
	global_load_dwordx4 v[128:131], v[132:133], off offset:528
	s_nop 0
	global_load_dwordx4 v[132:135], v[132:133], off offset:512
	v_lshl_add_u64 v[162:163], v[160:161], 1, s[86:87]
	v_lshl_add_u64 v[230:231], v[162:163], 0, v[168:169]
	s_add_u32 s6, s73, s6
	v_cmp_ne_u32_e64 s[2:3], 0, v213
	v_cmp_eq_u32_e64 s[4:5], 0, v213
	s_addc_u32 s7, s67, s7
	s_lshl_b32 s12, s60, 2
	s_waitcnt vmcnt(7)
	v_pk_fma_f32 v[214:215], v[120:121], v[212:213], v[148:149] op_sel_hi:[1,0,1]
	s_waitcnt vmcnt(6)
	v_pk_fma_f32 v[172:173], v[124:125], v[212:213], v[156:157] op_sel_hi:[1,0,1]
	v_pk_fma_f32 v[174:175], v[126:127], v[212:213], v[158:159] op_sel_hi:[1,0,1]
	v_cvt_pk_bf16_f32 v168, v172, v173
	v_pk_mul_f32 v[172:173], v[172:173], v[172:173]
	v_cvt_pk_bf16_f32 v169, v174, v175
	v_pk_mul_f32 v[174:175], v[174:175], v[174:175]
	v_add_f32_e32 v167, v172, v173
	v_add_f32_e32 v167, v174, v167
	v_cvt_pk_bf16_f32 v170, v214, v215
	v_pk_mul_f32 v[214:215], v[214:215], v[214:215]
	v_add_f32_e32 v167, v175, v167
	v_pk_fma_f32 v[216:217], v[122:123], v[212:213], v[150:151] op_sel_hi:[1,0,1]
	v_add_f32_e32 v167, v214, v167
	s_waitcnt vmcnt(4)
	v_pk_fma_f32 v[218:219], v[116:117], v[212:213], v[152:153] op_sel_hi:[1,0,1]
	v_pk_fma_f32 v[220:221], v[118:119], v[212:213], v[154:155] op_sel_hi:[1,0,1]
	v_pk_fma_f32 v[222:223], v[112:113], v[212:213], v[144:145] op_sel_hi:[1,0,1]
	v_pk_fma_f32 v[228:229], v[114:115], v[212:213], v[146:147] op_sel_hi:[1,0,1]
	v_cvt_pk_bf16_f32 v171, v216, v217
	v_pk_mul_f32 v[216:217], v[216:217], v[216:217]
	v_add_f32_e32 v167, v215, v167
	global_store_dwordx4 v[230:231], v[168:171], off
	v_add_f32_e32 v167, v216, v167
	v_add_f32_e32 v167, v217, v167
	v_cvt_pk_bf16_f32 v168, v218, v219
	v_cvt_pk_bf16_f32 v169, v220, v221
	v_cvt_pk_bf16_f32 v170, v222, v223
	v_cvt_pk_bf16_f32 v171, v228, v229
	global_store_dwordx4 v[230:231], v[168:171], off offset:256
	s_nop 1
	v_pk_mul_f32 v[168:169], v[218:219], v[218:219]
	v_pk_mul_f32 v[170:171], v[220:221], v[220:221]
	v_add_f32_e32 v167, v168, v167
	v_add_f32_e32 v167, v169, v167
	v_add_f32_e32 v167, v170, v167
	v_pk_mul_f32 v[218:219], v[222:223], v[222:223]
	v_add_f32_e32 v167, v171, v167
	v_add_f32_e32 v167, v218, v167
	v_pk_mul_f32 v[220:221], v[228:229], v[228:229]
	v_add_f32_e32 v167, v219, v167
	v_add_f32_e32 v167, v220, v167
	v_add_f32_e32 v167, v221, v167
	ds_bpermute_b32 v168, v166, v167
	s_waitcnt lgkmcnt(0)
	v_add_f32_e32 v167, v167, v168
	ds_bpermute_b32 v168, v165, v167
	s_and_saveexec_b64 s[8:9], s[4:5]
	s_cbranch_execz .LBB0_1999
	s_add_i32 s13, s12, 0
	v_lshl_add_u32 v169, v164, 4, s13
	v_add_u32_e32 v169, 0x20000, v169
	v_lshl_add_u64 v[170:171], v[192:193], 4, s[6:7]
	s_waitcnt lgkmcnt(0)
	v_add_f32_e32 v167, v167, v168
	global_store_dword v[170:171], v167, off
	ds_write_b32 v169, v167
